# v061: v056 + every packed f32 VALU op (v_pk_mul/add/fma_f32) split into its two scalar lanes
# speedup vs baseline: 1.0017x; 1.0017x over previous
.LBB0_17:
	global_load_dwordx4 v[12:15], v[10:11], off
	global_load_dwordx4 v[16:19], v[10:11], off offset:2048
	global_load_dwordx4 v[20:23], v[10:11], off offset:16
	global_load_dwordx4 v[24:27], v[10:11], off offset:2064
	v_add_u32_e32 v2, s6, v2
	v_cmp_lt_i32_e32 vcc, s14, v2
	s_or_b64 s[12:13], vcc, s[12:13]
	v_lshl_add_u64 v[10:11], v[10:11], 0, s[10:11]
	s_waitcnt vmcnt(3)
	v_mov_b32_e32 v30, v13
	s_waitcnt vmcnt(2)
	v_mov_b32_e32 v31, v17
	v_mov_b32_e32 v32, v14
	v_mov_b32_e32 v33, v18
	s_waitcnt vmcnt(1)
	v_mov_b32_e32 v38, v21
	s_waitcnt vmcnt(0)
	v_mov_b32_e32 v39, v25
	v_mov_b32_e32 v40, v22
	v_mov_b32_e32 v41, v26
	v_mov_b32_e32 v28, v12
	v_mov_b32_e32 v29, v16
	v_mov_b32_e32 v34, v15
	v_mov_b32_e32 v35, v19
	v_mov_b32_e32 v36, v20
	v_mov_b32_e32 v37, v24
	v_mov_b32_e32 v42, v23
	v_mov_b32_e32 v43, v27
	v_mul_f32 v30, v30, v30
	v_mul_f32 v31, v31, v31
	v_mul_f32 v32, v32, v32
	v_mul_f32 v33, v33, v33
	v_mul_f32 v38, v38, v38
	v_mul_f32 v39, v39, v39
	v_mul_f32 v40, v40, v40
	v_mul_f32 v41, v41, v41
	v_fma_f32 v28, v28, v28, v30
	v_fma_f32 v29, v29, v29, v31
	v_fma_f32 v30, v34, v34, v32
	v_fma_f32 v31, v35, v35, v33
	v_fma_f32 v32, v36, v36, v38
	v_fma_f32 v33, v37, v37, v39
	v_fma_f32 v34, v42, v42, v40
	v_fma_f32 v35, v43, v43, v41
	v_add_f32 v28, v28, v30
	v_add_f32 v29, v29, v31
	v_add_f32 v30, v32, v34
	v_add_f32 v31, v33, v35
	s_nop 0
	v_add_f32 v28, v28, v30
	v_add_f32 v29, v29, v31
	s_nop 0
	v_add_f32_e32 v3, v28, v29
	ds_swizzle_b32 v28, v3 offset:swizzle(SWAP,1)
	s_waitcnt lgkmcnt(0)
	v_add_f32_e32 v3, v3, v28
	ds_swizzle_b32 v28, v3 offset:swizzle(SWAP,2)
	s_waitcnt lgkmcnt(0)
	v_add_f32_e32 v3, v3, v28
	ds_swizzle_b32 v28, v3 offset:swizzle(SWAP,4)
	s_waitcnt lgkmcnt(0)
	v_add_f32_e32 v3, v3, v28
	ds_swizzle_b32 v28, v3 offset:swizzle(SWAP,8)
	s_waitcnt lgkmcnt(0)
	v_add_f32_e32 v3, v3, v28
	ds_swizzle_b32 v28, v3 offset:swizzle(SWAP,16)
	s_waitcnt lgkmcnt(0)
	v_add_f32_e32 v3, v3, v28
	s_nop 0
	v_readlane_b32 s24, v3, 32
	v_readlane_b32 s15, v3, 0
	s_nop 0
	v_mov_b32_e32 v3, s24
	v_add_f32_e32 v3, s15, v3
	v_fmamk_f32 v3, v3, 0x3a800000, v1
	v_mul_f32_e32 v28, 0x4b800000, v3
	v_cmp_gt_f32_e32 vcc, s7, v3
	s_nop 1
	v_cndmask_b32_e32 v3, v3, v28, vcc
	v_rsq_f32_e32 v3, v3
	s_nop 0
	v_mul_f32_e32 v28, 0x45800000, v3
	v_cndmask_b32_e32 v28, v3, v28, vcc
	v_mul_f32 v14, v14, v28
	v_mul_f32 v15, v15, v28
	v_mul_f32 v12, v12, v28
	v_mul_f32 v13, v13, v28
	v_mul_f32 v22, v22, v28
	v_mul_f32 v23, v23, v28
	v_mul_f32 v20, v20, v28
	v_mul_f32 v21, v21, v28
	v_mul_f32 v18, v18, v28
	v_mul_f32 v19, v19, v28
	v_mul_f32 v16, v16, v28
	v_mul_f32 v17, v17, v28
	v_mul_f32 v26, v26, v28
	v_mul_f32 v27, v27, v28
	v_mul_f32 v24, v24, v28
	v_mul_f32 v25, v25, v28
	v_cvt_pk_bf16_f32 v12, v12, v13
	v_cvt_pk_bf16_f32 v13, v14, v15
	v_cvt_pk_bf16_f32 v14, v20, v21
	v_cvt_pk_bf16_f32 v15, v22, v23
	v_cvt_pk_bf16_f32 v16, v16, v17
	v_cvt_pk_bf16_f32 v17, v18, v19
	v_cvt_pk_bf16_f32 v18, v24, v25
	v_cvt_pk_bf16_f32 v19, v26, v27
	global_store_dwordx4 v[4:5], v[12:15], off offset:-1024
	global_store_dwordx4 v[4:5], v[16:19], off
	v_lshl_add_u64 v[4:5], v[4:5], 0, s[8:9]
	s_andn2_b64 exec, exec, s[12:13]
	s_cbranch_execnz .LBB0_17

.LBB0_248:
	v_ashrrev_i32_e32 v68, 3, v133
	v_subrev_u32_e32 v66, s1, v68
	s_add_i32 s1, s30, s95
	v_add_u32_e32 v69, s1, v66
	v_ashrrev_i32_e32 v66, 8, v69
	v_ashrrev_i32_e32 v67, 31, v66
	v_and_b32_e32 v70, 3, v68
	v_lshlrev_b32_e32 v71, 2, v68
	v_lshrrev_b32_e32 v68, 1, v69
	s_movk_i32 s1, 0x90
	v_lshlrev_b64 v[66:67], 8, v[66:67]
	v_and_b32_e32 v68, 0x6c, v68
	v_and_or_b32 v69, v71, s1, v70
	v_or3_b32 v68, v69, v68, v66
	v_add_u32_e32 v66, 0, v71
	s_and_b64 vcc, exec, s[12:13]
	v_mad_u32_u24 v66, v1, s92, v66
	s_waitcnt lgkmcnt(0)
	s_barrier
	s_cbranch_vccnz .LBB0_252
	ds_read2_b32 v[70:71], v66 offset1:65
	ds_read2_b32 v[72:73], v66 offset0:130 offset1:195
	v_add_u32_e32 v69, 0x400, v66
	ds_read2_b32 v[74:75], v69 offset0:4 offset1:69
	ds_read2_b32 v[76:77], v69 offset0:134 offset1:199
	v_add_u32_e32 v69, 0x4200, v66
	s_waitcnt lgkmcnt(3)
	v_mul_f32 v62, v62, v70
	v_mul_f32 v63, v63, v71
	s_waitcnt lgkmcnt(2)
	v_mul_f32 v64, v64, v72
	v_mul_f32 v65, v65, v73
	s_waitcnt lgkmcnt(1)
	v_mul_f32 v70, v58, v74
	v_mul_f32 v71, v59, v75
	v_cvt_pk_bf16_f32 v58, v62, v63
	v_mad_u64_u32 v[62:63], s[12:13], v68, s56, 0
	v_cvt_pk_bf16_f32 v59, v64, v65
	v_mov_b32_e32 v64, v63
	s_waitcnt lgkmcnt(0)
	v_mul_f32 v72, v60, v76
	v_mul_f32 v73, v61, v77
	v_cvt_pk_bf16_f32 v60, v70, v71
	v_mad_u64_u32 v[64:65], s[12:13], v67, s56, v[64:65]
	ds_read2_b32 v[70:71], v69 offset0:66 offset1:131
	v_add_u32_e32 v69, 0x4400, v66
	v_cvt_pk_bf16_f32 v61, v72, v73
	v_mov_b32_e32 v63, v64
	v_add_u32_e32 v64, 0x4000, v66
	ds_read2_b32 v[72:73], v69 offset0:68 offset1:133
	v_add_u32_e32 v69, 0x4600, v66
	ds_read2_b32 v[64:65], v64 offset0:64 offset1:129
	ds_read2_b32 v[74:75], v69 offset0:70 offset1:135
	v_or_b32_e32 v78, s86, v1
	v_lshl_add_u64 v[62:63], v[62:63], 1, s[76:77]
	v_ashrrev_i32_e32 v79, 31, v78
	v_lshl_add_u64 v[62:63], v[78:79], 1, v[62:63]
	global_store_dwordx4 v[62:63], v[58:61], off
	s_waitcnt lgkmcnt(1)
	v_mul_f32 v54, v54, v64
	v_mul_f32 v55, v55, v65
	v_mul_f32 v56, v56, v70
	v_mul_f32 v57, v57, v71
	v_mul_f32 v58, v26, v72
	v_mul_f32 v59, v27, v73
	s_waitcnt lgkmcnt(0)
	v_mul_f32 v60, v28, v74
	v_mul_f32 v61, v29, v75
	v_cvt_pk_bf16_f32 v26, v54, v55
	v_cvt_pk_bf16_f32 v27, v56, v57
	v_cvt_pk_bf16_f32 v28, v58, v59
	v_cvt_pk_bf16_f32 v29, v60, v61
	global_store_dwordx4 v[62:63], v[26:29], off offset:128
	s_and_b64 vcc, exec, s[10:11]
	s_cbranch_vccz .LBB0_253

.LBB0_251:
	v_add_u32_e32 v18, 0x10400, v66
	v_add_u32_e32 v19, 0x10504, v66
	v_add_u32_e32 v20, 0x10608, v66
	v_add_u32_e32 v21, 0x1070c, v66
	v_add_u32_e32 v26, 0x10810, v66
	v_add_u32_e32 v27, 0x10914, v66
	v_add_u32_e32 v28, 0x10a18, v66
	v_add_u32_e32 v29, 0x10b1c, v66
	ds_read_b32 v18, v18
	ds_read_b32 v19, v19
	ds_read_b32 v20, v20
	ds_read_b32 v21, v21
	ds_read_b32 v26, v26
	ds_read_b32 v27, v27
	ds_read_b32 v28, v28
	ds_read_b32 v29, v29
	s_waitcnt lgkmcnt(6)
	v_mul_f32 v18, v38, v18
	v_mul_f32 v19, v39, v19
	s_waitcnt lgkmcnt(4)
	v_mul_f32 v20, v40, v20
	v_mul_f32 v21, v41, v21
	s_waitcnt lgkmcnt(2)
	v_mul_f32 v26, v34, v26
	v_mul_f32 v27, v35, v27
	v_cvt_pk_bf16_f32 v18, v18, v19
	s_waitcnt lgkmcnt(0)
	v_mul_f32 v28, v36, v28
	v_mul_f32 v29, v37, v29
	v_cvt_pk_bf16_f32 v19, v20, v21
	v_cvt_pk_bf16_f32 v20, v26, v27
	v_mad_u64_u32 v[26:27], s[0:1], v68, s56, 0
	v_cvt_pk_bf16_f32 v21, v28, v29
	v_mov_b32_e32 v28, v27
	v_mad_u64_u32 v[28:29], s[0:1], v67, s56, v[28:29]
	v_mov_b32_e32 v27, v28
	v_add_u32_e32 v28, 0x14500, v66
	v_add_u32_e32 v29, 0x14604, v66
	v_add_u32_e32 v34, 0x14708, v66
	v_add_u32_e32 v35, 0x1480c, v66
	v_add_u32_e32 v36, 0x14910, v66
	v_add_u32_e32 v37, 0x14a14, v66
	v_add_u32_e32 v38, 0x14b18, v66
	v_add_u32_e32 v39, 0x14c1c, v66
	ds_read_b32 v28, v28
	ds_read_b32 v29, v29
	ds_read_b32 v34, v34
	ds_read_b32 v35, v35
	ds_read_b32 v36, v36
	ds_read_b32 v37, v37
	ds_read_b32 v38, v38
	ds_read_b32 v39, v39
	v_or_b32_e32 v42, s84, v1
	v_lshl_add_u64 v[26:27], v[26:27], 1, s[76:77]
	v_ashrrev_i32_e32 v43, 31, v42
	v_lshl_add_u64 v[26:27], v[42:43], 1, v[26:27]
	global_store_dwordx4 v[26:27], v[18:21], off
	s_waitcnt lgkmcnt(6)
	s_nop 0
	v_mul_f32 v18, v30, v28
	v_mul_f32 v19, v31, v29
	s_waitcnt lgkmcnt(4)
	v_mul_f32 v20, v32, v34
	v_mul_f32 v21, v33, v35
	s_waitcnt lgkmcnt(2)
	v_mul_f32 v28, v6, v36
	v_mul_f32 v29, v7, v37
	s_waitcnt lgkmcnt(0)
	v_mul_f32 v30, v8, v38
	v_mul_f32 v31, v9, v39
	v_cvt_pk_bf16_f32 v6, v18, v19
	v_cvt_pk_bf16_f32 v7, v20, v21
	v_cvt_pk_bf16_f32 v8, v28, v29
	v_cvt_pk_bf16_f32 v9, v30, v31
	global_store_dwordx4 v[26:27], v[6:9], off offset:128
	s_and_b64 vcc, exec, s[6:7]
	s_cbranch_vccnz .LBB0_167
	s_branch .LBB0_255

.LBB0_253:
	v_add_u32_e32 v26, 0x8000, v66
	v_add_u32_e32 v54, 0x8400, v66
	ds_read2_b32 v[26:27], v26 offset0:128 offset1:193
	ds_read2_b32 v[28:29], v54 offset0:2 offset1:67
	ds_read2_b32 v[54:55], v54 offset0:132 offset1:197
	v_add_u32_e32 v56, 0x8800, v66
	ds_read2_b32 v[56:57], v56 offset0:6 offset1:71
	v_or_b32_e32 v58, s0, v1
	s_waitcnt lgkmcnt(3)
	v_mul_f32 v26, v50, v26
	v_mul_f32 v27, v51, v27
	s_waitcnt lgkmcnt(2)
	v_mul_f32 v28, v52, v28
	v_mul_f32 v29, v53, v29
	s_waitcnt lgkmcnt(1)
	v_mul_f32 v46, v46, v54
	v_mul_f32 v47, v47, v55
	s_waitcnt lgkmcnt(0)
	v_mul_f32 v48, v48, v56
	v_mul_f32 v49, v49, v57
	v_cvt_pk_bf16_f32 v26, v26, v27
	v_cvt_pk_bf16_f32 v27, v28, v29
	v_cvt_pk_bf16_f32 v28, v46, v47
	v_mad_u64_u32 v[46:47], s[0:1], v68, s56, 0
	v_cvt_pk_bf16_f32 v29, v48, v49
	v_mov_b32_e32 v48, v47
	v_mad_u64_u32 v[48:49], s[0:1], v67, s56, v[48:49]
	v_mov_b32_e32 v47, v48
	v_add_u32_e32 v48, 0xc200, v66
	v_add_u32_e32 v50, 0xc400, v66
	v_add_u32_e32 v52, 0xc600, v66
	v_add_u32_e32 v54, 0xc800, v66
	ds_read2_b32 v[48:49], v48 offset0:64 offset1:129
	ds_read2_b32 v[50:51], v50 offset0:66 offset1:131
	ds_read2_b32 v[52:53], v52 offset0:68 offset1:133
	ds_read2_b32 v[54:55], v54 offset0:70 offset1:135
	v_lshl_add_u64 v[46:47], v[46:47], 1, s[76:77]
	v_ashrrev_i32_e32 v59, 31, v58
	v_lshl_add_u64 v[46:47], v[58:59], 1, v[46:47]
	global_store_dwordx4 v[46:47], v[26:29], off
	s_waitcnt lgkmcnt(3)
	s_nop 0
	v_mul_f32 v26, v42, v48
	v_mul_f32 v27, v43, v49
	s_waitcnt lgkmcnt(2)
	v_mul_f32 v28, v44, v50
	v_mul_f32 v29, v45, v51
	s_waitcnt lgkmcnt(1)
	v_mul_f32 v42, v18, v52
	v_mul_f32 v43, v19, v53
	s_waitcnt lgkmcnt(0)
	v_mul_f32 v44, v20, v54
	v_mul_f32 v45, v21, v55
	v_cvt_pk_bf16_f32 v18, v26, v27
	v_cvt_pk_bf16_f32 v19, v28, v29
	v_cvt_pk_bf16_f32 v20, v42, v43
	v_cvt_pk_bf16_f32 v21, v44, v45
	global_store_dwordx4 v[46:47], v[18:21], off offset:128
	s_and_b64 vcc, exec, s[8:9]
	s_cbranch_vccz .LBB0_251

.LBB0_255:
	v_add_u32_e32 v6, 0x18600, v66
	v_add_u32_e32 v7, 0x18704, v66
	v_add_u32_e32 v8, 0x18808, v66
	v_add_u32_e32 v9, 0x1890c, v66
	v_add_u32_e32 v18, 0x18a10, v66
	v_add_u32_e32 v19, 0x18b14, v66
	v_add_u32_e32 v20, 0x18c18, v66
	v_add_u32_e32 v21, 0x18d1c, v66
	ds_read_b32 v6, v6
	ds_read_b32 v7, v7
	ds_read_b32 v8, v8
	ds_read_b32 v9, v9
	ds_read_b32 v18, v18
	ds_read_b32 v19, v19
	ds_read_b32 v20, v20
	ds_read_b32 v21, v21
	s_waitcnt lgkmcnt(6)
	v_mul_f32 v6, v22, v6
	v_mul_f32 v7, v23, v7
	s_waitcnt lgkmcnt(4)
	v_mul_f32 v8, v24, v8
	v_mul_f32 v9, v25, v9
	s_waitcnt lgkmcnt(2)
	v_mul_f32 v14, v14, v18
	v_mul_f32 v15, v15, v19
	v_cvt_pk_bf16_f32 v6, v6, v7
	s_waitcnt lgkmcnt(0)
	v_mul_f32 v16, v16, v20
	v_mul_f32 v17, v17, v21
	v_cvt_pk_bf16_f32 v7, v8, v9
	v_cvt_pk_bf16_f32 v8, v14, v15
	v_mad_u64_u32 v[14:15], s[0:1], v68, s56, 0
	v_cvt_pk_bf16_f32 v9, v16, v17
	v_mov_b32_e32 v16, v15
	v_mad_u64_u32 v[16:17], s[0:1], v67, s56, v[16:17]
	v_or_b32_e32 v26, s82, v1
	v_add_u32_e32 v1, 0x1c700, v66
	v_add_u32_e32 v17, 0x1c804, v66
	v_add_u32_e32 v18, 0x1c908, v66
	v_add_u32_e32 v19, 0x1ca0c, v66
	v_add_u32_e32 v20, 0x1cb10, v66
	v_add_u32_e32 v21, 0x1cc14, v66
	v_add_u32_e32 v22, 0x1cd18, v66
	v_add_u32_e32 v23, 0x1ce1c, v66
	v_mov_b32_e32 v15, v16
	ds_read_b32 v16, v1
	ds_read_b32 v17, v17
	ds_read_b32 v18, v18
	ds_read_b32 v19, v19
	ds_read_b32 v20, v20
	ds_read_b32 v21, v21
	ds_read_b32 v22, v22
	ds_read_b32 v23, v23
	v_lshl_add_u64 v[14:15], v[14:15], 1, s[76:77]
	v_ashrrev_i32_e32 v27, 31, v26
	v_lshl_add_u64 v[14:15], v[26:27], 1, v[14:15]
	global_store_dwordx4 v[14:15], v[6:9], off
	s_waitcnt lgkmcnt(6)
	s_nop 0
	v_mul_f32 v6, v10, v16
	v_mul_f32 v7, v11, v17
	s_waitcnt lgkmcnt(4)
	v_mul_f32 v8, v12, v18
	v_mul_f32 v9, v13, v19
	s_waitcnt lgkmcnt(2)
	v_mul_f32 v10, v2, v20
	v_mul_f32 v11, v3, v21
	s_waitcnt lgkmcnt(0)
	v_mul_f32 v12, v4, v22
	v_mul_f32 v13, v5, v23
	v_cvt_pk_bf16_f32 v2, v6, v7
	v_cvt_pk_bf16_f32 v3, v8, v9
	v_cvt_pk_bf16_f32 v4, v10, v11
	v_cvt_pk_bf16_f32 v5, v12, v13
	global_store_dwordx4 v[14:15], v[2:5], off offset:128
	s_branch .LBB0_167

.LBB0_330:
	s_lshl_b64 s[0:1], s[38:39], 2
	s_add_u32 s0, s12, s0
	s_addc_u32 s1, s13, s1
	global_load_dwordx4 v[20:23], v134, s[0:1]
	global_load_dwordx4 v[24:27], v134, s[0:1] offset:16
	v_mov_b32_e32 v30, v15
	v_mov_b32_e32 v31, v7
	v_mov_b32_e32 v34, v17
	v_mov_b32_e32 v35, v9
	v_mov_b32_e32 v38, v11
	v_mov_b32_e32 v39, v3
	v_mov_b32_e32 v42, v13
	v_mov_b32_e32 v43, v5
	v_mov_b32_e32 v28, v14
	v_mov_b32_e32 v29, v6
	v_mov_b32_e32 v32, v16
	v_mov_b32_e32 v33, v8
	v_mov_b32_e32 v36, v10
	v_mov_b32_e32 v37, v2
	v_mov_b32_e32 v40, v12
	v_mov_b32_e32 v41, v4
	v_mul_f32 v30, v30, v30
	v_mul_f32 v31, v31, v31
	v_mul_f32 v34, v34, v34
	v_mul_f32 v35, v35, v35
	v_mul_f32 v38, v38, v38
	v_mul_f32 v39, v39, v39
	v_mul_f32 v42, v42, v42
	v_mul_f32 v43, v43, v43
	v_fma_f32 v28, v28, v28, v30
	v_fma_f32 v29, v29, v29, v31
	v_fma_f32 v30, v32, v32, v34
	v_fma_f32 v31, v33, v33, v35
	v_fma_f32 v32, v36, v36, v38
	v_fma_f32 v33, v37, v37, v39
	v_fma_f32 v34, v40, v40, v42
	v_fma_f32 v35, v41, v41, v43
	v_add_f32 v28, v28, v30
	v_add_f32 v29, v29, v31
	v_add_f32 v30, v32, v34
	v_add_f32 v31, v33, v35
	v_and_b32_e32 v45, 64, v148
	v_add_f32 v28, v28, v30
	v_add_f32 v29, v29, v31
	v_xor_b32_e32 v44, 32, v148
	v_add_f32_e32 v28, v28, v29
	ds_swizzle_b32 v29, v28 offset:swizzle(SWAP,16)
	v_add_u32_e32 v30, 64, v45
	v_cmp_lt_i32_e32 vcc, v44, v30
	v_mov_b32_e32 v139, v135
	v_mov_b32_e32 v137, v135
	v_cndmask_b32_e32 v30, v148, v44, vcc
	v_lshlrev_b32_e32 v30, 2, v30
	s_waitcnt lgkmcnt(0)
	v_add_f32_e32 v32, v28, v29
	ds_bpermute_b32 v33, v30, v32
	v_lshl_add_u64 v[28:29], v[18:19], 2, s[14:15]
	v_lshl_add_u64 v[30:31], v[18:19], 1, s[18:19]
	v_lshl_add_u64 v[28:29], v[28:29], 0, v[134:135]
	v_lshl_add_u64 v[30:31], v[30:31], 0, v[138:139]
	s_waitcnt lgkmcnt(0)
	v_add_f32_e32 v32, v32, v33
	v_fmamk_f32 v32, v32, 0x3c800000, v147
	v_mul_f32_e32 v33, 0x4b800000, v32
	v_cmp_gt_f32_e32 vcc, s64, v32
	s_mov_b64 s[6:7], 0x1a923c00
	s_nop 0
	v_cndmask_b32_e32 v32, v32, v33, vcc
	v_rsq_f32_e32 v32, v32
	s_nop 0
	v_mul_f32_e32 v33, 0x45800000, v32
	v_cndmask_b32_e32 v32, v32, v33, vcc
	v_mul_f32 v14, v14, v32
	v_mul_f32 v15, v15, v32
	v_mul_f32 v16, v16, v32
	v_mul_f32 v17, v17, v32
	v_mul_f32 v34, v10, v32
	v_mul_f32 v35, v11, v32
	v_mul_f32 v36, v12, v32
	v_mul_f32 v37, v13, v32
	v_mul_f32 v8, v8, v32
	v_mul_f32 v9, v9, v32
	v_mul_f32 v6, v6, v32
	v_mul_f32 v7, v7, v32
	v_mul_f32 v4, v4, v32
	v_mul_f32 v5, v5, v32
	v_mul_f32 v2, v2, v32
	v_mul_f32 v3, v3, v32
	s_waitcnt vmcnt(0)
	v_mul_f32 v12, v22, v16
	v_mul_f32 v13, v23, v17
	v_mul_f32 v10, v20, v14
	v_mul_f32 v11, v21, v15
	v_mul_f32 v16, v26, v36
	v_mul_f32 v17, v27, v37
	v_mul_f32 v14, v24, v34
	v_mul_f32 v15, v25, v35
	global_store_dwordx4 v[28:29], v[10:13], off
	global_store_dwordx4 v[28:29], v[14:17], off offset:16
	s_nop 0
	v_cvt_pk_bf16_f32 v10, v10, v11
	v_cvt_pk_bf16_f32 v11, v12, v13
	v_cvt_pk_bf16_f32 v12, v14, v15
	v_cvt_pk_bf16_f32 v13, v16, v17
	global_store_dwordx4 v[30:31], v[10:13], off
	global_load_dwordx4 v[10:13], v134, s[0:1] offset:128
	s_nop 0
	global_load_dwordx4 v[14:17], v134, s[0:1] offset:144
	s_mov_b64 s[0:1], 0x56cc000
	s_waitcnt vmcnt(1)
	v_mul_f32 v6, v10, v6
	v_mul_f32 v7, v11, v7
	v_mul_f32 v8, v12, v8
	v_mul_f32 v9, v13, v9
	s_waitcnt vmcnt(0)
	v_mul_f32 v2, v14, v2
	v_mul_f32 v3, v15, v3
	v_mul_f32 v4, v16, v4
	v_mul_f32 v5, v17, v5
	global_store_dwordx4 v[28:29], v[6:9], off offset:128

.LBB0_342:
	s_lshl_b32 s38, s38, 6
	s_andn2_b64 vcc, exec, s[6:7]
	s_ashr_i32 s39, s38, 31
	s_cbranch_vccnz .LBB0_344
	v_mov_b32_e32 v152, v127
	v_mov_b32_e32 v153, v119
	v_mov_b32_e32 v150, v126
	v_mov_b32_e32 v151, v118
	v_mul_f32 v152, v152, v152
	v_mul_f32 v153, v153, v153
	v_mov_b32_e32 v154, v129
	v_mov_b32_e32 v155, v121
	v_fma_f32 v150, v150, v150, v152
	v_fma_f32 v151, v151, v151, v153
	v_mov_b32_e32 v152, v128
	v_mov_b32_e32 v153, v120
	v_mul_f32 v154, v154, v154
	v_mul_f32 v155, v155, v155
	v_mov_b32_e32 v156, v125
	v_fma_f32 v152, v152, v152, v154
	v_fma_f32 v153, v153, v153, v155
	v_mov_b32_e32 v154, v123
	v_mov_b32_e32 v155, v115
	v_add_f32 v150, v150, v152
	v_add_f32 v151, v151, v153
	v_mov_b32_e32 v152, v122
	v_mov_b32_e32 v153, v114
	v_mul_f32 v154, v154, v154
	v_mul_f32 v155, v155, v155
	v_mov_b32_e32 v157, v117
	v_fma_f32 v152, v152, v152, v154
	v_fma_f32 v153, v153, v153, v155
	v_mov_b32_e32 v154, v124
	v_mov_b32_e32 v155, v116
	v_mul_f32 v156, v156, v156
	v_mul_f32 v157, v157, v157
	v_and_b32_e32 v141, 64, v148
	v_fma_f32 v154, v154, v154, v156
	v_fma_f32 v155, v155, v155, v157
	v_add_u32_e32 v141, 64, v141
	v_add_f32 v152, v152, v154
	v_add_f32 v153, v153, v155
	s_lshl_b64 s[6:7], s[38:39], 2
	v_add_f32 v150, v150, v152
	v_add_f32 v151, v151, v153
	s_add_u32 s6, s12, s6
	v_add_f32_e32 v137, v150, v151
	ds_swizzle_b32 v139, v137 offset:swizzle(SWAP,16)
	s_addc_u32 s7, s13, s7
	s_mov_b64 s[42:43], 0x1a923c00
	s_waitcnt lgkmcnt(0)
	v_add_f32_e32 v137, v137, v139
	v_xor_b32_e32 v139, 32, v148
	v_cmp_lt_i32_e32 vcc, v139, v141
	s_nop 1
	v_cndmask_b32_e32 v139, v148, v139, vcc
	v_lshlrev_b32_e32 v139, 2, v139
	ds_bpermute_b32 v139, v139, v137
	s_waitcnt lgkmcnt(0)
	v_add_f32_e32 v137, v137, v139
	v_fmamk_f32 v137, v137, 0x3c800000, v147
	v_cmp_gt_f32_e32 vcc, s64, v137
	v_mul_f32_e32 v139, 0x4b800000, v137
	s_nop 0
	v_cndmask_b32_e32 v137, v137, v139, vcc
	v_rsq_f32_e32 v137, v137
	s_nop 0
	v_mul_f32_e32 v139, 0x45800000, v137
	v_cndmask_b32_e32 v154, v137, v139, vcc
	v_mul_f32 v156, v126, v154
	v_mul_f32 v157, v127, v154
	v_mul_f32 v158, v128, v154
	v_mul_f32 v159, v129, v154
	global_load_dwordx4 v[126:129], v134, s[6:7] offset:16
	global_load_dwordx4 v[150:153], v134, s[6:7]
	v_mul_f32 v122, v122, v154
	v_mul_f32 v123, v123, v154
	v_mul_f32 v124, v124, v154
	v_mul_f32 v125, v125, v154
	v_mov_b32_e32 v139, v135
	v_mul_f32 v116, v116, v154
	v_mul_f32 v117, v117, v154
	v_mul_f32 v114, v114, v154
	v_mul_f32 v115, v115, v154
	v_mov_b32_e32 v137, v135
	s_waitcnt vmcnt(0)
	v_mul_f32 v122, v126, v122
	v_mul_f32 v123, v127, v123
	v_lshl_add_u64 v[126:127], v[142:143], 2, s[14:15]
	v_mul_f32 v152, v152, v158
	v_mul_f32 v153, v153, v159
	v_mul_f32 v150, v150, v156
	v_mul_f32 v151, v151, v157
	v_mul_f32 v124, v128, v124
	v_mul_f32 v125, v129, v125
	v_lshl_add_u64 v[156:157], v[126:127], 0, v[134:135]
	v_lshl_add_u64 v[126:127], v[142:143], 1, s[18:19]
	v_lshl_add_u64 v[158:159], v[126:127], 0, v[138:139]
	v_cvt_pk_bf16_f32 v126, v150, v151
	v_cvt_pk_bf16_f32 v127, v152, v153
	v_cvt_pk_bf16_f32 v128, v122, v123
	v_cvt_pk_bf16_f32 v129, v124, v125
	global_store_dwordx4 v[156:157], v[150:153], off
	global_store_dwordx4 v[156:157], v[122:125], off offset:16
	global_store_dwordx4 v[158:159], v[126:129], off
	s_nop 1
	v_mul_f32 v126, v120, v154
	v_mul_f32 v127, v121, v154
	v_mul_f32 v128, v118, v154
	v_mul_f32 v129, v119, v154
	global_load_dwordx4 v[122:125], v134, s[6:7] offset:144
	global_load_dwordx4 v[118:121], v134, s[6:7] offset:128
	s_mov_b64 s[6:7], 0x56cc000
	s_waitcnt vmcnt(1)
	v_mul_f32 v114, v122, v114
	v_mul_f32 v115, v123, v115
	s_waitcnt vmcnt(0)
	v_mul_f32 v118, v118, v128
	v_mul_f32 v119, v119, v129
	v_mul_f32 v120, v120, v126
	v_mul_f32 v121, v121, v127
	v_mul_f32 v116, v124, v116
	v_mul_f32 v117, v125, v117
	global_store_dwordx4 v[156:157], v[118:121], off offset:128
	s_branch .LBB0_345

.LBB0_347:
	s_andn2_b64 vcc, exec, s[0:1]
	s_cbranch_vccnz .LBB0_349
	s_lshl_b64 s[0:1], s[38:39], 2
	s_add_u32 s0, s12, s0
	s_addc_u32 s1, s13, s1
	global_load_dwordx4 v[116:119], v134, s[0:1]
	global_load_dwordx4 v[120:123], v134, s[0:1] offset:16
	v_mov_b32_e32 v126, v111
	v_mov_b32_e32 v127, v103
	v_mov_b32_e32 v142, v113
	v_mov_b32_e32 v143, v105
	v_mov_b32_e32 v152, v107
	v_mov_b32_e32 v153, v99
	v_mov_b32_e32 v156, v109
	v_mov_b32_e32 v157, v101
	v_mov_b32_e32 v124, v110
	v_mov_b32_e32 v125, v102
	v_mov_b32_e32 v128, v112
	v_mov_b32_e32 v129, v104
	v_mov_b32_e32 v150, v106
	v_mov_b32_e32 v151, v98
	v_mov_b32_e32 v154, v108
	v_mov_b32_e32 v155, v100
	v_mul_f32 v126, v126, v126
	v_mul_f32 v127, v127, v127
	v_mul_f32 v142, v142, v142
	v_mul_f32 v143, v143, v143
	v_mul_f32 v152, v152, v152
	v_mul_f32 v153, v153, v153
	v_mul_f32 v156, v156, v156
	v_mul_f32 v157, v157, v157
	v_fma_f32 v124, v124, v124, v126
	v_fma_f32 v125, v125, v125, v127
	v_fma_f32 v126, v128, v128, v142
	v_fma_f32 v127, v129, v129, v143
	v_fma_f32 v128, v150, v150, v152
	v_fma_f32 v129, v151, v151, v153
	v_fma_f32 v142, v154, v154, v156
	v_fma_f32 v143, v155, v155, v157
	v_add_f32 v124, v124, v126
	v_add_f32 v125, v125, v127
	v_add_f32 v126, v128, v142
	v_add_f32 v127, v129, v143
	v_and_b32_e32 v139, 64, v148
	v_add_f32 v124, v124, v126
	v_add_f32 v125, v125, v127
	v_xor_b32_e32 v137, 32, v148
	v_add_f32_e32 v124, v124, v125
	ds_swizzle_b32 v125, v124 offset:swizzle(SWAP,16)
	v_add_u32_e32 v126, 64, v139
	v_cmp_lt_i32_e32 vcc, v137, v126
	v_mov_b32_e32 v139, v135
	s_mov_b64 s[42:43], 0x1a923c00
	v_cndmask_b32_e32 v126, v148, v137, vcc
	v_lshlrev_b32_e32 v126, 2, v126
	s_waitcnt lgkmcnt(0)
	v_add_f32_e32 v128, v124, v125
	ds_bpermute_b32 v129, v126, v128
	v_lshl_add_u64 v[124:125], v[114:115], 2, s[14:15]
	v_lshl_add_u64 v[126:127], v[114:115], 1, s[18:19]
	v_lshl_add_u64 v[124:125], v[124:125], 0, v[134:135]
	v_lshl_add_u64 v[126:127], v[126:127], 0, v[138:139]
	s_waitcnt lgkmcnt(0)
	v_add_f32_e32 v128, v128, v129
	v_fmamk_f32 v128, v128, 0x3c800000, v147
	v_mul_f32_e32 v129, 0x4b800000, v128
	v_cmp_gt_f32_e32 vcc, s64, v128
	v_mov_b32_e32 v137, v135
	s_nop 0
	v_cndmask_b32_e32 v128, v128, v129, vcc
	v_rsq_f32_e32 v128, v128
	s_nop 0
	v_mul_f32_e32 v129, 0x45800000, v128
	v_cndmask_b32_e32 v128, v128, v129, vcc
	v_mul_f32 v110, v110, v128
	v_mul_f32 v111, v111, v128
	v_mul_f32 v112, v112, v128
	v_mul_f32 v113, v113, v128
	v_mul_f32 v142, v106, v128
	v_mul_f32 v143, v107, v128
	v_mul_f32 v150, v108, v128
	v_mul_f32 v151, v109, v128
	v_mul_f32 v104, v104, v128
	v_mul_f32 v105, v105, v128
	v_mul_f32 v102, v102, v128
	v_mul_f32 v103, v103, v128
	v_mul_f32 v100, v100, v128
	v_mul_f32 v101, v101, v128
	v_mul_f32 v98, v98, v128
	v_mul_f32 v99, v99, v128
	s_waitcnt vmcnt(0)
	v_mul_f32 v108, v118, v112
	v_mul_f32 v109, v119, v113
	v_mul_f32 v106, v116, v110
	v_mul_f32 v107, v117, v111
	v_mul_f32 v112, v122, v150
	v_mul_f32 v113, v123, v151
	v_mul_f32 v110, v120, v142
	v_mul_f32 v111, v121, v143
	global_store_dwordx4 v[124:125], v[106:109], off
	global_store_dwordx4 v[124:125], v[110:113], off offset:16
	s_nop 0
	v_cvt_pk_bf16_f32 v106, v106, v107
	v_cvt_pk_bf16_f32 v107, v108, v109
	v_cvt_pk_bf16_f32 v108, v110, v111
	v_cvt_pk_bf16_f32 v109, v112, v113
	global_store_dwordx4 v[126:127], v[106:109], off
	global_load_dwordx4 v[106:109], v134, s[0:1] offset:128
	s_nop 0
	global_load_dwordx4 v[110:113], v134, s[0:1] offset:144
	s_mov_b64 s[0:1], 0x56cc000
	s_waitcnt vmcnt(1)
	v_mul_f32 v102, v106, v102
	v_mul_f32 v103, v107, v103
	v_mul_f32 v104, v108, v104
	v_mul_f32 v105, v109, v105
	s_waitcnt vmcnt(0)
	v_mul_f32 v98, v110, v98
	v_mul_f32 v99, v111, v99
	v_mul_f32 v100, v112, v100
	v_mul_f32 v101, v113, v101
	global_store_dwordx4 v[124:125], v[102:105], off offset:128
	s_branch .LBB0_350

.LBB0_352:
	s_andn2_b64 vcc, exec, s[0:1]
	s_cbranch_vccnz .LBB0_354
	s_lshl_b64 s[0:1], s[38:39], 2
	s_add_u32 s0, s12, s0
	s_addc_u32 s1, s13, s1
	global_load_dwordx4 v[100:103], v134, s[0:1]
	global_load_dwordx4 v[104:107], v134, s[0:1] offset:16
	v_mov_b32_e32 v110, v95
	v_mov_b32_e32 v111, v87
	v_mov_b32_e32 v114, v97
	v_mov_b32_e32 v115, v89
	v_mov_b32_e32 v118, v91
	v_mov_b32_e32 v119, v83
	v_mov_b32_e32 v122, v93
	v_mov_b32_e32 v123, v85
	v_mov_b32_e32 v108, v94
	v_mov_b32_e32 v109, v86
	v_mov_b32_e32 v112, v96
	v_mov_b32_e32 v113, v88
	v_mov_b32_e32 v116, v90
	v_mov_b32_e32 v117, v82
	v_mov_b32_e32 v120, v92
	v_mov_b32_e32 v121, v84
	v_mul_f32 v110, v110, v110
	v_mul_f32 v111, v111, v111
	v_mul_f32 v114, v114, v114
	v_mul_f32 v115, v115, v115
	v_mul_f32 v118, v118, v118
	v_mul_f32 v119, v119, v119
	v_mul_f32 v122, v122, v122
	v_mul_f32 v123, v123, v123
	v_fma_f32 v108, v108, v108, v110
	v_fma_f32 v109, v109, v109, v111
	v_fma_f32 v110, v112, v112, v114
	v_fma_f32 v111, v113, v113, v115
	v_fma_f32 v112, v116, v116, v118
	v_fma_f32 v113, v117, v117, v119
	v_fma_f32 v114, v120, v120, v122
	v_fma_f32 v115, v121, v121, v123
	v_add_f32 v108, v108, v110
	v_add_f32 v109, v109, v111
	v_add_f32 v110, v112, v114
	v_add_f32 v111, v113, v115
	v_and_b32_e32 v125, 64, v148
	v_add_f32 v108, v108, v110
	v_add_f32 v109, v109, v111
	v_xor_b32_e32 v124, 32, v148
	v_add_f32_e32 v108, v108, v109
	ds_swizzle_b32 v109, v108 offset:swizzle(SWAP,16)
	v_add_u32_e32 v110, 64, v125
	v_cmp_lt_i32_e32 vcc, v124, v110
	v_mov_b32_e32 v139, v135
	v_mov_b32_e32 v137, v135
	v_cndmask_b32_e32 v110, v148, v124, vcc
	v_lshlrev_b32_e32 v110, 2, v110
	s_waitcnt lgkmcnt(0)
	v_add_f32_e32 v112, v108, v109
	ds_bpermute_b32 v113, v110, v112
	v_lshl_add_u64 v[108:109], v[98:99], 2, s[14:15]
	v_lshl_add_u64 v[110:111], v[98:99], 1, s[18:19]
	v_lshl_add_u64 v[108:109], v[108:109], 0, v[134:135]
	v_lshl_add_u64 v[110:111], v[110:111], 0, v[138:139]
	s_waitcnt lgkmcnt(0)
	v_add_f32_e32 v112, v112, v113
	v_fmamk_f32 v112, v112, 0x3c800000, v147
	v_mul_f32_e32 v113, 0x4b800000, v112
	v_cmp_gt_f32_e32 vcc, s64, v112
	s_mov_b64 s[42:43], 0x1a923c00
	s_nop 0
	v_cndmask_b32_e32 v112, v112, v113, vcc
	v_rsq_f32_e32 v112, v112
	s_nop 0
	v_mul_f32_e32 v113, 0x45800000, v112
	v_cndmask_b32_e32 v112, v112, v113, vcc
	v_mul_f32 v94, v94, v112
	v_mul_f32 v95, v95, v112
	v_mul_f32 v96, v96, v112
	v_mul_f32 v97, v97, v112
	v_mul_f32 v114, v90, v112
	v_mul_f32 v115, v91, v112
	v_mul_f32 v116, v92, v112
	v_mul_f32 v117, v93, v112
	v_mul_f32 v88, v88, v112
	v_mul_f32 v89, v89, v112
	v_mul_f32 v86, v86, v112
	v_mul_f32 v87, v87, v112
	v_mul_f32 v84, v84, v112
	v_mul_f32 v85, v85, v112
	v_mul_f32 v82, v82, v112
	v_mul_f32 v83, v83, v112
	s_waitcnt vmcnt(0)
	v_mul_f32 v92, v102, v96
	v_mul_f32 v93, v103, v97
	v_mul_f32 v90, v100, v94
	v_mul_f32 v91, v101, v95
	v_mul_f32 v96, v106, v116
	v_mul_f32 v97, v107, v117
	v_mul_f32 v94, v104, v114
	v_mul_f32 v95, v105, v115
	global_store_dwordx4 v[108:109], v[90:93], off
	global_store_dwordx4 v[108:109], v[94:97], off offset:16
	s_nop 0
	v_cvt_pk_bf16_f32 v90, v90, v91
	v_cvt_pk_bf16_f32 v91, v92, v93
	v_cvt_pk_bf16_f32 v92, v94, v95
	v_cvt_pk_bf16_f32 v93, v96, v97
	global_store_dwordx4 v[110:111], v[90:93], off
	global_load_dwordx4 v[90:93], v134, s[0:1] offset:128
	s_nop 0
	global_load_dwordx4 v[94:97], v134, s[0:1] offset:144
	s_mov_b64 s[0:1], 0x56cc000
	s_waitcnt vmcnt(1)
	v_mul_f32 v86, v90, v86
	v_mul_f32 v87, v91, v87
	v_mul_f32 v88, v92, v88
	v_mul_f32 v89, v93, v89
	s_waitcnt vmcnt(0)
	v_mul_f32 v82, v94, v82
	v_mul_f32 v83, v95, v83
	v_mul_f32 v84, v96, v84
	v_mul_f32 v85, v97, v85
	global_store_dwordx4 v[108:109], v[86:89], off offset:128
	s_branch .LBB0_355

.LBB0_357:
	s_andn2_b64 vcc, exec, s[0:1]
	s_cbranch_vccnz .LBB0_359
	s_lshl_b64 s[0:1], s[38:39], 2
	s_add_u32 s0, s12, s0
	s_addc_u32 s1, s13, s1
	global_load_dwordx4 v[84:87], v134, s[0:1]
	global_load_dwordx4 v[88:91], v134, s[0:1] offset:16
	v_mov_b32_e32 v94, v79
	v_mov_b32_e32 v95, v71
	v_mov_b32_e32 v98, v81
	v_mov_b32_e32 v99, v73
	v_mov_b32_e32 v102, v75
	v_mov_b32_e32 v103, v67
	v_mov_b32_e32 v106, v77
	v_mov_b32_e32 v107, v69
	v_mov_b32_e32 v92, v78
	v_mov_b32_e32 v93, v70
	v_mov_b32_e32 v96, v80
	v_mov_b32_e32 v97, v72
	v_mov_b32_e32 v100, v74
	v_mov_b32_e32 v101, v66
	v_mov_b32_e32 v104, v76
	v_mov_b32_e32 v105, v68
	v_mul_f32 v94, v94, v94
	v_mul_f32 v95, v95, v95
	v_mul_f32 v98, v98, v98
	v_mul_f32 v99, v99, v99
	v_mul_f32 v102, v102, v102
	v_mul_f32 v103, v103, v103
	v_mul_f32 v106, v106, v106
	v_mul_f32 v107, v107, v107
	v_fma_f32 v92, v92, v92, v94
	v_fma_f32 v93, v93, v93, v95
	v_fma_f32 v94, v96, v96, v98
	v_fma_f32 v95, v97, v97, v99
	v_fma_f32 v96, v100, v100, v102
	v_fma_f32 v97, v101, v101, v103
	v_fma_f32 v98, v104, v104, v106
	v_fma_f32 v99, v105, v105, v107
	v_add_f32 v92, v92, v94
	v_add_f32 v93, v93, v95
	v_add_f32 v94, v96, v98
	v_add_f32 v95, v97, v99
	v_and_b32_e32 v109, 64, v148
	v_add_f32 v92, v92, v94
	v_add_f32 v93, v93, v95
	v_xor_b32_e32 v108, 32, v148
	v_add_f32_e32 v92, v92, v93
	ds_swizzle_b32 v93, v92 offset:swizzle(SWAP,16)
	v_add_u32_e32 v94, 64, v109
	v_cmp_lt_i32_e32 vcc, v108, v94
	v_mov_b32_e32 v139, v135
	v_mov_b32_e32 v137, v135
	v_cndmask_b32_e32 v94, v148, v108, vcc
	v_lshlrev_b32_e32 v94, 2, v94
	s_waitcnt lgkmcnt(0)
	v_add_f32_e32 v96, v92, v93
	ds_bpermute_b32 v97, v94, v96
	v_lshl_add_u64 v[92:93], v[82:83], 2, s[14:15]
	v_lshl_add_u64 v[94:95], v[82:83], 1, s[18:19]
	v_lshl_add_u64 v[92:93], v[92:93], 0, v[134:135]
	v_lshl_add_u64 v[94:95], v[94:95], 0, v[138:139]
	s_waitcnt lgkmcnt(0)
	v_add_f32_e32 v96, v96, v97
	v_fmamk_f32 v96, v96, 0x3c800000, v147
	v_mul_f32_e32 v97, 0x4b800000, v96
	v_cmp_gt_f32_e32 vcc, s64, v96
	s_mov_b64 s[42:43], 0x1a923c00
	s_nop 0
	v_cndmask_b32_e32 v96, v96, v97, vcc
	v_rsq_f32_e32 v96, v96
	s_nop 0
	v_mul_f32_e32 v97, 0x45800000, v96
	v_cndmask_b32_e32 v96, v96, v97, vcc
	v_mul_f32 v78, v78, v96
	v_mul_f32 v79, v79, v96
	v_mul_f32 v80, v80, v96
	v_mul_f32 v81, v81, v96
	v_mul_f32 v98, v74, v96
	v_mul_f32 v99, v75, v96
	v_mul_f32 v100, v76, v96
	v_mul_f32 v101, v77, v96
	v_mul_f32 v72, v72, v96
	v_mul_f32 v73, v73, v96
	v_mul_f32 v70, v70, v96
	v_mul_f32 v71, v71, v96
	v_mul_f32 v68, v68, v96
	v_mul_f32 v69, v69, v96
	v_mul_f32 v66, v66, v96
	v_mul_f32 v67, v67, v96
	s_waitcnt vmcnt(0)
	v_mul_f32 v76, v86, v80
	v_mul_f32 v77, v87, v81
	v_mul_f32 v74, v84, v78
	v_mul_f32 v75, v85, v79
	v_mul_f32 v80, v90, v100
	v_mul_f32 v81, v91, v101
	v_mul_f32 v78, v88, v98
	v_mul_f32 v79, v89, v99
	global_store_dwordx4 v[92:93], v[74:77], off
	global_store_dwordx4 v[92:93], v[78:81], off offset:16
	s_nop 0
	v_cvt_pk_bf16_f32 v74, v74, v75
	v_cvt_pk_bf16_f32 v75, v76, v77
	v_cvt_pk_bf16_f32 v76, v78, v79
	v_cvt_pk_bf16_f32 v77, v80, v81
	global_store_dwordx4 v[94:95], v[74:77], off
	global_load_dwordx4 v[74:77], v134, s[0:1] offset:128
	s_nop 0
	global_load_dwordx4 v[78:81], v134, s[0:1] offset:144
	s_mov_b64 s[0:1], 0x56cc000
	s_waitcnt vmcnt(1)
	v_mul_f32 v70, v74, v70
	v_mul_f32 v71, v75, v71
	v_mul_f32 v72, v76, v72
	v_mul_f32 v73, v77, v73
	s_waitcnt vmcnt(0)
	v_mul_f32 v66, v78, v66
	v_mul_f32 v67, v79, v67
	v_mul_f32 v68, v80, v68
	v_mul_f32 v69, v81, v69
	global_store_dwordx4 v[92:93], v[70:73], off offset:128
	s_branch .LBB0_360

.LBB0_362:
	s_andn2_b64 vcc, exec, s[0:1]
	s_cbranch_vccnz .LBB0_364
	s_lshl_b64 s[0:1], s[38:39], 2
	s_add_u32 s0, s12, s0
	s_addc_u32 s1, s13, s1
	global_load_dwordx4 v[68:71], v134, s[0:1]
	global_load_dwordx4 v[72:75], v134, s[0:1] offset:16
	v_mov_b32_e32 v78, v63
	v_mov_b32_e32 v79, v55
	v_mov_b32_e32 v82, v65
	v_mov_b32_e32 v83, v57
	v_mov_b32_e32 v86, v59
	v_mov_b32_e32 v87, v51
	v_mov_b32_e32 v90, v61
	v_mov_b32_e32 v91, v53
	v_mov_b32_e32 v76, v62
	v_mov_b32_e32 v77, v54
	v_mov_b32_e32 v80, v64
	v_mov_b32_e32 v81, v56
	v_mov_b32_e32 v84, v58
	v_mov_b32_e32 v85, v50
	v_mov_b32_e32 v88, v60
	v_mov_b32_e32 v89, v52
	v_mul_f32 v78, v78, v78
	v_mul_f32 v79, v79, v79
	v_mul_f32 v82, v82, v82
	v_mul_f32 v83, v83, v83
	v_mul_f32 v86, v86, v86
	v_mul_f32 v87, v87, v87
	v_mul_f32 v90, v90, v90
	v_mul_f32 v91, v91, v91
	v_fma_f32 v76, v76, v76, v78
	v_fma_f32 v77, v77, v77, v79
	v_fma_f32 v78, v80, v80, v82
	v_fma_f32 v79, v81, v81, v83
	v_fma_f32 v80, v84, v84, v86
	v_fma_f32 v81, v85, v85, v87
	v_fma_f32 v82, v88, v88, v90
	v_fma_f32 v83, v89, v89, v91
	v_add_f32 v76, v76, v78
	v_add_f32 v77, v77, v79
	v_add_f32 v78, v80, v82
	v_add_f32 v79, v81, v83
	v_and_b32_e32 v93, 64, v148
	v_add_f32 v76, v76, v78
	v_add_f32 v77, v77, v79
	v_xor_b32_e32 v92, 32, v148
	v_add_f32_e32 v76, v76, v77
	ds_swizzle_b32 v77, v76 offset:swizzle(SWAP,16)
	v_add_u32_e32 v78, 64, v93
	v_cmp_lt_i32_e32 vcc, v92, v78
	v_mov_b32_e32 v139, v135
	v_mov_b32_e32 v137, v135
	v_cndmask_b32_e32 v78, v148, v92, vcc
	v_lshlrev_b32_e32 v78, 2, v78
	s_waitcnt lgkmcnt(0)
	v_add_f32_e32 v80, v76, v77
	ds_bpermute_b32 v81, v78, v80
	v_lshl_add_u64 v[76:77], v[66:67], 2, s[14:15]
	v_lshl_add_u64 v[78:79], v[66:67], 1, s[18:19]
	v_lshl_add_u64 v[76:77], v[76:77], 0, v[134:135]
	v_lshl_add_u64 v[78:79], v[78:79], 0, v[138:139]
	s_waitcnt lgkmcnt(0)
	v_add_f32_e32 v80, v80, v81
	v_fmamk_f32 v80, v80, 0x3c800000, v147
	v_mul_f32_e32 v81, 0x4b800000, v80
	v_cmp_gt_f32_e32 vcc, s64, v80
	s_mov_b64 s[42:43], 0x1a923c00
	s_nop 0
	v_cndmask_b32_e32 v80, v80, v81, vcc
	v_rsq_f32_e32 v80, v80
	s_nop 0
	v_mul_f32_e32 v81, 0x45800000, v80
	v_cndmask_b32_e32 v80, v80, v81, vcc
	v_mul_f32 v62, v62, v80
	v_mul_f32 v63, v63, v80
	v_mul_f32 v64, v64, v80
	v_mul_f32 v65, v65, v80
	v_mul_f32 v82, v58, v80
	v_mul_f32 v83, v59, v80
	v_mul_f32 v84, v60, v80
	v_mul_f32 v85, v61, v80
	v_mul_f32 v56, v56, v80
	v_mul_f32 v57, v57, v80
	v_mul_f32 v54, v54, v80
	v_mul_f32 v55, v55, v80
	v_mul_f32 v52, v52, v80
	v_mul_f32 v53, v53, v80
	v_mul_f32 v50, v50, v80
	v_mul_f32 v51, v51, v80
	s_waitcnt vmcnt(0)
	v_mul_f32 v60, v70, v64
	v_mul_f32 v61, v71, v65
	v_mul_f32 v58, v68, v62
	v_mul_f32 v59, v69, v63
	v_mul_f32 v64, v74, v84
	v_mul_f32 v65, v75, v85
	v_mul_f32 v62, v72, v82
	v_mul_f32 v63, v73, v83
	global_store_dwordx4 v[76:77], v[58:61], off
	global_store_dwordx4 v[76:77], v[62:65], off offset:16
	s_nop 0
	v_cvt_pk_bf16_f32 v58, v58, v59
	v_cvt_pk_bf16_f32 v59, v60, v61
	v_cvt_pk_bf16_f32 v60, v62, v63
	v_cvt_pk_bf16_f32 v61, v64, v65
	global_store_dwordx4 v[78:79], v[58:61], off
	global_load_dwordx4 v[58:61], v134, s[0:1] offset:128
	s_nop 0
	global_load_dwordx4 v[62:65], v134, s[0:1] offset:144
	s_mov_b64 s[0:1], 0x56cc000
	s_waitcnt vmcnt(1)
	v_mul_f32 v54, v58, v54
	v_mul_f32 v55, v59, v55
	v_mul_f32 v56, v60, v56
	v_mul_f32 v57, v61, v57
	s_waitcnt vmcnt(0)
	v_mul_f32 v50, v62, v50
	v_mul_f32 v51, v63, v51
	v_mul_f32 v52, v64, v52
	v_mul_f32 v53, v65, v53
	global_store_dwordx4 v[76:77], v[54:57], off offset:128
	s_branch .LBB0_365

.LBB0_367:
	s_andn2_b64 vcc, exec, s[0:1]
	s_cbranch_vccnz .LBB0_369
	s_lshl_b64 s[0:1], s[38:39], 2
	s_add_u32 s0, s12, s0
	s_addc_u32 s1, s13, s1
	global_load_dwordx4 v[52:55], v134, s[0:1]
	global_load_dwordx4 v[56:59], v134, s[0:1] offset:16
	v_mov_b32_e32 v62, v47
	v_mov_b32_e32 v63, v39
	v_mov_b32_e32 v66, v49
	v_mov_b32_e32 v67, v41
	v_mov_b32_e32 v70, v43
	v_mov_b32_e32 v71, v35
	v_mov_b32_e32 v74, v45
	v_mov_b32_e32 v75, v37
	v_mov_b32_e32 v60, v46
	v_mov_b32_e32 v61, v38
	v_mov_b32_e32 v64, v48
	v_mov_b32_e32 v65, v40
	v_mov_b32_e32 v68, v42
	v_mov_b32_e32 v69, v34
	v_mov_b32_e32 v72, v44
	v_mov_b32_e32 v73, v36
	v_mul_f32 v62, v62, v62
	v_mul_f32 v63, v63, v63
	v_mul_f32 v66, v66, v66
	v_mul_f32 v67, v67, v67
	v_mul_f32 v70, v70, v70
	v_mul_f32 v71, v71, v71
	v_mul_f32 v74, v74, v74
	v_mul_f32 v75, v75, v75
	v_fma_f32 v60, v60, v60, v62
	v_fma_f32 v61, v61, v61, v63
	v_fma_f32 v62, v64, v64, v66
	v_fma_f32 v63, v65, v65, v67
	v_fma_f32 v64, v68, v68, v70
	v_fma_f32 v65, v69, v69, v71
	v_fma_f32 v66, v72, v72, v74
	v_fma_f32 v67, v73, v73, v75
	v_add_f32 v60, v60, v62
	v_add_f32 v61, v61, v63
	v_add_f32 v62, v64, v66
	v_add_f32 v63, v65, v67
	v_and_b32_e32 v77, 64, v148
	v_add_f32 v60, v60, v62
	v_add_f32 v61, v61, v63
	v_xor_b32_e32 v76, 32, v148
	v_add_f32_e32 v60, v60, v61
	ds_swizzle_b32 v61, v60 offset:swizzle(SWAP,16)
	v_add_u32_e32 v62, 64, v77
	v_cmp_lt_i32_e32 vcc, v76, v62
	v_mov_b32_e32 v139, v135
	v_mov_b32_e32 v137, v135
	v_cndmask_b32_e32 v62, v148, v76, vcc
	v_lshlrev_b32_e32 v62, 2, v62
	s_waitcnt lgkmcnt(0)
	v_add_f32_e32 v64, v60, v61
	ds_bpermute_b32 v65, v62, v64
	v_lshl_add_u64 v[60:61], v[50:51], 2, s[14:15]
	v_lshl_add_u64 v[62:63], v[50:51], 1, s[18:19]
	v_lshl_add_u64 v[60:61], v[60:61], 0, v[134:135]
	v_lshl_add_u64 v[62:63], v[62:63], 0, v[138:139]
	s_waitcnt lgkmcnt(0)
	v_add_f32_e32 v64, v64, v65
	v_fmamk_f32 v64, v64, 0x3c800000, v147
	v_mul_f32_e32 v65, 0x4b800000, v64
	v_cmp_gt_f32_e32 vcc, s64, v64
	s_mov_b64 s[42:43], 0x1a923c00
	s_nop 0
	v_cndmask_b32_e32 v64, v64, v65, vcc
	v_rsq_f32_e32 v64, v64
	s_nop 0
	v_mul_f32_e32 v65, 0x45800000, v64
	v_cndmask_b32_e32 v64, v64, v65, vcc
	v_mul_f32 v46, v46, v64
	v_mul_f32 v47, v47, v64
	v_mul_f32 v48, v48, v64
	v_mul_f32 v49, v49, v64
	v_mul_f32 v66, v42, v64
	v_mul_f32 v67, v43, v64
	v_mul_f32 v68, v44, v64
	v_mul_f32 v69, v45, v64
	v_mul_f32 v40, v40, v64
	v_mul_f32 v41, v41, v64
	v_mul_f32 v38, v38, v64
	v_mul_f32 v39, v39, v64
	v_mul_f32 v36, v36, v64
	v_mul_f32 v37, v37, v64
	v_mul_f32 v34, v34, v64
	v_mul_f32 v35, v35, v64
	s_waitcnt vmcnt(0)
	v_mul_f32 v44, v54, v48
	v_mul_f32 v45, v55, v49
	v_mul_f32 v42, v52, v46
	v_mul_f32 v43, v53, v47
	v_mul_f32 v48, v58, v68
	v_mul_f32 v49, v59, v69
	v_mul_f32 v46, v56, v66
	v_mul_f32 v47, v57, v67
	global_store_dwordx4 v[60:61], v[42:45], off
	global_store_dwordx4 v[60:61], v[46:49], off offset:16
	s_nop 0
	v_cvt_pk_bf16_f32 v42, v42, v43
	v_cvt_pk_bf16_f32 v43, v44, v45
	v_cvt_pk_bf16_f32 v44, v46, v47
	v_cvt_pk_bf16_f32 v45, v48, v49
	global_store_dwordx4 v[62:63], v[42:45], off
	global_load_dwordx4 v[42:45], v134, s[0:1] offset:128
	s_nop 0
	global_load_dwordx4 v[46:49], v134, s[0:1] offset:144
	s_mov_b64 s[0:1], 0x56cc000
	s_waitcnt vmcnt(1)
	v_mul_f32 v38, v42, v38
	v_mul_f32 v39, v43, v39
	v_mul_f32 v40, v44, v40
	v_mul_f32 v41, v45, v41
	s_waitcnt vmcnt(0)
	v_mul_f32 v34, v46, v34
	v_mul_f32 v35, v47, v35
	v_mul_f32 v36, v48, v36
	v_mul_f32 v37, v49, v37
	global_store_dwordx4 v[60:61], v[38:41], off offset:128
	s_branch .LBB0_370

.LBB0_372:
	s_andn2_b64 vcc, exec, s[0:1]
	s_cbranch_vccnz .LBB0_374
	s_lshl_b64 s[0:1], s[38:39], 2
	s_add_u32 s0, s12, s0
	s_addc_u32 s1, s13, s1
	global_load_dwordx4 v[36:39], v134, s[0:1]
	global_load_dwordx4 v[40:43], v134, s[0:1] offset:16
	v_mov_b32_e32 v46, v31
	v_mov_b32_e32 v47, v23
	v_mov_b32_e32 v50, v33
	v_mov_b32_e32 v51, v25
	v_mov_b32_e32 v54, v27
	v_mov_b32_e32 v55, v19
	v_mov_b32_e32 v58, v29
	v_mov_b32_e32 v59, v21
	v_mov_b32_e32 v44, v30
	v_mov_b32_e32 v45, v22
	v_mov_b32_e32 v48, v32
	v_mov_b32_e32 v49, v24
	v_mov_b32_e32 v52, v26
	v_mov_b32_e32 v53, v18
	v_mov_b32_e32 v56, v28
	v_mov_b32_e32 v57, v20
	v_mul_f32 v46, v46, v46
	v_mul_f32 v47, v47, v47
	v_mul_f32 v50, v50, v50
	v_mul_f32 v51, v51, v51
	v_mul_f32 v54, v54, v54
	v_mul_f32 v55, v55, v55
	v_mul_f32 v58, v58, v58
	v_mul_f32 v59, v59, v59
	v_fma_f32 v44, v44, v44, v46
	v_fma_f32 v45, v45, v45, v47
	v_fma_f32 v46, v48, v48, v50
	v_fma_f32 v47, v49, v49, v51
	v_fma_f32 v48, v52, v52, v54
	v_fma_f32 v49, v53, v53, v55
	v_fma_f32 v50, v56, v56, v58
	v_fma_f32 v51, v57, v57, v59
	v_add_f32 v44, v44, v46
	v_add_f32 v45, v45, v47
	v_add_f32 v46, v48, v50
	v_add_f32 v47, v49, v51
	v_and_b32_e32 v61, 64, v148
	v_add_f32 v44, v44, v46
	v_add_f32 v45, v45, v47
	v_xor_b32_e32 v60, 32, v148
	v_add_f32_e32 v44, v44, v45
	ds_swizzle_b32 v45, v44 offset:swizzle(SWAP,16)
	v_add_u32_e32 v46, 64, v61
	v_cmp_lt_i32_e32 vcc, v60, v46
	v_mov_b32_e32 v139, v135
	v_mov_b32_e32 v137, v135
	v_cndmask_b32_e32 v46, v148, v60, vcc
	v_lshlrev_b32_e32 v46, 2, v46
	s_waitcnt lgkmcnt(0)
	v_add_f32_e32 v48, v44, v45
	ds_bpermute_b32 v49, v46, v48
	v_lshl_add_u64 v[44:45], v[34:35], 2, s[14:15]
	v_lshl_add_u64 v[46:47], v[34:35], 1, s[18:19]
	v_lshl_add_u64 v[44:45], v[44:45], 0, v[134:135]
	v_lshl_add_u64 v[46:47], v[46:47], 0, v[138:139]
	s_waitcnt lgkmcnt(0)
	v_add_f32_e32 v48, v48, v49
	v_fmamk_f32 v48, v48, 0x3c800000, v147
	v_mul_f32_e32 v49, 0x4b800000, v48
	v_cmp_gt_f32_e32 vcc, s64, v48
	s_mov_b64 s[42:43], 0x1a923c00
	s_nop 0
	v_cndmask_b32_e32 v48, v48, v49, vcc
	v_rsq_f32_e32 v48, v48
	s_nop 0
	v_mul_f32_e32 v49, 0x45800000, v48
	v_cndmask_b32_e32 v48, v48, v49, vcc
	v_mul_f32 v30, v30, v48
	v_mul_f32 v31, v31, v48
	v_mul_f32 v32, v32, v48
	v_mul_f32 v33, v33, v48
	v_mul_f32 v50, v26, v48
	v_mul_f32 v51, v27, v48
	v_mul_f32 v52, v28, v48
	v_mul_f32 v53, v29, v48
	v_mul_f32 v24, v24, v48
	v_mul_f32 v25, v25, v48
	v_mul_f32 v22, v22, v48
	v_mul_f32 v23, v23, v48
	v_mul_f32 v20, v20, v48
	v_mul_f32 v21, v21, v48
	v_mul_f32 v18, v18, v48
	v_mul_f32 v19, v19, v48
	s_waitcnt vmcnt(0)
	v_mul_f32 v28, v38, v32
	v_mul_f32 v29, v39, v33
	v_mul_f32 v26, v36, v30
	v_mul_f32 v27, v37, v31
	v_mul_f32 v32, v42, v52
	v_mul_f32 v33, v43, v53
	v_mul_f32 v30, v40, v50
	v_mul_f32 v31, v41, v51
	global_store_dwordx4 v[44:45], v[26:29], off
	global_store_dwordx4 v[44:45], v[30:33], off offset:16
	s_nop 0
	v_cvt_pk_bf16_f32 v26, v26, v27
	v_cvt_pk_bf16_f32 v27, v28, v29
	v_cvt_pk_bf16_f32 v28, v30, v31
	v_cvt_pk_bf16_f32 v29, v32, v33
	global_store_dwordx4 v[46:47], v[26:29], off
	global_load_dwordx4 v[26:29], v134, s[0:1] offset:128
	s_nop 0
	global_load_dwordx4 v[30:33], v134, s[0:1] offset:144
	s_mov_b64 s[0:1], 0x56cc000
	s_waitcnt vmcnt(1)
	v_mul_f32 v22, v26, v22
	v_mul_f32 v23, v27, v23
	v_mul_f32 v24, v28, v24
	v_mul_f32 v25, v29, v25
	s_waitcnt vmcnt(0)
	v_mul_f32 v18, v30, v18
	v_mul_f32 v19, v31, v19
	v_mul_f32 v20, v32, v20
	v_mul_f32 v21, v33, v21
	global_store_dwordx4 v[44:45], v[22:25], off offset:128
	s_branch .LBB0_375

.LBB0_505:
	s_add_u32 s18, s16, 0x100
	s_addc_u32 s19, s17, 0
	s_cmp_eq_u32 s62, 12
	s_cselect_b32 s50, s9, s18
	s_cselect_b32 s51, s1, s19
	s_cselect_b32 s20, s43, s52
	s_cselect_b32 s21, s41, s53
	s_add_u32 s48, s50, 0x80
	s_addc_u32 s49, s51, 0
	s_add_i32 s64, 0, 0x10000
	v_add_u32_e32 v150, s64, v1
	ds_read_b128 v[132:135], v150
	ds_read_b128 v[142:145], v150 offset:1024
	ds_read_b128 v[146:149], v150 offset:2048
	ds_read_b128 v[150:153], v150 offset:3072
	s_add_u32 s16, s16, 0x40080
	s_addc_u32 s17, s17, 0
	ds_read_b128 v[154:157], v3
	ds_read_b128 v[158:161], v3 offset:1024
	ds_read_b128 v[162:165], v3 offset:2048
	ds_read_b128 v[166:169], v3 offset:3072
	ds_read_b128 v[170:173], v3 offset:4096
	ds_read_b128 v[174:177], v3 offset:5120
	ds_read_b128 v[178:181], v3 offset:6144
	ds_read_b128 v[182:185], v3 offset:7168
	s_add_i32 m0, s74, 0xc000
	s_nop 0
	global_load_lds_dwordx4 v136, s[16:17]
	s_add_i32 m0, s74, 0xe000
	s_nop 0
	global_load_lds_dwordx4 v138, s[16:17]
	s_waitcnt lgkmcnt(8)
	s_barrier
	s_waitcnt lgkmcnt(0)
	s_setprio 1
	s_waitcnt lgkmcnt(0)
	v_mfma_f32_16x16x32_bf16 v[128:131], v[132:135], v[154:157], v[128:131]
	v_mfma_f32_16x16x32_bf16 v[124:127], v[146:149], v[154:157], v[124:127]
	v_mfma_f32_16x16x32_bf16 v[112:115], v[132:135], v[162:165], v[112:115]
	v_mfma_f32_16x16x32_bf16 v[108:111], v[146:149], v[162:165], v[108:111]
	v_mfma_f32_16x16x32_bf16 v[96:99], v[132:135], v[170:173], v[96:99]
	v_mfma_f32_16x16x32_bf16 v[92:95], v[146:149], v[170:173], v[92:95]
	v_mfma_f32_16x16x32_bf16 v[80:83], v[132:135], v[178:181], v[80:83]
	v_mfma_f32_16x16x32_bf16 v[76:79], v[146:149], v[178:181], v[76:79]
	v_mfma_f32_16x16x32_bf16 v[128:131], v[142:145], v[158:161], v[128:131]
	v_mfma_f32_16x16x32_bf16 v[124:127], v[150:153], v[158:161], v[124:127]
	v_mfma_f32_16x16x32_bf16 v[112:115], v[142:145], v[166:169], v[112:115]
	v_mfma_f32_16x16x32_bf16 v[108:111], v[150:153], v[166:169], v[108:111]
	v_mfma_f32_16x16x32_bf16 v[96:99], v[142:145], v[174:177], v[96:99]
	v_mfma_f32_16x16x32_bf16 v[92:95], v[150:153], v[174:177], v[92:95]
	v_mfma_f32_16x16x32_bf16 v[80:83], v[142:145], v[182:185], v[80:83]
	v_mfma_f32_16x16x32_bf16 v[76:79], v[150:153], v[182:185], v[76:79]
	s_setprio 0
	s_barrier
	s_add_i32 s65, 0, 0x14000
	v_add_u32_e32 v194, s65, v1
	s_mov_b64 s[16:17], s[20:21]
	s_add_i32 s64, s64, s73
	ds_read_b128 v[186:189], v194
	ds_read_b128 v[190:193], v194 offset:1024
	ds_read_b128 v[210:213], v194 offset:2048
	ds_read_b128 v[214:217], v194 offset:3072
	s_mov_b32 m0, s64
	s_nop 0
	global_load_lds_dwordx4 v136, s[16:17]
	s_add_i32 m0, s64, 0x2000
	s_nop 0
	global_load_lds_dwordx4 v138, s[16:17]
	s_barrier
	s_waitcnt lgkmcnt(0)
	s_setprio 1
	s_waitcnt lgkmcnt(0)
	v_mfma_f32_16x16x32_bf16 v[120:123], v[186:189], v[154:157], v[120:123]
	v_mfma_f32_16x16x32_bf16 v[116:119], v[210:213], v[154:157], v[116:119]
	v_mfma_f32_16x16x32_bf16 v[104:107], v[186:189], v[162:165], v[104:107]
	v_mfma_f32_16x16x32_bf16 v[100:103], v[210:213], v[162:165], v[100:103]
	v_mfma_f32_16x16x32_bf16 v[88:91], v[186:189], v[170:173], v[88:91]
	v_mfma_f32_16x16x32_bf16 v[84:87], v[210:213], v[170:173], v[84:87]
	v_mfma_f32_16x16x32_bf16 v[72:75], v[186:189], v[178:181], v[72:75]
	v_mfma_f32_16x16x32_bf16 v[68:71], v[210:213], v[178:181], v[68:71]
	v_mfma_f32_16x16x32_bf16 v[120:123], v[190:193], v[158:161], v[120:123]
	v_mfma_f32_16x16x32_bf16 v[116:119], v[214:217], v[158:161], v[116:119]
	v_mfma_f32_16x16x32_bf16 v[104:107], v[190:193], v[166:169], v[104:107]
	v_mfma_f32_16x16x32_bf16 v[100:103], v[214:217], v[166:169], v[100:103]
	v_mfma_f32_16x16x32_bf16 v[88:91], v[190:193], v[174:177], v[88:91]
	v_mfma_f32_16x16x32_bf16 v[84:87], v[214:217], v[174:177], v[84:87]
	v_mfma_f32_16x16x32_bf16 v[72:75], v[190:193], v[182:185], v[72:75]
	v_mfma_f32_16x16x32_bf16 v[68:71], v[214:217], v[182:185], v[68:71]
	s_setprio 0
	s_mov_b64 s[16:17], s[50:51]
	s_mov_b32 m0, s74
	s_barrier
	ds_read_b128 v[154:157], v3 offset:16384
	ds_read_b128 v[158:161], v3 offset:17408
	ds_read_b128 v[162:165], v3 offset:18432
	ds_read_b128 v[166:169], v3 offset:19456
	ds_read_b128 v[170:173], v3 offset:20480
	ds_read_b128 v[174:177], v3 offset:21504
	ds_read_b128 v[178:181], v3 offset:22528
	ds_read_b128 v[182:185], v3 offset:23552
	s_nop 0
	global_load_lds_dwordx4 v136, s[16:17]
	s_mov_b32 m0, s75
	s_nop 0
	global_load_lds_dwordx4 v138, s[16:17]
	s_barrier
	s_waitcnt lgkmcnt(0)
	s_setprio 1
	s_waitcnt lgkmcnt(0)
	v_mfma_f32_16x16x32_bf16 v[64:67], v[132:135], v[154:157], v[64:67]
	v_mfma_f32_16x16x32_bf16 v[60:63], v[146:149], v[154:157], v[60:63]
	v_mfma_f32_16x16x32_bf16 v[48:51], v[132:135], v[162:165], v[48:51]
	v_mfma_f32_16x16x32_bf16 v[44:47], v[146:149], v[162:165], v[44:47]
	v_mfma_f32_16x16x32_bf16 v[32:35], v[132:135], v[170:173], v[32:35]
	v_mfma_f32_16x16x32_bf16 v[28:31], v[146:149], v[170:173], v[28:31]
	v_mfma_f32_16x16x32_bf16 v[16:19], v[132:135], v[178:181], v[16:19]
	v_mfma_f32_16x16x32_bf16 v[12:15], v[146:149], v[178:181], v[12:15]
	v_mfma_f32_16x16x32_bf16 v[64:67], v[142:145], v[158:161], v[64:67]
	v_mfma_f32_16x16x32_bf16 v[60:63], v[150:153], v[158:161], v[60:63]
	v_mfma_f32_16x16x32_bf16 v[48:51], v[142:145], v[166:169], v[48:51]
	v_mfma_f32_16x16x32_bf16 v[44:47], v[150:153], v[166:169], v[44:47]
	v_mfma_f32_16x16x32_bf16 v[32:35], v[142:145], v[174:177], v[32:35]
	v_mfma_f32_16x16x32_bf16 v[28:31], v[150:153], v[174:177], v[28:31]
	v_mfma_f32_16x16x32_bf16 v[16:19], v[142:145], v[182:185], v[16:19]
	v_mfma_f32_16x16x32_bf16 v[12:15], v[150:153], v[182:185], v[12:15]
	s_setprio 0
	s_barrier
	s_add_u32 s16, s20, 0x40000
	s_addc_u32 s17, s21, 0
	s_add_i32 s64, s65, s73
	s_mov_b32 m0, s64
	s_nop 0
	global_load_lds_dwordx4 v136, s[16:17]
	s_add_i32 m0, s64, 0x2000
	s_nop 0
	global_load_lds_dwordx4 v138, s[16:17]
	s_waitcnt vmcnt(6)
	s_barrier
	s_setprio 1
	v_mfma_f32_16x16x32_bf16 v[56:59], v[186:189], v[154:157], v[56:59]
	v_mfma_f32_16x16x32_bf16 v[52:55], v[210:213], v[154:157], v[52:55]
	v_mfma_f32_16x16x32_bf16 v[40:43], v[186:189], v[162:165], v[40:43]
	v_mfma_f32_16x16x32_bf16 v[36:39], v[210:213], v[162:165], v[36:39]
	v_mfma_f32_16x16x32_bf16 v[24:27], v[186:189], v[170:173], v[24:27]
	v_mfma_f32_16x16x32_bf16 v[20:23], v[210:213], v[170:173], v[20:23]
	v_mfma_f32_16x16x32_bf16 v[8:11], v[186:189], v[178:181], v[8:11]
	v_mfma_f32_16x16x32_bf16 v[4:7], v[210:213], v[178:181], v[4:7]
	v_mfma_f32_16x16x32_bf16 v[56:59], v[190:193], v[158:161], v[56:59]
	v_mfma_f32_16x16x32_bf16 v[52:55], v[214:217], v[158:161], v[52:55]
	v_mfma_f32_16x16x32_bf16 v[40:43], v[190:193], v[166:169], v[40:43]
	v_mfma_f32_16x16x32_bf16 v[36:39], v[214:217], v[166:169], v[36:39]
	v_mfma_f32_16x16x32_bf16 v[24:27], v[190:193], v[174:177], v[24:27]
	v_mfma_f32_16x16x32_bf16 v[20:23], v[214:217], v[174:177], v[20:23]
	v_mfma_f32_16x16x32_bf16 v[8:11], v[190:193], v[182:185], v[8:11]
	v_mfma_f32_16x16x32_bf16 v[4:7], v[214:217], v[182:185], v[4:7]
	s_setprio 0
	s_add_i32 s64, 0, 0x18000
	v_add_u32_e32 v150, s64, v1
	s_barrier
	ds_read_b128 v[132:135], v150
	ds_read_b128 v[142:145], v150 offset:1024
	ds_read_b128 v[146:149], v150 offset:2048
	ds_read_b128 v[150:153], v150 offset:3072
	s_add_u32 s16, s50, 0x40000
	s_addc_u32 s17, s51, 0
	s_mov_b32 m0, s78
	ds_read_b128 v[154:157], v3 offset:32768
	ds_read_b128 v[158:161], v3 offset:33792
	ds_read_b128 v[162:165], v3 offset:34816
	ds_read_b128 v[166:169], v3 offset:35840
	ds_read_b128 v[170:173], v3 offset:36864
	ds_read_b128 v[174:177], v3 offset:37888
	ds_read_b128 v[178:181], v3 offset:38912
	ds_read_b128 v[182:185], v3 offset:39936
	s_nop 0
	global_load_lds_dwordx4 v136, s[16:17]
	s_mov_b32 m0, s79
	s_nop 0
	global_load_lds_dwordx4 v138, s[16:17]
	s_waitcnt lgkmcnt(8)
	s_barrier
	s_waitcnt lgkmcnt(0)
	s_setprio 1
	s_waitcnt lgkmcnt(0)
	v_mfma_f32_16x16x32_bf16 v[128:131], v[132:135], v[154:157], v[128:131]
	v_mfma_f32_16x16x32_bf16 v[124:127], v[146:149], v[154:157], v[124:127]
	v_mfma_f32_16x16x32_bf16 v[112:115], v[132:135], v[162:165], v[112:115]
	v_mfma_f32_16x16x32_bf16 v[108:111], v[146:149], v[162:165], v[108:111]
	v_mfma_f32_16x16x32_bf16 v[96:99], v[132:135], v[170:173], v[96:99]
	v_mfma_f32_16x16x32_bf16 v[92:95], v[146:149], v[170:173], v[92:95]
	v_mfma_f32_16x16x32_bf16 v[80:83], v[132:135], v[178:181], v[80:83]
	v_mfma_f32_16x16x32_bf16 v[76:79], v[146:149], v[178:181], v[76:79]
	v_mfma_f32_16x16x32_bf16 v[128:131], v[142:145], v[158:161], v[128:131]
	v_mfma_f32_16x16x32_bf16 v[124:127], v[150:153], v[158:161], v[124:127]
	v_mfma_f32_16x16x32_bf16 v[112:115], v[142:145], v[166:169], v[112:115]
	v_mfma_f32_16x16x32_bf16 v[108:111], v[150:153], v[166:169], v[108:111]
	v_mfma_f32_16x16x32_bf16 v[96:99], v[142:145], v[174:177], v[96:99]
	v_mfma_f32_16x16x32_bf16 v[92:95], v[150:153], v[174:177], v[92:95]
	v_mfma_f32_16x16x32_bf16 v[80:83], v[142:145], v[182:185], v[80:83]
	v_mfma_f32_16x16x32_bf16 v[76:79], v[150:153], v[182:185], v[76:79]
	s_setprio 0
	s_barrier
	s_add_i32 s50, 0, 0x1c000
	s_add_u32 s16, s20, 0x80
	v_add_u32_e32 v194, s50, v1
	s_addc_u32 s17, s21, 0
	s_add_i32 s51, s64, s73
	ds_read_b128 v[186:189], v194
	ds_read_b128 v[190:193], v194 offset:1024
	ds_read_b128 v[210:213], v194 offset:2048
	ds_read_b128 v[214:217], v194 offset:3072
	s_mov_b32 m0, s51
	s_nop 0
	global_load_lds_dwordx4 v136, s[16:17]
	s_add_i32 m0, s51, 0x2000
	s_nop 0
	global_load_lds_dwordx4 v138, s[16:17]
	s_barrier
	s_waitcnt lgkmcnt(0)
	s_setprio 1
	s_waitcnt lgkmcnt(0)
	v_mfma_f32_16x16x32_bf16 v[120:123], v[186:189], v[154:157], v[120:123]
	v_mfma_f32_16x16x32_bf16 v[116:119], v[210:213], v[154:157], v[116:119]
	v_mfma_f32_16x16x32_bf16 v[104:107], v[186:189], v[162:165], v[104:107]
	v_mfma_f32_16x16x32_bf16 v[100:103], v[210:213], v[162:165], v[100:103]
	v_mfma_f32_16x16x32_bf16 v[88:91], v[186:189], v[170:173], v[88:91]
	v_mfma_f32_16x16x32_bf16 v[84:87], v[210:213], v[170:173], v[84:87]
	v_mfma_f32_16x16x32_bf16 v[72:75], v[186:189], v[178:181], v[72:75]
	v_mfma_f32_16x16x32_bf16 v[68:71], v[210:213], v[178:181], v[68:71]
	v_mfma_f32_16x16x32_bf16 v[120:123], v[190:193], v[158:161], v[120:123]
	v_mfma_f32_16x16x32_bf16 v[116:119], v[214:217], v[158:161], v[116:119]
	v_mfma_f32_16x16x32_bf16 v[104:107], v[190:193], v[166:169], v[104:107]
	v_mfma_f32_16x16x32_bf16 v[100:103], v[214:217], v[166:169], v[100:103]
	v_mfma_f32_16x16x32_bf16 v[88:91], v[190:193], v[174:177], v[88:91]
	v_mfma_f32_16x16x32_bf16 v[84:87], v[214:217], v[174:177], v[84:87]
	v_mfma_f32_16x16x32_bf16 v[72:75], v[190:193], v[182:185], v[72:75]
	v_mfma_f32_16x16x32_bf16 v[68:71], v[214:217], v[182:185], v[68:71]
	s_setprio 0
	s_mov_b32 m0, s80
	s_barrier
	ds_read_b128 v[154:157], v3 offset:49152
	ds_read_b128 v[158:161], v3 offset:50176
	ds_read_b128 v[162:165], v3 offset:51200
	ds_read_b128 v[166:169], v3 offset:52224
	ds_read_b128 v[170:173], v3 offset:53248
	ds_read_b128 v[174:177], v3 offset:54272
	ds_read_b128 v[178:181], v3 offset:55296
	ds_read_b128 v[182:185], v3 offset:56320
	s_nop 0
	global_load_lds_dwordx4 v136, s[48:49]
	s_mov_b32 m0, s81
	s_nop 0
	global_load_lds_dwordx4 v138, s[48:49]
	s_barrier
	s_waitcnt lgkmcnt(0)
	s_setprio 1
	s_waitcnt lgkmcnt(0)
	v_mfma_f32_16x16x32_bf16 v[64:67], v[132:135], v[154:157], v[64:67]
	v_mfma_f32_16x16x32_bf16 v[60:63], v[146:149], v[154:157], v[60:63]
	v_mfma_f32_16x16x32_bf16 v[48:51], v[132:135], v[162:165], v[48:51]
	v_mfma_f32_16x16x32_bf16 v[44:47], v[146:149], v[162:165], v[44:47]
	v_mfma_f32_16x16x32_bf16 v[32:35], v[132:135], v[170:173], v[32:35]
	v_mfma_f32_16x16x32_bf16 v[28:31], v[146:149], v[170:173], v[28:31]
	v_mfma_f32_16x16x32_bf16 v[16:19], v[132:135], v[178:181], v[16:19]
	v_mfma_f32_16x16x32_bf16 v[12:15], v[146:149], v[178:181], v[12:15]
	v_mfma_f32_16x16x32_bf16 v[64:67], v[142:145], v[158:161], v[64:67]
	v_mfma_f32_16x16x32_bf16 v[60:63], v[150:153], v[158:161], v[60:63]
	v_mfma_f32_16x16x32_bf16 v[48:51], v[142:145], v[166:169], v[48:51]
	v_mfma_f32_16x16x32_bf16 v[44:47], v[150:153], v[166:169], v[44:47]
	v_mfma_f32_16x16x32_bf16 v[32:35], v[142:145], v[174:177], v[32:35]
	v_mfma_f32_16x16x32_bf16 v[28:31], v[150:153], v[174:177], v[28:31]
	v_mfma_f32_16x16x32_bf16 v[16:19], v[142:145], v[182:185], v[16:19]
	v_mfma_f32_16x16x32_bf16 v[12:15], v[150:153], v[182:185], v[12:15]
	s_setprio 0
	s_barrier
	s_add_u32 s16, s20, 0x40080
	s_addc_u32 s17, s21, 0
	s_add_i32 s20, s50, s73
	s_mov_b32 m0, s20
	s_nop 0
	global_load_lds_dwordx4 v136, s[16:17]
	s_add_i32 m0, s20, 0x2000
	s_nop 0
	global_load_lds_dwordx4 v138, s[16:17]
	s_waitcnt vmcnt(6)
	s_barrier
	s_setprio 1
	v_mfma_f32_16x16x32_bf16 v[56:59], v[186:189], v[154:157], v[56:59]
	v_mfma_f32_16x16x32_bf16 v[52:55], v[210:213], v[154:157], v[52:55]
	v_mfma_f32_16x16x32_bf16 v[40:43], v[186:189], v[162:165], v[40:43]
	v_mfma_f32_16x16x32_bf16 v[36:39], v[210:213], v[162:165], v[36:39]
	v_mfma_f32_16x16x32_bf16 v[24:27], v[186:189], v[170:173], v[24:27]
	v_mfma_f32_16x16x32_bf16 v[20:23], v[210:213], v[170:173], v[20:23]
	v_mfma_f32_16x16x32_bf16 v[8:11], v[186:189], v[178:181], v[8:11]
	v_mfma_f32_16x16x32_bf16 v[4:7], v[210:213], v[178:181], v[4:7]
	v_mfma_f32_16x16x32_bf16 v[56:59], v[190:193], v[158:161], v[56:59]
	v_mfma_f32_16x16x32_bf16 v[52:55], v[214:217], v[158:161], v[52:55]
	v_mfma_f32_16x16x32_bf16 v[40:43], v[190:193], v[166:169], v[40:43]
	v_mfma_f32_16x16x32_bf16 v[36:39], v[214:217], v[166:169], v[36:39]
	v_mfma_f32_16x16x32_bf16 v[24:27], v[190:193], v[174:177], v[24:27]
	v_mfma_f32_16x16x32_bf16 v[20:23], v[214:217], v[174:177], v[20:23]
	v_mfma_f32_16x16x32_bf16 v[8:11], v[190:193], v[182:185], v[8:11]
	v_mfma_f32_16x16x32_bf16 v[4:7], v[214:217], v[182:185], v[4:7]
	s_setprio 0
	s_add_i32 s62, s62, 2
	s_add_u32 s52, s52, 0x100
	s_addc_u32 s53, s53, 0
	s_cmp_gt_u32 s62, 13
	s_mov_b64 s[16:17], s[18:19]
	s_barrier
	s_cbranch_scc0 .LBB0_505
	v_mov_b32_e32 v132, v0
	s_lshl_b32 s16, s0, 2
	v_readfirstlane_b32 s1, v132
	s_bfe_u32 s9, s1, 0x20006
	s_ashr_i32 s1, s1, 2
	s_lshl_b32 s0, s8, 8
	s_andn2_b32 s1, s1, 63
	s_add_i32 s1, s1, s0
	v_and_or_b32 v142, v132, 15, s1
	v_ashrrev_i32_e32 v143, 31, v142
	v_bfe_u32 v134, v132, 4, 2
	v_lshl_add_u64 v[132:133], v[142:143], 2, s[24:25]
	global_load_dword v135, v[132:133], off
	global_load_dword v147, v[132:133], off offset:64
	global_load_dword v173, v[132:133], off offset:128
	global_load_dword v172, v[132:133], off offset:192
	global_load_dword v171, v[132:133], off offset:512
	global_load_dword v170, v[132:133], off offset:576
	global_load_dword v169, v[132:133], off offset:640
	global_load_dword v168, v[132:133], off offset:704
	s_or_b32 s17, s9, s16
	s_cmp_gt_i32 s17, 5
	s_cselect_b64 s[0:1], -1, 0
	s_cmp_gt_u32 s17, 9
	s_cselect_b64 s[8:9], -1, 0
	s_cmp_lg_u32 s17, 10
	s_cselect_b64 s[50:51], -1, 0
	s_cmp_gt_u32 s16, 11
	s_cselect_b64 s[48:49], -1, 0
	s_lshl_b32 s68, s17, 6
	s_add_i32 s16, s68, 0xfffffd00
	v_lshlrev_b32_e32 v157, 3, v134
	v_or_b32_e32 v144, s16, v157
	v_cmp_eq_u32_e64 s[16:17], 0, v134
	s_mov_b64 s[18:19], -1
	s_waitcnt vmcnt(0)
	v_fmamk_f32 v132, v135, 0x3a800000, v231
	v_cmp_gt_f32_e32 vcc, s11, v132
	v_mul_f32_e32 v133, 0x4b800000, v132
	s_nop 0
	v_cndmask_b32_e32 v132, v132, v133, vcc
	v_rsq_f32_e32 v132, v132
	s_nop 0
	v_mul_f32_e32 v133, 0x45800000, v132
	v_cndmask_b32_e32 v146, v132, v133, vcc
	s_and_b64 vcc, exec, s[0:1]
	s_cbranch_vccz .LBB0_519
	s_and_b64 vcc, exec, s[8:9]
	s_cbranch_vccz .LBB0_516
	s_and_b64 vcc, exec, s[50:51]
	s_cbranch_vccz .LBB0_512
	s_andn2_b64 vcc, exec, s[48:49]
	s_cbranch_vccnz .LBB0_511
	v_mov_b64_e32 v[148:149], s[38:39]
	s_movk_i32 s18, 0x480
	v_mad_i64_i32 v[148:149], s[18:19], v142, s18, v[148:149]
	v_mov_b32_e32 v145, v2
	v_mul_f32 v134, v130, v146
	v_mul_f32 v135, v131, v146
	v_mul_f32 v132, v128, v146
	v_mul_f32 v133, v129, v146
	v_lshl_add_u64 v[150:151], v[144:145], 2, v[148:149]
	global_store_dwordx4 v[150:151], v[132:135], off
	v_ashrrev_i32_e32 v145, 31, v144
	v_lshl_add_u64 v[148:149], v[144:145], 2, v[148:149]
	v_mul_f32 v134, v126, v146
	v_mul_f32 v135, v127, v146
	v_mul_f32 v132, v124, v146
	v_mul_f32 v133, v125, v146
	global_store_dwordx4 v[150:151], v[132:135], off offset:16
	s_nop 1
	v_mul_f32 v134, v122, v146
	v_mul_f32 v135, v123, v146
	v_mul_f32 v132, v120, v146
	v_mul_f32 v133, v121, v146
	global_store_dwordx4 v[148:149], v[132:135], off offset:128
	s_nop 1
	v_mul_f32 v134, v118, v146
	v_mul_f32 v135, v119, v146
	v_mul_f32 v132, v116, v146
	v_mul_f32 v133, v117, v146
	global_store_dwordx4 v[148:149], v[132:135], off offset:144

.LBB0_512:
	s_andn2_b64 vcc, exec, s[18:19]
	s_cbranch_vccnz .LBB0_515
	s_andn2_b64 vcc, exec, s[6:7]
	s_cbranch_vccnz .LBB0_515
	v_mov_b64_e32 v[148:149], s[38:39]
	s_movk_i32 s18, 0x480
	v_mad_i64_i32 v[148:149], s[18:19], v142, s18, v[148:149]
	v_lshlrev_b32_e32 v150, 2, v157
	v_mov_b32_e32 v151, v2
	v_mul_f32 v134, v130, v146
	v_mul_f32 v135, v131, v146
	v_mul_f32 v132, v128, v146
	v_mul_f32 v133, v129, v146
	v_lshl_add_u64 v[148:149], v[148:149], 0, v[150:151]
	global_store_dwordx4 v[148:149], v[132:135], off offset:1024
	s_nop 1
	v_mul_f32 v134, v126, v146
	v_mul_f32 v135, v127, v146
	v_mul_f32 v132, v124, v146
	v_mul_f32 v133, v125, v146
	global_store_dwordx4 v[148:149], v[132:135], off offset:1040

.LBB0_516:
	s_andn2_b64 vcc, exec, s[18:19]
	s_cbranch_vccnz .LBB0_518
	v_lshlrev_b64 v[132:133], 9, v[142:143]
	v_lshl_add_u64 v[132:133], s[30:31], 0, v[132:133]
	v_mul_f32 v162, v130, v146
	v_mul_f32 v163, v131, v146
	v_mul_f32 v164, v128, v146
	v_mul_f32 v165, v129, v146
	v_lshl_add_u64 v[166:167], s[68:69], 1, v[132:133]
	v_mul_f32 v132, v162, v162
	v_mul_f32 v133, v163, v163
	v_mul_f32 v134, v164, v164
	v_mul_f32 v135, v165, v165
	v_mul_f32 v158, v126, v146
	v_mul_f32 v159, v127, v146
	v_pk_mov_b32 v[148:149], v[134:135], v[132:133] op_sel:[1,0]
	v_mov_b32_e32 v135, v133
	v_add_f32 v132, v148, v134
	v_add_f32 v133, v149, v135
	v_mul_f32 v160, v124, v146
	v_mul_f32 v161, v125, v146
	v_add_f32 v133, v132, v133
	v_add_f32 v132, v132, v132
	v_mul_f32 v134, v158, v158
	v_mul_f32 v135, v159, v159
	v_mul_f32 v148, v160, v160
	v_mul_f32 v149, v161, v161
	v_mul_f32 v154, v120, v146
	v_mul_f32 v155, v121, v146
	v_pk_mov_b32 v[150:151], v[148:149], v[134:135] op_sel:[1,0]
	v_mov_b32_e32 v149, v135
	v_mul_f32 v152, v122, v146
	v_mul_f32 v153, v123, v146
	v_mul_f32_e32 v132, v154, v154
	v_add_f32 v134, v150, v148
	v_add_f32 v135, v151, v149
	v_fma_f32 v174, v154, v154, v132
	v_fma_f32 v175, v155, v155, v132
	v_mul_f32_e32 v132, v152, v152
	v_add_f32 v135, v134, v135
	v_add_f32 v134, v134, v134
	v_fma_f32 v176, v152, v152, v132
	v_fma_f32 v177, v153, v153, v132
	v_mul_f32 v148, v118, v146
	v_mul_f32 v149, v119, v146
	v_mul_f32 v150, v116, v146
	v_mul_f32 v151, v117, v146
	v_mul_f32_e32 v132, v148, v148
	v_mul_f32_e32 v174, v150, v150
	v_mul_f32_e32 v176, v151, v151
	v_mul_f32_e32 v134, v149, v149
	v_add_f32 v174, v174, v176
	v_add_f32 v175, v175, v177
	v_add_f32 v132, v132, v134
	v_add_f32 v133, v133, v135
	v_and_b32_e32 v134, 64, v236
	v_add_f32 v132, v174, v132
	v_add_f32 v133, v175, v133
	v_add_u32_e32 v134, 64, v134
	v_add_f32_e32 v132, v132, v133
	ds_swizzle_b32 v133, v132 offset:swizzle(SWAP,16)
	v_lshlrev_b32_e32 v145, 2, v157
	v_lshlrev_b32_e32 v178, 1, v157
	v_mov_b32_e32 v179, v2
	v_lshl_add_u64 v[166:167], v[166:167], 0, v[178:179]
	s_waitcnt lgkmcnt(0)
	v_add_f32_e32 v132, v132, v133
	v_xor_b32_e32 v133, 32, v236
	v_cmp_lt_i32_e32 vcc, v133, v134
	s_nop 1
	v_cndmask_b32_e32 v133, v236, v133, vcc
	v_lshlrev_b32_e32 v133, 2, v133
	ds_bpermute_b32 v133, v133, v132
	s_waitcnt lgkmcnt(0)
	v_add_f32_e32 v132, v132, v133
	v_fmamk_f32 v132, v132, 0x3c800000, v231
	v_cmp_gt_f32_e32 vcc, s11, v132
	v_mul_f32_e32 v133, 0x4b800000, v132
	s_nop 0
	v_cndmask_b32_e32 v132, v132, v133, vcc
	v_rsq_f32_e32 v132, v132
	s_nop 0
	v_mul_f32_e32 v133, 0x45800000, v132
	v_cndmask_b32_e32 v132, v132, v133, vcc
	v_mul_f32_e32 v156, 0x3e38aa3b, v132
	global_load_dwordx4 v[132:135], v145, s[36:37] offset:16
	global_load_dwordx4 v[174:177], v145, s[36:37]
	v_mul_f32 v164, v164, v156
	v_mul_f32 v165, v165, v156
	v_mul_f32 v162, v162, v156
	v_mul_f32 v163, v163, v156
	v_mul_f32 v160, v160, v156
	v_mul_f32 v161, v161, v156
	v_mul_f32 v158, v158, v156
	v_mul_f32 v159, v159, v156
	v_mul_f32 v154, v154, v156
	v_mul_f32 v155, v155, v156
	v_mul_f32 v152, v152, v156
	v_mul_f32 v153, v153, v156
	v_mul_f32 v150, v150, v156
	v_mul_f32 v151, v151, v156
	v_mul_f32 v148, v148, v156
	v_mul_f32 v149, v149, v156
	s_waitcnt vmcnt(1)
	v_mul_f32 v158, v134, v158
	v_mul_f32 v159, v135, v159
	s_waitcnt vmcnt(0)
	v_mul_f32 v162, v176, v162
	v_mul_f32 v163, v177, v163
	v_mul_f32 v164, v174, v164
	v_mul_f32 v165, v175, v165
	v_mul_f32 v134, v132, v160
	v_mul_f32 v135, v133, v161
	v_cvt_pk_bf16_f32 v132, v164, v165
	v_cvt_pk_bf16_f32 v133, v162, v163
	v_cvt_pk_bf16_f32 v134, v134, v135
	v_cvt_pk_bf16_f32 v135, v158, v159
	global_store_dwordx4 v[166:167], v[132:135], off offset:-768
	global_load_dwordx4 v[132:135], v145, s[36:37] offset:144
	s_nop 0
	global_load_dwordx4 v[158:161], v145, s[36:37] offset:128
	s_waitcnt vmcnt(1)
	v_mul_f32 v148, v134, v148
	v_mul_f32 v149, v135, v149
	s_waitcnt vmcnt(0)
	v_mul_f32 v152, v160, v152
	v_mul_f32 v153, v161, v153
	v_mul_f32 v154, v158, v154
	v_mul_f32 v155, v159, v155
	v_mul_f32 v134, v132, v150
	v_mul_f32 v135, v133, v151
	v_cvt_pk_bf16_f32 v132, v154, v155
	v_cvt_pk_bf16_f32 v133, v152, v153
	v_cvt_pk_bf16_f32 v134, v134, v135
	v_cvt_pk_bf16_f32 v135, v148, v149
	global_store_dwordx4 v[166:167], v[132:135], off offset:-704

.LBB0_519:
	s_nop 0
	v_or_b32_e32 v132, s68, v157
	s_andn2_b64 vcc, exec, s[18:19]
	v_ashrrev_i32_e32 v133, 31, v132
	s_cbranch_vccnz .LBB0_523
	v_mul_f32 v130, v130, v146
	v_mul_f32 v131, v131, v146
	v_mul_f32 v128, v128, v146
	v_mul_f32 v129, v129, v146
	v_mul_f32 v134, v126, v146
	v_mul_f32 v135, v127, v146
	v_mul_f32 v126, v124, v146
	v_mul_f32 v127, v125, v146
	v_mul_f32_e32 v124, v129, v129
	v_mul_f32_e32 v125, v131, v131
	v_fmac_f32_e32 v124, v128, v128
	v_fmac_f32_e32 v125, v130, v130
	v_add_f32_e32 v124, v124, v125
	v_mul_f32_e32 v125, v127, v127
	v_mul_f32_e32 v145, v135, v135
	v_fmac_f32_e32 v125, v126, v126
	v_fmac_f32_e32 v145, v134, v134
	v_add_f32_e32 v125, v125, v145
	v_add_f32_e32 v145, v124, v125
	v_mov_b64_e32 v[124:125], s[26:27]
	s_movk_i32 s18, 0x300
	v_mad_i64_i32 v[124:125], s[18:19], v142, s18, v[124:125]
	v_mul_f32 v122, v122, v146
	v_mul_f32 v123, v123, v146
	v_mul_f32 v120, v120, v146
	v_mul_f32 v121, v121, v146
	v_lshl_add_u64 v[148:149], v[132:133], 1, v[124:125]
	v_cvt_pk_bf16_f32 v125, v130, v131
	v_mul_f32 v130, v116, v146
	v_mul_f32 v131, v117, v146
	v_mul_f32_e32 v116, v121, v121
	v_mul_f32_e32 v117, v123, v123
	v_cvt_pk_bf16_f32 v124, v128, v129
	v_mul_f32 v128, v118, v146
	v_mul_f32 v129, v119, v146
	v_fmac_f32_e32 v116, v120, v120
	v_fmac_f32_e32 v117, v122, v122
	v_add_f32_e32 v116, v116, v117
	v_mul_f32_e32 v117, v131, v131
	v_mul_f32_e32 v118, v129, v129
	v_fmac_f32_e32 v117, v130, v130
	v_fmac_f32_e32 v118, v128, v128
	v_add_f32_e32 v117, v117, v118
	v_add_f32_e32 v116, v116, v117
	v_add_f32_e32 v116, v145, v116
	ds_swizzle_b32 v117, v116 offset:swizzle(SWAP,16)
	v_and_b32_e32 v119, 64, v236
	v_add_u32_e32 v119, 64, v119
	v_cvt_pk_bf16_f32 v126, v126, v127
	v_cvt_pk_bf16_f32 v127, v134, v135
	s_waitcnt lgkmcnt(0)
	v_add_f32_e32 v116, v116, v117
	v_xor_b32_e32 v117, 32, v236
	v_cmp_lt_i32_e32 vcc, v117, v119
	v_cvt_pk_bf16_f32 v118, v120, v121
	v_cvt_pk_bf16_f32 v119, v122, v123
	v_cndmask_b32_e32 v117, v236, v117, vcc
	v_lshlrev_b32_e32 v117, 2, v117
	ds_bpermute_b32 v117, v117, v116
	v_cvt_pk_bf16_f32 v120, v130, v131
	v_cvt_pk_bf16_f32 v121, v128, v129
	global_store_dwordx4 v[148:149], v[124:127], off
	global_store_dwordx4 v[148:149], v[118:121], off offset:64
	s_and_saveexec_b64 s[18:19], s[16:17]
	s_cbranch_execz .LBB0_522
	s_waitcnt lgkmcnt(0)
	v_add_f32_e32 v118, v116, v117
	v_lshl_add_u64 v[116:117], v[142:143], 2, s[28:29]
	global_atomic_add_f32 v[116:117], v118, off

.LBB0_523:
	v_fmamk_f32 v116, v147, 0x3a800000, v231
	s_waitcnt lgkmcnt(0)
	v_mul_f32_e32 v117, 0x4b800000, v116
	v_cmp_gt_f32_e32 vcc, s11, v116
	v_or_b32_e32 v122, 16, v142
	v_ashrrev_i32_e32 v123, 31, v122
	v_cndmask_b32_e32 v116, v116, v117, vcc
	v_rsq_f32_e32 v116, v116
	s_mov_b64 s[52:53], -1
	v_mul_f32_e32 v117, 0x45800000, v116
	v_cndmask_b32_e32 v120, v116, v117, vcc
	v_cndmask_b32_e64 v116, 0, 1, s[0:1]
	v_cmp_ne_u32_e64 s[20:21], 1, v116
	v_cndmask_b32_e64 v116, 0, 1, s[8:9]
	s_andn2_b64 vcc, exec, s[0:1]
	v_cmp_ne_u32_e64 s[18:19], 1, v116
	s_cbranch_vccnz .LBB0_536
	s_and_b64 vcc, exec, s[18:19]
	s_mov_b64 s[0:1], -1
	s_cbranch_vccnz .LBB0_533
	s_andn2_b64 vcc, exec, s[50:51]
	s_cbranch_vccnz .LBB0_529
	s_andn2_b64 vcc, exec, s[48:49]
	s_cbranch_vccnz .LBB0_528
	v_mov_b64_e32 v[124:125], s[38:39]
	s_movk_i32 s0, 0x480
	v_mad_i64_i32 v[124:125], s[0:1], v122, s0, v[124:125]
	v_mov_b32_e32 v145, v2
	v_mul_f32 v118, v114, v120
	v_mul_f32 v119, v115, v120
	v_mul_f32 v116, v112, v120
	v_mul_f32 v117, v113, v120
	v_lshl_add_u64 v[126:127], v[144:145], 2, v[124:125]
	global_store_dwordx4 v[126:127], v[116:119], off
	v_ashrrev_i32_e32 v145, 31, v144
	v_lshl_add_u64 v[124:125], v[144:145], 2, v[124:125]
	v_mul_f32 v118, v110, v120
	v_mul_f32 v119, v111, v120
	v_mul_f32 v116, v108, v120
	v_mul_f32 v117, v109, v120
	global_store_dwordx4 v[126:127], v[116:119], off offset:16
	s_nop 1
	v_mul_f32 v118, v106, v120
	v_mul_f32 v119, v107, v120
	v_mul_f32 v116, v104, v120
	v_mul_f32 v117, v105, v120
	global_store_dwordx4 v[124:125], v[116:119], off offset:128
	s_nop 1
	v_mul_f32 v118, v102, v120
	v_mul_f32 v119, v103, v120
	v_mul_f32 v116, v100, v120
	v_mul_f32 v117, v101, v120
	global_store_dwordx4 v[124:125], v[116:119], off offset:144

.LBB0_529:
	s_andn2_b64 vcc, exec, s[0:1]
	s_cbranch_vccnz .LBB0_532
	s_andn2_b64 vcc, exec, s[6:7]
	s_cbranch_vccnz .LBB0_532
	v_mov_b64_e32 v[124:125], s[38:39]
	s_movk_i32 s0, 0x480
	v_mad_i64_i32 v[124:125], s[0:1], v122, s0, v[124:125]
	v_lshlrev_b32_e32 v126, 2, v157
	v_mov_b32_e32 v127, v2
	v_mul_f32 v118, v114, v120
	v_mul_f32 v119, v115, v120
	v_mul_f32 v116, v112, v120
	v_mul_f32 v117, v113, v120
	v_lshl_add_u64 v[124:125], v[124:125], 0, v[126:127]
	global_store_dwordx4 v[124:125], v[116:119], off offset:1024
	s_nop 1
	v_mul_f32 v118, v110, v120
	v_mul_f32 v119, v111, v120
	v_mul_f32 v116, v108, v120
	v_mul_f32 v117, v109, v120
	global_store_dwordx4 v[124:125], v[116:119], off offset:1040

.LBB0_533:
	s_andn2_b64 vcc, exec, s[0:1]
	s_cbranch_vccnz .LBB0_535
	v_lshlrev_b64 v[116:117], 9, v[122:123]
	v_lshl_add_u64 v[116:117], s[30:31], 0, v[116:117]
	v_mul_f32 v150, v114, v120
	v_mul_f32 v151, v115, v120
	v_mul_f32 v152, v112, v120
	v_mul_f32 v153, v113, v120
	v_lshl_add_u64 v[154:155], s[68:69], 1, v[116:117]
	v_mul_f32 v116, v150, v150
	v_mul_f32 v117, v151, v151
	v_mul_f32 v118, v152, v152
	v_mul_f32 v119, v153, v153
	v_mul_f32 v146, v110, v120
	v_mul_f32 v147, v111, v120
	v_pk_mov_b32 v[124:125], v[118:119], v[116:117] op_sel:[1,0]
	v_mov_b32_e32 v119, v117
	v_add_f32 v116, v124, v118
	v_add_f32 v117, v125, v119
	v_mul_f32 v148, v108, v120
	v_mul_f32 v149, v109, v120
	v_add_f32 v117, v116, v117
	v_add_f32 v116, v116, v116
	v_mul_f32 v118, v146, v146
	v_mul_f32 v119, v147, v147
	v_mul_f32 v124, v148, v148
	v_mul_f32 v125, v149, v149
	v_mul_f32 v130, v104, v120
	v_mul_f32 v131, v105, v120
	v_pk_mov_b32 v[126:127], v[124:125], v[118:119] op_sel:[1,0]
	v_mov_b32_e32 v125, v119
	v_mul_f32 v128, v106, v120
	v_mul_f32 v129, v107, v120
	v_mul_f32_e32 v116, v130, v130
	v_add_f32 v118, v126, v124
	v_add_f32 v119, v127, v125
	v_fma_f32 v134, v130, v130, v116
	v_fma_f32 v135, v131, v131, v116
	v_mul_f32_e32 v116, v128, v128
	v_add_f32 v119, v118, v119
	v_add_f32 v118, v118, v118
	v_fma_f32 v158, v128, v128, v116
	v_fma_f32 v159, v129, v129, v116
	v_mul_f32 v124, v102, v120
	v_mul_f32 v125, v103, v120
	v_mul_f32 v126, v100, v120
	v_mul_f32 v127, v101, v120
	v_mul_f32_e32 v116, v124, v124
	v_mul_f32_e32 v134, v126, v126
	v_mul_f32_e32 v158, v127, v127
	v_mul_f32_e32 v118, v125, v125
	v_add_f32 v134, v134, v158
	v_add_f32 v135, v135, v159
	v_add_f32 v116, v116, v118
	v_add_f32 v117, v117, v119
	v_and_b32_e32 v118, 64, v236
	v_add_f32 v116, v134, v116
	v_add_f32 v117, v135, v117
	v_add_u32_e32 v118, 64, v118
	v_add_f32_e32 v116, v116, v117
	ds_swizzle_b32 v117, v116 offset:swizzle(SWAP,16)
	v_lshlrev_b32_e32 v121, 2, v157
	v_lshlrev_b32_e32 v162, 1, v157
	v_mov_b32_e32 v163, v2
	v_lshl_add_u64 v[154:155], v[154:155], 0, v[162:163]
	s_waitcnt lgkmcnt(0)
	v_add_f32_e32 v116, v116, v117
	v_xor_b32_e32 v117, 32, v236
	v_cmp_lt_i32_e32 vcc, v117, v118
	s_nop 1
	v_cndmask_b32_e32 v117, v236, v117, vcc
	v_lshlrev_b32_e32 v117, 2, v117
	ds_bpermute_b32 v117, v117, v116
	s_waitcnt lgkmcnt(0)
	v_add_f32_e32 v116, v116, v117
	v_fmamk_f32 v116, v116, 0x3c800000, v231
	v_cmp_gt_f32_e32 vcc, s11, v116
	v_mul_f32_e32 v117, 0x4b800000, v116
	s_nop 0
	v_cndmask_b32_e32 v116, v116, v117, vcc
	v_rsq_f32_e32 v116, v116
	s_nop 0
	v_mul_f32_e32 v117, 0x45800000, v116
	v_cndmask_b32_e32 v116, v116, v117, vcc
	v_mul_f32_e32 v134, 0x3e38aa3b, v116
	global_load_dwordx4 v[116:119], v121, s[36:37] offset:16
	global_load_dwordx4 v[158:161], v121, s[36:37]
	v_mul_f32 v152, v152, v134
	v_mul_f32 v153, v153, v134
	v_mul_f32 v150, v150, v134
	v_mul_f32 v151, v151, v134
	v_mul_f32 v148, v148, v134
	v_mul_f32 v149, v149, v134
	v_mul_f32 v146, v146, v134
	v_mul_f32 v147, v147, v134
	v_mul_f32 v130, v130, v134
	v_mul_f32 v131, v131, v134
	v_mul_f32 v128, v128, v134
	v_mul_f32 v129, v129, v134
	v_mul_f32 v126, v126, v134
	v_mul_f32 v127, v127, v134
	v_mul_f32 v124, v124, v134
	v_mul_f32 v125, v125, v134
	s_waitcnt vmcnt(1)
	v_mul_f32 v146, v118, v146
	v_mul_f32 v147, v119, v147
	s_waitcnt vmcnt(0)
	v_mul_f32 v150, v160, v150
	v_mul_f32 v151, v161, v151
	v_mul_f32 v152, v158, v152
	v_mul_f32 v153, v159, v153
	v_mul_f32 v118, v116, v148
	v_mul_f32 v119, v117, v149
	v_cvt_pk_bf16_f32 v116, v152, v153
	v_cvt_pk_bf16_f32 v117, v150, v151
	v_cvt_pk_bf16_f32 v118, v118, v119
	v_cvt_pk_bf16_f32 v119, v146, v147
	global_store_dwordx4 v[154:155], v[116:119], off offset:-768
	global_load_dwordx4 v[116:119], v121, s[36:37] offset:144
	s_nop 0
	global_load_dwordx4 v[146:149], v121, s[36:37] offset:128
	s_waitcnt vmcnt(1)
	v_mul_f32 v124, v118, v124
	v_mul_f32 v125, v119, v125
	s_waitcnt vmcnt(0)
	v_mul_f32 v128, v148, v128
	v_mul_f32 v129, v149, v129
	v_mul_f32 v130, v146, v130
	v_mul_f32 v131, v147, v131
	v_mul_f32 v118, v116, v126
	v_mul_f32 v119, v117, v127
	v_cvt_pk_bf16_f32 v116, v130, v131
	v_cvt_pk_bf16_f32 v117, v128, v129
	v_cvt_pk_bf16_f32 v118, v118, v119
	v_cvt_pk_bf16_f32 v119, v124, v125
	global_store_dwordx4 v[154:155], v[116:119], off offset:-704

.LBB0_536:
	s_andn2_b64 vcc, exec, s[52:53]
	s_cbranch_vccnz .LBB0_540
	v_mul_f32 v114, v114, v120
	v_mul_f32 v115, v115, v120
	v_mul_f32 v112, v112, v120
	v_mul_f32 v113, v113, v120
	v_mul_f32 v116, v110, v120
	v_mul_f32 v117, v111, v120
	v_mul_f32 v110, v108, v120
	v_mul_f32 v111, v109, v120
	v_mul_f32_e32 v108, v113, v113
	v_mul_f32_e32 v109, v115, v115
	v_fmac_f32_e32 v108, v112, v112
	v_fmac_f32_e32 v109, v114, v114
	v_add_f32_e32 v108, v108, v109
	v_mul_f32_e32 v109, v111, v111
	v_mul_f32_e32 v118, v117, v117
	v_fmac_f32_e32 v109, v110, v110
	v_fmac_f32_e32 v118, v116, v116
	v_add_f32_e32 v109, v109, v118
	v_add_f32_e32 v121, v108, v109
	v_mov_b64_e32 v[108:109], s[26:27]
	s_movk_i32 s0, 0x300
	v_mad_i64_i32 v[108:109], s[0:1], v122, s0, v[108:109]
	v_mul_f32 v106, v106, v120
	v_mul_f32 v107, v107, v120
	v_mul_f32 v104, v104, v120
	v_mul_f32 v105, v105, v120
	v_lshl_add_u64 v[118:119], v[132:133], 1, v[108:109]
	v_cvt_pk_bf16_f32 v109, v114, v115
	v_mul_f32 v114, v100, v120
	v_mul_f32 v115, v101, v120
	v_mul_f32_e32 v100, v105, v105
	v_mul_f32_e32 v101, v107, v107
	v_cvt_pk_bf16_f32 v108, v112, v113
	v_mul_f32 v112, v102, v120
	v_mul_f32 v113, v103, v120
	v_fmac_f32_e32 v100, v104, v104
	v_fmac_f32_e32 v101, v106, v106
	v_add_f32_e32 v100, v100, v101
	v_mul_f32_e32 v101, v115, v115
	v_mul_f32_e32 v102, v113, v113
	v_fmac_f32_e32 v101, v114, v114
	v_fmac_f32_e32 v102, v112, v112
	v_add_f32_e32 v101, v101, v102
	v_add_f32_e32 v100, v100, v101
	v_add_f32_e32 v100, v121, v100
	ds_swizzle_b32 v101, v100 offset:swizzle(SWAP,16)
	v_and_b32_e32 v103, 64, v236
	v_add_u32_e32 v103, 64, v103
	v_cvt_pk_bf16_f32 v110, v110, v111
	v_cvt_pk_bf16_f32 v111, v116, v117
	s_waitcnt lgkmcnt(0)
	v_add_f32_e32 v100, v100, v101
	v_xor_b32_e32 v101, 32, v236
	v_cmp_lt_i32_e32 vcc, v101, v103
	v_cvt_pk_bf16_f32 v102, v104, v105
	v_cvt_pk_bf16_f32 v103, v106, v107
	v_cndmask_b32_e32 v101, v236, v101, vcc
	v_lshlrev_b32_e32 v101, 2, v101
	ds_bpermute_b32 v101, v101, v100
	v_cvt_pk_bf16_f32 v104, v114, v115
	v_cvt_pk_bf16_f32 v105, v112, v113
	global_store_dwordx4 v[118:119], v[108:111], off
	global_store_dwordx4 v[118:119], v[102:105], off offset:64
	s_and_saveexec_b64 s[0:1], s[16:17]
	s_cbranch_execz .LBB0_539
	s_waitcnt lgkmcnt(0)
	v_add_f32_e32 v102, v100, v101
	v_lshl_add_u64 v[100:101], v[142:143], 2, s[28:29]
	global_atomic_add_f32 v[100:101], v102, off offset:64

.LBB0_540:
	v_fmamk_f32 v100, v173, 0x3a800000, v231
	s_waitcnt lgkmcnt(0)
	v_mul_f32_e32 v101, 0x4b800000, v100
	v_cmp_gt_f32_e32 vcc, s11, v100
	v_or_b32_e32 v106, 32, v142
	v_ashrrev_i32_e32 v107, 31, v106
	v_cndmask_b32_e32 v100, v100, v101, vcc
	v_rsq_f32_e32 v100, v100
	s_mov_b64 s[0:1], -1
	v_mul_f32_e32 v101, 0x45800000, v100
	v_cndmask_b32_e32 v104, v100, v101, vcc
	s_and_b64 vcc, exec, s[20:21]
	s_cbranch_vccnz .LBB0_553
	s_and_b64 vcc, exec, s[18:19]
	s_cbranch_vccnz .LBB0_550
	s_andn2_b64 vcc, exec, s[50:51]
	s_cbranch_vccnz .LBB0_546
	s_andn2_b64 vcc, exec, s[48:49]
	s_cbranch_vccnz .LBB0_545
	v_mov_b64_e32 v[108:109], s[38:39]
	s_movk_i32 s0, 0x480
	v_mad_i64_i32 v[108:109], s[0:1], v106, s0, v[108:109]
	v_mov_b32_e32 v145, v2
	v_mul_f32 v102, v98, v104
	v_mul_f32 v103, v99, v104
	v_mul_f32 v100, v96, v104
	v_mul_f32 v101, v97, v104
	v_lshl_add_u64 v[110:111], v[144:145], 2, v[108:109]
	global_store_dwordx4 v[110:111], v[100:103], off
	v_ashrrev_i32_e32 v145, 31, v144
	v_lshl_add_u64 v[108:109], v[144:145], 2, v[108:109]
	v_mul_f32 v102, v94, v104
	v_mul_f32 v103, v95, v104
	v_mul_f32 v100, v92, v104
	v_mul_f32 v101, v93, v104
	global_store_dwordx4 v[110:111], v[100:103], off offset:16
	s_nop 1
	v_mul_f32 v102, v90, v104
	v_mul_f32 v103, v91, v104
	v_mul_f32 v100, v88, v104
	v_mul_f32 v101, v89, v104
	global_store_dwordx4 v[108:109], v[100:103], off offset:128
	s_nop 1
	v_mul_f32 v102, v86, v104
	v_mul_f32 v103, v87, v104
	v_mul_f32 v100, v84, v104
	v_mul_f32 v101, v85, v104
	global_store_dwordx4 v[108:109], v[100:103], off offset:144

.LBB0_546:
	s_andn2_b64 vcc, exec, s[0:1]
	s_cbranch_vccnz .LBB0_549
	s_andn2_b64 vcc, exec, s[6:7]
	s_cbranch_vccnz .LBB0_549
	v_mov_b64_e32 v[108:109], s[38:39]
	s_movk_i32 s0, 0x480
	v_mad_i64_i32 v[108:109], s[0:1], v106, s0, v[108:109]
	v_lshlrev_b32_e32 v110, 2, v157
	v_mov_b32_e32 v111, v2
	v_mul_f32 v102, v98, v104
	v_mul_f32 v103, v99, v104
	v_mul_f32 v100, v96, v104
	v_mul_f32 v101, v97, v104
	v_lshl_add_u64 v[108:109], v[108:109], 0, v[110:111]
	global_store_dwordx4 v[108:109], v[100:103], off offset:1024
	s_nop 1
	v_mul_f32 v102, v94, v104
	v_mul_f32 v103, v95, v104
	v_mul_f32 v100, v92, v104
	v_mul_f32 v101, v93, v104
	global_store_dwordx4 v[108:109], v[100:103], off offset:1040

.LBB0_550:
	s_andn2_b64 vcc, exec, s[0:1]
	s_cbranch_vccnz .LBB0_552
	v_lshlrev_b64 v[100:101], 9, v[106:107]
	v_lshl_add_u64 v[100:101], s[30:31], 0, v[100:101]
	v_mul_f32 v122, v98, v104
	v_mul_f32 v123, v99, v104
	v_mul_f32 v124, v96, v104
	v_mul_f32 v125, v97, v104
	v_lshl_add_u64 v[126:127], s[68:69], 1, v[100:101]
	v_mul_f32 v100, v122, v122
	v_mul_f32 v101, v123, v123
	v_mul_f32 v102, v124, v124
	v_mul_f32 v103, v125, v125
	v_mul_f32 v118, v94, v104
	v_mul_f32 v119, v95, v104
	v_pk_mov_b32 v[108:109], v[102:103], v[100:101] op_sel:[1,0]
	v_mov_b32_e32 v103, v101
	v_add_f32 v100, v108, v102
	v_add_f32 v101, v109, v103
	v_mul_f32 v120, v92, v104
	v_mul_f32 v121, v93, v104
	v_add_f32 v101, v100, v101
	v_add_f32 v100, v100, v100
	v_mul_f32 v102, v118, v118
	v_mul_f32 v103, v119, v119
	v_mul_f32 v108, v120, v120
	v_mul_f32 v109, v121, v121
	v_mul_f32 v114, v88, v104
	v_mul_f32 v115, v89, v104
	v_pk_mov_b32 v[110:111], v[108:109], v[102:103] op_sel:[1,0]
	v_mov_b32_e32 v109, v103
	v_mul_f32 v112, v90, v104
	v_mul_f32 v113, v91, v104
	v_mul_f32_e32 v100, v114, v114
	v_add_f32 v102, v110, v108
	v_add_f32 v103, v111, v109
	v_fma_f32 v116, v114, v114, v100
	v_fma_f32 v117, v115, v115, v100
	v_mul_f32_e32 v100, v112, v112
	v_add_f32 v103, v102, v103
	v_add_f32 v102, v102, v102
	v_fma_f32 v128, v112, v112, v100
	v_fma_f32 v129, v113, v113, v100
	v_mul_f32 v108, v86, v104
	v_mul_f32 v109, v87, v104
	v_mul_f32 v110, v84, v104
	v_mul_f32 v111, v85, v104
	v_mul_f32_e32 v100, v108, v108
	v_mul_f32_e32 v116, v110, v110
	v_mul_f32_e32 v128, v111, v111
	v_mul_f32_e32 v102, v109, v109
	v_add_f32 v116, v116, v128
	v_add_f32 v117, v117, v129
	v_add_f32 v100, v100, v102
	v_add_f32 v101, v101, v103
	v_and_b32_e32 v102, 64, v236
	v_add_f32 v100, v116, v100
	v_add_f32 v101, v117, v101
	v_add_u32_e32 v102, 64, v102
	v_add_f32_e32 v100, v100, v101
	ds_swizzle_b32 v101, v100 offset:swizzle(SWAP,16)
	v_lshlrev_b32_e32 v105, 2, v157
	v_lshlrev_b32_e32 v134, 1, v157
	v_mov_b32_e32 v135, v2
	v_lshl_add_u64 v[126:127], v[126:127], 0, v[134:135]
	s_waitcnt lgkmcnt(0)
	v_add_f32_e32 v100, v100, v101
	v_xor_b32_e32 v101, 32, v236
	v_cmp_lt_i32_e32 vcc, v101, v102
	s_nop 1
	v_cndmask_b32_e32 v101, v236, v101, vcc
	v_lshlrev_b32_e32 v101, 2, v101
	ds_bpermute_b32 v101, v101, v100
	s_waitcnt lgkmcnt(0)
	v_add_f32_e32 v100, v100, v101
	v_fmamk_f32 v100, v100, 0x3c800000, v231
	v_cmp_gt_f32_e32 vcc, s11, v100
	v_mul_f32_e32 v101, 0x4b800000, v100
	s_nop 0
	v_cndmask_b32_e32 v100, v100, v101, vcc
	v_rsq_f32_e32 v100, v100
	s_nop 0
	v_mul_f32_e32 v101, 0x45800000, v100
	v_cndmask_b32_e32 v100, v100, v101, vcc
	v_mul_f32_e32 v116, 0x3e38aa3b, v100
	global_load_dwordx4 v[100:103], v105, s[36:37] offset:16
	global_load_dwordx4 v[128:131], v105, s[36:37]
	v_mul_f32 v124, v124, v116
	v_mul_f32 v125, v125, v116
	v_mul_f32 v122, v122, v116
	v_mul_f32 v123, v123, v116
	v_mul_f32 v120, v120, v116
	v_mul_f32 v121, v121, v116
	v_mul_f32 v118, v118, v116
	v_mul_f32 v119, v119, v116
	v_mul_f32 v114, v114, v116
	v_mul_f32 v115, v115, v116
	v_mul_f32 v112, v112, v116
	v_mul_f32 v113, v113, v116
	v_mul_f32 v110, v110, v116
	v_mul_f32 v111, v111, v116
	v_mul_f32 v108, v108, v116
	v_mul_f32 v109, v109, v116
	s_waitcnt vmcnt(1)
	v_mul_f32 v118, v102, v118
	v_mul_f32 v119, v103, v119
	s_waitcnt vmcnt(0)
	v_mul_f32 v122, v130, v122
	v_mul_f32 v123, v131, v123
	v_mul_f32 v124, v128, v124
	v_mul_f32 v125, v129, v125
	v_mul_f32 v102, v100, v120
	v_mul_f32 v103, v101, v121
	v_cvt_pk_bf16_f32 v100, v124, v125
	v_cvt_pk_bf16_f32 v101, v122, v123
	v_cvt_pk_bf16_f32 v102, v102, v103
	v_cvt_pk_bf16_f32 v103, v118, v119
	global_store_dwordx4 v[126:127], v[100:103], off offset:-768
	global_load_dwordx4 v[100:103], v105, s[36:37] offset:144
	s_nop 0
	global_load_dwordx4 v[118:121], v105, s[36:37] offset:128
	s_waitcnt vmcnt(1)
	v_mul_f32 v108, v102, v108
	v_mul_f32 v109, v103, v109
	s_waitcnt vmcnt(0)
	v_mul_f32 v112, v120, v112
	v_mul_f32 v113, v121, v113
	v_mul_f32 v114, v118, v114
	v_mul_f32 v115, v119, v115
	v_mul_f32 v102, v100, v110
	v_mul_f32 v103, v101, v111
	v_cvt_pk_bf16_f32 v100, v114, v115
	v_cvt_pk_bf16_f32 v101, v112, v113
	v_cvt_pk_bf16_f32 v102, v102, v103
	v_cvt_pk_bf16_f32 v103, v108, v109
	global_store_dwordx4 v[126:127], v[100:103], off offset:-704

.LBB0_553:
	s_andn2_b64 vcc, exec, s[0:1]
	s_cbranch_vccnz .LBB0_557
	v_mul_f32 v98, v98, v104
	v_mul_f32 v99, v99, v104
	v_mul_f32 v96, v96, v104
	v_mul_f32 v97, v97, v104
	v_mul_f32 v100, v94, v104
	v_mul_f32 v101, v95, v104
	v_mul_f32 v94, v92, v104
	v_mul_f32 v95, v93, v104
	v_mul_f32_e32 v92, v97, v97
	v_mul_f32_e32 v93, v99, v99
	v_fmac_f32_e32 v92, v96, v96
	v_fmac_f32_e32 v93, v98, v98
	v_add_f32_e32 v92, v92, v93
	v_mul_f32_e32 v93, v95, v95
	v_mul_f32_e32 v102, v101, v101
	v_fmac_f32_e32 v93, v94, v94
	v_fmac_f32_e32 v102, v100, v100
	v_add_f32_e32 v93, v93, v102
	v_add_f32_e32 v105, v92, v93
	v_mov_b64_e32 v[92:93], s[26:27]
	s_movk_i32 s0, 0x300
	v_mad_i64_i32 v[92:93], s[0:1], v106, s0, v[92:93]
	v_mul_f32 v90, v90, v104
	v_mul_f32 v91, v91, v104
	v_mul_f32 v88, v88, v104
	v_mul_f32 v89, v89, v104
	v_lshl_add_u64 v[102:103], v[132:133], 1, v[92:93]
	v_cvt_pk_bf16_f32 v93, v98, v99
	v_mul_f32 v98, v84, v104
	v_mul_f32 v99, v85, v104
	v_mul_f32_e32 v84, v89, v89
	v_mul_f32_e32 v85, v91, v91
	v_cvt_pk_bf16_f32 v92, v96, v97
	v_mul_f32 v96, v86, v104
	v_mul_f32 v97, v87, v104
	v_fmac_f32_e32 v84, v88, v88
	v_fmac_f32_e32 v85, v90, v90
	v_add_f32_e32 v84, v84, v85
	v_mul_f32_e32 v85, v99, v99
	v_mul_f32_e32 v86, v97, v97
	v_fmac_f32_e32 v85, v98, v98
	v_fmac_f32_e32 v86, v96, v96
	v_add_f32_e32 v85, v85, v86
	v_add_f32_e32 v84, v84, v85
	v_add_f32_e32 v84, v105, v84
	ds_swizzle_b32 v85, v84 offset:swizzle(SWAP,16)
	v_and_b32_e32 v87, 64, v236
	v_add_u32_e32 v87, 64, v87
	v_cvt_pk_bf16_f32 v94, v94, v95
	v_cvt_pk_bf16_f32 v95, v100, v101
	s_waitcnt lgkmcnt(0)
	v_add_f32_e32 v84, v84, v85
	v_xor_b32_e32 v85, 32, v236
	v_cmp_lt_i32_e32 vcc, v85, v87
	v_cvt_pk_bf16_f32 v86, v88, v89
	v_cvt_pk_bf16_f32 v87, v90, v91
	v_cndmask_b32_e32 v85, v236, v85, vcc
	v_lshlrev_b32_e32 v85, 2, v85
	ds_bpermute_b32 v85, v85, v84
	v_cvt_pk_bf16_f32 v88, v98, v99
	v_cvt_pk_bf16_f32 v89, v96, v97
	global_store_dwordx4 v[102:103], v[92:95], off
	global_store_dwordx4 v[102:103], v[86:89], off offset:64
	s_and_saveexec_b64 s[0:1], s[16:17]
	s_cbranch_execz .LBB0_556
	s_waitcnt lgkmcnt(0)
	v_add_f32_e32 v86, v84, v85
	v_lshl_add_u64 v[84:85], v[142:143], 2, s[28:29]
	global_atomic_add_f32 v[84:85], v86, off offset:128

.LBB0_557:
	v_fmamk_f32 v84, v172, 0x3a800000, v231
	s_waitcnt lgkmcnt(0)
	v_mul_f32_e32 v85, 0x4b800000, v84
	v_cmp_gt_f32_e32 vcc, s11, v84
	v_or_b32_e32 v90, 48, v142
	v_ashrrev_i32_e32 v91, 31, v90
	v_cndmask_b32_e32 v84, v84, v85, vcc
	v_rsq_f32_e32 v84, v84
	s_mov_b64 s[0:1], -1
	v_mul_f32_e32 v85, 0x45800000, v84
	v_cndmask_b32_e32 v88, v84, v85, vcc
	s_and_b64 vcc, exec, s[20:21]
	s_cbranch_vccnz .LBB0_570
	s_and_b64 vcc, exec, s[18:19]
	s_cbranch_vccnz .LBB0_567
	s_andn2_b64 vcc, exec, s[50:51]
	s_cbranch_vccnz .LBB0_563
	s_andn2_b64 vcc, exec, s[48:49]
	s_cbranch_vccnz .LBB0_562
	v_mov_b64_e32 v[92:93], s[38:39]
	s_movk_i32 s0, 0x480
	v_mad_i64_i32 v[92:93], s[0:1], v90, s0, v[92:93]
	v_mov_b32_e32 v145, v2
	v_mul_f32 v86, v82, v88
	v_mul_f32 v87, v83, v88
	v_mul_f32 v84, v80, v88
	v_mul_f32 v85, v81, v88
	v_lshl_add_u64 v[94:95], v[144:145], 2, v[92:93]
	global_store_dwordx4 v[94:95], v[84:87], off
	v_ashrrev_i32_e32 v145, 31, v144
	v_lshl_add_u64 v[92:93], v[144:145], 2, v[92:93]
	v_mul_f32 v86, v78, v88
	v_mul_f32 v87, v79, v88
	v_mul_f32 v84, v76, v88
	v_mul_f32 v85, v77, v88
	global_store_dwordx4 v[94:95], v[84:87], off offset:16
	s_nop 1
	v_mul_f32 v86, v74, v88
	v_mul_f32 v87, v75, v88
	v_mul_f32 v84, v72, v88
	v_mul_f32 v85, v73, v88
	global_store_dwordx4 v[92:93], v[84:87], off offset:128
	s_nop 1
	v_mul_f32 v86, v70, v88
	v_mul_f32 v87, v71, v88
	v_mul_f32 v84, v68, v88
	v_mul_f32 v85, v69, v88
	global_store_dwordx4 v[92:93], v[84:87], off offset:144

.LBB0_563:
	s_andn2_b64 vcc, exec, s[0:1]
	s_cbranch_vccnz .LBB0_566
	s_andn2_b64 vcc, exec, s[6:7]
	s_cbranch_vccnz .LBB0_566
	v_mov_b64_e32 v[92:93], s[38:39]
	s_movk_i32 s0, 0x480
	v_mad_i64_i32 v[92:93], s[0:1], v90, s0, v[92:93]
	v_lshlrev_b32_e32 v94, 2, v157
	v_mov_b32_e32 v95, v2
	v_mul_f32 v86, v82, v88
	v_mul_f32 v87, v83, v88
	v_mul_f32 v84, v80, v88
	v_mul_f32 v85, v81, v88
	v_lshl_add_u64 v[92:93], v[92:93], 0, v[94:95]
	global_store_dwordx4 v[92:93], v[84:87], off offset:1024
	s_nop 1
	v_mul_f32 v86, v78, v88
	v_mul_f32 v87, v79, v88
	v_mul_f32 v84, v76, v88
	v_mul_f32 v85, v77, v88
	global_store_dwordx4 v[92:93], v[84:87], off offset:1040

.LBB0_567:
	s_andn2_b64 vcc, exec, s[0:1]
	s_cbranch_vccnz .LBB0_569
	v_lshlrev_b64 v[84:85], 9, v[90:91]
	v_lshl_add_u64 v[84:85], s[30:31], 0, v[84:85]
	v_mul_f32 v106, v82, v88
	v_mul_f32 v107, v83, v88
	v_mul_f32 v108, v80, v88
	v_mul_f32 v109, v81, v88
	v_lshl_add_u64 v[110:111], s[68:69], 1, v[84:85]
	v_mul_f32 v84, v106, v106
	v_mul_f32 v85, v107, v107
	v_mul_f32 v86, v108, v108
	v_mul_f32 v87, v109, v109
	v_mul_f32 v102, v78, v88
	v_mul_f32 v103, v79, v88
	v_pk_mov_b32 v[92:93], v[86:87], v[84:85] op_sel:[1,0]
	v_mov_b32_e32 v87, v85
	v_add_f32 v84, v92, v86
	v_add_f32 v85, v93, v87
	v_mul_f32 v104, v76, v88
	v_mul_f32 v105, v77, v88
	v_add_f32 v85, v84, v85
	v_add_f32 v84, v84, v84
	v_mul_f32 v86, v102, v102
	v_mul_f32 v87, v103, v103
	v_mul_f32 v92, v104, v104
	v_mul_f32 v93, v105, v105
	v_mul_f32 v98, v72, v88
	v_mul_f32 v99, v73, v88
	v_pk_mov_b32 v[94:95], v[92:93], v[86:87] op_sel:[1,0]
	v_mov_b32_e32 v93, v87
	v_mul_f32 v96, v74, v88
	v_mul_f32 v97, v75, v88
	v_mul_f32_e32 v84, v98, v98
	v_add_f32 v86, v94, v92
	v_add_f32 v87, v95, v93
	v_fma_f32 v100, v98, v98, v84
	v_fma_f32 v101, v99, v99, v84
	v_mul_f32_e32 v84, v96, v96
	v_add_f32 v87, v86, v87
	v_add_f32 v86, v86, v86
	v_fma_f32 v112, v96, v96, v84
	v_fma_f32 v113, v97, v97, v84
	v_mul_f32 v92, v70, v88
	v_mul_f32 v93, v71, v88
	v_mul_f32 v94, v68, v88
	v_mul_f32 v95, v69, v88
	v_mul_f32_e32 v84, v92, v92
	v_mul_f32_e32 v100, v94, v94
	v_mul_f32_e32 v112, v95, v95
	v_mul_f32_e32 v86, v93, v93
	v_add_f32 v100, v100, v112
	v_add_f32 v101, v101, v113
	v_add_f32 v84, v84, v86
	v_add_f32 v85, v85, v87
	v_and_b32_e32 v86, 64, v236
	v_add_f32 v84, v100, v84
	v_add_f32 v85, v101, v85
	v_add_u32_e32 v86, 64, v86
	v_add_f32_e32 v84, v84, v85
	ds_swizzle_b32 v85, v84 offset:swizzle(SWAP,16)
	v_lshlrev_b32_e32 v89, 2, v157
	v_lshlrev_b32_e32 v116, 1, v157
	v_mov_b32_e32 v117, v2
	v_lshl_add_u64 v[110:111], v[110:111], 0, v[116:117]
	s_waitcnt lgkmcnt(0)
	v_add_f32_e32 v84, v84, v85
	v_xor_b32_e32 v85, 32, v236
	v_cmp_lt_i32_e32 vcc, v85, v86
	s_nop 1
	v_cndmask_b32_e32 v85, v236, v85, vcc
	v_lshlrev_b32_e32 v85, 2, v85
	ds_bpermute_b32 v85, v85, v84
	s_waitcnt lgkmcnt(0)
	v_add_f32_e32 v84, v84, v85
	v_fmamk_f32 v84, v84, 0x3c800000, v231
	v_cmp_gt_f32_e32 vcc, s11, v84
	v_mul_f32_e32 v85, 0x4b800000, v84
	s_nop 0
	v_cndmask_b32_e32 v84, v84, v85, vcc
	v_rsq_f32_e32 v84, v84
	s_nop 0
	v_mul_f32_e32 v85, 0x45800000, v84
	v_cndmask_b32_e32 v84, v84, v85, vcc
	v_mul_f32_e32 v100, 0x3e38aa3b, v84
	global_load_dwordx4 v[84:87], v89, s[36:37] offset:16
	global_load_dwordx4 v[112:115], v89, s[36:37]
	v_mul_f32 v108, v108, v100
	v_mul_f32 v109, v109, v100
	v_mul_f32 v106, v106, v100
	v_mul_f32 v107, v107, v100
	v_mul_f32 v104, v104, v100
	v_mul_f32 v105, v105, v100
	v_mul_f32 v102, v102, v100
	v_mul_f32 v103, v103, v100
	v_mul_f32 v98, v98, v100
	v_mul_f32 v99, v99, v100
	v_mul_f32 v96, v96, v100
	v_mul_f32 v97, v97, v100
	v_mul_f32 v94, v94, v100
	v_mul_f32 v95, v95, v100
	v_mul_f32 v92, v92, v100
	v_mul_f32 v93, v93, v100
	s_waitcnt vmcnt(1)
	v_mul_f32 v102, v86, v102
	v_mul_f32 v103, v87, v103
	s_waitcnt vmcnt(0)
	v_mul_f32 v106, v114, v106
	v_mul_f32 v107, v115, v107
	v_mul_f32 v108, v112, v108
	v_mul_f32 v109, v113, v109
	v_mul_f32 v86, v84, v104
	v_mul_f32 v87, v85, v105
	v_cvt_pk_bf16_f32 v84, v108, v109
	v_cvt_pk_bf16_f32 v85, v106, v107
	v_cvt_pk_bf16_f32 v86, v86, v87
	v_cvt_pk_bf16_f32 v87, v102, v103
	global_store_dwordx4 v[110:111], v[84:87], off offset:-768
	global_load_dwordx4 v[84:87], v89, s[36:37] offset:144
	s_nop 0
	global_load_dwordx4 v[102:105], v89, s[36:37] offset:128
	s_waitcnt vmcnt(1)
	v_mul_f32 v92, v86, v92
	v_mul_f32 v93, v87, v93
	s_waitcnt vmcnt(0)
	v_mul_f32 v96, v104, v96
	v_mul_f32 v97, v105, v97
	v_mul_f32 v98, v102, v98
	v_mul_f32 v99, v103, v99
	v_mul_f32 v86, v84, v94
	v_mul_f32 v87, v85, v95
	v_cvt_pk_bf16_f32 v84, v98, v99
	v_cvt_pk_bf16_f32 v85, v96, v97
	v_cvt_pk_bf16_f32 v86, v86, v87
	v_cvt_pk_bf16_f32 v87, v92, v93
	global_store_dwordx4 v[110:111], v[84:87], off offset:-704

.LBB0_570:
	s_andn2_b64 vcc, exec, s[0:1]
	s_cbranch_vccnz .LBB0_574
	v_mul_f32 v82, v82, v88
	v_mul_f32 v83, v83, v88
	v_mul_f32 v80, v80, v88
	v_mul_f32 v81, v81, v88
	v_mul_f32 v84, v78, v88
	v_mul_f32 v85, v79, v88
	v_mul_f32 v78, v76, v88
	v_mul_f32 v79, v77, v88
	v_mul_f32_e32 v76, v81, v81
	v_mul_f32_e32 v77, v83, v83
	v_fmac_f32_e32 v76, v80, v80
	v_fmac_f32_e32 v77, v82, v82
	v_add_f32_e32 v76, v76, v77
	v_mul_f32_e32 v77, v79, v79
	v_mul_f32_e32 v86, v85, v85
	v_fmac_f32_e32 v77, v78, v78
	v_fmac_f32_e32 v86, v84, v84
	v_add_f32_e32 v77, v77, v86
	v_add_f32_e32 v89, v76, v77
	v_mov_b64_e32 v[76:77], s[26:27]
	s_movk_i32 s0, 0x300
	v_mad_i64_i32 v[76:77], s[0:1], v90, s0, v[76:77]
	v_mul_f32 v74, v74, v88
	v_mul_f32 v75, v75, v88
	v_mul_f32 v72, v72, v88
	v_mul_f32 v73, v73, v88
	v_lshl_add_u64 v[86:87], v[132:133], 1, v[76:77]
	v_cvt_pk_bf16_f32 v77, v82, v83
	v_mul_f32 v82, v68, v88
	v_mul_f32 v83, v69, v88
	v_mul_f32_e32 v68, v73, v73
	v_mul_f32_e32 v69, v75, v75
	v_cvt_pk_bf16_f32 v76, v80, v81
	v_mul_f32 v80, v70, v88
	v_mul_f32 v81, v71, v88
	v_fmac_f32_e32 v68, v72, v72
	v_fmac_f32_e32 v69, v74, v74
	v_add_f32_e32 v68, v68, v69
	v_mul_f32_e32 v69, v83, v83
	v_mul_f32_e32 v70, v81, v81
	v_fmac_f32_e32 v69, v82, v82
	v_fmac_f32_e32 v70, v80, v80
	v_add_f32_e32 v69, v69, v70
	v_add_f32_e32 v68, v68, v69
	v_add_f32_e32 v68, v89, v68
	ds_swizzle_b32 v69, v68 offset:swizzle(SWAP,16)
	v_and_b32_e32 v71, 64, v236
	v_add_u32_e32 v71, 64, v71
	v_cvt_pk_bf16_f32 v78, v78, v79
	v_cvt_pk_bf16_f32 v79, v84, v85
	s_waitcnt lgkmcnt(0)
	v_add_f32_e32 v68, v68, v69
	v_xor_b32_e32 v69, 32, v236
	v_cmp_lt_i32_e32 vcc, v69, v71
	v_cvt_pk_bf16_f32 v70, v72, v73
	v_cvt_pk_bf16_f32 v71, v74, v75
	v_cndmask_b32_e32 v69, v236, v69, vcc
	v_lshlrev_b32_e32 v69, 2, v69
	ds_bpermute_b32 v69, v69, v68
	v_cvt_pk_bf16_f32 v72, v82, v83
	v_cvt_pk_bf16_f32 v73, v80, v81
	global_store_dwordx4 v[86:87], v[76:79], off
	global_store_dwordx4 v[86:87], v[70:73], off offset:64
	s_and_saveexec_b64 s[0:1], s[16:17]
	s_cbranch_execz .LBB0_573
	s_waitcnt lgkmcnt(0)
	v_add_f32_e32 v70, v68, v69
	v_lshl_add_u64 v[68:69], v[142:143], 2, s[28:29]
	global_atomic_add_f32 v[68:69], v70, off offset:192

.LBB0_574:
	v_fmamk_f32 v68, v171, 0x3a800000, v231
	s_waitcnt lgkmcnt(0)
	v_mul_f32_e32 v69, 0x4b800000, v68
	v_cmp_gt_f32_e32 vcc, s11, v68
	v_add_u32_e32 v74, 0x80, v142
	v_ashrrev_i32_e32 v75, 31, v74
	v_cndmask_b32_e32 v68, v68, v69, vcc
	v_rsq_f32_e32 v68, v68
	s_mov_b64 s[0:1], -1
	v_mul_f32_e32 v69, 0x45800000, v68
	v_cndmask_b32_e32 v72, v68, v69, vcc
	s_and_b64 vcc, exec, s[20:21]
	s_cbranch_vccnz .LBB0_587
	s_and_b64 vcc, exec, s[18:19]
	s_cbranch_vccnz .LBB0_584
	s_andn2_b64 vcc, exec, s[50:51]
	s_cbranch_vccnz .LBB0_580
	s_andn2_b64 vcc, exec, s[48:49]
	s_cbranch_vccnz .LBB0_579
	v_mov_b64_e32 v[76:77], s[38:39]
	s_movk_i32 s0, 0x480
	v_mad_i64_i32 v[76:77], s[0:1], v74, s0, v[76:77]
	v_mov_b32_e32 v145, v2
	v_mul_f32 v70, v66, v72
	v_mul_f32 v71, v67, v72
	v_mul_f32 v68, v64, v72
	v_mul_f32 v69, v65, v72
	v_lshl_add_u64 v[78:79], v[144:145], 2, v[76:77]
	global_store_dwordx4 v[78:79], v[68:71], off
	v_ashrrev_i32_e32 v145, 31, v144
	v_lshl_add_u64 v[76:77], v[144:145], 2, v[76:77]
	v_mul_f32 v70, v62, v72
	v_mul_f32 v71, v63, v72
	v_mul_f32 v68, v60, v72
	v_mul_f32 v69, v61, v72
	global_store_dwordx4 v[78:79], v[68:71], off offset:16
	s_nop 1
	v_mul_f32 v70, v58, v72
	v_mul_f32 v71, v59, v72
	v_mul_f32 v68, v56, v72
	v_mul_f32 v69, v57, v72
	global_store_dwordx4 v[76:77], v[68:71], off offset:128
	s_nop 1
	v_mul_f32 v70, v54, v72
	v_mul_f32 v71, v55, v72
	v_mul_f32 v68, v52, v72
	v_mul_f32 v69, v53, v72
	global_store_dwordx4 v[76:77], v[68:71], off offset:144

.LBB0_580:
	s_andn2_b64 vcc, exec, s[0:1]
	s_cbranch_vccnz .LBB0_583
	s_andn2_b64 vcc, exec, s[6:7]
	s_cbranch_vccnz .LBB0_583
	v_mov_b64_e32 v[76:77], s[38:39]
	s_movk_i32 s0, 0x480
	v_mad_i64_i32 v[76:77], s[0:1], v74, s0, v[76:77]
	v_lshlrev_b32_e32 v78, 2, v157
	v_mov_b32_e32 v79, v2
	v_mul_f32 v70, v66, v72
	v_mul_f32 v71, v67, v72
	v_mul_f32 v68, v64, v72
	v_mul_f32 v69, v65, v72
	v_lshl_add_u64 v[76:77], v[76:77], 0, v[78:79]
	global_store_dwordx4 v[76:77], v[68:71], off offset:1024
	s_nop 1
	v_mul_f32 v70, v62, v72
	v_mul_f32 v71, v63, v72
	v_mul_f32 v68, v60, v72
	v_mul_f32 v69, v61, v72
	global_store_dwordx4 v[76:77], v[68:71], off offset:1040

.LBB0_584:
	s_andn2_b64 vcc, exec, s[0:1]
	s_cbranch_vccnz .LBB0_586
	v_lshlrev_b64 v[68:69], 9, v[74:75]
	v_lshl_add_u64 v[68:69], s[30:31], 0, v[68:69]
	v_mul_f32 v90, v66, v72
	v_mul_f32 v91, v67, v72
	v_mul_f32 v92, v64, v72
	v_mul_f32 v93, v65, v72
	v_lshl_add_u64 v[94:95], s[68:69], 1, v[68:69]
	v_mul_f32 v68, v90, v90
	v_mul_f32 v69, v91, v91
	v_mul_f32 v70, v92, v92
	v_mul_f32 v71, v93, v93
	v_mul_f32 v86, v62, v72
	v_mul_f32 v87, v63, v72
	v_pk_mov_b32 v[76:77], v[70:71], v[68:69] op_sel:[1,0]
	v_mov_b32_e32 v71, v69
	v_add_f32 v68, v76, v70
	v_add_f32 v69, v77, v71
	v_mul_f32 v88, v60, v72
	v_mul_f32 v89, v61, v72
	v_add_f32 v69, v68, v69
	v_add_f32 v68, v68, v68
	v_mul_f32 v70, v86, v86
	v_mul_f32 v71, v87, v87
	v_mul_f32 v76, v88, v88
	v_mul_f32 v77, v89, v89
	v_mul_f32 v82, v56, v72
	v_mul_f32 v83, v57, v72
	v_pk_mov_b32 v[78:79], v[76:77], v[70:71] op_sel:[1,0]
	v_mov_b32_e32 v77, v71
	v_mul_f32 v80, v58, v72
	v_mul_f32 v81, v59, v72
	v_mul_f32_e32 v68, v82, v82
	v_add_f32 v70, v78, v76
	v_add_f32 v71, v79, v77
	v_fma_f32 v84, v82, v82, v68
	v_fma_f32 v85, v83, v83, v68
	v_mul_f32_e32 v68, v80, v80
	v_add_f32 v71, v70, v71
	v_add_f32 v70, v70, v70
	v_fma_f32 v96, v80, v80, v68
	v_fma_f32 v97, v81, v81, v68
	v_mul_f32 v76, v54, v72
	v_mul_f32 v77, v55, v72
	v_mul_f32 v78, v52, v72
	v_mul_f32 v79, v53, v72
	v_mul_f32_e32 v68, v76, v76
	v_mul_f32_e32 v84, v78, v78
	v_mul_f32_e32 v96, v79, v79
	v_mul_f32_e32 v70, v77, v77
	v_add_f32 v84, v84, v96
	v_add_f32 v85, v85, v97
	v_add_f32 v68, v68, v70
	v_add_f32 v69, v69, v71
	v_and_b32_e32 v70, 64, v236
	v_add_f32 v68, v84, v68
	v_add_f32 v69, v85, v69
	v_add_u32_e32 v70, 64, v70
	v_add_f32_e32 v68, v68, v69
	ds_swizzle_b32 v69, v68 offset:swizzle(SWAP,16)
	v_lshlrev_b32_e32 v73, 2, v157
	v_lshlrev_b32_e32 v100, 1, v157
	v_mov_b32_e32 v101, v2
	v_lshl_add_u64 v[94:95], v[94:95], 0, v[100:101]
	s_waitcnt lgkmcnt(0)
	v_add_f32_e32 v68, v68, v69
	v_xor_b32_e32 v69, 32, v236
	v_cmp_lt_i32_e32 vcc, v69, v70
	s_nop 1
	v_cndmask_b32_e32 v69, v236, v69, vcc
	v_lshlrev_b32_e32 v69, 2, v69
	ds_bpermute_b32 v69, v69, v68
	s_waitcnt lgkmcnt(0)
	v_add_f32_e32 v68, v68, v69
	v_fmamk_f32 v68, v68, 0x3c800000, v231
	v_cmp_gt_f32_e32 vcc, s11, v68
	v_mul_f32_e32 v69, 0x4b800000, v68
	s_nop 0
	v_cndmask_b32_e32 v68, v68, v69, vcc
	v_rsq_f32_e32 v68, v68
	s_nop 0
	v_mul_f32_e32 v69, 0x45800000, v68
	v_cndmask_b32_e32 v68, v68, v69, vcc
	v_mul_f32_e32 v84, 0x3e38aa3b, v68
	global_load_dwordx4 v[68:71], v73, s[36:37] offset:16
	global_load_dwordx4 v[96:99], v73, s[36:37]
	v_mul_f32 v92, v92, v84
	v_mul_f32 v93, v93, v84
	v_mul_f32 v90, v90, v84
	v_mul_f32 v91, v91, v84
	v_mul_f32 v88, v88, v84
	v_mul_f32 v89, v89, v84
	v_mul_f32 v86, v86, v84
	v_mul_f32 v87, v87, v84
	v_mul_f32 v82, v82, v84
	v_mul_f32 v83, v83, v84
	v_mul_f32 v80, v80, v84
	v_mul_f32 v81, v81, v84
	v_mul_f32 v78, v78, v84
	v_mul_f32 v79, v79, v84
	v_mul_f32 v76, v76, v84
	v_mul_f32 v77, v77, v84
	s_waitcnt vmcnt(1)
	v_mul_f32 v86, v70, v86
	v_mul_f32 v87, v71, v87
	s_waitcnt vmcnt(0)
	v_mul_f32 v90, v98, v90
	v_mul_f32 v91, v99, v91
	v_mul_f32 v92, v96, v92
	v_mul_f32 v93, v97, v93
	v_mul_f32 v70, v68, v88
	v_mul_f32 v71, v69, v89
	v_cvt_pk_bf16_f32 v68, v92, v93
	v_cvt_pk_bf16_f32 v69, v90, v91
	v_cvt_pk_bf16_f32 v70, v70, v71
	v_cvt_pk_bf16_f32 v71, v86, v87
	global_store_dwordx4 v[94:95], v[68:71], off offset:-768
	global_load_dwordx4 v[68:71], v73, s[36:37] offset:144
	s_nop 0
	global_load_dwordx4 v[86:89], v73, s[36:37] offset:128
	s_waitcnt vmcnt(1)
	v_mul_f32 v76, v70, v76
	v_mul_f32 v77, v71, v77
	s_waitcnt vmcnt(0)
	v_mul_f32 v80, v88, v80
	v_mul_f32 v81, v89, v81
	v_mul_f32 v82, v86, v82
	v_mul_f32 v83, v87, v83
	v_mul_f32 v70, v68, v78
	v_mul_f32 v71, v69, v79
	v_cvt_pk_bf16_f32 v68, v82, v83
	v_cvt_pk_bf16_f32 v69, v80, v81
	v_cvt_pk_bf16_f32 v70, v70, v71
	v_cvt_pk_bf16_f32 v71, v76, v77
	global_store_dwordx4 v[94:95], v[68:71], off offset:-704

.LBB0_587:
	s_andn2_b64 vcc, exec, s[0:1]
	s_cbranch_vccnz .LBB0_591
	v_mul_f32 v66, v66, v72
	v_mul_f32 v67, v67, v72
	v_mul_f32 v64, v64, v72
	v_mul_f32 v65, v65, v72
	v_mul_f32 v68, v62, v72
	v_mul_f32 v69, v63, v72
	v_mul_f32 v62, v60, v72
	v_mul_f32 v63, v61, v72
	v_mul_f32_e32 v60, v65, v65
	v_mul_f32_e32 v61, v67, v67
	v_fmac_f32_e32 v60, v64, v64
	v_fmac_f32_e32 v61, v66, v66
	v_add_f32_e32 v60, v60, v61
	v_mul_f32_e32 v61, v63, v63
	v_mul_f32_e32 v70, v69, v69
	v_fmac_f32_e32 v61, v62, v62
	v_fmac_f32_e32 v70, v68, v68
	v_add_f32_e32 v61, v61, v70
	v_add_f32_e32 v73, v60, v61
	v_mov_b64_e32 v[60:61], s[26:27]
	s_movk_i32 s0, 0x300
	v_mad_i64_i32 v[60:61], s[0:1], v74, s0, v[60:61]
	v_mul_f32 v58, v58, v72
	v_mul_f32 v59, v59, v72
	v_mul_f32 v56, v56, v72
	v_mul_f32 v57, v57, v72
	v_lshl_add_u64 v[70:71], v[132:133], 1, v[60:61]
	v_cvt_pk_bf16_f32 v61, v66, v67
	v_mul_f32 v66, v52, v72
	v_mul_f32 v67, v53, v72
	v_mul_f32_e32 v52, v57, v57
	v_mul_f32_e32 v53, v59, v59
	v_cvt_pk_bf16_f32 v60, v64, v65
	v_mul_f32 v64, v54, v72
	v_mul_f32 v65, v55, v72
	v_fmac_f32_e32 v52, v56, v56
	v_fmac_f32_e32 v53, v58, v58
	v_add_f32_e32 v52, v52, v53
	v_mul_f32_e32 v53, v67, v67
	v_mul_f32_e32 v54, v65, v65
	v_fmac_f32_e32 v53, v66, v66
	v_fmac_f32_e32 v54, v64, v64
	v_add_f32_e32 v53, v53, v54
	v_add_f32_e32 v52, v52, v53
	v_add_f32_e32 v52, v73, v52
	ds_swizzle_b32 v53, v52 offset:swizzle(SWAP,16)
	v_and_b32_e32 v55, 64, v236
	v_add_u32_e32 v55, 64, v55
	v_cvt_pk_bf16_f32 v62, v62, v63
	v_cvt_pk_bf16_f32 v63, v68, v69
	s_waitcnt lgkmcnt(0)
	v_add_f32_e32 v52, v52, v53
	v_xor_b32_e32 v53, 32, v236
	v_cmp_lt_i32_e32 vcc, v53, v55
	v_cvt_pk_bf16_f32 v54, v56, v57
	v_cvt_pk_bf16_f32 v55, v58, v59
	v_cndmask_b32_e32 v53, v236, v53, vcc
	v_lshlrev_b32_e32 v53, 2, v53
	ds_bpermute_b32 v53, v53, v52
	v_cvt_pk_bf16_f32 v56, v66, v67
	v_cvt_pk_bf16_f32 v57, v64, v65
	global_store_dwordx4 v[70:71], v[60:63], off
	global_store_dwordx4 v[70:71], v[54:57], off offset:64
	s_and_saveexec_b64 s[0:1], s[16:17]
	s_cbranch_execz .LBB0_590
	s_waitcnt lgkmcnt(0)
	v_add_f32_e32 v54, v52, v53
	v_lshl_add_u64 v[52:53], v[142:143], 2, s[28:29]
	global_atomic_add_f32 v[52:53], v54, off offset:512

.LBB0_591:
	v_fmamk_f32 v52, v170, 0x3a800000, v231
	s_waitcnt lgkmcnt(0)
	v_mul_f32_e32 v53, 0x4b800000, v52
	v_cmp_gt_f32_e32 vcc, s11, v52
	v_add_u32_e32 v58, 0x90, v142
	v_ashrrev_i32_e32 v59, 31, v58
	v_cndmask_b32_e32 v52, v52, v53, vcc
	v_rsq_f32_e32 v52, v52
	s_mov_b64 s[0:1], -1
	v_mul_f32_e32 v53, 0x45800000, v52
	v_cndmask_b32_e32 v56, v52, v53, vcc
	s_and_b64 vcc, exec, s[20:21]
	s_cbranch_vccnz .LBB0_604
	s_and_b64 vcc, exec, s[18:19]
	s_cbranch_vccnz .LBB0_601
	s_andn2_b64 vcc, exec, s[50:51]
	s_cbranch_vccnz .LBB0_597
	s_andn2_b64 vcc, exec, s[48:49]
	s_cbranch_vccnz .LBB0_596
	v_mov_b64_e32 v[60:61], s[38:39]
	s_movk_i32 s0, 0x480
	v_mad_i64_i32 v[60:61], s[0:1], v58, s0, v[60:61]
	v_mov_b32_e32 v145, v2
	v_mul_f32 v54, v50, v56
	v_mul_f32 v55, v51, v56
	v_mul_f32 v52, v48, v56
	v_mul_f32 v53, v49, v56
	v_lshl_add_u64 v[62:63], v[144:145], 2, v[60:61]
	global_store_dwordx4 v[62:63], v[52:55], off
	v_ashrrev_i32_e32 v145, 31, v144
	v_lshl_add_u64 v[60:61], v[144:145], 2, v[60:61]
	v_mul_f32 v54, v46, v56
	v_mul_f32 v55, v47, v56
	v_mul_f32 v52, v44, v56
	v_mul_f32 v53, v45, v56
	global_store_dwordx4 v[62:63], v[52:55], off offset:16
	s_nop 1
	v_mul_f32 v54, v42, v56
	v_mul_f32 v55, v43, v56
	v_mul_f32 v52, v40, v56
	v_mul_f32 v53, v41, v56
	global_store_dwordx4 v[60:61], v[52:55], off offset:128
	s_nop 1
	v_mul_f32 v54, v38, v56
	v_mul_f32 v55, v39, v56
	v_mul_f32 v52, v36, v56
	v_mul_f32 v53, v37, v56
	global_store_dwordx4 v[60:61], v[52:55], off offset:144

.LBB0_597:
	s_andn2_b64 vcc, exec, s[0:1]
	s_cbranch_vccnz .LBB0_600
	s_andn2_b64 vcc, exec, s[6:7]
	s_cbranch_vccnz .LBB0_600
	v_mov_b64_e32 v[60:61], s[38:39]
	s_movk_i32 s0, 0x480
	v_mad_i64_i32 v[60:61], s[0:1], v58, s0, v[60:61]
	v_lshlrev_b32_e32 v62, 2, v157
	v_mov_b32_e32 v63, v2
	v_mul_f32 v54, v50, v56
	v_mul_f32 v55, v51, v56
	v_mul_f32 v52, v48, v56
	v_mul_f32 v53, v49, v56
	v_lshl_add_u64 v[60:61], v[60:61], 0, v[62:63]
	global_store_dwordx4 v[60:61], v[52:55], off offset:1024
	s_nop 1
	v_mul_f32 v54, v46, v56
	v_mul_f32 v55, v47, v56
	v_mul_f32 v52, v44, v56
	v_mul_f32 v53, v45, v56
	global_store_dwordx4 v[60:61], v[52:55], off offset:1040

.LBB0_601:
	s_andn2_b64 vcc, exec, s[0:1]
	s_cbranch_vccnz .LBB0_603
	v_lshlrev_b64 v[52:53], 9, v[58:59]
	v_lshl_add_u64 v[52:53], s[30:31], 0, v[52:53]
	v_mul_f32 v74, v50, v56
	v_mul_f32 v75, v51, v56
	v_mul_f32 v76, v48, v56
	v_mul_f32 v77, v49, v56
	v_lshl_add_u64 v[78:79], s[68:69], 1, v[52:53]
	v_mul_f32 v52, v74, v74
	v_mul_f32 v53, v75, v75
	v_mul_f32 v54, v76, v76
	v_mul_f32 v55, v77, v77
	v_mul_f32 v70, v46, v56
	v_mul_f32 v71, v47, v56
	v_pk_mov_b32 v[60:61], v[54:55], v[52:53] op_sel:[1,0]
	v_mov_b32_e32 v55, v53
	v_add_f32 v52, v60, v54
	v_add_f32 v53, v61, v55
	v_mul_f32 v72, v44, v56
	v_mul_f32 v73, v45, v56
	v_add_f32 v53, v52, v53
	v_add_f32 v52, v52, v52
	v_mul_f32 v54, v70, v70
	v_mul_f32 v55, v71, v71
	v_mul_f32 v60, v72, v72
	v_mul_f32 v61, v73, v73
	v_mul_f32 v66, v40, v56
	v_mul_f32 v67, v41, v56
	v_pk_mov_b32 v[62:63], v[60:61], v[54:55] op_sel:[1,0]
	v_mov_b32_e32 v61, v55
	v_mul_f32 v64, v42, v56
	v_mul_f32 v65, v43, v56
	v_mul_f32_e32 v52, v66, v66
	v_add_f32 v54, v62, v60
	v_add_f32 v55, v63, v61
	v_fma_f32 v68, v66, v66, v52
	v_fma_f32 v69, v67, v67, v52
	v_mul_f32_e32 v52, v64, v64
	v_add_f32 v55, v54, v55
	v_add_f32 v54, v54, v54
	v_fma_f32 v80, v64, v64, v52
	v_fma_f32 v81, v65, v65, v52
	v_mul_f32 v60, v38, v56
	v_mul_f32 v61, v39, v56
	v_mul_f32 v62, v36, v56
	v_mul_f32 v63, v37, v56
	v_mul_f32_e32 v52, v60, v60
	v_mul_f32_e32 v68, v62, v62
	v_mul_f32_e32 v80, v63, v63
	v_mul_f32_e32 v54, v61, v61
	v_add_f32 v68, v68, v80
	v_add_f32 v69, v69, v81
	v_add_f32 v52, v52, v54
	v_add_f32 v53, v53, v55
	v_and_b32_e32 v54, 64, v236
	v_add_f32 v52, v68, v52
	v_add_f32 v53, v69, v53
	v_add_u32_e32 v54, 64, v54
	v_add_f32_e32 v52, v52, v53
	ds_swizzle_b32 v53, v52 offset:swizzle(SWAP,16)
	v_lshlrev_b32_e32 v57, 2, v157
	v_lshlrev_b32_e32 v84, 1, v157
	v_mov_b32_e32 v85, v2
	v_lshl_add_u64 v[78:79], v[78:79], 0, v[84:85]
	s_waitcnt lgkmcnt(0)
	v_add_f32_e32 v52, v52, v53
	v_xor_b32_e32 v53, 32, v236
	v_cmp_lt_i32_e32 vcc, v53, v54
	s_nop 1
	v_cndmask_b32_e32 v53, v236, v53, vcc
	v_lshlrev_b32_e32 v53, 2, v53
	ds_bpermute_b32 v53, v53, v52
	s_waitcnt lgkmcnt(0)
	v_add_f32_e32 v52, v52, v53
	v_fmamk_f32 v52, v52, 0x3c800000, v231
	v_cmp_gt_f32_e32 vcc, s11, v52
	v_mul_f32_e32 v53, 0x4b800000, v52
	s_nop 0
	v_cndmask_b32_e32 v52, v52, v53, vcc
	v_rsq_f32_e32 v52, v52
	s_nop 0
	v_mul_f32_e32 v53, 0x45800000, v52
	v_cndmask_b32_e32 v52, v52, v53, vcc
	v_mul_f32_e32 v68, 0x3e38aa3b, v52
	global_load_dwordx4 v[52:55], v57, s[36:37] offset:16
	global_load_dwordx4 v[80:83], v57, s[36:37]
	v_mul_f32 v76, v76, v68
	v_mul_f32 v77, v77, v68
	v_mul_f32 v74, v74, v68
	v_mul_f32 v75, v75, v68
	v_mul_f32 v72, v72, v68
	v_mul_f32 v73, v73, v68
	v_mul_f32 v70, v70, v68
	v_mul_f32 v71, v71, v68
	v_mul_f32 v66, v66, v68
	v_mul_f32 v67, v67, v68
	v_mul_f32 v64, v64, v68
	v_mul_f32 v65, v65, v68
	v_mul_f32 v62, v62, v68
	v_mul_f32 v63, v63, v68
	v_mul_f32 v60, v60, v68
	v_mul_f32 v61, v61, v68
	s_waitcnt vmcnt(1)
	v_mul_f32 v70, v54, v70
	v_mul_f32 v71, v55, v71
	s_waitcnt vmcnt(0)
	v_mul_f32 v74, v82, v74
	v_mul_f32 v75, v83, v75
	v_mul_f32 v76, v80, v76
	v_mul_f32 v77, v81, v77
	v_mul_f32 v54, v52, v72
	v_mul_f32 v55, v53, v73
	v_cvt_pk_bf16_f32 v52, v76, v77
	v_cvt_pk_bf16_f32 v53, v74, v75
	v_cvt_pk_bf16_f32 v54, v54, v55
	v_cvt_pk_bf16_f32 v55, v70, v71
	global_store_dwordx4 v[78:79], v[52:55], off offset:-768
	global_load_dwordx4 v[52:55], v57, s[36:37] offset:144
	s_nop 0
	global_load_dwordx4 v[70:73], v57, s[36:37] offset:128
	s_waitcnt vmcnt(1)
	v_mul_f32 v60, v54, v60
	v_mul_f32 v61, v55, v61
	s_waitcnt vmcnt(0)
	v_mul_f32 v64, v72, v64
	v_mul_f32 v65, v73, v65
	v_mul_f32 v66, v70, v66
	v_mul_f32 v67, v71, v67
	v_mul_f32 v54, v52, v62
	v_mul_f32 v55, v53, v63
	v_cvt_pk_bf16_f32 v52, v66, v67
	v_cvt_pk_bf16_f32 v53, v64, v65
	v_cvt_pk_bf16_f32 v54, v54, v55
	v_cvt_pk_bf16_f32 v55, v60, v61
	global_store_dwordx4 v[78:79], v[52:55], off offset:-704

.LBB0_604:
	s_andn2_b64 vcc, exec, s[0:1]
	s_cbranch_vccnz .LBB0_608
	v_mul_f32 v50, v50, v56
	v_mul_f32 v51, v51, v56
	v_mul_f32 v48, v48, v56
	v_mul_f32 v49, v49, v56
	v_mul_f32 v52, v46, v56
	v_mul_f32 v53, v47, v56
	v_mul_f32 v46, v44, v56
	v_mul_f32 v47, v45, v56
	v_mul_f32_e32 v44, v49, v49
	v_mul_f32_e32 v45, v51, v51
	v_fmac_f32_e32 v44, v48, v48
	v_fmac_f32_e32 v45, v50, v50
	v_add_f32_e32 v44, v44, v45
	v_mul_f32_e32 v45, v47, v47
	v_mul_f32_e32 v54, v53, v53
	v_fmac_f32_e32 v45, v46, v46
	v_fmac_f32_e32 v54, v52, v52
	v_add_f32_e32 v45, v45, v54
	v_add_f32_e32 v57, v44, v45
	v_mov_b64_e32 v[44:45], s[26:27]
	s_movk_i32 s0, 0x300
	v_mad_i64_i32 v[44:45], s[0:1], v58, s0, v[44:45]
	v_mul_f32 v42, v42, v56
	v_mul_f32 v43, v43, v56
	v_mul_f32 v40, v40, v56
	v_mul_f32 v41, v41, v56
	v_lshl_add_u64 v[54:55], v[132:133], 1, v[44:45]
	v_cvt_pk_bf16_f32 v45, v50, v51
	v_mul_f32 v50, v36, v56
	v_mul_f32 v51, v37, v56
	v_mul_f32_e32 v36, v41, v41
	v_mul_f32_e32 v37, v43, v43
	v_cvt_pk_bf16_f32 v44, v48, v49
	v_mul_f32 v48, v38, v56
	v_mul_f32 v49, v39, v56
	v_fmac_f32_e32 v36, v40, v40
	v_fmac_f32_e32 v37, v42, v42
	v_add_f32_e32 v36, v36, v37
	v_mul_f32_e32 v37, v51, v51
	v_mul_f32_e32 v38, v49, v49
	v_fmac_f32_e32 v37, v50, v50
	v_fmac_f32_e32 v38, v48, v48
	v_add_f32_e32 v37, v37, v38
	v_add_f32_e32 v36, v36, v37
	v_add_f32_e32 v36, v57, v36
	ds_swizzle_b32 v37, v36 offset:swizzle(SWAP,16)
	v_and_b32_e32 v39, 64, v236
	v_add_u32_e32 v39, 64, v39
	v_cvt_pk_bf16_f32 v46, v46, v47
	v_cvt_pk_bf16_f32 v47, v52, v53
	s_waitcnt lgkmcnt(0)
	v_add_f32_e32 v36, v36, v37
	v_xor_b32_e32 v37, 32, v236
	v_cmp_lt_i32_e32 vcc, v37, v39
	v_cvt_pk_bf16_f32 v38, v40, v41
	v_cvt_pk_bf16_f32 v39, v42, v43
	v_cndmask_b32_e32 v37, v236, v37, vcc
	v_lshlrev_b32_e32 v37, 2, v37
	ds_bpermute_b32 v37, v37, v36
	v_cvt_pk_bf16_f32 v40, v50, v51
	v_cvt_pk_bf16_f32 v41, v48, v49
	global_store_dwordx4 v[54:55], v[44:47], off
	global_store_dwordx4 v[54:55], v[38:41], off offset:64
	s_and_saveexec_b64 s[0:1], s[16:17]
	s_cbranch_execz .LBB0_607
	s_waitcnt lgkmcnt(0)
	v_add_f32_e32 v38, v36, v37
	v_lshl_add_u64 v[36:37], v[142:143], 2, s[28:29]
	global_atomic_add_f32 v[36:37], v38, off offset:576

.LBB0_608:
	v_fmamk_f32 v36, v169, 0x3a800000, v231
	s_waitcnt lgkmcnt(0)
	v_mul_f32_e32 v37, 0x4b800000, v36
	v_cmp_gt_f32_e32 vcc, s11, v36
	v_add_u32_e32 v42, 0xa0, v142
	v_ashrrev_i32_e32 v43, 31, v42
	v_cndmask_b32_e32 v36, v36, v37, vcc
	v_rsq_f32_e32 v36, v36
	s_mov_b64 s[0:1], -1
	v_mul_f32_e32 v37, 0x45800000, v36
	v_cndmask_b32_e32 v40, v36, v37, vcc
	s_and_b64 vcc, exec, s[20:21]
	s_cbranch_vccnz .LBB0_621
	s_and_b64 vcc, exec, s[18:19]
	s_cbranch_vccnz .LBB0_618
	s_andn2_b64 vcc, exec, s[50:51]
	s_cbranch_vccnz .LBB0_614
	s_andn2_b64 vcc, exec, s[48:49]
	s_cbranch_vccnz .LBB0_613
	v_mov_b64_e32 v[44:45], s[38:39]
	s_movk_i32 s0, 0x480
	v_mad_i64_i32 v[44:45], s[0:1], v42, s0, v[44:45]
	v_mov_b32_e32 v145, v2
	v_mul_f32 v38, v34, v40
	v_mul_f32 v39, v35, v40
	v_mul_f32 v36, v32, v40
	v_mul_f32 v37, v33, v40
	v_lshl_add_u64 v[46:47], v[144:145], 2, v[44:45]
	global_store_dwordx4 v[46:47], v[36:39], off
	v_ashrrev_i32_e32 v145, 31, v144
	v_lshl_add_u64 v[44:45], v[144:145], 2, v[44:45]
	v_mul_f32 v38, v30, v40
	v_mul_f32 v39, v31, v40
	v_mul_f32 v36, v28, v40
	v_mul_f32 v37, v29, v40
	global_store_dwordx4 v[46:47], v[36:39], off offset:16
	s_nop 1
	v_mul_f32 v38, v26, v40
	v_mul_f32 v39, v27, v40
	v_mul_f32 v36, v24, v40
	v_mul_f32 v37, v25, v40
	global_store_dwordx4 v[44:45], v[36:39], off offset:128
	s_nop 1
	v_mul_f32 v38, v22, v40
	v_mul_f32 v39, v23, v40
	v_mul_f32 v36, v20, v40
	v_mul_f32 v37, v21, v40
	global_store_dwordx4 v[44:45], v[36:39], off offset:144

.LBB0_614:
	s_andn2_b64 vcc, exec, s[0:1]
	s_cbranch_vccnz .LBB0_617
	s_andn2_b64 vcc, exec, s[6:7]
	s_cbranch_vccnz .LBB0_617
	v_mov_b64_e32 v[44:45], s[38:39]
	s_movk_i32 s0, 0x480
	v_mad_i64_i32 v[44:45], s[0:1], v42, s0, v[44:45]
	v_lshlrev_b32_e32 v46, 2, v157
	v_mov_b32_e32 v47, v2
	v_mul_f32 v38, v34, v40
	v_mul_f32 v39, v35, v40
	v_mul_f32 v36, v32, v40
	v_mul_f32 v37, v33, v40
	v_lshl_add_u64 v[44:45], v[44:45], 0, v[46:47]
	global_store_dwordx4 v[44:45], v[36:39], off offset:1024
	s_nop 1
	v_mul_f32 v38, v30, v40
	v_mul_f32 v39, v31, v40
	v_mul_f32 v36, v28, v40
	v_mul_f32 v37, v29, v40
	global_store_dwordx4 v[44:45], v[36:39], off offset:1040

.LBB0_618:
	s_andn2_b64 vcc, exec, s[0:1]
	s_cbranch_vccnz .LBB0_620
	v_lshlrev_b64 v[36:37], 9, v[42:43]
	v_lshl_add_u64 v[36:37], s[30:31], 0, v[36:37]
	v_mul_f32 v58, v34, v40
	v_mul_f32 v59, v35, v40
	v_mul_f32 v60, v32, v40
	v_mul_f32 v61, v33, v40
	v_lshl_add_u64 v[62:63], s[68:69], 1, v[36:37]
	v_mul_f32 v36, v58, v58
	v_mul_f32 v37, v59, v59
	v_mul_f32 v38, v60, v60
	v_mul_f32 v39, v61, v61
	v_mul_f32 v54, v30, v40
	v_mul_f32 v55, v31, v40
	v_pk_mov_b32 v[44:45], v[38:39], v[36:37] op_sel:[1,0]
	v_mov_b32_e32 v39, v37
	v_add_f32 v36, v44, v38
	v_add_f32 v37, v45, v39
	v_mul_f32 v56, v28, v40
	v_mul_f32 v57, v29, v40
	v_add_f32 v37, v36, v37
	v_add_f32 v36, v36, v36
	v_mul_f32 v38, v54, v54
	v_mul_f32 v39, v55, v55
	v_mul_f32 v44, v56, v56
	v_mul_f32 v45, v57, v57
	v_mul_f32 v50, v24, v40
	v_mul_f32 v51, v25, v40
	v_pk_mov_b32 v[46:47], v[44:45], v[38:39] op_sel:[1,0]
	v_mov_b32_e32 v45, v39
	v_mul_f32 v48, v26, v40
	v_mul_f32 v49, v27, v40
	v_mul_f32_e32 v36, v50, v50
	v_add_f32 v38, v46, v44
	v_add_f32 v39, v47, v45
	v_fma_f32 v52, v50, v50, v36
	v_fma_f32 v53, v51, v51, v36
	v_mul_f32_e32 v36, v48, v48
	v_add_f32 v39, v38, v39
	v_add_f32 v38, v38, v38
	v_fma_f32 v64, v48, v48, v36
	v_fma_f32 v65, v49, v49, v36
	v_mul_f32 v44, v22, v40
	v_mul_f32 v45, v23, v40
	v_mul_f32 v46, v20, v40
	v_mul_f32 v47, v21, v40
	v_mul_f32_e32 v36, v44, v44
	v_mul_f32_e32 v52, v46, v46
	v_mul_f32_e32 v64, v47, v47
	v_mul_f32_e32 v38, v45, v45
	v_add_f32 v52, v52, v64
	v_add_f32 v53, v53, v65
	v_add_f32 v36, v36, v38
	v_add_f32 v37, v37, v39
	v_and_b32_e32 v38, 64, v236
	v_add_f32 v36, v52, v36
	v_add_f32 v37, v53, v37
	v_add_u32_e32 v38, 64, v38
	v_add_f32_e32 v36, v36, v37
	ds_swizzle_b32 v37, v36 offset:swizzle(SWAP,16)
	v_lshlrev_b32_e32 v41, 2, v157
	v_lshlrev_b32_e32 v68, 1, v157
	v_mov_b32_e32 v69, v2
	v_lshl_add_u64 v[62:63], v[62:63], 0, v[68:69]
	s_waitcnt lgkmcnt(0)
	v_add_f32_e32 v36, v36, v37
	v_xor_b32_e32 v37, 32, v236
	v_cmp_lt_i32_e32 vcc, v37, v38
	s_nop 1
	v_cndmask_b32_e32 v37, v236, v37, vcc
	v_lshlrev_b32_e32 v37, 2, v37
	ds_bpermute_b32 v37, v37, v36
	s_waitcnt lgkmcnt(0)
	v_add_f32_e32 v36, v36, v37
	v_fmamk_f32 v36, v36, 0x3c800000, v231
	v_cmp_gt_f32_e32 vcc, s11, v36
	v_mul_f32_e32 v37, 0x4b800000, v36
	s_nop 0
	v_cndmask_b32_e32 v36, v36, v37, vcc
	v_rsq_f32_e32 v36, v36
	s_nop 0
	v_mul_f32_e32 v37, 0x45800000, v36
	v_cndmask_b32_e32 v36, v36, v37, vcc
	v_mul_f32_e32 v52, 0x3e38aa3b, v36
	global_load_dwordx4 v[36:39], v41, s[36:37] offset:16
	global_load_dwordx4 v[64:67], v41, s[36:37]
	v_mul_f32 v60, v60, v52
	v_mul_f32 v61, v61, v52
	v_mul_f32 v58, v58, v52
	v_mul_f32 v59, v59, v52
	v_mul_f32 v56, v56, v52
	v_mul_f32 v57, v57, v52
	v_mul_f32 v54, v54, v52
	v_mul_f32 v55, v55, v52
	v_mul_f32 v50, v50, v52
	v_mul_f32 v51, v51, v52
	v_mul_f32 v48, v48, v52
	v_mul_f32 v49, v49, v52
	v_mul_f32 v46, v46, v52
	v_mul_f32 v47, v47, v52
	v_mul_f32 v44, v44, v52
	v_mul_f32 v45, v45, v52
	s_waitcnt vmcnt(1)
	v_mul_f32 v54, v38, v54
	v_mul_f32 v55, v39, v55
	s_waitcnt vmcnt(0)
	v_mul_f32 v58, v66, v58
	v_mul_f32 v59, v67, v59
	v_mul_f32 v60, v64, v60
	v_mul_f32 v61, v65, v61
	v_mul_f32 v38, v36, v56
	v_mul_f32 v39, v37, v57
	v_cvt_pk_bf16_f32 v36, v60, v61
	v_cvt_pk_bf16_f32 v37, v58, v59
	v_cvt_pk_bf16_f32 v38, v38, v39
	v_cvt_pk_bf16_f32 v39, v54, v55
	global_store_dwordx4 v[62:63], v[36:39], off offset:-768
	global_load_dwordx4 v[36:39], v41, s[36:37] offset:144
	s_nop 0
	global_load_dwordx4 v[54:57], v41, s[36:37] offset:128
	s_waitcnt vmcnt(1)
	v_mul_f32 v44, v38, v44
	v_mul_f32 v45, v39, v45
	s_waitcnt vmcnt(0)
	v_mul_f32 v48, v56, v48
	v_mul_f32 v49, v57, v49
	v_mul_f32 v50, v54, v50
	v_mul_f32 v51, v55, v51
	v_mul_f32 v38, v36, v46
	v_mul_f32 v39, v37, v47
	v_cvt_pk_bf16_f32 v36, v50, v51
	v_cvt_pk_bf16_f32 v37, v48, v49
	v_cvt_pk_bf16_f32 v38, v38, v39
	v_cvt_pk_bf16_f32 v39, v44, v45
	global_store_dwordx4 v[62:63], v[36:39], off offset:-704

.LBB0_621:
	s_andn2_b64 vcc, exec, s[0:1]
	s_cbranch_vccnz .LBB0_625
	v_mul_f32 v34, v34, v40
	v_mul_f32 v35, v35, v40
	v_mul_f32 v32, v32, v40
	v_mul_f32 v33, v33, v40
	v_mul_f32 v36, v30, v40
	v_mul_f32 v37, v31, v40
	v_mul_f32 v30, v28, v40
	v_mul_f32 v31, v29, v40
	v_mul_f32_e32 v28, v33, v33
	v_mul_f32_e32 v29, v35, v35
	v_fmac_f32_e32 v28, v32, v32
	v_fmac_f32_e32 v29, v34, v34
	v_add_f32_e32 v28, v28, v29
	v_mul_f32_e32 v29, v31, v31
	v_mul_f32_e32 v38, v37, v37
	v_fmac_f32_e32 v29, v30, v30
	v_fmac_f32_e32 v38, v36, v36
	v_add_f32_e32 v29, v29, v38
	v_add_f32_e32 v41, v28, v29
	v_mov_b64_e32 v[28:29], s[26:27]
	s_movk_i32 s0, 0x300
	v_mad_i64_i32 v[28:29], s[0:1], v42, s0, v[28:29]
	v_mul_f32 v26, v26, v40
	v_mul_f32 v27, v27, v40
	v_mul_f32 v24, v24, v40
	v_mul_f32 v25, v25, v40
	v_lshl_add_u64 v[38:39], v[132:133], 1, v[28:29]
	v_cvt_pk_bf16_f32 v29, v34, v35
	v_mul_f32 v34, v20, v40
	v_mul_f32 v35, v21, v40
	v_mul_f32_e32 v20, v25, v25
	v_mul_f32_e32 v21, v27, v27
	v_cvt_pk_bf16_f32 v28, v32, v33
	v_mul_f32 v32, v22, v40
	v_mul_f32 v33, v23, v40
	v_fmac_f32_e32 v20, v24, v24
	v_fmac_f32_e32 v21, v26, v26
	v_add_f32_e32 v20, v20, v21
	v_mul_f32_e32 v21, v35, v35
	v_mul_f32_e32 v22, v33, v33
	v_fmac_f32_e32 v21, v34, v34
	v_fmac_f32_e32 v22, v32, v32
	v_add_f32_e32 v21, v21, v22
	v_add_f32_e32 v20, v20, v21
	v_add_f32_e32 v20, v41, v20
	ds_swizzle_b32 v21, v20 offset:swizzle(SWAP,16)
	v_and_b32_e32 v23, 64, v236
	v_add_u32_e32 v23, 64, v23
	v_cvt_pk_bf16_f32 v30, v30, v31
	v_cvt_pk_bf16_f32 v31, v36, v37
	s_waitcnt lgkmcnt(0)
	v_add_f32_e32 v20, v20, v21
	v_xor_b32_e32 v21, 32, v236
	v_cmp_lt_i32_e32 vcc, v21, v23
	v_cvt_pk_bf16_f32 v22, v24, v25
	v_cvt_pk_bf16_f32 v23, v26, v27
	v_cndmask_b32_e32 v21, v236, v21, vcc
	v_lshlrev_b32_e32 v21, 2, v21
	ds_bpermute_b32 v21, v21, v20
	v_cvt_pk_bf16_f32 v24, v34, v35
	v_cvt_pk_bf16_f32 v25, v32, v33
	global_store_dwordx4 v[38:39], v[28:31], off
	global_store_dwordx4 v[38:39], v[22:25], off offset:64
	s_and_saveexec_b64 s[0:1], s[16:17]
	s_cbranch_execz .LBB0_624
	s_waitcnt lgkmcnt(0)
	v_add_f32_e32 v22, v20, v21
	v_lshl_add_u64 v[20:21], v[142:143], 2, s[28:29]
	global_atomic_add_f32 v[20:21], v22, off offset:640

.LBB0_625:
	v_fmamk_f32 v20, v168, 0x3a800000, v231
	s_waitcnt lgkmcnt(0)
	v_mul_f32_e32 v21, 0x4b800000, v20
	v_cmp_gt_f32_e32 vcc, s11, v20
	v_add_u32_e32 v26, 0xb0, v142
	v_ashrrev_i32_e32 v27, 31, v26
	v_cndmask_b32_e32 v20, v20, v21, vcc
	v_rsq_f32_e32 v20, v20
	s_mov_b64 s[0:1], -1
	v_mul_f32_e32 v21, 0x45800000, v20
	v_cndmask_b32_e32 v24, v20, v21, vcc
	s_and_b64 vcc, exec, s[20:21]
	s_cbranch_vccnz .LBB0_638
	s_and_b64 vcc, exec, s[18:19]
	s_cbranch_vccnz .LBB0_635
	s_andn2_b64 vcc, exec, s[50:51]
	s_cbranch_vccnz .LBB0_631
	s_andn2_b64 vcc, exec, s[48:49]
	s_cbranch_vccnz .LBB0_630
	v_mov_b64_e32 v[28:29], s[38:39]
	s_movk_i32 s0, 0x480
	v_mad_i64_i32 v[28:29], s[0:1], v26, s0, v[28:29]
	v_mov_b32_e32 v145, v2
	v_mul_f32 v22, v18, v24
	v_mul_f32 v23, v19, v24
	v_mul_f32 v20, v16, v24
	v_mul_f32 v21, v17, v24
	v_lshl_add_u64 v[30:31], v[144:145], 2, v[28:29]
	global_store_dwordx4 v[30:31], v[20:23], off
	v_ashrrev_i32_e32 v145, 31, v144
	v_lshl_add_u64 v[28:29], v[144:145], 2, v[28:29]
	v_mul_f32 v22, v14, v24
	v_mul_f32 v23, v15, v24
	v_mul_f32 v20, v12, v24
	v_mul_f32 v21, v13, v24
	global_store_dwordx4 v[30:31], v[20:23], off offset:16
	s_nop 1
	v_mul_f32 v22, v10, v24
	v_mul_f32 v23, v11, v24
	v_mul_f32 v20, v8, v24
	v_mul_f32 v21, v9, v24
	global_store_dwordx4 v[28:29], v[20:23], off offset:128
	s_nop 1
	v_mul_f32 v22, v6, v24
	v_mul_f32 v23, v7, v24
	v_mul_f32 v20, v4, v24
	v_mul_f32 v21, v5, v24
	global_store_dwordx4 v[28:29], v[20:23], off offset:144

.LBB0_631:
	s_andn2_b64 vcc, exec, s[0:1]
	s_cbranch_vccnz .LBB0_634
	s_andn2_b64 vcc, exec, s[6:7]
	s_cbranch_vccnz .LBB0_634
	v_mov_b64_e32 v[28:29], s[38:39]
	s_movk_i32 s0, 0x480
	v_mad_i64_i32 v[28:29], s[0:1], v26, s0, v[28:29]
	v_lshlrev_b32_e32 v30, 2, v157
	v_mov_b32_e32 v31, v2
	v_mul_f32 v22, v18, v24
	v_mul_f32 v23, v19, v24
	v_mul_f32 v20, v16, v24
	v_mul_f32 v21, v17, v24
	v_lshl_add_u64 v[28:29], v[28:29], 0, v[30:31]
	global_store_dwordx4 v[28:29], v[20:23], off offset:1024
	s_nop 1
	v_mul_f32 v22, v14, v24
	v_mul_f32 v23, v15, v24
	v_mul_f32 v20, v12, v24
	v_mul_f32 v21, v13, v24
	global_store_dwordx4 v[28:29], v[20:23], off offset:1040

.LBB0_635:
	s_andn2_b64 vcc, exec, s[0:1]
	s_cbranch_vccnz .LBB0_637
	v_lshlrev_b64 v[20:21], 9, v[26:27]
	v_lshl_add_u64 v[20:21], s[30:31], 0, v[20:21]
	v_mul_f32 v42, v18, v24
	v_mul_f32 v43, v19, v24
	v_mul_f32 v44, v16, v24
	v_mul_f32 v45, v17, v24
	v_lshl_add_u64 v[46:47], s[68:69], 1, v[20:21]
	v_mul_f32 v20, v42, v42
	v_mul_f32 v21, v43, v43
	v_mul_f32 v22, v44, v44
	v_mul_f32 v23, v45, v45
	v_mul_f32 v38, v14, v24
	v_mul_f32 v39, v15, v24
	v_pk_mov_b32 v[28:29], v[22:23], v[20:21] op_sel:[1,0]
	v_mov_b32_e32 v23, v21
	v_add_f32 v20, v28, v22
	v_add_f32 v21, v29, v23
	v_mul_f32 v40, v12, v24
	v_mul_f32 v41, v13, v24
	v_add_f32 v21, v20, v21
	v_add_f32 v20, v20, v20
	v_mul_f32 v22, v38, v38
	v_mul_f32 v23, v39, v39
	v_mul_f32 v28, v40, v40
	v_mul_f32 v29, v41, v41
	v_mul_f32 v34, v8, v24
	v_mul_f32 v35, v9, v24
	v_pk_mov_b32 v[30:31], v[28:29], v[22:23] op_sel:[1,0]
	v_mov_b32_e32 v29, v23
	v_mul_f32 v32, v10, v24
	v_mul_f32 v33, v11, v24
	v_mul_f32_e32 v20, v34, v34
	v_add_f32 v22, v30, v28
	v_add_f32 v23, v31, v29
	v_fma_f32 v36, v34, v34, v20
	v_fma_f32 v37, v35, v35, v20
	v_mul_f32_e32 v20, v32, v32
	v_add_f32 v23, v22, v23
	v_add_f32 v22, v22, v22
	v_fma_f32 v48, v32, v32, v20
	v_fma_f32 v49, v33, v33, v20
	v_mul_f32 v28, v6, v24
	v_mul_f32 v29, v7, v24
	v_mul_f32 v30, v4, v24
	v_mul_f32 v31, v5, v24
	v_mul_f32_e32 v20, v28, v28
	v_mul_f32_e32 v36, v30, v30
	v_mul_f32_e32 v48, v31, v31
	v_mul_f32_e32 v22, v29, v29
	v_add_f32 v36, v36, v48
	v_add_f32 v37, v37, v49
	v_add_f32 v20, v20, v22
	v_add_f32 v21, v21, v23
	v_and_b32_e32 v22, 64, v236
	v_add_f32 v20, v36, v20
	v_add_f32 v21, v37, v21
	v_add_u32_e32 v22, 64, v22
	v_add_f32_e32 v20, v20, v21
	ds_swizzle_b32 v21, v20 offset:swizzle(SWAP,16)
	v_lshlrev_b32_e32 v25, 2, v157
	v_lshlrev_b32_e32 v52, 1, v157
	v_mov_b32_e32 v53, v2
	v_lshl_add_u64 v[46:47], v[46:47], 0, v[52:53]
	s_waitcnt lgkmcnt(0)
	v_add_f32_e32 v20, v20, v21
	v_xor_b32_e32 v21, 32, v236
	v_cmp_lt_i32_e32 vcc, v21, v22
	s_nop 1
	v_cndmask_b32_e32 v21, v236, v21, vcc
	v_lshlrev_b32_e32 v21, 2, v21
	ds_bpermute_b32 v21, v21, v20
	s_waitcnt lgkmcnt(0)
	v_add_f32_e32 v20, v20, v21
	v_fmamk_f32 v20, v20, 0x3c800000, v231
	v_cmp_gt_f32_e32 vcc, s11, v20
	v_mul_f32_e32 v21, 0x4b800000, v20
	s_nop 0
	v_cndmask_b32_e32 v20, v20, v21, vcc
	v_rsq_f32_e32 v20, v20
	s_nop 0
	v_mul_f32_e32 v21, 0x45800000, v20
	v_cndmask_b32_e32 v20, v20, v21, vcc
	v_mul_f32_e32 v36, 0x3e38aa3b, v20
	global_load_dwordx4 v[20:23], v25, s[36:37] offset:16
	global_load_dwordx4 v[48:51], v25, s[36:37]
	v_mul_f32 v44, v44, v36
	v_mul_f32 v45, v45, v36
	v_mul_f32 v42, v42, v36
	v_mul_f32 v43, v43, v36
	v_mul_f32 v40, v40, v36
	v_mul_f32 v41, v41, v36
	v_mul_f32 v38, v38, v36
	v_mul_f32 v39, v39, v36
	v_mul_f32 v34, v34, v36
	v_mul_f32 v35, v35, v36
	v_mul_f32 v32, v32, v36
	v_mul_f32 v33, v33, v36
	v_mul_f32 v30, v30, v36
	v_mul_f32 v31, v31, v36
	v_mul_f32 v28, v28, v36
	v_mul_f32 v29, v29, v36
	s_waitcnt vmcnt(1)
	v_mul_f32 v38, v22, v38
	v_mul_f32 v39, v23, v39
	s_waitcnt vmcnt(0)
	v_mul_f32 v42, v50, v42
	v_mul_f32 v43, v51, v43
	v_mul_f32 v44, v48, v44
	v_mul_f32 v45, v49, v45
	v_mul_f32 v22, v20, v40
	v_mul_f32 v23, v21, v41
	v_cvt_pk_bf16_f32 v20, v44, v45
	v_cvt_pk_bf16_f32 v21, v42, v43
	v_cvt_pk_bf16_f32 v22, v22, v23
	v_cvt_pk_bf16_f32 v23, v38, v39
	global_store_dwordx4 v[46:47], v[20:23], off offset:-768
	global_load_dwordx4 v[20:23], v25, s[36:37] offset:144
	s_nop 0
	global_load_dwordx4 v[38:41], v25, s[36:37] offset:128
	s_waitcnt vmcnt(1)
	v_mul_f32 v28, v22, v28
	v_mul_f32 v29, v23, v29
	s_waitcnt vmcnt(0)
	v_mul_f32 v32, v40, v32
	v_mul_f32 v33, v41, v33
	v_mul_f32 v34, v38, v34
	v_mul_f32 v35, v39, v35
	v_mul_f32 v22, v20, v30
	v_mul_f32 v23, v21, v31
	v_cvt_pk_bf16_f32 v20, v34, v35
	v_cvt_pk_bf16_f32 v21, v32, v33
	v_cvt_pk_bf16_f32 v22, v22, v23
	v_cvt_pk_bf16_f32 v23, v28, v29
	global_store_dwordx4 v[46:47], v[20:23], off offset:-704

.LBB0_638:
	s_andn2_b64 vcc, exec, s[0:1]
	s_cbranch_vccnz .LBB0_497
	v_mul_f32 v18, v18, v24
	v_mul_f32 v19, v19, v24
	v_mul_f32 v16, v16, v24
	v_mul_f32 v17, v17, v24
	v_mul_f32 v20, v14, v24
	v_mul_f32 v21, v15, v24
	v_mul_f32 v14, v12, v24
	v_mul_f32 v15, v13, v24
	v_mul_f32_e32 v12, v17, v17
	v_mul_f32_e32 v13, v19, v19
	v_fmac_f32_e32 v12, v16, v16
	v_fmac_f32_e32 v13, v18, v18
	v_add_f32_e32 v12, v12, v13
	v_mul_f32_e32 v13, v15, v15
	v_mul_f32_e32 v22, v21, v21
	v_fmac_f32_e32 v13, v14, v14
	v_fmac_f32_e32 v22, v20, v20
	v_add_f32_e32 v13, v13, v22
	v_add_f32_e32 v25, v12, v13
	v_mov_b64_e32 v[12:13], s[26:27]
	s_movk_i32 s0, 0x300
	v_mad_i64_i32 v[12:13], s[0:1], v26, s0, v[12:13]
	v_mul_f32 v10, v10, v24
	v_mul_f32 v11, v11, v24
	v_mul_f32 v8, v8, v24
	v_mul_f32 v9, v9, v24
	v_lshl_add_u64 v[22:23], v[132:133], 1, v[12:13]
	v_cvt_pk_bf16_f32 v13, v18, v19
	v_mul_f32 v18, v4, v24
	v_mul_f32 v19, v5, v24
	v_mul_f32_e32 v4, v9, v9
	v_mul_f32_e32 v5, v11, v11
	v_cvt_pk_bf16_f32 v12, v16, v17
	v_mul_f32 v16, v6, v24
	v_mul_f32 v17, v7, v24
	v_fmac_f32_e32 v4, v8, v8
	v_fmac_f32_e32 v5, v10, v10
	v_add_f32_e32 v4, v4, v5
	v_mul_f32_e32 v5, v19, v19
	v_mul_f32_e32 v6, v17, v17
	v_fmac_f32_e32 v5, v18, v18
	v_fmac_f32_e32 v6, v16, v16
	v_add_f32_e32 v5, v5, v6
	v_add_f32_e32 v4, v4, v5
	v_add_f32_e32 v4, v25, v4
	ds_swizzle_b32 v5, v4 offset:swizzle(SWAP,16)
	v_and_b32_e32 v7, 64, v236
	v_add_u32_e32 v7, 64, v7
	v_cvt_pk_bf16_f32 v14, v14, v15
	v_cvt_pk_bf16_f32 v15, v20, v21
	s_waitcnt lgkmcnt(0)
	v_add_f32_e32 v4, v4, v5
	v_xor_b32_e32 v5, 32, v236
	v_cmp_lt_i32_e32 vcc, v5, v7
	v_cvt_pk_bf16_f32 v6, v8, v9
	v_cvt_pk_bf16_f32 v7, v10, v11
	v_cndmask_b32_e32 v5, v236, v5, vcc
	v_lshlrev_b32_e32 v5, 2, v5
	ds_bpermute_b32 v5, v5, v4
	v_cvt_pk_bf16_f32 v8, v18, v19
	v_cvt_pk_bf16_f32 v9, v16, v17
	global_store_dwordx4 v[22:23], v[12:15], off
	global_store_dwordx4 v[22:23], v[6:9], off offset:64
	s_and_saveexec_b64 s[0:1], s[16:17]
	s_cbranch_execz .LBB0_496
	s_waitcnt lgkmcnt(0)
	v_add_f32_e32 v6, v4, v5
	v_lshl_add_u64 v[4:5], v[142:143], 2, s[28:29]
	global_atomic_add_f32 v[4:5], v6, off offset:704
	s_branch .LBB0_496

.LBB0_740:
	s_or_b64 exec, exec, s[48:49]
	s_waitcnt vmcnt(0)
	v_mul_f32_e32 v63, v19, v19
	v_mul_f32_e32 v65, v18, v18
	v_mul_f32_e32 v64, v17, v17
	v_mul_f32_e32 v62, v16, v16
	v_add_f32 v62, v64, v62
	v_add_f32 v63, v65, v63
	s_nop 0
	v_add_f32_e32 v29, v62, v63
	ds_swizzle_b32 v31, v29 offset:swizzle(SWAP,1)
	s_waitcnt lgkmcnt(0)
	v_add_f32_e32 v29, v29, v31
	ds_swizzle_b32 v31, v29 offset:swizzle(SWAP,2)
	s_waitcnt lgkmcnt(0)
	v_add_f32_e32 v29, v29, v31
	ds_swizzle_b32 v31, v29 offset:swizzle(SWAP,4)
	s_waitcnt lgkmcnt(0)
	v_add_f32_e32 v29, v29, v31
	ds_swizzle_b32 v31, v29 offset:swizzle(SWAP,8)
	s_waitcnt lgkmcnt(0)
	v_add_f32_e32 v29, v29, v31
	ds_swizzle_b32 v31, v29 offset:swizzle(SWAP,16)
	s_waitcnt lgkmcnt(0)
	v_add_f32_e32 v29, v29, v31
	s_nop 0
	v_readlane_b32 s49, v29, 32
	v_readlane_b32 s48, v29, 0
	s_nop 0
	v_mov_b32_e32 v29, s49
	v_add_f32_e32 v29, s48, v29
	v_fmamk_f32 v29, v29, 0x3b800000, v231
	v_cmp_gt_f32_e32 vcc, s11, v29
	v_mul_f32_e32 v31, 0x4b800000, v29
	s_nop 0
	v_cndmask_b32_e32 v29, v29, v31, vcc
	v_rsq_f32_e32 v29, v29
	s_nop 0
	v_mul_f32_e32 v31, 0x45800000, v29
	v_cndmask_b32_e32 v62, v29, v31, vcc
	v_mul_f32 v16, v16, v62
	v_mul_f32 v17, v17, v62
	v_mul_f32 v18, v18, v62
	v_mul_f32 v19, v19, v62
	v_mul_f32 v16, v4, v16
	v_mul_f32 v17, v5, v17
	v_mul_f32 v18, v6, v18
	v_mul_f32 v19, v7, v19
	v_lshl_add_u64 v[62:63], v[60:61], 0, v[48:49]
	global_store_dwordx4 v[62:63], v[16:19], off
	s_nop 1
	v_cvt_pk_bf16_f32 v16, v16, v17
	v_cvt_pk_bf16_f32 v17, v18, v19
	v_lshl_add_u64 v[18:19], s[30:31], 0, v[50:51]
	global_store_dwordx2 v[18:19], v[16:17], off
	s_and_saveexec_b64 s[48:49], s[16:17]
	s_cbranch_execz .LBB0_742
	v_mul_f32_e32 v16, v30, v32
	v_fma_f32 v18, v28, v34, -v16
	v_lshl_add_u64 v[16:17], v[52:53], 0, v[48:49]
	v_add_co_u32_e32 v16, vcc, 0x4100000, v16
	v_mul_f32_e32 v19, v30, v34
	s_nop 0
	v_addc_co_u32_e32 v17, vcc, 0, v17, vcc
	v_fmac_f32_e32 v19, v28, v32
	global_store_dword v[16:17], v18, off offset:1024
	global_store_dword v[16:17], v19, off offset:1088
	v_lshl_add_u64 v[16:17], s[30:31], 0, v[54:55]
	v_add_co_u32_e32 v16, vcc, 0x13b6e000, v16
	v_cvt_pk_bf16_f32 v18, v18, s0
	s_nop 0
	v_addc_co_u32_e32 v17, vcc, 0, v17, vcc
	global_store_short v[16:17], v18, off offset:3584
	v_cvt_pk_bf16_f32 v18, v19, s0
	global_store_short v[16:17], v18, off offset:3616
.LBB0_742:
	s_or_b64 exec, exec, s[48:49]
	v_mul_f32_e32 v17, v11, v11
	v_mul_f32_e32 v19, v10, v10
	v_mul_f32_e32 v18, v9, v9
	v_mul_f32_e32 v16, v8, v8
	v_mul_f32_e32 v29, v15, v15
	v_mul_f32_e32 v31, v14, v14
	v_mul_f32_e32 v30, v13, v13
	v_mul_f32_e32 v28, v12, v12
	s_and_saveexec_b64 s[48:49], s[20:21]
	s_cbranch_execz .LBB0_745
	v_add_f32 v28, v30, v28
	v_add_f32 v29, v31, v29
	s_nop 0
	v_add_f32_e32 v28, v28, v29
	ds_swizzle_b32 v29, v28 offset:swizzle(SWAP,1)
	s_waitcnt lgkmcnt(0)
	v_add_f32_e32 v28, v28, v29
	ds_swizzle_b32 v29, v28 offset:swizzle(SWAP,2)
	s_waitcnt lgkmcnt(0)
	v_add_f32_e32 v28, v28, v29
	ds_swizzle_b32 v29, v28 offset:swizzle(SWAP,4)
	s_waitcnt lgkmcnt(0)
	v_add_f32_e32 v28, v28, v29
	ds_swizzle_b32 v29, v28 offset:swizzle(SWAP,8)
	s_waitcnt lgkmcnt(0)
	v_add_f32_e32 v28, v28, v29
	ds_swizzle_b32 v29, v28 offset:swizzle(SWAP,16)
	s_waitcnt lgkmcnt(0)
	v_add_f32_e32 v28, v28, v29
	s_nop 0
	v_readlane_b32 s21, v28, 32
	v_readlane_b32 s20, v28, 0
	s_nop 0
	v_mov_b32_e32 v28, s21
	v_add_f32_e32 v28, s20, v28
	v_fmamk_f32 v28, v28, 0x3b800000, v231
	v_cmp_gt_f32_e32 vcc, s11, v28
	v_mul_f32_e32 v29, 0x4b800000, v28
	s_movk_i32 s20, 0x120
	v_cndmask_b32_e32 v28, v28, v29, vcc
	v_rsq_f32_e32 v28, v28
	s_nop 0
	v_mul_f32_e32 v29, 0x45800000, v28
	v_cndmask_b32_e32 v28, v28, v29, vcc
	v_mul_f32 v12, v12, v28
	v_mul_f32 v13, v13, v28
	v_mul_f32 v14, v14, v28
	v_mul_f32 v15, v15, v28
	v_mul_f32 v28, v4, v12
	v_mul_f32 v29, v5, v13
	v_mad_i64_i32 v[12:13], s[20:21], v35, s20, 0
	v_mul_f32 v30, v6, v14
	v_mul_f32 v31, v7, v15
	v_lshl_add_u64 v[14:15], v[12:13], 2, v[44:45]
	global_store_dwordx4 v[14:15], v[28:31], off
	v_cvt_pk_bf16_f32 v14, v28, v29
	v_cvt_pk_bf16_f32 v15, v30, v31
	v_lshl_add_u64 v[28:29], v[12:13], 1, v[46:47]
	global_store_dwordx2 v[28:29], v[14:15], off
	s_and_b64 exec, exec, s[16:17]
	s_cbranch_execz .LBB0_745
	v_mul_f32_e32 v14, v3, v21
	v_fma_f32 v30, v1, v23, -v14
	v_mul_f32_e32 v3, v3, v23
	v_lshl_add_u64 v[14:15], v[12:13], 0, v[40:41]
	v_fmac_f32_e32 v3, v1, v21
	v_lshl_add_u64 v[28:29], v[14:15], 2, s[44:45]
	v_lshl_add_u64 v[12:13], v[12:13], 0, v[42:43]
	v_cvt_pk_bf16_f32 v1, v30, s0
	v_lshl_add_u64 v[14:15], v[14:15], 1, s[46:47]
	global_store_dword v[28:29], v30, off
	v_lshl_add_u64 v[28:29], v[12:13], 2, s[44:45]
	global_store_short v[14:15], v1, off
	v_cvt_pk_bf16_f32 v1, v3, s0
	v_lshl_add_u64 v[12:13], v[12:13], 1, s[46:47]
	global_store_dword v[28:29], v3, off
	global_store_short v[12:13], v1, off
.LBB0_745:
	s_or_b64 exec, exec, s[48:49]
	s_and_saveexec_b64 s[20:21], s[18:19]
	s_cbranch_execz .LBB0_729
	v_add_f32 v12, v18, v16
	v_add_f32 v13, v19, v17
	s_nop 0
	v_add_f32_e32 v1, v12, v13
	ds_swizzle_b32 v3, v1 offset:swizzle(SWAP,1)
	s_waitcnt lgkmcnt(0)
	v_add_f32_e32 v1, v1, v3
	ds_swizzle_b32 v3, v1 offset:swizzle(SWAP,2)
	s_waitcnt lgkmcnt(0)
	v_add_f32_e32 v1, v1, v3
	ds_swizzle_b32 v3, v1 offset:swizzle(SWAP,4)
	s_waitcnt lgkmcnt(0)
	v_add_f32_e32 v1, v1, v3
	ds_swizzle_b32 v3, v1 offset:swizzle(SWAP,8)
	s_waitcnt lgkmcnt(0)
	v_add_f32_e32 v1, v1, v3
	ds_swizzle_b32 v3, v1 offset:swizzle(SWAP,16)
	s_waitcnt lgkmcnt(0)
	v_add_f32_e32 v1, v1, v3
	s_nop 0
	v_readlane_b32 s19, v1, 32
	v_readlane_b32 s18, v1, 0
	s_nop 0
	v_mov_b32_e32 v1, s19
	v_add_f32_e32 v1, s18, v1
	v_fmamk_f32 v1, v1, 0x3b800000, v231
	v_cmp_gt_f32_e32 vcc, s11, v1
	v_mul_f32_e32 v3, 0x4b800000, v1
	s_movk_i32 s18, 0x120
	v_cndmask_b32_e32 v1, v1, v3, vcc
	v_rsq_f32_e32 v1, v1
	s_nop 0
	v_mul_f32_e32 v3, 0x45800000, v1
	v_cndmask_b32_e32 v12, v1, v3, vcc
	v_mul_f32 v8, v8, v12
	v_mul_f32 v9, v9, v12
	v_mul_f32 v10, v10, v12
	v_mul_f32 v11, v11, v12
	s_nop 0
	v_mul_f32 v12, v6, v10
	v_mul_f32 v13, v7, v11
	v_mul_f32 v10, v4, v8
	v_mul_f32 v11, v5, v9
	v_mad_i64_i32 v[8:9], s[18:19], v33, s18, 0
	v_lshl_add_u64 v[14:15], v[8:9], 2, v[44:45]
	global_store_dwordx4 v[14:15], v[10:13], off
	s_nop 1
	v_cvt_pk_bf16_f32 v10, v10, v11
	v_cvt_pk_bf16_f32 v11, v12, v13
	v_lshl_add_u64 v[12:13], v[8:9], 1, v[46:47]
	global_store_dwordx2 v[12:13], v[10:11], off
	s_and_b64 exec, exec, s[16:17]
	s_cbranch_execz .LBB0_729
	v_mul_f32_e32 v1, v22, v24
	v_lshl_add_u64 v[10:11], v[8:9], 0, v[40:41]
	v_fma_f32 v1, v20, v26, -v1
	v_mul_f32_e32 v3, v22, v26
	v_lshl_add_u64 v[12:13], v[10:11], 2, s[44:45]
	v_fmac_f32_e32 v3, v20, v24
	global_store_dword v[12:13], v1, off
	v_lshl_add_u64 v[8:9], v[8:9], 0, v[42:43]
	v_cvt_pk_bf16_f32 v1, v1, s0
	v_lshl_add_u64 v[10:11], v[10:11], 1, s[46:47]
	v_lshl_add_u64 v[12:13], v[8:9], 2, s[44:45]
	global_store_short v[10:11], v1, off
	v_cvt_pk_bf16_f32 v1, v3, s0
	v_lshl_add_u64 v[8:9], v[8:9], 1, s[46:47]
	global_store_dword v[12:13], v3, off
	global_store_short v[8:9], v1, off
	s_branch .LBB0_729

.LBB0_769:
	s_add_u32 s0, s8, 0x100
	s_addc_u32 s1, s9, 0
	s_cmp_eq_u32 s62, 2
	s_cselect_b32 s22, s42, s0
	s_cselect_b32 s23, s43, s1
	s_cselect_b32 s18, s44, s47
	s_cselect_b32 s19, s45, s49
	s_add_u32 s20, s22, 0x80
	s_addc_u32 s21, s23, 0
	s_add_i32 s64, 0, 0x10000
	v_add_u32_e32 v144, s64, v1
	ds_read_b128 v[132:135], v144
	ds_read_b128 v[136:139], v144 offset:1024
	ds_read_b128 v[140:143], v144 offset:2048
	ds_read_b128 v[144:147], v144 offset:3072
	s_add_u32 s8, s8, 0x18080
	s_addc_u32 s9, s9, 0
	ds_read_b128 v[152:155], v3
	ds_read_b128 v[156:159], v3 offset:1024
	ds_read_b128 v[160:163], v3 offset:2048
	ds_read_b128 v[164:167], v3 offset:3072
	ds_read_b128 v[168:171], v3 offset:4096
	ds_read_b128 v[172:175], v3 offset:5120
	ds_read_b128 v[176:179], v3 offset:6144
	ds_read_b128 v[180:183], v3 offset:7168
	s_add_i32 m0, s57, 0xc000
	s_nop 0
	global_load_lds_dwordx4 v148, s[8:9]
	s_add_i32 m0, s57, 0xe000
	s_nop 0
	global_load_lds_dwordx4 v150, s[8:9]
	s_waitcnt lgkmcnt(8)
	s_barrier
	s_waitcnt lgkmcnt(0)
	s_setprio 1
	s_waitcnt lgkmcnt(0)
	v_mfma_f32_16x16x32_bf16 v[128:131], v[132:135], v[152:155], v[128:131]
	v_mfma_f32_16x16x32_bf16 v[124:127], v[140:143], v[152:155], v[124:127]
	v_mfma_f32_16x16x32_bf16 v[112:115], v[132:135], v[160:163], v[112:115]
	v_mfma_f32_16x16x32_bf16 v[108:111], v[140:143], v[160:163], v[108:111]
	v_mfma_f32_16x16x32_bf16 v[96:99], v[132:135], v[168:171], v[96:99]
	v_mfma_f32_16x16x32_bf16 v[92:95], v[140:143], v[168:171], v[92:95]
	v_mfma_f32_16x16x32_bf16 v[80:83], v[132:135], v[176:179], v[80:83]
	v_mfma_f32_16x16x32_bf16 v[76:79], v[140:143], v[176:179], v[76:79]
	v_mfma_f32_16x16x32_bf16 v[128:131], v[136:139], v[156:159], v[128:131]
	v_mfma_f32_16x16x32_bf16 v[124:127], v[144:147], v[156:159], v[124:127]
	v_mfma_f32_16x16x32_bf16 v[112:115], v[136:139], v[164:167], v[112:115]
	v_mfma_f32_16x16x32_bf16 v[108:111], v[144:147], v[164:167], v[108:111]
	v_mfma_f32_16x16x32_bf16 v[96:99], v[136:139], v[172:175], v[96:99]
	v_mfma_f32_16x16x32_bf16 v[92:95], v[144:147], v[172:175], v[92:95]
	v_mfma_f32_16x16x32_bf16 v[80:83], v[136:139], v[180:183], v[80:83]
	v_mfma_f32_16x16x32_bf16 v[76:79], v[144:147], v[180:183], v[76:79]
	s_setprio 0
	s_barrier
	s_add_i32 s65, 0, 0x14000
	v_add_u32_e32 v210, s65, v1
	s_mov_b64 s[8:9], s[18:19]
	s_add_i32 s64, s64, s56
	ds_read_b128 v[184:187], v210
	ds_read_b128 v[188:191], v210 offset:1024
	ds_read_b128 v[192:195], v210 offset:2048
	ds_read_b128 v[210:213], v210 offset:3072
	s_mov_b32 m0, s64
	s_nop 0
	global_load_lds_dwordx4 v148, s[8:9]
	s_add_i32 m0, s64, 0x2000
	s_nop 0
	global_load_lds_dwordx4 v150, s[8:9]
	s_barrier
	s_waitcnt lgkmcnt(0)
	s_setprio 1
	s_waitcnt lgkmcnt(0)
	v_mfma_f32_16x16x32_bf16 v[120:123], v[184:187], v[152:155], v[120:123]
	v_mfma_f32_16x16x32_bf16 v[116:119], v[192:195], v[152:155], v[116:119]
	v_mfma_f32_16x16x32_bf16 v[104:107], v[184:187], v[160:163], v[104:107]
	v_mfma_f32_16x16x32_bf16 v[100:103], v[192:195], v[160:163], v[100:103]
	v_mfma_f32_16x16x32_bf16 v[88:91], v[184:187], v[168:171], v[88:91]
	v_mfma_f32_16x16x32_bf16 v[84:87], v[192:195], v[168:171], v[84:87]
	v_mfma_f32_16x16x32_bf16 v[72:75], v[184:187], v[176:179], v[72:75]
	v_mfma_f32_16x16x32_bf16 v[68:71], v[192:195], v[176:179], v[68:71]
	v_mfma_f32_16x16x32_bf16 v[120:123], v[188:191], v[156:159], v[120:123]
	v_mfma_f32_16x16x32_bf16 v[116:119], v[210:213], v[156:159], v[116:119]
	v_mfma_f32_16x16x32_bf16 v[104:107], v[188:191], v[164:167], v[104:107]
	v_mfma_f32_16x16x32_bf16 v[100:103], v[210:213], v[164:167], v[100:103]
	v_mfma_f32_16x16x32_bf16 v[88:91], v[188:191], v[172:175], v[88:91]
	v_mfma_f32_16x16x32_bf16 v[84:87], v[210:213], v[172:175], v[84:87]
	v_mfma_f32_16x16x32_bf16 v[72:75], v[188:191], v[180:183], v[72:75]
	v_mfma_f32_16x16x32_bf16 v[68:71], v[210:213], v[180:183], v[68:71]
	s_setprio 0
	s_mov_b64 s[8:9], s[22:23]
	s_mov_b32 m0, s57
	s_barrier
	ds_read_b128 v[152:155], v3 offset:16384
	ds_read_b128 v[156:159], v3 offset:17408
	ds_read_b128 v[160:163], v3 offset:18432
	ds_read_b128 v[164:167], v3 offset:19456
	ds_read_b128 v[168:171], v3 offset:20480
	ds_read_b128 v[172:175], v3 offset:21504
	ds_read_b128 v[176:179], v3 offset:22528
	ds_read_b128 v[180:183], v3 offset:23552
	s_nop 0
	global_load_lds_dwordx4 v148, s[8:9]
	s_mov_b32 m0, s63
	s_nop 0
	global_load_lds_dwordx4 v150, s[8:9]
	s_barrier
	s_waitcnt lgkmcnt(0)
	s_setprio 1
	s_waitcnt lgkmcnt(0)
	v_mfma_f32_16x16x32_bf16 v[64:67], v[132:135], v[152:155], v[64:67]
	v_mfma_f32_16x16x32_bf16 v[60:63], v[140:143], v[152:155], v[60:63]
	v_mfma_f32_16x16x32_bf16 v[48:51], v[132:135], v[160:163], v[48:51]
	v_mfma_f32_16x16x32_bf16 v[44:47], v[140:143], v[160:163], v[44:47]
	v_mfma_f32_16x16x32_bf16 v[32:35], v[132:135], v[168:171], v[32:35]
	v_mfma_f32_16x16x32_bf16 v[28:31], v[140:143], v[168:171], v[28:31]
	v_mfma_f32_16x16x32_bf16 v[16:19], v[132:135], v[176:179], v[16:19]
	v_mfma_f32_16x16x32_bf16 v[12:15], v[140:143], v[176:179], v[12:15]
	v_mfma_f32_16x16x32_bf16 v[64:67], v[136:139], v[156:159], v[64:67]
	v_mfma_f32_16x16x32_bf16 v[60:63], v[144:147], v[156:159], v[60:63]
	v_mfma_f32_16x16x32_bf16 v[48:51], v[136:139], v[164:167], v[48:51]
	v_mfma_f32_16x16x32_bf16 v[44:47], v[144:147], v[164:167], v[44:47]
	v_mfma_f32_16x16x32_bf16 v[32:35], v[136:139], v[172:175], v[32:35]
	v_mfma_f32_16x16x32_bf16 v[28:31], v[144:147], v[172:175], v[28:31]
	v_mfma_f32_16x16x32_bf16 v[16:19], v[136:139], v[180:183], v[16:19]
	v_mfma_f32_16x16x32_bf16 v[12:15], v[144:147], v[180:183], v[12:15]
	s_setprio 0
	s_barrier
	s_add_u32 s8, s18, 0x18000
	s_addc_u32 s9, s19, 0
	s_add_i32 s64, s65, s56
	s_mov_b32 m0, s64
	s_nop 0
	global_load_lds_dwordx4 v148, s[8:9]
	s_add_i32 m0, s64, 0x2000
	s_nop 0
	global_load_lds_dwordx4 v150, s[8:9]
	s_waitcnt vmcnt(6)
	s_barrier
	s_setprio 1
	v_mfma_f32_16x16x32_bf16 v[56:59], v[184:187], v[152:155], v[56:59]
	v_mfma_f32_16x16x32_bf16 v[52:55], v[192:195], v[152:155], v[52:55]
	v_mfma_f32_16x16x32_bf16 v[40:43], v[184:187], v[160:163], v[40:43]
	v_mfma_f32_16x16x32_bf16 v[36:39], v[192:195], v[160:163], v[36:39]
	v_mfma_f32_16x16x32_bf16 v[24:27], v[184:187], v[168:171], v[24:27]
	v_mfma_f32_16x16x32_bf16 v[20:23], v[192:195], v[168:171], v[20:23]
	v_mfma_f32_16x16x32_bf16 v[8:11], v[184:187], v[176:179], v[8:11]
	v_mfma_f32_16x16x32_bf16 v[4:7], v[192:195], v[176:179], v[4:7]
	v_mfma_f32_16x16x32_bf16 v[56:59], v[188:191], v[156:159], v[56:59]
	v_mfma_f32_16x16x32_bf16 v[52:55], v[210:213], v[156:159], v[52:55]
	v_mfma_f32_16x16x32_bf16 v[40:43], v[188:191], v[164:167], v[40:43]
	v_mfma_f32_16x16x32_bf16 v[36:39], v[210:213], v[164:167], v[36:39]
	v_mfma_f32_16x16x32_bf16 v[24:27], v[188:191], v[172:175], v[24:27]
	v_mfma_f32_16x16x32_bf16 v[20:23], v[210:213], v[172:175], v[20:23]
	v_mfma_f32_16x16x32_bf16 v[8:11], v[188:191], v[180:183], v[8:11]
	v_mfma_f32_16x16x32_bf16 v[4:7], v[210:213], v[180:183], v[4:7]
	s_setprio 0
	s_add_i32 s64, 0, 0x18000
	v_add_u32_e32 v144, s64, v1
	s_barrier
	ds_read_b128 v[132:135], v144
	ds_read_b128 v[136:139], v144 offset:1024
	ds_read_b128 v[140:143], v144 offset:2048
	ds_read_b128 v[144:147], v144 offset:3072
	s_add_u32 s8, s22, 0x18000
	s_addc_u32 s9, s23, 0
	s_mov_b32 m0, s72
	ds_read_b128 v[152:155], v3 offset:32768
	ds_read_b128 v[156:159], v3 offset:33792
	ds_read_b128 v[160:163], v3 offset:34816
	ds_read_b128 v[164:167], v3 offset:35840
	ds_read_b128 v[168:171], v3 offset:36864
	ds_read_b128 v[172:175], v3 offset:37888
	ds_read_b128 v[176:179], v3 offset:38912
	ds_read_b128 v[180:183], v3 offset:39936
	s_nop 0
	global_load_lds_dwordx4 v148, s[8:9]
	s_mov_b32 m0, s73
	s_nop 0
	global_load_lds_dwordx4 v150, s[8:9]
	s_waitcnt lgkmcnt(8)
	s_barrier
	s_waitcnt lgkmcnt(0)
	s_setprio 1
	s_waitcnt lgkmcnt(0)
	v_mfma_f32_16x16x32_bf16 v[128:131], v[132:135], v[152:155], v[128:131]
	v_mfma_f32_16x16x32_bf16 v[124:127], v[140:143], v[152:155], v[124:127]
	v_mfma_f32_16x16x32_bf16 v[112:115], v[132:135], v[160:163], v[112:115]
	v_mfma_f32_16x16x32_bf16 v[108:111], v[140:143], v[160:163], v[108:111]
	v_mfma_f32_16x16x32_bf16 v[96:99], v[132:135], v[168:171], v[96:99]
	v_mfma_f32_16x16x32_bf16 v[92:95], v[140:143], v[168:171], v[92:95]
	v_mfma_f32_16x16x32_bf16 v[80:83], v[132:135], v[176:179], v[80:83]
	v_mfma_f32_16x16x32_bf16 v[76:79], v[140:143], v[176:179], v[76:79]
	v_mfma_f32_16x16x32_bf16 v[128:131], v[136:139], v[156:159], v[128:131]
	v_mfma_f32_16x16x32_bf16 v[124:127], v[144:147], v[156:159], v[124:127]
	v_mfma_f32_16x16x32_bf16 v[112:115], v[136:139], v[164:167], v[112:115]
	v_mfma_f32_16x16x32_bf16 v[108:111], v[144:147], v[164:167], v[108:111]
	v_mfma_f32_16x16x32_bf16 v[96:99], v[136:139], v[172:175], v[96:99]
	v_mfma_f32_16x16x32_bf16 v[92:95], v[144:147], v[172:175], v[92:95]
	v_mfma_f32_16x16x32_bf16 v[80:83], v[136:139], v[180:183], v[80:83]
	v_mfma_f32_16x16x32_bf16 v[76:79], v[144:147], v[180:183], v[76:79]
	s_setprio 0
	s_barrier
	s_add_i32 s22, 0, 0x1c000
	s_add_u32 s8, s18, 0x80
	v_add_u32_e32 v210, s22, v1
	s_addc_u32 s9, s19, 0
	s_add_i32 s23, s64, s56
	ds_read_b128 v[184:187], v210
	ds_read_b128 v[188:191], v210 offset:1024
	ds_read_b128 v[192:195], v210 offset:2048
	ds_read_b128 v[210:213], v210 offset:3072
	s_mov_b32 m0, s23
	s_nop 0
	global_load_lds_dwordx4 v148, s[8:9]
	s_add_i32 m0, s23, 0x2000
	s_nop 0
	global_load_lds_dwordx4 v150, s[8:9]
	s_barrier
	s_waitcnt lgkmcnt(0)
	s_setprio 1
	s_waitcnt lgkmcnt(0)
	v_mfma_f32_16x16x32_bf16 v[120:123], v[184:187], v[152:155], v[120:123]
	v_mfma_f32_16x16x32_bf16 v[116:119], v[192:195], v[152:155], v[116:119]
	v_mfma_f32_16x16x32_bf16 v[104:107], v[184:187], v[160:163], v[104:107]
	v_mfma_f32_16x16x32_bf16 v[100:103], v[192:195], v[160:163], v[100:103]
	v_mfma_f32_16x16x32_bf16 v[88:91], v[184:187], v[168:171], v[88:91]
	v_mfma_f32_16x16x32_bf16 v[84:87], v[192:195], v[168:171], v[84:87]
	v_mfma_f32_16x16x32_bf16 v[72:75], v[184:187], v[176:179], v[72:75]
	v_mfma_f32_16x16x32_bf16 v[68:71], v[192:195], v[176:179], v[68:71]
	v_mfma_f32_16x16x32_bf16 v[120:123], v[188:191], v[156:159], v[120:123]
	v_mfma_f32_16x16x32_bf16 v[116:119], v[210:213], v[156:159], v[116:119]
	v_mfma_f32_16x16x32_bf16 v[104:107], v[188:191], v[164:167], v[104:107]
	v_mfma_f32_16x16x32_bf16 v[100:103], v[210:213], v[164:167], v[100:103]
	v_mfma_f32_16x16x32_bf16 v[88:91], v[188:191], v[172:175], v[88:91]
	v_mfma_f32_16x16x32_bf16 v[84:87], v[210:213], v[172:175], v[84:87]
	v_mfma_f32_16x16x32_bf16 v[72:75], v[188:191], v[180:183], v[72:75]
	v_mfma_f32_16x16x32_bf16 v[68:71], v[210:213], v[180:183], v[68:71]
	s_setprio 0
	s_mov_b32 m0, s68
	s_barrier
	ds_read_b128 v[152:155], v3 offset:49152
	ds_read_b128 v[156:159], v3 offset:50176
	ds_read_b128 v[160:163], v3 offset:51200
	ds_read_b128 v[164:167], v3 offset:52224
	ds_read_b128 v[168:171], v3 offset:53248
	ds_read_b128 v[172:175], v3 offset:54272
	ds_read_b128 v[176:179], v3 offset:55296
	ds_read_b128 v[180:183], v3 offset:56320
	s_nop 0
	global_load_lds_dwordx4 v148, s[20:21]
	s_mov_b32 m0, s74
	s_nop 0
	global_load_lds_dwordx4 v150, s[20:21]
	s_barrier
	s_waitcnt lgkmcnt(0)
	s_setprio 1
	s_waitcnt lgkmcnt(0)
	v_mfma_f32_16x16x32_bf16 v[64:67], v[132:135], v[152:155], v[64:67]
	v_mfma_f32_16x16x32_bf16 v[60:63], v[140:143], v[152:155], v[60:63]
	v_mfma_f32_16x16x32_bf16 v[48:51], v[132:135], v[160:163], v[48:51]
	v_mfma_f32_16x16x32_bf16 v[44:47], v[140:143], v[160:163], v[44:47]
	v_mfma_f32_16x16x32_bf16 v[32:35], v[132:135], v[168:171], v[32:35]
	v_mfma_f32_16x16x32_bf16 v[28:31], v[140:143], v[168:171], v[28:31]
	v_mfma_f32_16x16x32_bf16 v[16:19], v[132:135], v[176:179], v[16:19]
	v_mfma_f32_16x16x32_bf16 v[12:15], v[140:143], v[176:179], v[12:15]
	v_mfma_f32_16x16x32_bf16 v[64:67], v[136:139], v[156:159], v[64:67]
	v_mfma_f32_16x16x32_bf16 v[60:63], v[144:147], v[156:159], v[60:63]
	v_mfma_f32_16x16x32_bf16 v[48:51], v[136:139], v[164:167], v[48:51]
	v_mfma_f32_16x16x32_bf16 v[44:47], v[144:147], v[164:167], v[44:47]
	v_mfma_f32_16x16x32_bf16 v[32:35], v[136:139], v[172:175], v[32:35]
	v_mfma_f32_16x16x32_bf16 v[28:31], v[144:147], v[172:175], v[28:31]
	v_mfma_f32_16x16x32_bf16 v[16:19], v[136:139], v[180:183], v[16:19]
	v_mfma_f32_16x16x32_bf16 v[12:15], v[144:147], v[180:183], v[12:15]
	s_setprio 0
	s_barrier
	s_add_u32 s8, s18, 0x18080
	s_addc_u32 s9, s19, 0
	s_add_i32 s18, s22, s56
	s_mov_b32 m0, s18
	s_nop 0
	global_load_lds_dwordx4 v148, s[8:9]
	s_add_i32 m0, s18, 0x2000
	s_nop 0
	global_load_lds_dwordx4 v150, s[8:9]
	s_waitcnt vmcnt(6)
	s_barrier
	s_setprio 1
	v_mfma_f32_16x16x32_bf16 v[56:59], v[184:187], v[152:155], v[56:59]
	v_mfma_f32_16x16x32_bf16 v[52:55], v[192:195], v[152:155], v[52:55]
	v_mfma_f32_16x16x32_bf16 v[40:43], v[184:187], v[160:163], v[40:43]
	v_mfma_f32_16x16x32_bf16 v[36:39], v[192:195], v[160:163], v[36:39]
	v_mfma_f32_16x16x32_bf16 v[24:27], v[184:187], v[168:171], v[24:27]
	v_mfma_f32_16x16x32_bf16 v[20:23], v[192:195], v[168:171], v[20:23]
	v_mfma_f32_16x16x32_bf16 v[8:11], v[184:187], v[176:179], v[8:11]
	v_mfma_f32_16x16x32_bf16 v[4:7], v[192:195], v[176:179], v[4:7]
	v_mfma_f32_16x16x32_bf16 v[56:59], v[188:191], v[156:159], v[56:59]
	v_mfma_f32_16x16x32_bf16 v[52:55], v[210:213], v[156:159], v[52:55]
	v_mfma_f32_16x16x32_bf16 v[40:43], v[188:191], v[164:167], v[40:43]
	v_mfma_f32_16x16x32_bf16 v[36:39], v[210:213], v[164:167], v[36:39]
	v_mfma_f32_16x16x32_bf16 v[24:27], v[188:191], v[172:175], v[24:27]
	v_mfma_f32_16x16x32_bf16 v[20:23], v[210:213], v[172:175], v[20:23]
	v_mfma_f32_16x16x32_bf16 v[8:11], v[188:191], v[180:183], v[8:11]
	v_mfma_f32_16x16x32_bf16 v[4:7], v[210:213], v[180:183], v[4:7]
	s_setprio 0
	s_add_i32 s62, s62, 2
	s_add_u32 s47, s47, 0x100
	s_addc_u32 s49, s49, 0
	s_cmp_gt_u32 s62, 3
	s_mov_b64 s[8:9], s[0:1]
	s_barrier
	s_cbranch_scc0 .LBB0_769
	v_mov_b32_e32 v132, v0
	s_nop 0
	v_readfirstlane_b32 s0, v132
	s_lshr_b32 s1, s0, 6
	s_and_b32 s49, s1, 3
	s_cmp_eq_u32 s48, 4
	s_cselect_b64 s[8:9], -1, 0
	s_cmp_gt_u32 s49, 1
	s_cselect_b64 s[18:19], -1, 0
	s_and_b64 s[8:9], s[8:9], s[18:19]
	s_and_b64 vcc, exec, s[8:9]
	s_cbranch_vccnz .LBB0_757
	s_ashr_i32 s0, s0, 2
	s_lshl_b32 s1, s46, 8
	s_andn2_b32 s0, s0, 63
	s_add_i32 s0, s0, s1
	v_and_or_b32 v152, v132, 15, s0
	v_ashrrev_i32_e32 v153, 31, v152
	v_bfe_u32 v134, v132, 4, 2
	v_lshl_add_u64 v[132:133], v[152:153], 2, s[6:7]
	global_load_dword v135, v[132:133], off
	global_load_dword v178, v[132:133], off offset:64
	global_load_dword v177, v[132:133], off offset:128
	global_load_dword v176, v[132:133], off offset:192
	global_load_dword v175, v[132:133], off offset:512
	global_load_dword v174, v[132:133], off offset:576
	global_load_dword v173, v[132:133], off offset:640
	global_load_dword v172, v[132:133], off offset:704
	s_cmp_gt_i32 s48, 2
	s_cselect_b64 s[0:1], -1, 0
	v_lshlrev_b32_e32 v179, 3, v134
	s_lshl_b32 s8, s48, 3
	s_lshl_b32 s9, s49, 1
	s_or_b32 s8, s8, s9
	s_sub_i32 s46, s8, 24
	v_cmp_eq_u32_e64 s[18:19], 0, v134
	v_cmp_ne_u32_e64 s[20:21], 0, v134
	s_mov_b64 s[8:9], -1
	v_lshlrev_b32_e32 v154, 2, v179
	s_waitcnt vmcnt(0)
	v_fmamk_f32 v132, v135, 0x3b2aaaab, v231
	v_cmp_gt_f32_e32 vcc, s11, v132
	v_mul_f32_e32 v133, 0x4b800000, v132
	s_nop 0
	v_cndmask_b32_e32 v132, v132, v133, vcc
	v_rsq_f32_e32 v132, v132
	s_nop 0
	v_mul_f32_e32 v133, 0x45800000, v132
	v_cndmask_b32_e32 v158, v132, v133, vcc
	v_and_b32_e32 v132, 8, v179
	v_mov_b32_e32 v159, v158
	s_and_b64 vcc, exec, s[0:1]
	v_lshlrev_b32_e32 v156, 2, v132
	v_mul_f32 v128, v128, v158
	v_mul_f32 v129, v129, v159
	v_mul_f32 v124, v124, v158
	v_mul_f32 v125, v125, v159
	s_cbranch_vccz .LBB0_781
	v_and_b32_e32 v133, 64, v236
	v_xor_b32_e32 v132, 32, v236
	v_add_u32_e32 v133, 64, v133
	v_cmp_lt_i32_e32 vcc, v132, v133
	v_mov_b32_e32 v162, v158
	v_mov_b32_e32 v163, v158
	v_cndmask_b32_e32 v132, v236, v132, vcc
	v_mul_f32 v160, v130, v162
	v_mul_f32 v161, v131, v163
	v_lshlrev_b32_e32 v170, 2, v132
	v_mul_f32_e32 v132, v129, v129
	v_mul_f32_e32 v133, v161, v161
	v_fmac_f32_e32 v132, v128, v128
	v_fmac_f32_e32 v133, v160, v160
	v_add_f32_e32 v155, v132, v133
	global_load_dwordx4 v[136:139], v154, s[40:41] offset:272
	global_load_dwordx4 v[144:147], v154, s[40:41] offset:256
	global_load_dwordx4 v[132:135], v156, s[26:27] offset:16
	global_load_dwordx4 v[140:143], v156, s[26:27]
	v_mul_f32 v162, v126, v162
	v_mul_f32 v163, v127, v163
	v_mul_f32_e32 v157, v125, v125
	v_mul_f32_e32 v164, v163, v163
	v_fmac_f32_e32 v157, v124, v124
	v_fmac_f32_e32 v164, v162, v162
	v_add_f32_e32 v157, v157, v164
	v_add_f32_e32 v155, v155, v157
	ds_swizzle_b32 v157, v155 offset:swizzle(SWAP,16)
	s_waitcnt lgkmcnt(0)
	v_add_f32_e32 v155, v155, v157
	ds_bpermute_b32 v157, v170, v155
	s_and_saveexec_b64 s[8:9], s[20:21]
	s_xor_b64 s[8:9], exec, s[8:9]
	s_ashr_i32 s47, s46, 31
	s_or_saveexec_b64 s[8:9], s[8:9]
	v_mov_b64_e32 v[164:165], s[46:47]
	s_xor_b64 exec, exec, s[8:9]
	s_cbranch_execz .LBB0_776
	s_ashr_i32 s47, s46, 31
	s_mul_i32 s22, s46, 0x10400
	s_mul_hi_i32 s23, s46, 0x10400
	s_add_u32 s22, s35, s22
	s_addc_u32 s23, s54, s23
	s_waitcnt lgkmcnt(0)
	v_add_f32_e32 v155, v155, v157
	v_lshl_add_u64 v[164:165], v[152:153], 2, s[22:23]
	global_atomic_add_f32 v[164:165], v155, off
	v_mov_b64_e32 v[164:165], s[46:47]
.LBB0_776:
	s_or_b64 exec, exec, s[8:9]
	s_waitcnt vmcnt(3)
	v_mul_f32 v138, v162, v138
	v_mul_f32 v139, v163, v139
	v_mul_f32 v136, v124, v136
	v_mul_f32 v137, v125, v137
	s_waitcnt vmcnt(1)
	v_mul_f32 v138, v138, v134
	v_mul_f32 v139, v139, v135
	v_mul_f32 v134, v136, v132
	v_mul_f32 v135, v137, v133
	v_mad_i64_i32 v[132:133], s[8:9], v152, 12, v[164:165]
	v_mov_b64_e32 v[136:137], s[28:29]
	v_mad_u64_u32 v[136:137], s[8:9], v132, s77, v[136:137]
	v_mov_b32_e32 v132, v137
	v_mul_f32 v146, v160, v146
	v_mul_f32 v147, v161, v147
	v_mul_f32 v144, v128, v144
	v_mul_f32 v145, v129, v145
	v_mad_u64_u32 v[132:133], s[8:9], v133, s77, v[132:133]
	s_waitcnt vmcnt(0)
	v_mul_f32 v142, v146, v142
	v_mul_f32 v143, v147, v143
	v_mul_f32 v140, v144, v140
	v_mul_f32 v141, v145, v141
	v_mov_b32_e32 v137, v132
	v_lshlrev_b32_e32 v160, 1, v179
	v_mov_b32_e32 v161, v2
	v_mov_b32_e32 v155, v2
	v_lshl_add_u64 v[136:137], v[136:137], 0, v[160:161]
	v_cvt_pk_bf16_f32 v132, v140, v141
	v_cvt_pk_bf16_f32 v133, v142, v143
	v_cvt_pk_bf16_f32 v134, v134, v135
	v_cvt_pk_bf16_f32 v135, v138, v139
	v_lshl_add_u64 v[166:167], s[40:41], 0, v[154:155]
	s_waitcnt lgkmcnt(0)
	v_mov_b32_e32 v157, v2
	global_store_dwordx4 v[136:137], v[132:135], off offset:128
	v_lshl_add_u64 v[168:169], s[26:27], 0, v[156:157]
	global_load_dwordx4 v[136:139], v[166:167], off offset:272
	global_load_dwordx4 v[144:147], v[166:167], off offset:256
	global_load_dwordx4 v[132:135], v[168:169], off offset:16
	global_load_dwordx4 v[140:143], v[168:169], off
	v_mov_b32_e32 v162, v158
	v_mov_b32_e32 v163, v158
	v_mul_f32 v166, v122, v162
	v_mul_f32 v167, v123, v163
	v_mul_f32 v168, v120, v158
	v_mul_f32 v169, v121, v159
	v_mul_f32_e32 v157, v167, v167
	v_mul_f32_e32 v155, v169, v169
	v_fmac_f32_e32 v155, v168, v168
	v_fmac_f32_e32 v157, v166, v166
	v_mul_f32 v164, v118, v162
	v_mul_f32 v165, v119, v163
	v_mul_f32 v162, v116, v158
	v_mul_f32 v163, v117, v159
	v_add_f32_e32 v155, v155, v157
	v_mul_f32_e32 v157, v163, v163
	v_mul_f32_e32 v161, v165, v165
	v_fmac_f32_e32 v157, v162, v162
	v_fmac_f32_e32 v161, v164, v164
	v_add_f32_e32 v157, v157, v161
	v_add_f32_e32 v155, v155, v157
	ds_swizzle_b32 v157, v155 offset:swizzle(SWAP,16)
	s_or_b32 s8, s46, 1
	s_waitcnt lgkmcnt(0)
	v_add_f32_e32 v155, v155, v157
	ds_bpermute_b32 v157, v170, v155
	s_and_saveexec_b64 s[22:23], s[20:21]
	s_xor_b64 s[22:23], exec, s[22:23]
	s_ashr_i32 s9, s8, 31
	s_or_saveexec_b64 s[22:23], s[22:23]
	v_mov_b64_e32 v[170:171], s[8:9]
	s_xor_b64 exec, exec, s[22:23]
	s_cbranch_execz .LBB0_780
	s_ashr_i32 s9, s8, 31
	s_mul_i32 s62, s8, 0x10400
	s_mul_hi_i32 s47, s8, 0x10400
	s_add_u32 s64, s35, s62
	s_addc_u32 s65, s54, s47
	s_waitcnt lgkmcnt(0)
	v_add_f32_e32 v155, v155, v157
	v_lshl_add_u64 v[170:171], v[152:153], 2, s[64:65]
	global_atomic_add_f32 v[170:171], v155, off
	v_mov_b64_e32 v[170:171], s[8:9]
.LBB0_780:
	s_or_b64 exec, exec, s[22:23]
	v_mad_i64_i32 v[180:181], s[8:9], v152, 12, 0
	s_waitcnt vmcnt(3)
	v_mul_f32 v138, v164, v138
	v_mul_f32 v139, v165, v139
	v_mul_f32 v136, v162, v136
	v_mul_f32 v137, v163, v137
	s_waitcnt vmcnt(1)
	v_mul_f32 v138, v138, v134
	v_mul_f32 v139, v139, v135
	v_mul_f32 v134, v136, v132
	v_mul_f32 v135, v137, v133
	v_lshl_add_u64 v[132:133], v[170:171], 0, v[180:181]
	v_mov_b64_e32 v[136:137], s[28:29]
	v_mad_u64_u32 v[136:137], s[8:9], v132, s77, v[136:137]
	v_mov_b32_e32 v132, v137
	v_mul_f32 v146, v166, v146
	v_mul_f32 v147, v167, v147
	v_mul_f32 v144, v168, v144
	v_mul_f32 v145, v169, v145
	v_mad_u64_u32 v[132:133], s[8:9], v133, s77, v[132:133]
	s_waitcnt vmcnt(0)
	v_mul_f32 v142, v146, v142
	v_mul_f32 v143, v147, v143
	v_mul_f32 v140, v144, v140
	v_mul_f32 v141, v145, v141
	v_mov_b32_e32 v137, v132
	v_mov_b32_e32 v161, v2
	v_lshl_add_u64 v[136:137], v[136:137], 0, v[160:161]
	v_cvt_pk_bf16_f32 v132, v140, v141
	v_cvt_pk_bf16_f32 v133, v142, v143
	v_cvt_pk_bf16_f32 v134, v134, v135
	v_cvt_pk_bf16_f32 v135, v138, v139
	s_mov_b64 s[8:9], 0
	global_store_dwordx4 v[136:137], v[132:135], off offset:128
.LBB0_781:
	s_lshl_b32 s22, s48, 2
	s_or_b32 s48, s49, s22
	s_ashr_i32 s49, s48, 31
	s_mul_hi_i32 s80, s48, 0x10400
	s_mul_i32 s81, s48, 0x10400
	s_and_b64 vcc, exec, s[8:9]
	v_lshlrev_b32_e32 v132, 1, v179
	s_cbranch_vccz .LBB0_785
	v_mov_b32_e32 v164, v158
	v_mov_b32_e32 v165, v158
	v_mul_f32 v130, v130, v164
	v_mul_f32 v131, v131, v165
	v_mul_f32_e32 v133, v129, v129
	v_mul_f32_e32 v134, v131, v131
	v_mul_f32 v126, v126, v164
	v_mul_f32 v127, v127, v165
	v_fmac_f32_e32 v133, v128, v128
	v_fmac_f32_e32 v134, v130, v130
	v_add_f32_e32 v133, v133, v134
	v_mul_f32_e32 v134, v125, v125
	v_mul_f32_e32 v135, v127, v127
	v_fmac_f32_e32 v134, v124, v124
	v_fmac_f32_e32 v135, v126, v126
	v_add_f32_e32 v134, v134, v135
	v_add_f32_e32 v155, v133, v134
	global_load_dwordx4 v[134:137], v154, s[40:41] offset:16
	global_load_dwordx4 v[138:141], v154, s[40:41]
	global_load_dwordx4 v[142:145], v154, s[24:25] offset:16
	global_load_dwordx4 v[160:163], v154, s[24:25]
	v_mad_i64_i32 v[146:147], s[8:9], v152, 12, s[48:49]
	v_mov_b32_e32 v133, v2
	s_waitcnt vmcnt(0)
	v_mul_f32 v136, v136, v144
	v_mul_f32 v137, v137, v145
	v_mul_f32 v134, v134, v142
	v_mul_f32 v135, v135, v143
	v_mul_f32 v136, v126, v136
	v_mul_f32 v137, v127, v137
	v_mul_f32 v126, v124, v134
	v_mul_f32 v127, v125, v135
	v_mul_f32 v140, v140, v162
	v_mul_f32 v141, v141, v163
	v_cvt_pk_bf16_f32 v126, v126, v127
	v_cvt_pk_bf16_f32 v127, v136, v137
	v_mul_f32 v134, v122, v164
	v_mul_f32 v135, v123, v165
	v_mul_f32 v136, v120, v158
	v_mul_f32 v137, v121, v159
	v_mul_f32 v138, v138, v160
	v_mul_f32 v139, v139, v161
	v_mul_f32 v130, v130, v140
	v_mul_f32 v131, v131, v141
	v_mul_f32 v140, v116, v158
	v_mul_f32 v141, v117, v159
	v_mul_f32_e32 v116, v137, v137
	v_mul_f32_e32 v117, v135, v135
	v_mov_b64_e32 v[142:143], s[28:29]
	v_mul_f32 v128, v128, v138
	v_mul_f32 v129, v129, v139
	v_mul_f32 v138, v118, v164
	v_mul_f32 v139, v119, v165
	v_fmac_f32_e32 v116, v136, v136
	v_fmac_f32_e32 v117, v134, v134
	v_mad_u64_u32 v[142:143], s[8:9], v146, s77, v[142:143]
	v_add_f32_e32 v116, v116, v117
	v_mul_f32_e32 v117, v141, v141
	v_mul_f32_e32 v118, v139, v139
	v_mad_i32_i24 v143, v147, s77, v143
	v_fmac_f32_e32 v117, v140, v140
	v_fmac_f32_e32 v118, v138, v138
	v_lshl_add_u64 v[142:143], v[142:143], 0, v[132:133]
	v_cvt_pk_bf16_f32 v124, v128, v129
	v_cvt_pk_bf16_f32 v125, v130, v131
	v_add_f32_e32 v117, v117, v118
	global_store_dwordx4 v[142:143], v[124:127], off
	v_add_f32_e32 v116, v116, v117
	v_add_f32_e32 v133, v155, v116
	global_load_dwordx4 v[116:119], v154, s[40:41] offset:144
	global_load_dwordx4 v[120:123], v154, s[40:41] offset:128
	global_load_dwordx4 v[124:127], v154, s[24:25] offset:144
	global_load_dwordx4 v[128:131], v154, s[24:25] offset:128
	s_waitcnt vmcnt(0)
	v_mul_f32 v118, v118, v126
	v_mul_f32 v119, v119, v127
	v_mul_f32 v122, v122, v130
	v_mul_f32 v123, v123, v131
	v_mul_f32 v120, v120, v128
	v_mul_f32 v121, v121, v129
	v_mul_f32 v116, v116, v124
	v_mul_f32 v117, v117, v125
	v_mul_f32 v122, v134, v122
	v_mul_f32 v123, v135, v123
	v_mul_f32 v120, v136, v120
	v_mul_f32 v121, v137, v121
	v_mul_f32 v124, v138, v118
	v_mul_f32 v125, v139, v119
	v_mul_f32 v118, v140, v116
	v_mul_f32 v119, v141, v117
	v_cvt_pk_bf16_f32 v116, v120, v121
	v_cvt_pk_bf16_f32 v117, v122, v123
	v_cvt_pk_bf16_f32 v118, v118, v119
	v_cvt_pk_bf16_f32 v119, v124, v125
	global_store_dwordx4 v[142:143], v[116:119], off offset:64
	ds_swizzle_b32 v116, v133 offset:swizzle(SWAP,16)
	s_nop 0
	v_and_b32_e32 v118, 64, v236
	v_xor_b32_e32 v117, 32, v236
	v_add_u32_e32 v118, 64, v118
	v_cmp_lt_i32_e32 vcc, v117, v118
	s_waitcnt lgkmcnt(0)
	v_add_f32_e32 v116, v133, v116
	v_cndmask_b32_e32 v117, v236, v117, vcc
	v_lshlrev_b32_e32 v117, 2, v117
	ds_bpermute_b32 v117, v117, v116
	s_and_saveexec_b64 s[8:9], s[18:19]
	s_cbranch_execz .LBB0_784
	s_add_u32 s22, s35, s81
	s_addc_u32 s23, s54, s80
	s_waitcnt lgkmcnt(0)
	v_add_f32_e32 v118, v116, v117
	v_lshl_add_u64 v[116:117], v[152:153], 2, s[22:23]
	global_atomic_add_f32 v[116:117], v118, off

.LBB0_785:
	v_fmamk_f32 v116, v178, 0x3b2aaaab, v231
	s_waitcnt lgkmcnt(0)
	v_mul_f32_e32 v117, 0x4b800000, v116
	v_cmp_gt_f32_e32 vcc, s11, v116
	v_or_b32_e32 v146, 16, v152
	s_mov_b64 s[8:9], -1
	v_cndmask_b32_e32 v116, v116, v117, vcc
	v_rsq_f32_e32 v116, v116
	s_nop 0
	v_mul_f32_e32 v117, 0x45800000, v116
	v_cndmask_b32_e32 v134, v116, v117, vcc
	v_mov_b32_e32 v135, v134
	v_cndmask_b32_e64 v116, 0, 1, s[0:1]
	v_cmp_ne_u32_e64 s[22:23], 1, v116
	s_andn2_b64 vcc, exec, s[0:1]
	v_mul_f32 v112, v112, v134
	v_mul_f32 v113, v113, v135
	v_mul_f32 v108, v108, v134
	v_mul_f32 v109, v109, v135
	s_cbranch_vccnz .LBB0_795
	v_and_b32_e32 v117, 64, v236
	v_xor_b32_e32 v116, 32, v236
	v_add_u32_e32 v117, 64, v117
	v_cmp_lt_i32_e32 vcc, v116, v117
	v_mov_b32_e32 v138, v134
	v_mov_b32_e32 v139, v134
	v_cndmask_b32_e32 v116, v236, v116, vcc
	v_mul_f32 v136, v114, v138
	v_mul_f32 v137, v115, v139
	v_lshlrev_b32_e32 v144, 2, v116
	v_mul_f32_e32 v116, v113, v113
	v_mul_f32_e32 v117, v137, v137
	v_fmac_f32_e32 v116, v112, v112
	v_fmac_f32_e32 v117, v136, v136
	v_add_f32_e32 v133, v116, v117
	global_load_dwordx4 v[120:123], v154, s[40:41] offset:272
	global_load_dwordx4 v[128:131], v154, s[40:41] offset:256
	global_load_dwordx4 v[116:119], v156, s[26:27] offset:16
	global_load_dwordx4 v[124:127], v156, s[26:27]
	v_mul_f32 v138, v110, v138
	v_mul_f32 v139, v111, v139
	v_mul_f32_e32 v140, v109, v109
	v_mul_f32_e32 v141, v139, v139
	v_fmac_f32_e32 v140, v108, v108
	v_fmac_f32_e32 v141, v138, v138
	v_add_f32_e32 v140, v140, v141
	v_add_f32_e32 v133, v133, v140
	ds_swizzle_b32 v140, v133 offset:swizzle(SWAP,16)
	s_waitcnt lgkmcnt(0)
	v_add_f32_e32 v133, v133, v140
	ds_bpermute_b32 v142, v144, v133
	s_and_saveexec_b64 s[0:1], s[20:21]
	s_xor_b64 s[0:1], exec, s[0:1]
	s_ashr_i32 s47, s46, 31
	s_or_saveexec_b64 s[0:1], s[0:1]
	v_mov_b64_e32 v[140:141], s[46:47]
	s_xor_b64 exec, exec, s[0:1]
	s_cbranch_execz .LBB0_790
	s_ashr_i32 s47, s46, 31
	s_mul_i32 s8, s46, 0x10400
	s_mul_hi_i32 s9, s46, 0x10400
	s_add_u32 s8, s35, s8
	s_addc_u32 s9, s54, s9
	s_waitcnt lgkmcnt(0)
	v_add_f32_e32 v133, v133, v142
	v_lshl_add_u64 v[140:141], v[152:153], 2, s[8:9]
	global_atomic_add_f32 v[140:141], v133, off offset:64
	v_mov_b64_e32 v[140:141], s[46:47]
.LBB0_790:
	s_or_b64 exec, exec, s[0:1]
	s_waitcnt vmcnt(3)
	v_mul_f32 v122, v138, v122
	v_mul_f32 v123, v139, v123
	v_mul_f32 v120, v108, v120
	v_mul_f32 v121, v109, v121
	s_waitcnt vmcnt(1)
	v_mul_f32 v122, v122, v118
	v_mul_f32 v123, v123, v119
	v_mul_f32 v118, v120, v116
	v_mul_f32 v119, v121, v117
	v_mad_i64_i32 v[116:117], s[0:1], v146, 12, v[140:141]
	v_mov_b64_e32 v[120:121], s[28:29]
	v_mad_u64_u32 v[120:121], s[0:1], v116, s77, v[120:121]
	v_mov_b32_e32 v116, v121
	v_mul_f32 v130, v136, v130
	v_mul_f32 v131, v137, v131
	v_mul_f32 v128, v112, v128
	v_mul_f32 v129, v113, v129
	v_mad_u64_u32 v[116:117], s[0:1], v117, s77, v[116:117]
	s_waitcnt vmcnt(0)
	v_mul_f32 v126, v130, v126
	v_mul_f32 v127, v131, v127
	v_mul_f32 v124, v128, v124
	v_mul_f32 v125, v129, v125
	v_mov_b32_e32 v121, v116
	v_mov_b32_e32 v133, v2
	v_mov_b32_e32 v155, v2
	v_lshl_add_u64 v[120:121], v[120:121], 0, v[132:133]
	v_cvt_pk_bf16_f32 v116, v124, v125
	v_cvt_pk_bf16_f32 v117, v126, v127
	v_cvt_pk_bf16_f32 v118, v118, v119
	v_cvt_pk_bf16_f32 v119, v122, v123
	s_waitcnt lgkmcnt(0)
	v_lshl_add_u64 v[142:143], s[40:41], 0, v[154:155]
	v_mov_b32_e32 v157, v2
	global_store_dwordx4 v[120:121], v[116:119], off offset:128
	v_lshl_add_u64 v[158:159], s[26:27], 0, v[156:157]
	global_load_dwordx4 v[120:123], v[142:143], off offset:272
	global_load_dwordx4 v[128:131], v[142:143], off offset:256
	global_load_dwordx4 v[116:119], v[158:159], off offset:16
	global_load_dwordx4 v[124:127], v[158:159], off
	v_mov_b32_e32 v136, v134
	v_mov_b32_e32 v137, v134
	v_mul_f32 v140, v106, v136
	v_mul_f32 v141, v107, v137
	v_mul_f32 v142, v104, v134
	v_mul_f32 v143, v105, v135
	v_mul_f32_e32 v138, v141, v141
	v_mul_f32_e32 v133, v143, v143
	v_fmac_f32_e32 v133, v142, v142
	v_fmac_f32_e32 v138, v140, v140
	v_add_f32_e32 v133, v133, v138
	v_mul_f32 v138, v102, v136
	v_mul_f32 v139, v103, v137
	v_mul_f32 v136, v100, v134
	v_mul_f32 v137, v101, v135
	v_mul_f32_e32 v147, v139, v139
	v_mul_f32_e32 v145, v137, v137
	v_fmac_f32_e32 v145, v136, v136
	v_fmac_f32_e32 v147, v138, v138
	v_add_f32_e32 v145, v145, v147
	v_add_f32_e32 v133, v133, v145
	ds_swizzle_b32 v145, v133 offset:swizzle(SWAP,16)
	s_or_b32 s0, s46, 1
	s_waitcnt lgkmcnt(0)
	v_add_f32_e32 v133, v133, v145
	ds_bpermute_b32 v147, v144, v133
	s_and_saveexec_b64 s[8:9], s[20:21]
	s_xor_b64 s[8:9], exec, s[8:9]
	s_ashr_i32 s1, s0, 31
	s_or_saveexec_b64 s[8:9], s[8:9]
	v_mov_b64_e32 v[144:145], s[0:1]
	s_xor_b64 exec, exec, s[8:9]
	s_cbranch_execz .LBB0_794
	s_ashr_i32 s1, s0, 31
	s_mul_i32 s62, s0, 0x10400
	s_mul_hi_i32 s47, s0, 0x10400
	s_add_u32 s64, s35, s62
	s_addc_u32 s65, s54, s47
	s_waitcnt lgkmcnt(0)
	v_add_f32_e32 v133, v133, v147
	v_lshl_add_u64 v[144:145], v[152:153], 2, s[64:65]
	global_atomic_add_f32 v[144:145], v133, off offset:64
	v_mov_b64_e32 v[144:145], s[0:1]
.LBB0_794:
	s_or_b64 exec, exec, s[8:9]
	v_mad_i64_i32 v[158:159], s[0:1], v146, 12, 0
	s_waitcnt vmcnt(3)
	v_mul_f32 v122, v138, v122
	v_mul_f32 v123, v139, v123
	v_mul_f32 v120, v136, v120
	v_mul_f32 v121, v137, v121
	s_waitcnt vmcnt(1)
	v_mul_f32 v122, v122, v118
	v_mul_f32 v123, v123, v119
	v_mul_f32 v118, v120, v116
	v_mul_f32 v119, v121, v117
	v_lshl_add_u64 v[116:117], v[144:145], 0, v[158:159]
	v_mov_b64_e32 v[120:121], s[28:29]
	v_mad_u64_u32 v[120:121], s[0:1], v116, s77, v[120:121]
	v_mov_b32_e32 v116, v121
	v_mul_f32 v130, v140, v130
	v_mul_f32 v131, v141, v131
	v_mul_f32 v128, v142, v128
	v_mul_f32 v129, v143, v129
	v_mad_u64_u32 v[116:117], s[0:1], v117, s77, v[116:117]
	s_waitcnt vmcnt(0)
	v_mul_f32 v126, v130, v126
	v_mul_f32 v127, v131, v127
	v_mul_f32 v124, v128, v124
	v_mul_f32 v125, v129, v125
	v_mov_b32_e32 v121, v116
	v_mov_b32_e32 v133, v2
	v_lshl_add_u64 v[120:121], v[120:121], 0, v[132:133]
	v_cvt_pk_bf16_f32 v116, v124, v125
	v_cvt_pk_bf16_f32 v117, v126, v127
	v_cvt_pk_bf16_f32 v118, v118, v119
	v_cvt_pk_bf16_f32 v119, v122, v123
	s_mov_b64 s[8:9], 0
	global_store_dwordx4 v[120:121], v[116:119], off offset:128
.LBB0_795:
	s_and_b64 vcc, exec, s[8:9]
	s_cbranch_vccz .LBB0_799
	v_mov_b32_e32 v136, v134
	v_mov_b32_e32 v137, v134
	v_mul_f32 v138, v114, v136
	v_mul_f32 v139, v115, v137
	v_mul_f32_e32 v114, v113, v113
	v_mul_f32_e32 v115, v139, v139
	v_mul_f32 v110, v110, v136
	v_mul_f32 v111, v111, v137
	v_fmac_f32_e32 v114, v112, v112
	v_fmac_f32_e32 v115, v138, v138
	v_add_f32_e32 v114, v114, v115
	v_mul_f32_e32 v115, v109, v109
	v_mul_f32_e32 v116, v111, v111
	v_fmac_f32_e32 v115, v108, v108
	v_fmac_f32_e32 v116, v110, v110
	v_add_f32_e32 v115, v115, v116
	v_add_f32_e32 v140, v114, v115
	global_load_dwordx4 v[114:117], v154, s[40:41] offset:16
	global_load_dwordx4 v[118:121], v154, s[40:41]
	global_load_dwordx4 v[122:125], v154, s[24:25] offset:16
	global_load_dwordx4 v[126:129], v154, s[24:25]
	v_mad_i64_i32 v[130:131], s[0:1], v146, 12, s[48:49]
	v_mov_b32_e32 v133, v2
	s_waitcnt vmcnt(1)
	v_mul_f32 v116, v116, v124
	v_mul_f32 v117, v117, v125
	v_mul_f32 v114, v114, v122
	v_mul_f32 v115, v115, v123
	s_waitcnt vmcnt(0)
	v_mul_f32 v118, v118, v126
	v_mul_f32 v119, v119, v127
	v_mul_f32 v116, v110, v116
	v_mul_f32 v117, v111, v117
	v_mul_f32 v110, v108, v114
	v_mul_f32 v111, v109, v115
	v_mul_f32 v120, v120, v128
	v_mul_f32 v121, v121, v129
	v_mul_f32 v112, v112, v118
	v_mul_f32 v113, v113, v119
	v_cvt_pk_bf16_f32 v110, v110, v111
	v_cvt_pk_bf16_f32 v111, v116, v117
	v_mul_f32 v116, v106, v136
	v_mul_f32 v117, v107, v137
	v_mul_f32 v118, v104, v134
	v_mul_f32 v119, v105, v135
	v_mul_f32 v120, v138, v120
	v_mul_f32 v121, v139, v121
	v_mul_f32 v124, v100, v134
	v_mul_f32 v125, v101, v135
	v_mul_f32_e32 v100, v119, v119
	v_mul_f32_e32 v101, v117, v117
	v_mov_b64_e32 v[122:123], s[28:29]
	v_cvt_pk_bf16_f32 v109, v120, v121
	v_mul_f32 v120, v102, v136
	v_mul_f32 v121, v103, v137
	v_fmac_f32_e32 v100, v118, v118
	v_fmac_f32_e32 v101, v116, v116
	v_mad_u64_u32 v[122:123], s[0:1], v130, s77, v[122:123]
	v_add_f32_e32 v100, v100, v101
	v_mul_f32_e32 v101, v125, v125
	v_mul_f32_e32 v102, v121, v121
	v_mad_i32_i24 v123, v131, s77, v123
	v_fmac_f32_e32 v101, v124, v124
	v_fmac_f32_e32 v102, v120, v120
	v_lshl_add_u64 v[122:123], v[122:123], 0, v[132:133]
	v_cvt_pk_bf16_f32 v108, v112, v113
	v_add_f32_e32 v101, v101, v102
	global_store_dwordx4 v[122:123], v[108:111], off
	v_add_f32_e32 v100, v100, v101
	v_add_f32_e32 v126, v140, v100
	global_load_dwordx4 v[100:103], v154, s[40:41] offset:144
	global_load_dwordx4 v[104:107], v154, s[40:41] offset:128
	global_load_dwordx4 v[108:111], v154, s[24:25] offset:144
	global_load_dwordx4 v[112:115], v154, s[24:25] offset:128
	s_waitcnt vmcnt(1)
	v_mul_f32 v102, v102, v110
	v_mul_f32 v103, v103, v111
	s_waitcnt vmcnt(0)
	v_mul_f32 v106, v106, v114
	v_mul_f32 v107, v107, v115
	v_mul_f32 v104, v104, v112
	v_mul_f32 v105, v105, v113
	v_mul_f32 v100, v100, v108
	v_mul_f32 v101, v101, v109
	v_mul_f32 v106, v116, v106
	v_mul_f32 v107, v117, v107
	v_mul_f32 v104, v118, v104
	v_mul_f32 v105, v119, v105
	v_mul_f32 v108, v120, v102
	v_mul_f32 v109, v121, v103
	v_mul_f32 v102, v124, v100
	v_mul_f32 v103, v125, v101
	v_cvt_pk_bf16_f32 v100, v104, v105
	v_cvt_pk_bf16_f32 v101, v106, v107
	v_cvt_pk_bf16_f32 v102, v102, v103
	v_cvt_pk_bf16_f32 v103, v108, v109
	global_store_dwordx4 v[122:123], v[100:103], off offset:64
	ds_swizzle_b32 v100, v126 offset:swizzle(SWAP,16)
	s_nop 0
	v_and_b32_e32 v102, 64, v236
	v_xor_b32_e32 v101, 32, v236
	v_add_u32_e32 v102, 64, v102
	v_cmp_lt_i32_e32 vcc, v101, v102
	s_waitcnt lgkmcnt(0)
	v_add_f32_e32 v100, v126, v100
	v_cndmask_b32_e32 v101, v236, v101, vcc
	v_lshlrev_b32_e32 v101, 2, v101
	ds_bpermute_b32 v101, v101, v100
	s_and_saveexec_b64 s[0:1], s[18:19]
	s_cbranch_execz .LBB0_798
	s_add_u32 s8, s35, s81
	s_addc_u32 s9, s54, s80
	s_waitcnt lgkmcnt(0)
	v_add_f32_e32 v102, v100, v101
	v_lshl_add_u64 v[100:101], v[152:153], 2, s[8:9]
	global_atomic_add_f32 v[100:101], v102, off offset:64

.LBB0_799:
	v_fmamk_f32 v100, v177, 0x3b2aaaab, v231
	s_waitcnt lgkmcnt(0)
	v_mul_f32_e32 v101, 0x4b800000, v100
	v_cmp_gt_f32_e32 vcc, s11, v100
	v_or_b32_e32 v128, 32, v152
	s_mov_b64 s[0:1], -1
	v_cndmask_b32_e32 v100, v100, v101, vcc
	v_rsq_f32_e32 v100, v100
	s_nop 0
	v_mul_f32_e32 v101, 0x45800000, v100
	v_cndmask_b32_e32 v116, v100, v101, vcc
	v_mov_b32_e32 v117, v116
	s_and_b64 vcc, exec, s[22:23]
	v_mul_f32 v96, v96, v116
	v_mul_f32 v97, v97, v117
	v_mul_f32 v92, v92, v116
	v_mul_f32 v93, v93, v117
	s_cbranch_vccnz .LBB0_809
	v_and_b32_e32 v101, 64, v236
	v_xor_b32_e32 v100, 32, v236
	v_add_u32_e32 v101, 64, v101
	v_cmp_lt_i32_e32 vcc, v100, v101
	v_mov_b32_e32 v120, v116
	v_mov_b32_e32 v121, v116
	v_cndmask_b32_e32 v100, v236, v100, vcc
	v_mul_f32 v118, v98, v120
	v_mul_f32 v119, v99, v121
	v_lshlrev_b32_e32 v126, 2, v100
	v_mul_f32_e32 v100, v97, v97
	v_mul_f32_e32 v101, v119, v119
	v_fmac_f32_e32 v100, v96, v96
	v_fmac_f32_e32 v101, v118, v118
	v_add_f32_e32 v122, v100, v101
	global_load_dwordx4 v[104:107], v154, s[40:41] offset:272
	global_load_dwordx4 v[112:115], v154, s[40:41] offset:256
	global_load_dwordx4 v[100:103], v156, s[26:27] offset:16
	global_load_dwordx4 v[108:111], v156, s[26:27]
	v_mul_f32 v120, v94, v120
	v_mul_f32 v121, v95, v121
	v_mul_f32_e32 v123, v93, v93
	v_mul_f32_e32 v124, v121, v121
	v_fmac_f32_e32 v123, v92, v92
	v_fmac_f32_e32 v124, v120, v120
	v_add_f32_e32 v123, v123, v124
	v_add_f32_e32 v122, v122, v123
	ds_swizzle_b32 v123, v122 offset:swizzle(SWAP,16)
	s_waitcnt lgkmcnt(0)
	v_add_f32_e32 v124, v122, v123
	ds_bpermute_b32 v125, v126, v124
	s_and_saveexec_b64 s[0:1], s[20:21]
	s_xor_b64 s[0:1], exec, s[0:1]
	s_ashr_i32 s47, s46, 31
	s_or_saveexec_b64 s[0:1], s[0:1]
	v_mov_b64_e32 v[122:123], s[46:47]
	s_xor_b64 exec, exec, s[0:1]
	s_cbranch_execz .LBB0_804
	s_ashr_i32 s47, s46, 31
	s_mul_i32 s8, s46, 0x10400
	s_mul_hi_i32 s9, s46, 0x10400
	s_add_u32 s8, s35, s8
	s_addc_u32 s9, s54, s9
	s_waitcnt lgkmcnt(0)
	v_add_f32_e32 v124, v124, v125
	v_lshl_add_u64 v[122:123], v[152:153], 2, s[8:9]
	global_atomic_add_f32 v[122:123], v124, off offset:128
	v_mov_b64_e32 v[122:123], s[46:47]
.LBB0_804:
	s_or_b64 exec, exec, s[0:1]
	s_waitcnt vmcnt(3)
	v_mul_f32 v106, v120, v106
	v_mul_f32 v107, v121, v107
	v_mul_f32 v104, v92, v104
	v_mul_f32 v105, v93, v105
	s_waitcnt vmcnt(1)
	v_mul_f32 v106, v106, v102
	v_mul_f32 v107, v107, v103
	v_mul_f32 v102, v104, v100
	v_mul_f32 v103, v105, v101
	v_mad_i64_i32 v[100:101], s[0:1], v128, 12, v[122:123]
	v_mov_b64_e32 v[104:105], s[28:29]
	v_mad_u64_u32 v[104:105], s[0:1], v100, s77, v[104:105]
	v_mov_b32_e32 v100, v105
	v_mul_f32 v114, v118, v114
	v_mul_f32 v115, v119, v115
	v_mul_f32 v112, v96, v112
	v_mul_f32 v113, v97, v113
	v_mad_u64_u32 v[100:101], s[0:1], v101, s77, v[100:101]
	s_waitcnt vmcnt(0)
	v_mul_f32 v110, v114, v110
	v_mul_f32 v111, v115, v111
	v_mul_f32 v108, v112, v108
	v_mul_f32 v109, v113, v109
	v_mov_b32_e32 v105, v100
	v_mov_b32_e32 v133, v2
	v_mov_b32_e32 v155, v2
	v_lshl_add_u64 v[104:105], v[104:105], 0, v[132:133]
	v_cvt_pk_bf16_f32 v100, v108, v109
	v_cvt_pk_bf16_f32 v101, v110, v111
	v_cvt_pk_bf16_f32 v102, v102, v103
	v_cvt_pk_bf16_f32 v103, v106, v107
	s_waitcnt lgkmcnt(0)
	v_lshl_add_u64 v[124:125], s[40:41], 0, v[154:155]
	v_mov_b32_e32 v157, v2
	global_store_dwordx4 v[104:105], v[100:103], off offset:128
	v_lshl_add_u64 v[130:131], s[26:27], 0, v[156:157]
	global_load_dwordx4 v[104:107], v[124:125], off offset:272
	global_load_dwordx4 v[112:115], v[124:125], off offset:256
	global_load_dwordx4 v[100:103], v[130:131], off offset:16
	global_load_dwordx4 v[108:111], v[130:131], off
	v_mov_b32_e32 v118, v116
	v_mov_b32_e32 v119, v116
	v_mul_f32 v122, v90, v118
	v_mul_f32 v123, v91, v119
	v_mul_f32 v124, v88, v116
	v_mul_f32 v125, v89, v117
	v_mul_f32_e32 v121, v123, v123
	v_mul_f32_e32 v120, v125, v125
	v_fmac_f32_e32 v120, v124, v124
	v_fmac_f32_e32 v121, v122, v122
	v_add_f32_e32 v127, v120, v121
	v_mul_f32 v120, v86, v118
	v_mul_f32 v121, v87, v119
	v_mul_f32 v118, v84, v116
	v_mul_f32 v119, v85, v117
	v_mul_f32_e32 v130, v121, v121
	v_mul_f32_e32 v129, v119, v119
	v_fmac_f32_e32 v129, v118, v118
	v_fmac_f32_e32 v130, v120, v120
	v_add_f32_e32 v129, v129, v130
	v_add_f32_e32 v127, v127, v129
	ds_swizzle_b32 v129, v127 offset:swizzle(SWAP,16)
	s_or_b32 s0, s46, 1
	s_waitcnt lgkmcnt(0)
	v_add_f32_e32 v129, v127, v129
	ds_bpermute_b32 v130, v126, v129
	s_and_saveexec_b64 s[8:9], s[20:21]
	s_xor_b64 s[8:9], exec, s[8:9]
	s_ashr_i32 s1, s0, 31
	s_or_saveexec_b64 s[8:9], s[8:9]
	v_mov_b64_e32 v[126:127], s[0:1]
	s_xor_b64 exec, exec, s[8:9]
	s_cbranch_execz .LBB0_808
	s_ashr_i32 s1, s0, 31
	s_mul_i32 s62, s0, 0x10400
	s_mul_hi_i32 s47, s0, 0x10400
	s_add_u32 s64, s35, s62
	s_addc_u32 s65, s54, s47
	s_waitcnt lgkmcnt(0)
	v_add_f32_e32 v129, v129, v130
	v_lshl_add_u64 v[126:127], v[152:153], 2, s[64:65]
	global_atomic_add_f32 v[126:127], v129, off offset:128
	v_mov_b64_e32 v[126:127], s[0:1]
.LBB0_808:
	s_or_b64 exec, exec, s[8:9]
	s_waitcnt lgkmcnt(0)
	v_mad_i64_i32 v[130:131], s[0:1], v128, 12, 0
	s_waitcnt vmcnt(3)
	v_mul_f32 v106, v120, v106
	v_mul_f32 v107, v121, v107
	v_mul_f32 v104, v118, v104
	v_mul_f32 v105, v119, v105
	s_waitcnt vmcnt(1)
	v_mul_f32 v106, v106, v102
	v_mul_f32 v107, v107, v103
	v_mul_f32 v102, v104, v100
	v_mul_f32 v103, v105, v101
	v_lshl_add_u64 v[100:101], v[126:127], 0, v[130:131]
	v_mov_b64_e32 v[104:105], s[28:29]
	v_mad_u64_u32 v[104:105], s[0:1], v100, s77, v[104:105]
	v_mov_b32_e32 v100, v105
	v_mul_f32 v114, v122, v114
	v_mul_f32 v115, v123, v115
	v_mul_f32 v112, v124, v112
	v_mul_f32 v113, v125, v113
	v_mad_u64_u32 v[100:101], s[0:1], v101, s77, v[100:101]
	s_waitcnt vmcnt(0)
	v_mul_f32 v110, v114, v110
	v_mul_f32 v111, v115, v111
	v_mul_f32 v108, v112, v108
	v_mul_f32 v109, v113, v109
	v_mov_b32_e32 v105, v100
	v_mov_b32_e32 v133, v2
	v_lshl_add_u64 v[104:105], v[104:105], 0, v[132:133]
	v_cvt_pk_bf16_f32 v100, v108, v109
	v_cvt_pk_bf16_f32 v101, v110, v111
	v_cvt_pk_bf16_f32 v102, v102, v103
	v_cvt_pk_bf16_f32 v103, v106, v107
	s_mov_b64 s[0:1], 0
	global_store_dwordx4 v[104:105], v[100:103], off offset:128
.LBB0_809:
	s_and_b64 vcc, exec, s[0:1]
	s_cbranch_vccz .LBB0_813
	v_mov_b32_e32 v118, v116
	v_mov_b32_e32 v119, v116
	v_mul_f32 v120, v98, v118
	v_mul_f32 v121, v99, v119
	v_mul_f32_e32 v98, v97, v97
	v_mul_f32_e32 v99, v121, v121
	v_mul_f32 v94, v94, v118
	v_mul_f32 v95, v95, v119
	v_fmac_f32_e32 v98, v96, v96
	v_fmac_f32_e32 v99, v120, v120
	v_add_f32_e32 v98, v98, v99
	v_mul_f32_e32 v99, v93, v93
	v_mul_f32_e32 v100, v95, v95
	v_fmac_f32_e32 v99, v92, v92
	v_fmac_f32_e32 v100, v94, v94
	v_add_f32_e32 v99, v99, v100
	v_add_f32_e32 v122, v98, v99
	global_load_dwordx4 v[98:101], v154, s[40:41] offset:16
	global_load_dwordx4 v[102:105], v154, s[40:41]
	global_load_dwordx4 v[106:109], v154, s[24:25] offset:16
	global_load_dwordx4 v[110:113], v154, s[24:25]
	v_mad_i64_i32 v[114:115], s[0:1], v128, 12, s[48:49]
	v_mov_b32_e32 v133, v2
	s_waitcnt vmcnt(1)
	v_mul_f32 v100, v100, v108
	v_mul_f32 v101, v101, v109
	v_mul_f32 v98, v98, v106
	v_mul_f32 v99, v99, v107
	s_waitcnt vmcnt(0)
	v_mul_f32 v102, v102, v110
	v_mul_f32 v103, v103, v111
	v_mul_f32 v100, v94, v100
	v_mul_f32 v101, v95, v101
	v_mul_f32 v94, v92, v98
	v_mul_f32 v95, v93, v99
	v_mul_f32 v104, v104, v112
	v_mul_f32 v105, v105, v113
	v_mul_f32 v96, v96, v102
	v_mul_f32 v97, v97, v103
	v_cvt_pk_bf16_f32 v94, v94, v95
	v_cvt_pk_bf16_f32 v95, v100, v101
	v_mul_f32 v100, v90, v118
	v_mul_f32 v101, v91, v119
	v_mul_f32 v102, v88, v116
	v_mul_f32 v103, v89, v117
	v_mul_f32 v104, v120, v104
	v_mul_f32 v105, v121, v105
	v_mul_f32 v108, v84, v116
	v_mul_f32 v109, v85, v117
	v_mul_f32_e32 v84, v103, v103
	v_mul_f32_e32 v85, v101, v101
	v_mov_b64_e32 v[106:107], s[28:29]
	v_cvt_pk_bf16_f32 v93, v104, v105
	v_mul_f32 v104, v86, v118
	v_mul_f32 v105, v87, v119
	v_fmac_f32_e32 v84, v102, v102
	v_fmac_f32_e32 v85, v100, v100
	v_mad_u64_u32 v[106:107], s[0:1], v114, s77, v[106:107]
	v_add_f32_e32 v84, v84, v85
	v_mul_f32_e32 v85, v109, v109
	v_mul_f32_e32 v86, v105, v105
	v_mad_i32_i24 v107, v115, s77, v107
	v_fmac_f32_e32 v85, v108, v108
	v_fmac_f32_e32 v86, v104, v104
	v_lshl_add_u64 v[106:107], v[106:107], 0, v[132:133]
	v_cvt_pk_bf16_f32 v92, v96, v97
	v_add_f32_e32 v85, v85, v86
	global_store_dwordx4 v[106:107], v[92:95], off
	v_add_f32_e32 v84, v84, v85
	v_add_f32_e32 v110, v122, v84
	global_load_dwordx4 v[84:87], v154, s[40:41] offset:144
	global_load_dwordx4 v[88:91], v154, s[40:41] offset:128
	global_load_dwordx4 v[92:95], v154, s[24:25] offset:144
	global_load_dwordx4 v[96:99], v154, s[24:25] offset:128
	s_waitcnt vmcnt(1)
	v_mul_f32 v86, v86, v94
	v_mul_f32 v87, v87, v95
	s_waitcnt vmcnt(0)
	v_mul_f32 v90, v90, v98
	v_mul_f32 v91, v91, v99
	v_mul_f32 v88, v88, v96
	v_mul_f32 v89, v89, v97
	v_mul_f32 v84, v84, v92
	v_mul_f32 v85, v85, v93
	v_mul_f32 v90, v100, v90
	v_mul_f32 v91, v101, v91
	v_mul_f32 v88, v102, v88
	v_mul_f32 v89, v103, v89
	v_mul_f32 v92, v104, v86
	v_mul_f32 v93, v105, v87
	v_mul_f32 v86, v108, v84
	v_mul_f32 v87, v109, v85
	v_cvt_pk_bf16_f32 v84, v88, v89
	v_cvt_pk_bf16_f32 v85, v90, v91
	v_cvt_pk_bf16_f32 v86, v86, v87
	v_cvt_pk_bf16_f32 v87, v92, v93
	global_store_dwordx4 v[106:107], v[84:87], off offset:64
	ds_swizzle_b32 v84, v110 offset:swizzle(SWAP,16)
	s_nop 0
	v_and_b32_e32 v86, 64, v236
	v_xor_b32_e32 v85, 32, v236
	v_add_u32_e32 v86, 64, v86
	v_cmp_lt_i32_e32 vcc, v85, v86
	s_waitcnt lgkmcnt(0)
	v_add_f32_e32 v84, v110, v84
	v_cndmask_b32_e32 v85, v236, v85, vcc
	v_lshlrev_b32_e32 v85, 2, v85
	ds_bpermute_b32 v85, v85, v84
	s_and_saveexec_b64 s[0:1], s[18:19]
	s_cbranch_execz .LBB0_812
	s_add_u32 s8, s35, s81
	s_addc_u32 s9, s54, s80
	s_waitcnt lgkmcnt(0)
	v_add_f32_e32 v86, v84, v85
	v_lshl_add_u64 v[84:85], v[152:153], 2, s[8:9]
	global_atomic_add_f32 v[84:85], v86, off offset:128

.LBB0_813:
	v_fmamk_f32 v84, v176, 0x3b2aaaab, v231
	s_waitcnt lgkmcnt(0)
	v_mul_f32_e32 v85, 0x4b800000, v84
	v_cmp_gt_f32_e32 vcc, s11, v84
	v_or_b32_e32 v112, 48, v152
	s_mov_b64 s[0:1], -1
	v_cndmask_b32_e32 v84, v84, v85, vcc
	v_rsq_f32_e32 v84, v84
	s_nop 0
	v_mul_f32_e32 v85, 0x45800000, v84
	v_cndmask_b32_e32 v100, v84, v85, vcc
	v_mov_b32_e32 v101, v100
	s_and_b64 vcc, exec, s[22:23]
	v_mul_f32 v80, v80, v100
	v_mul_f32 v81, v81, v101
	v_mul_f32 v76, v76, v100
	v_mul_f32 v77, v77, v101
	s_cbranch_vccnz .LBB0_823
	v_and_b32_e32 v85, 64, v236
	v_xor_b32_e32 v84, 32, v236
	v_add_u32_e32 v85, 64, v85
	v_cmp_lt_i32_e32 vcc, v84, v85
	v_mov_b32_e32 v104, v100
	v_mov_b32_e32 v105, v100
	v_cndmask_b32_e32 v84, v236, v84, vcc
	v_mul_f32 v102, v82, v104
	v_mul_f32 v103, v83, v105
	v_lshlrev_b32_e32 v110, 2, v84
	v_mul_f32_e32 v84, v81, v81
	v_mul_f32_e32 v85, v103, v103
	v_fmac_f32_e32 v84, v80, v80
	v_fmac_f32_e32 v85, v102, v102
	v_add_f32_e32 v106, v84, v85
	global_load_dwordx4 v[88:91], v154, s[40:41] offset:272
	global_load_dwordx4 v[96:99], v154, s[40:41] offset:256
	global_load_dwordx4 v[84:87], v156, s[26:27] offset:16
	global_load_dwordx4 v[92:95], v156, s[26:27]
	v_mul_f32 v104, v78, v104
	v_mul_f32 v105, v79, v105
	v_mul_f32_e32 v107, v77, v77
	v_mul_f32_e32 v108, v105, v105
	v_fmac_f32_e32 v107, v76, v76
	v_fmac_f32_e32 v108, v104, v104
	v_add_f32_e32 v107, v107, v108
	v_add_f32_e32 v106, v106, v107
	ds_swizzle_b32 v107, v106 offset:swizzle(SWAP,16)
	s_waitcnt lgkmcnt(0)
	v_add_f32_e32 v108, v106, v107
	ds_bpermute_b32 v109, v110, v108
	s_and_saveexec_b64 s[0:1], s[20:21]
	s_xor_b64 s[0:1], exec, s[0:1]
	s_ashr_i32 s47, s46, 31
	s_or_saveexec_b64 s[0:1], s[0:1]
	v_mov_b64_e32 v[106:107], s[46:47]
	s_xor_b64 exec, exec, s[0:1]
	s_cbranch_execz .LBB0_818
	s_ashr_i32 s47, s46, 31
	s_mul_i32 s8, s46, 0x10400
	s_mul_hi_i32 s9, s46, 0x10400
	s_add_u32 s8, s35, s8
	s_addc_u32 s9, s54, s9
	s_waitcnt lgkmcnt(0)
	v_add_f32_e32 v108, v108, v109
	v_lshl_add_u64 v[106:107], v[152:153], 2, s[8:9]
	global_atomic_add_f32 v[106:107], v108, off offset:192
	v_mov_b64_e32 v[106:107], s[46:47]
.LBB0_818:
	s_or_b64 exec, exec, s[0:1]
	s_waitcnt vmcnt(3)
	v_mul_f32 v90, v104, v90
	v_mul_f32 v91, v105, v91
	v_mul_f32 v88, v76, v88
	v_mul_f32 v89, v77, v89
	s_waitcnt vmcnt(1)
	v_mul_f32 v90, v90, v86
	v_mul_f32 v91, v91, v87
	v_mul_f32 v86, v88, v84
	v_mul_f32 v87, v89, v85
	v_mad_i64_i32 v[84:85], s[0:1], v112, 12, v[106:107]
	v_mov_b64_e32 v[88:89], s[28:29]
	v_mad_u64_u32 v[88:89], s[0:1], v84, s77, v[88:89]
	v_mov_b32_e32 v84, v89
	v_mul_f32 v98, v102, v98
	v_mul_f32 v99, v103, v99
	v_mul_f32 v96, v80, v96
	v_mul_f32 v97, v81, v97
	v_mad_u64_u32 v[84:85], s[0:1], v85, s77, v[84:85]
	s_waitcnt vmcnt(0)
	v_mul_f32 v94, v98, v94
	v_mul_f32 v95, v99, v95
	v_mul_f32 v92, v96, v92
	v_mul_f32 v93, v97, v93
	v_mov_b32_e32 v89, v84
	v_mov_b32_e32 v133, v2
	v_mov_b32_e32 v155, v2
	v_lshl_add_u64 v[88:89], v[88:89], 0, v[132:133]
	v_cvt_pk_bf16_f32 v84, v92, v93
	v_cvt_pk_bf16_f32 v85, v94, v95
	v_cvt_pk_bf16_f32 v86, v86, v87
	v_cvt_pk_bf16_f32 v87, v90, v91
	s_waitcnt lgkmcnt(0)
	v_lshl_add_u64 v[108:109], s[40:41], 0, v[154:155]
	v_mov_b32_e32 v157, v2
	global_store_dwordx4 v[88:89], v[84:87], off offset:128
	v_lshl_add_u64 v[114:115], s[26:27], 0, v[156:157]
	global_load_dwordx4 v[88:91], v[108:109], off offset:272
	global_load_dwordx4 v[96:99], v[108:109], off offset:256
	global_load_dwordx4 v[84:87], v[114:115], off offset:16
	global_load_dwordx4 v[92:95], v[114:115], off
	v_mov_b32_e32 v102, v100
	v_mov_b32_e32 v103, v100
	v_mul_f32 v106, v74, v102
	v_mul_f32 v107, v75, v103
	v_mul_f32 v108, v72, v100
	v_mul_f32 v109, v73, v101
	v_mul_f32_e32 v105, v107, v107
	v_mul_f32_e32 v104, v109, v109
	v_fmac_f32_e32 v104, v108, v108
	v_fmac_f32_e32 v105, v106, v106
	v_add_f32_e32 v111, v104, v105
	v_mul_f32 v104, v70, v102
	v_mul_f32 v105, v71, v103
	v_mul_f32 v102, v68, v100
	v_mul_f32 v103, v69, v101
	v_mul_f32_e32 v114, v105, v105
	v_mul_f32_e32 v113, v103, v103
	v_fmac_f32_e32 v113, v102, v102
	v_fmac_f32_e32 v114, v104, v104
	v_add_f32_e32 v113, v113, v114
	v_add_f32_e32 v111, v111, v113
	ds_swizzle_b32 v113, v111 offset:swizzle(SWAP,16)
	s_or_b32 s0, s46, 1
	s_waitcnt lgkmcnt(0)
	v_add_f32_e32 v113, v111, v113
	ds_bpermute_b32 v114, v110, v113
	s_and_saveexec_b64 s[8:9], s[20:21]
	s_xor_b64 s[8:9], exec, s[8:9]
	s_ashr_i32 s1, s0, 31
	s_or_saveexec_b64 s[8:9], s[8:9]
	v_mov_b64_e32 v[110:111], s[0:1]
	s_xor_b64 exec, exec, s[8:9]
	s_cbranch_execz .LBB0_822
	s_ashr_i32 s1, s0, 31
	s_mul_i32 s62, s0, 0x10400
	s_mul_hi_i32 s47, s0, 0x10400
	s_add_u32 s64, s35, s62
	s_addc_u32 s65, s54, s47
	s_waitcnt lgkmcnt(0)
	v_add_f32_e32 v113, v113, v114
	v_lshl_add_u64 v[110:111], v[152:153], 2, s[64:65]
	global_atomic_add_f32 v[110:111], v113, off offset:192
	v_mov_b64_e32 v[110:111], s[0:1]
.LBB0_822:
	s_or_b64 exec, exec, s[8:9]
	s_waitcnt lgkmcnt(0)
	v_mad_i64_i32 v[114:115], s[0:1], v112, 12, 0
	s_waitcnt vmcnt(3)
	v_mul_f32 v90, v104, v90
	v_mul_f32 v91, v105, v91
	v_mul_f32 v88, v102, v88
	v_mul_f32 v89, v103, v89
	s_waitcnt vmcnt(1)
	v_mul_f32 v90, v90, v86
	v_mul_f32 v91, v91, v87
	v_mul_f32 v86, v88, v84
	v_mul_f32 v87, v89, v85
	v_lshl_add_u64 v[84:85], v[110:111], 0, v[114:115]
	v_mov_b64_e32 v[88:89], s[28:29]
	v_mad_u64_u32 v[88:89], s[0:1], v84, s77, v[88:89]
	v_mov_b32_e32 v84, v89
	v_mul_f32 v98, v106, v98
	v_mul_f32 v99, v107, v99
	v_mul_f32 v96, v108, v96
	v_mul_f32 v97, v109, v97
	v_mad_u64_u32 v[84:85], s[0:1], v85, s77, v[84:85]
	s_waitcnt vmcnt(0)
	v_mul_f32 v94, v98, v94
	v_mul_f32 v95, v99, v95
	v_mul_f32 v92, v96, v92
	v_mul_f32 v93, v97, v93
	v_mov_b32_e32 v89, v84
	v_mov_b32_e32 v133, v2
	v_lshl_add_u64 v[88:89], v[88:89], 0, v[132:133]
	v_cvt_pk_bf16_f32 v84, v92, v93
	v_cvt_pk_bf16_f32 v85, v94, v95
	v_cvt_pk_bf16_f32 v86, v86, v87
	v_cvt_pk_bf16_f32 v87, v90, v91
	s_mov_b64 s[0:1], 0
	global_store_dwordx4 v[88:89], v[84:87], off offset:128
.LBB0_823:
	s_and_b64 vcc, exec, s[0:1]
	s_cbranch_vccz .LBB0_827
	v_mov_b32_e32 v102, v100
	v_mov_b32_e32 v103, v100
	v_mul_f32 v104, v82, v102
	v_mul_f32 v105, v83, v103
	v_mul_f32_e32 v82, v81, v81
	v_mul_f32_e32 v83, v105, v105
	v_mul_f32 v78, v78, v102
	v_mul_f32 v79, v79, v103
	v_fmac_f32_e32 v82, v80, v80
	v_fmac_f32_e32 v83, v104, v104
	v_add_f32_e32 v82, v82, v83
	v_mul_f32_e32 v83, v77, v77
	v_mul_f32_e32 v84, v79, v79
	v_fmac_f32_e32 v83, v76, v76
	v_fmac_f32_e32 v84, v78, v78
	v_add_f32_e32 v83, v83, v84
	v_add_f32_e32 v106, v82, v83
	global_load_dwordx4 v[82:85], v154, s[40:41] offset:16
	global_load_dwordx4 v[86:89], v154, s[40:41]
	global_load_dwordx4 v[90:93], v154, s[24:25] offset:16
	global_load_dwordx4 v[94:97], v154, s[24:25]
	v_mad_i64_i32 v[98:99], s[0:1], v112, 12, s[48:49]
	v_mov_b32_e32 v133, v2
	s_waitcnt vmcnt(1)
	v_mul_f32 v84, v84, v92
	v_mul_f32 v85, v85, v93
	v_mul_f32 v82, v82, v90
	v_mul_f32 v83, v83, v91
	s_waitcnt vmcnt(0)
	v_mul_f32 v86, v86, v94
	v_mul_f32 v87, v87, v95
	v_mul_f32 v84, v78, v84
	v_mul_f32 v85, v79, v85
	v_mul_f32 v78, v76, v82
	v_mul_f32 v79, v77, v83
	v_mul_f32 v88, v88, v96
	v_mul_f32 v89, v89, v97
	v_mul_f32 v80, v80, v86
	v_mul_f32 v81, v81, v87
	v_cvt_pk_bf16_f32 v78, v78, v79
	v_cvt_pk_bf16_f32 v79, v84, v85
	v_mul_f32 v84, v74, v102
	v_mul_f32 v85, v75, v103
	v_mul_f32 v86, v72, v100
	v_mul_f32 v87, v73, v101
	v_mul_f32 v88, v104, v88
	v_mul_f32 v89, v105, v89
	v_mul_f32 v92, v68, v100
	v_mul_f32 v93, v69, v101
	v_mul_f32_e32 v68, v87, v87
	v_mul_f32_e32 v69, v85, v85
	v_mov_b64_e32 v[90:91], s[28:29]
	v_cvt_pk_bf16_f32 v77, v88, v89
	v_mul_f32 v88, v70, v102
	v_mul_f32 v89, v71, v103
	v_fmac_f32_e32 v68, v86, v86
	v_fmac_f32_e32 v69, v84, v84
	v_mad_u64_u32 v[90:91], s[0:1], v98, s77, v[90:91]
	v_add_f32_e32 v68, v68, v69
	v_mul_f32_e32 v69, v93, v93
	v_mul_f32_e32 v70, v89, v89
	v_mad_i32_i24 v91, v99, s77, v91
	v_fmac_f32_e32 v69, v92, v92
	v_fmac_f32_e32 v70, v88, v88
	v_lshl_add_u64 v[90:91], v[90:91], 0, v[132:133]
	v_cvt_pk_bf16_f32 v76, v80, v81
	v_add_f32_e32 v69, v69, v70
	global_store_dwordx4 v[90:91], v[76:79], off
	v_add_f32_e32 v68, v68, v69
	v_add_f32_e32 v94, v106, v68
	global_load_dwordx4 v[68:71], v154, s[40:41] offset:144
	global_load_dwordx4 v[72:75], v154, s[40:41] offset:128
	global_load_dwordx4 v[76:79], v154, s[24:25] offset:144
	global_load_dwordx4 v[80:83], v154, s[24:25] offset:128
	s_waitcnt vmcnt(1)
	v_mul_f32 v70, v70, v78
	v_mul_f32 v71, v71, v79
	s_waitcnt vmcnt(0)
	v_mul_f32 v74, v74, v82
	v_mul_f32 v75, v75, v83
	v_mul_f32 v72, v72, v80
	v_mul_f32 v73, v73, v81
	v_mul_f32 v68, v68, v76
	v_mul_f32 v69, v69, v77
	v_mul_f32 v74, v84, v74
	v_mul_f32 v75, v85, v75
	v_mul_f32 v72, v86, v72
	v_mul_f32 v73, v87, v73
	v_mul_f32 v76, v88, v70
	v_mul_f32 v77, v89, v71
	v_mul_f32 v70, v92, v68
	v_mul_f32 v71, v93, v69
	v_cvt_pk_bf16_f32 v68, v72, v73
	v_cvt_pk_bf16_f32 v69, v74, v75
	v_cvt_pk_bf16_f32 v70, v70, v71
	v_cvt_pk_bf16_f32 v71, v76, v77
	global_store_dwordx4 v[90:91], v[68:71], off offset:64
	ds_swizzle_b32 v68, v94 offset:swizzle(SWAP,16)
	s_nop 0
	v_and_b32_e32 v70, 64, v236
	v_xor_b32_e32 v69, 32, v236
	v_add_u32_e32 v70, 64, v70
	v_cmp_lt_i32_e32 vcc, v69, v70
	s_waitcnt lgkmcnt(0)
	v_add_f32_e32 v68, v94, v68
	v_cndmask_b32_e32 v69, v236, v69, vcc
	v_lshlrev_b32_e32 v69, 2, v69
	ds_bpermute_b32 v69, v69, v68
	s_and_saveexec_b64 s[0:1], s[18:19]
	s_cbranch_execz .LBB0_826
	s_add_u32 s8, s35, s81
	s_addc_u32 s9, s54, s80
	s_waitcnt lgkmcnt(0)
	v_add_f32_e32 v70, v68, v69
	v_lshl_add_u64 v[68:69], v[152:153], 2, s[8:9]
	global_atomic_add_f32 v[68:69], v70, off offset:192

.LBB0_827:
	v_fmamk_f32 v68, v175, 0x3b2aaaab, v231
	s_waitcnt lgkmcnt(0)
	v_mul_f32_e32 v69, 0x4b800000, v68
	v_cmp_gt_f32_e32 vcc, s11, v68
	v_add_u32_e32 v96, 0x80, v152
	s_mov_b64 s[0:1], -1
	v_cndmask_b32_e32 v68, v68, v69, vcc
	v_rsq_f32_e32 v68, v68
	s_nop 0
	v_mul_f32_e32 v69, 0x45800000, v68
	v_cndmask_b32_e32 v84, v68, v69, vcc
	v_mov_b32_e32 v85, v84
	s_and_b64 vcc, exec, s[22:23]
	v_mul_f32 v64, v64, v84
	v_mul_f32 v65, v65, v85
	v_mul_f32 v60, v60, v84
	v_mul_f32 v61, v61, v85
	s_cbranch_vccnz .LBB0_837
	v_and_b32_e32 v69, 64, v236
	v_xor_b32_e32 v68, 32, v236
	v_add_u32_e32 v69, 64, v69
	v_cmp_lt_i32_e32 vcc, v68, v69
	v_mov_b32_e32 v88, v84
	v_mov_b32_e32 v89, v84
	v_cndmask_b32_e32 v68, v236, v68, vcc
	v_mul_f32 v86, v66, v88
	v_mul_f32 v87, v67, v89
	v_lshlrev_b32_e32 v94, 2, v68
	v_mul_f32_e32 v68, v65, v65
	v_mul_f32_e32 v69, v87, v87
	v_fmac_f32_e32 v68, v64, v64
	v_fmac_f32_e32 v69, v86, v86
	v_add_f32_e32 v90, v68, v69
	global_load_dwordx4 v[72:75], v154, s[40:41] offset:272
	global_load_dwordx4 v[80:83], v154, s[40:41] offset:256
	global_load_dwordx4 v[68:71], v156, s[26:27] offset:16
	global_load_dwordx4 v[76:79], v156, s[26:27]
	v_mul_f32 v88, v62, v88
	v_mul_f32 v89, v63, v89
	v_mul_f32_e32 v91, v61, v61
	v_mul_f32_e32 v92, v89, v89
	v_fmac_f32_e32 v91, v60, v60
	v_fmac_f32_e32 v92, v88, v88
	v_add_f32_e32 v91, v91, v92
	v_add_f32_e32 v90, v90, v91
	ds_swizzle_b32 v91, v90 offset:swizzle(SWAP,16)
	s_waitcnt lgkmcnt(0)
	v_add_f32_e32 v92, v90, v91
	ds_bpermute_b32 v93, v94, v92
	s_and_saveexec_b64 s[0:1], s[20:21]
	s_xor_b64 s[0:1], exec, s[0:1]
	s_ashr_i32 s47, s46, 31
	s_or_saveexec_b64 s[0:1], s[0:1]
	v_mov_b64_e32 v[90:91], s[46:47]
	s_xor_b64 exec, exec, s[0:1]
	s_cbranch_execz .LBB0_832
	s_ashr_i32 s47, s46, 31
	s_mul_i32 s8, s46, 0x10400
	s_mul_hi_i32 s9, s46, 0x10400
	s_add_u32 s8, s35, s8
	s_addc_u32 s9, s54, s9
	s_waitcnt lgkmcnt(0)
	v_add_f32_e32 v92, v92, v93
	v_lshl_add_u64 v[90:91], v[152:153], 2, s[8:9]
	global_atomic_add_f32 v[90:91], v92, off offset:512
	v_mov_b64_e32 v[90:91], s[46:47]
.LBB0_832:
	s_or_b64 exec, exec, s[0:1]
	s_waitcnt vmcnt(3)
	v_mul_f32 v74, v88, v74
	v_mul_f32 v75, v89, v75
	v_mul_f32 v72, v60, v72
	v_mul_f32 v73, v61, v73
	s_waitcnt vmcnt(1)
	v_mul_f32 v74, v74, v70
	v_mul_f32 v75, v75, v71
	v_mul_f32 v70, v72, v68
	v_mul_f32 v71, v73, v69
	v_mad_i64_i32 v[68:69], s[0:1], v96, 12, v[90:91]
	v_mov_b64_e32 v[72:73], s[28:29]
	v_mad_u64_u32 v[72:73], s[0:1], v68, s77, v[72:73]
	v_mov_b32_e32 v68, v73
	v_mul_f32 v82, v86, v82
	v_mul_f32 v83, v87, v83
	v_mul_f32 v80, v64, v80
	v_mul_f32 v81, v65, v81
	v_mad_u64_u32 v[68:69], s[0:1], v69, s77, v[68:69]
	s_waitcnt vmcnt(0)
	v_mul_f32 v78, v82, v78
	v_mul_f32 v79, v83, v79
	v_mul_f32 v76, v80, v76
	v_mul_f32 v77, v81, v77
	v_mov_b32_e32 v73, v68
	v_mov_b32_e32 v133, v2
	v_mov_b32_e32 v155, v2
	v_lshl_add_u64 v[72:73], v[72:73], 0, v[132:133]
	v_cvt_pk_bf16_f32 v68, v76, v77
	v_cvt_pk_bf16_f32 v69, v78, v79
	v_cvt_pk_bf16_f32 v70, v70, v71
	v_cvt_pk_bf16_f32 v71, v74, v75
	s_waitcnt lgkmcnt(0)
	v_lshl_add_u64 v[92:93], s[40:41], 0, v[154:155]
	v_mov_b32_e32 v157, v2
	global_store_dwordx4 v[72:73], v[68:71], off offset:128
	v_lshl_add_u64 v[98:99], s[26:27], 0, v[156:157]
	global_load_dwordx4 v[72:75], v[92:93], off offset:272
	global_load_dwordx4 v[80:83], v[92:93], off offset:256
	global_load_dwordx4 v[68:71], v[98:99], off offset:16
	global_load_dwordx4 v[76:79], v[98:99], off
	v_mov_b32_e32 v86, v84
	v_mov_b32_e32 v87, v84
	v_mul_f32 v90, v58, v86
	v_mul_f32 v91, v59, v87
	v_mul_f32 v92, v56, v84
	v_mul_f32 v93, v57, v85
	v_mul_f32_e32 v89, v91, v91
	v_mul_f32_e32 v88, v93, v93
	v_fmac_f32_e32 v88, v92, v92
	v_fmac_f32_e32 v89, v90, v90
	v_add_f32_e32 v95, v88, v89
	v_mul_f32 v88, v54, v86
	v_mul_f32 v89, v55, v87
	v_mul_f32 v86, v52, v84
	v_mul_f32 v87, v53, v85
	v_mul_f32_e32 v98, v89, v89
	v_mul_f32_e32 v97, v87, v87
	v_fmac_f32_e32 v97, v86, v86
	v_fmac_f32_e32 v98, v88, v88
	v_add_f32_e32 v97, v97, v98
	v_add_f32_e32 v95, v95, v97
	ds_swizzle_b32 v97, v95 offset:swizzle(SWAP,16)
	s_or_b32 s0, s46, 1
	s_waitcnt lgkmcnt(0)
	v_add_f32_e32 v97, v95, v97
	ds_bpermute_b32 v98, v94, v97
	s_and_saveexec_b64 s[8:9], s[20:21]
	s_xor_b64 s[8:9], exec, s[8:9]
	s_ashr_i32 s1, s0, 31
	s_or_saveexec_b64 s[8:9], s[8:9]
	v_mov_b64_e32 v[94:95], s[0:1]
	s_xor_b64 exec, exec, s[8:9]
	s_cbranch_execz .LBB0_836
	s_ashr_i32 s1, s0, 31
	s_mul_i32 s62, s0, 0x10400
	s_mul_hi_i32 s47, s0, 0x10400
	s_add_u32 s64, s35, s62
	s_addc_u32 s65, s54, s47
	s_waitcnt lgkmcnt(0)
	v_add_f32_e32 v97, v97, v98
	v_lshl_add_u64 v[94:95], v[152:153], 2, s[64:65]
	global_atomic_add_f32 v[94:95], v97, off offset:512
	v_mov_b64_e32 v[94:95], s[0:1]
.LBB0_836:
	s_or_b64 exec, exec, s[8:9]
	s_waitcnt lgkmcnt(0)
	v_mad_i64_i32 v[98:99], s[0:1], v96, 12, 0
	s_waitcnt vmcnt(3)
	v_mul_f32 v74, v88, v74
	v_mul_f32 v75, v89, v75
	v_mul_f32 v72, v86, v72
	v_mul_f32 v73, v87, v73
	s_waitcnt vmcnt(1)
	v_mul_f32 v74, v74, v70
	v_mul_f32 v75, v75, v71
	v_mul_f32 v70, v72, v68
	v_mul_f32 v71, v73, v69
	v_lshl_add_u64 v[68:69], v[94:95], 0, v[98:99]
	v_mov_b64_e32 v[72:73], s[28:29]
	v_mad_u64_u32 v[72:73], s[0:1], v68, s77, v[72:73]
	v_mov_b32_e32 v68, v73
	v_mul_f32 v82, v90, v82
	v_mul_f32 v83, v91, v83
	v_mul_f32 v80, v92, v80
	v_mul_f32 v81, v93, v81
	v_mad_u64_u32 v[68:69], s[0:1], v69, s77, v[68:69]
	s_waitcnt vmcnt(0)
	v_mul_f32 v78, v82, v78
	v_mul_f32 v79, v83, v79
	v_mul_f32 v76, v80, v76
	v_mul_f32 v77, v81, v77
	v_mov_b32_e32 v73, v68
	v_mov_b32_e32 v133, v2
	v_lshl_add_u64 v[72:73], v[72:73], 0, v[132:133]
	v_cvt_pk_bf16_f32 v68, v76, v77
	v_cvt_pk_bf16_f32 v69, v78, v79
	v_cvt_pk_bf16_f32 v70, v70, v71
	v_cvt_pk_bf16_f32 v71, v74, v75
	s_mov_b64 s[0:1], 0
	global_store_dwordx4 v[72:73], v[68:71], off offset:128
.LBB0_837:
	s_and_b64 vcc, exec, s[0:1]
	s_cbranch_vccz .LBB0_841
	v_mov_b32_e32 v86, v84
	v_mov_b32_e32 v87, v84
	v_mul_f32 v88, v66, v86
	v_mul_f32 v89, v67, v87
	v_mul_f32_e32 v66, v65, v65
	v_mul_f32_e32 v67, v89, v89
	v_mul_f32 v62, v62, v86
	v_mul_f32 v63, v63, v87
	v_fmac_f32_e32 v66, v64, v64
	v_fmac_f32_e32 v67, v88, v88
	v_add_f32_e32 v66, v66, v67
	v_mul_f32_e32 v67, v61, v61
	v_mul_f32_e32 v68, v63, v63
	v_fmac_f32_e32 v67, v60, v60
	v_fmac_f32_e32 v68, v62, v62
	v_add_f32_e32 v67, v67, v68
	v_add_f32_e32 v90, v66, v67
	global_load_dwordx4 v[66:69], v154, s[40:41] offset:16
	global_load_dwordx4 v[70:73], v154, s[40:41]
	global_load_dwordx4 v[74:77], v154, s[24:25] offset:16
	global_load_dwordx4 v[78:81], v154, s[24:25]
	v_mad_i64_i32 v[82:83], s[0:1], v96, 12, s[48:49]
	v_mov_b32_e32 v133, v2
	s_waitcnt vmcnt(1)
	v_mul_f32 v68, v68, v76
	v_mul_f32 v69, v69, v77
	v_mul_f32 v66, v66, v74
	v_mul_f32 v67, v67, v75
	s_waitcnt vmcnt(0)
	v_mul_f32 v70, v70, v78
	v_mul_f32 v71, v71, v79
	v_mul_f32 v68, v62, v68
	v_mul_f32 v69, v63, v69
	v_mul_f32 v62, v60, v66
	v_mul_f32 v63, v61, v67
	v_mul_f32 v72, v72, v80
	v_mul_f32 v73, v73, v81
	v_mul_f32 v64, v64, v70
	v_mul_f32 v65, v65, v71
	v_cvt_pk_bf16_f32 v62, v62, v63
	v_cvt_pk_bf16_f32 v63, v68, v69
	v_mul_f32 v68, v58, v86
	v_mul_f32 v69, v59, v87
	v_mul_f32 v70, v56, v84
	v_mul_f32 v71, v57, v85
	v_mul_f32 v72, v88, v72
	v_mul_f32 v73, v89, v73
	v_mul_f32 v76, v52, v84
	v_mul_f32 v77, v53, v85
	v_mul_f32_e32 v52, v71, v71
	v_mul_f32_e32 v53, v69, v69
	v_mov_b64_e32 v[74:75], s[28:29]
	v_cvt_pk_bf16_f32 v61, v72, v73
	v_mul_f32 v72, v54, v86
	v_mul_f32 v73, v55, v87
	v_fmac_f32_e32 v52, v70, v70
	v_fmac_f32_e32 v53, v68, v68
	v_mad_u64_u32 v[74:75], s[0:1], v82, s77, v[74:75]
	v_add_f32_e32 v52, v52, v53
	v_mul_f32_e32 v53, v77, v77
	v_mul_f32_e32 v54, v73, v73
	v_mad_i32_i24 v75, v83, s77, v75
	v_fmac_f32_e32 v53, v76, v76
	v_fmac_f32_e32 v54, v72, v72
	v_lshl_add_u64 v[74:75], v[74:75], 0, v[132:133]
	v_cvt_pk_bf16_f32 v60, v64, v65
	v_add_f32_e32 v53, v53, v54
	global_store_dwordx4 v[74:75], v[60:63], off
	v_add_f32_e32 v52, v52, v53
	v_add_f32_e32 v78, v90, v52
	global_load_dwordx4 v[52:55], v154, s[40:41] offset:144
	global_load_dwordx4 v[56:59], v154, s[40:41] offset:128
	global_load_dwordx4 v[60:63], v154, s[24:25] offset:144
	global_load_dwordx4 v[64:67], v154, s[24:25] offset:128
	s_waitcnt vmcnt(1)
	v_mul_f32 v54, v54, v62
	v_mul_f32 v55, v55, v63
	s_waitcnt vmcnt(0)
	v_mul_f32 v58, v58, v66
	v_mul_f32 v59, v59, v67
	v_mul_f32 v56, v56, v64
	v_mul_f32 v57, v57, v65
	v_mul_f32 v52, v52, v60
	v_mul_f32 v53, v53, v61
	v_mul_f32 v58, v68, v58
	v_mul_f32 v59, v69, v59
	v_mul_f32 v56, v70, v56
	v_mul_f32 v57, v71, v57
	v_mul_f32 v60, v72, v54
	v_mul_f32 v61, v73, v55
	v_mul_f32 v54, v76, v52
	v_mul_f32 v55, v77, v53
	v_cvt_pk_bf16_f32 v52, v56, v57
	v_cvt_pk_bf16_f32 v53, v58, v59
	v_cvt_pk_bf16_f32 v54, v54, v55
	v_cvt_pk_bf16_f32 v55, v60, v61
	global_store_dwordx4 v[74:75], v[52:55], off offset:64
	ds_swizzle_b32 v52, v78 offset:swizzle(SWAP,16)
	s_nop 0
	v_and_b32_e32 v54, 64, v236
	v_xor_b32_e32 v53, 32, v236
	v_add_u32_e32 v54, 64, v54
	v_cmp_lt_i32_e32 vcc, v53, v54
	s_waitcnt lgkmcnt(0)
	v_add_f32_e32 v52, v78, v52
	v_cndmask_b32_e32 v53, v236, v53, vcc
	v_lshlrev_b32_e32 v53, 2, v53
	ds_bpermute_b32 v53, v53, v52
	s_and_saveexec_b64 s[0:1], s[18:19]
	s_cbranch_execz .LBB0_840
	s_add_u32 s8, s35, s81
	s_addc_u32 s9, s54, s80
	s_waitcnt lgkmcnt(0)
	v_add_f32_e32 v54, v52, v53
	v_lshl_add_u64 v[52:53], v[152:153], 2, s[8:9]
	global_atomic_add_f32 v[52:53], v54, off offset:512

.LBB0_841:
	v_fmamk_f32 v52, v174, 0x3b2aaaab, v231
	s_waitcnt lgkmcnt(0)
	v_mul_f32_e32 v53, 0x4b800000, v52
	v_cmp_gt_f32_e32 vcc, s11, v52
	v_add_u32_e32 v80, 0x90, v152
	s_mov_b64 s[0:1], -1
	v_cndmask_b32_e32 v52, v52, v53, vcc
	v_rsq_f32_e32 v52, v52
	s_nop 0
	v_mul_f32_e32 v53, 0x45800000, v52
	v_cndmask_b32_e32 v68, v52, v53, vcc
	v_mov_b32_e32 v69, v68
	s_and_b64 vcc, exec, s[22:23]
	v_mul_f32 v48, v48, v68
	v_mul_f32 v49, v49, v69
	v_mul_f32 v44, v44, v68
	v_mul_f32 v45, v45, v69
	s_cbranch_vccnz .LBB0_851
	v_and_b32_e32 v53, 64, v236
	v_xor_b32_e32 v52, 32, v236
	v_add_u32_e32 v53, 64, v53
	v_cmp_lt_i32_e32 vcc, v52, v53
	v_mov_b32_e32 v72, v68
	v_mov_b32_e32 v73, v68
	v_cndmask_b32_e32 v52, v236, v52, vcc
	v_mul_f32 v70, v50, v72
	v_mul_f32 v71, v51, v73
	v_lshlrev_b32_e32 v78, 2, v52
	v_mul_f32_e32 v52, v49, v49
	v_mul_f32_e32 v53, v71, v71
	v_fmac_f32_e32 v52, v48, v48
	v_fmac_f32_e32 v53, v70, v70
	v_add_f32_e32 v74, v52, v53
	global_load_dwordx4 v[56:59], v154, s[40:41] offset:272
	global_load_dwordx4 v[64:67], v154, s[40:41] offset:256
	global_load_dwordx4 v[52:55], v156, s[26:27] offset:16
	global_load_dwordx4 v[60:63], v156, s[26:27]
	v_mul_f32 v72, v46, v72
	v_mul_f32 v73, v47, v73
	v_mul_f32_e32 v75, v45, v45
	v_mul_f32_e32 v76, v73, v73
	v_fmac_f32_e32 v75, v44, v44
	v_fmac_f32_e32 v76, v72, v72
	v_add_f32_e32 v75, v75, v76
	v_add_f32_e32 v74, v74, v75
	ds_swizzle_b32 v75, v74 offset:swizzle(SWAP,16)
	s_waitcnt lgkmcnt(0)
	v_add_f32_e32 v76, v74, v75
	ds_bpermute_b32 v77, v78, v76
	s_and_saveexec_b64 s[0:1], s[20:21]
	s_xor_b64 s[0:1], exec, s[0:1]
	s_ashr_i32 s47, s46, 31
	s_or_saveexec_b64 s[0:1], s[0:1]
	v_mov_b64_e32 v[74:75], s[46:47]
	s_xor_b64 exec, exec, s[0:1]
	s_cbranch_execz .LBB0_846
	s_ashr_i32 s47, s46, 31
	s_mul_i32 s8, s46, 0x10400
	s_mul_hi_i32 s9, s46, 0x10400
	s_add_u32 s8, s35, s8
	s_addc_u32 s9, s54, s9
	s_waitcnt lgkmcnt(0)
	v_add_f32_e32 v76, v76, v77
	v_lshl_add_u64 v[74:75], v[152:153], 2, s[8:9]
	global_atomic_add_f32 v[74:75], v76, off offset:576
	v_mov_b64_e32 v[74:75], s[46:47]
.LBB0_846:
	s_or_b64 exec, exec, s[0:1]
	s_waitcnt vmcnt(3)
	v_mul_f32 v58, v72, v58
	v_mul_f32 v59, v73, v59
	v_mul_f32 v56, v44, v56
	v_mul_f32 v57, v45, v57
	s_waitcnt vmcnt(1)
	v_mul_f32 v58, v58, v54
	v_mul_f32 v59, v59, v55
	v_mul_f32 v54, v56, v52
	v_mul_f32 v55, v57, v53
	v_mad_i64_i32 v[52:53], s[0:1], v80, 12, v[74:75]
	v_mov_b64_e32 v[56:57], s[28:29]
	v_mad_u64_u32 v[56:57], s[0:1], v52, s77, v[56:57]
	v_mov_b32_e32 v52, v57
	v_mul_f32 v66, v70, v66
	v_mul_f32 v67, v71, v67
	v_mul_f32 v64, v48, v64
	v_mul_f32 v65, v49, v65
	v_mad_u64_u32 v[52:53], s[0:1], v53, s77, v[52:53]
	s_waitcnt vmcnt(0)
	v_mul_f32 v62, v66, v62
	v_mul_f32 v63, v67, v63
	v_mul_f32 v60, v64, v60
	v_mul_f32 v61, v65, v61
	v_mov_b32_e32 v57, v52
	v_mov_b32_e32 v133, v2
	v_mov_b32_e32 v155, v2
	v_lshl_add_u64 v[56:57], v[56:57], 0, v[132:133]
	v_cvt_pk_bf16_f32 v52, v60, v61
	v_cvt_pk_bf16_f32 v53, v62, v63
	v_cvt_pk_bf16_f32 v54, v54, v55
	v_cvt_pk_bf16_f32 v55, v58, v59
	s_waitcnt lgkmcnt(0)
	v_lshl_add_u64 v[76:77], s[40:41], 0, v[154:155]
	v_mov_b32_e32 v157, v2
	global_store_dwordx4 v[56:57], v[52:55], off offset:128
	v_lshl_add_u64 v[82:83], s[26:27], 0, v[156:157]
	global_load_dwordx4 v[56:59], v[76:77], off offset:272
	global_load_dwordx4 v[64:67], v[76:77], off offset:256
	global_load_dwordx4 v[52:55], v[82:83], off offset:16
	global_load_dwordx4 v[60:63], v[82:83], off
	v_mov_b32_e32 v70, v68
	v_mov_b32_e32 v71, v68
	v_mul_f32 v74, v42, v70
	v_mul_f32 v75, v43, v71
	v_mul_f32 v76, v40, v68
	v_mul_f32 v77, v41, v69
	v_mul_f32_e32 v73, v75, v75
	v_mul_f32_e32 v72, v77, v77
	v_fmac_f32_e32 v72, v76, v76
	v_fmac_f32_e32 v73, v74, v74
	v_add_f32_e32 v79, v72, v73
	v_mul_f32 v72, v38, v70
	v_mul_f32 v73, v39, v71
	v_mul_f32 v70, v36, v68
	v_mul_f32 v71, v37, v69
	v_mul_f32_e32 v82, v73, v73
	v_mul_f32_e32 v81, v71, v71
	v_fmac_f32_e32 v81, v70, v70
	v_fmac_f32_e32 v82, v72, v72
	v_add_f32_e32 v81, v81, v82
	v_add_f32_e32 v79, v79, v81
	ds_swizzle_b32 v81, v79 offset:swizzle(SWAP,16)
	s_or_b32 s0, s46, 1
	s_waitcnt lgkmcnt(0)
	v_add_f32_e32 v81, v79, v81
	ds_bpermute_b32 v82, v78, v81
	s_and_saveexec_b64 s[8:9], s[20:21]
	s_xor_b64 s[8:9], exec, s[8:9]
	s_ashr_i32 s1, s0, 31
	s_or_saveexec_b64 s[8:9], s[8:9]
	v_mov_b64_e32 v[78:79], s[0:1]
	s_xor_b64 exec, exec, s[8:9]
	s_cbranch_execz .LBB0_850
	s_ashr_i32 s1, s0, 31
	s_mul_i32 s62, s0, 0x10400
	s_mul_hi_i32 s47, s0, 0x10400
	s_add_u32 s64, s35, s62
	s_addc_u32 s65, s54, s47
	s_waitcnt lgkmcnt(0)
	v_add_f32_e32 v81, v81, v82
	v_lshl_add_u64 v[78:79], v[152:153], 2, s[64:65]
	global_atomic_add_f32 v[78:79], v81, off offset:576
	v_mov_b64_e32 v[78:79], s[0:1]
.LBB0_850:
	s_or_b64 exec, exec, s[8:9]
	s_waitcnt lgkmcnt(0)
	v_mad_i64_i32 v[82:83], s[0:1], v80, 12, 0
	s_waitcnt vmcnt(3)
	v_mul_f32 v58, v72, v58
	v_mul_f32 v59, v73, v59
	v_mul_f32 v56, v70, v56
	v_mul_f32 v57, v71, v57
	s_waitcnt vmcnt(1)
	v_mul_f32 v58, v58, v54
	v_mul_f32 v59, v59, v55
	v_mul_f32 v54, v56, v52
	v_mul_f32 v55, v57, v53
	v_lshl_add_u64 v[52:53], v[78:79], 0, v[82:83]
	v_mov_b64_e32 v[56:57], s[28:29]
	v_mad_u64_u32 v[56:57], s[0:1], v52, s77, v[56:57]
	v_mov_b32_e32 v52, v57
	v_mul_f32 v66, v74, v66
	v_mul_f32 v67, v75, v67
	v_mul_f32 v64, v76, v64
	v_mul_f32 v65, v77, v65
	v_mad_u64_u32 v[52:53], s[0:1], v53, s77, v[52:53]
	s_waitcnt vmcnt(0)
	v_mul_f32 v62, v66, v62
	v_mul_f32 v63, v67, v63
	v_mul_f32 v60, v64, v60
	v_mul_f32 v61, v65, v61
	v_mov_b32_e32 v57, v52
	v_mov_b32_e32 v133, v2
	v_lshl_add_u64 v[56:57], v[56:57], 0, v[132:133]
	v_cvt_pk_bf16_f32 v52, v60, v61
	v_cvt_pk_bf16_f32 v53, v62, v63
	v_cvt_pk_bf16_f32 v54, v54, v55
	v_cvt_pk_bf16_f32 v55, v58, v59
	s_mov_b64 s[0:1], 0
	global_store_dwordx4 v[56:57], v[52:55], off offset:128
.LBB0_851:
	s_and_b64 vcc, exec, s[0:1]
	s_cbranch_vccz .LBB0_855
	v_mov_b32_e32 v70, v68
	v_mov_b32_e32 v71, v68
	v_mul_f32 v72, v50, v70
	v_mul_f32 v73, v51, v71
	v_mul_f32_e32 v50, v49, v49
	v_mul_f32_e32 v51, v73, v73
	v_mul_f32 v46, v46, v70
	v_mul_f32 v47, v47, v71
	v_fmac_f32_e32 v50, v48, v48
	v_fmac_f32_e32 v51, v72, v72
	v_add_f32_e32 v50, v50, v51
	v_mul_f32_e32 v51, v45, v45
	v_mul_f32_e32 v52, v47, v47
	v_fmac_f32_e32 v51, v44, v44
	v_fmac_f32_e32 v52, v46, v46
	v_add_f32_e32 v51, v51, v52
	v_add_f32_e32 v74, v50, v51
	global_load_dwordx4 v[50:53], v154, s[40:41] offset:16
	global_load_dwordx4 v[54:57], v154, s[40:41]
	global_load_dwordx4 v[58:61], v154, s[24:25] offset:16
	global_load_dwordx4 v[62:65], v154, s[24:25]
	v_mad_i64_i32 v[66:67], s[0:1], v80, 12, s[48:49]
	v_mov_b32_e32 v133, v2
	s_waitcnt vmcnt(1)
	v_mul_f32 v52, v52, v60
	v_mul_f32 v53, v53, v61
	v_mul_f32 v50, v50, v58
	v_mul_f32 v51, v51, v59
	s_waitcnt vmcnt(0)
	v_mul_f32 v54, v54, v62
	v_mul_f32 v55, v55, v63
	v_mul_f32 v52, v46, v52
	v_mul_f32 v53, v47, v53
	v_mul_f32 v46, v44, v50
	v_mul_f32 v47, v45, v51
	v_mul_f32 v56, v56, v64
	v_mul_f32 v57, v57, v65
	v_mul_f32 v48, v48, v54
	v_mul_f32 v49, v49, v55
	v_cvt_pk_bf16_f32 v46, v46, v47
	v_cvt_pk_bf16_f32 v47, v52, v53
	v_mul_f32 v52, v42, v70
	v_mul_f32 v53, v43, v71
	v_mul_f32 v54, v40, v68
	v_mul_f32 v55, v41, v69
	v_mul_f32 v56, v72, v56
	v_mul_f32 v57, v73, v57
	v_mul_f32 v60, v36, v68
	v_mul_f32 v61, v37, v69
	v_mul_f32_e32 v36, v55, v55
	v_mul_f32_e32 v37, v53, v53
	v_mov_b64_e32 v[58:59], s[28:29]
	v_cvt_pk_bf16_f32 v45, v56, v57
	v_mul_f32 v56, v38, v70
	v_mul_f32 v57, v39, v71
	v_fmac_f32_e32 v36, v54, v54
	v_fmac_f32_e32 v37, v52, v52
	v_mad_u64_u32 v[58:59], s[0:1], v66, s77, v[58:59]
	v_add_f32_e32 v36, v36, v37
	v_mul_f32_e32 v37, v61, v61
	v_mul_f32_e32 v38, v57, v57
	v_mad_i32_i24 v59, v67, s77, v59
	v_fmac_f32_e32 v37, v60, v60
	v_fmac_f32_e32 v38, v56, v56
	v_lshl_add_u64 v[58:59], v[58:59], 0, v[132:133]
	v_cvt_pk_bf16_f32 v44, v48, v49
	v_add_f32_e32 v37, v37, v38
	global_store_dwordx4 v[58:59], v[44:47], off
	v_add_f32_e32 v36, v36, v37
	v_add_f32_e32 v62, v74, v36
	global_load_dwordx4 v[36:39], v154, s[40:41] offset:144
	global_load_dwordx4 v[40:43], v154, s[40:41] offset:128
	global_load_dwordx4 v[44:47], v154, s[24:25] offset:144
	global_load_dwordx4 v[48:51], v154, s[24:25] offset:128
	s_waitcnt vmcnt(1)
	v_mul_f32 v38, v38, v46
	v_mul_f32 v39, v39, v47
	s_waitcnt vmcnt(0)
	v_mul_f32 v42, v42, v50
	v_mul_f32 v43, v43, v51
	v_mul_f32 v40, v40, v48
	v_mul_f32 v41, v41, v49
	v_mul_f32 v36, v36, v44
	v_mul_f32 v37, v37, v45
	v_mul_f32 v42, v52, v42
	v_mul_f32 v43, v53, v43
	v_mul_f32 v40, v54, v40
	v_mul_f32 v41, v55, v41
	v_mul_f32 v44, v56, v38
	v_mul_f32 v45, v57, v39
	v_mul_f32 v38, v60, v36
	v_mul_f32 v39, v61, v37
	v_cvt_pk_bf16_f32 v36, v40, v41
	v_cvt_pk_bf16_f32 v37, v42, v43
	v_cvt_pk_bf16_f32 v38, v38, v39
	v_cvt_pk_bf16_f32 v39, v44, v45
	global_store_dwordx4 v[58:59], v[36:39], off offset:64
	ds_swizzle_b32 v36, v62 offset:swizzle(SWAP,16)
	s_nop 0
	v_and_b32_e32 v38, 64, v236
	v_xor_b32_e32 v37, 32, v236
	v_add_u32_e32 v38, 64, v38
	v_cmp_lt_i32_e32 vcc, v37, v38
	s_waitcnt lgkmcnt(0)
	v_add_f32_e32 v36, v62, v36
	v_cndmask_b32_e32 v37, v236, v37, vcc
	v_lshlrev_b32_e32 v37, 2, v37
	ds_bpermute_b32 v37, v37, v36
	s_and_saveexec_b64 s[0:1], s[18:19]
	s_cbranch_execz .LBB0_854
	s_add_u32 s8, s35, s81
	s_addc_u32 s9, s54, s80
	s_waitcnt lgkmcnt(0)
	v_add_f32_e32 v38, v36, v37
	v_lshl_add_u64 v[36:37], v[152:153], 2, s[8:9]
	global_atomic_add_f32 v[36:37], v38, off offset:576

.LBB0_855:
	v_fmamk_f32 v36, v173, 0x3b2aaaab, v231
	s_waitcnt lgkmcnt(0)
	v_mul_f32_e32 v37, 0x4b800000, v36
	v_cmp_gt_f32_e32 vcc, s11, v36
	v_add_u32_e32 v64, 0xa0, v152
	s_mov_b64 s[0:1], -1
	v_cndmask_b32_e32 v36, v36, v37, vcc
	v_rsq_f32_e32 v36, v36
	s_nop 0
	v_mul_f32_e32 v37, 0x45800000, v36
	v_cndmask_b32_e32 v52, v36, v37, vcc
	v_mov_b32_e32 v53, v52
	s_and_b64 vcc, exec, s[22:23]
	v_mul_f32 v32, v32, v52
	v_mul_f32 v33, v33, v53
	v_mul_f32 v28, v28, v52
	v_mul_f32 v29, v29, v53
	s_cbranch_vccnz .LBB0_865
	v_and_b32_e32 v37, 64, v236
	v_xor_b32_e32 v36, 32, v236
	v_add_u32_e32 v37, 64, v37
	v_cmp_lt_i32_e32 vcc, v36, v37
	v_mov_b32_e32 v56, v52
	v_mov_b32_e32 v57, v52
	v_cndmask_b32_e32 v36, v236, v36, vcc
	v_mul_f32 v54, v34, v56
	v_mul_f32 v55, v35, v57
	v_lshlrev_b32_e32 v62, 2, v36
	v_mul_f32_e32 v36, v33, v33
	v_mul_f32_e32 v37, v55, v55
	v_fmac_f32_e32 v36, v32, v32
	v_fmac_f32_e32 v37, v54, v54
	v_add_f32_e32 v58, v36, v37
	global_load_dwordx4 v[40:43], v154, s[40:41] offset:272
	global_load_dwordx4 v[48:51], v154, s[40:41] offset:256
	global_load_dwordx4 v[36:39], v156, s[26:27] offset:16
	global_load_dwordx4 v[44:47], v156, s[26:27]
	v_mul_f32 v56, v30, v56
	v_mul_f32 v57, v31, v57
	v_mul_f32_e32 v59, v29, v29
	v_mul_f32_e32 v60, v57, v57
	v_fmac_f32_e32 v59, v28, v28
	v_fmac_f32_e32 v60, v56, v56
	v_add_f32_e32 v59, v59, v60
	v_add_f32_e32 v58, v58, v59
	ds_swizzle_b32 v59, v58 offset:swizzle(SWAP,16)
	s_waitcnt lgkmcnt(0)
	v_add_f32_e32 v60, v58, v59
	ds_bpermute_b32 v61, v62, v60
	s_and_saveexec_b64 s[0:1], s[20:21]
	s_xor_b64 s[0:1], exec, s[0:1]
	s_ashr_i32 s47, s46, 31
	s_or_saveexec_b64 s[0:1], s[0:1]
	v_mov_b64_e32 v[58:59], s[46:47]
	s_xor_b64 exec, exec, s[0:1]
	s_cbranch_execz .LBB0_860
	s_ashr_i32 s47, s46, 31
	s_mul_i32 s8, s46, 0x10400
	s_mul_hi_i32 s9, s46, 0x10400
	s_add_u32 s8, s35, s8
	s_addc_u32 s9, s54, s9
	s_waitcnt lgkmcnt(0)
	v_add_f32_e32 v60, v60, v61
	v_lshl_add_u64 v[58:59], v[152:153], 2, s[8:9]
	global_atomic_add_f32 v[58:59], v60, off offset:640
	v_mov_b64_e32 v[58:59], s[46:47]
.LBB0_860:
	s_or_b64 exec, exec, s[0:1]
	s_waitcnt vmcnt(3)
	v_mul_f32 v42, v56, v42
	v_mul_f32 v43, v57, v43
	v_mul_f32 v40, v28, v40
	v_mul_f32 v41, v29, v41
	s_waitcnt vmcnt(1)
	v_mul_f32 v42, v42, v38
	v_mul_f32 v43, v43, v39
	v_mul_f32 v38, v40, v36
	v_mul_f32 v39, v41, v37
	v_mad_i64_i32 v[36:37], s[0:1], v64, 12, v[58:59]
	v_mov_b64_e32 v[40:41], s[28:29]
	v_mad_u64_u32 v[40:41], s[0:1], v36, s77, v[40:41]
	v_mov_b32_e32 v36, v41
	v_mul_f32 v50, v54, v50
	v_mul_f32 v51, v55, v51
	v_mul_f32 v48, v32, v48
	v_mul_f32 v49, v33, v49
	v_mad_u64_u32 v[36:37], s[0:1], v37, s77, v[36:37]
	s_waitcnt vmcnt(0)
	v_mul_f32 v46, v50, v46
	v_mul_f32 v47, v51, v47
	v_mul_f32 v44, v48, v44
	v_mul_f32 v45, v49, v45
	v_mov_b32_e32 v41, v36
	v_mov_b32_e32 v133, v2
	v_mov_b32_e32 v155, v2
	v_lshl_add_u64 v[40:41], v[40:41], 0, v[132:133]
	v_cvt_pk_bf16_f32 v36, v44, v45
	v_cvt_pk_bf16_f32 v37, v46, v47
	v_cvt_pk_bf16_f32 v38, v38, v39
	v_cvt_pk_bf16_f32 v39, v42, v43
	s_waitcnt lgkmcnt(0)
	v_lshl_add_u64 v[60:61], s[40:41], 0, v[154:155]
	v_mov_b32_e32 v157, v2
	global_store_dwordx4 v[40:41], v[36:39], off offset:128
	v_lshl_add_u64 v[66:67], s[26:27], 0, v[156:157]
	global_load_dwordx4 v[40:43], v[60:61], off offset:272
	global_load_dwordx4 v[48:51], v[60:61], off offset:256
	global_load_dwordx4 v[36:39], v[66:67], off offset:16
	global_load_dwordx4 v[44:47], v[66:67], off
	v_mov_b32_e32 v54, v52
	v_mov_b32_e32 v55, v52
	v_mul_f32 v58, v26, v54
	v_mul_f32 v59, v27, v55
	v_mul_f32 v60, v24, v52
	v_mul_f32 v61, v25, v53
	v_mul_f32_e32 v57, v59, v59
	v_mul_f32_e32 v56, v61, v61
	v_fmac_f32_e32 v56, v60, v60
	v_fmac_f32_e32 v57, v58, v58
	v_add_f32_e32 v63, v56, v57
	v_mul_f32 v56, v22, v54
	v_mul_f32 v57, v23, v55
	v_mul_f32 v54, v20, v52
	v_mul_f32 v55, v21, v53
	v_mul_f32_e32 v66, v57, v57
	v_mul_f32_e32 v65, v55, v55
	v_fmac_f32_e32 v65, v54, v54
	v_fmac_f32_e32 v66, v56, v56
	v_add_f32_e32 v65, v65, v66
	v_add_f32_e32 v63, v63, v65
	ds_swizzle_b32 v65, v63 offset:swizzle(SWAP,16)
	s_or_b32 s0, s46, 1
	s_waitcnt lgkmcnt(0)
	v_add_f32_e32 v65, v63, v65
	ds_bpermute_b32 v66, v62, v65
	s_and_saveexec_b64 s[8:9], s[20:21]
	s_xor_b64 s[8:9], exec, s[8:9]
	s_ashr_i32 s1, s0, 31
	s_or_saveexec_b64 s[8:9], s[8:9]
	v_mov_b64_e32 v[62:63], s[0:1]
	s_xor_b64 exec, exec, s[8:9]
	s_cbranch_execz .LBB0_864
	s_ashr_i32 s1, s0, 31
	s_mul_i32 s62, s0, 0x10400
	s_mul_hi_i32 s47, s0, 0x10400
	s_add_u32 s64, s35, s62
	s_addc_u32 s65, s54, s47
	s_waitcnt lgkmcnt(0)
	v_add_f32_e32 v65, v65, v66
	v_lshl_add_u64 v[62:63], v[152:153], 2, s[64:65]
	global_atomic_add_f32 v[62:63], v65, off offset:640
	v_mov_b64_e32 v[62:63], s[0:1]
.LBB0_864:
	s_or_b64 exec, exec, s[8:9]
	s_waitcnt lgkmcnt(0)
	v_mad_i64_i32 v[66:67], s[0:1], v64, 12, 0
	s_waitcnt vmcnt(3)
	v_mul_f32 v42, v56, v42
	v_mul_f32 v43, v57, v43
	v_mul_f32 v40, v54, v40
	v_mul_f32 v41, v55, v41
	s_waitcnt vmcnt(1)
	v_mul_f32 v42, v42, v38
	v_mul_f32 v43, v43, v39
	v_mul_f32 v38, v40, v36
	v_mul_f32 v39, v41, v37
	v_lshl_add_u64 v[36:37], v[62:63], 0, v[66:67]
	v_mov_b64_e32 v[40:41], s[28:29]
	v_mad_u64_u32 v[40:41], s[0:1], v36, s77, v[40:41]
	v_mov_b32_e32 v36, v41
	v_mul_f32 v50, v58, v50
	v_mul_f32 v51, v59, v51
	v_mul_f32 v48, v60, v48
	v_mul_f32 v49, v61, v49
	v_mad_u64_u32 v[36:37], s[0:1], v37, s77, v[36:37]
	s_waitcnt vmcnt(0)
	v_mul_f32 v46, v50, v46
	v_mul_f32 v47, v51, v47
	v_mul_f32 v44, v48, v44
	v_mul_f32 v45, v49, v45
	v_mov_b32_e32 v41, v36
	v_mov_b32_e32 v133, v2
	v_lshl_add_u64 v[40:41], v[40:41], 0, v[132:133]
	v_cvt_pk_bf16_f32 v36, v44, v45
	v_cvt_pk_bf16_f32 v37, v46, v47
	v_cvt_pk_bf16_f32 v38, v38, v39
	v_cvt_pk_bf16_f32 v39, v42, v43
	s_mov_b64 s[0:1], 0
	global_store_dwordx4 v[40:41], v[36:39], off offset:128
.LBB0_865:
	s_and_b64 vcc, exec, s[0:1]
	s_cbranch_vccz .LBB0_869
	v_mov_b32_e32 v54, v52
	v_mov_b32_e32 v55, v52
	v_mul_f32 v56, v34, v54
	v_mul_f32 v57, v35, v55
	v_mul_f32_e32 v34, v33, v33
	v_mul_f32_e32 v35, v57, v57
	v_mul_f32 v30, v30, v54
	v_mul_f32 v31, v31, v55
	v_fmac_f32_e32 v34, v32, v32
	v_fmac_f32_e32 v35, v56, v56
	v_add_f32_e32 v34, v34, v35
	v_mul_f32_e32 v35, v29, v29
	v_mul_f32_e32 v36, v31, v31
	v_fmac_f32_e32 v35, v28, v28
	v_fmac_f32_e32 v36, v30, v30
	v_add_f32_e32 v35, v35, v36
	v_add_f32_e32 v58, v34, v35
	global_load_dwordx4 v[34:37], v154, s[40:41] offset:16
	global_load_dwordx4 v[38:41], v154, s[40:41]
	global_load_dwordx4 v[42:45], v154, s[24:25] offset:16
	global_load_dwordx4 v[46:49], v154, s[24:25]
	v_mad_i64_i32 v[50:51], s[0:1], v64, 12, s[48:49]
	v_mov_b32_e32 v133, v2
	s_waitcnt vmcnt(1)
	v_mul_f32 v36, v36, v44
	v_mul_f32 v37, v37, v45
	v_mul_f32 v34, v34, v42
	v_mul_f32 v35, v35, v43
	s_waitcnt vmcnt(0)
	v_mul_f32 v38, v38, v46
	v_mul_f32 v39, v39, v47
	v_mul_f32 v36, v30, v36
	v_mul_f32 v37, v31, v37
	v_mul_f32 v30, v28, v34
	v_mul_f32 v31, v29, v35
	v_mul_f32 v40, v40, v48
	v_mul_f32 v41, v41, v49
	v_mul_f32 v32, v32, v38
	v_mul_f32 v33, v33, v39
	v_cvt_pk_bf16_f32 v30, v30, v31
	v_cvt_pk_bf16_f32 v31, v36, v37
	v_mul_f32 v36, v26, v54
	v_mul_f32 v37, v27, v55
	v_mul_f32 v38, v24, v52
	v_mul_f32 v39, v25, v53
	v_mul_f32 v40, v56, v40
	v_mul_f32 v41, v57, v41
	v_mul_f32 v44, v20, v52
	v_mul_f32 v45, v21, v53
	v_mul_f32_e32 v20, v39, v39
	v_mul_f32_e32 v21, v37, v37
	v_mov_b64_e32 v[42:43], s[28:29]
	v_cvt_pk_bf16_f32 v29, v40, v41
	v_mul_f32 v40, v22, v54
	v_mul_f32 v41, v23, v55
	v_fmac_f32_e32 v20, v38, v38
	v_fmac_f32_e32 v21, v36, v36
	v_mad_u64_u32 v[42:43], s[0:1], v50, s77, v[42:43]
	v_add_f32_e32 v20, v20, v21
	v_mul_f32_e32 v21, v45, v45
	v_mul_f32_e32 v22, v41, v41
	v_mad_i32_i24 v43, v51, s77, v43
	v_fmac_f32_e32 v21, v44, v44
	v_fmac_f32_e32 v22, v40, v40
	v_lshl_add_u64 v[42:43], v[42:43], 0, v[132:133]
	v_cvt_pk_bf16_f32 v28, v32, v33
	v_add_f32_e32 v21, v21, v22
	global_store_dwordx4 v[42:43], v[28:31], off
	v_add_f32_e32 v20, v20, v21
	v_add_f32_e32 v46, v58, v20
	global_load_dwordx4 v[20:23], v154, s[40:41] offset:144
	global_load_dwordx4 v[24:27], v154, s[40:41] offset:128
	global_load_dwordx4 v[28:31], v154, s[24:25] offset:144
	global_load_dwordx4 v[32:35], v154, s[24:25] offset:128
	s_waitcnt vmcnt(1)
	v_mul_f32 v22, v22, v30
	v_mul_f32 v23, v23, v31
	s_waitcnt vmcnt(0)
	v_mul_f32 v26, v26, v34
	v_mul_f32 v27, v27, v35
	v_mul_f32 v24, v24, v32
	v_mul_f32 v25, v25, v33
	v_mul_f32 v20, v20, v28
	v_mul_f32 v21, v21, v29
	v_mul_f32 v26, v36, v26
	v_mul_f32 v27, v37, v27
	v_mul_f32 v24, v38, v24
	v_mul_f32 v25, v39, v25
	v_mul_f32 v28, v40, v22
	v_mul_f32 v29, v41, v23
	v_mul_f32 v22, v44, v20
	v_mul_f32 v23, v45, v21
	v_cvt_pk_bf16_f32 v20, v24, v25
	v_cvt_pk_bf16_f32 v21, v26, v27
	v_cvt_pk_bf16_f32 v22, v22, v23
	v_cvt_pk_bf16_f32 v23, v28, v29
	global_store_dwordx4 v[42:43], v[20:23], off offset:64
	ds_swizzle_b32 v20, v46 offset:swizzle(SWAP,16)
	s_nop 0
	v_and_b32_e32 v22, 64, v236
	v_xor_b32_e32 v21, 32, v236
	v_add_u32_e32 v22, 64, v22
	v_cmp_lt_i32_e32 vcc, v21, v22
	s_waitcnt lgkmcnt(0)
	v_add_f32_e32 v20, v46, v20
	v_cndmask_b32_e32 v21, v236, v21, vcc
	v_lshlrev_b32_e32 v21, 2, v21
	ds_bpermute_b32 v21, v21, v20
	s_and_saveexec_b64 s[0:1], s[18:19]
	s_cbranch_execz .LBB0_868
	s_add_u32 s8, s35, s81
	s_addc_u32 s9, s54, s80
	s_waitcnt lgkmcnt(0)
	v_add_f32_e32 v22, v20, v21
	v_lshl_add_u64 v[20:21], v[152:153], 2, s[8:9]
	global_atomic_add_f32 v[20:21], v22, off offset:640

.LBB0_869:
	v_fmamk_f32 v20, v172, 0x3b2aaaab, v231
	s_waitcnt lgkmcnt(0)
	v_mul_f32_e32 v21, 0x4b800000, v20
	v_cmp_gt_f32_e32 vcc, s11, v20
	v_add_u32_e32 v48, 0xb0, v152
	s_mov_b64 s[0:1], -1
	v_cndmask_b32_e32 v20, v20, v21, vcc
	v_rsq_f32_e32 v20, v20
	s_nop 0
	v_mul_f32_e32 v21, 0x45800000, v20
	v_cndmask_b32_e32 v36, v20, v21, vcc
	v_mov_b32_e32 v37, v36
	s_and_b64 vcc, exec, s[22:23]
	v_mul_f32 v16, v16, v36
	v_mul_f32 v17, v17, v37
	v_mul_f32 v12, v12, v36
	v_mul_f32 v13, v13, v37
	s_cbranch_vccnz .LBB0_879
	v_and_b32_e32 v21, 64, v236
	v_xor_b32_e32 v20, 32, v236
	v_add_u32_e32 v21, 64, v21
	v_cmp_lt_i32_e32 vcc, v20, v21
	v_mov_b32_e32 v40, v36
	v_mov_b32_e32 v41, v36
	v_cndmask_b32_e32 v20, v236, v20, vcc
	v_mul_f32 v38, v18, v40
	v_mul_f32 v39, v19, v41
	v_lshlrev_b32_e32 v46, 2, v20
	v_mul_f32_e32 v20, v17, v17
	v_mul_f32_e32 v21, v39, v39
	v_fmac_f32_e32 v20, v16, v16
	v_fmac_f32_e32 v21, v38, v38
	v_add_f32_e32 v42, v20, v21
	global_load_dwordx4 v[24:27], v154, s[40:41] offset:272
	global_load_dwordx4 v[32:35], v154, s[40:41] offset:256
	global_load_dwordx4 v[20:23], v156, s[26:27] offset:16
	global_load_dwordx4 v[28:31], v156, s[26:27]
	v_mul_f32 v40, v14, v40
	v_mul_f32 v41, v15, v41
	v_mul_f32_e32 v43, v13, v13
	v_mul_f32_e32 v44, v41, v41
	v_fmac_f32_e32 v43, v12, v12
	v_fmac_f32_e32 v44, v40, v40
	v_add_f32_e32 v43, v43, v44
	v_add_f32_e32 v42, v42, v43
	ds_swizzle_b32 v43, v42 offset:swizzle(SWAP,16)
	s_waitcnt lgkmcnt(0)
	v_add_f32_e32 v44, v42, v43
	ds_bpermute_b32 v45, v46, v44
	s_and_saveexec_b64 s[0:1], s[20:21]
	s_xor_b64 s[0:1], exec, s[0:1]
	s_ashr_i32 s47, s46, 31
	s_or_saveexec_b64 s[0:1], s[0:1]
	v_mov_b64_e32 v[42:43], s[46:47]
	s_xor_b64 exec, exec, s[0:1]
	s_cbranch_execz .LBB0_874
	s_ashr_i32 s47, s46, 31
	s_mul_i32 s8, s46, 0x10400
	s_mul_hi_i32 s9, s46, 0x10400
	s_add_u32 s8, s35, s8
	s_addc_u32 s9, s54, s9
	s_waitcnt lgkmcnt(0)
	v_add_f32_e32 v44, v44, v45
	v_lshl_add_u64 v[42:43], v[152:153], 2, s[8:9]
	global_atomic_add_f32 v[42:43], v44, off offset:704
	v_mov_b64_e32 v[42:43], s[46:47]
.LBB0_874:
	s_or_b64 exec, exec, s[0:1]
	s_waitcnt vmcnt(3)
	v_mul_f32 v26, v40, v26
	v_mul_f32 v27, v41, v27
	v_mul_f32 v24, v12, v24
	v_mul_f32 v25, v13, v25
	s_waitcnt vmcnt(1)
	v_mul_f32 v26, v26, v22
	v_mul_f32 v27, v27, v23
	v_mul_f32 v22, v24, v20
	v_mul_f32 v23, v25, v21
	v_mad_i64_i32 v[20:21], s[0:1], v48, 12, v[42:43]
	v_mov_b64_e32 v[24:25], s[28:29]
	v_mad_u64_u32 v[24:25], s[0:1], v20, s77, v[24:25]
	v_mov_b32_e32 v20, v25
	v_mul_f32 v34, v38, v34
	v_mul_f32 v35, v39, v35
	v_mul_f32 v32, v16, v32
	v_mul_f32 v33, v17, v33
	v_mad_u64_u32 v[20:21], s[0:1], v21, s77, v[20:21]
	s_waitcnt vmcnt(0)
	v_mul_f32 v30, v34, v30
	v_mul_f32 v31, v35, v31
	v_mul_f32 v28, v32, v28
	v_mul_f32 v29, v33, v29
	v_mov_b32_e32 v25, v20
	v_mov_b32_e32 v133, v2
	v_mov_b32_e32 v155, v2
	v_lshl_add_u64 v[24:25], v[24:25], 0, v[132:133]
	v_cvt_pk_bf16_f32 v20, v28, v29
	v_cvt_pk_bf16_f32 v21, v30, v31
	v_cvt_pk_bf16_f32 v22, v22, v23
	v_cvt_pk_bf16_f32 v23, v26, v27
	s_waitcnt lgkmcnt(0)
	v_lshl_add_u64 v[44:45], s[40:41], 0, v[154:155]
	v_mov_b32_e32 v157, v2
	global_store_dwordx4 v[24:25], v[20:23], off offset:128
	v_lshl_add_u64 v[50:51], s[26:27], 0, v[156:157]
	global_load_dwordx4 v[24:27], v[44:45], off offset:272
	global_load_dwordx4 v[32:35], v[44:45], off offset:256
	global_load_dwordx4 v[20:23], v[50:51], off offset:16
	global_load_dwordx4 v[28:31], v[50:51], off
	v_mov_b32_e32 v38, v36
	v_mov_b32_e32 v39, v36
	v_mul_f32 v42, v10, v38
	v_mul_f32 v43, v11, v39
	v_mul_f32 v44, v8, v36
	v_mul_f32 v45, v9, v37
	v_mul_f32_e32 v41, v43, v43
	v_mul_f32_e32 v40, v45, v45
	v_fmac_f32_e32 v40, v44, v44
	v_fmac_f32_e32 v41, v42, v42
	v_add_f32_e32 v47, v40, v41
	v_mul_f32 v40, v6, v38
	v_mul_f32 v41, v7, v39
	v_mul_f32 v38, v4, v36
	v_mul_f32 v39, v5, v37
	v_mul_f32_e32 v50, v41, v41
	v_mul_f32_e32 v49, v39, v39
	v_fmac_f32_e32 v49, v38, v38
	v_fmac_f32_e32 v50, v40, v40
	v_add_f32_e32 v49, v49, v50
	v_add_f32_e32 v47, v47, v49
	ds_swizzle_b32 v49, v47 offset:swizzle(SWAP,16)
	s_or_b32 s0, s46, 1
	s_waitcnt lgkmcnt(0)
	v_add_f32_e32 v49, v47, v49
	ds_bpermute_b32 v50, v46, v49
	s_and_saveexec_b64 s[8:9], s[20:21]
	s_xor_b64 s[8:9], exec, s[8:9]
	s_ashr_i32 s1, s0, 31
	s_or_saveexec_b64 s[8:9], s[8:9]
	v_mov_b64_e32 v[46:47], s[0:1]
	s_xor_b64 exec, exec, s[8:9]
	s_cbranch_execz .LBB0_878
	s_ashr_i32 s1, s0, 31
	s_mul_i32 s20, s0, 0x10400
	s_mul_hi_i32 s21, s0, 0x10400
	s_add_u32 s20, s35, s20
	s_addc_u32 s21, s54, s21
	s_waitcnt lgkmcnt(0)
	v_add_f32_e32 v49, v49, v50
	v_lshl_add_u64 v[46:47], v[152:153], 2, s[20:21]
	global_atomic_add_f32 v[46:47], v49, off offset:704
	v_mov_b64_e32 v[46:47], s[0:1]
.LBB0_878:
	s_or_b64 exec, exec, s[8:9]
	s_waitcnt lgkmcnt(0)
	v_mad_i64_i32 v[50:51], s[0:1], v48, 12, 0
	s_waitcnt vmcnt(3)
	v_mul_f32 v26, v40, v26
	v_mul_f32 v27, v41, v27
	v_mul_f32 v24, v38, v24
	v_mul_f32 v25, v39, v25
	s_waitcnt vmcnt(1)
	v_mul_f32 v26, v26, v22
	v_mul_f32 v27, v27, v23
	v_mul_f32 v22, v24, v20
	v_mul_f32 v23, v25, v21
	v_lshl_add_u64 v[20:21], v[46:47], 0, v[50:51]
	v_mov_b64_e32 v[24:25], s[28:29]
	v_mad_u64_u32 v[24:25], s[0:1], v20, s77, v[24:25]
	v_mov_b32_e32 v20, v25
	v_mul_f32 v34, v42, v34
	v_mul_f32 v35, v43, v35
	v_mul_f32 v32, v44, v32
	v_mul_f32 v33, v45, v33
	v_mad_u64_u32 v[20:21], s[0:1], v21, s77, v[20:21]
	s_waitcnt vmcnt(0)
	v_mul_f32 v30, v34, v30
	v_mul_f32 v31, v35, v31
	v_mul_f32 v28, v32, v28
	v_mul_f32 v29, v33, v29
	v_mov_b32_e32 v25, v20
	v_mov_b32_e32 v133, v2
	v_lshl_add_u64 v[24:25], v[24:25], 0, v[132:133]
	v_cvt_pk_bf16_f32 v20, v28, v29
	v_cvt_pk_bf16_f32 v21, v30, v31
	v_cvt_pk_bf16_f32 v22, v22, v23
	v_cvt_pk_bf16_f32 v23, v26, v27
	s_mov_b64 s[0:1], 0
	global_store_dwordx4 v[24:25], v[20:23], off offset:128
.LBB0_879:
	s_and_b64 vcc, exec, s[0:1]
	s_cbranch_vccz .LBB0_756
	v_mov_b32_e32 v38, v36
	v_mov_b32_e32 v39, v36
	v_mul_f32 v40, v18, v38
	v_mul_f32 v41, v19, v39
	v_mul_f32_e32 v18, v17, v17
	v_mul_f32_e32 v19, v41, v41
	v_mul_f32 v14, v14, v38
	v_mul_f32 v15, v15, v39
	v_fmac_f32_e32 v18, v16, v16
	v_fmac_f32_e32 v19, v40, v40
	v_add_f32_e32 v18, v18, v19
	v_mul_f32_e32 v19, v13, v13
	v_mul_f32_e32 v20, v15, v15
	v_fmac_f32_e32 v19, v12, v12
	v_fmac_f32_e32 v20, v14, v14
	v_add_f32_e32 v19, v19, v20
	v_add_f32_e32 v42, v18, v19
	global_load_dwordx4 v[18:21], v154, s[40:41] offset:16
	global_load_dwordx4 v[22:25], v154, s[40:41]
	global_load_dwordx4 v[26:29], v154, s[24:25] offset:16
	global_load_dwordx4 v[30:33], v154, s[24:25]
	v_mad_i64_i32 v[34:35], s[0:1], v48, 12, s[48:49]
	v_mov_b32_e32 v133, v2
	s_waitcnt vmcnt(1)
	v_mul_f32 v20, v20, v28
	v_mul_f32 v21, v21, v29
	v_mul_f32 v18, v18, v26
	v_mul_f32 v19, v19, v27
	s_waitcnt vmcnt(0)
	v_mul_f32 v22, v22, v30
	v_mul_f32 v23, v23, v31
	v_mul_f32 v20, v14, v20
	v_mul_f32 v21, v15, v21
	v_mul_f32 v14, v12, v18
	v_mul_f32 v15, v13, v19
	v_mul_f32 v24, v24, v32
	v_mul_f32 v25, v25, v33
	v_mul_f32 v16, v16, v22
	v_mul_f32 v17, v17, v23
	v_cvt_pk_bf16_f32 v14, v14, v15
	v_cvt_pk_bf16_f32 v15, v20, v21
	v_mul_f32 v20, v10, v38
	v_mul_f32 v21, v11, v39
	v_mul_f32 v22, v8, v36
	v_mul_f32 v23, v9, v37
	v_mul_f32 v24, v40, v24
	v_mul_f32 v25, v41, v25
	v_mul_f32 v28, v4, v36
	v_mul_f32 v29, v5, v37
	v_mul_f32_e32 v4, v23, v23
	v_mul_f32_e32 v5, v21, v21
	v_mov_b64_e32 v[26:27], s[28:29]
	v_cvt_pk_bf16_f32 v13, v24, v25
	v_mul_f32 v24, v6, v38
	v_mul_f32 v25, v7, v39
	v_fmac_f32_e32 v4, v22, v22
	v_fmac_f32_e32 v5, v20, v20
	v_mad_u64_u32 v[26:27], s[0:1], v34, s77, v[26:27]
	v_add_f32_e32 v4, v4, v5
	v_mul_f32_e32 v5, v29, v29
	v_mul_f32_e32 v6, v25, v25
	v_mad_i32_i24 v27, v35, s77, v27
	v_fmac_f32_e32 v5, v28, v28
	v_fmac_f32_e32 v6, v24, v24
	v_lshl_add_u64 v[26:27], v[26:27], 0, v[132:133]
	v_cvt_pk_bf16_f32 v12, v16, v17
	v_add_f32_e32 v5, v5, v6
	global_store_dwordx4 v[26:27], v[12:15], off
	v_add_f32_e32 v4, v4, v5
	v_add_f32_e32 v30, v42, v4
	global_load_dwordx4 v[4:7], v154, s[40:41] offset:144
	global_load_dwordx4 v[8:11], v154, s[40:41] offset:128
	global_load_dwordx4 v[12:15], v154, s[24:25] offset:144
	global_load_dwordx4 v[16:19], v154, s[24:25] offset:128
	s_waitcnt vmcnt(1)
	v_mul_f32 v6, v6, v14
	v_mul_f32 v7, v7, v15
	s_waitcnt vmcnt(0)
	v_mul_f32 v10, v10, v18
	v_mul_f32 v11, v11, v19
	v_mul_f32 v8, v8, v16
	v_mul_f32 v9, v9, v17
	v_mul_f32 v4, v4, v12
	v_mul_f32 v5, v5, v13
	v_mul_f32 v10, v20, v10
	v_mul_f32 v11, v21, v11
	v_mul_f32 v8, v22, v8
	v_mul_f32 v9, v23, v9
	v_mul_f32 v12, v24, v6
	v_mul_f32 v13, v25, v7
	v_mul_f32 v6, v28, v4
	v_mul_f32 v7, v29, v5
	v_cvt_pk_bf16_f32 v4, v8, v9
	v_cvt_pk_bf16_f32 v5, v10, v11
	v_cvt_pk_bf16_f32 v6, v6, v7
	v_cvt_pk_bf16_f32 v7, v12, v13
	global_store_dwordx4 v[26:27], v[4:7], off offset:64
	ds_swizzle_b32 v4, v30 offset:swizzle(SWAP,16)
	s_nop 0
	v_and_b32_e32 v6, 64, v236
	v_xor_b32_e32 v5, 32, v236
	v_add_u32_e32 v6, 64, v6
	v_cmp_lt_i32_e32 vcc, v5, v6
	s_waitcnt lgkmcnt(0)
	v_add_f32_e32 v4, v30, v4
	v_cndmask_b32_e32 v5, v236, v5, vcc
	v_lshlrev_b32_e32 v5, 2, v5
	ds_bpermute_b32 v5, v5, v4
	s_and_saveexec_b64 s[0:1], s[18:19]
	s_cbranch_execz .LBB0_755
	s_add_u32 s8, s35, s81
	s_addc_u32 s9, s54, s80
	s_waitcnt lgkmcnt(0)
	v_add_f32_e32 v6, v4, v5
	v_lshl_add_u64 v[4:5], v[152:153], 2, s[8:9]
	global_atomic_add_f32 v[4:5], v6, off offset:704
	s_branch .LBB0_755

.LBB0_897:
	s_or_b64 exec, exec, s[0:1]
	s_and_saveexec_b64 s[0:1], s[18:19]
	s_cbranch_execz .LBB0_901
	v_max_f32_e32 v100, v85, v85
	v_max_f32_e32 v141, v84, v84
	v_max_f32_e32 v100, v141, v100
	v_max3_f32 v100, v100, v86, v87
	v_max3_f32 v100, v100, v88, v89
	v_max3_f32 v100, v100, v90, v91
	v_max3_f32 v100, v100, v92, v93
	v_max3_f32 v100, v100, v94, v95
	v_max3_f32 v100, v100, v96, v97
	v_max3_f32 v100, v100, v98, v99
	v_max3_f32 v100, v100, v52, v53
	v_max3_f32 v100, v100, v54, v55
	v_max3_f32 v100, v100, v56, v57
	v_max3_f32 v100, v100, v58, v59
	v_and_b32_e32 v142, 64, v236
	v_max3_f32 v100, v100, v60, v61
	v_xor_b32_e32 v141, 32, v236
	v_add_u32_e32 v142, 64, v142
	v_max3_f32 v100, v100, v62, v63
	v_cmp_lt_i32_e32 vcc, v141, v142
	v_max3_f32 v100, v100, v64, v65
	v_max3_f32 v100, v100, v66, v67
	v_cndmask_b32_e32 v141, v236, v141, vcc
	v_lshlrev_b32_e32 v141, 2, v141
	ds_bpermute_b32 v141, v141, v100
	s_waitcnt lgkmcnt(0)
	v_max3_f32 v141, v139, v100, v141
	v_sub_f32_e32 v100, v139, v141
	v_exp_f32_e32 v100, v100
	s_nop 0
	v_cmp_neq_f32_e32 vcc, 1.0, v100
	s_cbranch_vccz .LBB0_900
	v_mul_f32 v34, v34, v100
	v_mul_f32 v35, v35, v100
	v_mul_f32 v32, v32, v100
	v_mul_f32 v33, v33, v100
	v_mul_f32 v30, v30, v100
	v_mul_f32 v31, v31, v100
	v_mul_f32 v28, v28, v100
	v_mul_f32 v29, v29, v100
	v_mul_f32 v26, v26, v100
	v_mul_f32 v27, v27, v100
	v_mul_f32 v24, v24, v100
	v_mul_f32 v25, v25, v100
	v_mul_f32 v22, v22, v100
	v_mul_f32 v23, v23, v100
	v_mul_f32 v20, v20, v100
	v_mul_f32 v21, v21, v100
	v_mul_f32 v18, v18, v100
	v_mul_f32 v19, v19, v100
	v_mul_f32 v16, v16, v100
	v_mul_f32 v17, v17, v100
	v_mul_f32 v14, v14, v100
	v_mul_f32 v15, v15, v100
	v_mul_f32 v12, v12, v100
	v_mul_f32 v13, v13, v100
	v_mul_f32 v10, v10, v100
	v_mul_f32 v11, v11, v100
	v_mul_f32 v8, v8, v100
	v_mul_f32 v9, v9, v100
	v_mul_f32 v6, v6, v100
	v_mul_f32 v7, v7, v100
	v_mul_f32 v4, v4, v100
	v_mul_f32 v5, v5, v100

.LBB0_906:
	v_max_f32_e32 v37, v37, v37
	v_max_f32_e32 v36, v36, v36
	v_max_f32_e32 v36, v36, v37
	v_max3_f32 v36, v36, v38, v39
	v_max3_f32 v36, v36, v40, v41
	v_max3_f32 v36, v36, v42, v43
	v_max3_f32 v36, v36, v44, v45
	v_max3_f32 v36, v36, v46, v47
	v_max3_f32 v36, v36, v48, v49
	v_max3_f32 v36, v36, v50, v51
	v_max3_f32 v36, v36, v68, v69
	v_max3_f32 v36, v36, v70, v71
	v_max3_f32 v36, v36, v72, v73
	v_max3_f32 v36, v36, v74, v75
	v_and_b32_e32 v38, 64, v236
	v_max3_f32 v36, v36, v76, v77
	v_xor_b32_e32 v37, 32, v236
	v_add_u32_e32 v38, 64, v38
	v_max3_f32 v36, v36, v78, v79
	v_cmp_lt_i32_e32 vcc, v37, v38
	v_max3_f32 v36, v36, v80, v81
	v_max3_f32 v36, v36, v82, v83
	v_cndmask_b32_e32 v37, v236, v37, vcc
	v_lshlrev_b32_e32 v37, 2, v37
	ds_bpermute_b32 v37, v37, v36
	s_waitcnt lgkmcnt(0)
	v_max3_f32 v37, v139, v36, v37
	v_sub_f32_e32 v36, v139, v37
	v_exp_f32_e32 v36, v36
	s_nop 0
	v_cmp_neq_f32_e32 vcc, 1.0, v36
	s_cbranch_vccz .LBB0_908
	v_mul_f32 v34, v34, v36
	v_mul_f32 v35, v35, v36
	v_mul_f32 v32, v32, v36
	v_mul_f32 v33, v33, v36
	v_mul_f32 v30, v30, v36
	v_mul_f32 v31, v31, v36
	v_mul_f32 v28, v28, v36
	v_mul_f32 v29, v29, v36
	v_mul_f32 v26, v26, v36
	v_mul_f32 v27, v27, v36
	v_mul_f32 v24, v24, v36
	v_mul_f32 v25, v25, v36
	v_mul_f32 v22, v22, v36
	v_mul_f32 v23, v23, v36
	v_mul_f32 v20, v20, v36
	v_mul_f32 v21, v21, v36
	v_mul_f32 v18, v18, v36
	v_mul_f32 v19, v19, v36
	v_mul_f32 v16, v16, v36
	v_mul_f32 v17, v17, v36
	v_mul_f32 v14, v14, v36
	v_mul_f32 v15, v15, v36
	v_mul_f32 v12, v12, v36
	v_mul_f32 v13, v13, v36
	v_mul_f32 v10, v10, v36
	v_mul_f32 v11, v11, v36
	v_mul_f32 v8, v8, v36
	v_mul_f32 v9, v9, v36
	v_mul_f32 v6, v6, v36
	v_mul_f32 v7, v7, v36
	v_mul_f32 v4, v4, v36
	v_mul_f32 v5, v5, v36

.LBB0_909:
	s_nop 3
	v_max_f32_e32 v36, v85, v85
	v_max_f32_e32 v37, v84, v84
	v_max_f32_e32 v36, v37, v36
	v_max3_f32 v36, v36, v86, v87
	v_max3_f32 v36, v36, v88, v89
	v_max3_f32 v36, v36, v90, v91
	v_max3_f32 v36, v36, v92, v93
	v_max3_f32 v36, v36, v94, v95
	v_max3_f32 v36, v36, v96, v97
	v_max3_f32 v36, v36, v98, v99
	v_max3_f32 v36, v36, v52, v53
	v_max3_f32 v36, v36, v54, v55
	v_max3_f32 v36, v36, v56, v57
	v_max3_f32 v36, v36, v58, v59
	v_and_b32_e32 v38, 64, v236
	v_max3_f32 v36, v36, v60, v61
	v_xor_b32_e32 v37, 32, v236
	v_add_u32_e32 v38, 64, v38
	v_max3_f32 v36, v36, v62, v63
	v_cmp_lt_i32_e32 vcc, v37, v38
	v_max3_f32 v36, v36, v64, v65
	v_max3_f32 v36, v36, v66, v67
	v_cndmask_b32_e32 v37, v236, v37, vcc
	v_lshlrev_b32_e32 v37, 2, v37
	ds_bpermute_b32 v37, v37, v36
	s_waitcnt lgkmcnt(0)
	v_max3_f32 v37, v139, v36, v37
	v_sub_f32_e32 v36, v139, v37
	v_exp_f32_e32 v36, v36
	s_nop 0
	v_cmp_neq_f32_e32 vcc, 1.0, v36
	s_cbranch_vccz .LBB0_911
	v_mul_f32 v34, v34, v36
	v_mul_f32 v35, v35, v36
	v_mul_f32 v32, v32, v36
	v_mul_f32 v33, v33, v36
	v_mul_f32 v30, v30, v36
	v_mul_f32 v31, v31, v36
	v_mul_f32 v28, v28, v36
	v_mul_f32 v29, v29, v36
	v_mul_f32 v26, v26, v36
	v_mul_f32 v27, v27, v36
	v_mul_f32 v24, v24, v36
	v_mul_f32 v25, v25, v36
	v_mul_f32 v22, v22, v36
	v_mul_f32 v23, v23, v36
	v_mul_f32 v20, v20, v36
	v_mul_f32 v21, v21, v36
	v_mul_f32 v18, v18, v36
	v_mul_f32 v19, v19, v36
	v_mul_f32 v16, v16, v36
	v_mul_f32 v17, v17, v36
	v_mul_f32 v14, v14, v36
	v_mul_f32 v15, v15, v36
	v_mul_f32 v12, v12, v36
	v_mul_f32 v13, v13, v36
	v_mul_f32 v10, v10, v36
	v_mul_f32 v11, v11, v36
	v_mul_f32 v8, v8, v36
	v_mul_f32 v9, v9, v36
	v_mul_f32 v6, v6, v36
	v_mul_f32 v7, v7, v36
	v_mul_f32 v4, v4, v36
	v_mul_f32 v5, v5, v36

.LBB0_940:
	s_and_saveexec_b64 s[8:9], s[22:23]
	s_cbranch_execz .LBB0_887
	s_waitcnt lgkmcnt(0)
	v_add_f32_e32 v3, v3, v36
	v_div_scale_f32 v36, s[16:17], v3, v3, 1.0
	v_rcp_f32_e32 v37, v36
	v_div_scale_f32 v38, vcc, 1.0, v3, 1.0
	v_mov_b32_e32 v41, v2
	v_fma_f32 v39, -v36, v37, 1.0
	v_fmac_f32_e32 v37, v39, v37
	v_mul_f32_e32 v39, v38, v37
	v_fma_f32 v40, -v36, v39, v38
	v_fmac_f32_e32 v39, v40, v37
	v_fma_f32 v36, -v36, v39, v38
	v_div_fmas_f32 v36, v36, v37, v39
	v_div_fixup_f32 v36, v36, v3, 1.0
	v_lshlrev_b64 v[38:39], 11, v[132:133]
	v_lshl_add_u64 v[38:39], s[0:1], 0, v[38:39]
	v_lshlrev_b32_e32 v40, 3, v1
	v_mul_f32 v20, v36, v20
	v_mul_f32 v21, v36, v21
	v_mul_f32 v22, v36, v22
	v_mul_f32 v23, v36, v23
	v_mul_f32 v4, v36, v4
	v_mul_f32 v5, v36, v5
	v_mul_f32 v6, v36, v6
	v_mul_f32 v7, v36, v7
	v_lshl_add_u64 v[38:39], v[38:39], 0, v[40:41]
	v_cvt_pk_bf16_f32 v20, v20, v21
	v_cvt_pk_bf16_f32 v21, v22, v23
	v_cvt_pk_bf16_f32 v4, v4, v5
	v_cvt_pk_bf16_f32 v5, v6, v7
	global_store_dwordx2 v[38:39], v[20:21], off
	v_mul_f32 v20, v36, v24
	v_mul_f32 v21, v36, v25
	v_mul_f32 v22, v36, v26
	v_mul_f32 v23, v36, v27
	global_store_dwordx2 v[38:39], v[4:5], off offset:64
	v_mul_f32 v4, v36, v8
	v_mul_f32 v5, v36, v9
	v_mul_f32 v6, v36, v10
	v_mul_f32 v7, v36, v11
	v_cvt_pk_bf16_f32 v20, v20, v21
	v_cvt_pk_bf16_f32 v21, v22, v23
	v_cvt_pk_bf16_f32 v4, v4, v5
	v_cvt_pk_bf16_f32 v5, v6, v7
	global_store_dwordx2 v[38:39], v[20:21], off offset:16
	v_mul_f32 v20, v36, v28
	v_mul_f32 v21, v36, v29
	v_mul_f32 v22, v36, v30
	v_mul_f32 v23, v36, v31
	global_store_dwordx2 v[38:39], v[4:5], off offset:80
	v_mul_f32 v4, v36, v12
	v_mul_f32 v5, v36, v13
	v_mul_f32 v6, v36, v14
	v_mul_f32 v7, v36, v15
	v_cvt_pk_bf16_f32 v20, v20, v21
	v_cvt_pk_bf16_f32 v21, v22, v23
	v_cvt_pk_bf16_f32 v4, v4, v5
	v_cvt_pk_bf16_f32 v5, v6, v7
	global_store_dwordx2 v[38:39], v[20:21], off offset:32
	v_mul_f32 v20, v36, v32
	v_mul_f32 v21, v36, v33
	v_mul_f32 v22, v36, v34
	v_mul_f32 v23, v36, v35
	global_store_dwordx2 v[38:39], v[4:5], off offset:96
	v_mul_f32 v4, v36, v16
	v_mul_f32 v5, v36, v17
	v_mul_f32 v6, v36, v18
	v_mul_f32 v7, v36, v19
	v_cvt_pk_bf16_f32 v20, v20, v21
	v_cvt_pk_bf16_f32 v21, v22, v23
	v_cvt_pk_bf16_f32 v4, v4, v5
	v_cvt_pk_bf16_f32 v5, v6, v7
	global_store_dwordx2 v[38:39], v[20:21], off offset:48
	global_store_dwordx2 v[38:39], v[4:5], off offset:112
	s_branch .LBB0_887

.LBB0_1019:
	s_andn2_b64 vcc, exec, s[36:37]
	s_ashr_i32 s9, s8, 31
	s_cbranch_vccnz .LBB0_1024
	v_mul_f32 v174, v146, v146
	v_mul_f32 v175, v147, v147
	v_mul_f32 v176, v144, v144
	v_mul_f32 v177, v145, v145
	s_nop 0
	v_pk_mov_b32 v[180:181], v[176:177], v[174:175] op_sel:[1,0]
	v_mov_b32_e32 v177, v175
	v_add_f32 v174, v180, v176
	v_add_f32 v175, v181, v177
	v_mul_f32 v176, v140, v140
	v_mul_f32 v177, v141, v141
	v_add_f32 v182, v174, v174
	v_add_f32 v183, v174, v175
	v_mul_f32 v174, v142, v142
	v_mul_f32 v175, v143, v143
	s_nop 0
	v_pk_mov_b32 v[180:181], v[176:177], v[174:175] op_sel:[1,0]
	v_mov_b32_e32 v177, v175
	v_add_f32 v174, v180, v176
	v_add_f32 v175, v181, v177
	v_mov_b32_e32 v176, v137
	v_mov_b32_e32 v177, v133
	v_add_f32 v184, v174, v174
	v_add_f32 v185, v174, v175
	v_mov_b32_e32 v174, v136
	v_mov_b32_e32 v175, v132
	v_mul_f32 v176, v176, v176
	v_mul_f32 v177, v177, v177
	v_mov_b32_e32 v180, v139
	v_mov_b32_e32 v181, v135
	v_fma_f32 v174, v174, v174, v176
	v_fma_f32 v175, v175, v175, v177
	v_mov_b32_e32 v176, v138
	v_mov_b32_e32 v177, v134
	v_mul_f32 v180, v180, v180
	v_mul_f32 v181, v181, v181
	v_mov_b32_e32 v193, v185
	v_fma_f32 v176, v176, v176, v180
	v_fma_f32 v177, v177, v177, v181
	s_waitcnt vmcnt(0)
	v_and_b32_e32 v180, 0xffff0000, v162
	v_add_f32 v174, v174, v176
	v_add_f32 v175, v175, v177
	v_lshlrev_b32_e32 v176, 16, v161
	v_add_f32 v186, v174, v174
	v_add_f32 v187, v174, v175
	v_lshlrev_b32_e32 v174, 16, v160
	v_and_b32_e32 v175, 0xffff0000, v160
	v_mul_f32_e32 v160, v174, v174
	v_fma_f32 v188, v174, v174, v160
	v_fma_f32 v189, v175, v175, v160
	v_and_b32_e32 v177, 0xffff0000, v161
	v_mul_f32_e32 v160, v176, v176
	v_fma_f32 v190, v176, v176, v160
	v_fma_f32 v191, v177, v177, v160
	v_lshlrev_b32_e32 v160, 16, v162
	v_mov_b32_e32 v161, v183
	v_mov_b32_e32 v192, v160
	v_lshlrev_b32_e32 v162, 16, v163
	v_and_b32_e32 v163, 0xffff0000, v163
	v_mul_f32 v192, v160, v192
	v_mul_f32 v193, v161, v193
	v_add_f32 v182, v182, v184
	v_add_f32 v183, v183, v185
	v_mul_f32_e32 v186, v180, v180
	v_mul_f32_e32 v188, v162, v162
	v_mul_f32_e32 v190, v163, v163
	v_mov_b32_e32 v193, v183
	v_add_f32 v182, v192, v186
	v_add_f32 v183, v193, v187
	v_add_f32 v184, v188, v190
	v_add_f32 v185, v189, v191
	v_and_b32_e32 v181, 64, v236
	v_add_f32 v182, v182, v184
	v_add_f32 v183, v183, v185
	v_add_u32_e32 v181, 64, v181
	v_add_f32_e32 v161, v182, v183
	ds_swizzle_b32 v178, v161 offset:swizzle(SWAP,16)
	s_waitcnt lgkmcnt(0)
	v_add_f32_e32 v161, v161, v178
	v_xor_b32_e32 v178, 32, v236
	v_cmp_lt_i32_e32 vcc, v178, v181
	s_nop 1
	v_cndmask_b32_e32 v178, v236, v178, vcc
	v_lshlrev_b32_e32 v178, 2, v178
	ds_bpermute_b32 v178, v178, v161
	s_waitcnt lgkmcnt(0)
	v_add_f32_e32 v161, v161, v178
	v_fmamk_f32 v161, v161, 0x3c2aaaab, v231
	v_mul_f32_e32 v178, 0x4b800000, v161
	v_cmp_gt_f32_e32 vcc, s11, v161
	s_nop 1
	v_cndmask_b32_e32 v161, v161, v178, vcc
	v_rsq_f32_e32 v161, v161
	s_nop 0
	v_mul_f32_e32 v178, 0x45800000, v161
	v_cndmask_b32_e32 v178, v161, v178, vcc
	s_and_saveexec_b64 s[18:19], s[16:17]
	s_cbranch_execz .LBB0_1022
	v_mad_u64_u32 v[182:183], s[36:37], v172, 48, s[26:27]
	v_mov_b32_e32 v184, v183
	v_mad_u64_u32 v[184:185], s[36:37], v173, 48, v[184:185]
	v_mov_b32_e32 v183, v184
	v_lshl_add_u64 v[182:183], s[8:9], 2, v[182:183]
	global_store_dword v[182:183], v178, off
.LBB0_1022:
	s_or_b64 exec, exec, s[18:19]
	s_and_b64 vcc, exec, s[20:21]
	s_cbranch_vccnz .LBB0_1024
	v_mad_u64_u32 v[182:183], s[18:19], v172, 12, s[8:9]
	v_mov_b64_e32 v[186:187], s[22:23]
	v_mov_b32_e32 v184, v183
	v_mad_u64_u32 v[182:183], s[18:19], v182, s77, v[186:187]
	v_mad_u64_u32 v[184:185], s[18:19], v173, 12, v[184:185]
	v_mov_b32_e32 v186, v183
	v_mad_u64_u32 v[184:185], s[18:19], v184, s77, v[186:187]
	v_mov_b32_e32 v183, v184
	v_lshlrev_b32_e32 v184, 1, v179
	v_mov_b32_e32 v185, v2
	v_lshl_add_u64 v[182:183], v[182:183], 0, v[184:185]
	v_mul_f32 v146, v146, v178
	v_mul_f32 v147, v147, v178
	v_mul_f32 v144, v144, v178
	v_mul_f32 v145, v145, v178
	v_mul_f32 v184, v142, v178
	v_mul_f32 v185, v143, v178
	v_mul_f32 v142, v140, v178
	v_mul_f32 v143, v141, v178
	v_cvt_pk_bf16_f32 v140, v144, v145
	v_cvt_pk_bf16_f32 v141, v146, v147
	v_cvt_pk_bf16_f32 v142, v142, v143
	v_cvt_pk_bf16_f32 v143, v184, v185
	global_store_dwordx4 v[182:183], v[140:143], off
	v_mul_f32 v138, v138, v178
	v_mul_f32 v139, v139, v178
	v_mul_f32 v136, v136, v178
	v_mul_f32 v137, v137, v178
	v_mul_f32 v140, v134, v178
	v_mul_f32 v141, v135, v178
	v_mul_f32 v134, v132, v178
	v_mul_f32 v135, v133, v178
	v_cvt_pk_bf16_f32 v132, v136, v137
	v_cvt_pk_bf16_f32 v133, v138, v139
	v_cvt_pk_bf16_f32 v134, v134, v135
	v_cvt_pk_bf16_f32 v135, v140, v141
	v_mov_b32_e32 v161, v180
	global_store_dwordx4 v[182:183], v[132:135], off offset:64
	v_mul_f32 v136, v162, v178
	v_mul_f32 v137, v163, v178
	v_mul_f32 v138, v160, v178
	v_mul_f32 v139, v161, v178
	v_mul_f32 v134, v178, v176
	v_mul_f32 v135, v178, v177
	v_mul_f32 v132, v178, v174
	v_mul_f32 v133, v178, v175
	v_cvt_pk_bf16_f32 v132, v132, v133
	v_cvt_pk_bf16_f32 v133, v134, v135
	v_cvt_pk_bf16_f32 v134, v138, v139
	v_cvt_pk_bf16_f32 v135, v136, v137
	global_store_dwordx4 v[182:183], v[132:135], off offset:128

.LBB0_1028:
	s_andn2_b64 vcc, exec, s[0:1]
	s_cbranch_vccnz .LBB0_1033
	v_mul_f32 v132, v126, v126
	v_mul_f32 v133, v127, v127
	v_mul_f32 v134, v124, v124
	v_mul_f32 v135, v125, v125
	s_waitcnt vmcnt(0)
	v_and_b32_e32 v142, 0xffff0000, v158
	v_pk_mov_b32 v[136:137], v[134:135], v[132:133] op_sel:[1,0]
	v_mov_b32_e32 v135, v133
	v_add_f32 v132, v136, v134
	v_add_f32 v133, v137, v135
	v_mul_f32 v134, v120, v120
	v_mul_f32 v135, v121, v121
	v_add_f32 v144, v132, v132
	v_add_f32 v145, v132, v133
	v_mul_f32 v132, v122, v122
	v_mul_f32 v133, v123, v123
	v_lshlrev_b32_e32 v138, 16, v159
	v_pk_mov_b32 v[136:137], v[134:135], v[132:133] op_sel:[1,0]
	v_mov_b32_e32 v135, v133
	v_add_f32 v132, v136, v134
	v_add_f32 v133, v137, v135
	v_mov_b32_e32 v134, v117
	v_mov_b32_e32 v135, v113
	v_add_f32 v146, v132, v132
	v_add_f32 v147, v132, v133
	v_mov_b32_e32 v132, v116
	v_mov_b32_e32 v133, v112
	v_mul_f32 v134, v134, v134
	v_mul_f32 v135, v135, v135
	v_mov_b32_e32 v136, v119
	v_mov_b32_e32 v137, v115
	v_fma_f32 v132, v132, v132, v134
	v_fma_f32 v133, v133, v133, v135
	v_mov_b32_e32 v134, v118
	v_mov_b32_e32 v135, v114
	v_mul_f32 v136, v136, v136
	v_mul_f32 v137, v137, v137
	v_and_b32_e32 v139, 0xffff0000, v159
	v_fma_f32 v134, v134, v134, v136
	v_fma_f32 v135, v135, v135, v137
	v_lshlrev_b32_e32 v136, 16, v157
	v_add_f32 v132, v132, v134
	v_add_f32 v133, v133, v135
	v_and_b32_e32 v137, 0xffff0000, v157
	v_add_f32 v160, v132, v132
	v_add_f32 v161, v132, v133
	v_lshlrev_b32_e32 v132, 16, v156
	v_and_b32_e32 v133, 0xffff0000, v156
	v_mul_f32_e32 v134, v132, v132
	v_fma_f32 v162, v132, v132, v134
	v_fma_f32 v163, v133, v133, v134
	v_mul_f32_e32 v134, v136, v136
	v_fma_f32 v156, v136, v136, v134
	v_fma_f32 v157, v137, v137, v134
	v_lshlrev_b32_e32 v134, 16, v158
	v_mov_b32_e32 v135, v145
	v_mov_b32_e32 v158, v134
	v_mov_b32_e32 v159, v147
	v_mul_f32 v158, v134, v158
	v_mul_f32 v159, v135, v159
	v_add_f32 v144, v144, v146
	v_add_f32 v145, v145, v147
	v_mul_f32_e32 v160, v142, v142
	v_mul_f32_e32 v162, v138, v138
	v_mul_f32_e32 v156, v139, v139
	v_mov_b32_e32 v159, v145
	v_add_f32 v144, v158, v160
	v_add_f32 v145, v159, v161
	v_add_f32 v146, v162, v156
	v_add_f32 v147, v163, v157
	v_and_b32_e32 v143, 64, v236
	v_add_f32 v144, v144, v146
	v_add_f32 v145, v145, v147
	v_add_u32_e32 v143, 64, v143
	v_add_f32_e32 v135, v144, v145
	ds_swizzle_b32 v140, v135 offset:swizzle(SWAP,16)
	s_waitcnt lgkmcnt(0)
	v_add_f32_e32 v135, v135, v140
	v_xor_b32_e32 v140, 32, v236
	v_cmp_lt_i32_e32 vcc, v140, v143
	s_nop 1
	v_cndmask_b32_e32 v140, v236, v140, vcc
	v_lshlrev_b32_e32 v140, 2, v140
	ds_bpermute_b32 v140, v140, v135
	s_waitcnt lgkmcnt(0)
	v_add_f32_e32 v135, v135, v140
	v_fmamk_f32 v135, v135, 0x3c2aaaab, v231
	v_mul_f32_e32 v140, 0x4b800000, v135
	v_cmp_gt_f32_e32 vcc, s11, v135
	s_nop 1
	v_cndmask_b32_e32 v135, v135, v140, vcc
	v_rsq_f32_e32 v135, v135
	s_nop 0
	v_mul_f32_e32 v140, 0x45800000, v135
	v_cndmask_b32_e32 v140, v135, v140, vcc
	s_and_saveexec_b64 s[0:1], s[16:17]
	s_cbranch_execz .LBB0_1031
	v_mad_u64_u32 v[144:145], s[36:37], v141, 48, s[26:27]
	v_mov_b32_e32 v146, v145
	v_mad_u64_u32 v[146:147], s[36:37], v173, 48, v[146:147]
	v_mov_b32_e32 v145, v146
	v_lshl_add_u64 v[144:145], s[8:9], 2, v[144:145]
	global_store_dword v[144:145], v140, off
.LBB0_1031:
	s_or_b64 exec, exec, s[0:1]
	s_and_b64 vcc, exec, s[20:21]
	s_cbranch_vccnz .LBB0_1033
	v_mad_u64_u32 v[144:145], s[0:1], v141, 12, s[8:9]
	v_mov_b64_e32 v[156:157], s[22:23]
	v_mov_b32_e32 v146, v145
	v_mad_u64_u32 v[144:145], s[0:1], v144, s77, v[156:157]
	v_mad_u64_u32 v[146:147], s[0:1], v173, 12, v[146:147]
	v_mov_b32_e32 v156, v145
	v_mad_u64_u32 v[146:147], s[0:1], v146, s77, v[156:157]
	v_mov_b32_e32 v145, v146
	v_lshlrev_b32_e32 v146, 1, v179
	v_mov_b32_e32 v147, v2
	v_lshl_add_u64 v[144:145], v[144:145], 0, v[146:147]
	v_mul_f32 v126, v126, v140
	v_mul_f32 v127, v127, v140
	v_mul_f32 v124, v124, v140
	v_mul_f32 v125, v125, v140
	v_mul_f32 v146, v122, v140
	v_mul_f32 v147, v123, v140
	v_mul_f32 v122, v120, v140
	v_mul_f32 v123, v121, v140
	v_cvt_pk_bf16_f32 v120, v124, v125
	v_cvt_pk_bf16_f32 v121, v126, v127
	v_cvt_pk_bf16_f32 v122, v122, v123
	v_cvt_pk_bf16_f32 v123, v146, v147
	global_store_dwordx4 v[144:145], v[120:123], off
	v_mul_f32 v118, v118, v140
	v_mul_f32 v119, v119, v140
	v_mul_f32 v116, v116, v140
	v_mul_f32 v117, v117, v140
	v_mul_f32 v120, v114, v140
	v_mul_f32 v121, v115, v140
	v_mul_f32 v114, v112, v140
	v_mul_f32 v115, v113, v140
	v_cvt_pk_bf16_f32 v112, v116, v117
	v_cvt_pk_bf16_f32 v113, v118, v119
	v_cvt_pk_bf16_f32 v114, v114, v115
	v_cvt_pk_bf16_f32 v115, v120, v121
	v_mov_b32_e32 v135, v142
	global_store_dwordx4 v[144:145], v[112:115], off offset:64
	v_mul_f32 v116, v138, v140
	v_mul_f32 v117, v139, v140
	v_mul_f32 v118, v134, v140
	v_mul_f32 v119, v135, v140
	v_mul_f32 v114, v140, v136
	v_mul_f32 v115, v140, v137
	v_mul_f32 v112, v140, v132
	v_mul_f32 v113, v140, v133
	v_cvt_pk_bf16_f32 v112, v112, v113
	v_cvt_pk_bf16_f32 v113, v114, v115
	v_cvt_pk_bf16_f32 v114, v118, v119
	v_cvt_pk_bf16_f32 v115, v116, v117
	global_store_dwordx4 v[144:145], v[112:115], off offset:128

.LBB0_1037:
	s_andn2_b64 vcc, exec, s[0:1]
	s_cbranch_vccnz .LBB0_1042
	v_mul_f32 v112, v106, v106
	v_mul_f32 v113, v107, v107
	v_mul_f32 v114, v104, v104
	v_mul_f32 v115, v105, v105
	s_waitcnt vmcnt(0)
	v_and_b32_e32 v122, 0xffff0000, v154
	v_pk_mov_b32 v[116:117], v[114:115], v[112:113] op_sel:[1,0]
	v_mov_b32_e32 v115, v113
	v_add_f32 v112, v116, v114
	v_add_f32 v113, v117, v115
	v_mul_f32 v114, v100, v100
	v_mul_f32 v115, v101, v101
	v_add_f32 v124, v112, v112
	v_add_f32 v125, v112, v113
	v_mul_f32 v112, v102, v102
	v_mul_f32 v113, v103, v103
	v_lshlrev_b32_e32 v118, 16, v155
	v_pk_mov_b32 v[116:117], v[114:115], v[112:113] op_sel:[1,0]
	v_mov_b32_e32 v115, v113
	v_add_f32 v112, v116, v114
	v_add_f32 v113, v117, v115
	v_mov_b32_e32 v114, v97
	v_mov_b32_e32 v115, v93
	v_add_f32 v126, v112, v112
	v_add_f32 v127, v112, v113
	v_mov_b32_e32 v112, v96
	v_mov_b32_e32 v113, v92
	v_mul_f32 v114, v114, v114
	v_mul_f32 v115, v115, v115
	v_mov_b32_e32 v116, v99
	v_mov_b32_e32 v117, v95
	v_fma_f32 v112, v112, v112, v114
	v_fma_f32 v113, v113, v113, v115
	v_mov_b32_e32 v114, v98
	v_mov_b32_e32 v115, v94
	v_mul_f32 v116, v116, v116
	v_mul_f32 v117, v117, v117
	v_mov_b32_e32 v139, v127
	v_fma_f32 v114, v114, v114, v116
	v_fma_f32 v115, v115, v115, v117
	v_lshlrev_b32_e32 v116, 16, v153
	v_add_f32 v112, v112, v114
	v_add_f32 v113, v113, v115
	v_and_b32_e32 v117, 0xffff0000, v153
	v_add_f32 v132, v112, v112
	v_add_f32 v133, v112, v113
	v_lshlrev_b32_e32 v112, 16, v152
	v_and_b32_e32 v113, 0xffff0000, v152
	v_mul_f32_e32 v114, v112, v112
	v_fma_f32 v134, v112, v112, v114
	v_fma_f32 v135, v113, v113, v114
	v_mul_f32_e32 v114, v116, v116
	v_fma_f32 v136, v116, v116, v114
	v_fma_f32 v137, v117, v117, v114
	v_lshlrev_b32_e32 v114, 16, v154
	v_mov_b32_e32 v115, v125
	v_mov_b32_e32 v138, v114
	v_and_b32_e32 v119, 0xffff0000, v155
	v_mul_f32 v138, v114, v138
	v_mul_f32 v139, v115, v139
	v_add_f32 v124, v124, v126
	v_add_f32 v125, v125, v127
	v_mul_f32_e32 v132, v122, v122
	v_mul_f32_e32 v134, v118, v118
	v_mul_f32_e32 v136, v119, v119
	v_mov_b32_e32 v139, v125
	v_add_f32 v124, v138, v132
	v_add_f32 v125, v139, v133
	v_add_f32 v126, v134, v136
	v_add_f32 v127, v135, v137
	v_and_b32_e32 v123, 64, v236
	v_add_f32 v124, v124, v126
	v_add_f32 v125, v125, v127
	v_add_u32_e32 v123, 64, v123
	v_add_f32_e32 v115, v124, v125
	ds_swizzle_b32 v120, v115 offset:swizzle(SWAP,16)
	s_waitcnt lgkmcnt(0)
	v_add_f32_e32 v115, v115, v120
	v_xor_b32_e32 v120, 32, v236
	v_cmp_lt_i32_e32 vcc, v120, v123
	s_nop 1
	v_cndmask_b32_e32 v120, v236, v120, vcc
	v_lshlrev_b32_e32 v120, 2, v120
	ds_bpermute_b32 v120, v120, v115
	s_waitcnt lgkmcnt(0)
	v_add_f32_e32 v115, v115, v120
	v_fmamk_f32 v115, v115, 0x3c2aaaab, v231
	v_mul_f32_e32 v120, 0x4b800000, v115
	v_cmp_gt_f32_e32 vcc, s11, v115
	s_nop 1
	v_cndmask_b32_e32 v115, v115, v120, vcc
	v_rsq_f32_e32 v115, v115
	s_nop 0
	v_mul_f32_e32 v120, 0x45800000, v115
	v_cndmask_b32_e32 v120, v115, v120, vcc
	s_and_saveexec_b64 s[0:1], s[16:17]
	s_cbranch_execz .LBB0_1040
	v_mad_u64_u32 v[124:125], s[36:37], v121, 48, s[26:27]
	v_mov_b32_e32 v126, v125
	v_mad_u64_u32 v[126:127], s[36:37], v173, 48, v[126:127]
	v_mov_b32_e32 v125, v126
	v_lshl_add_u64 v[124:125], s[8:9], 2, v[124:125]
	global_store_dword v[124:125], v120, off
.LBB0_1040:
	s_or_b64 exec, exec, s[0:1]
	s_and_b64 vcc, exec, s[20:21]
	s_cbranch_vccnz .LBB0_1042
	v_mad_u64_u32 v[124:125], s[0:1], v121, 12, s[8:9]
	v_mov_b64_e32 v[132:133], s[22:23]
	v_mov_b32_e32 v126, v125
	v_mad_u64_u32 v[124:125], s[0:1], v124, s77, v[132:133]
	v_mad_u64_u32 v[126:127], s[0:1], v173, 12, v[126:127]
	v_mov_b32_e32 v132, v125
	v_mad_u64_u32 v[126:127], s[0:1], v126, s77, v[132:133]
	v_mov_b32_e32 v125, v126
	v_lshlrev_b32_e32 v126, 1, v179
	v_mov_b32_e32 v127, v2
	v_lshl_add_u64 v[124:125], v[124:125], 0, v[126:127]
	v_mul_f32 v106, v106, v120
	v_mul_f32 v107, v107, v120
	v_mul_f32 v104, v104, v120
	v_mul_f32 v105, v105, v120
	v_mul_f32 v126, v102, v120
	v_mul_f32 v127, v103, v120
	v_mul_f32 v102, v100, v120
	v_mul_f32 v103, v101, v120
	v_cvt_pk_bf16_f32 v100, v104, v105
	v_cvt_pk_bf16_f32 v101, v106, v107
	v_cvt_pk_bf16_f32 v102, v102, v103
	v_cvt_pk_bf16_f32 v103, v126, v127
	global_store_dwordx4 v[124:125], v[100:103], off
	v_mul_f32 v98, v98, v120
	v_mul_f32 v99, v99, v120
	v_mul_f32 v96, v96, v120
	v_mul_f32 v97, v97, v120
	v_mul_f32 v100, v94, v120
	v_mul_f32 v101, v95, v120
	v_mul_f32 v94, v92, v120
	v_mul_f32 v95, v93, v120
	v_cvt_pk_bf16_f32 v92, v96, v97
	v_cvt_pk_bf16_f32 v93, v98, v99
	v_cvt_pk_bf16_f32 v94, v94, v95
	v_cvt_pk_bf16_f32 v95, v100, v101
	v_mov_b32_e32 v115, v122
	global_store_dwordx4 v[124:125], v[92:95], off offset:64
	v_mul_f32 v96, v118, v120
	v_mul_f32 v97, v119, v120
	v_mul_f32 v98, v114, v120
	v_mul_f32 v99, v115, v120
	v_mul_f32 v94, v120, v116
	v_mul_f32 v95, v120, v117
	v_mul_f32 v92, v120, v112
	v_mul_f32 v93, v120, v113
	v_cvt_pk_bf16_f32 v92, v92, v93
	v_cvt_pk_bf16_f32 v93, v94, v95
	v_cvt_pk_bf16_f32 v94, v98, v99
	v_cvt_pk_bf16_f32 v95, v96, v97
	global_store_dwordx4 v[124:125], v[92:95], off offset:128

.LBB0_1046:
	s_andn2_b64 vcc, exec, s[0:1]
	s_cbranch_vccnz .LBB0_1051
	v_mul_f32 v92, v86, v86
	v_mul_f32 v93, v87, v87
	v_mul_f32 v94, v84, v84
	v_mul_f32 v95, v85, v85
	s_waitcnt vmcnt(0)
	v_and_b32_e32 v102, 0xffff0000, v150
	v_pk_mov_b32 v[96:97], v[94:95], v[92:93] op_sel:[1,0]
	v_mov_b32_e32 v95, v93
	v_add_f32 v92, v96, v94
	v_add_f32 v93, v97, v95
	v_mul_f32 v94, v80, v80
	v_mul_f32 v95, v81, v81
	v_add_f32 v104, v92, v92
	v_add_f32 v105, v92, v93
	v_mul_f32 v92, v82, v82
	v_mul_f32 v93, v83, v83
	v_lshlrev_b32_e32 v98, 16, v151
	v_pk_mov_b32 v[96:97], v[94:95], v[92:93] op_sel:[1,0]
	v_mov_b32_e32 v95, v93
	v_add_f32 v92, v96, v94
	v_add_f32 v93, v97, v95
	v_mov_b32_e32 v94, v77
	v_mov_b32_e32 v95, v73
	v_add_f32 v106, v92, v92
	v_add_f32 v107, v92, v93
	v_mov_b32_e32 v92, v76
	v_mov_b32_e32 v93, v72
	v_mul_f32 v94, v94, v94
	v_mul_f32 v95, v95, v95
	v_mov_b32_e32 v96, v79
	v_mov_b32_e32 v97, v75
	v_fma_f32 v92, v92, v92, v94
	v_fma_f32 v93, v93, v93, v95
	v_mov_b32_e32 v94, v78
	v_mov_b32_e32 v95, v74
	v_mul_f32 v96, v96, v96
	v_mul_f32 v97, v97, v97
	v_mov_b32_e32 v119, v107
	v_fma_f32 v94, v94, v94, v96
	v_fma_f32 v95, v95, v95, v97
	v_lshlrev_b32_e32 v96, 16, v149
	v_add_f32 v92, v92, v94
	v_add_f32 v93, v93, v95
	v_and_b32_e32 v97, 0xffff0000, v149
	v_add_f32 v112, v92, v92
	v_add_f32 v113, v92, v93
	v_lshlrev_b32_e32 v92, 16, v148
	v_and_b32_e32 v93, 0xffff0000, v148
	v_mul_f32_e32 v94, v92, v92
	v_fma_f32 v114, v92, v92, v94
	v_fma_f32 v115, v93, v93, v94
	v_mul_f32_e32 v94, v96, v96
	v_fma_f32 v116, v96, v96, v94
	v_fma_f32 v117, v97, v97, v94
	v_lshlrev_b32_e32 v94, 16, v150
	v_mov_b32_e32 v95, v105
	v_mov_b32_e32 v118, v94
	v_and_b32_e32 v99, 0xffff0000, v151
	v_mul_f32 v118, v94, v118
	v_mul_f32 v119, v95, v119
	v_add_f32 v104, v104, v106
	v_add_f32 v105, v105, v107
	v_mul_f32_e32 v112, v102, v102
	v_mul_f32_e32 v114, v98, v98
	v_mul_f32_e32 v116, v99, v99
	v_mov_b32_e32 v119, v105
	v_add_f32 v104, v118, v112
	v_add_f32 v105, v119, v113
	v_add_f32 v106, v114, v116
	v_add_f32 v107, v115, v117
	v_and_b32_e32 v103, 64, v236
	v_add_f32 v104, v104, v106
	v_add_f32 v105, v105, v107
	v_add_u32_e32 v103, 64, v103
	v_add_f32_e32 v95, v104, v105
	ds_swizzle_b32 v100, v95 offset:swizzle(SWAP,16)
	s_waitcnt lgkmcnt(0)
	v_add_f32_e32 v95, v95, v100
	v_xor_b32_e32 v100, 32, v236
	v_cmp_lt_i32_e32 vcc, v100, v103
	s_nop 1
	v_cndmask_b32_e32 v100, v236, v100, vcc
	v_lshlrev_b32_e32 v100, 2, v100
	ds_bpermute_b32 v100, v100, v95
	s_waitcnt lgkmcnt(0)
	v_add_f32_e32 v95, v95, v100
	v_fmamk_f32 v95, v95, 0x3c2aaaab, v231
	v_mul_f32_e32 v100, 0x4b800000, v95
	v_cmp_gt_f32_e32 vcc, s11, v95
	s_nop 1
	v_cndmask_b32_e32 v95, v95, v100, vcc
	v_rsq_f32_e32 v95, v95
	s_nop 0
	v_mul_f32_e32 v100, 0x45800000, v95
	v_cndmask_b32_e32 v100, v95, v100, vcc
	s_and_saveexec_b64 s[0:1], s[16:17]
	s_cbranch_execz .LBB0_1049
	v_mad_u64_u32 v[104:105], s[36:37], v101, 48, s[26:27]
	v_mov_b32_e32 v106, v105
	v_mad_u64_u32 v[106:107], s[36:37], v173, 48, v[106:107]
	v_mov_b32_e32 v105, v106
	v_lshl_add_u64 v[104:105], s[8:9], 2, v[104:105]
	global_store_dword v[104:105], v100, off
.LBB0_1049:
	s_or_b64 exec, exec, s[0:1]
	s_and_b64 vcc, exec, s[20:21]
	s_cbranch_vccnz .LBB0_1051
	v_mad_u64_u32 v[104:105], s[0:1], v101, 12, s[8:9]
	v_mov_b64_e32 v[112:113], s[22:23]
	v_mov_b32_e32 v106, v105
	v_mad_u64_u32 v[104:105], s[0:1], v104, s77, v[112:113]
	v_mad_u64_u32 v[106:107], s[0:1], v173, 12, v[106:107]
	v_mov_b32_e32 v112, v105
	v_mad_u64_u32 v[106:107], s[0:1], v106, s77, v[112:113]
	v_mov_b32_e32 v105, v106
	v_lshlrev_b32_e32 v106, 1, v179
	v_mov_b32_e32 v107, v2
	v_lshl_add_u64 v[104:105], v[104:105], 0, v[106:107]
	v_mul_f32 v86, v86, v100
	v_mul_f32 v87, v87, v100
	v_mul_f32 v84, v84, v100
	v_mul_f32 v85, v85, v100
	v_mul_f32 v106, v82, v100
	v_mul_f32 v107, v83, v100
	v_mul_f32 v82, v80, v100
	v_mul_f32 v83, v81, v100
	v_cvt_pk_bf16_f32 v80, v84, v85
	v_cvt_pk_bf16_f32 v81, v86, v87
	v_cvt_pk_bf16_f32 v82, v82, v83
	v_cvt_pk_bf16_f32 v83, v106, v107
	global_store_dwordx4 v[104:105], v[80:83], off
	v_mul_f32 v78, v78, v100
	v_mul_f32 v79, v79, v100
	v_mul_f32 v76, v76, v100
	v_mul_f32 v77, v77, v100
	v_mul_f32 v80, v74, v100
	v_mul_f32 v81, v75, v100
	v_mul_f32 v74, v72, v100
	v_mul_f32 v75, v73, v100
	v_cvt_pk_bf16_f32 v72, v76, v77
	v_cvt_pk_bf16_f32 v73, v78, v79
	v_cvt_pk_bf16_f32 v74, v74, v75
	v_cvt_pk_bf16_f32 v75, v80, v81
	v_mov_b32_e32 v95, v102
	global_store_dwordx4 v[104:105], v[72:75], off offset:64
	v_mul_f32 v76, v98, v100
	v_mul_f32 v77, v99, v100
	v_mul_f32 v78, v94, v100
	v_mul_f32 v79, v95, v100
	v_mul_f32 v74, v100, v96
	v_mul_f32 v75, v100, v97
	v_mul_f32 v72, v100, v92
	v_mul_f32 v73, v100, v93
	v_cvt_pk_bf16_f32 v72, v72, v73
	v_cvt_pk_bf16_f32 v73, v74, v75
	v_cvt_pk_bf16_f32 v74, v78, v79
	v_cvt_pk_bf16_f32 v75, v76, v77
	global_store_dwordx4 v[104:105], v[72:75], off offset:128

.LBB0_1055:
	s_andn2_b64 vcc, exec, s[0:1]
	s_cbranch_vccnz .LBB0_1061
	v_mul_f32 v74, v66, v66
	v_mul_f32 v75, v67, v67
	v_mul_f32 v76, v64, v64
	v_mul_f32 v77, v65, v65
	s_waitcnt vmcnt(0)
	v_and_b32_e32 v83, 0xffff0000, v130
	v_pk_mov_b32 v[78:79], v[76:77], v[74:75] op_sel:[1,0]
	v_mov_b32_e32 v77, v75
	v_add_f32 v74, v78, v76
	v_add_f32 v75, v79, v77
	v_mul_f32 v76, v60, v60
	v_mul_f32 v77, v61, v61
	v_add_f32 v84, v74, v74
	v_add_f32 v85, v74, v75
	v_mul_f32 v74, v62, v62
	v_mul_f32 v75, v63, v63
	v_lshlrev_b32_e32 v80, 16, v131
	v_pk_mov_b32 v[78:79], v[76:77], v[74:75] op_sel:[1,0]
	v_mov_b32_e32 v77, v75
	v_add_f32 v74, v78, v76
	v_add_f32 v75, v79, v77
	v_mov_b32_e32 v76, v57
	v_mov_b32_e32 v77, v53
	v_add_f32 v86, v74, v74
	v_add_f32 v87, v74, v75
	v_mov_b32_e32 v74, v56
	v_mov_b32_e32 v75, v52
	v_mul_f32 v76, v76, v76
	v_mul_f32 v77, v77, v77
	v_mov_b32_e32 v78, v59
	v_mov_b32_e32 v79, v55
	v_fma_f32 v74, v74, v74, v76
	v_fma_f32 v75, v75, v75, v77
	v_mov_b32_e32 v76, v58
	v_mov_b32_e32 v77, v54
	v_mul_f32 v78, v78, v78
	v_mul_f32 v79, v79, v79
	v_mov_b32_e32 v99, v87
	v_fma_f32 v76, v76, v76, v78
	v_fma_f32 v77, v77, v77, v79
	v_lshlrev_b32_e32 v78, 16, v129
	v_add_f32 v74, v74, v76
	v_add_f32 v75, v75, v77
	v_and_b32_e32 v79, 0xffff0000, v129
	v_add_f32 v92, v74, v74
	v_add_f32 v93, v74, v75
	v_lshlrev_b32_e32 v74, 16, v128
	v_and_b32_e32 v75, 0xffff0000, v128
	v_mul_f32_e32 v76, v74, v74
	v_fma_f32 v94, v74, v74, v76
	v_fma_f32 v95, v75, v75, v76
	v_mul_f32_e32 v76, v78, v78
	v_fma_f32 v96, v78, v78, v76
	v_fma_f32 v97, v79, v79, v76
	v_lshlrev_b32_e32 v76, 16, v130
	v_mov_b32_e32 v77, v85
	v_mov_b32_e32 v98, v76
	v_and_b32_e32 v81, 0xffff0000, v131
	v_mul_f32 v98, v76, v98
	v_mul_f32 v99, v77, v99
	v_add_f32 v84, v84, v86
	v_add_f32 v85, v85, v87
	v_mul_f32_e32 v92, v83, v83
	v_mul_f32_e32 v94, v80, v80
	v_mul_f32_e32 v96, v81, v81
	v_mov_b32_e32 v99, v85
	v_add_f32 v84, v98, v92
	v_add_f32 v85, v99, v93
	v_add_f32 v86, v94, v96
	v_add_f32 v87, v95, v97
	s_nop 0
	v_add_f32 v84, v84, v86
	v_add_f32 v85, v85, v87
	s_nop 0
	v_add_f32_e32 v77, v84, v85
	ds_swizzle_b32 v82, v77 offset:swizzle(SWAP,16)
	v_and_b32_e32 v84, 64, v236
	v_add_u32_e32 v84, 64, v84
	s_waitcnt lgkmcnt(0)
	v_add_f32_e32 v77, v77, v82
	v_xor_b32_e32 v82, 32, v236
	v_cmp_lt_i32_e32 vcc, v82, v84
	s_nop 1
	v_cndmask_b32_e32 v82, v236, v82, vcc
	v_lshlrev_b32_e32 v82, 2, v82
	ds_bpermute_b32 v82, v82, v77
	s_waitcnt lgkmcnt(0)
	v_add_f32_e32 v77, v77, v82
	v_fmamk_f32 v77, v77, 0x3c2aaaab, v231
	v_mul_f32_e32 v82, 0x4b800000, v77
	v_cmp_gt_f32_e32 vcc, s11, v77
	s_nop 1
	v_cndmask_b32_e32 v77, v77, v82, vcc
	v_rsq_f32_e32 v77, v77
	s_nop 0
	v_mul_f32_e32 v82, 0x45800000, v77
	v_cndmask_b32_e32 v82, v77, v82, vcc
	s_and_saveexec_b64 s[0:1], s[16:17]
	s_cbranch_execz .LBB0_1058
	v_mad_u64_u32 v[84:85], s[20:21], v72, 48, s[26:27]
	v_mov_b32_e32 v86, v85
	v_mad_u64_u32 v[86:87], s[20:21], v73, 48, v[86:87]
	v_mov_b32_e32 v85, v86
	v_lshl_add_u64 v[84:85], s[8:9], 2, v[84:85]
	global_store_dword v[84:85], v82, off
.LBB0_1058:
	s_or_b64 exec, exec, s[0:1]
	s_mov_b64 s[0:1], 0x4000
	v_cmp_gt_u64_e32 vcc, s[0:1], v[72:73]
	s_and_saveexec_b64 s[0:1], vcc
	s_cbranch_execz .LBB0_1060
	v_mad_u64_u32 v[84:85], s[20:21], v72, 12, s[8:9]
	v_mov_b64_e32 v[86:87], s[22:23]
	v_mov_b32_e32 v72, v85
	v_mad_u64_u32 v[84:85], s[20:21], v84, s77, v[86:87]
	v_mad_u64_u32 v[72:73], s[20:21], v73, 12, v[72:73]
	v_mov_b32_e32 v86, v85
	v_mad_u64_u32 v[72:73], s[20:21], v72, s77, v[86:87]
	v_mov_b32_e32 v85, v72
	v_lshlrev_b32_e32 v72, 1, v179
	v_mov_b32_e32 v73, v2
	v_lshl_add_u64 v[72:73], v[84:85], 0, v[72:73]
	v_mul_f32 v66, v66, v82
	v_mul_f32 v67, v67, v82
	v_mul_f32 v64, v64, v82
	v_mul_f32 v65, v65, v82
	v_mul_f32 v84, v62, v82
	v_mul_f32 v85, v63, v82
	v_mul_f32 v62, v60, v82
	v_mul_f32 v63, v61, v82
	v_cvt_pk_bf16_f32 v60, v64, v65
	v_cvt_pk_bf16_f32 v61, v66, v67
	v_cvt_pk_bf16_f32 v62, v62, v63
	v_cvt_pk_bf16_f32 v63, v84, v85
	global_store_dwordx4 v[72:73], v[60:63], off
	v_mul_f32 v58, v58, v82
	v_mul_f32 v59, v59, v82
	v_mul_f32 v56, v56, v82
	v_mul_f32 v57, v57, v82
	v_mul_f32 v60, v54, v82
	v_mul_f32 v61, v55, v82
	v_mul_f32 v54, v52, v82
	v_mul_f32 v55, v53, v82
	v_cvt_pk_bf16_f32 v52, v56, v57
	v_cvt_pk_bf16_f32 v53, v58, v59
	v_cvt_pk_bf16_f32 v54, v54, v55
	v_cvt_pk_bf16_f32 v55, v60, v61
	v_mov_b32_e32 v77, v83
	global_store_dwordx4 v[72:73], v[52:55], off offset:64
	v_mul_f32 v56, v80, v82
	v_mul_f32 v57, v81, v82
	v_mul_f32 v58, v76, v82
	v_mul_f32 v59, v77, v82
	v_mul_f32 v54, v82, v78
	v_mul_f32 v55, v82, v79
	v_mul_f32 v52, v82, v74
	v_mul_f32 v53, v82, v75
	v_cvt_pk_bf16_f32 v52, v52, v53
	v_cvt_pk_bf16_f32 v53, v54, v55
	v_cvt_pk_bf16_f32 v54, v58, v59
	v_cvt_pk_bf16_f32 v55, v56, v57
	global_store_dwordx4 v[72:73], v[52:55], off offset:128

.LBB0_1065:
	s_andn2_b64 vcc, exec, s[0:1]
	s_cbranch_vccnz .LBB0_1071
	v_mul_f32 v54, v50, v50
	v_mul_f32 v55, v51, v51
	v_mul_f32 v56, v48, v48
	v_mul_f32 v57, v49, v49
	s_waitcnt vmcnt(0)
	v_and_b32_e32 v63, 0xffff0000, v110
	v_pk_mov_b32 v[58:59], v[56:57], v[54:55] op_sel:[1,0]
	v_mov_b32_e32 v57, v55
	v_add_f32 v54, v58, v56
	v_add_f32 v55, v59, v57
	v_mul_f32 v56, v44, v44
	v_mul_f32 v57, v45, v45
	v_add_f32 v64, v54, v54
	v_add_f32 v65, v54, v55
	v_mul_f32 v54, v46, v46
	v_mul_f32 v55, v47, v47
	v_lshlrev_b32_e32 v60, 16, v111
	v_pk_mov_b32 v[58:59], v[56:57], v[54:55] op_sel:[1,0]
	v_mov_b32_e32 v57, v55
	v_add_f32 v54, v58, v56
	v_add_f32 v55, v59, v57
	v_mov_b32_e32 v56, v41
	v_mov_b32_e32 v57, v37
	v_add_f32 v66, v54, v54
	v_add_f32 v67, v54, v55
	v_mov_b32_e32 v54, v40
	v_mov_b32_e32 v55, v36
	v_mul_f32 v56, v56, v56
	v_mul_f32 v57, v57, v57
	v_mov_b32_e32 v58, v43
	v_mov_b32_e32 v59, v39
	v_fma_f32 v54, v54, v54, v56
	v_fma_f32 v55, v55, v55, v57
	v_mov_b32_e32 v56, v42
	v_mov_b32_e32 v57, v38
	v_mul_f32 v58, v58, v58
	v_mul_f32 v59, v59, v59
	v_mov_b32_e32 v79, v67
	v_fma_f32 v56, v56, v56, v58
	v_fma_f32 v57, v57, v57, v59
	v_lshlrev_b32_e32 v58, 16, v109
	v_add_f32 v54, v54, v56
	v_add_f32 v55, v55, v57
	v_and_b32_e32 v59, 0xffff0000, v109
	v_add_f32 v72, v54, v54
	v_add_f32 v73, v54, v55
	v_lshlrev_b32_e32 v54, 16, v108
	v_and_b32_e32 v55, 0xffff0000, v108
	v_mul_f32_e32 v56, v54, v54
	v_fma_f32 v74, v54, v54, v56
	v_fma_f32 v75, v55, v55, v56
	v_mul_f32_e32 v56, v58, v58
	v_fma_f32 v76, v58, v58, v56
	v_fma_f32 v77, v59, v59, v56
	v_lshlrev_b32_e32 v56, 16, v110
	v_mov_b32_e32 v57, v65
	v_mov_b32_e32 v78, v56
	v_and_b32_e32 v61, 0xffff0000, v111
	v_mul_f32 v78, v56, v78
	v_mul_f32 v79, v57, v79
	v_add_f32 v64, v64, v66
	v_add_f32 v65, v65, v67
	v_mul_f32_e32 v72, v63, v63
	v_mul_f32_e32 v74, v60, v60
	v_mul_f32_e32 v76, v61, v61
	v_mov_b32_e32 v79, v65
	v_add_f32 v64, v78, v72
	v_add_f32 v65, v79, v73
	v_add_f32 v66, v74, v76
	v_add_f32 v67, v75, v77
	s_nop 0
	v_add_f32 v64, v64, v66
	v_add_f32 v65, v65, v67
	s_nop 0
	v_add_f32_e32 v57, v64, v65
	ds_swizzle_b32 v62, v57 offset:swizzle(SWAP,16)
	v_and_b32_e32 v64, 64, v236
	v_add_u32_e32 v64, 64, v64
	s_waitcnt lgkmcnt(0)
	v_add_f32_e32 v57, v57, v62
	v_xor_b32_e32 v62, 32, v236
	v_cmp_lt_i32_e32 vcc, v62, v64
	s_nop 1
	v_cndmask_b32_e32 v62, v236, v62, vcc
	v_lshlrev_b32_e32 v62, 2, v62
	ds_bpermute_b32 v62, v62, v57
	s_waitcnt lgkmcnt(0)
	v_add_f32_e32 v57, v57, v62
	v_fmamk_f32 v57, v57, 0x3c2aaaab, v231
	v_mul_f32_e32 v62, 0x4b800000, v57
	v_cmp_gt_f32_e32 vcc, s11, v57
	s_nop 1
	v_cndmask_b32_e32 v57, v57, v62, vcc
	v_rsq_f32_e32 v57, v57
	s_nop 0
	v_mul_f32_e32 v62, 0x45800000, v57
	v_cndmask_b32_e32 v62, v57, v62, vcc
	s_and_saveexec_b64 s[0:1], s[16:17]
	s_cbranch_execz .LBB0_1068
	v_mad_u64_u32 v[64:65], s[20:21], v52, 48, s[26:27]
	v_mov_b32_e32 v66, v65
	v_mad_u64_u32 v[66:67], s[20:21], v53, 48, v[66:67]
	v_mov_b32_e32 v65, v66
	v_lshl_add_u64 v[64:65], s[8:9], 2, v[64:65]
	global_store_dword v[64:65], v62, off
.LBB0_1068:
	s_or_b64 exec, exec, s[0:1]
	s_mov_b64 s[0:1], 0x4000
	v_cmp_gt_u64_e32 vcc, s[0:1], v[52:53]
	s_and_saveexec_b64 s[0:1], vcc
	s_cbranch_execz .LBB0_1070
	v_mad_u64_u32 v[64:65], s[20:21], v52, 12, s[8:9]
	v_mov_b64_e32 v[66:67], s[22:23]
	v_mov_b32_e32 v52, v65
	v_mad_u64_u32 v[64:65], s[20:21], v64, s77, v[66:67]
	v_mad_u64_u32 v[52:53], s[20:21], v53, 12, v[52:53]
	v_mov_b32_e32 v66, v65
	v_mad_u64_u32 v[52:53], s[20:21], v52, s77, v[66:67]
	v_mov_b32_e32 v65, v52
	v_lshlrev_b32_e32 v52, 1, v179
	v_mov_b32_e32 v53, v2
	v_lshl_add_u64 v[52:53], v[64:65], 0, v[52:53]
	v_mul_f32 v50, v50, v62
	v_mul_f32 v51, v51, v62
	v_mul_f32 v48, v48, v62
	v_mul_f32 v49, v49, v62
	v_mul_f32 v64, v46, v62
	v_mul_f32 v65, v47, v62
	v_mul_f32 v46, v44, v62
	v_mul_f32 v47, v45, v62
	v_cvt_pk_bf16_f32 v44, v48, v49
	v_cvt_pk_bf16_f32 v45, v50, v51
	v_cvt_pk_bf16_f32 v46, v46, v47
	v_cvt_pk_bf16_f32 v47, v64, v65
	global_store_dwordx4 v[52:53], v[44:47], off
	v_mul_f32 v42, v42, v62
	v_mul_f32 v43, v43, v62
	v_mul_f32 v40, v40, v62
	v_mul_f32 v41, v41, v62
	v_mul_f32 v44, v38, v62
	v_mul_f32 v45, v39, v62
	v_mul_f32 v38, v36, v62
	v_mul_f32 v39, v37, v62
	v_cvt_pk_bf16_f32 v36, v40, v41
	v_cvt_pk_bf16_f32 v37, v42, v43
	v_cvt_pk_bf16_f32 v38, v38, v39
	v_cvt_pk_bf16_f32 v39, v44, v45
	v_mov_b32_e32 v57, v63
	global_store_dwordx4 v[52:53], v[36:39], off offset:64
	v_mul_f32 v40, v60, v62
	v_mul_f32 v41, v61, v62
	v_mul_f32 v42, v56, v62
	v_mul_f32 v43, v57, v62
	v_mul_f32 v38, v62, v58
	v_mul_f32 v39, v62, v59
	v_mul_f32 v36, v62, v54
	v_mul_f32 v37, v62, v55
	v_cvt_pk_bf16_f32 v36, v36, v37
	v_cvt_pk_bf16_f32 v37, v38, v39
	v_cvt_pk_bf16_f32 v38, v42, v43
	v_cvt_pk_bf16_f32 v39, v40, v41
	global_store_dwordx4 v[52:53], v[36:39], off offset:128

.LBB0_1075:
	s_andn2_b64 vcc, exec, s[0:1]
	s_cbranch_vccnz .LBB0_1081
	v_mul_f32 v38, v34, v34
	v_mul_f32 v39, v35, v35
	v_mul_f32 v40, v32, v32
	v_mul_f32 v41, v33, v33
	s_waitcnt vmcnt(0)
	v_and_b32_e32 v47, 0xffff0000, v90
	v_pk_mov_b32 v[42:43], v[40:41], v[38:39] op_sel:[1,0]
	v_mov_b32_e32 v41, v39
	v_add_f32 v38, v42, v40
	v_add_f32 v39, v43, v41
	v_mul_f32 v40, v28, v28
	v_mul_f32 v41, v29, v29
	v_add_f32 v48, v38, v38
	v_add_f32 v49, v38, v39
	v_mul_f32 v38, v30, v30
	v_mul_f32 v39, v31, v31
	v_lshlrev_b32_e32 v44, 16, v91
	v_pk_mov_b32 v[42:43], v[40:41], v[38:39] op_sel:[1,0]
	v_mov_b32_e32 v41, v39
	v_add_f32 v38, v42, v40
	v_add_f32 v39, v43, v41
	v_mov_b32_e32 v40, v25
	v_mov_b32_e32 v41, v21
	v_add_f32 v50, v38, v38
	v_add_f32 v51, v38, v39
	v_mov_b32_e32 v38, v24
	v_mov_b32_e32 v39, v20
	v_mul_f32 v40, v40, v40
	v_mul_f32 v41, v41, v41
	v_mov_b32_e32 v42, v27
	v_mov_b32_e32 v43, v23
	v_fma_f32 v38, v38, v38, v40
	v_fma_f32 v39, v39, v39, v41
	v_mov_b32_e32 v40, v26
	v_mov_b32_e32 v41, v22
	v_mul_f32 v42, v42, v42
	v_mul_f32 v43, v43, v43
	v_mov_b32_e32 v59, v51
	v_fma_f32 v40, v40, v40, v42
	v_fma_f32 v41, v41, v41, v43
	v_lshlrev_b32_e32 v42, 16, v89
	v_add_f32 v38, v38, v40
	v_add_f32 v39, v39, v41
	v_and_b32_e32 v43, 0xffff0000, v89
	v_add_f32 v52, v38, v38
	v_add_f32 v53, v38, v39
	v_lshlrev_b32_e32 v38, 16, v88
	v_and_b32_e32 v39, 0xffff0000, v88
	v_mul_f32_e32 v40, v38, v38
	v_fma_f32 v54, v38, v38, v40
	v_fma_f32 v55, v39, v39, v40
	v_mul_f32_e32 v40, v42, v42
	v_fma_f32 v56, v42, v42, v40
	v_fma_f32 v57, v43, v43, v40
	v_lshlrev_b32_e32 v40, 16, v90
	v_mov_b32_e32 v41, v49
	v_mov_b32_e32 v58, v40
	v_and_b32_e32 v45, 0xffff0000, v91
	v_mul_f32 v58, v40, v58
	v_mul_f32 v59, v41, v59
	v_add_f32 v48, v48, v50
	v_add_f32 v49, v49, v51
	v_mul_f32_e32 v52, v47, v47
	v_mul_f32_e32 v54, v44, v44
	v_mul_f32_e32 v56, v45, v45
	v_mov_b32_e32 v59, v49
	v_add_f32 v48, v58, v52
	v_add_f32 v49, v59, v53
	v_add_f32 v50, v54, v56
	v_add_f32 v51, v55, v57
	s_nop 0
	v_add_f32 v48, v48, v50
	v_add_f32 v49, v49, v51
	s_nop 0
	v_add_f32_e32 v41, v48, v49
	ds_swizzle_b32 v46, v41 offset:swizzle(SWAP,16)
	v_and_b32_e32 v48, 64, v236
	v_add_u32_e32 v48, 64, v48
	s_waitcnt lgkmcnt(0)
	v_add_f32_e32 v41, v41, v46
	v_xor_b32_e32 v46, 32, v236
	v_cmp_lt_i32_e32 vcc, v46, v48
	s_nop 1
	v_cndmask_b32_e32 v46, v236, v46, vcc
	v_lshlrev_b32_e32 v46, 2, v46
	ds_bpermute_b32 v46, v46, v41
	s_waitcnt lgkmcnt(0)
	v_add_f32_e32 v41, v41, v46
	v_fmamk_f32 v41, v41, 0x3c2aaaab, v231
	v_mul_f32_e32 v46, 0x4b800000, v41
	v_cmp_gt_f32_e32 vcc, s11, v41
	s_nop 1
	v_cndmask_b32_e32 v41, v41, v46, vcc
	v_rsq_f32_e32 v41, v41
	s_nop 0
	v_mul_f32_e32 v46, 0x45800000, v41
	v_cndmask_b32_e32 v46, v41, v46, vcc
	s_and_saveexec_b64 s[0:1], s[16:17]
	s_cbranch_execz .LBB0_1078
	v_mad_u64_u32 v[48:49], s[20:21], v36, 48, s[26:27]
	v_mov_b32_e32 v50, v49
	v_mad_u64_u32 v[50:51], s[20:21], v37, 48, v[50:51]
	v_mov_b32_e32 v49, v50
	v_lshl_add_u64 v[48:49], s[8:9], 2, v[48:49]
	global_store_dword v[48:49], v46, off
.LBB0_1078:
	s_or_b64 exec, exec, s[0:1]
	s_mov_b64 s[0:1], 0x4000
	v_cmp_gt_u64_e32 vcc, s[0:1], v[36:37]
	s_and_saveexec_b64 s[0:1], vcc
	s_cbranch_execz .LBB0_1080
	v_mad_u64_u32 v[48:49], s[20:21], v36, 12, s[8:9]
	v_mov_b64_e32 v[50:51], s[22:23]
	v_mov_b32_e32 v36, v49
	v_mad_u64_u32 v[48:49], s[20:21], v48, s77, v[50:51]
	v_mad_u64_u32 v[36:37], s[20:21], v37, 12, v[36:37]
	v_mov_b32_e32 v50, v49
	v_mad_u64_u32 v[36:37], s[20:21], v36, s77, v[50:51]
	v_mov_b32_e32 v49, v36
	v_lshlrev_b32_e32 v36, 1, v179
	v_mov_b32_e32 v37, v2
	v_lshl_add_u64 v[36:37], v[48:49], 0, v[36:37]
	v_mul_f32 v34, v34, v46
	v_mul_f32 v35, v35, v46
	v_mul_f32 v32, v32, v46
	v_mul_f32 v33, v33, v46
	v_mul_f32 v48, v30, v46
	v_mul_f32 v49, v31, v46
	v_mul_f32 v30, v28, v46
	v_mul_f32 v31, v29, v46
	v_cvt_pk_bf16_f32 v28, v32, v33
	v_cvt_pk_bf16_f32 v29, v34, v35
	v_cvt_pk_bf16_f32 v30, v30, v31
	v_cvt_pk_bf16_f32 v31, v48, v49
	global_store_dwordx4 v[36:37], v[28:31], off
	v_mul_f32 v26, v26, v46
	v_mul_f32 v27, v27, v46
	v_mul_f32 v24, v24, v46
	v_mul_f32 v25, v25, v46
	v_mul_f32 v28, v22, v46
	v_mul_f32 v29, v23, v46
	v_mul_f32 v22, v20, v46
	v_mul_f32 v23, v21, v46
	v_cvt_pk_bf16_f32 v20, v24, v25
	v_cvt_pk_bf16_f32 v21, v26, v27
	v_cvt_pk_bf16_f32 v22, v22, v23
	v_cvt_pk_bf16_f32 v23, v28, v29
	v_mov_b32_e32 v41, v47
	global_store_dwordx4 v[36:37], v[20:23], off offset:64
	v_mul_f32 v24, v44, v46
	v_mul_f32 v25, v45, v46
	v_mul_f32 v26, v40, v46
	v_mul_f32 v27, v41, v46
	v_mul_f32 v22, v46, v42
	v_mul_f32 v23, v46, v43
	v_mul_f32 v20, v46, v38
	v_mul_f32 v21, v46, v39
	v_cvt_pk_bf16_f32 v20, v20, v21
	v_cvt_pk_bf16_f32 v21, v22, v23
	v_cvt_pk_bf16_f32 v22, v26, v27
	v_cvt_pk_bf16_f32 v23, v24, v25
	global_store_dwordx4 v[36:37], v[20:23], off offset:128

.LBB0_1085:
	s_andn2_b64 vcc, exec, s[0:1]
	s_cbranch_vccnz .LBB0_1002
	v_mul_f32 v22, v18, v18
	v_mul_f32 v23, v19, v19
	v_mul_f32 v24, v16, v16
	v_mul_f32 v25, v17, v17
	s_waitcnt vmcnt(0)
	v_and_b32_e32 v31, 0xffff0000, v70
	v_pk_mov_b32 v[26:27], v[24:25], v[22:23] op_sel:[1,0]
	v_mov_b32_e32 v25, v23
	v_add_f32 v22, v26, v24
	v_add_f32 v23, v27, v25
	v_mul_f32 v24, v12, v12
	v_mul_f32 v25, v13, v13
	v_add_f32 v32, v22, v22
	v_add_f32 v33, v22, v23
	v_mul_f32 v22, v14, v14
	v_mul_f32 v23, v15, v15
	v_lshlrev_b32_e32 v28, 16, v71
	v_pk_mov_b32 v[26:27], v[24:25], v[22:23] op_sel:[1,0]
	v_mov_b32_e32 v25, v23
	v_add_f32 v22, v26, v24
	v_add_f32 v23, v27, v25
	v_mov_b32_e32 v24, v9
	v_mov_b32_e32 v25, v5
	v_add_f32 v34, v22, v22
	v_add_f32 v35, v22, v23
	v_mov_b32_e32 v22, v8
	v_mov_b32_e32 v23, v4
	v_mul_f32 v24, v24, v24
	v_mul_f32 v25, v25, v25
	v_mov_b32_e32 v26, v11
	v_mov_b32_e32 v27, v7
	v_fma_f32 v22, v22, v22, v24
	v_fma_f32 v23, v23, v23, v25
	v_mov_b32_e32 v24, v10
	v_mov_b32_e32 v25, v6
	v_mul_f32 v26, v26, v26
	v_mul_f32 v27, v27, v27
	v_mov_b32_e32 v43, v35
	v_fma_f32 v24, v24, v24, v26
	v_fma_f32 v25, v25, v25, v27
	v_lshlrev_b32_e32 v26, 16, v69
	v_add_f32 v22, v22, v24
	v_add_f32 v23, v23, v25
	v_and_b32_e32 v27, 0xffff0000, v69
	v_add_f32 v36, v22, v22
	v_add_f32 v37, v22, v23
	v_lshlrev_b32_e32 v22, 16, v68
	v_and_b32_e32 v23, 0xffff0000, v68
	v_mul_f32_e32 v24, v22, v22
	v_fma_f32 v38, v22, v22, v24
	v_fma_f32 v39, v23, v23, v24
	v_mul_f32_e32 v24, v26, v26
	v_fma_f32 v40, v26, v26, v24
	v_fma_f32 v41, v27, v27, v24
	v_lshlrev_b32_e32 v24, 16, v70
	v_mov_b32_e32 v25, v33
	v_mov_b32_e32 v42, v24
	v_and_b32_e32 v29, 0xffff0000, v71
	v_mul_f32 v42, v24, v42
	v_mul_f32 v43, v25, v43
	v_add_f32 v32, v32, v34
	v_add_f32 v33, v33, v35
	v_mul_f32_e32 v36, v31, v31
	v_mul_f32_e32 v38, v28, v28
	v_mul_f32_e32 v40, v29, v29
	v_mov_b32_e32 v43, v33
	v_add_f32 v32, v42, v36
	v_add_f32 v33, v43, v37
	v_add_f32 v34, v38, v40
	v_add_f32 v35, v39, v41
	s_nop 0
	v_add_f32 v32, v32, v34
	v_add_f32 v33, v33, v35
	s_nop 0
	v_add_f32_e32 v25, v32, v33
	ds_swizzle_b32 v30, v25 offset:swizzle(SWAP,16)
	v_and_b32_e32 v32, 64, v236
	v_add_u32_e32 v32, 64, v32
	s_waitcnt lgkmcnt(0)
	v_add_f32_e32 v25, v25, v30
	v_xor_b32_e32 v30, 32, v236
	v_cmp_lt_i32_e32 vcc, v30, v32
	s_nop 1
	v_cndmask_b32_e32 v30, v236, v30, vcc
	v_lshlrev_b32_e32 v30, 2, v30
	ds_bpermute_b32 v30, v30, v25
	s_waitcnt lgkmcnt(0)
	v_add_f32_e32 v25, v25, v30
	v_fmamk_f32 v25, v25, 0x3c2aaaab, v231
	v_mul_f32_e32 v30, 0x4b800000, v25
	v_cmp_gt_f32_e32 vcc, s11, v25
	s_nop 1
	v_cndmask_b32_e32 v25, v25, v30, vcc
	v_rsq_f32_e32 v25, v25
	s_nop 0
	v_mul_f32_e32 v30, 0x45800000, v25
	v_cndmask_b32_e32 v30, v25, v30, vcc
	s_and_saveexec_b64 s[0:1], s[16:17]
	s_cbranch_execz .LBB0_1088
	v_mad_u64_u32 v[32:33], s[16:17], v20, 48, s[26:27]
	v_mov_b32_e32 v34, v33
	v_mad_u64_u32 v[34:35], s[16:17], v21, 48, v[34:35]
	v_mov_b32_e32 v33, v34
	v_lshl_add_u64 v[32:33], s[8:9], 2, v[32:33]
	global_store_dword v[32:33], v30, off
.LBB0_1088:
	s_or_b64 exec, exec, s[0:1]
	s_mov_b64 s[0:1], 0x4000
	v_cmp_gt_u64_e32 vcc, s[0:1], v[20:21]
	s_and_saveexec_b64 s[0:1], vcc
	s_cbranch_execz .LBB0_1001
	v_mad_u64_u32 v[32:33], s[8:9], v20, 12, s[8:9]
	v_mov_b64_e32 v[34:35], s[22:23]
	v_mov_b32_e32 v20, v33
	v_mad_u64_u32 v[32:33], s[8:9], v32, s77, v[34:35]
	v_mad_u64_u32 v[20:21], s[8:9], v21, 12, v[20:21]
	v_mov_b32_e32 v34, v33
	v_mad_u64_u32 v[20:21], s[8:9], v20, s77, v[34:35]
	v_mov_b32_e32 v33, v20
	v_lshlrev_b32_e32 v20, 1, v179
	v_mov_b32_e32 v21, v2
	v_lshl_add_u64 v[20:21], v[32:33], 0, v[20:21]
	v_mul_f32 v18, v18, v30
	v_mul_f32 v19, v19, v30
	v_mul_f32 v16, v16, v30
	v_mul_f32 v17, v17, v30
	v_mul_f32 v32, v14, v30
	v_mul_f32 v33, v15, v30
	v_mul_f32 v14, v12, v30
	v_mul_f32 v15, v13, v30
	v_cvt_pk_bf16_f32 v12, v16, v17
	v_cvt_pk_bf16_f32 v13, v18, v19
	v_cvt_pk_bf16_f32 v14, v14, v15
	v_cvt_pk_bf16_f32 v15, v32, v33
	global_store_dwordx4 v[20:21], v[12:15], off
	v_mul_f32 v10, v10, v30
	v_mul_f32 v11, v11, v30
	v_mul_f32 v8, v8, v30
	v_mul_f32 v9, v9, v30
	v_mul_f32 v12, v6, v30
	v_mul_f32 v13, v7, v30
	v_mul_f32 v6, v4, v30
	v_mul_f32 v7, v5, v30
	v_cvt_pk_bf16_f32 v4, v8, v9
	v_cvt_pk_bf16_f32 v5, v10, v11
	v_cvt_pk_bf16_f32 v6, v6, v7
	v_cvt_pk_bf16_f32 v7, v12, v13
	v_mov_b32_e32 v25, v31
	global_store_dwordx4 v[20:21], v[4:7], off offset:64
	v_mul_f32 v8, v28, v30
	v_mul_f32 v9, v29, v30
	v_mul_f32 v10, v24, v30
	v_mul_f32 v11, v25, v30
	v_mul_f32 v6, v30, v26
	v_mul_f32 v7, v30, v27
	v_mul_f32 v4, v30, v22
	v_mul_f32 v5, v30, v23
	v_cvt_pk_bf16_f32 v4, v4, v5
	v_cvt_pk_bf16_f32 v5, v6, v7
	v_cvt_pk_bf16_f32 v6, v10, v11
	v_cvt_pk_bf16_f32 v7, v8, v9
	global_store_dwordx4 v[20:21], v[4:7], off offset:128
	s_branch .LBB0_1001

.LBB0_1171:
	s_or_b64 exec, exec, s[20:21]
	v_rsq_f32_e32 v44, v3
	v_lshlrev_b32_e32 v46, 16, v40
	v_and_b32_e32 v47, 0xffff0000, v40
	v_lshlrev_b32_e32 v40, 16, v41
	v_mul_f32_e32 v45, 0x45800000, v44
	v_cndmask_b32_e64 v44, v44, v45, s[22:23]
	v_mul_f32_e32 v44, 0x3e16c740, v44
	v_and_b32_e32 v41, 0xffff0000, v41
	v_mul_f32 v40, v44, v40
	v_mul_f32 v41, v44, v41
	v_cvt_pk_bf16_f32 v131, v40, v41
	v_lshlrev_b32_e32 v40, 16, v42
	v_and_b32_e32 v41, 0xffff0000, v42
	v_mul_f32 v40, v44, v40
	v_mul_f32 v41, v44, v41
	v_cvt_pk_bf16_f32 v132, v40, v41
	v_lshlrev_b32_e32 v40, 16, v43
	v_and_b32_e32 v41, 0xffff0000, v43
	v_mul_f32 v40, v44, v40
	v_mul_f32 v41, v44, v41
	v_cvt_pk_bf16_f32 v133, v40, v41
	v_lshlrev_b32_e32 v40, 16, v36
	v_and_b32_e32 v41, 0xffff0000, v36
	v_lshlrev_b32_e32 v36, 16, v37
	v_and_b32_e32 v37, 0xffff0000, v37
	v_mul_f32 v36, v44, v36
	v_mul_f32 v37, v44, v37
	v_cvt_pk_bf16_f32 v135, v36, v37
	v_lshlrev_b32_e32 v36, 16, v38
	v_and_b32_e32 v37, 0xffff0000, v38
	v_mul_f32 v36, v44, v36
	v_mul_f32 v37, v44, v37
	v_cvt_pk_bf16_f32 v136, v36, v37
	v_lshlrev_b32_e32 v36, 16, v39
	v_and_b32_e32 v37, 0xffff0000, v39
	v_mul_f32 v36, v44, v36
	v_mul_f32 v37, v44, v37
	v_cvt_pk_bf16_f32 v137, v36, v37
	v_lshlrev_b32_e32 v36, 16, v32
	v_and_b32_e32 v37, 0xffff0000, v32
	v_lshlrev_b32_e32 v32, 16, v33
	v_and_b32_e32 v33, 0xffff0000, v33
	v_mul_f32 v32, v44, v32
	v_mul_f32 v33, v44, v33
	v_cvt_pk_bf16_f32 v139, v32, v33
	v_lshlrev_b32_e32 v32, 16, v34
	v_and_b32_e32 v33, 0xffff0000, v34
	v_mul_f32 v32, v44, v32
	v_mul_f32 v33, v44, v33
	v_cvt_pk_bf16_f32 v140, v32, v33
	v_lshlrev_b32_e32 v32, 16, v35
	v_and_b32_e32 v33, 0xffff0000, v35
	v_mul_f32 v32, v44, v32
	v_mul_f32 v33, v44, v33
	v_cvt_pk_bf16_f32 v141, v32, v33
	v_lshlrev_b32_e32 v32, 16, v28
	v_and_b32_e32 v33, 0xffff0000, v28
	v_lshlrev_b32_e32 v28, 16, v29
	v_and_b32_e32 v29, 0xffff0000, v29
	v_mul_f32 v28, v44, v28
	v_mul_f32 v29, v44, v29
	v_cvt_pk_bf16_f32 v143, v28, v29
	v_lshlrev_b32_e32 v28, 16, v30
	v_and_b32_e32 v29, 0xffff0000, v30
	v_mul_f32 v28, v44, v28
	v_mul_f32 v29, v44, v29
	v_cvt_pk_bf16_f32 v144, v28, v29
	v_lshlrev_b32_e32 v28, 16, v31
	v_and_b32_e32 v29, 0xffff0000, v31
	v_mul_f32 v28, v44, v28
	v_mul_f32 v29, v44, v29
	v_cvt_pk_bf16_f32 v145, v28, v29
	v_lshlrev_b32_e32 v28, 16, v24
	v_and_b32_e32 v29, 0xffff0000, v24
	v_lshlrev_b32_e32 v24, 16, v25
	v_and_b32_e32 v25, 0xffff0000, v25
	v_mul_f32 v28, v44, v28
	v_mul_f32 v29, v44, v29
	v_mul_f32 v24, v44, v24
	v_mul_f32 v25, v44, v25
	v_cvt_pk_bf16_f32 v28, v28, v29
	v_cvt_pk_bf16_f32 v29, v24, v25
	v_lshlrev_b32_e32 v24, 16, v26
	v_and_b32_e32 v25, 0xffff0000, v26
	v_mul_f32 v24, v44, v24
	v_mul_f32 v25, v44, v25
	v_cvt_pk_bf16_f32 v26, v24, v25
	v_lshlrev_b32_e32 v24, 16, v27
	v_and_b32_e32 v25, 0xffff0000, v27
	v_mul_f32 v24, v44, v24
	v_mul_f32 v25, v44, v25
	v_cvt_pk_bf16_f32 v27, v24, v25
	v_lshlrev_b32_e32 v24, 16, v20
	v_and_b32_e32 v25, 0xffff0000, v20
	v_lshlrev_b32_e32 v20, 16, v21
	v_and_b32_e32 v21, 0xffff0000, v21
	v_mul_f32 v20, v44, v20
	v_mul_f32 v21, v44, v21
	v_cvt_pk_bf16_f32 v31, v20, v21
	v_lshlrev_b32_e32 v20, 16, v22
	v_and_b32_e32 v21, 0xffff0000, v22
	v_mul_f32 v32, v44, v32
	v_mul_f32 v33, v44, v33
	v_mul_f32 v20, v44, v20
	v_mul_f32 v21, v44, v21
	v_cvt_pk_bf16_f32 v142, v32, v33
	v_cvt_pk_bf16_f32 v33, v20, v21
	v_lshlrev_b32_e32 v20, 16, v23
	v_and_b32_e32 v21, 0xffff0000, v23
	v_mul_f32 v20, v44, v20
	v_mul_f32 v21, v44, v21
	v_cvt_pk_bf16_f32 v35, v20, v21
	v_mul_f32 v40, v44, v40
	v_mul_f32 v41, v44, v41
	v_mul_f32 v24, v44, v24
	v_mul_f32 v25, v44, v25
	v_lshlrev_b32_e32 v32, 16, v33
	v_and_b32_e32 v33, 0xffff0000, v33
	v_lshlrev_b32_e32 v34, 16, v35
	v_and_b32_e32 v35, 0xffff0000, v35
	v_cvt_pk_bf16_f32 v134, v40, v41
	v_cvt_pk_bf16_f32 v30, v24, v25
	v_lshlrev_b32_e32 v24, 16, v26
	v_and_b32_e32 v25, 0xffff0000, v26
	v_lshlrev_b32_e32 v26, 16, v27
	v_and_b32_e32 v27, 0xffff0000, v27
	v_mul_f32 v40, v6, v34
	v_mul_f32 v41, v7, v35
	v_mul_f32 v42, v4, v32
	v_mul_f32 v43, v5, v33
	v_fma_f32 v40, v10, v26, -v40
	v_fma_f32 v41, v11, v27, -v41
	v_fma_f32 v42, v8, v24, -v42
	v_fma_f32 v43, v9, v25, -v43
	v_mul_f32 v10, v10, v34
	v_mul_f32 v11, v11, v35
	v_mul_f32 v8, v8, v32
	v_mul_f32 v9, v9, v33
	v_fma_f32 v6, v6, v26, v10
	v_fma_f32 v7, v7, v27, v11
	v_fma_f32 v4, v4, v24, v8
	v_fma_f32 v5, v5, v25, v9
	v_lshlrev_b32_e32 v3, 3, v61
	v_cvt_pk_bf16_f32 v152, v4, v5
	v_cvt_pk_bf16_f32 v153, v6, v7
	v_add_u32_e32 v6, 64, v1
	v_mov_b64_e32 v[4:5], s[8:9]
	v_add_u32_e32 v171, s25, v53
	v_cmp_lt_i32_e32 vcc, 7, v52
	v_cmp_gt_i32_e64 s[20:21], 8, v52
	v_mad_i64_i32 v[4:5], s[22:23], v6, s71, v[4:5]
	v_lshlrev_b32_e32 v52, 1, v3
	v_mov_b32_e32 v53, v2
	v_lshl_add_u64 v[4:5], v[4:5], 0, v[52:53]
	global_load_dwordx4 v[154:157], v[4:5], off
	v_mul_f32 v36, v44, v36
	v_mul_f32 v37, v44, v37
	v_lshlrev_b32_e32 v20, 16, v28
	v_and_b32_e32 v21, 0xffff0000, v28
	v_lshlrev_b32_e32 v22, 16, v29
	v_and_b32_e32 v23, 0xffff0000, v29
	v_lshlrev_b32_e32 v28, 16, v30
	v_and_b32_e32 v29, 0xffff0000, v30
	v_lshlrev_b32_e32 v30, 16, v31
	v_and_b32_e32 v31, 0xffff0000, v31
	v_cvt_pk_bf16_f32 v138, v36, v37
	v_mul_f32 v36, v18, v30
	v_mul_f32 v37, v19, v31
	v_mul_f32 v38, v16, v28
	v_mul_f32 v39, v17, v29
	v_fma_f32 v36, v14, v22, -v36
	v_fma_f32 v37, v15, v23, -v37
	v_fma_f32 v38, v12, v20, -v38
	v_fma_f32 v39, v13, v21, -v39
	v_mul_f32 v14, v14, v30
	v_mul_f32 v15, v15, v31
	v_mul_f32 v12, v12, v28
	v_mul_f32 v13, v13, v29
	s_movk_i32 s22, 0xffe0
	v_mul_f32 v46, v44, v46
	v_mul_f32 v47, v44, v47
	v_fma_f32 v14, v18, v22, v14
	v_fma_f32 v15, v19, v23, v15
	v_fma_f32 v12, v16, v20, v12
	v_fma_f32 v13, v17, v21, v13
	v_cmp_lt_i32_e64 s[22:23], s22, v171
	v_cvt_pk_bf16_f32 v130, v46, v47
	v_cvt_pk_bf16_f32 v146, v38, v39
	v_cvt_pk_bf16_f32 v147, v36, v37
	v_cvt_pk_bf16_f32 v148, v42, v43
	v_cvt_pk_bf16_f32 v149, v40, v41
	v_cvt_pk_bf16_f32 v150, v12, v13
	v_cvt_pk_bf16_f32 v151, v14, v15
	s_and_b64 s[22:23], s[20:21], s[22:23]
	v_mul_u32_u24_e32 v61, 0xd0, v55
	s_and_saveexec_b64 s[26:27], s[22:23]
	s_xor_b64 s[22:23], exec, s[26:27]
	s_cbranch_execz .LBB0_1173
	v_lshlrev_b32_e32 v50, 4, v56
	v_add3_u32 v3, 0, v61, v50
	ds_read_b128 v[4:7], v3 offset:0
	ds_read_b128 v[8:11], v3 offset:32
	ds_read_b128 v[12:15], v3 offset:64
	ds_read_b128 v[62:65], v3 offset:96
	ds_read_b128 v[66:69], v3 offset:128
	ds_read_b128 v[70:73], v3 offset:160
	ds_read_b128 v[34:37], v3 offset:6656
	ds_read_b128 v[74:77], v3 offset:6688
	ds_read_b128 v[78:81], v3 offset:6720
	ds_read_b128 v[82:85], v3 offset:6752
	ds_read_b128 v[86:89], v3 offset:6784
	ds_read_b128 v[90:93], v3 offset:6816
	s_waitcnt lgkmcnt(0)
	s_nop 0
	v_mfma_f32_32x32x16_bf16 v[18:33], v[4:7], v[130:133], 0
	v_mfma_f32_32x32x16_bf16 v[34:49], v[34:37], v[130:133], 0
	v_mfma_f32_32x32x16_bf16 v[18:33], v[8:11], v[134:137], v[18:33]
	v_mfma_f32_32x32x16_bf16 v[34:49], v[74:77], v[134:137], v[34:49]
	v_mfma_f32_32x32x16_bf16 v[18:33], v[12:15], v[138:141], v[18:33]
	v_mfma_f32_32x32x16_bf16 v[34:49], v[78:81], v[138:141], v[34:49]
	v_mfma_f32_32x32x16_bf16 v[18:33], v[62:65], v[142:145], v[18:33]
	v_mfma_f32_32x32x16_bf16 v[34:49], v[82:85], v[142:145], v[34:49]
	v_mfma_f32_32x32x16_bf16 v[18:33], v[66:69], v[146:149], v[18:33]
	v_mfma_f32_32x32x16_bf16 v[34:49], v[86:89], v[146:149], v[34:49]
	v_mfma_f32_32x32x16_bf16 v[18:33], v[70:73], v[150:153], v[18:33]
	v_mfma_f32_32x32x16_bf16 v[34:49], v[90:93], v[150:153], v[34:49]

.Lpa_A1_resc:
	v_max_f32_e32 v3, v186, v3
	v_sub_f32_e32 v232, v186, v3
	v_exp_f32_e32 v232, v232
	s_nop 0
	v_mul_f32 v80, v80, v232
	v_mul_f32 v81, v81, v232
	v_mul_f32 v78, v78, v232
	v_mul_f32 v79, v79, v232
	v_mul_f32 v76, v76, v232
	v_mul_f32 v77, v77, v232
	v_mul_f32 v74, v74, v232
	v_mul_f32 v75, v75, v232
	v_mul_f32 v72, v72, v232
	v_mul_f32 v73, v73, v232
	v_mul_f32 v70, v70, v232
	v_mul_f32 v71, v71, v232
	v_mul_f32 v68, v68, v232
	v_mul_f32 v69, v69, v232
	v_mul_f32 v66, v66, v232
	v_mul_f32 v67, v67, v232
	v_mul_f32 v64, v64, v232
	v_mul_f32 v65, v65, v232
	v_mul_f32 v62, v62, v232
	v_mul_f32 v63, v63, v232
	v_mul_f32 v60, v60, v232
	v_mul_f32 v61, v61, v232
	v_mul_f32 v58, v58, v232
	v_mul_f32 v59, v59, v232
	v_mul_f32 v56, v56, v232
	v_mul_f32 v57, v57, v232
	v_mul_f32 v54, v54, v232
	v_mul_f32 v55, v55, v232
	v_mul_f32 v52, v52, v232
	v_mul_f32 v53, v53, v232
	v_mul_f32 v50, v50, v232
	v_mul_f32 v51, v51, v232
	s_branch .Lpa_A1_rjoin

.LBB0_1191:
	s_or_b64 exec, exec, s[26:27]
	v_max_f32_e32 v3, v19, v19
	v_max_f32_e32 v4, v18, v18
	v_max_f32_e32 v3, v4, v3
	v_max3_f32 v3, v3, v20, v21
	v_max3_f32 v3, v3, v22, v23
	v_max3_f32 v3, v3, v24, v25
	v_max3_f32 v3, v3, v26, v27
	v_max3_f32 v3, v3, v28, v29
	v_max3_f32 v3, v3, v30, v31
	v_max3_f32 v3, v3, v32, v33
	v_max3_f32 v3, v3, v34, v35
	v_max3_f32 v3, v3, v36, v37
	v_max3_f32 v3, v3, v38, v39
	v_max3_f32 v3, v3, v40, v41
	v_and_b32_e32 v5, 64, v236
	v_max3_f32 v3, v3, v42, v43
	v_xor_b32_e32 v4, 32, v236
	v_add_u32_e32 v5, 64, v5
	v_max3_f32 v3, v3, v44, v45
	v_cmp_lt_i32_e32 vcc, v4, v5
	v_max3_f32 v3, v3, v46, v47
	v_max3_f32 v3, v3, v48, v49
	v_cndmask_b32_e32 v4, v236, v4, vcc
	v_lshlrev_b32_e32 v4, 2, v4
	ds_bpermute_b32 v4, v4, v3
	s_waitcnt lgkmcnt(0)
	v_max3_f32 v3, v186, v3, v4
	v_sub_f32_e32 v4, v186, v3
	v_exp_f32_e32 v4, v4
	s_nop 0
	v_cmp_neq_f32_e32 vcc, 1.0, v4
	s_cbranch_vccz .LBB0_1193
	v_mul_f32 v80, v80, v4
	v_mul_f32 v81, v81, v4
	v_mul_f32 v78, v78, v4
	v_mul_f32 v79, v79, v4
	v_mul_f32 v76, v76, v4
	v_mul_f32 v77, v77, v4
	v_mul_f32 v74, v74, v4
	v_mul_f32 v75, v75, v4
	v_mul_f32 v72, v72, v4
	v_mul_f32 v73, v73, v4
	v_mul_f32 v70, v70, v4
	v_mul_f32 v71, v71, v4
	v_mul_f32 v68, v68, v4
	v_mul_f32 v69, v69, v4
	v_mul_f32 v66, v66, v4
	v_mul_f32 v67, v67, v4
	v_mul_f32 v64, v64, v4
	v_mul_f32 v65, v65, v4
	v_mul_f32 v62, v62, v4
	v_mul_f32 v63, v63, v4
	v_mul_f32 v60, v60, v4
	v_mul_f32 v61, v61, v4
	v_mul_f32 v58, v58, v4
	v_mul_f32 v59, v59, v4
	v_mul_f32 v56, v56, v4
	v_mul_f32 v57, v57, v4
	v_mul_f32 v54, v54, v4
	v_mul_f32 v55, v55, v4
	v_mul_f32 v52, v52, v4
	v_mul_f32 v53, v53, v4
	v_mul_f32 v50, v50, v4
	v_mul_f32 v51, v51, v4

.LBB0_1214:
	s_or_b64 exec, exec, s[84:85]
	v_max_f32_e32 v3, v99, v99
	v_max_f32_e32 v4, v98, v98
	v_max_f32_e32 v3, v4, v3
	v_max3_f32 v3, v3, v100, v101
	v_max3_f32 v3, v3, v102, v103
	v_max3_f32 v3, v3, v104, v105
	v_max3_f32 v3, v3, v106, v107
	v_max3_f32 v3, v3, v108, v109
	v_max3_f32 v3, v3, v110, v111
	v_max3_f32 v3, v3, v112, v113
	v_max3_f32 v3, v3, v82, v83
	v_max3_f32 v3, v3, v84, v85
	v_max3_f32 v3, v3, v86, v87
	v_max3_f32 v3, v3, v88, v89
	v_and_b32_e32 v5, 64, v236
	v_max3_f32 v3, v3, v90, v91
	v_xor_b32_e32 v4, 32, v236
	v_add_u32_e32 v5, 64, v5
	v_max3_f32 v3, v3, v92, v93
	v_cmp_lt_i32_e32 vcc, v4, v5
	v_max3_f32 v3, v3, v94, v95
	v_max3_f32 v3, v3, v96, v97
	v_cndmask_b32_e32 v4, v236, v4, vcc
	v_lshlrev_b32_e32 v4, 2, v4
	ds_bpermute_b32 v4, v4, v3
	s_waitcnt lgkmcnt(0)
	v_max3_f32 v3, v186, v3, v4
	v_sub_f32_e32 v4, v186, v3
	v_exp_f32_e32 v4, v4
	s_nop 0
	v_cmp_neq_f32_e32 vcc, 1.0, v4
	s_cbranch_vccz .LBB0_1216
	v_mul_f32 v80, v80, v4
	v_mul_f32 v81, v81, v4
	v_mul_f32 v78, v78, v4
	v_mul_f32 v79, v79, v4
	v_mul_f32 v76, v76, v4
	v_mul_f32 v77, v77, v4
	v_mul_f32 v74, v74, v4
	v_mul_f32 v75, v75, v4
	v_mul_f32 v72, v72, v4
	v_mul_f32 v73, v73, v4
	v_mul_f32 v70, v70, v4
	v_mul_f32 v71, v71, v4
	v_mul_f32 v68, v68, v4
	v_mul_f32 v69, v69, v4
	v_mul_f32 v66, v66, v4
	v_mul_f32 v67, v67, v4
	v_mul_f32 v64, v64, v4
	v_mul_f32 v65, v65, v4
	v_mul_f32 v62, v62, v4
	v_mul_f32 v63, v63, v4
	v_mul_f32 v60, v60, v4
	v_mul_f32 v61, v61, v4
	v_mul_f32 v58, v58, v4
	v_mul_f32 v59, v59, v4
	v_mul_f32 v56, v56, v4
	v_mul_f32 v57, v57, v4
	v_mul_f32 v54, v54, v4
	v_mul_f32 v55, v55, v4
	v_mul_f32 v52, v52, v4
	v_mul_f32 v53, v53, v4
	v_mul_f32 v50, v50, v4
	v_mul_f32 v51, v51, v4

.LBB0_1236:
	s_and_saveexec_b64 s[0:1], s[20:21]
	s_cbranch_execz .LBB0_1148
	v_and_b32_e32 v3, 64, v236
	v_xor_b32_e32 v1, 32, v236
	v_add_u32_e32 v3, 64, v3
	v_cmp_lt_i32_e32 vcc, v1, v3
	s_nop 1
	v_cndmask_b32_e32 v1, v236, v1, vcc
	v_lshlrev_b32_e32 v1, 2, v1
	ds_bpermute_b32 v1, v1, v185
	s_and_b64 exec, exec, s[14:15]
	s_cbranch_execz .LBB0_1148
	s_lshl_b32 s8, s64, 11
	v_readlane_b32 s9, v255, 29
	s_add_u32 s8, s9, s8
	v_readlane_b32 s9, v255, 33
	s_addc_u32 s9, s9, 0
	s_lshl_b32 s14, s74, 7
	s_waitcnt lgkmcnt(0)
	v_add_f32_e32 v1, v185, v1
	s_add_u32 s8, s8, s14
	v_div_scale_f32 v3, s[14:15], v1, v1, 1.0
	v_rcp_f32_e32 v4, v3
	s_addc_u32 s9, s9, 0
	v_lshlrev_b32_e32 v8, 1, v172
	v_mov_b32_e32 v9, v2
	v_fma_f32 v5, -v3, v4, 1.0
	v_fmac_f32_e32 v4, v5, v4
	v_div_scale_f32 v5, vcc, 1.0, v1, 1.0
	v_mul_f32_e32 v6, v5, v4
	v_fma_f32 v7, -v3, v6, v5
	v_fmac_f32_e32 v6, v7, v4
	v_fma_f32 v3, -v3, v6, v5
	v_div_fmas_f32 v3, v3, v4, v6
	v_lshlrev_b64 v[6:7], 11, v[162:163]
	v_div_fixup_f32 v4, v3, v1, 1.0
	v_lshl_add_u64 v[6:7], s[8:9], 0, v[6:7]
	v_lshl_add_u64 v[6:7], v[6:7], 0, v[8:9]
	v_mul_f32 v8, v66, v4
	v_mul_f32 v9, v67, v4
	v_mul_f32 v10, v68, v4
	v_mul_f32 v11, v69, v4
	v_cvt_pk_bf16_f32 v8, v8, v9
	v_cvt_pk_bf16_f32 v9, v10, v11
	global_store_dwordx2 v[6:7], v[8:9], off
	v_mul_f32 v8, v70, v4
	v_mul_f32 v9, v71, v4
	v_mul_f32 v10, v72, v4
	v_mul_f32 v11, v73, v4
	v_cvt_pk_bf16_f32 v8, v8, v9
	v_cvt_pk_bf16_f32 v9, v10, v11
	global_store_dwordx2 v[6:7], v[8:9], off offset:16
	v_mul_f32 v8, v74, v4
	v_mul_f32 v9, v75, v4
	v_mul_f32 v10, v76, v4
	v_mul_f32 v11, v77, v4
	v_cvt_pk_bf16_f32 v8, v8, v9
	v_cvt_pk_bf16_f32 v9, v10, v11
	global_store_dwordx2 v[6:7], v[8:9], off offset:32
	v_mul_f32 v8, v78, v4
	v_mul_f32 v9, v79, v4
	v_mul_f32 v10, v80, v4
	v_mul_f32 v11, v81, v4
	v_cvt_pk_bf16_f32 v8, v8, v9
	v_cvt_pk_bf16_f32 v9, v10, v11
	global_store_dwordx2 v[6:7], v[8:9], off offset:48
	v_mul_f32 v8, v50, v4
	v_mul_f32 v9, v51, v4
	v_mul_f32 v10, v52, v4
	v_mul_f32 v11, v53, v4
	v_cvt_pk_bf16_f32 v8, v8, v9
	v_cvt_pk_bf16_f32 v9, v10, v11
	global_store_dwordx2 v[6:7], v[8:9], off offset:64
	v_mul_f32 v8, v54, v4
	v_mul_f32 v9, v55, v4
	v_mul_f32 v10, v56, v4
	v_mul_f32 v11, v57, v4
	v_cvt_pk_bf16_f32 v8, v8, v9
	v_cvt_pk_bf16_f32 v9, v10, v11
	global_store_dwordx2 v[6:7], v[8:9], off offset:80
	v_mul_f32 v8, v58, v4
	v_mul_f32 v9, v59, v4
	v_mul_f32 v10, v60, v4
	v_mul_f32 v11, v61, v4
	v_cvt_pk_bf16_f32 v8, v8, v9
	v_cvt_pk_bf16_f32 v9, v10, v11
	global_store_dwordx2 v[6:7], v[8:9], off offset:96
	v_mul_f32 v8, v62, v4
	v_mul_f32 v9, v63, v4
	v_mul_f32 v5, v65, v4
	v_mul_f32 v4, v64, v4
	v_cvt_pk_bf16_f32 v8, v8, v9
	v_cvt_pk_bf16_f32 v9, v4, v5
	global_store_dwordx2 v[6:7], v[8:9], off offset:112
	s_branch .LBB0_1148

.LBB0_1264:
	s_or_b64 exec, exec, s[8:9]
	v_lshlrev_b32_e32 v173, 2, v3
	v_lshlrev_b32_e32 v174, 2, v173
	v_mov_b32_e32 v175, v2
	v_lshl_add_u64 v[12:13], s[0:1], 0, v[174:175]
	v_lshl_add_u64 v[180:181], s[68:69], 2, v[12:13]
	s_mov_b32 s0, 0x10000
	s_waitcnt vmcnt(8)
	v_add_co_u32_e32 v156, vcc, s0, v180
	s_waitcnt vmcnt(7)
	v_mfma_f32_32x32x16_bf16 v[4:19], v[4:7], v[8:11], 0
	v_addc_co_u32_e32 v157, vcc, 0, v181, vcc
	global_load_dwordx4 v[164:167], v[182:183], off offset:224
	s_nop 0
	global_load_dwordx4 v[156:159], v[156:157], off offset:1024
	s_mov_b32 s0, 0x358637bd
	v_and_b32_e32 v160, 0xffffffc0, v1
	v_lshlrev_b32_e32 v161, 1, v178
	v_add3_u32 v168, 0, v160, v161
	s_waitcnt vmcnt(8)
	v_mfma_f32_32x32x16_bf16 v[4:19], v[100:103], v[124:127], v[4:19]
	v_mov_b64_e32 v[100:101], s[0:1]
	s_waitcnt vmcnt(5)
	v_fma_f32 v102, v144, s58, v100
	v_fma_f32 v103, v145, s58, v100
	s_movk_i32 s0, 0x6f00
	v_mul_f32_e32 v124, 0x4b800000, v102
	v_cmp_gt_f32_e32 vcc, s11, v102
	v_mfma_f32_32x32x16_bf16 v[4:19], v[120:123], v[132:135], v[4:19]
	s_nop 0
	v_cndmask_b32_e32 v102, v102, v124, vcc
	v_rsq_f32_e32 v102, v102
	v_mad_u32_u24 v120, v3, s0, v168
	v_mul_f32_e32 v121, 0x45800000, v102
	v_cndmask_b32_e32 v102, v102, v121, vcc
	v_mfma_f32_32x32x16_bf16 v[4:19], v[108:111], v[148:151], v[4:19]
	v_mul_f32_e32 v121, 0x4b800000, v103
	v_cmp_gt_f32_e32 vcc, s11, v103
	v_mul_f32_e32 v102, 0x3e16c740, v102
	v_mov_b32_e32 v108, 0
	v_cndmask_b32_e32 v103, v103, v121, vcc
	s_nop 6
	v_rsq_f32_e32 v8, v103
	v_mov_b32_e32 v109, 0
	v_mul_f32_e32 v4, v102, v4
	v_cvt_pk_bf16_f32 v4, v4, s0
	ds_write_b16 v120, v4
	v_mul_f32_e32 v4, 0x45800000, v8
	v_cndmask_b32_e32 v4, v8, v4, vcc
	v_fma_f32 v8, v146, s58, v100
	v_fma_f32 v9, v147, s58, v100
	v_mul_f32_e32 v4, 0x3e16c740, v4
	v_mul_f32_e32 v10, 0x4b800000, v8
	v_cmp_gt_f32_e32 vcc, s11, v8
	v_mul_f32_e32 v4, v4, v5
	v_cvt_pk_bf16_f32 v4, v4, s0
	v_cndmask_b32_e32 v8, v8, v10, vcc
	v_rsq_f32_e32 v8, v8
	ds_write_b16 v120, v4 offset:7104
	v_mul_f32_e32 v5, 0x4b800000, v9
	v_mov_b32_e32 v100, 0
	v_mul_f32_e32 v4, 0x45800000, v8
	v_cndmask_b32_e32 v4, v8, v4, vcc
	v_cmp_gt_f32_e32 vcc, s11, v9
	v_mul_f32_e32 v4, 0x3e16c740, v4
	v_mul_f32_e32 v4, v4, v6
	v_cndmask_b32_e32 v5, v9, v5, vcc
	v_rsq_f32_e32 v5, v5
	v_cvt_pk_bf16_f32 v4, v4, s0
	ds_write_b16 v120, v4 offset:14208
	v_mov_b32_e32 v110, 0
	v_mul_f32_e32 v4, 0x45800000, v5
	v_cndmask_b32_e32 v4, v5, v4, vcc
	v_mul_f32_e32 v4, 0x3e16c740, v4
	v_mul_f32_e32 v4, v4, v7
	v_cvt_pk_bf16_f32 v4, v4, s0
	v_mov_b32_e32 v111, 0
	ds_write_b16 v120, v4 offset:21312
	s_and_saveexec_b64 s[0:1], s[18:19]
	s_cbranch_execz .LBB0_1266
	global_load_dwordx4 v[108:111], v[184:185], off offset:384

.LBB0_1272:
	s_or_b64 exec, exec, s[0:1]
	s_waitcnt vmcnt(7)
	v_mfma_f32_32x32x16_bf16 v[4:19], v[112:115], v[128:131], 0
	v_add_co_u32_e32 v112, vcc, 0x20000, v180
	s_mov_b32 s0, 0x358637bd
	s_nop 0
	v_addc_co_u32_e32 v113, vcc, 0, v181, vcc
	global_load_dwordx4 v[160:163], v[182:183], off offset:352
	s_nop 0
	global_load_dwordx4 v[112:115], v[112:113], off offset:2048
	v_mul_u32_u24_e32 v3, 0x6f00, v3
	s_waitcnt vmcnt(8)
	v_mfma_f32_32x32x16_bf16 v[4:19], v[104:107], v[140:143], v[4:19]
	v_mov_b64_e32 v[104:105], s[0:1]
	s_waitcnt vmcnt(5)
	v_fma_f32 v106, v156, s58, v104
	v_fma_f32 v107, v157, s58, v104
	v_add_u32_e32 v3, v168, v3
	v_mul_f32_e32 v128, 0x4b800000, v106
	v_cmp_gt_f32_e32 vcc, s11, v106
	v_mfma_f32_32x32x16_bf16 v[4:19], v[136:139], v[152:155], v[4:19]
	s_nop 0
	v_cndmask_b32_e32 v106, v106, v128, vcc
	v_rsq_f32_e32 v106, v106
	s_nop 0
	v_mul_f32_e32 v128, 0x45800000, v106
	v_cndmask_b32_e32 v106, v106, v128, vcc
	v_mfma_f32_32x32x16_bf16 v[4:19], v[116:119], v[164:167], v[4:19]
	v_cmp_gt_f32_e32 vcc, s11, v107
	v_mov_b32_e32 v116, 0
	v_mov_b32_e32 v117, 0
	v_mov_b32_e32 v118, 0
	v_mov_b32_e32 v119, 0
	s_nop 6
	v_mul_f32_e32 v8, 0x3e16c740, v106
	v_mul_f32_e32 v4, v8, v4
	v_mul_f32_e32 v8, 0x4b800000, v107
	v_cndmask_b32_e32 v8, v107, v8, vcc
	v_rsq_f32_e32 v8, v8
	v_cvt_pk_bf16_f32 v4, v4, s0
	ds_write_b16 v3, v4 offset:592
	v_mul_f32_e32 v4, 0x45800000, v8
	v_cndmask_b32_e32 v4, v8, v4, vcc
	v_fma_f32 v8, v158, s58, v104
	v_fma_f32 v9, v159, s58, v104
	v_mul_f32_e32 v4, 0x3e16c740, v4
	v_mul_f32_e32 v10, 0x4b800000, v8
	v_cmp_gt_f32_e32 vcc, s11, v8
	v_mul_f32_e32 v4, v4, v5
	v_cvt_pk_bf16_f32 v4, v4, s0
	v_cndmask_b32_e32 v8, v8, v10, vcc
	v_rsq_f32_e32 v8, v8
	ds_write_b16 v3, v4 offset:7696
	v_mul_f32_e32 v5, 0x4b800000, v9
	v_mov_b32_e32 v104, 0
	v_mul_f32_e32 v4, 0x45800000, v8
	v_cndmask_b32_e32 v4, v8, v4, vcc
	v_cmp_gt_f32_e32 vcc, s11, v9
	v_mul_f32_e32 v4, 0x3e16c740, v4
	v_mul_f32_e32 v4, v4, v6
	v_cndmask_b32_e32 v5, v9, v5, vcc
	v_rsq_f32_e32 v5, v5
	v_cvt_pk_bf16_f32 v4, v4, s0
	ds_write_b16 v3, v4 offset:14800
	v_mul_f32_e32 v4, 0x45800000, v5
	v_cndmask_b32_e32 v4, v5, v4, vcc
	v_mul_f32_e32 v4, 0x3e16c740, v4
	v_mul_f32_e32 v4, v4, v7
	v_cvt_pk_bf16_f32 v4, v4, s0
	ds_write_b16 v3, v4 offset:21904
	s_and_saveexec_b64 s[0:1], s[18:19]
	s_cbranch_execz .LBB0_1274
	global_load_dwordx4 v[116:119], v[184:185], off offset:576

.LBB0_1280:
	s_or_b64 exec, exec, s[0:1]
	s_waitcnt vmcnt(7)
	v_mfma_f32_32x32x16_bf16 v[4:19], v[108:111], v[132:135], 0
	v_add_co_u32_e32 v108, vcc, 0x30000, v180
	s_mov_b32 s0, 0x358637bd
	s_nop 0
	v_addc_co_u32_e32 v109, vcc, 0, v181, vcc
	global_load_dwordx4 v[164:167], v[182:183], off offset:480
	s_nop 0
	global_load_dwordx4 v[108:111], v[108:109], off offset:3072
	s_waitcnt vmcnt(8)
	v_mfma_f32_32x32x16_bf16 v[4:19], v[100:103], v[144:147], v[4:19]
	v_mov_b64_e32 v[100:101], s[0:1]
	s_waitcnt vmcnt(5)
	v_fma_f32 v102, v112, s58, v100
	v_fma_f32 v103, v113, s58, v100
	v_mov_b32_e32 v113, 0
	v_mul_f32_e32 v112, 0x4b800000, v102
	v_cmp_gt_f32_e32 vcc, s11, v102
	v_mfma_f32_32x32x16_bf16 v[4:19], v[124:127], v[148:151], v[4:19]
	s_nop 0
	v_cndmask_b32_e32 v102, v102, v112, vcc
	v_rsq_f32_e32 v102, v102
	s_nop 0
	v_mul_f32_e32 v112, 0x45800000, v102
	v_cndmask_b32_e32 v102, v102, v112, vcc
	v_mfma_f32_32x32x16_bf16 v[4:19], v[120:123], v[160:163], v[4:19]
	v_mul_f32_e32 v112, 0x4b800000, v103
	v_cmp_gt_f32_e32 vcc, s11, v103
	v_mul_f32_e32 v102, 0x3e16c740, v102
	s_nop 0
	v_cndmask_b32_e32 v103, v103, v112, vcc
	s_nop 6
	v_rsq_f32_e32 v8, v103
	v_mov_b32_e32 v112, 0
	v_mul_f32_e32 v4, v102, v4
	v_cvt_pk_bf16_f32 v4, v4, s0
	ds_write_b16 v3, v4 offset:1184
	v_mul_f32_e32 v4, 0x45800000, v8
	v_cndmask_b32_e32 v4, v8, v4, vcc
	v_fma_f32 v8, v114, s58, v100
	v_fma_f32 v9, v115, s58, v100
	v_mul_f32_e32 v4, 0x3e16c740, v4
	v_mul_f32_e32 v10, 0x4b800000, v8
	v_cmp_gt_f32_e32 vcc, s11, v8
	v_mul_f32_e32 v4, v4, v5
	v_cvt_pk_bf16_f32 v4, v4, s0
	v_cndmask_b32_e32 v8, v8, v10, vcc
	v_rsq_f32_e32 v8, v8
	ds_write_b16 v3, v4 offset:8288
	v_mul_f32_e32 v5, 0x4b800000, v9
	v_mov_b32_e32 v100, 0
	v_mul_f32_e32 v4, 0x45800000, v8
	v_cndmask_b32_e32 v4, v8, v4, vcc
	v_cmp_gt_f32_e32 vcc, s11, v9
	v_mul_f32_e32 v4, 0x3e16c740, v4
	v_mul_f32_e32 v4, v4, v6
	v_cndmask_b32_e32 v5, v9, v5, vcc
	v_rsq_f32_e32 v5, v5
	v_cvt_pk_bf16_f32 v4, v4, s0
	ds_write_b16 v3, v4 offset:15392
	v_mov_b32_e32 v114, 0
	v_mul_f32_e32 v4, 0x45800000, v5
	v_cndmask_b32_e32 v4, v5, v4, vcc
	v_mul_f32_e32 v4, 0x3e16c740, v4
	v_mul_f32_e32 v4, v4, v7
	v_cvt_pk_bf16_f32 v4, v4, s0
	v_mov_b32_e32 v115, 0
	ds_write_b16 v3, v4 offset:22496
	s_and_saveexec_b64 s[0:1], s[18:19]
	s_cbranch_execz .LBB0_1282
	global_load_dwordx4 v[112:115], v[184:185], off offset:768

.LBB0_1288:
	s_or_b64 exec, exec, s[0:1]
	s_waitcnt vmcnt(7)
	v_mfma_f32_32x32x16_bf16 v[4:19], v[116:119], v[140:143], 0
	v_add_co_u32_e32 v116, vcc, 0x41000, v180
	s_mov_b32 s0, 0x358637bd
	s_nop 0
	v_addc_co_u32_e32 v117, vcc, 0, v181, vcc
	global_load_dwordx4 v[168:171], v[182:183], off offset:608
	s_nop 0
	global_load_dwordx4 v[116:119], v[116:117], off
	s_waitcnt vmcnt(8)
	v_mfma_f32_32x32x16_bf16 v[4:19], v[104:107], v[152:155], v[4:19]
	v_mov_b64_e32 v[104:105], s[0:1]
	s_waitcnt vmcnt(5)
	v_fma_f32 v106, v108, s58, v104
	v_fma_f32 v107, v109, s58, v104
	v_mov_b32_e32 v109, 0
	v_mul_f32_e32 v108, 0x4b800000, v106
	v_cmp_gt_f32_e32 vcc, s11, v106
	v_mfma_f32_32x32x16_bf16 v[4:19], v[136:139], v[156:159], v[4:19]
	s_nop 0
	v_cndmask_b32_e32 v106, v106, v108, vcc
	v_rsq_f32_e32 v106, v106
	s_nop 0
	v_mul_f32_e32 v108, 0x45800000, v106
	v_cndmask_b32_e32 v106, v106, v108, vcc
	v_mfma_f32_32x32x16_bf16 v[4:19], v[128:131], v[164:167], v[4:19]
	v_mul_f32_e32 v108, 0x4b800000, v107
	v_cmp_gt_f32_e32 vcc, s11, v107
	v_mul_f32_e32 v106, 0x3e16c740, v106
	s_nop 0
	v_cndmask_b32_e32 v107, v107, v108, vcc
	s_nop 6
	v_rsq_f32_e32 v8, v107
	v_mov_b32_e32 v108, 0
	v_mul_f32_e32 v4, v106, v4
	v_cvt_pk_bf16_f32 v4, v4, s0
	ds_write_b16 v3, v4 offset:1776
	v_mul_f32_e32 v4, 0x45800000, v8
	v_cndmask_b32_e32 v4, v8, v4, vcc
	v_fma_f32 v8, v110, s58, v104
	v_fma_f32 v9, v111, s58, v104
	v_mul_f32_e32 v4, 0x3e16c740, v4
	v_mul_f32_e32 v10, 0x4b800000, v8
	v_cmp_gt_f32_e32 vcc, s11, v8
	v_mul_f32_e32 v4, v4, v5
	v_cvt_pk_bf16_f32 v4, v4, s0
	v_cndmask_b32_e32 v8, v8, v10, vcc
	v_rsq_f32_e32 v8, v8
	ds_write_b16 v3, v4 offset:8880
	v_mul_f32_e32 v5, 0x4b800000, v9
	v_mov_b32_e32 v104, 0
	v_mul_f32_e32 v4, 0x45800000, v8
	v_cndmask_b32_e32 v4, v8, v4, vcc
	v_cmp_gt_f32_e32 vcc, s11, v9
	v_mul_f32_e32 v4, 0x3e16c740, v4
	v_mul_f32_e32 v4, v4, v6
	v_cndmask_b32_e32 v5, v9, v5, vcc
	v_rsq_f32_e32 v5, v5
	v_cvt_pk_bf16_f32 v4, v4, s0
	ds_write_b16 v3, v4 offset:15984
	v_mov_b32_e32 v110, 0
	v_mul_f32_e32 v4, 0x45800000, v5
	v_cndmask_b32_e32 v4, v5, v4, vcc
	v_mul_f32_e32 v4, 0x3e16c740, v4
	v_mul_f32_e32 v4, v4, v7
	v_cvt_pk_bf16_f32 v4, v4, s0
	v_mov_b32_e32 v111, 0
	ds_write_b16 v3, v4 offset:23088
	s_and_saveexec_b64 s[0:1], s[18:19]
	s_cbranch_execz .LBB0_1290
	global_load_dwordx4 v[108:111], v[184:185], off offset:960

.LBB0_1296:
	s_or_b64 exec, exec, s[0:1]
	s_waitcnt vmcnt(7)
	v_mfma_f32_32x32x16_bf16 v[4:19], v[112:115], v[144:147], 0
	v_add_co_u32_e32 v112, vcc, 0x51000, v180
	s_mov_b32 s0, 0x358637bd
	s_nop 0
	v_addc_co_u32_e32 v113, vcc, 0, v181, vcc
	v_mov_b32_e32 v114, 0
	v_mov_b32_e32 v115, 0
	s_waitcnt vmcnt(6)
	v_mfma_f32_32x32x16_bf16 v[4:19], v[100:103], v[148:151], v[4:19]
	global_load_dwordx4 v[164:167], v[182:183], off offset:736
	global_load_dwordx4 v[148:151], v[112:113], off offset:1024
	v_mov_b64_e32 v[100:101], s[0:1]
	s_waitcnt vmcnt(5)
	v_fma_f32 v102, v116, s58, v100
	v_fma_f32 v103, v117, s58, v100
	v_mov_b32_e32 v113, 0
	v_mul_f32_e32 v112, 0x4b800000, v102
	v_cmp_gt_f32_e32 vcc, s11, v102
	v_mfma_f32_32x32x16_bf16 v[4:19], v[132:135], v[160:163], v[4:19]
	s_nop 0
	v_cndmask_b32_e32 v102, v102, v112, vcc
	v_rsq_f32_e32 v102, v102
	s_nop 0
	v_mul_f32_e32 v112, 0x45800000, v102
	v_cndmask_b32_e32 v102, v102, v112, vcc
	v_mfma_f32_32x32x16_bf16 v[4:19], v[124:127], v[168:171], v[4:19]
	v_mul_f32_e32 v112, 0x4b800000, v103
	v_cmp_gt_f32_e32 vcc, s11, v103
	v_mul_f32_e32 v102, 0x3e16c740, v102
	s_nop 0
	v_cndmask_b32_e32 v103, v103, v112, vcc
	s_nop 6
	v_rsq_f32_e32 v8, v103
	v_mov_b32_e32 v112, 0
	v_mul_f32_e32 v4, v102, v4
	v_cvt_pk_bf16_f32 v4, v4, s0
	ds_write_b16 v3, v4 offset:2368
	v_mul_f32_e32 v4, 0x45800000, v8
	v_cndmask_b32_e32 v4, v8, v4, vcc
	v_fma_f32 v8, v118, s58, v100
	v_fma_f32 v9, v119, s58, v100
	v_mul_f32_e32 v4, 0x3e16c740, v4
	v_mul_f32_e32 v10, 0x4b800000, v8
	v_cmp_gt_f32_e32 vcc, s11, v8
	v_mul_f32_e32 v4, v4, v5
	v_cvt_pk_bf16_f32 v4, v4, s0
	v_cndmask_b32_e32 v8, v8, v10, vcc
	v_rsq_f32_e32 v8, v8
	ds_write_b16 v3, v4 offset:9472
	v_mul_f32_e32 v5, 0x4b800000, v9
	v_mov_b32_e32 v100, 0
	v_mul_f32_e32 v4, 0x45800000, v8
	v_cndmask_b32_e32 v4, v8, v4, vcc
	v_cmp_gt_f32_e32 vcc, s11, v9
	v_mul_f32_e32 v4, 0x3e16c740, v4
	v_mul_f32_e32 v4, v4, v6
	v_cndmask_b32_e32 v5, v9, v5, vcc
	v_rsq_f32_e32 v5, v5
	v_cvt_pk_bf16_f32 v4, v4, s0
	ds_write_b16 v3, v4 offset:16576
	v_mul_f32_e32 v4, 0x45800000, v5
	v_cndmask_b32_e32 v4, v5, v4, vcc
	v_mul_f32_e32 v4, 0x3e16c740, v4
	v_mul_f32_e32 v4, v4, v7
	v_cvt_pk_bf16_f32 v4, v4, s0
	ds_write_b16 v3, v4 offset:23680
	s_and_saveexec_b64 s[0:1], s[18:19]
	s_cbranch_execz .LBB0_1298
	global_load_dwordx4 v[112:115], v[184:185], off offset:1152

.LBB0_1304:
	s_or_b64 exec, exec, s[0:1]
	s_waitcnt vmcnt(7)
	v_mfma_f32_32x32x16_bf16 v[4:19], v[108:111], v[136:139], 0
	v_add_co_u32_e32 v108, vcc, 0x61000, v180
	s_mov_b32 s0, 0x358637bd
	s_nop 0
	v_addc_co_u32_e32 v109, vcc, 0, v181, vcc
	v_mov_b32_e32 v110, 0
	v_mov_b32_e32 v111, 0
	s_waitcnt vmcnt(6)
	v_mfma_f32_32x32x16_bf16 v[4:19], v[104:107], v[140:143], v[4:19]
	global_load_dwordx4 v[160:163], v[182:183], off offset:864
	global_load_dwordx4 v[140:143], v[108:109], off offset:2048
	v_mov_b64_e32 v[104:105], s[0:1]
	s_waitcnt vmcnt(5)
	v_fma_f32 v106, v148, s58, v104
	v_fma_f32 v107, v149, s58, v104
	v_mov_b32_e32 v109, 0
	v_mul_f32_e32 v108, 0x4b800000, v106
	v_cmp_gt_f32_e32 vcc, s11, v106
	v_mfma_f32_32x32x16_bf16 v[4:19], v[128:131], v[152:155], v[4:19]
	s_nop 0
	v_cndmask_b32_e32 v106, v106, v108, vcc
	v_rsq_f32_e32 v106, v106
	s_nop 0
	v_mul_f32_e32 v108, 0x45800000, v106
	v_cndmask_b32_e32 v106, v106, v108, vcc
	v_mfma_f32_32x32x16_bf16 v[4:19], v[120:123], v[164:167], v[4:19]
	v_mul_f32_e32 v108, 0x4b800000, v107
	v_cmp_gt_f32_e32 vcc, s11, v107
	v_mul_f32_e32 v106, 0x3e16c740, v106
	s_nop 0
	v_cndmask_b32_e32 v107, v107, v108, vcc
	s_nop 6
	v_rsq_f32_e32 v8, v107
	v_mov_b32_e32 v108, 0
	v_mul_f32_e32 v4, v106, v4
	v_cvt_pk_bf16_f32 v4, v4, s0
	ds_write_b16 v3, v4 offset:2960
	v_mul_f32_e32 v4, 0x45800000, v8
	v_cndmask_b32_e32 v4, v8, v4, vcc
	v_fma_f32 v8, v150, s58, v104
	v_fma_f32 v9, v151, s58, v104
	v_mul_f32_e32 v4, 0x3e16c740, v4
	v_mul_f32_e32 v10, 0x4b800000, v8
	v_cmp_gt_f32_e32 vcc, s11, v8
	v_mul_f32_e32 v4, v4, v5
	v_cvt_pk_bf16_f32 v4, v4, s0
	v_cndmask_b32_e32 v8, v8, v10, vcc
	v_rsq_f32_e32 v8, v8
	ds_write_b16 v3, v4 offset:10064
	v_mul_f32_e32 v5, 0x4b800000, v9
	v_mov_b32_e32 v104, 0
	v_mul_f32_e32 v4, 0x45800000, v8
	v_cndmask_b32_e32 v4, v8, v4, vcc
	v_cmp_gt_f32_e32 vcc, s11, v9
	v_mul_f32_e32 v4, 0x3e16c740, v4
	v_mul_f32_e32 v4, v4, v6
	v_cndmask_b32_e32 v5, v9, v5, vcc
	v_rsq_f32_e32 v5, v5
	v_cvt_pk_bf16_f32 v4, v4, s0
	ds_write_b16 v3, v4 offset:17168
	v_mul_f32_e32 v4, 0x45800000, v5
	v_cndmask_b32_e32 v4, v5, v4, vcc
	v_mul_f32_e32 v4, 0x3e16c740, v4
	v_mul_f32_e32 v4, v4, v7
	v_cvt_pk_bf16_f32 v4, v4, s0
	ds_write_b16 v3, v4 offset:24272
	s_and_saveexec_b64 s[0:1], s[18:19]
	s_cbranch_execz .LBB0_1306
	global_load_dwordx4 v[108:111], v[184:185], off offset:1344

.LBB0_1312:
	s_or_b64 exec, exec, s[0:1]
	s_waitcnt vmcnt(7)
	v_mfma_f32_32x32x16_bf16 v[4:19], v[112:115], v[132:135], 0
	v_add_co_u32_e32 v112, vcc, 0x71000, v180
	s_mov_b32 s0, 0x358637bd
	s_nop 0
	v_addc_co_u32_e32 v113, vcc, 0, v181, vcc
	global_load_dwordx4 v[164:167], v[182:183], off offset:992
	s_nop 0
	global_load_dwordx4 v[112:115], v[112:113], off offset:3072
	s_waitcnt vmcnt(8)
	v_mfma_f32_32x32x16_bf16 v[4:19], v[100:103], v[144:147], v[4:19]
	v_mov_b64_e32 v[100:101], s[0:1]
	s_waitcnt vmcnt(5)
	v_fma_f32 v102, v140, s58, v100
	v_fma_f32 v103, v141, s58, v100
	v_mul_f32_e32 v132, 0x4b800000, v102
	v_cmp_gt_f32_e32 vcc, s11, v102
	v_mfma_f32_32x32x16_bf16 v[4:19], v[124:127], v[156:159], v[4:19]
	s_nop 0
	v_cndmask_b32_e32 v102, v102, v132, vcc
	v_rsq_f32_e32 v102, v102
	s_nop 0
	v_mul_f32_e32 v124, 0x45800000, v102
	v_cndmask_b32_e32 v102, v102, v124, vcc
	v_mfma_f32_32x32x16_bf16 v[4:19], v[116:119], v[160:163], v[4:19]
	v_mul_f32_e32 v124, 0x4b800000, v103
	v_cmp_gt_f32_e32 vcc, s11, v103
	v_mul_f32_e32 v102, 0x3e16c740, v102
	v_mov_b32_e32 v116, 0
	v_cndmask_b32_e32 v103, v103, v124, vcc
	s_nop 6
	v_rsq_f32_e32 v8, v103
	v_mov_b32_e32 v117, 0
	v_mul_f32_e32 v4, v102, v4
	v_cvt_pk_bf16_f32 v4, v4, s0
	ds_write_b16 v3, v4 offset:3552
	v_mul_f32_e32 v4, 0x45800000, v8
	v_cndmask_b32_e32 v4, v8, v4, vcc
	v_fma_f32 v8, v142, s58, v100
	v_fma_f32 v9, v143, s58, v100
	v_mul_f32_e32 v4, 0x3e16c740, v4
	v_mul_f32_e32 v10, 0x4b800000, v8
	v_cmp_gt_f32_e32 vcc, s11, v8
	v_mul_f32_e32 v4, v4, v5
	v_cvt_pk_bf16_f32 v4, v4, s0
	v_cndmask_b32_e32 v8, v8, v10, vcc
	v_rsq_f32_e32 v8, v8
	ds_write_b16 v3, v4 offset:10656
	v_mul_f32_e32 v5, 0x4b800000, v9
	v_mov_b32_e32 v100, 0
	v_mul_f32_e32 v4, 0x45800000, v8
	v_cndmask_b32_e32 v4, v8, v4, vcc
	v_cmp_gt_f32_e32 vcc, s11, v9
	v_mul_f32_e32 v4, 0x3e16c740, v4
	v_mul_f32_e32 v4, v4, v6
	v_cndmask_b32_e32 v5, v9, v5, vcc
	v_rsq_f32_e32 v5, v5
	v_cvt_pk_bf16_f32 v4, v4, s0
	ds_write_b16 v3, v4 offset:17760
	v_mov_b32_e32 v118, 0
	v_mul_f32_e32 v4, 0x45800000, v5
	v_cndmask_b32_e32 v4, v5, v4, vcc
	v_mul_f32_e32 v4, 0x3e16c740, v4
	v_mul_f32_e32 v4, v4, v7
	v_cvt_pk_bf16_f32 v4, v4, s0
	v_mov_b32_e32 v119, 0
	ds_write_b16 v3, v4 offset:24864
	s_and_saveexec_b64 s[0:1], s[18:19]
	s_cbranch_execz .LBB0_1314
	global_load_dwordx4 v[116:119], v[184:185], off offset:1536

.LBB0_1320:
	s_or_b64 exec, exec, s[0:1]
	s_waitcnt vmcnt(7)
	v_mfma_f32_32x32x16_bf16 v[4:19], v[108:111], v[136:139], 0
	v_add_co_u32_e32 v108, vcc, 0x82000, v180
	s_mov_b32 s0, 0x358637bd
	s_nop 0
	v_addc_co_u32_e32 v109, vcc, 0, v181, vcc
	s_waitcnt vmcnt(6)
	v_mfma_f32_32x32x16_bf16 v[4:19], v[104:107], v[148:151], v[4:19]
	global_load_dwordx4 v[168:171], v[182:183], off offset:1120
	global_load_dwordx4 v[104:107], v[108:109], off
	v_mov_b64_e32 v[108:109], s[0:1]
	s_waitcnt vmcnt(5)
	v_fma_f32 v110, v112, s58, v108
	v_fma_f32 v111, v113, s58, v108
	v_mov_b32_e32 v113, 0
	v_mul_f32_e32 v112, 0x4b800000, v110
	v_cmp_gt_f32_e32 vcc, s11, v110
	v_mfma_f32_32x32x16_bf16 v[4:19], v[128:131], v[152:155], v[4:19]
	s_nop 0
	v_cndmask_b32_e32 v110, v110, v112, vcc
	v_rsq_f32_e32 v110, v110
	s_nop 0
	v_mul_f32_e32 v112, 0x45800000, v110
	v_cndmask_b32_e32 v110, v110, v112, vcc
	v_mfma_f32_32x32x16_bf16 v[4:19], v[120:123], v[164:167], v[4:19]
	v_mul_f32_e32 v112, 0x4b800000, v111
	v_cmp_gt_f32_e32 vcc, s11, v111
	v_mul_f32_e32 v110, 0x3e16c740, v110
	s_nop 0
	v_cndmask_b32_e32 v111, v111, v112, vcc
	s_nop 6
	v_rsq_f32_e32 v8, v111
	v_mov_b32_e32 v112, 0
	v_mul_f32_e32 v4, v110, v4
	v_cvt_pk_bf16_f32 v4, v4, s0
	ds_write_b16 v3, v4 offset:4144
	v_mul_f32_e32 v4, 0x45800000, v8
	v_cndmask_b32_e32 v4, v8, v4, vcc
	v_fma_f32 v8, v114, s58, v108
	v_fma_f32 v9, v115, s58, v108
	v_mul_f32_e32 v4, 0x3e16c740, v4
	v_mul_f32_e32 v10, 0x4b800000, v8
	v_cmp_gt_f32_e32 vcc, s11, v8
	v_mul_f32_e32 v4, v4, v5
	v_cvt_pk_bf16_f32 v4, v4, s0
	v_cndmask_b32_e32 v8, v8, v10, vcc
	v_rsq_f32_e32 v8, v8
	ds_write_b16 v3, v4 offset:11248
	v_mul_f32_e32 v5, 0x4b800000, v9
	v_mov_b32_e32 v108, 0
	v_mul_f32_e32 v4, 0x45800000, v8
	v_cndmask_b32_e32 v4, v8, v4, vcc
	v_cmp_gt_f32_e32 vcc, s11, v9
	v_mul_f32_e32 v4, 0x3e16c740, v4
	v_mul_f32_e32 v4, v4, v6
	v_cndmask_b32_e32 v5, v9, v5, vcc
	v_rsq_f32_e32 v5, v5
	v_cvt_pk_bf16_f32 v4, v4, s0
	ds_write_b16 v3, v4 offset:18352
	v_mov_b32_e32 v114, 0
	v_mul_f32_e32 v4, 0x45800000, v5
	v_cndmask_b32_e32 v4, v5, v4, vcc
	v_mul_f32_e32 v4, 0x3e16c740, v4
	v_mul_f32_e32 v4, v4, v7
	v_cvt_pk_bf16_f32 v4, v4, s0
	v_mov_b32_e32 v115, 0
	ds_write_b16 v3, v4 offset:25456
	s_and_saveexec_b64 s[0:1], s[18:19]
	s_cbranch_execz .LBB0_1322
	global_load_dwordx4 v[112:115], v[184:185], off offset:1728

.LBB0_1328:
	s_or_b64 exec, exec, s[0:1]
	s_waitcnt vmcnt(7)
	v_mfma_f32_32x32x16_bf16 v[4:19], v[116:119], v[140:143], 0
	v_add_co_u32_e32 v116, vcc, 0x92000, v180
	s_mov_b32 s0, 0x358637bd
	s_nop 0
	v_addc_co_u32_e32 v117, vcc, 0, v181, vcc
	global_load_dwordx4 v[164:167], v[182:183], off offset:1248
	global_load_dwordx4 v[160:163], v[116:117], off offset:1024
	s_waitcnt vmcnt(8)
	v_mfma_f32_32x32x16_bf16 v[4:19], v[100:103], v[144:147], v[4:19]
	v_mov_b64_e32 v[100:101], s[0:1]
	s_waitcnt vmcnt(5)
	v_fma_f32 v102, v104, s58, v100
	v_fma_f32 v103, v105, s58, v100
	v_mov_b32_e32 v105, 0
	v_mul_f32_e32 v104, 0x4b800000, v102
	v_cmp_gt_f32_e32 vcc, s11, v102
	v_mfma_f32_32x32x16_bf16 v[4:19], v[132:135], v[156:159], v[4:19]
	s_nop 0
	v_cndmask_b32_e32 v102, v102, v104, vcc
	v_rsq_f32_e32 v102, v102
	s_nop 0
	v_mul_f32_e32 v104, 0x45800000, v102
	v_cndmask_b32_e32 v102, v102, v104, vcc
	v_mfma_f32_32x32x16_bf16 v[4:19], v[124:127], v[168:171], v[4:19]
	v_mul_f32_e32 v104, 0x4b800000, v103
	v_cmp_gt_f32_e32 vcc, s11, v103
	v_mul_f32_e32 v102, 0x3e16c740, v102
	s_nop 0
	v_cndmask_b32_e32 v103, v103, v104, vcc
	s_nop 6
	v_rsq_f32_e32 v8, v103
	v_mov_b32_e32 v104, 0
	v_mul_f32_e32 v4, v102, v4
	v_cvt_pk_bf16_f32 v4, v4, s0
	ds_write_b16 v3, v4 offset:4736
	v_mul_f32_e32 v4, 0x45800000, v8
	v_cndmask_b32_e32 v4, v8, v4, vcc
	v_fma_f32 v8, v106, s58, v100
	v_fma_f32 v9, v107, s58, v100
	v_mul_f32_e32 v4, 0x3e16c740, v4
	v_mul_f32_e32 v10, 0x4b800000, v8
	v_cmp_gt_f32_e32 vcc, s11, v8
	v_mul_f32_e32 v4, v4, v5
	v_cvt_pk_bf16_f32 v4, v4, s0
	v_cndmask_b32_e32 v8, v8, v10, vcc
	v_rsq_f32_e32 v8, v8
	ds_write_b16 v3, v4 offset:11840
	v_mul_f32_e32 v5, 0x4b800000, v9
	v_mov_b32_e32 v100, 0
	v_mul_f32_e32 v4, 0x45800000, v8
	v_cndmask_b32_e32 v4, v8, v4, vcc
	v_cmp_gt_f32_e32 vcc, s11, v9
	v_mul_f32_e32 v4, 0x3e16c740, v4
	v_mul_f32_e32 v4, v4, v6
	v_cndmask_b32_e32 v5, v9, v5, vcc
	v_rsq_f32_e32 v5, v5
	v_cvt_pk_bf16_f32 v4, v4, s0
	ds_write_b16 v3, v4 offset:18944
	v_mov_b32_e32 v106, 0
	v_mul_f32_e32 v4, 0x45800000, v5
	v_cndmask_b32_e32 v4, v5, v4, vcc
	v_mul_f32_e32 v4, 0x3e16c740, v4
	v_mul_f32_e32 v4, v4, v7
	v_cvt_pk_bf16_f32 v4, v4, s0
	v_mov_b32_e32 v107, 0
	ds_write_b16 v3, v4 offset:26048
	s_and_saveexec_b64 s[0:1], s[18:19]
	s_cbranch_execz .LBB0_1330
	global_load_dwordx4 v[104:107], v[184:185], off offset:1920

.LBB0_1336:
	s_or_b64 exec, exec, s[0:1]
	s_waitcnt vmcnt(7)
	v_mfma_f32_32x32x16_bf16 v[4:19], v[112:115], v[136:139], 0
	v_add_co_u32_e32 v136, vcc, 0xa2000, v180
	s_mov_b32 s0, 0x358637bd
	s_nop 0
	v_addc_co_u32_e32 v137, vcc, 0, v181, vcc
	s_waitcnt vmcnt(6)
	v_mfma_f32_32x32x16_bf16 v[4:19], v[108:111], v[148:151], v[4:19]
	global_load_dwordx4 v[112:115], v[182:183], off offset:1376
	global_load_dwordx4 v[108:111], v[136:137], off offset:2048
	v_mov_b64_e32 v[136:137], s[0:1]
	s_waitcnt vmcnt(5)
	v_fma_f32 v138, v160, s58, v136
	v_fma_f32 v139, v161, s58, v136
	v_mul_f32_e32 v148, 0x4b800000, v138
	v_cmp_gt_f32_e32 vcc, s11, v138
	v_mfma_f32_32x32x16_bf16 v[4:19], v[128:131], v[152:155], v[4:19]
	s_nop 0
	v_cndmask_b32_e32 v138, v138, v148, vcc
	v_rsq_f32_e32 v128, v138
	v_mov_b32_e32 v130, 0
	v_mov_b32_e32 v131, 0
	v_mul_f32_e32 v129, 0x45800000, v128
	v_cndmask_b32_e32 v128, v128, v129, vcc
	v_mfma_f32_32x32x16_bf16 v[4:19], v[120:123], v[164:167], v[4:19]
	v_mul_f32_e32 v129, 0x4b800000, v139
	v_cmp_gt_f32_e32 vcc, s11, v139
	v_mul_f32_e32 v128, 0x3e16c740, v128
	v_mov_b32_e32 v120, 0
	v_cndmask_b32_e32 v129, v139, v129, vcc
	s_nop 6
	v_rsq_f32_e32 v8, v129
	v_mov_b32_e32 v129, 0
	v_mul_f32_e32 v4, v128, v4
	v_cvt_pk_bf16_f32 v4, v4, s0
	ds_write_b16 v3, v4 offset:5328
	v_mul_f32_e32 v4, 0x45800000, v8
	v_cndmask_b32_e32 v4, v8, v4, vcc
	v_fma_f32 v8, v162, s58, v136
	v_fma_f32 v9, v163, s58, v136
	v_mul_f32_e32 v4, 0x3e16c740, v4
	v_mul_f32_e32 v10, 0x4b800000, v8
	v_cmp_gt_f32_e32 vcc, s11, v8
	v_mul_f32_e32 v4, v4, v5
	v_cvt_pk_bf16_f32 v4, v4, s0
	v_cndmask_b32_e32 v8, v8, v10, vcc
	v_rsq_f32_e32 v8, v8
	ds_write_b16 v3, v4 offset:12432
	v_mul_f32_e32 v5, 0x4b800000, v9
	v_mov_b32_e32 v128, 0
	v_mul_f32_e32 v4, 0x45800000, v8
	v_cndmask_b32_e32 v4, v8, v4, vcc
	v_cmp_gt_f32_e32 vcc, s11, v9
	v_mul_f32_e32 v4, 0x3e16c740, v4
	v_mul_f32_e32 v4, v4, v6
	v_cndmask_b32_e32 v5, v9, v5, vcc
	v_rsq_f32_e32 v5, v5
	v_cvt_pk_bf16_f32 v4, v4, s0
	ds_write_b16 v3, v4 offset:19536
	v_mul_f32_e32 v4, 0x45800000, v5
	v_cndmask_b32_e32 v4, v5, v4, vcc
	v_mul_f32_e32 v4, 0x3e16c740, v4
	v_mul_f32_e32 v4, v4, v7
	v_cvt_pk_bf16_f32 v4, v4, s0
	ds_write_b16 v3, v4 offset:26640
	s_and_saveexec_b64 s[0:1], s[18:19]
	s_cbranch_execz .LBB0_1338
	global_load_dwordx4 v[128:131], v[184:185], off offset:2112

.LBB0_1344:
	s_or_b64 exec, exec, s[0:1]
	s_waitcnt vmcnt(7)
	v_mfma_f32_32x32x16_bf16 v[4:19], v[104:107], v[116:119], 0
	global_load_dwordx4 v[164:167], v[182:183], off offset:1504
	s_mov_b32 s0, 0x358637bd
	s_waitcnt vmcnt(7)
	v_mfma_f32_32x32x16_bf16 v[4:19], v[100:103], v[124:127], v[4:19]
	v_mov_b64_e32 v[100:101], s[0:1]
	s_waitcnt vmcnt(6)
	v_mfma_f32_32x32x16_bf16 v[4:19], v[140:143], v[144:147], v[4:19]
	s_waitcnt vmcnt(5)
	v_mfma_f32_32x32x16_bf16 v[4:19], v[132:135], v[112:115], v[4:19]
	s_waitcnt vmcnt(4)
	s_nop 10
	v_fma_f32 v8, v108, s58, v100
	v_fma_f32 v9, v109, s58, v100
	s_nop 0
	v_mul_f32_e32 v10, 0x4b800000, v8
	v_cmp_gt_f32_e64 s[18:19], s11, v8
	v_cmp_gt_f32_e32 vcc, s11, v9
	s_nop 0
	v_cndmask_b32_e64 v8, v8, v10, s[18:19]
	v_rsq_f32_e32 v8, v8
	s_nop 0
	v_mul_f32_e32 v10, 0x45800000, v8
	v_cndmask_b32_e64 v8, v8, v10, s[18:19]
	v_mul_f32_e32 v8, 0x3e16c740, v8
	v_mul_f32_e32 v4, v8, v4
	v_cvt_pk_bf16_f32 v4, v4, s0
	ds_write_b16 v3, v4 offset:5920
	v_mul_f32_e32 v4, 0x4b800000, v9
	v_cndmask_b32_e32 v4, v9, v4, vcc
	v_rsq_f32_e32 v4, v4
	s_nop 0
	v_mul_f32_e32 v8, 0x45800000, v4
	v_cndmask_b32_e32 v4, v4, v8, vcc
	v_mul_f32_e32 v4, 0x3e16c740, v4
	v_mul_f32_e32 v4, v4, v5
	v_cvt_pk_bf16_f32 v4, v4, s0
	ds_write_b16 v3, v4 offset:13024
	v_fma_f32 v4, v110, s58, v100
	v_fma_f32 v5, v111, s58, v100
	s_nop 0
	v_mul_f32_e32 v8, 0x4b800000, v4
	v_cmp_gt_f32_e64 s[18:19], s11, v4
	v_cmp_gt_f32_e32 vcc, s11, v5
	s_nop 0
	v_cndmask_b32_e64 v4, v4, v8, s[18:19]
	v_rsq_f32_e32 v4, v4
	s_nop 0
	v_mul_f32_e32 v8, 0x45800000, v4
	v_cndmask_b32_e64 v4, v4, v8, s[18:19]
	v_mul_f32_e32 v4, 0x3e16c740, v4
	v_mul_f32_e32 v4, v4, v6
	v_cvt_pk_bf16_f32 v4, v4, s0
	ds_write_b16 v3, v4 offset:20128
	v_mul_f32_e32 v4, 0x4b800000, v5
	v_cndmask_b32_e32 v4, v5, v4, vcc
	v_rsq_f32_e32 v4, v4
	s_nop 0
	v_mul_f32_e32 v5, 0x45800000, v4
	v_cndmask_b32_e32 v4, v4, v5, vcc
	v_mul_f32_e32 v4, 0x3e16c740, v4
	v_mul_f32_e32 v4, v4, v7
	v_cvt_pk_bf16_f32 v4, v4, s0
	ds_write_b16 v3, v4 offset:27232
	s_waitcnt vmcnt(3)
	v_mfma_f32_32x32x16_bf16 v[4:19], v[128:131], v[136:139], 0
	s_mov_b32 s0, 0xb2000
	s_waitcnt vmcnt(2)
	v_mfma_f32_32x32x16_bf16 v[4:19], v[120:123], v[148:151], v[4:19]
	s_waitcnt vmcnt(1)
	v_mfma_f32_32x32x16_bf16 v[4:19], v[156:159], v[160:163], v[4:19]
	s_waitcnt vmcnt(0)
	v_mfma_f32_32x32x16_bf16 v[4:19], v[152:155], v[164:167], v[4:19]
	s_nop 11
	v_add_co_u32_e32 v8, vcc, s0, v180
	s_nop 1
	v_addc_co_u32_e32 v9, vcc, 0, v181, vcc
	global_load_dwordx4 v[8:11], v[8:9], off offset:3072
	s_waitcnt vmcnt(0)
	v_fma_f32 v8, v8, s58, v100
	v_fma_f32 v9, v9, s58, v100
	s_nop 0
	v_mul_f32_e32 v12, 0x4b800000, v8
	v_cmp_gt_f32_e64 s[18:19], s11, v8
	v_cmp_gt_f32_e32 vcc, s11, v9
	s_nop 0
	v_cndmask_b32_e64 v8, v8, v12, s[18:19]
	v_rsq_f32_e32 v8, v8
	s_nop 0
	v_mul_f32_e32 v12, 0x45800000, v8
	v_cndmask_b32_e64 v8, v8, v12, s[18:19]
	v_mul_f32_e32 v8, 0x3e16c740, v8
	v_mul_f32_e32 v4, v8, v4
	v_cvt_pk_bf16_f32 v4, v4, s0
	ds_write_b16 v3, v4 offset:6512
	v_mul_f32_e32 v4, 0x4b800000, v9
	v_cndmask_b32_e32 v4, v9, v4, vcc
	v_rsq_f32_e32 v4, v4
	s_nop 0
	v_mul_f32_e32 v8, 0x45800000, v4
	v_cndmask_b32_e32 v4, v4, v8, vcc
	v_mul_f32_e32 v4, 0x3e16c740, v4
	v_mul_f32_e32 v4, v4, v5
	v_cvt_pk_bf16_f32 v4, v4, s0
	ds_write_b16 v3, v4 offset:13616
	v_fma_f32 v4, v10, s58, v100
	v_fma_f32 v5, v11, s58, v100
	s_nop 0
	v_mul_f32_e32 v8, 0x4b800000, v4
	v_cmp_gt_f32_e64 s[18:19], s11, v4
	v_cmp_gt_f32_e32 vcc, s11, v5
	s_nop 0
	v_cndmask_b32_e64 v4, v4, v8, s[18:19]
	v_rsq_f32_e32 v4, v4
	s_nop 0
	v_mul_f32_e32 v8, 0x45800000, v4
	v_cndmask_b32_e64 v4, v4, v8, s[18:19]
	v_mul_f32_e32 v4, 0x3e16c740, v4
	v_mul_f32_e32 v4, v4, v6
	v_cvt_pk_bf16_f32 v4, v4, s0
	ds_write_b16 v3, v4 offset:20720
	v_mul_f32_e32 v4, 0x4b800000, v5
	v_cndmask_b32_e32 v4, v5, v4, vcc
	v_rsq_f32_e32 v4, v4
	s_nop 0
	v_mul_f32_e32 v5, 0x45800000, v4
	v_cndmask_b32_e32 v4, v4, v5, vcc
	v_mul_f32_e32 v4, 0x3e16c740, v4
	v_mul_f32_e32 v4, v4, v7
	v_cvt_pk_bf16_f32 v4, v4, s0
	v_cmp_gt_i32_e32 vcc, s77, v1
	ds_write_b16 v3, v4 offset:27824
	s_and_saveexec_b64 s[0:1], vcc
	s_cbranch_execz .LBB0_1346
	v_ashrrev_i32_e32 v3, 1, v1
	s_mov_b32 s8, 0x2aaaaaab
	v_mul_hi_i32 v4, v3, s8
	v_lshrrev_b32_e32 v5, 31, v4
	v_ashrrev_i32_e32 v4, 1, v4
	v_add_u32_e32 v12, v4, v5
	v_mul_lo_u32 v4, v12, 12
	v_sub_u32_e32 v14, v3, v4
	v_ashrrev_i32_e32 v13, 31, v12
	v_lshl_add_u64 v[4:5], s[94:95], 0, v[12:13]
	v_ashrrev_i32_e32 v15, 31, v14
	v_mad_u64_u32 v[6:7], s[8:9], v4, 12, v[14:15]
	v_lshl_add_u64 v[14:15], v[14:15], 0, s[90:91]
	v_mov_b64_e32 v[16:17], s[86:87]
	s_mov_b32 s18, 0x10400
	v_mad_i32_i24 v7, v5, 12, v7
	v_mov_b64_e32 v[4:5], s[82:83]
	v_mad_u64_u32 v[16:17], s[8:9], v14, s18, v[16:17]
	v_and_b32_e32 v18, 1, v1
	v_mad_u64_u32 v[4:5], s[8:9], v6, s77, v[4:5]
	v_mad_i32_i24 v17, v15, s18, v17
	v_mad_i32_i24 v5, v7, s77, v5
	v_lshlrev_b32_e32 v108, 4, v18
	v_mov_b32_e32 v109, v2
	v_lshl_add_u64 v[14:15], s[94:95], 2, v[16:17]
	v_lshl_add_u64 v[8:9], v[4:5], 0, v[108:109]
	v_lshl_add_u64 v[14:15], v[12:13], 2, v[14:15]
	global_load_dwordx4 v[4:7], v[8:9], off offset:128
	s_nop 0
	global_load_dwordx4 v[8:11], v[8:9], off offset:160
	v_lshlrev_b32_e32 v12, 4, v12
	global_load_dword v115, v[14:15], off
	v_ashrrev_i32_e32 v13, 31, v12
	v_mov_b64_e32 v[14:15], 0x20000
	v_lshl_add_u64 v[100:101], v[12:13], 2, v[14:15]
	v_lshl_add_u64 v[12:13], s[6:7], 0, v[100:101]
	v_lshlrev_b32_e32 v102, 5, v18
	v_mov_b32_e32 v103, v2
	v_lshl_add_u64 v[100:101], s[80:81], 0, v[100:101]
	v_lshl_add_u64 v[16:17], v[12:13], 0, v[102:103]
	v_lshl_add_u64 v[104:105], v[100:101], 0, v[102:103]
	global_load_dwordx4 v[12:15], v[16:17], off
	s_nop 0
	global_load_dwordx4 v[16:19], v[16:17], off offset:16
	s_nop 0
	global_load_dwordx4 v[100:103], v[104:105], off
	s_nop 0
	global_load_dwordx4 v[104:107], v[104:105], off offset:16
	v_mul_lo_u32 v3, v3, s33
	v_add3_u32 v3, 0, v3, v108
	s_waitcnt vmcnt(6)
	v_lshlrev_b32_e32 v108, 16, v4
	s_waitcnt vmcnt(5)
	v_lshlrev_b32_e32 v112, 16, v8
	v_and_b32_e32 v113, 0xffff0000, v8
	s_waitcnt vmcnt(4)
	v_fmamk_f32 v115, v115, 0x3c2aaaab, v231
	v_mul_f32_e32 v116, 0x4b800000, v115
	v_cmp_gt_f32_e32 vcc, s11, v115
	v_lshlrev_b32_e32 v8, 16, v9
	v_and_b32_e32 v9, 0xffff0000, v9
	v_cndmask_b32_e32 v115, v115, v116, vcc
	v_rsq_f32_e32 v116, v115
	v_lshlrev_b32_e32 v114, 16, v10
	v_and_b32_e32 v115, 0xffff0000, v10
	v_lshlrev_b32_e32 v10, 16, v11
	v_mul_f32_e32 v117, 0x45800000, v116
	v_cndmask_b32_e32 v116, v116, v117, vcc
	v_mul_f32_e32 v116, 0x3e16c740, v116
	v_and_b32_e32 v11, 0xffff0000, v11
	s_waitcnt vmcnt(1)
	v_mul_f32 v102, v102, v116
	v_mul_f32 v103, v103, v116
	v_mul_f32 v100, v100, v116
	v_mul_f32 v101, v101, v116
	s_waitcnt vmcnt(0)
	v_mul_f32 v106, v106, v116
	v_mul_f32 v107, v107, v116
	v_mul_f32 v104, v104, v116
	v_mul_f32 v105, v105, v116
	v_and_b32_e32 v109, 0xffff0000, v4
	v_lshlrev_b32_e32 v4, 16, v5
	v_and_b32_e32 v5, 0xffff0000, v5
	v_lshlrev_b32_e32 v110, 16, v6
	v_and_b32_e32 v111, 0xffff0000, v6
	v_lshlrev_b32_e32 v6, 16, v7
	v_and_b32_e32 v7, 0xffff0000, v7
	v_mul_f32 v12, v12, v116
	v_mul_f32 v13, v13, v116
	v_mul_f32 v14, v14, v116
	v_mul_f32 v15, v15, v116
	v_mul_f32 v16, v16, v116
	v_mul_f32 v17, v17, v116
	v_mul_f32 v18, v18, v116
	v_mul_f32 v19, v19, v116
	v_mul_f32 v116, v100, v112
	v_mul_f32 v117, v101, v113
	v_mul_f32 v118, v102, v8
	v_mul_f32 v119, v103, v9
	v_mul_f32 v120, v104, v114
	v_mul_f32 v121, v105, v115
	v_mul_f32 v122, v106, v10
	v_mul_f32 v123, v107, v11
	v_mul_f32 v112, v12, v112
	v_mul_f32 v113, v13, v113
	v_mul_f32 v8, v14, v8
	v_mul_f32 v9, v15, v9
	v_mul_f32 v114, v16, v114
	v_mul_f32 v115, v17, v115
	v_mul_f32 v10, v18, v10
	v_mul_f32 v11, v19, v11
	v_fma_f32 v14, v14, v4, -v118
	v_fma_f32 v15, v15, v5, -v119
	v_fma_f32 v12, v12, v108, -v116
	v_fma_f32 v13, v13, v109, -v117
	v_fma_f32 v18, v18, v6, -v122
	v_fma_f32 v19, v19, v7, -v123
	v_fma_f32 v16, v16, v110, -v120
	v_fma_f32 v17, v17, v111, -v121
	v_fma_f32 v102, v102, v4, v8
	v_fma_f32 v103, v103, v5, v9
	v_fma_f32 v8, v100, v108, v112
	v_fma_f32 v9, v101, v109, v113
	v_fma_f32 v100, v106, v6, v10
	v_fma_f32 v101, v107, v7, v11
	v_fma_f32 v10, v104, v110, v114
	v_fma_f32 v11, v105, v111, v115
	v_cvt_pk_bf16_f32 v4, v12, v13
	v_cvt_pk_bf16_f32 v5, v14, v15
	v_cvt_pk_bf16_f32 v6, v16, v17
	v_cvt_pk_bf16_f32 v7, v18, v19
	v_cvt_pk_bf16_f32 v8, v8, v9
	v_cvt_pk_bf16_f32 v9, v102, v103
	v_cvt_pk_bf16_f32 v10, v10, v11
	v_cvt_pk_bf16_f32 v11, v100, v101
	ds_write_b128 v3, v[4:7] offset:512
	ds_write_b128 v3, v[8:11] offset:544

.LlazyA_rescale:
	v_max_f32_e32 v3, v166, v148
	v_sub_f32_e32 v148, v166, v3
	v_exp_f32_e32 v232, v148
	s_nop 0
	v_mul_f32 v80, v80, v232
	v_mul_f32 v81, v81, v232
	v_mul_f32 v78, v78, v232
	v_mul_f32 v79, v79, v232
	v_mul_f32 v76, v76, v232
	v_mul_f32 v77, v77, v232
	v_mul_f32 v74, v74, v232
	v_mul_f32 v75, v75, v232
	v_mul_f32 v72, v72, v232
	v_mul_f32 v73, v73, v232
	v_mul_f32 v70, v70, v232
	v_mul_f32 v71, v71, v232
	v_mul_f32 v68, v68, v232
	v_mul_f32 v69, v69, v232
	v_mul_f32 v66, v66, v232
	v_mul_f32 v67, v67, v232
	v_mul_f32 v64, v64, v232
	v_mul_f32 v65, v65, v232
	v_mul_f32_e64 v62, v62, v232
	v_mul_f32_e64 v63, v63, v232
	v_mul_f32_e64 v60, v60, v232
	v_mul_f32_e64 v61, v61, v232
	v_mul_f32_e64 v58, v58, v232
	v_mul_f32_e64 v59, v59, v232
	v_mul_f32 v56, v56, v232
	v_mul_f32 v57, v57, v232
	v_mul_f32 v54, v54, v232
	v_mul_f32 v55, v55, v232
	v_mul_f32 v52, v52, v232
	v_mul_f32 v53, v53, v232
	v_mul_f32 v50, v50, v232
	v_mul_f32 v51, v51, v232
	v_mul_f32 v144, v144, v232
	v_mul_f32 v145, v145, v232
	v_mul_f32 v142, v142, v232
	v_mul_f32 v143, v143, v232
	v_mul_f32_e64 v140, v140, v232
	v_mul_f32_e64 v141, v141, v232
	v_mul_f32_e64 v138, v138, v232
	v_mul_f32_e64 v139, v139, v232
	v_mul_f32_e64 v136, v136, v232
	v_mul_f32_e64 v137, v137, v232
	v_mul_f32 v134, v134, v232
	v_mul_f32 v135, v135, v232
	v_mul_f32 v132, v132, v232
	v_mul_f32 v133, v133, v232
	v_mul_f32 v130, v130, v232
	v_mul_f32 v131, v131, v232
	v_mul_f32 v128, v128, v232
	v_mul_f32 v129, v129, v232
	v_mul_f32 v126, v126, v232
	v_mul_f32 v127, v127, v232
	v_mul_f32 v124, v124, v232
	v_mul_f32 v125, v125, v232
	v_mul_f32 v122, v122, v232
	v_mul_f32 v123, v123, v232
	v_mul_f32 v120, v120, v232
	v_mul_f32 v121, v121, v232
	v_mul_f32 v118, v118, v232
	v_mul_f32 v119, v119, v232
	v_mul_f32 v116, v116, v232
	v_mul_f32 v117, v117, v232
	v_mul_f32 v114, v114, v232
	v_mul_f32 v115, v115, v232
	v_mul_f32 v112, v112, v232
	v_mul_f32 v113, v113, v232
	v_mul_f32 v110, v110, v232
	v_mul_f32 v111, v111, v232
	v_mul_f32 v108, v108, v232
	v_mul_f32 v109, v109, v232
	v_mul_f32 v106, v106, v232
	v_mul_f32 v107, v107, v232
	v_mul_f32 v104, v104, v232
	v_mul_f32 v105, v105, v232
	v_mul_f32 v102, v102, v232
	v_mul_f32 v103, v103, v232
	v_mul_f32 v100, v100, v232
	v_mul_f32 v101, v101, v232
	v_mul_f32 v98, v98, v232
	v_mul_f32 v99, v99, v232
	v_mul_f32 v96, v96, v232
	v_mul_f32 v97, v97, v232
	v_mul_f32 v94, v94, v232
	v_mul_f32 v95, v95, v232
	v_mul_f32 v92, v92, v232
	v_mul_f32 v93, v93, v232
	v_mul_f32 v90, v90, v232
	v_mul_f32 v91, v91, v232
	v_mul_f32 v88, v88, v232
	v_mul_f32 v89, v89, v232
	v_mul_f32 v86, v86, v232
	v_mul_f32 v87, v87, v232
	v_mul_f32 v84, v84, v232
	v_mul_f32 v85, v85, v232
	v_mul_f32 v82, v82, v232
	v_mul_f32 v83, v83, v232
	v_mul_f32 v48, v48, v232
	v_mul_f32 v49, v49, v232
	v_mul_f32 v46, v46, v232
	v_mul_f32 v47, v47, v232
	v_mul_f32 v44, v44, v232
	v_mul_f32 v45, v45, v232
	v_mul_f32 v42, v42, v232
	v_mul_f32 v43, v43, v232
	v_mul_f32 v40, v40, v232
	v_mul_f32 v41, v41, v232
	v_mul_f32 v38, v38, v232
	v_mul_f32 v39, v39, v232
	v_mul_f32 v36, v36, v232
	v_mul_f32 v37, v37, v232
	v_mul_f32 v34, v34, v232
	v_mul_f32 v35, v35, v232
	v_mul_f32 v32, v32, v232
	v_mul_f32 v33, v33, v232
	v_mul_f32 v30, v30, v232
	v_mul_f32 v31, v31, v232
	v_mul_f32 v28, v28, v232
	v_mul_f32 v29, v29, v232
	v_mul_f32 v26, v26, v232
	v_mul_f32 v27, v27, v232
	v_mul_f32 v24, v24, v232
	v_mul_f32 v25, v25, v232
	v_mul_f32 v22, v22, v232
	v_mul_f32 v23, v23, v232
	v_mul_f32 v20, v20, v232
	v_mul_f32 v21, v21, v232
	v_mul_f32 v18, v18, v232
	v_mul_f32 v19, v19, v232
	s_branch .LlazyA_join

.LBB0_1446:
	s_or_b64 exec, exec, s[8:9]
	v_lshlrev_b32_e32 v173, 2, v3
	v_lshlrev_b32_e32 v174, 2, v173
	v_mov_b32_e32 v175, v2
	v_lshl_add_u64 v[12:13], s[0:1], 0, v[174:175]
	v_lshl_add_u64 v[180:181], s[68:69], 2, v[12:13]
	s_mov_b32 s0, 0x10000
	v_add_co_u32_e32 v156, vcc, s0, v180
	s_waitcnt vmcnt(7)
	v_mfma_f32_32x32x16_bf16 v[4:19], v[4:7], v[8:11], 0
	v_addc_co_u32_e32 v157, vcc, 0, v181, vcc
	global_load_dwordx4 v[164:167], v[182:183], off offset:224
	s_nop 0
	global_load_dwordx4 v[156:159], v[156:157], off offset:1024
	s_mov_b32 s0, 0x358637bd
	v_and_b32_e32 v160, 0xffffffc0, v1
	v_lshlrev_b32_e32 v161, 1, v178
	v_add3_u32 v168, 0, v160, v161
	s_waitcnt vmcnt(8)
	v_mfma_f32_32x32x16_bf16 v[4:19], v[100:103], v[124:127], v[4:19]
	v_mov_b64_e32 v[100:101], s[0:1]
	s_waitcnt vmcnt(5)
	v_fma_f32 v102, v144, s58, v100
	v_fma_f32 v103, v145, s58, v100
	s_movk_i32 s0, 0x6f00
	v_mul_f32_e32 v124, 0x4b800000, v102
	v_cmp_gt_f32_e32 vcc, s11, v102
	v_mfma_f32_32x32x16_bf16 v[4:19], v[120:123], v[132:135], v[4:19]
	s_nop 0
	v_cndmask_b32_e32 v102, v102, v124, vcc
	v_rsq_f32_e32 v102, v102
	v_mad_u32_u24 v120, v3, s0, v168
	v_mul_f32_e32 v121, 0x45800000, v102
	v_cndmask_b32_e32 v102, v102, v121, vcc
	v_mfma_f32_32x32x16_bf16 v[4:19], v[108:111], v[148:151], v[4:19]
	v_mul_f32_e32 v121, 0x4b800000, v103
	v_cmp_gt_f32_e32 vcc, s11, v103
	v_mul_f32_e32 v102, 0x3e16c740, v102
	v_mov_b32_e32 v108, 0
	v_cndmask_b32_e32 v103, v103, v121, vcc
	s_nop 6
	v_rsq_f32_e32 v8, v103
	v_mov_b32_e32 v109, 0
	v_mul_f32_e32 v4, v102, v4
	v_cvt_pk_bf16_f32 v4, v4, s0
	ds_write_b16 v120, v4
	v_mul_f32_e32 v4, 0x45800000, v8
	v_cndmask_b32_e32 v4, v8, v4, vcc
	v_fma_f32 v8, v146, s58, v100
	v_fma_f32 v9, v147, s58, v100
	v_mul_f32_e32 v4, 0x3e16c740, v4
	v_mul_f32_e32 v10, 0x4b800000, v8
	v_cmp_gt_f32_e32 vcc, s11, v8
	v_mul_f32_e32 v4, v4, v5
	v_cvt_pk_bf16_f32 v4, v4, s0
	v_cndmask_b32_e32 v8, v8, v10, vcc
	v_rsq_f32_e32 v8, v8
	ds_write_b16 v120, v4 offset:7104
	v_mul_f32_e32 v5, 0x4b800000, v9
	v_mov_b32_e32 v100, 0
	v_mul_f32_e32 v4, 0x45800000, v8
	v_cndmask_b32_e32 v4, v8, v4, vcc
	v_cmp_gt_f32_e32 vcc, s11, v9
	v_mul_f32_e32 v4, 0x3e16c740, v4
	v_mul_f32_e32 v4, v4, v6
	v_cndmask_b32_e32 v5, v9, v5, vcc
	v_rsq_f32_e32 v5, v5
	v_cvt_pk_bf16_f32 v4, v4, s0
	ds_write_b16 v120, v4 offset:14208
	v_mov_b32_e32 v110, 0
	v_mul_f32_e32 v4, 0x45800000, v5
	v_cndmask_b32_e32 v4, v5, v4, vcc
	v_mul_f32_e32 v4, 0x3e16c740, v4
	v_mul_f32_e32 v4, v4, v7
	v_cvt_pk_bf16_f32 v4, v4, s0
	v_mov_b32_e32 v111, 0
	ds_write_b16 v120, v4 offset:21312
	s_and_saveexec_b64 s[0:1], s[18:19]
	s_cbranch_execz .LBB0_1448
	global_load_dwordx4 v[108:111], v[184:185], off offset:384

.LBB0_1526:
	s_or_b64 exec, exec, s[0:1]
	s_waitcnt vmcnt(7)
	v_mfma_f32_32x32x16_bf16 v[4:19], v[104:107], v[116:119], 0
	global_load_dwordx4 v[164:167], v[182:183], off offset:1504
	s_mov_b32 s0, 0x358637bd
	s_waitcnt vmcnt(7)
	v_mfma_f32_32x32x16_bf16 v[4:19], v[100:103], v[124:127], v[4:19]
	v_mov_b64_e32 v[100:101], s[0:1]
	s_waitcnt vmcnt(6)
	v_mfma_f32_32x32x16_bf16 v[4:19], v[140:143], v[144:147], v[4:19]
	s_waitcnt vmcnt(5)
	v_mfma_f32_32x32x16_bf16 v[4:19], v[132:135], v[112:115], v[4:19]
	s_waitcnt vmcnt(4)
	s_nop 10
	v_fma_f32 v8, v108, s58, v100
	v_fma_f32 v9, v109, s58, v100
	s_nop 0
	v_mul_f32_e32 v10, 0x4b800000, v8
	v_cmp_gt_f32_e64 s[18:19], s11, v8
	v_cmp_gt_f32_e32 vcc, s11, v9
	s_nop 0
	v_cndmask_b32_e64 v8, v8, v10, s[18:19]
	v_rsq_f32_e32 v8, v8
	s_nop 0
	v_mul_f32_e32 v10, 0x45800000, v8
	v_cndmask_b32_e64 v8, v8, v10, s[18:19]
	v_mul_f32_e32 v8, 0x3e16c740, v8
	v_mul_f32_e32 v4, v8, v4
	v_cvt_pk_bf16_f32 v4, v4, s0
	ds_write_b16 v3, v4 offset:5920
	v_mul_f32_e32 v4, 0x4b800000, v9
	v_cndmask_b32_e32 v4, v9, v4, vcc
	v_rsq_f32_e32 v4, v4
	s_nop 0
	v_mul_f32_e32 v8, 0x45800000, v4
	v_cndmask_b32_e32 v4, v4, v8, vcc
	v_mul_f32_e32 v4, 0x3e16c740, v4
	v_mul_f32_e32 v4, v4, v5
	v_cvt_pk_bf16_f32 v4, v4, s0
	ds_write_b16 v3, v4 offset:13024
	v_fma_f32 v4, v110, s58, v100
	v_fma_f32 v5, v111, s58, v100
	s_nop 0
	v_mul_f32_e32 v8, 0x4b800000, v4
	v_cmp_gt_f32_e64 s[18:19], s11, v4
	v_cmp_gt_f32_e32 vcc, s11, v5
	s_nop 0
	v_cndmask_b32_e64 v4, v4, v8, s[18:19]
	v_rsq_f32_e32 v4, v4
	s_nop 0
	v_mul_f32_e32 v8, 0x45800000, v4
	v_cndmask_b32_e64 v4, v4, v8, s[18:19]
	v_mul_f32_e32 v4, 0x3e16c740, v4
	v_mul_f32_e32 v4, v4, v6
	v_cvt_pk_bf16_f32 v4, v4, s0
	ds_write_b16 v3, v4 offset:20128
	v_mul_f32_e32 v4, 0x4b800000, v5
	v_cndmask_b32_e32 v4, v5, v4, vcc
	v_rsq_f32_e32 v4, v4
	s_nop 0
	v_mul_f32_e32 v5, 0x45800000, v4
	v_cndmask_b32_e32 v4, v4, v5, vcc
	v_mul_f32_e32 v4, 0x3e16c740, v4
	v_mul_f32_e32 v4, v4, v7
	v_cvt_pk_bf16_f32 v4, v4, s0
	ds_write_b16 v3, v4 offset:27232
	s_waitcnt vmcnt(3)
	v_mfma_f32_32x32x16_bf16 v[4:19], v[128:131], v[136:139], 0
	s_mov_b32 s0, 0xb2000
	s_waitcnt vmcnt(2)
	v_mfma_f32_32x32x16_bf16 v[4:19], v[120:123], v[148:151], v[4:19]
	s_waitcnt vmcnt(1)
	v_mfma_f32_32x32x16_bf16 v[4:19], v[156:159], v[160:163], v[4:19]
	s_waitcnt vmcnt(0)
	v_mfma_f32_32x32x16_bf16 v[4:19], v[152:155], v[164:167], v[4:19]
	s_nop 11
	v_add_co_u32_e32 v8, vcc, s0, v180
	s_nop 1
	v_addc_co_u32_e32 v9, vcc, 0, v181, vcc
	global_load_dwordx4 v[8:11], v[8:9], off offset:3072
	s_waitcnt vmcnt(0)
	v_fma_f32 v8, v8, s58, v100
	v_fma_f32 v9, v9, s58, v100
	s_nop 0
	v_mul_f32_e32 v12, 0x4b800000, v8
	v_cmp_gt_f32_e64 s[18:19], s11, v8
	v_cmp_gt_f32_e32 vcc, s11, v9
	s_nop 0
	v_cndmask_b32_e64 v8, v8, v12, s[18:19]
	v_rsq_f32_e32 v8, v8
	s_nop 0
	v_mul_f32_e32 v12, 0x45800000, v8
	v_cndmask_b32_e64 v8, v8, v12, s[18:19]
	v_mul_f32_e32 v8, 0x3e16c740, v8
	v_mul_f32_e32 v4, v8, v4
	v_cvt_pk_bf16_f32 v4, v4, s0
	ds_write_b16 v3, v4 offset:6512
	v_mul_f32_e32 v4, 0x4b800000, v9
	v_cndmask_b32_e32 v4, v9, v4, vcc
	v_rsq_f32_e32 v4, v4
	s_nop 0
	v_mul_f32_e32 v8, 0x45800000, v4
	v_cndmask_b32_e32 v4, v4, v8, vcc
	v_mul_f32_e32 v4, 0x3e16c740, v4
	v_mul_f32_e32 v4, v4, v5
	v_cvt_pk_bf16_f32 v4, v4, s0
	ds_write_b16 v3, v4 offset:13616
	v_fma_f32 v4, v10, s58, v100
	v_fma_f32 v5, v11, s58, v100
	s_nop 0
	v_mul_f32_e32 v8, 0x4b800000, v4
	v_cmp_gt_f32_e64 s[18:19], s11, v4
	v_cmp_gt_f32_e32 vcc, s11, v5
	s_nop 0
	v_cndmask_b32_e64 v4, v4, v8, s[18:19]
	v_rsq_f32_e32 v4, v4
	s_nop 0
	v_mul_f32_e32 v8, 0x45800000, v4
	v_cndmask_b32_e64 v4, v4, v8, s[18:19]
	v_mul_f32_e32 v4, 0x3e16c740, v4
	v_mul_f32_e32 v4, v4, v6
	v_cvt_pk_bf16_f32 v4, v4, s0
	ds_write_b16 v3, v4 offset:20720
	v_mul_f32_e32 v4, 0x4b800000, v5
	v_cndmask_b32_e32 v4, v5, v4, vcc
	v_rsq_f32_e32 v4, v4
	s_nop 0
	v_mul_f32_e32 v5, 0x45800000, v4
	v_cndmask_b32_e32 v4, v4, v5, vcc
	v_mul_f32_e32 v4, 0x3e16c740, v4
	v_mul_f32_e32 v4, v4, v7
	v_cvt_pk_bf16_f32 v4, v4, s0
	v_cmp_gt_i32_e32 vcc, s77, v1
	ds_write_b16 v3, v4 offset:27824
	s_and_saveexec_b64 s[0:1], vcc
	s_cbranch_execz .LBB0_1528
	v_ashrrev_i32_e32 v3, 1, v1
	s_mov_b32 s8, 0x2aaaaaab
	v_mul_hi_i32 v4, v3, s8
	v_lshrrev_b32_e32 v5, 31, v4
	v_ashrrev_i32_e32 v4, 1, v4
	v_add_u32_e32 v12, v4, v5
	v_mul_lo_u32 v4, v12, 12
	v_sub_u32_e32 v14, v3, v4
	v_ashrrev_i32_e32 v13, 31, v12
	v_lshl_add_u64 v[4:5], s[86:87], 0, v[12:13]
	v_ashrrev_i32_e32 v15, 31, v14
	v_mad_u64_u32 v[6:7], s[8:9], v4, 12, v[14:15]
	v_mad_i32_i24 v7, v5, 12, v7
	v_mov_b64_e32 v[4:5], s[50:51]
	v_mad_u64_u32 v[4:5], s[8:9], v6, s77, v[4:5]
	v_readlane_b32 s8, v255, 27
	v_readlane_b32 s9, v255, 28
	v_mov_b64_e32 v[16:17], s[52:53]
	s_mov_b32 s18, 0x10400
	v_lshl_add_u64 v[14:15], v[14:15], 0, s[8:9]
	v_mad_u64_u32 v[16:17], s[8:9], v14, s18, v[16:17]
	v_and_b32_e32 v18, 1, v1
	v_mad_i32_i24 v17, v15, s18, v17
	v_mad_i32_i24 v5, v7, s77, v5
	v_lshlrev_b32_e32 v108, 4, v18
	v_mov_b32_e32 v109, v2
	v_lshl_add_u64 v[14:15], s[86:87], 2, v[16:17]
	v_lshl_add_u64 v[8:9], v[4:5], 0, v[108:109]
	v_lshl_add_u64 v[14:15], v[12:13], 2, v[14:15]
	global_load_dwordx4 v[4:7], v[8:9], off offset:128
	s_nop 0
	global_load_dwordx4 v[8:11], v[8:9], off offset:160
	v_lshlrev_b32_e32 v12, 4, v12
	global_load_dword v115, v[14:15], off
	v_ashrrev_i32_e32 v13, 31, v12
	v_mov_b64_e32 v[14:15], 0x20000
	v_lshl_add_u64 v[100:101], v[12:13], 2, v[14:15]
	v_lshl_add_u64 v[12:13], s[54:55], 0, v[100:101]
	v_lshlrev_b32_e32 v102, 5, v18
	v_mov_b32_e32 v103, v2
	v_lshl_add_u64 v[100:101], s[56:57], 0, v[100:101]
	v_lshl_add_u64 v[16:17], v[12:13], 0, v[102:103]
	v_lshl_add_u64 v[104:105], v[100:101], 0, v[102:103]
	global_load_dwordx4 v[12:15], v[16:17], off
	s_nop 0
	global_load_dwordx4 v[16:19], v[16:17], off offset:16
	s_nop 0
	global_load_dwordx4 v[100:103], v[104:105], off
	s_nop 0
	global_load_dwordx4 v[104:107], v[104:105], off offset:16
	v_mul_lo_u32 v3, v3, s33
	v_add3_u32 v3, 0, v3, v108
	s_waitcnt vmcnt(6)
	v_lshlrev_b32_e32 v108, 16, v4
	s_waitcnt vmcnt(5)
	v_lshlrev_b32_e32 v112, 16, v8
	v_and_b32_e32 v113, 0xffff0000, v8
	s_waitcnt vmcnt(4)
	v_fmamk_f32 v115, v115, 0x3c2aaaab, v231
	v_mul_f32_e32 v116, 0x4b800000, v115
	v_cmp_gt_f32_e32 vcc, s11, v115
	v_lshlrev_b32_e32 v8, 16, v9
	v_and_b32_e32 v9, 0xffff0000, v9
	v_cndmask_b32_e32 v115, v115, v116, vcc
	v_rsq_f32_e32 v116, v115
	v_lshlrev_b32_e32 v114, 16, v10
	v_and_b32_e32 v115, 0xffff0000, v10
	v_lshlrev_b32_e32 v10, 16, v11
	v_mul_f32_e32 v117, 0x45800000, v116
	v_cndmask_b32_e32 v116, v116, v117, vcc
	v_mul_f32_e32 v116, 0x3e16c740, v116
	v_and_b32_e32 v11, 0xffff0000, v11
	s_waitcnt vmcnt(1)
	v_mul_f32 v102, v102, v116
	v_mul_f32 v103, v103, v116
	v_mul_f32 v100, v100, v116
	v_mul_f32 v101, v101, v116
	s_waitcnt vmcnt(0)
	v_mul_f32 v106, v106, v116
	v_mul_f32 v107, v107, v116
	v_mul_f32 v104, v104, v116
	v_mul_f32 v105, v105, v116
	v_and_b32_e32 v109, 0xffff0000, v4
	v_lshlrev_b32_e32 v4, 16, v5
	v_and_b32_e32 v5, 0xffff0000, v5
	v_lshlrev_b32_e32 v110, 16, v6
	v_and_b32_e32 v111, 0xffff0000, v6
	v_lshlrev_b32_e32 v6, 16, v7
	v_and_b32_e32 v7, 0xffff0000, v7
	v_mul_f32 v12, v12, v116
	v_mul_f32 v13, v13, v116
	v_mul_f32 v14, v14, v116
	v_mul_f32 v15, v15, v116
	v_mul_f32 v16, v16, v116
	v_mul_f32 v17, v17, v116
	v_mul_f32 v18, v18, v116
	v_mul_f32 v19, v19, v116
	v_mul_f32 v116, v100, v112
	v_mul_f32 v117, v101, v113
	v_mul_f32 v118, v102, v8
	v_mul_f32 v119, v103, v9
	v_mul_f32 v120, v104, v114
	v_mul_f32 v121, v105, v115
	v_mul_f32 v122, v106, v10
	v_mul_f32 v123, v107, v11
	v_mul_f32 v112, v12, v112
	v_mul_f32 v113, v13, v113
	v_mul_f32 v8, v14, v8
	v_mul_f32 v9, v15, v9
	v_mul_f32 v114, v16, v114
	v_mul_f32 v115, v17, v115
	v_mul_f32 v10, v18, v10
	v_mul_f32 v11, v19, v11
	v_fma_f32 v14, v14, v4, -v118
	v_fma_f32 v15, v15, v5, -v119
	v_fma_f32 v12, v12, v108, -v116
	v_fma_f32 v13, v13, v109, -v117
	v_fma_f32 v18, v18, v6, -v122
	v_fma_f32 v19, v19, v7, -v123
	v_fma_f32 v16, v16, v110, -v120
	v_fma_f32 v17, v17, v111, -v121
	v_fma_f32 v102, v102, v4, v8
	v_fma_f32 v103, v103, v5, v9
	v_fma_f32 v8, v100, v108, v112
	v_fma_f32 v9, v101, v109, v113
	v_fma_f32 v100, v106, v6, v10
	v_fma_f32 v101, v107, v7, v11
	v_fma_f32 v10, v104, v110, v114
	v_fma_f32 v11, v105, v111, v115
	v_cvt_pk_bf16_f32 v4, v12, v13
	v_cvt_pk_bf16_f32 v5, v14, v15
	v_cvt_pk_bf16_f32 v6, v16, v17
	v_cvt_pk_bf16_f32 v7, v18, v19
	v_cvt_pk_bf16_f32 v8, v8, v9
	v_cvt_pk_bf16_f32 v9, v102, v103
	v_cvt_pk_bf16_f32 v10, v10, v11
	v_cvt_pk_bf16_f32 v11, v100, v101
	ds_write_b128 v3, v[4:7] offset:512
	ds_write_b128 v3, v[8:11] offset:544

.LBB0_1667:
	s_or_b64 exec, exec, s[80:81]
	v_max_f32_e32 v3, v99, v99
	v_max_f32_e32 v4, v98, v98
	v_max_f32_e32 v3, v4, v3
	v_max3_f32 v3, v3, v100, v101
	v_max3_f32 v3, v3, v102, v103
	v_max3_f32 v3, v3, v104, v105
	v_max3_f32 v3, v3, v106, v107
	v_max3_f32 v3, v3, v108, v109
	v_max3_f32 v3, v3, v110, v111
	v_max3_f32 v3, v3, v112, v113
	v_max3_f32 v3, v3, v82, v83
	v_max3_f32 v3, v3, v84, v85
	v_max3_f32 v3, v3, v86, v87
	v_max3_f32 v3, v3, v88, v89
	v_and_b32_e32 v5, 64, v236
	v_max3_f32 v3, v3, v90, v91
	v_xor_b32_e32 v4, 32, v236
	v_add_u32_e32 v5, 64, v5
	v_max3_f32 v3, v3, v92, v93
	v_cmp_lt_i32_e32 vcc, v4, v5
	v_max3_f32 v3, v3, v94, v95
	v_max3_f32 v3, v3, v96, v97
	v_cndmask_b32_e32 v4, v236, v4, vcc
	v_lshlrev_b32_e32 v4, 2, v4
	ds_bpermute_b32 v4, v4, v3
	s_waitcnt lgkmcnt(0)
	v_max3_f32 v3, v186, v3, v4
	v_sub_f32_e32 v4, v186, v3
	v_exp_f32_e32 v4, v4
	s_nop 0
	v_cmp_neq_f32_e32 vcc, 1.0, v4
	s_cbranch_vccz .LBB0_1669
	v_mul_f32 v80, v80, v4
	v_mul_f32 v81, v81, v4
	v_mul_f32 v78, v78, v4
	v_mul_f32 v79, v79, v4
	v_mul_f32 v76, v76, v4
	v_mul_f32 v77, v77, v4
	v_mul_f32 v74, v74, v4
	v_mul_f32 v75, v75, v4
	v_mul_f32 v72, v72, v4
	v_mul_f32 v73, v73, v4
	v_mul_f32 v70, v70, v4
	v_mul_f32 v71, v71, v4
	v_mul_f32 v68, v68, v4
	v_mul_f32 v69, v69, v4
	v_mul_f32 v66, v66, v4
	v_mul_f32 v67, v67, v4
	v_mul_f32 v64, v64, v4
	v_mul_f32 v65, v65, v4
	v_mul_f32 v62, v62, v4
	v_mul_f32 v63, v63, v4
	v_mul_f32 v60, v60, v4
	v_mul_f32 v61, v61, v4
	v_mul_f32 v58, v58, v4
	v_mul_f32 v59, v59, v4
	v_mul_f32 v56, v56, v4
	v_mul_f32 v57, v57, v4
	v_mul_f32 v54, v54, v4
	v_mul_f32 v55, v55, v4
	v_mul_f32 v52, v52, v4
	v_mul_f32 v53, v53, v4
	v_mul_f32 v50, v50, v4
	v_mul_f32 v51, v51, v4

.LBB0_1689:
	s_and_saveexec_b64 s[0:1], s[20:21]
	s_cbranch_execz .LBB0_1601
	v_and_b32_e32 v3, 64, v236
	v_xor_b32_e32 v1, 32, v236
	v_add_u32_e32 v3, 64, v3
	v_cmp_lt_i32_e32 vcc, v1, v3
	s_nop 1
	v_cndmask_b32_e32 v1, v236, v1, vcc
	v_lshlrev_b32_e32 v1, 2, v1
	ds_bpermute_b32 v1, v1, v185
	s_and_b64 exec, exec, s[14:15]
	s_cbranch_execz .LBB0_1601
	s_lshl_b32 s8, s64, 11
	s_add_u32 s8, s95, s8
	s_addc_u32 s9, s97, 0
	s_lshl_b32 s14, s93, 7
	s_waitcnt lgkmcnt(0)
	v_add_f32_e32 v1, v185, v1
	s_add_u32 s8, s8, s14
	v_div_scale_f32 v3, s[14:15], v1, v1, 1.0
	v_rcp_f32_e32 v4, v3
	s_addc_u32 s9, s9, 0
	v_lshlrev_b32_e32 v8, 1, v172
	v_mov_b32_e32 v9, v2
	v_fma_f32 v5, -v3, v4, 1.0
	v_fmac_f32_e32 v4, v5, v4
	v_div_scale_f32 v5, vcc, 1.0, v1, 1.0
	v_mul_f32_e32 v6, v5, v4
	v_fma_f32 v7, -v3, v6, v5
	v_fmac_f32_e32 v6, v7, v4
	v_fma_f32 v3, -v3, v6, v5
	v_div_fmas_f32 v3, v3, v4, v6
	v_lshlrev_b64 v[6:7], 11, v[162:163]
	v_div_fixup_f32 v4, v3, v1, 1.0
	v_lshl_add_u64 v[6:7], s[8:9], 0, v[6:7]
	v_lshl_add_u64 v[6:7], v[6:7], 0, v[8:9]
	v_mul_f32 v8, v66, v4
	v_mul_f32 v9, v67, v4
	v_mul_f32 v10, v68, v4
	v_mul_f32 v11, v69, v4
	v_cvt_pk_bf16_f32 v8, v8, v9
	v_cvt_pk_bf16_f32 v9, v10, v11
	global_store_dwordx2 v[6:7], v[8:9], off
	v_mul_f32 v8, v70, v4
	v_mul_f32 v9, v71, v4
	v_mul_f32 v10, v72, v4
	v_mul_f32 v11, v73, v4
	v_cvt_pk_bf16_f32 v8, v8, v9
	v_cvt_pk_bf16_f32 v9, v10, v11
	global_store_dwordx2 v[6:7], v[8:9], off offset:16
	v_mul_f32 v8, v74, v4
	v_mul_f32 v9, v75, v4
	v_mul_f32 v10, v76, v4
	v_mul_f32 v11, v77, v4
	v_cvt_pk_bf16_f32 v8, v8, v9
	v_cvt_pk_bf16_f32 v9, v10, v11
	global_store_dwordx2 v[6:7], v[8:9], off offset:32
	v_mul_f32 v8, v78, v4
	v_mul_f32 v9, v79, v4
	v_mul_f32 v10, v80, v4
	v_mul_f32 v11, v81, v4
	v_cvt_pk_bf16_f32 v8, v8, v9
	v_cvt_pk_bf16_f32 v9, v10, v11
	global_store_dwordx2 v[6:7], v[8:9], off offset:48
	v_mul_f32 v8, v50, v4
	v_mul_f32 v9, v51, v4
	v_mul_f32 v10, v52, v4
	v_mul_f32 v11, v53, v4
	v_cvt_pk_bf16_f32 v8, v8, v9
	v_cvt_pk_bf16_f32 v9, v10, v11
	global_store_dwordx2 v[6:7], v[8:9], off offset:64
	v_mul_f32 v8, v54, v4
	v_mul_f32 v9, v55, v4
	v_mul_f32 v10, v56, v4
	v_mul_f32 v11, v57, v4
	v_cvt_pk_bf16_f32 v8, v8, v9
	v_cvt_pk_bf16_f32 v9, v10, v11
	global_store_dwordx2 v[6:7], v[8:9], off offset:80
	v_mul_f32 v8, v58, v4
	v_mul_f32 v9, v59, v4
	v_mul_f32 v10, v60, v4
	v_mul_f32 v11, v61, v4
	v_cvt_pk_bf16_f32 v8, v8, v9
	v_cvt_pk_bf16_f32 v9, v10, v11
	global_store_dwordx2 v[6:7], v[8:9], off offset:96
	v_mul_f32 v8, v62, v4
	v_mul_f32 v9, v63, v4
	v_mul_f32 v5, v65, v4
	v_mul_f32 v4, v64, v4
	v_cvt_pk_bf16_f32 v8, v8, v9
	v_cvt_pk_bf16_f32 v9, v4, v5
	global_store_dwordx2 v[6:7], v[8:9], off offset:112
	s_branch .LBB0_1601

.LBB0_1747:
	s_mul_hi_i32 s0, s8, 0x2aaaaaab
	s_lshr_b32 s1, s0, 31
	s_ashr_i32 s9, s0, 1
	s_add_i32 s9, s9, s1
	s_mul_i32 s0, s9, 12
	s_sub_i32 s0, s8, s0
	v_add_u32_e32 v4, s0, v1
	v_ashrrev_i32_e32 v5, 31, v4
	v_mad_i64_i32 v[84:85], s[18:19], s9, v234, v[4:5]
	s_mov_b64 s[18:19], 0x60
	v_lshlrev_b64 v[86:87], 3, v[84:85]
	v_lshl_add_u64 v[76:77], v[84:85], 0, s[18:19]
	v_lshl_add_u64 v[4:5], s[14:15], 0, v[86:87]
	v_lshlrev_b64 v[78:79], 3, v[76:77]
	s_barrier
	global_load_dword v22, v[4:5], off
	v_lshl_add_u64 v[4:5], s[14:15], 0, v[78:79]
	global_load_dword v90, v[4:5], off
	s_mov_b32 s1, 0xf149f2ca
	v_lshl_add_u64 v[86:87], s[6:7], 0, v[86:87]
	s_mov_b64 s[18:19], 0xc0
	v_lshl_add_u64 v[72:73], v[84:85], 0, s[18:19]
	v_lshl_add_u64 v[78:79], s[6:7], 0, v[78:79]
	v_lshlrev_b64 v[74:75], 3, v[72:73]
	v_lshl_add_u64 v[4:5], s[14:15], 0, v[74:75]
	s_mov_b64 s[18:19], 0x120
	v_lshl_add_u64 v[74:75], s[6:7], 0, v[74:75]
	v_lshl_add_u64 v[68:69], v[84:85], 0, s[18:19]
	v_lshlrev_b64 v[70:71], 3, v[68:69]
	global_load_dword v91, v[4:5], off
	s_mov_b64 s[18:19], 0x180
	v_lshl_add_u64 v[64:65], v[84:85], 0, s[18:19]
	v_lshlrev_b64 v[66:67], 3, v[64:65]
	s_mov_b64 s[18:19], 0x1e0
	v_lshl_add_u64 v[60:61], v[84:85], 0, s[18:19]
	v_lshlrev_b64 v[62:63], 3, v[60:61]
	s_mov_b64 s[18:19], 0x240
	v_lshl_add_u64 v[56:57], v[84:85], 0, s[18:19]
	s_mov_b64 s[18:19], 0x2a0
	v_lshlrev_b64 v[58:59], 3, v[56:57]
	v_lshl_add_u64 v[52:53], v[84:85], 0, s[18:19]
	s_mov_b64 s[18:19], 0x300
	v_lshlrev_b64 v[54:55], 3, v[52:53]
	v_lshl_add_u64 v[48:49], v[84:85], 0, s[18:19]
	s_mov_b64 s[18:19], 0x360
	v_lshlrev_b64 v[50:51], 3, v[48:49]
	v_lshl_add_u64 v[44:45], v[84:85], 0, s[18:19]
	s_mov_b64 s[18:19], 0x3c0
	v_lshlrev_b64 v[46:47], 3, v[44:45]
	v_lshl_add_u64 v[40:41], v[84:85], 0, s[18:19]
	s_mov_b64 s[18:19], 0x420
	v_lshlrev_b64 v[42:43], 3, v[40:41]
	v_lshl_add_u64 v[36:37], v[84:85], 0, s[18:19]
	s_mov_b64 s[18:19], 0x480
	v_lshlrev_b64 v[38:39], 3, v[36:37]
	v_lshl_add_u64 v[32:33], v[84:85], 0, s[18:19]
	s_mov_b64 s[18:19], 0x4e0
	v_lshlrev_b64 v[34:35], 3, v[32:33]
	v_lshl_add_u64 v[28:29], v[84:85], 0, s[18:19]
	v_lshlrev_b64 v[30:31], 3, v[28:29]
	s_mov_b64 s[18:19], 0x540
	v_lshl_add_u64 v[24:25], v[84:85], 0, s[18:19]
	v_lshlrev_b64 v[26:27], 3, v[24:25]
	s_mov_b64 s[18:19], 0x5a0
	v_lshlrev_b64 v[76:77], 10, v[76:77]
	v_lshl_add_u64 v[76:77], v[16:17], 0, v[76:77]
	v_lshlrev_b64 v[72:73], 10, v[72:73]
	v_lshl_add_u64 v[72:73], v[16:17], 0, v[72:73]
	v_lshlrev_b64 v[68:69], 10, v[68:69]
	v_lshl_add_u64 v[68:69], v[16:17], 0, v[68:69]
	v_lshlrev_b64 v[64:65], 10, v[64:65]
	v_lshl_add_u64 v[64:65], v[16:17], 0, v[64:65]
	v_lshlrev_b64 v[60:61], 10, v[60:61]
	v_lshl_add_u64 v[60:61], v[16:17], 0, v[60:61]
	v_lshlrev_b64 v[56:57], 10, v[56:57]
	v_lshl_add_u64 v[56:57], v[16:17], 0, v[56:57]
	v_lshlrev_b64 v[52:53], 10, v[52:53]
	v_lshl_add_u64 v[52:53], v[16:17], 0, v[52:53]
	v_lshlrev_b64 v[48:49], 10, v[48:49]
	v_lshl_add_u64 v[48:49], v[16:17], 0, v[48:49]
	v_lshlrev_b64 v[44:45], 10, v[44:45]
	v_lshl_add_u64 v[44:45], v[16:17], 0, v[44:45]
	v_lshlrev_b64 v[40:41], 10, v[40:41]
	v_lshl_add_u64 v[40:41], v[16:17], 0, v[40:41]
	v_lshlrev_b64 v[36:37], 10, v[36:37]
	v_lshl_add_u64 v[36:37], v[16:17], 0, v[36:37]
	v_lshlrev_b64 v[32:33], 10, v[32:33]
	v_lshl_add_u64 v[32:33], v[16:17], 0, v[32:33]
	v_lshlrev_b64 v[28:29], 10, v[28:29]
	v_lshl_add_u64 v[28:29], v[16:17], 0, v[28:29]
	v_lshlrev_b64 v[24:25], 10, v[24:25]
	v_lshl_add_u64 v[24:25], v[16:17], 0, v[24:25]
	s_lshl_b32 s0, s0, 6
	s_waitcnt vmcnt(1)
	v_max3_f32 v6, v22, s1, v90
	s_mov_b32 s1, 0x34cd0000
	v_add_co_u32_e32 v86, vcc, s1, v86
	s_nop 1
	v_addc_co_u32_e32 v87, vcc, 0, v87, vcc
	v_add_co_u32_e32 v78, vcc, s1, v78
	global_load_dword v86, v[86:87], off offset:4
	s_nop 0
	v_addc_co_u32_e32 v79, vcc, 0, v79, vcc
	v_add_co_u32_e32 v74, vcc, s1, v74
	global_load_dword v78, v[78:79], off offset:4
	s_nop 0
	v_addc_co_u32_e32 v75, vcc, 0, v75, vcc
	global_load_dword v74, v[74:75], off offset:4
	v_lshl_add_u64 v[4:5], s[14:15], 0, v[70:71]
	v_lshl_add_u64 v[70:71], s[6:7], 0, v[70:71]
	v_add_co_u32_e32 v70, vcc, s1, v70
	global_load_dword v92, v[4:5], off
	s_nop 0
	v_addc_co_u32_e32 v71, vcc, 0, v71, vcc
	global_load_dword v70, v[70:71], off offset:4
	v_lshl_add_u64 v[4:5], s[14:15], 0, v[66:67]
	v_lshl_add_u64 v[66:67], s[6:7], 0, v[66:67]
	v_add_co_u32_e32 v66, vcc, s1, v66
	global_load_dword v93, v[4:5], off
	s_nop 0
	v_addc_co_u32_e32 v67, vcc, 0, v67, vcc
	global_load_dword v66, v[66:67], off offset:4
	v_lshl_add_u64 v[4:5], s[14:15], 0, v[62:63]
	v_lshl_add_u64 v[62:63], s[6:7], 0, v[62:63]
	v_add_co_u32_e32 v62, vcc, s1, v62
	global_load_dword v94, v[4:5], off
	s_nop 0
	v_addc_co_u32_e32 v63, vcc, 0, v63, vcc
	global_load_dword v62, v[62:63], off offset:4
	v_lshl_add_u64 v[4:5], s[14:15], 0, v[58:59]
	global_load_dword v95, v[4:5], off
	v_lshl_add_u64 v[4:5], s[14:15], 0, v[54:55]
	global_load_dword v96, v[4:5], off
	v_lshl_add_u64 v[4:5], s[14:15], 0, v[50:51]
	global_load_dword v97, v[4:5], off
	v_lshl_add_u64 v[4:5], s[14:15], 0, v[46:47]
	global_load_dword v83, v[4:5], off
	v_lshl_add_u64 v[4:5], s[14:15], 0, v[42:43]
	global_load_dword v82, v[4:5], off
	v_lshl_add_u64 v[4:5], s[14:15], 0, v[38:39]
	global_load_dword v81, v[4:5], off
	v_lshl_add_u64 v[4:5], s[14:15], 0, v[34:35]
	global_load_dword v80, v[4:5], off
	v_lshl_add_u64 v[4:5], s[14:15], 0, v[30:31]
	global_load_dword v23, v[4:5], off
	v_lshl_add_u64 v[4:5], s[14:15], 0, v[26:27]
	global_load_dword v21, v[4:5], off
	v_lshl_add_u64 v[4:5], v[84:85], 0, s[18:19]
	v_lshlrev_b64 v[84:85], 10, v[84:85]
	v_lshl_add_u64 v[84:85], v[16:17], 0, v[84:85]
	v_lshl_add_u64 v[58:59], s[6:7], 0, v[58:59]
	v_add_co_u32_e32 v58, vcc, s1, v58
	v_lshl_add_u64 v[54:55], s[6:7], 0, v[54:55]
	s_nop 0
	v_addc_co_u32_e32 v59, vcc, 0, v59, vcc
	v_add_co_u32_e32 v54, vcc, s1, v54
	v_lshl_add_u64 v[50:51], s[6:7], 0, v[50:51]
	s_nop 0
	v_addc_co_u32_e32 v55, vcc, 0, v55, vcc
	v_add_co_u32_e32 v50, vcc, s1, v50
	v_lshl_add_u64 v[46:47], s[6:7], 0, v[46:47]
	s_nop 0
	v_addc_co_u32_e32 v51, vcc, 0, v51, vcc
	v_add_co_u32_e32 v46, vcc, s1, v46
	v_lshl_add_u64 v[42:43], s[6:7], 0, v[42:43]
	s_nop 0
	v_addc_co_u32_e32 v47, vcc, 0, v47, vcc
	v_add_co_u32_e32 v42, vcc, s1, v42
	v_lshl_add_u64 v[38:39], s[6:7], 0, v[38:39]
	s_nop 0
	v_addc_co_u32_e32 v43, vcc, 0, v43, vcc
	v_add_co_u32_e32 v38, vcc, s1, v38
	v_lshl_add_u64 v[34:35], s[6:7], 0, v[34:35]
	s_nop 0
	v_addc_co_u32_e32 v39, vcc, 0, v39, vcc
	v_add_co_u32_e32 v34, vcc, s1, v34
	v_lshl_add_u64 v[30:31], s[6:7], 0, v[30:31]
	s_nop 0
	v_addc_co_u32_e32 v35, vcc, 0, v35, vcc
	v_add_co_u32_e32 v30, vcc, s1, v30
	v_lshl_add_u64 v[26:27], s[6:7], 0, v[26:27]
	s_waitcnt vmcnt(14)
	v_max3_f32 v6, v6, v91, v92
	v_addc_co_u32_e32 v31, vcc, 0, v31, vcc
	v_add_co_u32_e32 v26, vcc, s1, v26
	s_waitcnt vmcnt(10)
	v_max3_f32 v6, v6, v93, v94
	v_addc_co_u32_e32 v27, vcc, 0, v27, vcc
	s_waitcnt vmcnt(7)
	v_max3_f32 v6, v6, v95, v96
	s_waitcnt vmcnt(5)
	v_max3_f32 v6, v6, v97, v83
	s_waitcnt vmcnt(3)
	v_max3_f32 v6, v6, v82, v81
	s_waitcnt vmcnt(1)
	v_max3_f32 v13, v6, v80, v23
	v_lshlrev_b64 v[6:7], 3, v[4:5]
	v_lshl_add_u64 v[88:89], s[14:15], 0, v[6:7]
	global_load_dword v11, v[88:89], off
	v_lshl_add_u64 v[6:7], s[6:7], 0, v[6:7]
	v_add_co_u32_e32 v6, vcc, s1, v6
	v_lshlrev_b64 v[4:5], 10, v[4:5]
	s_nop 0
	v_addc_co_u32_e32 v7, vcc, 0, v7, vcc
	v_lshl_add_u64 v[4:5], v[16:17], 0, v[4:5]
	s_ashr_i32 s1, s0, 31
	s_waitcnt vmcnt(0)
	v_max3_f32 v13, v13, v21, v11
	v_sub_f32_e32 v22, v22, v13
	v_exp_f32_e32 v88, v22
	v_sub_f32_e32 v23, v23, v13
	v_sub_f32_e32 v21, v21, v13
	v_sub_f32_e32 v11, v11, v13
	v_fma_f32 v89, v86, v88, 0
	global_load_dwordx4 v[84:87], v[84:85], off
	global_load_dwordx4 v[162:165], v[76:77], off
	global_load_dwordx4 v[166:169], v[72:73], off
	global_load_dwordx4 v[170:173], v[68:69], off
	global_load_dwordx4 v[174:177], v[64:65], off
	global_load_dwordx4 v[178:181], v[60:61], off
	global_load_dwordx4 v[182:185], v[56:57], off
	global_load_dwordx4 v[186:189], v[52:53], off
	global_load_dwordx4 v[190:193], v[48:49], off
	global_load_dwordx4 v[194:197], v[44:45], off
	global_load_dwordx4 v[204:207], v[40:41], off
	global_load_dwordx4 v[210:213], v[36:37], off
	global_load_dwordx4 v[214:217], v[32:33], off
	global_load_dwordx4 v[218:221], v[28:29], off
	global_load_dwordx4 v[222:225], v[24:25], off
	global_load_dwordx4 v[226:229], v[4:5], off
	global_load_dword v248, v[58:59], off offset:4
	global_load_dword v249, v[54:55], off offset:4
	global_load_dword v250, v[50:51], off offset:4
	global_load_dword v251, v[46:47], off offset:4
	global_load_dword v232, v[42:43], off offset:4
	global_load_dword v233, v[38:39], off offset:4
	global_load_dword v198, v[34:35], off offset:4
	global_load_dword v199, v[30:31], off offset:4
	global_load_dword v244, v[26:27], off offset:4
	global_load_dword v245, v[6:7], off offset:4
	v_mov_b32_e32 v22, 0
	s_waitcnt vmcnt(0)
	v_pk_fma_f32 v[86:87], v[86:87], v[88:89], 0 op_sel_hi:[1,0,0]
	v_pk_fma_f32 v[84:85], v[84:85], v[88:89], 0 op_sel_hi:[1,0,0]
	v_sub_f32_e32 v88, v90, v13
	v_exp_f32_e32 v88, v88
	s_nop 0
	v_fmac_f32_e32 v89, v88, v78
	s_nop 0
	v_fma_f32 v76, v162, v88, v84
	v_fma_f32 v77, v163, v88, v85
	v_sub_f32_e32 v84, v91, v13
	v_exp_f32_e32 v84, v84
	v_fma_f32 v78, v164, v88, v86
	v_fma_f32 v79, v165, v88, v87
	v_fmac_f32_e32 v89, v84, v74
	s_nop 0
	v_fma_f32 v72, v84, v166, v76
	v_fma_f32 v73, v84, v167, v77
	v_sub_f32_e32 v76, v92, v13
	v_exp_f32_e32 v76, v76
	v_fma_f32 v74, v84, v168, v78
	v_fma_f32 v75, v84, v169, v79
	v_fmac_f32_e32 v89, v76, v70
	s_nop 0
	v_fma_f32 v68, v76, v170, v72
	v_fma_f32 v69, v76, v171, v73
	v_sub_f32_e32 v72, v93, v13
	v_exp_f32_e32 v72, v72
	v_fma_f32 v70, v76, v172, v74
	v_fma_f32 v71, v76, v173, v75
	v_fmac_f32_e32 v89, v72, v66
	s_nop 0
	v_fma_f32 v64, v72, v174, v68
	v_fma_f32 v65, v72, v175, v69
	v_sub_f32_e32 v68, v94, v13
	v_exp_f32_e32 v68, v68
	v_fma_f32 v66, v72, v176, v70
	v_fma_f32 v67, v72, v177, v71
	v_fmac_f32_e32 v89, v68, v62
	s_nop 0
	v_fma_f32 v62, v68, v180, v66
	v_fma_f32 v63, v68, v181, v67
	v_fma_f32 v60, v68, v178, v64
	v_fma_f32 v61, v68, v179, v65
	v_sub_f32_e32 v64, v95, v13
	v_exp_f32_e32 v64, v64
	s_nop 0
	v_fma_f32 v56, v64, v182, v60
	v_fma_f32 v57, v64, v183, v61
	v_sub_f32_e32 v60, v96, v13
	v_fma_f32 v58, v64, v184, v62
	v_fma_f32 v59, v64, v185, v63
	v_exp_f32_e32 v65, v60
	s_nop 0
	v_mul_f32 v54, v64, v248
	v_mul_f32 v55, v65, v249
	s_nop 0
	v_add_f32_e32 v54, v89, v54
	v_add_f32_e32 v61, v54, v55
	v_mov_b32_e32 v60, v65
	s_nop 0
	v_fma_f32 v54, v60, v188, v58
	v_fma_f32 v55, v60, v189, v59
	v_fma_f32 v52, v60, v186, v56
	v_fma_f32 v53, v60, v187, v57
	v_sub_f32_e32 v56, v97, v13
	v_exp_f32_e32 v56, v56
	s_nop 0
	v_fma_f32 v48, v56, v190, v52
	v_fma_f32 v49, v56, v191, v53
	v_sub_f32_e32 v52, v83, v13
	v_fma_f32 v50, v56, v192, v54
	v_fma_f32 v51, v56, v193, v55
	v_exp_f32_e32 v57, v52
	s_nop 0
	v_mul_f32 v46, v56, v250
	v_mul_f32 v47, v57, v251
	s_nop 0
	v_add_f32_e32 v46, v61, v46
	v_add_f32_e32 v53, v46, v47
	v_mov_b32_e32 v52, v57
	s_nop 0
	v_fma_f32 v46, v52, v196, v50
	v_fma_f32 v47, v52, v197, v51
	v_fma_f32 v44, v52, v194, v48
	v_fma_f32 v45, v52, v195, v49
	v_sub_f32_e32 v48, v82, v13
	v_exp_f32_e32 v48, v48
	s_nop 0
	v_fma_f32 v40, v48, v204, v44
	v_fma_f32 v41, v48, v205, v45
	v_sub_f32_e32 v44, v81, v13
	v_fma_f32 v42, v48, v206, v46
	v_fma_f32 v43, v48, v207, v47
	v_exp_f32_e32 v49, v44
	s_nop 0
	v_mul_f32 v38, v48, v232
	v_mul_f32 v39, v49, v233
	s_nop 0
	v_add_f32_e32 v38, v53, v38
	v_add_f32_e32 v45, v38, v39
	v_mov_b32_e32 v44, v49
	s_nop 0
	v_fma_f32 v38, v44, v212, v42
	v_fma_f32 v39, v44, v213, v43
	v_fma_f32 v36, v44, v210, v40
	v_fma_f32 v37, v44, v211, v41
	v_sub_f32_e32 v40, v80, v13
	v_exp_f32_e32 v40, v40
	s_nop 0
	v_fma_f32 v34, v40, v216, v38
	v_fma_f32 v35, v40, v217, v39
	v_fma_f32 v32, v40, v214, v36
	v_fma_f32 v33, v40, v215, v37
	v_exp_f32_e32 v41, v23
	s_nop 0
	v_mul_f32 v30, v40, v198
	v_mul_f32 v31, v41, v199
	s_nop 0
	v_add_f32_e32 v23, v45, v30
	v_add_f32_e32 v23, v23, v31
	v_mov_b32_e32 v36, v41
	s_nop 0
	v_fma_f32 v30, v36, v220, v34
	v_fma_f32 v31, v36, v221, v35
	v_fma_f32 v28, v36, v218, v32
	v_fma_f32 v29, v36, v219, v33
	v_exp_f32_e32 v32, v21
	s_nop 0
	v_fma_f32 v26, v32, v224, v30
	v_fma_f32 v27, v32, v225, v31
	v_fma_f32 v24, v32, v222, v28
	v_fma_f32 v25, v32, v223, v29
	v_exp_f32_e32 v33, v11
	v_mov_b32_e32 v30, v22
	v_mov_b32_e32 v31, v22
	v_mul_f32 v6, v32, v244
	v_mul_f32 v7, v33, v245
	s_nop 0
	v_add_f32_e32 v6, v23, v6
	v_add_f32_e32 v11, v6, v7
	v_div_scale_f32 v13, s[18:19], v11, v11, 1.0
	v_rcp_f32_e32 v21, v13
	v_mov_b32_e32 v28, v33
	s_mov_b32 s18, -4
	v_fma_f32 v23, -v13, v21, 1.0
	v_fmac_f32_e32 v21, v23, v21
	v_div_scale_f32 v23, vcc, 1.0, v11, 1.0
	s_nop 0
	v_fma_f32 v4, v28, v226, v24
	v_fma_f32 v5, v28, v227, v25
	v_mul_f32_e32 v24, v23, v21
	v_fma_f32 v25, -v13, v24, v23
	v_fmac_f32_e32 v24, v25, v21
	v_fma_f32 v13, -v13, v24, v23
	v_div_fmas_f32 v13, v13, v21, v24
	v_fma_f32 v6, v28, v228, v26
	v_fma_f32 v7, v28, v229, v27
	v_div_fixup_f32 v24, v13, v11, 1.0
	v_mul_f32 v6, v6, v24
	v_mul_f32 v7, v7, v24
	v_mul_f32 v4, v4, v24
	v_mul_f32 v5, v5, v24
	v_add_u32_e32 v11, v8, v10
	ds_write_b128 v11, v[4:7]
	v_lshl_add_u64 v[24:25], s[0:1], 2, v[18:19]
	s_mov_b32 s100, 0xffffb800
	s_mov_b32 s101, -1
	v_lshl_add_u64 v[194:195], v[24:25], 0, s[100:101]
	s_mov_b32 s100, 0x2400
	s_mov_b32 s101, 0
	global_load_dword v162, v[194:195], off offset:-3072
	global_load_dword v163, v[194:195], off
	global_load_dword v164, v[194:195], off offset:3072
	v_lshl_add_u64 v[194:195], v[194:195], 0, s[100:101]
	global_load_dword v165, v[194:195], off offset:-3072
	global_load_dword v166, v[194:195], off
	global_load_dword v167, v[194:195], off offset:3072
	v_lshl_add_u64 v[194:195], v[194:195], 0, s[100:101]
	global_load_dword v168, v[194:195], off offset:-3072
	global_load_dword v169, v[194:195], off
	global_load_dword v170, v[194:195], off offset:3072
	v_lshl_add_u64 v[194:195], v[194:195], 0, s[100:101]
	global_load_dword v171, v[194:195], off offset:-3072
	global_load_dword v172, v[194:195], off
	global_load_dword v173, v[194:195], off offset:3072
	v_lshl_add_u64 v[194:195], v[194:195], 0, s[100:101]
	global_load_dword v174, v[194:195], off offset:-3072
	global_load_dword v175, v[194:195], off
	global_load_dword v176, v[194:195], off offset:3072
	v_lshl_add_u64 v[194:195], v[194:195], 0, s[100:101]
	global_load_dword v177, v[194:195], off offset:-3072
	global_load_dword v178, v[194:195], off
	global_load_dword v179, v[194:195], off offset:3072
	v_lshl_add_u64 v[194:195], v[194:195], 0, s[100:101]
	global_load_dword v180, v[194:195], off offset:-3072
	global_load_dword v181, v[194:195], off
	global_load_dword v182, v[194:195], off offset:3072
	v_lshl_add_u64 v[194:195], v[194:195], 0, s[100:101]
	global_load_dword v183, v[194:195], off offset:-3072
	global_load_dword v184, v[194:195], off
	global_load_dword v185, v[194:195], off offset:3072
	v_lshl_add_u64 v[194:195], v[194:195], 0, s[100:101]
	global_load_dword v186, v[194:195], off offset:-3072
	global_load_dword v187, v[194:195], off
	global_load_dword v188, v[194:195], off offset:3072
	v_lshl_add_u64 v[194:195], v[194:195], 0, s[100:101]
	global_load_dword v189, v[194:195], off offset:-3072
	global_load_dword v190, v[194:195], off
	global_load_dword v191, v[194:195], off offset:3072
	v_lshl_add_u64 v[194:195], v[194:195], 0, s[100:101]
	global_load_dword v192, v[194:195], off offset:-3072
	global_load_dword v193, v[194:195], off
	v_mov_b32_e32 v11, v12
	v_mov_b32_e32 v23, v22
	v_mov_b32_e32 v26, v22
	v_mov_b32_e32 v27, v22
	v_mov_b32_e32 v28, v22
	v_mov_b32_e32 v29, v22
	s_waitcnt lgkmcnt(0)
	s_barrier
.LBB0_1748:
	s_waitcnt vmcnt(0)
	s_nop 0
	v_mov_b32_e32 v40, v162
	s_nop 0
	v_mov_b32_e32 v42, v163
	s_nop 0
	v_mov_b32_e32 v44, v164
	v_mov_b32_e32 v46, v165
	ds_read_b128 v[32:35], v11
	ds_read_b128 v[4:7], v11 offset:16
	ds_read_b128 v[36:39], v11 offset:1024
	s_waitcnt lgkmcnt(2)
	v_mov_b32_e32 v48, v32
	s_waitcnt lgkmcnt(0)
	v_mov_b32_e32 v49, v36
	v_mov_b32_e32 v36, v33
	v_mul_f32 v32, v42, v36
	v_mul_f32 v33, v42, v37
	v_mov_b32_e32 v37, v38
	v_mov_b32_e32 v38, v35
	v_mov_b32_e32 v36, v34
	v_fma_f32 v32, v40, v48, v32
	v_fma_f32 v33, v40, v49, v33
	v_mul_f32 v34, v46, v38
	v_mul_f32 v35, v46, v39
	v_fma_f32 v34, v44, v36, v34
	v_fma_f32 v35, v44, v37, v35
	v_add_f32 v32, v32, v34
	v_add_f32 v33, v33, v35
	s_nop 0
	v_add_f32 v26, v26, v32
	v_add_f32 v27, v27, v33
	ds_read_b128 v[32:35], v11 offset:2048
	ds_read_b128 v[36:39], v11 offset:3072
	s_waitcnt lgkmcnt(1)
	v_mov_b32_e32 v48, v32
	s_waitcnt lgkmcnt(0)
	v_mov_b32_e32 v49, v36
	v_mov_b32_e32 v36, v33
	v_mul_f32 v32, v42, v36
	v_mul_f32 v33, v42, v37
	v_mov_b32_e32 v37, v38
	v_mov_b32_e32 v38, v35
	v_mov_b32_e32 v36, v34
	v_mul_f32 v34, v46, v38
	v_mul_f32 v35, v46, v39
	v_fma_f32 v32, v40, v48, v32
	v_fma_f32 v33, v40, v49, v33
	v_fma_f32 v34, v44, v36, v34
	v_fma_f32 v35, v44, v37, v35
	v_add_f32 v32, v32, v34
	v_add_f32 v33, v33, v35
	s_nop 0
	v_add_f32 v28, v28, v32
	v_add_f32 v29, v29, v33
	ds_read_b128 v[32:35], v11 offset:4096
	ds_read_b128 v[36:39], v11 offset:5120
	s_waitcnt lgkmcnt(1)
	v_mov_b32_e32 v48, v32
	s_waitcnt lgkmcnt(0)
	v_mov_b32_e32 v49, v36
	v_mov_b32_e32 v36, v33
	v_mul_f32 v32, v42, v36
	v_mul_f32 v33, v42, v37
	v_mov_b32_e32 v37, v38
	v_mov_b32_e32 v38, v35
	v_mov_b32_e32 v36, v34
	v_mul_f32 v34, v46, v38
	v_mul_f32 v35, v46, v39
	v_fma_f32 v32, v40, v48, v32
	v_fma_f32 v33, v40, v49, v33
	v_fma_f32 v34, v44, v36, v34
	v_fma_f32 v35, v44, v37, v35
	v_add_f32 v32, v32, v34
	v_add_f32 v33, v33, v35
	v_mov_b32_e32 v41, v42
	v_add_f32 v30, v30, v32
	v_add_f32 v31, v31, v33
	ds_read_b128 v[32:35], v11 offset:6144
	v_mov_b32_e32 v45, v46
	v_mov_b32_e32 v43, v44
	s_waitcnt lgkmcnt(0)
	v_mul_f32_e32 v36, v42, v33
	v_fma_f32 v37, v41, v33, v36
	v_fma_f32 v36, v40, v32, v36
	v_mul_f32_e32 v32, v46, v35
	v_fma_f32 v38, v44, v34, v32
	v_fma_f32 v39, v45, v35, v32
	ds_read_b128 v[32:35], v11 offset:7168
	v_mov_b32_e32 v41, v46
	s_waitcnt lgkmcnt(0)
	v_mov_b32_e32 v44, v33
	v_mov_b32_e32 v33, v35
	v_mov_b32_e32 v45, v34
	v_mul_f32 v32, v40, v32
	v_mul_f32 v33, v41, v33
	s_nop 0
	v_fma_f32 v32, v42, v44, v32
	v_fma_f32 v33, v43, v45, v33
	v_mov_b32_e32 v44, v4
	v_mov_b32_e32 v37, v32
	v_mov_b32_e32 v39, v33
	v_add_f32 v32, v36, v38
	v_add_f32 v33, v37, v39
	s_nop 0
	v_add_f32 v22, v22, v32
	v_add_f32 v23, v23, v33
	s_nop 0
	v_mov_b32_e32 v32, v166
	s_nop 0
	v_mov_b32_e32 v34, v167
	s_nop 0
	v_mov_b32_e32 v38, v168
	v_mov_b32_e32 v36, v169
	ds_read_b128 v[40:43], v11 offset:1040
	s_waitcnt lgkmcnt(0)
	v_mov_b32_e32 v45, v40
	v_mov_b32_e32 v40, v5
	v_mul_f32 v4, v34, v40
	v_mul_f32 v5, v34, v41
	v_mov_b32_e32 v41, v42
	v_mov_b32_e32 v42, v7
	v_mov_b32_e32 v40, v6
	v_mul_f32 v6, v36, v42
	v_mul_f32 v7, v36, v43
	v_fma_f32 v4, v32, v44, v4
	v_fma_f32 v5, v32, v45, v5
	v_fma_f32 v6, v38, v40, v6
	v_fma_f32 v7, v38, v41, v7
	v_add_f32 v4, v4, v6
	v_add_f32 v5, v5, v7
	s_nop 0
	v_add_f32 v26, v26, v4
	v_add_f32 v27, v27, v5
	ds_read_b128 v[4:7], v11 offset:2064
	ds_read_b128 v[40:43], v11 offset:3088
	s_waitcnt lgkmcnt(1)
	v_mov_b32_e32 v44, v4
	s_waitcnt lgkmcnt(0)
	v_mov_b32_e32 v45, v40
	v_mov_b32_e32 v40, v5
	v_mul_f32 v4, v34, v40
	v_mul_f32 v5, v34, v41
	v_mov_b32_e32 v41, v42
	v_mov_b32_e32 v42, v7
	v_mov_b32_e32 v40, v6
	v_mul_f32 v6, v36, v42
	v_mul_f32 v7, v36, v43
	v_fma_f32 v4, v32, v44, v4
	v_fma_f32 v5, v32, v45, v5
	v_fma_f32 v6, v38, v40, v6
	v_fma_f32 v7, v38, v41, v7
	v_add_f32 v4, v4, v6
	v_add_f32 v5, v5, v7
	s_nop 0
	v_add_f32 v28, v28, v4
	v_add_f32 v29, v29, v5
	ds_read_b128 v[4:7], v11 offset:4112
	ds_read_b128 v[40:43], v11 offset:5136
	s_waitcnt lgkmcnt(1)
	v_mov_b32_e32 v44, v4
	s_waitcnt lgkmcnt(0)
	v_mov_b32_e32 v45, v40
	v_mov_b32_e32 v40, v5
	v_mul_f32 v4, v34, v40
	v_mul_f32 v5, v34, v41
	v_mov_b32_e32 v41, v42
	v_mov_b32_e32 v42, v7
	v_mov_b32_e32 v40, v6
	v_mul_f32 v6, v36, v42
	v_mul_f32 v7, v36, v43
	v_fma_f32 v4, v32, v44, v4
	v_fma_f32 v5, v32, v45, v5
	v_fma_f32 v6, v38, v40, v6
	v_fma_f32 v7, v38, v41, v7
	v_add_f32 v4, v4, v6
	v_add_f32 v5, v5, v7
	v_mov_b32_e32 v33, v34
	v_add_f32 v30, v30, v4
	v_add_f32 v31, v31, v5
	ds_read_b128 v[4:7], v11 offset:6160
	v_mov_b32_e32 v39, v36
	v_mov_b32_e32 v35, v38
	s_waitcnt lgkmcnt(0)
	v_mul_f32_e32 v40, v34, v5
	v_fma_f32 v41, v33, v5, v40
	v_fma_f32 v40, v32, v4, v40
	v_mul_f32_e32 v4, v36, v7
	v_fma_f32 v42, v38, v6, v4
	v_fma_f32 v43, v39, v7, v4
	ds_read_b128 v[4:7], v11 offset:7184
	v_mov_b32_e32 v33, v36
	v_add_u32_e32 v11, 32, v11
	s_waitcnt lgkmcnt(0)
	v_mov_b32_e32 v38, v5
	v_mov_b32_e32 v5, v7
	v_mov_b32_e32 v39, v6
	v_mul_f32 v4, v32, v4
	v_mul_f32 v5, v33, v5
	s_nop 0
	v_fma_f32 v4, v34, v38, v4
	v_fma_f32 v5, v35, v39, v5
	s_nop 0
	v_mov_b32_e32 v41, v4
	v_mov_b32_e32 v43, v5
	v_add_f32 v4, v40, v42
	v_add_f32 v5, v41, v43
	s_nop 0
	v_add_f32 v22, v22, v4
	v_add_f32 v23, v23, v5
	s_nop 0
	v_mov_b32_e32 v40, v170
	s_nop 0
	v_mov_b32_e32 v42, v171
	s_nop 0
	v_mov_b32_e32 v44, v172
	v_mov_b32_e32 v46, v173
	ds_read_b128 v[32:35], v11
	ds_read_b128 v[4:7], v11 offset:16
	ds_read_b128 v[36:39], v11 offset:1024
	s_waitcnt lgkmcnt(2)
	v_mov_b32_e32 v48, v32
	s_waitcnt lgkmcnt(0)
	v_mov_b32_e32 v49, v36
	v_mov_b32_e32 v36, v33
	v_mul_f32 v32, v42, v36
	v_mul_f32 v33, v42, v37
	v_mov_b32_e32 v37, v38
	v_mov_b32_e32 v38, v35
	v_mov_b32_e32 v36, v34
	v_fma_f32 v32, v40, v48, v32
	v_fma_f32 v33, v40, v49, v33
	v_mul_f32 v34, v46, v38
	v_mul_f32 v35, v46, v39
	v_fma_f32 v34, v44, v36, v34
	v_fma_f32 v35, v44, v37, v35
	v_add_f32 v32, v32, v34
	v_add_f32 v33, v33, v35
	s_nop 0
	v_add_f32 v26, v26, v32
	v_add_f32 v27, v27, v33
	ds_read_b128 v[32:35], v11 offset:2048
	ds_read_b128 v[36:39], v11 offset:3072
	s_waitcnt lgkmcnt(1)
	v_mov_b32_e32 v48, v32
	s_waitcnt lgkmcnt(0)
	v_mov_b32_e32 v49, v36
	v_mov_b32_e32 v36, v33
	v_mul_f32 v32, v42, v36
	v_mul_f32 v33, v42, v37
	v_mov_b32_e32 v37, v38
	v_mov_b32_e32 v38, v35
	v_mov_b32_e32 v36, v34
	v_mul_f32 v34, v46, v38
	v_mul_f32 v35, v46, v39
	v_fma_f32 v32, v40, v48, v32
	v_fma_f32 v33, v40, v49, v33
	v_fma_f32 v34, v44, v36, v34
	v_fma_f32 v35, v44, v37, v35
	v_add_f32 v32, v32, v34
	v_add_f32 v33, v33, v35
	s_nop 0
	v_add_f32 v28, v28, v32
	v_add_f32 v29, v29, v33
	ds_read_b128 v[32:35], v11 offset:4096
	ds_read_b128 v[36:39], v11 offset:5120
	s_waitcnt lgkmcnt(1)
	v_mov_b32_e32 v48, v32
	s_waitcnt lgkmcnt(0)
	v_mov_b32_e32 v49, v36
	v_mov_b32_e32 v36, v33
	v_mul_f32 v32, v42, v36
	v_mul_f32 v33, v42, v37
	v_mov_b32_e32 v37, v38
	v_mov_b32_e32 v38, v35
	v_mov_b32_e32 v36, v34
	v_mul_f32 v34, v46, v38
	v_mul_f32 v35, v46, v39
	v_fma_f32 v32, v40, v48, v32
	v_fma_f32 v33, v40, v49, v33
	v_fma_f32 v34, v44, v36, v34
	v_fma_f32 v35, v44, v37, v35
	v_add_f32 v32, v32, v34
	v_add_f32 v33, v33, v35
	v_mov_b32_e32 v41, v42
	v_add_f32 v30, v30, v32
	v_add_f32 v31, v31, v33
	ds_read_b128 v[32:35], v11 offset:6144
	v_mov_b32_e32 v45, v46
	v_mov_b32_e32 v43, v44
	s_waitcnt lgkmcnt(0)
	v_mul_f32_e32 v36, v42, v33
	v_fma_f32 v37, v41, v33, v36
	v_fma_f32 v36, v40, v32, v36
	v_mul_f32_e32 v32, v46, v35
	v_fma_f32 v38, v44, v34, v32
	v_fma_f32 v39, v45, v35, v32
	ds_read_b128 v[32:35], v11 offset:7168
	v_mov_b32_e32 v41, v46
	s_waitcnt lgkmcnt(0)
	v_mov_b32_e32 v44, v33
	v_mov_b32_e32 v33, v35
	v_mov_b32_e32 v45, v34
	v_mul_f32 v32, v40, v32
	v_mul_f32 v33, v41, v33
	s_nop 0
	v_fma_f32 v32, v42, v44, v32
	v_fma_f32 v33, v43, v45, v33
	v_mov_b32_e32 v44, v4
	v_mov_b32_e32 v37, v32
	v_mov_b32_e32 v39, v33
	v_add_f32 v32, v36, v38
	v_add_f32 v33, v37, v39
	s_nop 0
	v_add_f32 v22, v22, v32
	v_add_f32 v23, v23, v33
	s_nop 0
	v_mov_b32_e32 v32, v174
	s_nop 0
	v_mov_b32_e32 v34, v175
	s_nop 0
	v_mov_b32_e32 v38, v176
	v_mov_b32_e32 v36, v177
	ds_read_b128 v[40:43], v11 offset:1040
	s_waitcnt lgkmcnt(0)
	v_mov_b32_e32 v45, v40
	v_mov_b32_e32 v40, v5
	v_mul_f32 v4, v34, v40
	v_mul_f32 v5, v34, v41
	v_mov_b32_e32 v41, v42
	v_mov_b32_e32 v42, v7
	v_mov_b32_e32 v40, v6
	v_mul_f32 v6, v36, v42
	v_mul_f32 v7, v36, v43
	v_fma_f32 v4, v32, v44, v4
	v_fma_f32 v5, v32, v45, v5
	v_fma_f32 v6, v38, v40, v6
	v_fma_f32 v7, v38, v41, v7
	v_add_f32 v4, v4, v6
	v_add_f32 v5, v5, v7
	s_nop 0
	v_add_f32 v26, v26, v4
	v_add_f32 v27, v27, v5
	ds_read_b128 v[4:7], v11 offset:2064
	ds_read_b128 v[40:43], v11 offset:3088
	s_waitcnt lgkmcnt(1)
	v_mov_b32_e32 v44, v4
	s_waitcnt lgkmcnt(0)
	v_mov_b32_e32 v45, v40
	v_mov_b32_e32 v40, v5
	v_mul_f32 v4, v34, v40
	v_mul_f32 v5, v34, v41
	v_mov_b32_e32 v41, v42
	v_mov_b32_e32 v42, v7
	v_mov_b32_e32 v40, v6
	v_mul_f32 v6, v36, v42
	v_mul_f32 v7, v36, v43
	v_fma_f32 v4, v32, v44, v4
	v_fma_f32 v5, v32, v45, v5
	v_fma_f32 v6, v38, v40, v6
	v_fma_f32 v7, v38, v41, v7
	v_add_f32 v4, v4, v6
	v_add_f32 v5, v5, v7
	s_nop 0
	v_add_f32 v28, v28, v4
	v_add_f32 v29, v29, v5
	ds_read_b128 v[4:7], v11 offset:4112
	ds_read_b128 v[40:43], v11 offset:5136
	s_waitcnt lgkmcnt(1)
	v_mov_b32_e32 v44, v4
	s_waitcnt lgkmcnt(0)
	v_mov_b32_e32 v45, v40
	v_mov_b32_e32 v40, v5
	v_mul_f32 v4, v34, v40
	v_mul_f32 v5, v34, v41
	v_mov_b32_e32 v41, v42
	v_mov_b32_e32 v42, v7
	v_mov_b32_e32 v40, v6
	v_mul_f32 v6, v36, v42
	v_mul_f32 v7, v36, v43
	v_fma_f32 v4, v32, v44, v4
	v_fma_f32 v5, v32, v45, v5
	v_fma_f32 v6, v38, v40, v6
	v_fma_f32 v7, v38, v41, v7
	v_add_f32 v4, v4, v6
	v_add_f32 v5, v5, v7
	v_mov_b32_e32 v33, v34
	v_add_f32 v30, v30, v4
	v_add_f32 v31, v31, v5
	ds_read_b128 v[4:7], v11 offset:6160
	v_mov_b32_e32 v39, v36
	v_mov_b32_e32 v35, v38
	s_waitcnt lgkmcnt(0)
	v_mul_f32_e32 v40, v34, v5
	v_fma_f32 v41, v33, v5, v40
	v_fma_f32 v40, v32, v4, v40
	v_mul_f32_e32 v4, v36, v7
	v_fma_f32 v42, v38, v6, v4
	v_fma_f32 v43, v39, v7, v4
	ds_read_b128 v[4:7], v11 offset:7184
	v_mov_b32_e32 v33, v36
	v_add_u32_e32 v11, 32, v11
	s_waitcnt lgkmcnt(0)
	v_mov_b32_e32 v38, v5
	v_mov_b32_e32 v5, v7
	v_mov_b32_e32 v39, v6
	v_mul_f32 v4, v32, v4
	v_mul_f32 v5, v33, v5
	s_nop 0
	v_fma_f32 v4, v34, v38, v4
	v_fma_f32 v5, v35, v39, v5
	s_nop 0
	v_mov_b32_e32 v41, v4
	v_mov_b32_e32 v43, v5
	v_add_f32 v4, v40, v42
	v_add_f32 v5, v41, v43
	s_nop 0
	v_add_f32 v22, v22, v4
	v_add_f32 v23, v23, v5
	s_nop 0
	v_mov_b32_e32 v40, v178
	s_nop 0
	v_mov_b32_e32 v42, v179
	s_nop 0
	v_mov_b32_e32 v44, v180
	v_mov_b32_e32 v46, v181
	ds_read_b128 v[32:35], v11
	ds_read_b128 v[4:7], v11 offset:16
	ds_read_b128 v[36:39], v11 offset:1024
	s_waitcnt lgkmcnt(2)
	v_mov_b32_e32 v48, v32
	s_waitcnt lgkmcnt(0)
	v_mov_b32_e32 v49, v36
	v_mov_b32_e32 v36, v33
	v_mul_f32 v32, v42, v36
	v_mul_f32 v33, v42, v37
	v_mov_b32_e32 v37, v38
	v_mov_b32_e32 v38, v35
	v_mov_b32_e32 v36, v34
	v_fma_f32 v32, v40, v48, v32
	v_fma_f32 v33, v40, v49, v33
	v_mul_f32 v34, v46, v38
	v_mul_f32 v35, v46, v39
	v_fma_f32 v34, v44, v36, v34
	v_fma_f32 v35, v44, v37, v35
	v_add_f32 v32, v32, v34
	v_add_f32 v33, v33, v35
	s_nop 0
	v_add_f32 v26, v26, v32
	v_add_f32 v27, v27, v33
	ds_read_b128 v[32:35], v11 offset:2048
	ds_read_b128 v[36:39], v11 offset:3072
	s_waitcnt lgkmcnt(1)
	v_mov_b32_e32 v48, v32
	s_waitcnt lgkmcnt(0)
	v_mov_b32_e32 v49, v36
	v_mov_b32_e32 v36, v33
	v_mul_f32 v32, v42, v36
	v_mul_f32 v33, v42, v37
	v_mov_b32_e32 v37, v38
	v_mov_b32_e32 v38, v35
	v_mov_b32_e32 v36, v34
	v_mul_f32 v34, v46, v38
	v_mul_f32 v35, v46, v39
	v_fma_f32 v32, v40, v48, v32
	v_fma_f32 v33, v40, v49, v33
	v_fma_f32 v34, v44, v36, v34
	v_fma_f32 v35, v44, v37, v35
	v_add_f32 v32, v32, v34
	v_add_f32 v33, v33, v35
	s_nop 0
	v_add_f32 v28, v28, v32
	v_add_f32 v29, v29, v33
	ds_read_b128 v[32:35], v11 offset:4096
	ds_read_b128 v[36:39], v11 offset:5120
	s_waitcnt lgkmcnt(1)
	v_mov_b32_e32 v48, v32
	s_waitcnt lgkmcnt(0)
	v_mov_b32_e32 v49, v36
	v_mov_b32_e32 v36, v33
	v_mul_f32 v32, v42, v36
	v_mul_f32 v33, v42, v37
	v_mov_b32_e32 v37, v38
	v_mov_b32_e32 v38, v35
	v_mov_b32_e32 v36, v34
	v_mul_f32 v34, v46, v38
	v_mul_f32 v35, v46, v39
	v_fma_f32 v32, v40, v48, v32
	v_fma_f32 v33, v40, v49, v33
	v_fma_f32 v34, v44, v36, v34
	v_fma_f32 v35, v44, v37, v35
	v_add_f32 v32, v32, v34
	v_add_f32 v33, v33, v35
	v_mov_b32_e32 v41, v42
	v_add_f32 v30, v30, v32
	v_add_f32 v31, v31, v33
	ds_read_b128 v[32:35], v11 offset:6144
	v_mov_b32_e32 v45, v46
	v_mov_b32_e32 v43, v44
	s_waitcnt lgkmcnt(0)
	v_mul_f32_e32 v36, v42, v33
	v_fma_f32 v37, v41, v33, v36
	v_fma_f32 v36, v40, v32, v36
	v_mul_f32_e32 v32, v46, v35
	v_fma_f32 v38, v44, v34, v32
	v_fma_f32 v39, v45, v35, v32
	ds_read_b128 v[32:35], v11 offset:7168
	v_mov_b32_e32 v41, v46
	s_waitcnt lgkmcnt(0)
	v_mov_b32_e32 v44, v33
	v_mov_b32_e32 v33, v35
	v_mov_b32_e32 v45, v34
	v_mul_f32 v32, v40, v32
	v_mul_f32 v33, v41, v33
	s_nop 0
	v_fma_f32 v32, v42, v44, v32
	v_fma_f32 v33, v43, v45, v33
	v_mov_b32_e32 v44, v4
	v_mov_b32_e32 v37, v32
	v_mov_b32_e32 v39, v33
	v_add_f32 v32, v36, v38
	v_add_f32 v33, v37, v39
	s_nop 0
	v_add_f32 v22, v22, v32
	v_add_f32 v23, v23, v33
	s_nop 0
	v_mov_b32_e32 v32, v182
	s_nop 0
	v_mov_b32_e32 v34, v183
	s_nop 0
	v_mov_b32_e32 v38, v184
	v_mov_b32_e32 v36, v185
	ds_read_b128 v[40:43], v11 offset:1040
	s_waitcnt lgkmcnt(0)
	v_mov_b32_e32 v45, v40
	v_mov_b32_e32 v40, v5
	v_mul_f32 v4, v34, v40
	v_mul_f32 v5, v34, v41
	v_mov_b32_e32 v41, v42
	v_mov_b32_e32 v42, v7
	v_mov_b32_e32 v40, v6
	v_mul_f32 v6, v36, v42
	v_mul_f32 v7, v36, v43
	v_fma_f32 v4, v32, v44, v4
	v_fma_f32 v5, v32, v45, v5
	v_fma_f32 v6, v38, v40, v6
	v_fma_f32 v7, v38, v41, v7
	v_add_f32 v4, v4, v6
	v_add_f32 v5, v5, v7
	s_nop 0
	v_add_f32 v26, v26, v4
	v_add_f32 v27, v27, v5
	ds_read_b128 v[4:7], v11 offset:2064
	ds_read_b128 v[40:43], v11 offset:3088
	s_waitcnt lgkmcnt(1)
	v_mov_b32_e32 v44, v4
	s_waitcnt lgkmcnt(0)
	v_mov_b32_e32 v45, v40
	v_mov_b32_e32 v40, v5
	v_mul_f32 v4, v34, v40
	v_mul_f32 v5, v34, v41
	v_mov_b32_e32 v41, v42
	v_mov_b32_e32 v42, v7
	v_mov_b32_e32 v40, v6
	v_mul_f32 v6, v36, v42
	v_mul_f32 v7, v36, v43
	v_fma_f32 v4, v32, v44, v4
	v_fma_f32 v5, v32, v45, v5
	v_fma_f32 v6, v38, v40, v6
	v_fma_f32 v7, v38, v41, v7
	v_add_f32 v4, v4, v6
	v_add_f32 v5, v5, v7
	s_nop 0
	v_add_f32 v28, v28, v4
	v_add_f32 v29, v29, v5
	ds_read_b128 v[4:7], v11 offset:4112
	ds_read_b128 v[40:43], v11 offset:5136
	s_waitcnt lgkmcnt(1)
	v_mov_b32_e32 v44, v4
	s_waitcnt lgkmcnt(0)
	v_mov_b32_e32 v45, v40
	v_mov_b32_e32 v40, v5
	v_mul_f32 v4, v34, v40
	v_mul_f32 v5, v34, v41
	v_mov_b32_e32 v41, v42
	v_mov_b32_e32 v42, v7
	v_mov_b32_e32 v40, v6
	v_mul_f32 v6, v36, v42
	v_mul_f32 v7, v36, v43
	v_fma_f32 v4, v32, v44, v4
	v_fma_f32 v5, v32, v45, v5
	v_fma_f32 v6, v38, v40, v6
	v_fma_f32 v7, v38, v41, v7
	v_add_f32 v4, v4, v6
	v_add_f32 v5, v5, v7
	v_mov_b32_e32 v33, v34
	v_add_f32 v30, v30, v4
	v_add_f32 v31, v31, v5
	ds_read_b128 v[4:7], v11 offset:6160
	v_mov_b32_e32 v39, v36
	v_mov_b32_e32 v35, v38
	s_waitcnt lgkmcnt(0)
	v_mul_f32_e32 v40, v34, v5
	v_fma_f32 v41, v33, v5, v40
	v_fma_f32 v40, v32, v4, v40
	v_mul_f32_e32 v4, v36, v7
	v_fma_f32 v42, v38, v6, v4
	v_fma_f32 v43, v39, v7, v4
	ds_read_b128 v[4:7], v11 offset:7184
	v_mov_b32_e32 v33, v36
	v_add_u32_e32 v11, 32, v11
	s_waitcnt lgkmcnt(0)
	v_mov_b32_e32 v38, v5
	v_mov_b32_e32 v5, v7
	v_mov_b32_e32 v39, v6
	v_mul_f32 v4, v32, v4
	v_mul_f32 v5, v33, v5
	s_nop 0
	v_fma_f32 v4, v34, v38, v4
	v_fma_f32 v5, v35, v39, v5
	s_nop 0
	v_mov_b32_e32 v41, v4
	v_mov_b32_e32 v43, v5
	v_add_f32 v4, v40, v42
	v_add_f32 v5, v41, v43
	s_nop 0
	v_add_f32 v22, v22, v4
	v_add_f32 v23, v23, v5
	s_nop 0
	v_mov_b32_e32 v40, v186
	s_nop 0
	v_mov_b32_e32 v42, v187
	s_nop 0
	v_mov_b32_e32 v44, v188
	v_mov_b32_e32 v46, v189
	ds_read_b128 v[32:35], v11
	ds_read_b128 v[4:7], v11 offset:16
	ds_read_b128 v[36:39], v11 offset:1024
	s_waitcnt lgkmcnt(2)
	v_mov_b32_e32 v48, v32
	s_waitcnt lgkmcnt(0)
	v_mov_b32_e32 v49, v36
	v_mov_b32_e32 v36, v33
	v_mul_f32 v32, v42, v36
	v_mul_f32 v33, v42, v37
	v_mov_b32_e32 v37, v38
	v_mov_b32_e32 v38, v35
	v_mov_b32_e32 v36, v34
	v_fma_f32 v32, v40, v48, v32
	v_fma_f32 v33, v40, v49, v33
	v_mul_f32 v34, v46, v38
	v_mul_f32 v35, v46, v39
	v_fma_f32 v34, v44, v36, v34
	v_fma_f32 v35, v44, v37, v35
	v_add_f32 v32, v32, v34
	v_add_f32 v33, v33, v35
	s_nop 0
	v_add_f32 v26, v26, v32
	v_add_f32 v27, v27, v33
	ds_read_b128 v[32:35], v11 offset:2048
	ds_read_b128 v[36:39], v11 offset:3072
	s_waitcnt lgkmcnt(1)
	v_mov_b32_e32 v48, v32
	s_waitcnt lgkmcnt(0)
	v_mov_b32_e32 v49, v36
	v_mov_b32_e32 v36, v33
	v_mul_f32 v32, v42, v36
	v_mul_f32 v33, v42, v37
	v_mov_b32_e32 v37, v38
	v_mov_b32_e32 v38, v35
	v_mov_b32_e32 v36, v34
	v_mul_f32 v34, v46, v38
	v_mul_f32 v35, v46, v39
	v_fma_f32 v32, v40, v48, v32
	v_fma_f32 v33, v40, v49, v33
	v_fma_f32 v34, v44, v36, v34
	v_fma_f32 v35, v44, v37, v35
	v_add_f32 v32, v32, v34
	v_add_f32 v33, v33, v35
	s_nop 0
	v_add_f32 v28, v28, v32
	v_add_f32 v29, v29, v33
	ds_read_b128 v[32:35], v11 offset:4096
	ds_read_b128 v[36:39], v11 offset:5120
	s_waitcnt lgkmcnt(1)
	v_mov_b32_e32 v48, v32
	s_waitcnt lgkmcnt(0)
	v_mov_b32_e32 v49, v36
	v_mov_b32_e32 v36, v33
	v_mul_f32 v32, v42, v36
	v_mul_f32 v33, v42, v37
	v_mov_b32_e32 v37, v38
	v_mov_b32_e32 v38, v35
	v_mov_b32_e32 v36, v34
	v_mul_f32 v34, v46, v38
	v_mul_f32 v35, v46, v39
	v_fma_f32 v32, v40, v48, v32
	v_fma_f32 v33, v40, v49, v33
	v_fma_f32 v34, v44, v36, v34
	v_fma_f32 v35, v44, v37, v35
	v_add_f32 v32, v32, v34
	v_add_f32 v33, v33, v35
	v_mov_b32_e32 v41, v42
	v_add_f32 v30, v30, v32
	v_add_f32 v31, v31, v33
	ds_read_b128 v[32:35], v11 offset:6144
	v_mov_b32_e32 v45, v46
	v_mov_b32_e32 v43, v44
	s_waitcnt lgkmcnt(0)
	v_mul_f32_e32 v36, v42, v33
	v_fma_f32 v37, v41, v33, v36
	v_fma_f32 v36, v40, v32, v36
	v_mul_f32_e32 v32, v46, v35
	v_fma_f32 v38, v44, v34, v32
	v_fma_f32 v39, v45, v35, v32
	ds_read_b128 v[32:35], v11 offset:7168
	v_mov_b32_e32 v41, v46
	s_waitcnt lgkmcnt(0)
	v_mov_b32_e32 v44, v33
	v_mov_b32_e32 v33, v35
	v_mov_b32_e32 v45, v34
	v_mul_f32 v32, v40, v32
	v_mul_f32 v33, v41, v33
	s_nop 0
	v_fma_f32 v32, v42, v44, v32
	v_fma_f32 v33, v43, v45, v33
	v_mov_b32_e32 v44, v4
	v_mov_b32_e32 v37, v32
	v_mov_b32_e32 v39, v33
	v_add_f32 v32, v36, v38
	v_add_f32 v33, v37, v39
	s_nop 0
	v_add_f32 v22, v22, v32
	v_add_f32 v23, v23, v33
	s_nop 0
	v_mov_b32_e32 v32, v190
	s_nop 0
	v_mov_b32_e32 v34, v191
	s_nop 0
	v_mov_b32_e32 v38, v192
	v_mov_b32_e32 v36, v193
	ds_read_b128 v[40:43], v11 offset:1040
	s_waitcnt lgkmcnt(0)
	v_mov_b32_e32 v45, v40
	v_mov_b32_e32 v40, v5
	v_mul_f32 v4, v34, v40
	v_mul_f32 v5, v34, v41
	v_mov_b32_e32 v41, v42
	v_mov_b32_e32 v42, v7
	v_mov_b32_e32 v40, v6
	v_mul_f32 v6, v36, v42
	v_mul_f32 v7, v36, v43
	v_fma_f32 v4, v32, v44, v4
	v_fma_f32 v5, v32, v45, v5
	v_fma_f32 v6, v38, v40, v6
	v_fma_f32 v7, v38, v41, v7
	v_add_f32 v4, v4, v6
	v_add_f32 v5, v5, v7
	s_nop 0
	v_add_f32 v26, v26, v4
	v_add_f32 v27, v27, v5
	ds_read_b128 v[4:7], v11 offset:2064
	ds_read_b128 v[40:43], v11 offset:3088
	s_waitcnt lgkmcnt(1)
	v_mov_b32_e32 v44, v4
	s_waitcnt lgkmcnt(0)
	v_mov_b32_e32 v45, v40
	v_mov_b32_e32 v40, v5
	v_mul_f32 v4, v34, v40
	v_mul_f32 v5, v34, v41
	v_mov_b32_e32 v41, v42
	v_mov_b32_e32 v42, v7
	v_mov_b32_e32 v40, v6
	v_mul_f32 v6, v36, v42
	v_mul_f32 v7, v36, v43
	v_fma_f32 v4, v32, v44, v4
	v_fma_f32 v5, v32, v45, v5
	v_fma_f32 v6, v38, v40, v6
	v_fma_f32 v7, v38, v41, v7
	v_add_f32 v4, v4, v6
	v_add_f32 v5, v5, v7
	s_nop 0
	v_add_f32 v28, v28, v4
	v_add_f32 v29, v29, v5
	ds_read_b128 v[4:7], v11 offset:4112
	ds_read_b128 v[40:43], v11 offset:5136
	s_waitcnt lgkmcnt(1)
	v_mov_b32_e32 v44, v4
	s_waitcnt lgkmcnt(0)
	v_mov_b32_e32 v45, v40
	v_mov_b32_e32 v40, v5
	v_mul_f32 v4, v34, v40
	v_mul_f32 v5, v34, v41
	v_mov_b32_e32 v41, v42
	v_mov_b32_e32 v42, v7
	v_mov_b32_e32 v40, v6
	v_mul_f32 v6, v36, v42
	v_mul_f32 v7, v36, v43
	v_fma_f32 v4, v32, v44, v4
	v_fma_f32 v5, v32, v45, v5
	v_fma_f32 v6, v38, v40, v6
	v_fma_f32 v7, v38, v41, v7
	v_add_f32 v4, v4, v6
	v_add_f32 v5, v5, v7
	v_mov_b32_e32 v33, v34
	v_add_f32 v30, v30, v4
	v_add_f32 v31, v31, v5
	ds_read_b128 v[4:7], v11 offset:6160
	v_mov_b32_e32 v39, v36
	v_mov_b32_e32 v35, v38
	s_waitcnt lgkmcnt(0)
	v_mul_f32_e32 v40, v34, v5
	v_fma_f32 v41, v33, v5, v40
	v_fma_f32 v40, v32, v4, v40
	v_mul_f32_e32 v4, v36, v7
	v_fma_f32 v42, v38, v6, v4
	v_fma_f32 v43, v39, v7, v4
	ds_read_b128 v[4:7], v11 offset:7184
	v_mov_b32_e32 v33, v36
	v_add_u32_e32 v11, 32, v11
	s_waitcnt lgkmcnt(0)
	v_mov_b32_e32 v38, v5
	v_mov_b32_e32 v5, v7
	v_mov_b32_e32 v39, v6
	v_mul_f32 v4, v32, v4
	v_mul_f32 v5, v33, v5
	s_nop 0
	v_fma_f32 v4, v34, v38, v4
	v_fma_f32 v5, v35, v39, v5
	s_nop 0
	v_mov_b32_e32 v41, v4
	v_mov_b32_e32 v43, v5
	v_add_f32 v4, v40, v42
	v_add_f32 v5, v41, v43
	s_nop 0
	v_add_f32 v22, v22, v4
	v_add_f32 v23, v23, v5
	ds_write2st64_b32 v9, v26, v27 offset0:32 offset1:33
	ds_write2st64_b32 v9, v28, v29 offset0:34 offset1:35
	ds_write2st64_b32 v9, v30, v31 offset0:36 offset1:37
	ds_write2st64_b32 v9, v22, v23 offset0:38 offset1:39
	s_waitcnt lgkmcnt(0)
	s_barrier
	ds_read2st64_b32 v[4:5], v3 offset0:32 offset1:40
	ds_read2st64_b32 v[6:7], v3 offset0:48 offset1:56
	ds_read2st64_b32 v[22:23], v3 offset0:64 offset1:72
	s_lshl_b32 s18, s9, 3
	s_ashr_i32 s19, s18, 31
	s_waitcnt lgkmcnt(2)
	v_add_f32_e32 v4, 0, v4
	v_add_f32_e32 v11, v4, v5
	ds_read2st64_b32 v[4:5], v3 offset0:80 offset1:88
	s_waitcnt lgkmcnt(2)
	v_add_f32_e32 v6, v11, v6
	v_add_f32_e32 v6, v6, v7
	s_waitcnt lgkmcnt(1)
	v_add_f32_e32 v6, v6, v22
	v_add_f32_e32 v6, v6, v23
	s_waitcnt lgkmcnt(0)
	v_add_f32_e32 v4, v6, v4
	v_add_f32_e32 v4, v4, v5
	v_cvt_pk_bf16_f32 v6, v4, s0
	v_lshl_add_u64 v[4:5], s[18:19], 0, v[14:15]
	v_lshlrev_b64 v[4:5], 11, v[4:5]
	v_lshl_add_u64 v[4:5], s[16:17], 0, v[4:5]
	v_lshl_add_u64 v[4:5], s[0:1], 1, v[4:5]
	v_mov_b32_e32 v21, v2
	s_add_i32 s8, s8, s60
	v_lshl_add_u64 v[4:5], v[4:5], 0, v[20:21]
	s_cmpk_gt_i32 s8, 0x17f
	global_store_short v[4:5], v6, off
	s_cbranch_scc0 .LBB0_1747

.LBB0_1765:
	s_add_u32 s8, s0, 0x100
	s_addc_u32 s9, s1, 0
	s_cmp_eq_u32 s80, 12
	s_cselect_b32 s46, s65, s8
	s_cselect_b32 s47, s41, s9
	s_cselect_b32 s14, s67, s68
	s_cselect_b32 s15, s39, s79
	s_add_u32 s18, s46, 0x80
	s_addc_u32 s19, s47, 0
	s_add_i32 s81, 0, 0x10000
	v_add_u32_e32 v148, s81, v1
	ds_read_b128 v[132:135], v148
	ds_read_b128 v[140:143], v148 offset:1024
	ds_read_b128 v[144:147], v148 offset:2048
	ds_read_b128 v[148:151], v148 offset:3072
	s_add_u32 s0, s0, 0x40080
	s_addc_u32 s1, s1, 0
	ds_read_b128 v[152:155], v3
	ds_read_b128 v[156:159], v3 offset:1024
	ds_read_b128 v[160:163], v3 offset:2048
	ds_read_b128 v[164:167], v3 offset:3072
	ds_read_b128 v[168:171], v3 offset:4096
	ds_read_b128 v[172:175], v3 offset:5120
	ds_read_b128 v[176:179], v3 offset:6144
	ds_read_b128 v[180:183], v3 offset:7168
	s_add_i32 m0, s57, 0xc000
	s_nop 0
	global_load_lds_dwordx4 v138, s[0:1]
	s_add_i32 m0, s57, 0xe000
	s_nop 0
	global_load_lds_dwordx4 v136, s[0:1]
	s_waitcnt lgkmcnt(8)
	s_barrier
	s_waitcnt lgkmcnt(0)
	s_setprio 1
	s_waitcnt lgkmcnt(0)
	v_mfma_f32_16x16x32_bf16 v[128:131], v[132:135], v[152:155], v[128:131]
	v_mfma_f32_16x16x32_bf16 v[124:127], v[144:147], v[152:155], v[124:127]
	v_mfma_f32_16x16x32_bf16 v[112:115], v[132:135], v[160:163], v[112:115]
	v_mfma_f32_16x16x32_bf16 v[108:111], v[144:147], v[160:163], v[108:111]
	v_mfma_f32_16x16x32_bf16 v[96:99], v[132:135], v[168:171], v[96:99]
	v_mfma_f32_16x16x32_bf16 v[92:95], v[144:147], v[168:171], v[92:95]
	v_mfma_f32_16x16x32_bf16 v[80:83], v[132:135], v[176:179], v[80:83]
	v_mfma_f32_16x16x32_bf16 v[76:79], v[144:147], v[176:179], v[76:79]
	v_mfma_f32_16x16x32_bf16 v[128:131], v[140:143], v[156:159], v[128:131]
	v_mfma_f32_16x16x32_bf16 v[124:127], v[148:151], v[156:159], v[124:127]
	v_mfma_f32_16x16x32_bf16 v[112:115], v[140:143], v[164:167], v[112:115]
	v_mfma_f32_16x16x32_bf16 v[108:111], v[148:151], v[164:167], v[108:111]
	v_mfma_f32_16x16x32_bf16 v[96:99], v[140:143], v[172:175], v[96:99]
	v_mfma_f32_16x16x32_bf16 v[92:95], v[148:151], v[172:175], v[92:95]
	v_mfma_f32_16x16x32_bf16 v[80:83], v[140:143], v[180:183], v[80:83]
	v_mfma_f32_16x16x32_bf16 v[76:79], v[148:151], v[180:183], v[76:79]
	s_setprio 0
	s_barrier
	s_add_i32 s82, 0, 0x14000
	v_add_u32_e32 v210, s82, v1
	s_mov_b64 s[0:1], s[14:15]
	s_add_i32 s81, s81, s56
	ds_read_b128 v[184:187], v210
	ds_read_b128 v[188:191], v210 offset:1024
	ds_read_b128 v[192:195], v210 offset:2048
	ds_read_b128 v[210:213], v210 offset:3072
	s_mov_b32 m0, s81
	s_nop 0
	global_load_lds_dwordx4 v138, s[0:1]
	s_add_i32 m0, s81, 0x2000
	s_nop 0
	global_load_lds_dwordx4 v136, s[0:1]
	s_barrier
	s_waitcnt lgkmcnt(0)
	s_setprio 1
	s_waitcnt lgkmcnt(0)
	v_mfma_f32_16x16x32_bf16 v[120:123], v[184:187], v[152:155], v[120:123]
	v_mfma_f32_16x16x32_bf16 v[116:119], v[192:195], v[152:155], v[116:119]
	v_mfma_f32_16x16x32_bf16 v[104:107], v[184:187], v[160:163], v[104:107]
	v_mfma_f32_16x16x32_bf16 v[100:103], v[192:195], v[160:163], v[100:103]
	v_mfma_f32_16x16x32_bf16 v[88:91], v[184:187], v[168:171], v[88:91]
	v_mfma_f32_16x16x32_bf16 v[84:87], v[192:195], v[168:171], v[84:87]
	v_mfma_f32_16x16x32_bf16 v[72:75], v[184:187], v[176:179], v[72:75]
	v_mfma_f32_16x16x32_bf16 v[68:71], v[192:195], v[176:179], v[68:71]
	v_mfma_f32_16x16x32_bf16 v[120:123], v[188:191], v[156:159], v[120:123]
	v_mfma_f32_16x16x32_bf16 v[116:119], v[210:213], v[156:159], v[116:119]
	v_mfma_f32_16x16x32_bf16 v[104:107], v[188:191], v[164:167], v[104:107]
	v_mfma_f32_16x16x32_bf16 v[100:103], v[210:213], v[164:167], v[100:103]
	v_mfma_f32_16x16x32_bf16 v[88:91], v[188:191], v[172:175], v[88:91]
	v_mfma_f32_16x16x32_bf16 v[84:87], v[210:213], v[172:175], v[84:87]
	v_mfma_f32_16x16x32_bf16 v[72:75], v[188:191], v[180:183], v[72:75]
	v_mfma_f32_16x16x32_bf16 v[68:71], v[210:213], v[180:183], v[68:71]
	s_setprio 0
	s_mov_b64 s[0:1], s[46:47]
	s_mov_b32 m0, s57
	s_barrier
	ds_read_b128 v[152:155], v3 offset:16384
	ds_read_b128 v[156:159], v3 offset:17408
	ds_read_b128 v[160:163], v3 offset:18432
	ds_read_b128 v[164:167], v3 offset:19456
	ds_read_b128 v[168:171], v3 offset:20480
	ds_read_b128 v[172:175], v3 offset:21504
	ds_read_b128 v[176:179], v3 offset:22528
	ds_read_b128 v[180:183], v3 offset:23552
	s_nop 0
	global_load_lds_dwordx4 v138, s[0:1]
	s_mov_b32 m0, s62
	s_nop 0
	global_load_lds_dwordx4 v136, s[0:1]
	s_barrier
	s_waitcnt lgkmcnt(0)
	s_setprio 1
	s_waitcnt lgkmcnt(0)
	v_mfma_f32_16x16x32_bf16 v[64:67], v[132:135], v[152:155], v[64:67]
	v_mfma_f32_16x16x32_bf16 v[60:63], v[144:147], v[152:155], v[60:63]
	v_mfma_f32_16x16x32_bf16 v[48:51], v[132:135], v[160:163], v[48:51]
	v_mfma_f32_16x16x32_bf16 v[44:47], v[144:147], v[160:163], v[44:47]
	v_mfma_f32_16x16x32_bf16 v[32:35], v[132:135], v[168:171], v[32:35]
	v_mfma_f32_16x16x32_bf16 v[28:31], v[144:147], v[168:171], v[28:31]
	v_mfma_f32_16x16x32_bf16 v[16:19], v[132:135], v[176:179], v[16:19]
	v_mfma_f32_16x16x32_bf16 v[12:15], v[144:147], v[176:179], v[12:15]
	v_mfma_f32_16x16x32_bf16 v[64:67], v[140:143], v[156:159], v[64:67]
	v_mfma_f32_16x16x32_bf16 v[60:63], v[148:151], v[156:159], v[60:63]
	v_mfma_f32_16x16x32_bf16 v[48:51], v[140:143], v[164:167], v[48:51]
	v_mfma_f32_16x16x32_bf16 v[44:47], v[148:151], v[164:167], v[44:47]
	v_mfma_f32_16x16x32_bf16 v[32:35], v[140:143], v[172:175], v[32:35]
	v_mfma_f32_16x16x32_bf16 v[28:31], v[148:151], v[172:175], v[28:31]
	v_mfma_f32_16x16x32_bf16 v[16:19], v[140:143], v[180:183], v[16:19]
	v_mfma_f32_16x16x32_bf16 v[12:15], v[148:151], v[180:183], v[12:15]
	s_setprio 0
	s_barrier
	s_add_u32 s0, s14, 0x40000
	s_addc_u32 s1, s15, 0
	s_add_i32 s81, s82, s56
	s_mov_b32 m0, s81
	s_nop 0
	global_load_lds_dwordx4 v138, s[0:1]
	s_add_i32 m0, s81, 0x2000
	s_nop 0
	global_load_lds_dwordx4 v136, s[0:1]
	s_waitcnt vmcnt(6)
	s_barrier
	s_setprio 1
	v_mfma_f32_16x16x32_bf16 v[56:59], v[184:187], v[152:155], v[56:59]
	v_mfma_f32_16x16x32_bf16 v[52:55], v[192:195], v[152:155], v[52:55]
	v_mfma_f32_16x16x32_bf16 v[40:43], v[184:187], v[160:163], v[40:43]
	v_mfma_f32_16x16x32_bf16 v[36:39], v[192:195], v[160:163], v[36:39]
	v_mfma_f32_16x16x32_bf16 v[24:27], v[184:187], v[168:171], v[24:27]
	v_mfma_f32_16x16x32_bf16 v[20:23], v[192:195], v[168:171], v[20:23]
	v_mfma_f32_16x16x32_bf16 v[8:11], v[184:187], v[176:179], v[8:11]
	v_mfma_f32_16x16x32_bf16 v[4:7], v[192:195], v[176:179], v[4:7]
	v_mfma_f32_16x16x32_bf16 v[56:59], v[188:191], v[156:159], v[56:59]
	v_mfma_f32_16x16x32_bf16 v[52:55], v[210:213], v[156:159], v[52:55]
	v_mfma_f32_16x16x32_bf16 v[40:43], v[188:191], v[164:167], v[40:43]
	v_mfma_f32_16x16x32_bf16 v[36:39], v[210:213], v[164:167], v[36:39]
	v_mfma_f32_16x16x32_bf16 v[24:27], v[188:191], v[172:175], v[24:27]
	v_mfma_f32_16x16x32_bf16 v[20:23], v[210:213], v[172:175], v[20:23]
	v_mfma_f32_16x16x32_bf16 v[8:11], v[188:191], v[180:183], v[8:11]
	v_mfma_f32_16x16x32_bf16 v[4:7], v[210:213], v[180:183], v[4:7]
	s_setprio 0
	s_add_i32 s81, 0, 0x18000
	v_add_u32_e32 v148, s81, v1
	s_barrier
	ds_read_b128 v[132:135], v148
	ds_read_b128 v[140:143], v148 offset:1024
	ds_read_b128 v[144:147], v148 offset:2048
	ds_read_b128 v[148:151], v148 offset:3072
	s_add_u32 s0, s46, 0x40000
	s_addc_u32 s1, s47, 0
	s_mov_b32 m0, s63
	ds_read_b128 v[152:155], v3 offset:32768
	ds_read_b128 v[156:159], v3 offset:33792
	ds_read_b128 v[160:163], v3 offset:34816
	ds_read_b128 v[164:167], v3 offset:35840
	ds_read_b128 v[168:171], v3 offset:36864
	ds_read_b128 v[172:175], v3 offset:37888
	ds_read_b128 v[176:179], v3 offset:38912
	ds_read_b128 v[180:183], v3 offset:39936
	s_nop 0
	global_load_lds_dwordx4 v138, s[0:1]
	s_mov_b32 m0, s72
	s_nop 0
	global_load_lds_dwordx4 v136, s[0:1]
	s_waitcnt lgkmcnt(8)
	s_barrier
	s_waitcnt lgkmcnt(0)
	s_setprio 1
	s_waitcnt lgkmcnt(0)
	v_mfma_f32_16x16x32_bf16 v[128:131], v[132:135], v[152:155], v[128:131]
	v_mfma_f32_16x16x32_bf16 v[124:127], v[144:147], v[152:155], v[124:127]
	v_mfma_f32_16x16x32_bf16 v[112:115], v[132:135], v[160:163], v[112:115]
	v_mfma_f32_16x16x32_bf16 v[108:111], v[144:147], v[160:163], v[108:111]
	v_mfma_f32_16x16x32_bf16 v[96:99], v[132:135], v[168:171], v[96:99]
	v_mfma_f32_16x16x32_bf16 v[92:95], v[144:147], v[168:171], v[92:95]
	v_mfma_f32_16x16x32_bf16 v[80:83], v[132:135], v[176:179], v[80:83]
	v_mfma_f32_16x16x32_bf16 v[76:79], v[144:147], v[176:179], v[76:79]
	v_mfma_f32_16x16x32_bf16 v[128:131], v[140:143], v[156:159], v[128:131]
	v_mfma_f32_16x16x32_bf16 v[124:127], v[148:151], v[156:159], v[124:127]
	v_mfma_f32_16x16x32_bf16 v[112:115], v[140:143], v[164:167], v[112:115]
	v_mfma_f32_16x16x32_bf16 v[108:111], v[148:151], v[164:167], v[108:111]
	v_mfma_f32_16x16x32_bf16 v[96:99], v[140:143], v[172:175], v[96:99]
	v_mfma_f32_16x16x32_bf16 v[92:95], v[148:151], v[172:175], v[92:95]
	v_mfma_f32_16x16x32_bf16 v[80:83], v[140:143], v[180:183], v[80:83]
	v_mfma_f32_16x16x32_bf16 v[76:79], v[148:151], v[180:183], v[76:79]
	s_setprio 0
	s_barrier
	s_add_i32 s46, 0, 0x1c000
	s_add_u32 s0, s14, 0x80
	v_add_u32_e32 v210, s46, v1
	s_addc_u32 s1, s15, 0
	s_add_i32 s47, s81, s56
	ds_read_b128 v[184:187], v210
	ds_read_b128 v[188:191], v210 offset:1024
	ds_read_b128 v[192:195], v210 offset:2048
	ds_read_b128 v[210:213], v210 offset:3072
	s_mov_b32 m0, s47
	s_nop 0
	global_load_lds_dwordx4 v138, s[0:1]
	s_add_i32 m0, s47, 0x2000
	s_nop 0
	global_load_lds_dwordx4 v136, s[0:1]
	s_barrier
	s_waitcnt lgkmcnt(0)
	s_setprio 1
	s_waitcnt lgkmcnt(0)
	v_mfma_f32_16x16x32_bf16 v[120:123], v[184:187], v[152:155], v[120:123]
	v_mfma_f32_16x16x32_bf16 v[116:119], v[192:195], v[152:155], v[116:119]
	v_mfma_f32_16x16x32_bf16 v[104:107], v[184:187], v[160:163], v[104:107]
	v_mfma_f32_16x16x32_bf16 v[100:103], v[192:195], v[160:163], v[100:103]
	v_mfma_f32_16x16x32_bf16 v[88:91], v[184:187], v[168:171], v[88:91]
	v_mfma_f32_16x16x32_bf16 v[84:87], v[192:195], v[168:171], v[84:87]
	v_mfma_f32_16x16x32_bf16 v[72:75], v[184:187], v[176:179], v[72:75]
	v_mfma_f32_16x16x32_bf16 v[68:71], v[192:195], v[176:179], v[68:71]
	v_mfma_f32_16x16x32_bf16 v[120:123], v[188:191], v[156:159], v[120:123]
	v_mfma_f32_16x16x32_bf16 v[116:119], v[210:213], v[156:159], v[116:119]
	v_mfma_f32_16x16x32_bf16 v[104:107], v[188:191], v[164:167], v[104:107]
	v_mfma_f32_16x16x32_bf16 v[100:103], v[210:213], v[164:167], v[100:103]
	v_mfma_f32_16x16x32_bf16 v[88:91], v[188:191], v[172:175], v[88:91]
	v_mfma_f32_16x16x32_bf16 v[84:87], v[210:213], v[172:175], v[84:87]
	v_mfma_f32_16x16x32_bf16 v[72:75], v[188:191], v[180:183], v[72:75]
	v_mfma_f32_16x16x32_bf16 v[68:71], v[210:213], v[180:183], v[68:71]
	s_setprio 0
	s_mov_b32 m0, s73
	s_barrier
	ds_read_b128 v[152:155], v3 offset:49152
	ds_read_b128 v[156:159], v3 offset:50176
	ds_read_b128 v[160:163], v3 offset:51200
	ds_read_b128 v[164:167], v3 offset:52224
	ds_read_b128 v[168:171], v3 offset:53248
	ds_read_b128 v[172:175], v3 offset:54272
	ds_read_b128 v[176:179], v3 offset:55296
	ds_read_b128 v[180:183], v3 offset:56320
	s_nop 0
	global_load_lds_dwordx4 v138, s[18:19]
	s_mov_b32 m0, s74
	s_nop 0
	global_load_lds_dwordx4 v136, s[18:19]
	s_barrier
	s_waitcnt lgkmcnt(0)
	s_setprio 1
	s_waitcnt lgkmcnt(0)
	v_mfma_f32_16x16x32_bf16 v[64:67], v[132:135], v[152:155], v[64:67]
	v_mfma_f32_16x16x32_bf16 v[60:63], v[144:147], v[152:155], v[60:63]
	v_mfma_f32_16x16x32_bf16 v[48:51], v[132:135], v[160:163], v[48:51]
	v_mfma_f32_16x16x32_bf16 v[44:47], v[144:147], v[160:163], v[44:47]
	v_mfma_f32_16x16x32_bf16 v[32:35], v[132:135], v[168:171], v[32:35]
	v_mfma_f32_16x16x32_bf16 v[28:31], v[144:147], v[168:171], v[28:31]
	v_mfma_f32_16x16x32_bf16 v[16:19], v[132:135], v[176:179], v[16:19]
	v_mfma_f32_16x16x32_bf16 v[12:15], v[144:147], v[176:179], v[12:15]
	v_mfma_f32_16x16x32_bf16 v[64:67], v[140:143], v[156:159], v[64:67]
	v_mfma_f32_16x16x32_bf16 v[60:63], v[148:151], v[156:159], v[60:63]
	v_mfma_f32_16x16x32_bf16 v[48:51], v[140:143], v[164:167], v[48:51]
	v_mfma_f32_16x16x32_bf16 v[44:47], v[148:151], v[164:167], v[44:47]
	v_mfma_f32_16x16x32_bf16 v[32:35], v[140:143], v[172:175], v[32:35]
	v_mfma_f32_16x16x32_bf16 v[28:31], v[148:151], v[172:175], v[28:31]
	v_mfma_f32_16x16x32_bf16 v[16:19], v[140:143], v[180:183], v[16:19]
	v_mfma_f32_16x16x32_bf16 v[12:15], v[148:151], v[180:183], v[12:15]
	s_setprio 0
	s_barrier
	s_add_u32 s0, s14, 0x40080
	s_addc_u32 s1, s15, 0
	s_add_i32 s14, s46, s56
	s_mov_b32 m0, s14
	s_nop 0
	global_load_lds_dwordx4 v138, s[0:1]
	s_add_i32 m0, s14, 0x2000
	s_nop 0
	global_load_lds_dwordx4 v136, s[0:1]
	s_waitcnt vmcnt(6)
	s_barrier
	s_setprio 1
	v_mfma_f32_16x16x32_bf16 v[56:59], v[184:187], v[152:155], v[56:59]
	v_mfma_f32_16x16x32_bf16 v[52:55], v[192:195], v[152:155], v[52:55]
	v_mfma_f32_16x16x32_bf16 v[40:43], v[184:187], v[160:163], v[40:43]
	v_mfma_f32_16x16x32_bf16 v[36:39], v[192:195], v[160:163], v[36:39]
	v_mfma_f32_16x16x32_bf16 v[24:27], v[184:187], v[168:171], v[24:27]
	v_mfma_f32_16x16x32_bf16 v[20:23], v[192:195], v[168:171], v[20:23]
	v_mfma_f32_16x16x32_bf16 v[8:11], v[184:187], v[176:179], v[8:11]
	v_mfma_f32_16x16x32_bf16 v[4:7], v[192:195], v[176:179], v[4:7]
	v_mfma_f32_16x16x32_bf16 v[56:59], v[188:191], v[156:159], v[56:59]
	v_mfma_f32_16x16x32_bf16 v[52:55], v[210:213], v[156:159], v[52:55]
	v_mfma_f32_16x16x32_bf16 v[40:43], v[188:191], v[164:167], v[40:43]
	v_mfma_f32_16x16x32_bf16 v[36:39], v[210:213], v[164:167], v[36:39]
	v_mfma_f32_16x16x32_bf16 v[24:27], v[188:191], v[172:175], v[24:27]
	v_mfma_f32_16x16x32_bf16 v[20:23], v[210:213], v[172:175], v[20:23]
	v_mfma_f32_16x16x32_bf16 v[8:11], v[188:191], v[180:183], v[8:11]
	v_mfma_f32_16x16x32_bf16 v[4:7], v[210:213], v[180:183], v[4:7]
	s_setprio 0
	s_add_i32 s80, s80, 2
	s_add_u32 s68, s68, 0x100
	s_addc_u32 s79, s79, 0
	s_cmp_gt_u32 s80, 13
	s_mov_b64 s[0:1], s[8:9]
	s_barrier
	s_cbranch_scc0 .LBB0_1765
	v_mov_b32_e32 v145, v0
	s_lshl_b32 s1, s64, 8
	v_readfirstlane_b32 s0, v145
	s_and_b32 s14, s0, 0xc0
	s_ashr_i32 s0, s0, 2
	v_and_b32_e32 v170, 15, v145
	s_and_b32 s15, s0, 0xffffffc0
	v_or_b32_e32 v132, s15, v170
	v_add_u32_e32 v132, s1, v132
	v_ashrrev_i32_e32 v133, 31, v132
	v_lshl_add_u64 v[132:133], v[132:133], 2, s[20:21]
	global_load_dword v134, v[132:133], off
	global_load_dword v174, v[132:133], off offset:64
	global_load_dword v173, v[132:133], off offset:128
	global_load_dword v172, v[132:133], off offset:192
	global_load_dword v171, v[132:133], off offset:512
	global_load_dword v169, v[132:133], off offset:576
	global_load_dword v168, v[132:133], off offset:640
	global_load_dword v167, v[132:133], off offset:704
	s_add_i32 s15, s15, s1
	s_cmp_gt_i32 s78, 2
	s_cselect_b64 s[0:1], -1, 0
	v_or_b32_e32 v142, s15, v170
	s_mov_b64 s[8:9], -1
	s_waitcnt vmcnt(0)
	v_fmamk_f32 v132, v134, 0x3a800000, v231
	v_cmp_gt_f32_e32 vcc, s11, v132
	v_mul_f32_e32 v133, 0x4b800000, v132
	s_nop 0
	v_cndmask_b32_e32 v132, v132, v133, vcc
	v_rsq_f32_e32 v132, v132
	s_nop 0
	v_mul_f32_e32 v133, 0x45800000, v132
	v_cndmask_b32_e32 v144, v132, v133, vcc
	v_lshrrev_b32_e32 v132, 1, v145
	v_and_b32_e32 v155, 24, v132
	s_and_b64 vcc, exec, s[0:1]
	v_lshlrev_b32_e32 v166, 2, v155
	v_lshlrev_b32_e32 v140, 1, v155
	s_cbranch_vccz .LBB0_1768
	v_ashrrev_i32_e32 v143, 31, v142
	v_lshlrev_b64 v[132:133], 9, v[142:143]
	v_lshl_add_u64 v[132:133], s[24:25], 0, v[132:133]
	s_lshl_b32 s68, s14, 1
	v_mul_f32 v160, v130, v144
	v_mul_f32 v161, v131, v144
	v_mul_f32 v162, v128, v144
	v_mul_f32 v163, v129, v144
	v_lshl_add_u64 v[164:165], v[132:133], 0, s[68:69]
	v_mul_f32 v132, v160, v160
	v_mul_f32 v133, v161, v161
	v_mul_f32 v134, v162, v162
	v_mul_f32 v135, v163, v163
	v_mul_f32 v156, v126, v144
	v_mul_f32 v157, v127, v144
	v_pk_mov_b32 v[146:147], v[134:135], v[132:133] op_sel:[1,0]
	v_mov_b32_e32 v135, v133
	v_add_f32 v132, v146, v134
	v_add_f32 v133, v147, v135
	v_mul_f32 v158, v124, v144
	v_mul_f32 v159, v125, v144
	v_add_f32 v133, v132, v133
	v_add_f32 v132, v132, v132
	v_mul_f32 v134, v156, v156
	v_mul_f32 v135, v157, v157
	v_mul_f32 v146, v158, v158
	v_mul_f32 v147, v159, v159
	v_mul_f32 v152, v120, v144
	v_mul_f32 v153, v121, v144
	v_pk_mov_b32 v[148:149], v[146:147], v[134:135] op_sel:[1,0]
	v_mov_b32_e32 v147, v135
	v_mul_f32 v150, v122, v144
	v_mul_f32 v151, v123, v144
	v_mul_f32_e32 v132, v152, v152
	v_add_f32 v134, v148, v146
	v_add_f32 v135, v149, v147
	v_fma_f32 v176, v152, v152, v132
	v_fma_f32 v177, v153, v153, v132
	v_mul_f32_e32 v132, v150, v150
	v_add_f32 v135, v134, v135
	v_add_f32 v134, v134, v134
	v_fma_f32 v178, v150, v150, v132
	v_fma_f32 v179, v151, v151, v132
	v_mul_f32 v146, v118, v144
	v_mul_f32 v147, v119, v144
	v_mul_f32 v148, v116, v144
	v_mul_f32 v149, v117, v144
	v_mul_f32_e32 v132, v146, v146
	v_mul_f32_e32 v176, v148, v148
	v_mul_f32_e32 v178, v149, v149
	v_mul_f32_e32 v134, v147, v147
	v_add_f32 v176, v176, v178
	v_add_f32 v177, v177, v179
	v_add_f32 v132, v132, v134
	v_add_f32 v133, v133, v135
	v_and_b32_e32 v134, 64, v236
	v_add_f32 v132, v176, v132
	v_add_f32 v133, v177, v133
	v_add_u32_e32 v134, 64, v134
	v_add_f32_e32 v132, v132, v133
	ds_swizzle_b32 v133, v132 offset:swizzle(SWAP,16)
	v_mov_b32_e32 v141, v2
	v_lshl_add_u64 v[164:165], v[164:165], 0, v[140:141]
	s_mov_b64 s[8:9], 0
	s_waitcnt lgkmcnt(0)
	v_add_f32_e32 v132, v132, v133
	v_xor_b32_e32 v133, 32, v236
	v_cmp_lt_i32_e32 vcc, v133, v134
	s_nop 1
	v_cndmask_b32_e32 v133, v236, v133, vcc
	v_lshlrev_b32_e32 v133, 2, v133
	ds_bpermute_b32 v133, v133, v132
	s_waitcnt lgkmcnt(0)
	v_add_f32_e32 v132, v132, v133
	v_fmamk_f32 v132, v132, 0x3c800000, v231
	v_cmp_gt_f32_e32 vcc, s11, v132
	v_mul_f32_e32 v133, 0x4b800000, v132
	s_nop 0
	v_cndmask_b32_e32 v132, v132, v133, vcc
	v_rsq_f32_e32 v132, v132
	s_nop 0
	v_mul_f32_e32 v133, 0x45800000, v132
	v_cndmask_b32_e32 v132, v132, v133, vcc
	v_mul_f32_e32 v154, 0x3e38aa3b, v132
	global_load_dwordx4 v[132:135], v166, s[26:27] offset:16
	global_load_dwordx4 v[176:179], v166, s[26:27]
	v_mul_f32 v162, v162, v154
	v_mul_f32 v163, v163, v154
	v_mul_f32 v160, v160, v154
	v_mul_f32 v161, v161, v154
	v_mul_f32 v158, v158, v154
	v_mul_f32 v159, v159, v154
	v_mul_f32 v156, v156, v154
	v_mul_f32 v157, v157, v154
	v_mul_f32 v152, v152, v154
	v_mul_f32 v153, v153, v154
	v_mul_f32 v150, v150, v154
	v_mul_f32 v151, v151, v154
	v_mul_f32 v148, v148, v154
	v_mul_f32 v149, v149, v154
	v_mul_f32 v146, v146, v154
	v_mul_f32 v147, v147, v154
	s_waitcnt vmcnt(1)
	v_mul_f32 v156, v134, v156
	v_mul_f32 v157, v135, v157
	s_waitcnt vmcnt(0)
	v_mul_f32 v160, v178, v160
	v_mul_f32 v161, v179, v161
	v_mul_f32 v162, v176, v162
	v_mul_f32 v163, v177, v163
	v_mul_f32 v134, v132, v158
	v_mul_f32 v135, v133, v159
	v_cvt_pk_bf16_f32 v132, v162, v163
	v_cvt_pk_bf16_f32 v133, v160, v161
	v_cvt_pk_bf16_f32 v134, v134, v135
	v_cvt_pk_bf16_f32 v135, v156, v157
	global_store_dwordx4 v[164:165], v[132:135], off
	global_load_dwordx4 v[132:135], v166, s[26:27] offset:144
	s_nop 0
	global_load_dwordx4 v[156:159], v166, s[26:27] offset:128
	s_waitcnt vmcnt(1)
	v_mul_f32 v146, v134, v146
	v_mul_f32 v147, v135, v147
	s_waitcnt vmcnt(0)
	v_mul_f32 v150, v158, v150
	v_mul_f32 v151, v159, v151
	v_mul_f32 v152, v156, v152
	v_mul_f32 v153, v157, v153
	v_mul_f32 v134, v132, v148
	v_mul_f32 v135, v133, v149
	v_cvt_pk_bf16_f32 v132, v152, v153
	v_cvt_pk_bf16_f32 v133, v150, v151
	v_cvt_pk_bf16_f32 v134, v134, v135
	v_cvt_pk_bf16_f32 v135, v146, v147
	global_store_dwordx4 v[164:165], v[132:135], off offset:64
.LBB0_1768:
	s_nop 1
	v_and_b32_e32 v132, 7, v145
	v_add_u32_e32 v132, 7, v132
	s_andn2_b64 vcc, exec, s[8:9]
	v_mov_b32_e32 v133, v2
	s_cbranch_vccnz .LBB0_1776
	s_movk_i32 s8, 0x3fff
	v_cmp_lt_i32_e32 vcc, s8, v142
	v_mov_b64_e32 v[134:135], 0
	s_and_saveexec_b64 s[8:9], vcc
	v_add_u32_e32 v134, 0xffffc000, v142
	v_lshrrev_b32_e32 v134, 3, v134
	v_mad_u64_u32 v[146:147], s[18:19], v134, 15, v[132:133]
	v_mov_b64_e32 v[134:135], s[30:31]
	v_mad_u64_u32 v[134:135], s[18:19], v146, s91, v[134:135]
	v_mad_u32_u24 v135, v147, s91, v135
	s_or_b64 exec, exec, s[8:9]
	s_lshl_b32 s8, s78, 8
	s_or_b32 s8, s14, s8
	v_or_b32_e32 v152, s8, v155
	v_mov_b64_e32 v[146:147], s[22:23]
	v_mul_f32 v130, v130, v144
	v_mul_f32 v131, v131, v144
	v_mul_f32 v128, v128, v144
	v_mul_f32 v129, v129, v144
	v_mul_f32 v126, v126, v144
	v_mul_f32 v127, v127, v144
	v_mul_f32 v124, v124, v144
	v_mul_f32 v125, v125, v144
	v_mad_i64_i32 v[146:147], s[8:9], v142, s71, v[146:147]
	v_ashrrev_i32_e32 v153, 31, v152
	v_cmp_ne_u64_e32 vcc, 0, v[134:135]
	v_lshl_add_u64 v[146:147], v[152:153], 1, v[146:147]
	v_cvt_pk_bf16_f32 v148, v128, v129
	v_cvt_pk_bf16_f32 v149, v130, v131
	v_cvt_pk_bf16_f32 v150, v124, v125
	v_cvt_pk_bf16_f32 v151, v126, v127
	v_lshl_add_u64 v[134:135], v[152:153], 2, v[134:135]
	global_store_dwordx4 v[146:147], v[148:151], off
	s_and_saveexec_b64 s[8:9], vcc
	s_cbranch_execz .LBB0_1773
	global_store_dwordx4 v[134:135], v[128:131], off
	global_store_dwordx4 v[134:135], v[124:127], off offset:16
.LBB0_1773:
	s_or_b64 exec, exec, s[8:9]
	v_mov_b32_e32 v145, v144
	v_mov_b32_e32 v124, v144
	v_mov_b32_e32 v125, v144
	v_mul_f32 v122, v122, v124
	v_mul_f32 v123, v123, v125
	v_mul_f32 v120, v120, v144
	v_mul_f32 v121, v121, v145
	v_mul_f32 v118, v118, v124
	v_mul_f32 v119, v119, v125
	v_mul_f32 v116, v116, v144
	v_mul_f32 v117, v117, v145
	v_cvt_pk_bf16_f32 v124, v120, v121
	v_cvt_pk_bf16_f32 v125, v122, v123
	v_cvt_pk_bf16_f32 v126, v116, v117
	v_cvt_pk_bf16_f32 v127, v118, v119
	global_store_dwordx4 v[146:147], v[124:127], off offset:64
	s_and_saveexec_b64 s[8:9], vcc
	s_cbranch_execz .LBB0_1775
	global_store_dwordx4 v[134:135], v[120:123], off offset:128
	global_store_dwordx4 v[134:135], v[116:119], off offset:144

.LBB0_1776:
	s_nop 0
	v_fmamk_f32 v116, v174, 0x3a800000, v231
	v_cmp_gt_f32_e32 vcc, s11, v116
	v_mul_f32_e32 v117, 0x4b800000, v116
	v_or_b32_e32 v122, 16, v142
	v_cndmask_b32_e32 v116, v116, v117, vcc
	v_rsq_f32_e32 v116, v116
	s_mov_b64 s[8:9], -1
	v_mul_f32_e32 v117, 0x45800000, v116
	v_cndmask_b32_e32 v120, v116, v117, vcc
	v_cndmask_b32_e64 v116, 0, 1, s[0:1]
	v_cmp_ne_u32_e64 s[18:19], 1, v116
	s_andn2_b64 vcc, exec, s[0:1]
	s_cbranch_vccnz .LBB0_1778
	v_ashrrev_i32_e32 v123, 31, v122
	v_lshlrev_b64 v[116:117], 9, v[122:123]
	v_lshl_add_u64 v[116:117], s[24:25], 0, v[116:117]
	s_lshl_b32 s68, s14, 1
	v_mul_f32 v148, v114, v120
	v_mul_f32 v149, v115, v120
	v_mul_f32 v150, v112, v120
	v_mul_f32 v151, v113, v120
	v_lshl_add_u64 v[152:153], v[116:117], 0, s[68:69]
	v_mul_f32 v116, v148, v148
	v_mul_f32 v117, v149, v149
	v_mul_f32 v118, v150, v150
	v_mul_f32 v119, v151, v151
	v_mul_f32 v144, v110, v120
	v_mul_f32 v145, v111, v120
	v_pk_mov_b32 v[124:125], v[118:119], v[116:117] op_sel:[1,0]
	v_mov_b32_e32 v119, v117
	v_add_f32 v116, v124, v118
	v_add_f32 v117, v125, v119
	v_mul_f32 v146, v108, v120
	v_mul_f32 v147, v109, v120
	v_add_f32 v117, v116, v117
	v_add_f32 v116, v116, v116
	v_mul_f32 v118, v144, v144
	v_mul_f32 v119, v145, v145
	v_mul_f32 v124, v146, v146
	v_mul_f32 v125, v147, v147
	v_mul_f32 v130, v104, v120
	v_mul_f32 v131, v105, v120
	v_pk_mov_b32 v[126:127], v[124:125], v[118:119] op_sel:[1,0]
	v_mov_b32_e32 v125, v119
	v_mul_f32 v128, v106, v120
	v_mul_f32 v129, v107, v120
	v_mul_f32_e32 v116, v130, v130
	v_add_f32 v118, v126, v124
	v_add_f32 v119, v127, v125
	v_fma_f32 v134, v130, v130, v116
	v_fma_f32 v135, v131, v131, v116
	v_mul_f32_e32 v116, v128, v128
	v_add_f32 v119, v118, v119
	v_add_f32 v118, v118, v118
	v_fma_f32 v156, v128, v128, v116
	v_fma_f32 v157, v129, v129, v116
	v_mul_f32 v124, v102, v120
	v_mul_f32 v125, v103, v120
	v_mul_f32 v126, v100, v120
	v_mul_f32 v127, v101, v120
	v_mul_f32_e32 v116, v124, v124
	v_mul_f32_e32 v134, v126, v126
	v_mul_f32_e32 v156, v127, v127
	v_mul_f32_e32 v118, v125, v125
	v_add_f32 v134, v134, v156
	v_add_f32 v135, v135, v157
	v_add_f32 v116, v116, v118
	v_add_f32 v117, v117, v119
	v_and_b32_e32 v118, 64, v236
	v_add_f32 v116, v134, v116
	v_add_f32 v117, v135, v117
	v_add_u32_e32 v118, 64, v118
	v_add_f32_e32 v116, v116, v117
	ds_swizzle_b32 v117, v116 offset:swizzle(SWAP,16)
	v_mov_b32_e32 v141, v2
	v_lshl_add_u64 v[152:153], v[152:153], 0, v[140:141]
	s_mov_b64 s[8:9], 0
	s_waitcnt lgkmcnt(0)
	v_add_f32_e32 v116, v116, v117
	v_xor_b32_e32 v117, 32, v236
	v_cmp_lt_i32_e32 vcc, v117, v118
	s_nop 1
	v_cndmask_b32_e32 v117, v236, v117, vcc
	v_lshlrev_b32_e32 v117, 2, v117
	ds_bpermute_b32 v117, v117, v116
	s_waitcnt lgkmcnt(0)
	v_add_f32_e32 v116, v116, v117
	v_fmamk_f32 v116, v116, 0x3c800000, v231
	v_cmp_gt_f32_e32 vcc, s11, v116
	v_mul_f32_e32 v117, 0x4b800000, v116
	s_nop 0
	v_cndmask_b32_e32 v116, v116, v117, vcc
	v_rsq_f32_e32 v116, v116
	s_nop 0
	v_mul_f32_e32 v117, 0x45800000, v116
	v_cndmask_b32_e32 v116, v116, v117, vcc
	v_mul_f32_e32 v134, 0x3e38aa3b, v116
	global_load_dwordx4 v[116:119], v166, s[26:27] offset:16
	global_load_dwordx4 v[156:159], v166, s[26:27]
	v_mul_f32 v150, v150, v134
	v_mul_f32 v151, v151, v134
	v_mul_f32 v148, v148, v134
	v_mul_f32 v149, v149, v134
	v_mul_f32 v146, v146, v134
	v_mul_f32 v147, v147, v134
	v_mul_f32 v144, v144, v134
	v_mul_f32 v145, v145, v134
	v_mul_f32 v130, v130, v134
	v_mul_f32 v131, v131, v134
	v_mul_f32 v128, v128, v134
	v_mul_f32 v129, v129, v134
	v_mul_f32 v126, v126, v134
	v_mul_f32 v127, v127, v134
	v_mul_f32 v124, v124, v134
	v_mul_f32 v125, v125, v134
	s_waitcnt vmcnt(1)
	v_mul_f32 v144, v118, v144
	v_mul_f32 v145, v119, v145
	s_waitcnt vmcnt(0)
	v_mul_f32 v148, v158, v148
	v_mul_f32 v149, v159, v149
	v_mul_f32 v150, v156, v150
	v_mul_f32 v151, v157, v151
	v_mul_f32 v118, v116, v146
	v_mul_f32 v119, v117, v147
	v_cvt_pk_bf16_f32 v116, v150, v151
	v_cvt_pk_bf16_f32 v117, v148, v149
	v_cvt_pk_bf16_f32 v118, v118, v119
	v_cvt_pk_bf16_f32 v119, v144, v145
	global_store_dwordx4 v[152:153], v[116:119], off
	global_load_dwordx4 v[116:119], v166, s[26:27] offset:144
	s_nop 0
	global_load_dwordx4 v[144:147], v166, s[26:27] offset:128
	s_waitcnt vmcnt(1)
	v_mul_f32 v124, v118, v124
	v_mul_f32 v125, v119, v125
	s_waitcnt vmcnt(0)
	v_mul_f32 v128, v146, v128
	v_mul_f32 v129, v147, v129
	v_mul_f32 v130, v144, v130
	v_mul_f32 v131, v145, v131
	v_mul_f32 v118, v116, v126
	v_mul_f32 v119, v117, v127
	v_cvt_pk_bf16_f32 v116, v130, v131
	v_cvt_pk_bf16_f32 v117, v128, v129
	v_cvt_pk_bf16_f32 v118, v118, v119
	v_cvt_pk_bf16_f32 v119, v124, v125
	global_store_dwordx4 v[152:153], v[116:119], off offset:64
.LBB0_1778:
	s_andn2_b64 vcc, exec, s[8:9]
	s_cbranch_vccnz .LBB0_1786
	s_movk_i32 s0, 0x3fff
	v_cmp_lt_i32_e32 vcc, s0, v122
	v_mov_b64_e32 v[116:117], 0
	s_and_saveexec_b64 s[0:1], vcc
	v_add_u32_e32 v116, 0xffffc010, v142
	v_lshrrev_b32_e32 v116, 3, v116
	v_mad_u64_u32 v[118:119], s[8:9], v116, 15, v[132:133]
	v_mov_b64_e32 v[116:117], s[30:31]
	v_mad_u64_u32 v[116:117], s[8:9], v118, s91, v[116:117]
	v_mad_u32_u24 v117, v119, s91, v117
	s_or_b64 exec, exec, s[0:1]
	s_lshl_b32 s0, s78, 8
	s_or_b32 s0, s14, s0
	v_or_b32_e32 v126, s0, v155
	v_mov_b64_e32 v[118:119], s[22:23]
	v_mul_f32 v114, v114, v120
	v_mul_f32 v115, v115, v120
	v_mul_f32 v112, v112, v120
	v_mul_f32 v113, v113, v120
	v_mul_f32 v110, v110, v120
	v_mul_f32 v111, v111, v120
	v_mul_f32 v108, v108, v120
	v_mul_f32 v109, v109, v120
	v_mad_i64_i32 v[118:119], s[0:1], v122, s71, v[118:119]
	v_ashrrev_i32_e32 v127, 31, v126
	v_cmp_ne_u64_e32 vcc, 0, v[116:117]
	v_lshl_add_u64 v[118:119], v[126:127], 1, v[118:119]
	v_cvt_pk_bf16_f32 v122, v112, v113
	v_cvt_pk_bf16_f32 v123, v114, v115
	v_cvt_pk_bf16_f32 v124, v108, v109
	v_cvt_pk_bf16_f32 v125, v110, v111
	v_lshl_add_u64 v[116:117], v[126:127], 2, v[116:117]
	global_store_dwordx4 v[118:119], v[122:125], off
	s_and_saveexec_b64 s[0:1], vcc
	s_cbranch_execz .LBB0_1783
	global_store_dwordx4 v[116:117], v[112:115], off
	global_store_dwordx4 v[116:117], v[108:111], off offset:16
.LBB0_1783:
	s_or_b64 exec, exec, s[0:1]
	v_mov_b32_e32 v121, v120
	v_mov_b32_e32 v108, v120
	v_mov_b32_e32 v109, v120
	v_mul_f32 v106, v106, v108
	v_mul_f32 v107, v107, v109
	v_mul_f32 v104, v104, v120
	v_mul_f32 v105, v105, v121
	v_mul_f32 v102, v102, v108
	v_mul_f32 v103, v103, v109
	v_mul_f32 v100, v100, v120
	v_mul_f32 v101, v101, v121
	v_cvt_pk_bf16_f32 v108, v104, v105
	v_cvt_pk_bf16_f32 v109, v106, v107
	v_cvt_pk_bf16_f32 v110, v100, v101
	v_cvt_pk_bf16_f32 v111, v102, v103
	global_store_dwordx4 v[118:119], v[108:111], off offset:64
	s_and_saveexec_b64 s[0:1], vcc
	s_cbranch_execz .LBB0_1785
	global_store_dwordx4 v[116:117], v[104:107], off offset:128
	global_store_dwordx4 v[116:117], v[100:103], off offset:144

.LBB0_1786:
	s_nop 0
	v_fmamk_f32 v100, v173, 0x3a800000, v231
	v_cmp_gt_f32_e32 vcc, s11, v100
	v_mul_f32_e32 v101, 0x4b800000, v100
	v_or_b32_e32 v106, 32, v142
	v_cndmask_b32_e32 v100, v100, v101, vcc
	v_rsq_f32_e32 v100, v100
	s_mov_b64 s[0:1], -1
	v_mul_f32_e32 v101, 0x45800000, v100
	v_cndmask_b32_e32 v104, v100, v101, vcc
	s_and_b64 vcc, exec, s[18:19]
	s_cbranch_vccnz .LBB0_1788
	v_ashrrev_i32_e32 v107, 31, v106
	v_lshlrev_b64 v[100:101], 9, v[106:107]
	v_lshl_add_u64 v[100:101], s[24:25], 0, v[100:101]
	s_lshl_b32 s68, s14, 1
	v_mul_f32 v122, v98, v104
	v_mul_f32 v123, v99, v104
	v_mul_f32 v124, v96, v104
	v_mul_f32 v125, v97, v104
	v_lshl_add_u64 v[126:127], v[100:101], 0, s[68:69]
	v_mul_f32 v100, v122, v122
	v_mul_f32 v101, v123, v123
	v_mul_f32 v102, v124, v124
	v_mul_f32 v103, v125, v125
	v_mul_f32 v118, v94, v104
	v_mul_f32 v119, v95, v104
	v_pk_mov_b32 v[108:109], v[102:103], v[100:101] op_sel:[1,0]
	v_mov_b32_e32 v103, v101
	v_add_f32 v100, v108, v102
	v_add_f32 v101, v109, v103
	v_mul_f32 v120, v92, v104
	v_mul_f32 v121, v93, v104
	v_add_f32 v101, v100, v101
	v_add_f32 v100, v100, v100
	v_mul_f32 v102, v118, v118
	v_mul_f32 v103, v119, v119
	v_mul_f32 v108, v120, v120
	v_mul_f32 v109, v121, v121
	v_mul_f32 v114, v88, v104
	v_mul_f32 v115, v89, v104
	v_pk_mov_b32 v[110:111], v[108:109], v[102:103] op_sel:[1,0]
	v_mov_b32_e32 v109, v103
	v_mul_f32 v112, v90, v104
	v_mul_f32 v113, v91, v104
	v_mul_f32_e32 v100, v114, v114
	v_add_f32 v102, v110, v108
	v_add_f32 v103, v111, v109
	v_fma_f32 v116, v114, v114, v100
	v_fma_f32 v117, v115, v115, v100
	v_mul_f32_e32 v100, v112, v112
	v_add_f32 v103, v102, v103
	v_add_f32 v102, v102, v102
	v_fma_f32 v128, v112, v112, v100
	v_fma_f32 v129, v113, v113, v100
	v_mul_f32 v108, v86, v104
	v_mul_f32 v109, v87, v104
	v_mul_f32 v110, v84, v104
	v_mul_f32 v111, v85, v104
	v_mul_f32_e32 v100, v108, v108
	v_mul_f32_e32 v116, v110, v110
	v_mul_f32_e32 v128, v111, v111
	v_mul_f32_e32 v102, v109, v109
	v_add_f32 v116, v116, v128
	v_add_f32 v117, v117, v129
	v_add_f32 v100, v100, v102
	v_add_f32 v101, v101, v103
	v_and_b32_e32 v102, 64, v236
	v_add_f32 v100, v116, v100
	v_add_f32 v101, v117, v101
	v_add_u32_e32 v102, 64, v102
	v_add_f32_e32 v100, v100, v101
	ds_swizzle_b32 v101, v100 offset:swizzle(SWAP,16)
	v_mov_b32_e32 v141, v2
	v_lshl_add_u64 v[126:127], v[126:127], 0, v[140:141]
	s_mov_b64 s[0:1], 0
	s_waitcnt lgkmcnt(0)
	v_add_f32_e32 v100, v100, v101
	v_xor_b32_e32 v101, 32, v236
	v_cmp_lt_i32_e32 vcc, v101, v102
	s_nop 1
	v_cndmask_b32_e32 v101, v236, v101, vcc
	v_lshlrev_b32_e32 v101, 2, v101
	ds_bpermute_b32 v101, v101, v100
	s_waitcnt lgkmcnt(0)
	v_add_f32_e32 v100, v100, v101
	v_fmamk_f32 v100, v100, 0x3c800000, v231
	v_cmp_gt_f32_e32 vcc, s11, v100
	v_mul_f32_e32 v101, 0x4b800000, v100
	s_nop 0
	v_cndmask_b32_e32 v100, v100, v101, vcc
	v_rsq_f32_e32 v100, v100
	s_nop 0
	v_mul_f32_e32 v101, 0x45800000, v100
	v_cndmask_b32_e32 v100, v100, v101, vcc
	v_mul_f32_e32 v116, 0x3e38aa3b, v100
	global_load_dwordx4 v[100:103], v166, s[26:27] offset:16
	global_load_dwordx4 v[128:131], v166, s[26:27]
	v_mul_f32 v124, v124, v116
	v_mul_f32 v125, v125, v116
	v_mul_f32 v122, v122, v116
	v_mul_f32 v123, v123, v116
	v_mul_f32 v120, v120, v116
	v_mul_f32 v121, v121, v116
	v_mul_f32 v118, v118, v116
	v_mul_f32 v119, v119, v116
	v_mul_f32 v114, v114, v116
	v_mul_f32 v115, v115, v116
	v_mul_f32 v112, v112, v116
	v_mul_f32 v113, v113, v116
	v_mul_f32 v110, v110, v116
	v_mul_f32 v111, v111, v116
	v_mul_f32 v108, v108, v116
	v_mul_f32 v109, v109, v116
	s_waitcnt vmcnt(1)
	v_mul_f32 v118, v102, v118
	v_mul_f32 v119, v103, v119
	s_waitcnt vmcnt(0)
	v_mul_f32 v122, v130, v122
	v_mul_f32 v123, v131, v123
	v_mul_f32 v124, v128, v124
	v_mul_f32 v125, v129, v125
	v_mul_f32 v102, v100, v120
	v_mul_f32 v103, v101, v121
	v_cvt_pk_bf16_f32 v100, v124, v125
	v_cvt_pk_bf16_f32 v101, v122, v123
	v_cvt_pk_bf16_f32 v102, v102, v103
	v_cvt_pk_bf16_f32 v103, v118, v119
	global_store_dwordx4 v[126:127], v[100:103], off
	global_load_dwordx4 v[100:103], v166, s[26:27] offset:144
	s_nop 0
	global_load_dwordx4 v[118:121], v166, s[26:27] offset:128
	s_waitcnt vmcnt(1)
	v_mul_f32 v108, v102, v108
	v_mul_f32 v109, v103, v109
	s_waitcnt vmcnt(0)
	v_mul_f32 v112, v120, v112
	v_mul_f32 v113, v121, v113
	v_mul_f32 v114, v118, v114
	v_mul_f32 v115, v119, v115
	v_mul_f32 v102, v100, v110
	v_mul_f32 v103, v101, v111
	v_cvt_pk_bf16_f32 v100, v114, v115
	v_cvt_pk_bf16_f32 v101, v112, v113
	v_cvt_pk_bf16_f32 v102, v102, v103
	v_cvt_pk_bf16_f32 v103, v108, v109
	global_store_dwordx4 v[126:127], v[100:103], off offset:64
.LBB0_1788:
	s_andn2_b64 vcc, exec, s[0:1]
	s_cbranch_vccnz .LBB0_1796
	s_movk_i32 s0, 0x3fff
	v_cmp_lt_i32_e32 vcc, s0, v106
	v_mov_b64_e32 v[100:101], 0
	s_and_saveexec_b64 s[0:1], vcc
	v_add_u32_e32 v100, 0xffffc020, v142
	v_lshrrev_b32_e32 v100, 3, v100
	v_mad_u64_u32 v[102:103], s[8:9], v100, 15, v[132:133]
	v_mov_b64_e32 v[100:101], s[30:31]
	v_mad_u64_u32 v[100:101], s[8:9], v102, s91, v[100:101]
	v_mad_u32_u24 v101, v103, s91, v101
	s_or_b64 exec, exec, s[0:1]
	s_lshl_b32 s0, s78, 8
	s_or_b32 s0, s14, s0
	v_or_b32_e32 v110, s0, v155
	v_mov_b64_e32 v[102:103], s[22:23]
	v_mul_f32 v98, v98, v104
	v_mul_f32 v99, v99, v104
	v_mul_f32 v96, v96, v104
	v_mul_f32 v97, v97, v104
	v_mul_f32 v94, v94, v104
	v_mul_f32 v95, v95, v104
	v_mul_f32 v92, v92, v104
	v_mul_f32 v93, v93, v104
	v_mad_i64_i32 v[102:103], s[0:1], v106, s71, v[102:103]
	v_ashrrev_i32_e32 v111, 31, v110
	v_cmp_ne_u64_e32 vcc, 0, v[100:101]
	v_lshl_add_u64 v[102:103], v[110:111], 1, v[102:103]
	v_cvt_pk_bf16_f32 v106, v96, v97
	v_cvt_pk_bf16_f32 v107, v98, v99
	v_cvt_pk_bf16_f32 v108, v92, v93
	v_cvt_pk_bf16_f32 v109, v94, v95
	v_lshl_add_u64 v[100:101], v[110:111], 2, v[100:101]
	global_store_dwordx4 v[102:103], v[106:109], off
	s_and_saveexec_b64 s[0:1], vcc
	s_cbranch_execz .LBB0_1793
	global_store_dwordx4 v[100:101], v[96:99], off
	global_store_dwordx4 v[100:101], v[92:95], off offset:16
.LBB0_1793:
	s_or_b64 exec, exec, s[0:1]
	v_mov_b32_e32 v105, v104
	v_mov_b32_e32 v92, v104
	v_mov_b32_e32 v93, v104
	v_mul_f32 v90, v90, v92
	v_mul_f32 v91, v91, v93
	v_mul_f32 v88, v88, v104
	v_mul_f32 v89, v89, v105
	v_mul_f32 v86, v86, v92
	v_mul_f32 v87, v87, v93
	v_mul_f32 v84, v84, v104
	v_mul_f32 v85, v85, v105
	v_cvt_pk_bf16_f32 v92, v88, v89
	v_cvt_pk_bf16_f32 v93, v90, v91
	v_cvt_pk_bf16_f32 v94, v84, v85
	v_cvt_pk_bf16_f32 v95, v86, v87
	global_store_dwordx4 v[102:103], v[92:95], off offset:64
	s_and_saveexec_b64 s[0:1], vcc
	s_cbranch_execz .LBB0_1795
	global_store_dwordx4 v[100:101], v[88:91], off offset:128
	global_store_dwordx4 v[100:101], v[84:87], off offset:144

.LBB0_1796:
	s_nop 0
	v_fmamk_f32 v84, v172, 0x3a800000, v231
	v_cmp_gt_f32_e32 vcc, s11, v84
	v_mul_f32_e32 v85, 0x4b800000, v84
	v_or_b32_e32 v90, 48, v142
	v_cndmask_b32_e32 v84, v84, v85, vcc
	v_rsq_f32_e32 v84, v84
	s_mov_b64 s[0:1], -1
	v_mul_f32_e32 v85, 0x45800000, v84
	v_cndmask_b32_e32 v88, v84, v85, vcc
	s_and_b64 vcc, exec, s[18:19]
	s_cbranch_vccnz .LBB0_1798
	v_ashrrev_i32_e32 v91, 31, v90
	v_lshlrev_b64 v[84:85], 9, v[90:91]
	v_lshl_add_u64 v[84:85], s[24:25], 0, v[84:85]
	s_lshl_b32 s68, s14, 1
	v_mul_f32 v106, v82, v88
	v_mul_f32 v107, v83, v88
	v_mul_f32 v108, v80, v88
	v_mul_f32 v109, v81, v88
	v_lshl_add_u64 v[110:111], v[84:85], 0, s[68:69]
	v_mul_f32 v84, v106, v106
	v_mul_f32 v85, v107, v107
	v_mul_f32 v86, v108, v108
	v_mul_f32 v87, v109, v109
	v_mul_f32 v102, v78, v88
	v_mul_f32 v103, v79, v88
	v_pk_mov_b32 v[92:93], v[86:87], v[84:85] op_sel:[1,0]
	v_mov_b32_e32 v87, v85
	v_add_f32 v84, v92, v86
	v_add_f32 v85, v93, v87
	v_mul_f32 v104, v76, v88
	v_mul_f32 v105, v77, v88
	v_add_f32 v85, v84, v85
	v_add_f32 v84, v84, v84
	v_mul_f32 v86, v102, v102
	v_mul_f32 v87, v103, v103
	v_mul_f32 v92, v104, v104
	v_mul_f32 v93, v105, v105
	v_mul_f32 v98, v72, v88
	v_mul_f32 v99, v73, v88
	v_pk_mov_b32 v[94:95], v[92:93], v[86:87] op_sel:[1,0]
	v_mov_b32_e32 v93, v87
	v_mul_f32 v96, v74, v88
	v_mul_f32 v97, v75, v88
	v_mul_f32_e32 v84, v98, v98
	v_add_f32 v86, v94, v92
	v_add_f32 v87, v95, v93
	v_fma_f32 v100, v98, v98, v84
	v_fma_f32 v101, v99, v99, v84
	v_mul_f32_e32 v84, v96, v96
	v_add_f32 v87, v86, v87
	v_add_f32 v86, v86, v86
	v_fma_f32 v112, v96, v96, v84
	v_fma_f32 v113, v97, v97, v84
	v_mul_f32 v92, v70, v88
	v_mul_f32 v93, v71, v88
	v_mul_f32 v94, v68, v88
	v_mul_f32 v95, v69, v88
	v_mul_f32_e32 v84, v92, v92
	v_mul_f32_e32 v100, v94, v94
	v_mul_f32_e32 v112, v95, v95
	v_mul_f32_e32 v86, v93, v93
	v_add_f32 v100, v100, v112
	v_add_f32 v101, v101, v113
	v_add_f32 v84, v84, v86
	v_add_f32 v85, v85, v87
	v_and_b32_e32 v86, 64, v236
	v_add_f32 v84, v100, v84
	v_add_f32 v85, v101, v85
	v_add_u32_e32 v86, 64, v86
	v_add_f32_e32 v84, v84, v85
	ds_swizzle_b32 v85, v84 offset:swizzle(SWAP,16)
	v_mov_b32_e32 v141, v2
	v_lshl_add_u64 v[110:111], v[110:111], 0, v[140:141]
	s_mov_b64 s[0:1], 0
	s_waitcnt lgkmcnt(0)
	v_add_f32_e32 v84, v84, v85
	v_xor_b32_e32 v85, 32, v236
	v_cmp_lt_i32_e32 vcc, v85, v86
	s_nop 1
	v_cndmask_b32_e32 v85, v236, v85, vcc
	v_lshlrev_b32_e32 v85, 2, v85
	ds_bpermute_b32 v85, v85, v84
	s_waitcnt lgkmcnt(0)
	v_add_f32_e32 v84, v84, v85
	v_fmamk_f32 v84, v84, 0x3c800000, v231
	v_cmp_gt_f32_e32 vcc, s11, v84
	v_mul_f32_e32 v85, 0x4b800000, v84
	s_nop 0
	v_cndmask_b32_e32 v84, v84, v85, vcc
	v_rsq_f32_e32 v84, v84
	s_nop 0
	v_mul_f32_e32 v85, 0x45800000, v84
	v_cndmask_b32_e32 v84, v84, v85, vcc
	v_mul_f32_e32 v100, 0x3e38aa3b, v84
	global_load_dwordx4 v[84:87], v166, s[26:27] offset:16
	global_load_dwordx4 v[112:115], v166, s[26:27]
	v_mul_f32 v108, v108, v100
	v_mul_f32 v109, v109, v100
	v_mul_f32 v106, v106, v100
	v_mul_f32 v107, v107, v100
	v_mul_f32 v104, v104, v100
	v_mul_f32 v105, v105, v100
	v_mul_f32 v102, v102, v100
	v_mul_f32 v103, v103, v100
	v_mul_f32 v98, v98, v100
	v_mul_f32 v99, v99, v100
	v_mul_f32 v96, v96, v100
	v_mul_f32 v97, v97, v100
	v_mul_f32 v94, v94, v100
	v_mul_f32 v95, v95, v100
	v_mul_f32 v92, v92, v100
	v_mul_f32 v93, v93, v100
	s_waitcnt vmcnt(1)
	v_mul_f32 v102, v86, v102
	v_mul_f32 v103, v87, v103
	s_waitcnt vmcnt(0)
	v_mul_f32 v106, v114, v106
	v_mul_f32 v107, v115, v107
	v_mul_f32 v108, v112, v108
	v_mul_f32 v109, v113, v109
	v_mul_f32 v86, v84, v104
	v_mul_f32 v87, v85, v105
	v_cvt_pk_bf16_f32 v84, v108, v109
	v_cvt_pk_bf16_f32 v85, v106, v107
	v_cvt_pk_bf16_f32 v86, v86, v87
	v_cvt_pk_bf16_f32 v87, v102, v103
	global_store_dwordx4 v[110:111], v[84:87], off
	global_load_dwordx4 v[84:87], v166, s[26:27] offset:144
	s_nop 0
	global_load_dwordx4 v[102:105], v166, s[26:27] offset:128
	s_waitcnt vmcnt(1)
	v_mul_f32 v92, v86, v92
	v_mul_f32 v93, v87, v93
	s_waitcnt vmcnt(0)
	v_mul_f32 v96, v104, v96
	v_mul_f32 v97, v105, v97
	v_mul_f32 v98, v102, v98
	v_mul_f32 v99, v103, v99
	v_mul_f32 v86, v84, v94
	v_mul_f32 v87, v85, v95
	v_cvt_pk_bf16_f32 v84, v98, v99
	v_cvt_pk_bf16_f32 v85, v96, v97
	v_cvt_pk_bf16_f32 v86, v86, v87
	v_cvt_pk_bf16_f32 v87, v92, v93
	global_store_dwordx4 v[110:111], v[84:87], off offset:64

.LBB0_1805:
	s_or_b64 exec, exec, s[0:1]
	s_lshl_b32 s0, s78, 8
	s_or_b32 s0, s14, s0
	v_or_b32_e32 v94, s0, v155
	v_mov_b64_e32 v[86:87], s[22:23]
	v_mul_f32 v82, v82, v88
	v_mul_f32 v83, v83, v88
	v_mul_f32 v80, v80, v88
	v_mul_f32 v81, v81, v88
	v_mul_f32 v78, v78, v88
	v_mul_f32 v79, v79, v88
	v_mul_f32 v76, v76, v88
	v_mul_f32 v77, v77, v88
	v_mad_i64_i32 v[86:87], s[0:1], v90, s71, v[86:87]
	v_ashrrev_i32_e32 v95, 31, v94
	v_cmp_ne_u64_e32 vcc, 0, v[84:85]
	v_lshl_add_u64 v[86:87], v[94:95], 1, v[86:87]
	v_cvt_pk_bf16_f32 v90, v80, v81
	v_cvt_pk_bf16_f32 v91, v82, v83
	v_cvt_pk_bf16_f32 v92, v76, v77
	v_cvt_pk_bf16_f32 v93, v78, v79
	v_lshl_add_u64 v[84:85], v[94:95], 2, v[84:85]
	global_store_dwordx4 v[86:87], v[90:93], off
	s_and_saveexec_b64 s[0:1], vcc
	s_cbranch_execz .LBB0_1807
	global_store_dwordx4 v[84:85], v[80:83], off
	global_store_dwordx4 v[84:85], v[76:79], off offset:16
.LBB0_1807:
	s_or_b64 exec, exec, s[0:1]
	v_mov_b32_e32 v89, v88
	v_mov_b32_e32 v76, v88
	v_mov_b32_e32 v77, v88
	v_mul_f32 v74, v74, v76
	v_mul_f32 v75, v75, v77
	v_mul_f32 v72, v72, v88
	v_mul_f32 v73, v73, v89
	v_mul_f32 v70, v70, v76
	v_mul_f32 v71, v71, v77
	v_mul_f32 v68, v68, v88
	v_mul_f32 v69, v69, v89
	v_cvt_pk_bf16_f32 v76, v72, v73
	v_cvt_pk_bf16_f32 v77, v74, v75
	v_cvt_pk_bf16_f32 v78, v68, v69
	v_cvt_pk_bf16_f32 v79, v70, v71
	global_store_dwordx4 v[86:87], v[76:79], off offset:64
	s_and_saveexec_b64 s[0:1], vcc
	s_cbranch_execz .LBB0_1809
	global_store_dwordx4 v[84:85], v[72:75], off offset:128
	global_store_dwordx4 v[84:85], v[68:71], off offset:144

.LBB0_1810:
	s_nop 0
	v_fmamk_f32 v68, v171, 0x3a800000, v231
	v_cmp_gt_f32_e32 vcc, s11, v68
	v_mul_f32_e32 v69, 0x4b800000, v68
	s_addk_i32 s15, 0x80
	v_cndmask_b32_e32 v68, v68, v69, vcc
	v_rsq_f32_e32 v68, v68
	v_or_b32_e32 v72, s15, v170
	s_mov_b64 s[0:1], -1
	v_mul_f32_e32 v69, 0x45800000, v68
	v_cndmask_b32_e32 v74, v68, v69, vcc
	s_and_b64 vcc, exec, s[18:19]
	s_cbranch_vccnz .LBB0_1812
	v_ashrrev_i32_e32 v73, 31, v72
	v_lshlrev_b64 v[68:69], 9, v[72:73]
	v_lshl_add_u64 v[68:69], s[24:25], 0, v[68:69]
	s_lshl_b32 s68, s14, 1
	v_mul_f32 v90, v66, v74
	v_mul_f32 v91, v67, v74
	v_mul_f32 v92, v64, v74
	v_mul_f32 v93, v65, v74
	v_lshl_add_u64 v[94:95], v[68:69], 0, s[68:69]
	v_mul_f32 v68, v90, v90
	v_mul_f32 v69, v91, v91
	v_mul_f32 v70, v92, v92
	v_mul_f32 v71, v93, v93
	v_mul_f32 v86, v62, v74
	v_mul_f32 v87, v63, v74
	v_pk_mov_b32 v[76:77], v[70:71], v[68:69] op_sel:[1,0]
	v_mov_b32_e32 v71, v69
	v_add_f32 v68, v76, v70
	v_add_f32 v69, v77, v71
	v_mul_f32 v88, v60, v74
	v_mul_f32 v89, v61, v74
	v_add_f32 v69, v68, v69
	v_add_f32 v68, v68, v68
	v_mul_f32 v70, v86, v86
	v_mul_f32 v71, v87, v87
	v_mul_f32 v76, v88, v88
	v_mul_f32 v77, v89, v89
	v_mul_f32 v82, v56, v74
	v_mul_f32 v83, v57, v74
	v_pk_mov_b32 v[78:79], v[76:77], v[70:71] op_sel:[1,0]
	v_mov_b32_e32 v77, v71
	v_mul_f32 v80, v58, v74
	v_mul_f32 v81, v59, v74
	v_mul_f32_e32 v68, v82, v82
	v_add_f32 v70, v78, v76
	v_add_f32 v71, v79, v77
	v_fma_f32 v84, v82, v82, v68
	v_fma_f32 v85, v83, v83, v68
	v_mul_f32_e32 v68, v80, v80
	v_add_f32 v71, v70, v71
	v_add_f32 v70, v70, v70
	v_fma_f32 v96, v80, v80, v68
	v_fma_f32 v97, v81, v81, v68
	v_mul_f32 v76, v54, v74
	v_mul_f32 v77, v55, v74
	v_mul_f32 v78, v52, v74
	v_mul_f32 v79, v53, v74
	v_mul_f32_e32 v68, v76, v76
	v_mul_f32_e32 v84, v78, v78
	v_mul_f32_e32 v96, v79, v79
	v_mul_f32_e32 v70, v77, v77
	v_add_f32 v84, v84, v96
	v_add_f32 v85, v85, v97
	v_add_f32 v68, v68, v70
	v_add_f32 v69, v69, v71
	v_and_b32_e32 v70, 64, v236
	v_add_f32 v68, v84, v68
	v_add_f32 v69, v85, v69
	v_add_u32_e32 v70, 64, v70
	v_add_f32_e32 v68, v68, v69
	ds_swizzle_b32 v69, v68 offset:swizzle(SWAP,16)
	v_mov_b32_e32 v141, v2
	v_lshl_add_u64 v[94:95], v[94:95], 0, v[140:141]
	s_mov_b64 s[0:1], 0
	s_waitcnt lgkmcnt(0)
	v_add_f32_e32 v68, v68, v69
	v_xor_b32_e32 v69, 32, v236
	v_cmp_lt_i32_e32 vcc, v69, v70
	s_nop 1
	v_cndmask_b32_e32 v69, v236, v69, vcc
	v_lshlrev_b32_e32 v69, 2, v69
	ds_bpermute_b32 v69, v69, v68
	s_waitcnt lgkmcnt(0)
	v_add_f32_e32 v68, v68, v69
	v_fmamk_f32 v68, v68, 0x3c800000, v231
	v_cmp_gt_f32_e32 vcc, s11, v68
	v_mul_f32_e32 v69, 0x4b800000, v68
	s_nop 0
	v_cndmask_b32_e32 v68, v68, v69, vcc
	v_rsq_f32_e32 v68, v68
	s_nop 0
	v_mul_f32_e32 v69, 0x45800000, v68
	v_cndmask_b32_e32 v68, v68, v69, vcc
	v_mul_f32_e32 v84, 0x3e38aa3b, v68
	global_load_dwordx4 v[68:71], v166, s[26:27] offset:16
	global_load_dwordx4 v[96:99], v166, s[26:27]
	v_mul_f32 v92, v92, v84
	v_mul_f32 v93, v93, v84
	v_mul_f32 v90, v90, v84
	v_mul_f32 v91, v91, v84
	v_mul_f32 v88, v88, v84
	v_mul_f32 v89, v89, v84
	v_mul_f32 v86, v86, v84
	v_mul_f32 v87, v87, v84
	v_mul_f32 v82, v82, v84
	v_mul_f32 v83, v83, v84
	v_mul_f32 v80, v80, v84
	v_mul_f32 v81, v81, v84
	v_mul_f32 v78, v78, v84
	v_mul_f32 v79, v79, v84
	v_mul_f32 v76, v76, v84
	v_mul_f32 v77, v77, v84
	s_waitcnt vmcnt(1)
	v_mul_f32 v86, v70, v86
	v_mul_f32 v87, v71, v87
	s_waitcnt vmcnt(0)
	v_mul_f32 v90, v98, v90
	v_mul_f32 v91, v99, v91
	v_mul_f32 v92, v96, v92
	v_mul_f32 v93, v97, v93
	v_mul_f32 v70, v68, v88
	v_mul_f32 v71, v69, v89
	v_cvt_pk_bf16_f32 v68, v92, v93
	v_cvt_pk_bf16_f32 v69, v90, v91
	v_cvt_pk_bf16_f32 v70, v70, v71
	v_cvt_pk_bf16_f32 v71, v86, v87
	global_store_dwordx4 v[94:95], v[68:71], off
	global_load_dwordx4 v[68:71], v166, s[26:27] offset:144
	s_nop 0
	global_load_dwordx4 v[86:89], v166, s[26:27] offset:128
	s_waitcnt vmcnt(1)
	v_mul_f32 v76, v70, v76
	v_mul_f32 v77, v71, v77
	s_waitcnt vmcnt(0)
	v_mul_f32 v80, v88, v80
	v_mul_f32 v81, v89, v81
	v_mul_f32 v82, v86, v82
	v_mul_f32 v83, v87, v83
	v_mul_f32 v70, v68, v78
	v_mul_f32 v71, v69, v79
	v_cvt_pk_bf16_f32 v68, v82, v83
	v_cvt_pk_bf16_f32 v69, v80, v81
	v_cvt_pk_bf16_f32 v70, v70, v71
	v_cvt_pk_bf16_f32 v71, v76, v77
	global_store_dwordx4 v[94:95], v[68:71], off offset:64
.LBB0_1812:
	s_andn2_b64 vcc, exec, s[0:1]
	s_cbranch_vccnz .LBB0_1820
	s_movk_i32 s0, 0x3fff
	v_cmp_lt_i32_e32 vcc, s0, v72
	v_mov_b64_e32 v[68:69], 0
	s_and_saveexec_b64 s[0:1], vcc
	v_add_u32_e32 v68, 0xffffc000, v72
	v_lshrrev_b32_e32 v68, 3, v68
	v_mad_u64_u32 v[70:71], s[8:9], v68, 15, v[132:133]
	v_mov_b64_e32 v[68:69], s[30:31]
	v_mad_u64_u32 v[68:69], s[8:9], v70, s91, v[68:69]
	v_mad_u32_u24 v69, v71, s91, v69
	s_or_b64 exec, exec, s[0:1]
	s_lshl_b32 s0, s78, 8
	s_or_b32 s0, s14, s0
	v_or_b32_e32 v80, s0, v155
	v_mov_b64_e32 v[70:71], s[22:23]
	v_mul_f32 v66, v66, v74
	v_mul_f32 v67, v67, v74
	v_mul_f32 v64, v64, v74
	v_mul_f32 v65, v65, v74
	v_mul_f32 v62, v62, v74
	v_mul_f32 v63, v63, v74
	v_mul_f32 v60, v60, v74
	v_mul_f32 v61, v61, v74
	v_mad_i64_i32 v[70:71], s[0:1], v72, s71, v[70:71]
	v_ashrrev_i32_e32 v81, 31, v80
	v_cmp_ne_u64_e32 vcc, 0, v[68:69]
	v_lshl_add_u64 v[70:71], v[80:81], 1, v[70:71]
	v_cvt_pk_bf16_f32 v76, v64, v65
	v_cvt_pk_bf16_f32 v77, v66, v67
	v_cvt_pk_bf16_f32 v78, v60, v61
	v_cvt_pk_bf16_f32 v79, v62, v63
	v_lshl_add_u64 v[68:69], v[80:81], 2, v[68:69]
	global_store_dwordx4 v[70:71], v[76:79], off
	s_and_saveexec_b64 s[0:1], vcc
	s_cbranch_execz .LBB0_1817
	global_store_dwordx4 v[68:69], v[64:67], off
	global_store_dwordx4 v[68:69], v[60:63], off offset:16
.LBB0_1817:
	s_or_b64 exec, exec, s[0:1]
	v_mov_b32_e32 v75, v74
	v_mov_b32_e32 v60, v74
	v_mov_b32_e32 v61, v74
	v_mul_f32 v58, v58, v60
	v_mul_f32 v59, v59, v61
	v_mul_f32 v56, v56, v74
	v_mul_f32 v57, v57, v75
	v_mul_f32 v54, v54, v60
	v_mul_f32 v55, v55, v61
	v_mul_f32 v52, v52, v74
	v_mul_f32 v53, v53, v75
	v_cvt_pk_bf16_f32 v60, v56, v57
	v_cvt_pk_bf16_f32 v61, v58, v59
	v_cvt_pk_bf16_f32 v62, v52, v53
	v_cvt_pk_bf16_f32 v63, v54, v55
	global_store_dwordx4 v[70:71], v[60:63], off offset:64
	s_and_saveexec_b64 s[0:1], vcc
	s_cbranch_execz .LBB0_1819
	global_store_dwordx4 v[68:69], v[56:59], off offset:128
	global_store_dwordx4 v[68:69], v[52:55], off offset:144

.LBB0_1820:
	s_nop 0
	v_fmamk_f32 v52, v169, 0x3a800000, v231
	v_cmp_gt_f32_e32 vcc, s11, v52
	v_mul_f32_e32 v53, 0x4b800000, v52
	v_or_b32_e32 v58, 16, v72
	v_cndmask_b32_e32 v52, v52, v53, vcc
	v_rsq_f32_e32 v52, v52
	s_mov_b64 s[0:1], -1
	v_mul_f32_e32 v53, 0x45800000, v52
	v_cndmask_b32_e32 v56, v52, v53, vcc
	s_and_b64 vcc, exec, s[18:19]
	s_cbranch_vccnz .LBB0_1822
	v_ashrrev_i32_e32 v59, 31, v58
	v_lshlrev_b64 v[52:53], 9, v[58:59]
	v_lshl_add_u64 v[52:53], s[24:25], 0, v[52:53]
	s_lshl_b32 s68, s14, 1
	v_mul_f32 v76, v50, v56
	v_mul_f32 v77, v51, v56
	v_mul_f32 v78, v48, v56
	v_mul_f32 v79, v49, v56
	v_lshl_add_u64 v[80:81], v[52:53], 0, s[68:69]
	v_mul_f32 v52, v76, v76
	v_mul_f32 v53, v77, v77
	v_mul_f32 v54, v78, v78
	v_mul_f32 v55, v79, v79
	v_mul_f32 v70, v46, v56
	v_mul_f32 v71, v47, v56
	v_pk_mov_b32 v[60:61], v[54:55], v[52:53] op_sel:[1,0]
	v_mov_b32_e32 v55, v53
	v_add_f32 v52, v60, v54
	v_add_f32 v53, v61, v55
	v_mul_f32 v74, v44, v56
	v_mul_f32 v75, v45, v56
	v_add_f32 v53, v52, v53
	v_add_f32 v52, v52, v52
	v_mul_f32 v54, v70, v70
	v_mul_f32 v55, v71, v71
	v_mul_f32 v60, v74, v74
	v_mul_f32 v61, v75, v75
	v_mul_f32 v66, v40, v56
	v_mul_f32 v67, v41, v56
	v_pk_mov_b32 v[62:63], v[60:61], v[54:55] op_sel:[1,0]
	v_mov_b32_e32 v61, v55
	v_mul_f32 v64, v42, v56
	v_mul_f32 v65, v43, v56
	v_mul_f32_e32 v52, v66, v66
	v_add_f32 v54, v62, v60
	v_add_f32 v55, v63, v61
	v_fma_f32 v68, v66, v66, v52
	v_fma_f32 v69, v67, v67, v52
	v_mul_f32_e32 v52, v64, v64
	v_add_f32 v55, v54, v55
	v_add_f32 v54, v54, v54
	v_fma_f32 v82, v64, v64, v52
	v_fma_f32 v83, v65, v65, v52
	v_mul_f32 v60, v38, v56
	v_mul_f32 v61, v39, v56
	v_mul_f32 v62, v36, v56
	v_mul_f32 v63, v37, v56
	v_mul_f32_e32 v52, v60, v60
	v_mul_f32_e32 v68, v62, v62
	v_mul_f32_e32 v82, v63, v63
	v_mul_f32_e32 v54, v61, v61
	v_add_f32 v68, v68, v82
	v_add_f32 v69, v69, v83
	v_add_f32 v52, v52, v54
	v_add_f32 v53, v53, v55
	v_and_b32_e32 v54, 64, v236
	v_add_f32 v52, v68, v52
	v_add_f32 v53, v69, v53
	v_add_u32_e32 v54, 64, v54
	v_add_f32_e32 v52, v52, v53
	ds_swizzle_b32 v53, v52 offset:swizzle(SWAP,16)
	v_mov_b32_e32 v141, v2
	v_lshl_add_u64 v[80:81], v[80:81], 0, v[140:141]
	s_mov_b64 s[0:1], 0
	s_waitcnt lgkmcnt(0)
	v_add_f32_e32 v52, v52, v53
	v_xor_b32_e32 v53, 32, v236
	v_cmp_lt_i32_e32 vcc, v53, v54
	s_nop 1
	v_cndmask_b32_e32 v53, v236, v53, vcc
	v_lshlrev_b32_e32 v53, 2, v53
	ds_bpermute_b32 v53, v53, v52
	s_waitcnt lgkmcnt(0)
	v_add_f32_e32 v52, v52, v53
	v_fmamk_f32 v52, v52, 0x3c800000, v231
	v_cmp_gt_f32_e32 vcc, s11, v52
	v_mul_f32_e32 v53, 0x4b800000, v52
	s_nop 0
	v_cndmask_b32_e32 v52, v52, v53, vcc
	v_rsq_f32_e32 v52, v52
	s_nop 0
	v_mul_f32_e32 v53, 0x45800000, v52
	v_cndmask_b32_e32 v52, v52, v53, vcc
	v_mul_f32_e32 v68, 0x3e38aa3b, v52
	global_load_dwordx4 v[52:55], v166, s[26:27] offset:16
	global_load_dwordx4 v[82:85], v166, s[26:27]
	v_mul_f32 v78, v78, v68
	v_mul_f32 v79, v79, v68
	v_mul_f32 v76, v76, v68
	v_mul_f32 v77, v77, v68
	v_mul_f32 v74, v74, v68
	v_mul_f32 v75, v75, v68
	v_mul_f32 v70, v70, v68
	v_mul_f32 v71, v71, v68
	v_mul_f32 v66, v66, v68
	v_mul_f32 v67, v67, v68
	v_mul_f32 v64, v64, v68
	v_mul_f32 v65, v65, v68
	v_mul_f32 v62, v62, v68
	v_mul_f32 v63, v63, v68
	v_mul_f32 v60, v60, v68
	v_mul_f32 v61, v61, v68
	s_waitcnt vmcnt(1)
	v_mul_f32 v70, v54, v70
	v_mul_f32 v71, v55, v71
	s_waitcnt vmcnt(0)
	v_mul_f32 v76, v84, v76
	v_mul_f32 v77, v85, v77
	v_mul_f32 v78, v82, v78
	v_mul_f32 v79, v83, v79
	v_mul_f32 v54, v52, v74
	v_mul_f32 v55, v53, v75
	v_cvt_pk_bf16_f32 v52, v78, v79
	v_cvt_pk_bf16_f32 v53, v76, v77
	v_cvt_pk_bf16_f32 v54, v54, v55
	v_cvt_pk_bf16_f32 v55, v70, v71
	global_store_dwordx4 v[80:81], v[52:55], off
	global_load_dwordx4 v[52:55], v166, s[26:27] offset:144
	s_nop 0
	global_load_dwordx4 v[74:77], v166, s[26:27] offset:128
	s_waitcnt vmcnt(1)
	v_mul_f32 v60, v54, v60
	v_mul_f32 v61, v55, v61
	s_waitcnt vmcnt(0)
	v_mul_f32 v64, v76, v64
	v_mul_f32 v65, v77, v65
	v_mul_f32 v66, v74, v66
	v_mul_f32 v67, v75, v67
	v_mul_f32 v54, v52, v62
	v_mul_f32 v55, v53, v63
	v_cvt_pk_bf16_f32 v52, v66, v67
	v_cvt_pk_bf16_f32 v53, v64, v65
	v_cvt_pk_bf16_f32 v54, v54, v55
	v_cvt_pk_bf16_f32 v55, v60, v61
	global_store_dwordx4 v[80:81], v[52:55], off offset:64
.LBB0_1822:
	s_andn2_b64 vcc, exec, s[0:1]
	s_cbranch_vccnz .LBB0_1830
	s_movk_i32 s0, 0x3fff
	v_cmp_lt_i32_e32 vcc, s0, v58
	v_mov_b64_e32 v[52:53], 0
	s_and_saveexec_b64 s[0:1], vcc
	v_add_u32_e32 v52, 0xffffc010, v72
	v_lshrrev_b32_e32 v52, 3, v52
	v_mad_u64_u32 v[54:55], s[8:9], v52, 15, v[132:133]
	v_mov_b64_e32 v[52:53], s[30:31]
	v_mad_u64_u32 v[52:53], s[8:9], v54, s91, v[52:53]
	v_mad_u32_u24 v53, v55, s91, v53
	s_or_b64 exec, exec, s[0:1]
	s_lshl_b32 s0, s78, 8
	s_or_b32 s0, s14, s0
	v_or_b32_e32 v62, s0, v155
	v_mov_b64_e32 v[54:55], s[22:23]
	v_mul_f32 v50, v50, v56
	v_mul_f32 v51, v51, v56
	v_mul_f32 v48, v48, v56
	v_mul_f32 v49, v49, v56
	v_mul_f32 v46, v46, v56
	v_mul_f32 v47, v47, v56
	v_mul_f32 v44, v44, v56
	v_mul_f32 v45, v45, v56
	v_mad_i64_i32 v[54:55], s[0:1], v58, s71, v[54:55]
	v_ashrrev_i32_e32 v63, 31, v62
	v_cmp_ne_u64_e32 vcc, 0, v[52:53]
	v_lshl_add_u64 v[54:55], v[62:63], 1, v[54:55]
	v_cvt_pk_bf16_f32 v58, v48, v49
	v_cvt_pk_bf16_f32 v59, v50, v51
	v_cvt_pk_bf16_f32 v60, v44, v45
	v_cvt_pk_bf16_f32 v61, v46, v47
	v_lshl_add_u64 v[52:53], v[62:63], 2, v[52:53]
	global_store_dwordx4 v[54:55], v[58:61], off
	s_and_saveexec_b64 s[0:1], vcc
	s_cbranch_execz .LBB0_1827
	global_store_dwordx4 v[52:53], v[48:51], off
	global_store_dwordx4 v[52:53], v[44:47], off offset:16
.LBB0_1827:
	s_or_b64 exec, exec, s[0:1]
	v_mov_b32_e32 v57, v56
	v_mov_b32_e32 v44, v56
	v_mov_b32_e32 v45, v56
	v_mul_f32 v42, v42, v44
	v_mul_f32 v43, v43, v45
	v_mul_f32 v40, v40, v56
	v_mul_f32 v41, v41, v57
	v_mul_f32 v38, v38, v44
	v_mul_f32 v39, v39, v45
	v_mul_f32 v36, v36, v56
	v_mul_f32 v37, v37, v57
	v_cvt_pk_bf16_f32 v44, v40, v41
	v_cvt_pk_bf16_f32 v45, v42, v43
	v_cvt_pk_bf16_f32 v46, v36, v37
	v_cvt_pk_bf16_f32 v47, v38, v39
	global_store_dwordx4 v[54:55], v[44:47], off offset:64
	s_and_saveexec_b64 s[0:1], vcc
	s_cbranch_execz .LBB0_1829
	global_store_dwordx4 v[52:53], v[40:43], off offset:128
	global_store_dwordx4 v[52:53], v[36:39], off offset:144

.LBB0_1830:
	s_nop 0
	v_fmamk_f32 v36, v168, 0x3a800000, v231
	v_cmp_gt_f32_e32 vcc, s11, v36
	v_mul_f32_e32 v37, 0x4b800000, v36
	v_or_b32_e32 v42, 32, v72
	v_cndmask_b32_e32 v36, v36, v37, vcc
	v_rsq_f32_e32 v36, v36
	s_mov_b64 s[0:1], -1
	v_mul_f32_e32 v37, 0x45800000, v36
	v_cndmask_b32_e32 v40, v36, v37, vcc
	s_and_b64 vcc, exec, s[18:19]
	s_cbranch_vccnz .LBB0_1832
	v_ashrrev_i32_e32 v43, 31, v42
	v_lshlrev_b64 v[36:37], 9, v[42:43]
	v_lshl_add_u64 v[36:37], s[24:25], 0, v[36:37]
	s_lshl_b32 s68, s14, 1
	v_mul_f32 v58, v34, v40
	v_mul_f32 v59, v35, v40
	v_mul_f32 v60, v32, v40
	v_mul_f32 v61, v33, v40
	v_lshl_add_u64 v[62:63], v[36:37], 0, s[68:69]
	v_mul_f32 v36, v58, v58
	v_mul_f32 v37, v59, v59
	v_mul_f32 v38, v60, v60
	v_mul_f32 v39, v61, v61
	v_mul_f32 v54, v30, v40
	v_mul_f32 v55, v31, v40
	v_pk_mov_b32 v[44:45], v[38:39], v[36:37] op_sel:[1,0]
	v_mov_b32_e32 v39, v37
	v_add_f32 v36, v44, v38
	v_add_f32 v37, v45, v39
	v_mul_f32 v56, v28, v40
	v_mul_f32 v57, v29, v40
	v_add_f32 v37, v36, v37
	v_add_f32 v36, v36, v36
	v_mul_f32 v38, v54, v54
	v_mul_f32 v39, v55, v55
	v_mul_f32 v44, v56, v56
	v_mul_f32 v45, v57, v57
	v_mul_f32 v50, v24, v40
	v_mul_f32 v51, v25, v40
	v_pk_mov_b32 v[46:47], v[44:45], v[38:39] op_sel:[1,0]
	v_mov_b32_e32 v45, v39
	v_mul_f32 v48, v26, v40
	v_mul_f32 v49, v27, v40
	v_mul_f32_e32 v36, v50, v50
	v_add_f32 v38, v46, v44
	v_add_f32 v39, v47, v45
	v_fma_f32 v52, v50, v50, v36
	v_fma_f32 v53, v51, v51, v36
	v_mul_f32_e32 v36, v48, v48
	v_add_f32 v39, v38, v39
	v_add_f32 v38, v38, v38
	v_fma_f32 v64, v48, v48, v36
	v_fma_f32 v65, v49, v49, v36
	v_mul_f32 v44, v22, v40
	v_mul_f32 v45, v23, v40
	v_mul_f32 v46, v20, v40
	v_mul_f32 v47, v21, v40
	v_mul_f32_e32 v36, v44, v44
	v_mul_f32_e32 v52, v46, v46
	v_mul_f32_e32 v64, v47, v47
	v_mul_f32_e32 v38, v45, v45
	v_add_f32 v52, v52, v64
	v_add_f32 v53, v53, v65
	v_add_f32 v36, v36, v38
	v_add_f32 v37, v37, v39
	v_and_b32_e32 v38, 64, v236
	v_add_f32 v36, v52, v36
	v_add_f32 v37, v53, v37
	v_add_u32_e32 v38, 64, v38
	v_add_f32_e32 v36, v36, v37
	ds_swizzle_b32 v37, v36 offset:swizzle(SWAP,16)
	v_mov_b32_e32 v141, v2
	v_lshl_add_u64 v[62:63], v[62:63], 0, v[140:141]
	s_mov_b64 s[0:1], 0
	s_waitcnt lgkmcnt(0)
	v_add_f32_e32 v36, v36, v37
	v_xor_b32_e32 v37, 32, v236
	v_cmp_lt_i32_e32 vcc, v37, v38
	s_nop 1
	v_cndmask_b32_e32 v37, v236, v37, vcc
	v_lshlrev_b32_e32 v37, 2, v37
	ds_bpermute_b32 v37, v37, v36
	s_waitcnt lgkmcnt(0)
	v_add_f32_e32 v36, v36, v37
	v_fmamk_f32 v36, v36, 0x3c800000, v231
	v_cmp_gt_f32_e32 vcc, s11, v36
	v_mul_f32_e32 v37, 0x4b800000, v36
	s_nop 0
	v_cndmask_b32_e32 v36, v36, v37, vcc
	v_rsq_f32_e32 v36, v36
	s_nop 0
	v_mul_f32_e32 v37, 0x45800000, v36
	v_cndmask_b32_e32 v36, v36, v37, vcc
	v_mul_f32_e32 v52, 0x3e38aa3b, v36
	global_load_dwordx4 v[36:39], v166, s[26:27] offset:16
	global_load_dwordx4 v[64:67], v166, s[26:27]
	v_mul_f32 v60, v60, v52
	v_mul_f32 v61, v61, v52
	v_mul_f32 v58, v58, v52
	v_mul_f32 v59, v59, v52
	v_mul_f32 v56, v56, v52
	v_mul_f32 v57, v57, v52
	v_mul_f32 v54, v54, v52
	v_mul_f32 v55, v55, v52
	v_mul_f32 v50, v50, v52
	v_mul_f32 v51, v51, v52
	v_mul_f32 v48, v48, v52
	v_mul_f32 v49, v49, v52
	v_mul_f32 v46, v46, v52
	v_mul_f32 v47, v47, v52
	v_mul_f32 v44, v44, v52
	v_mul_f32 v45, v45, v52
	s_waitcnt vmcnt(1)
	v_mul_f32 v54, v38, v54
	v_mul_f32 v55, v39, v55
	s_waitcnt vmcnt(0)
	v_mul_f32 v58, v66, v58
	v_mul_f32 v59, v67, v59
	v_mul_f32 v60, v64, v60
	v_mul_f32 v61, v65, v61
	v_mul_f32 v38, v36, v56
	v_mul_f32 v39, v37, v57
	v_cvt_pk_bf16_f32 v36, v60, v61
	v_cvt_pk_bf16_f32 v37, v58, v59
	v_cvt_pk_bf16_f32 v38, v38, v39
	v_cvt_pk_bf16_f32 v39, v54, v55
	global_store_dwordx4 v[62:63], v[36:39], off
	global_load_dwordx4 v[36:39], v166, s[26:27] offset:144
	s_nop 0
	global_load_dwordx4 v[54:57], v166, s[26:27] offset:128
	s_waitcnt vmcnt(1)
	v_mul_f32 v44, v38, v44
	v_mul_f32 v45, v39, v45
	s_waitcnt vmcnt(0)
	v_mul_f32 v48, v56, v48
	v_mul_f32 v49, v57, v49
	v_mul_f32 v50, v54, v50
	v_mul_f32 v51, v55, v51
	v_mul_f32 v38, v36, v46
	v_mul_f32 v39, v37, v47
	v_cvt_pk_bf16_f32 v36, v50, v51
	v_cvt_pk_bf16_f32 v37, v48, v49
	v_cvt_pk_bf16_f32 v38, v38, v39
	v_cvt_pk_bf16_f32 v39, v44, v45
	global_store_dwordx4 v[62:63], v[36:39], off offset:64
.LBB0_1832:
	s_andn2_b64 vcc, exec, s[0:1]
	s_cbranch_vccnz .LBB0_1840
	s_movk_i32 s0, 0x3fff
	v_cmp_lt_i32_e32 vcc, s0, v42
	v_mov_b64_e32 v[36:37], 0
	s_and_saveexec_b64 s[0:1], vcc
	v_add_u32_e32 v36, 0xffffc020, v72
	v_lshrrev_b32_e32 v36, 3, v36
	v_mad_u64_u32 v[38:39], s[8:9], v36, 15, v[132:133]
	v_mov_b64_e32 v[36:37], s[30:31]
	v_mad_u64_u32 v[36:37], s[8:9], v38, s91, v[36:37]
	v_mad_u32_u24 v37, v39, s91, v37
	s_or_b64 exec, exec, s[0:1]
	s_lshl_b32 s0, s78, 8
	s_or_b32 s0, s14, s0
	v_or_b32_e32 v46, s0, v155
	v_mov_b64_e32 v[38:39], s[22:23]
	v_mul_f32 v34, v34, v40
	v_mul_f32 v35, v35, v40
	v_mul_f32 v32, v32, v40
	v_mul_f32 v33, v33, v40
	v_mul_f32 v30, v30, v40
	v_mul_f32 v31, v31, v40
	v_mul_f32 v28, v28, v40
	v_mul_f32 v29, v29, v40
	v_mad_i64_i32 v[38:39], s[0:1], v42, s71, v[38:39]
	v_ashrrev_i32_e32 v47, 31, v46
	v_cmp_ne_u64_e32 vcc, 0, v[36:37]
	v_lshl_add_u64 v[38:39], v[46:47], 1, v[38:39]
	v_cvt_pk_bf16_f32 v42, v32, v33
	v_cvt_pk_bf16_f32 v43, v34, v35
	v_cvt_pk_bf16_f32 v44, v28, v29
	v_cvt_pk_bf16_f32 v45, v30, v31
	v_lshl_add_u64 v[36:37], v[46:47], 2, v[36:37]
	global_store_dwordx4 v[38:39], v[42:45], off
	s_and_saveexec_b64 s[0:1], vcc
	s_cbranch_execz .LBB0_1837
	global_store_dwordx4 v[36:37], v[32:35], off
	global_store_dwordx4 v[36:37], v[28:31], off offset:16
.LBB0_1837:
	s_or_b64 exec, exec, s[0:1]
	v_mov_b32_e32 v41, v40
	v_mov_b32_e32 v28, v40
	v_mov_b32_e32 v29, v40
	v_mul_f32 v26, v26, v28
	v_mul_f32 v27, v27, v29
	v_mul_f32 v24, v24, v40
	v_mul_f32 v25, v25, v41
	v_mul_f32 v22, v22, v28
	v_mul_f32 v23, v23, v29
	v_mul_f32 v20, v20, v40
	v_mul_f32 v21, v21, v41
	v_cvt_pk_bf16_f32 v28, v24, v25
	v_cvt_pk_bf16_f32 v29, v26, v27
	v_cvt_pk_bf16_f32 v30, v20, v21
	v_cvt_pk_bf16_f32 v31, v22, v23
	global_store_dwordx4 v[38:39], v[28:31], off offset:64
	s_and_saveexec_b64 s[0:1], vcc
	s_cbranch_execz .LBB0_1839
	global_store_dwordx4 v[36:37], v[24:27], off offset:128
	global_store_dwordx4 v[36:37], v[20:23], off offset:144

.LBB0_1840:
	s_nop 0
	v_fmamk_f32 v20, v167, 0x3a800000, v231
	v_cmp_gt_f32_e32 vcc, s11, v20
	v_mul_f32_e32 v21, 0x4b800000, v20
	v_or_b32_e32 v26, 48, v72
	v_cndmask_b32_e32 v20, v20, v21, vcc
	v_rsq_f32_e32 v20, v20
	s_mov_b64 s[0:1], -1
	v_mul_f32_e32 v21, 0x45800000, v20
	v_cndmask_b32_e32 v24, v20, v21, vcc
	s_and_b64 vcc, exec, s[18:19]
	s_cbranch_vccnz .LBB0_1842
	v_ashrrev_i32_e32 v27, 31, v26
	v_lshlrev_b64 v[20:21], 9, v[26:27]
	v_lshl_add_u64 v[20:21], s[24:25], 0, v[20:21]
	s_lshl_b32 s68, s14, 1
	v_mul_f32 v42, v18, v24
	v_mul_f32 v43, v19, v24
	v_mul_f32 v44, v16, v24
	v_mul_f32 v45, v17, v24
	v_lshl_add_u64 v[46:47], v[20:21], 0, s[68:69]
	v_mul_f32 v20, v42, v42
	v_mul_f32 v21, v43, v43
	v_mul_f32 v22, v44, v44
	v_mul_f32 v23, v45, v45
	v_mul_f32 v38, v14, v24
	v_mul_f32 v39, v15, v24
	v_pk_mov_b32 v[28:29], v[22:23], v[20:21] op_sel:[1,0]
	v_mov_b32_e32 v23, v21
	v_add_f32 v20, v28, v22
	v_add_f32 v21, v29, v23
	v_mul_f32 v40, v12, v24
	v_mul_f32 v41, v13, v24
	v_add_f32 v21, v20, v21
	v_add_f32 v20, v20, v20
	v_mul_f32 v22, v38, v38
	v_mul_f32 v23, v39, v39
	v_mul_f32 v28, v40, v40
	v_mul_f32 v29, v41, v41
	v_mul_f32 v34, v8, v24
	v_mul_f32 v35, v9, v24
	v_pk_mov_b32 v[30:31], v[28:29], v[22:23] op_sel:[1,0]
	v_mov_b32_e32 v29, v23
	v_mul_f32 v32, v10, v24
	v_mul_f32 v33, v11, v24
	v_mul_f32_e32 v20, v34, v34
	v_add_f32 v22, v30, v28
	v_add_f32 v23, v31, v29
	v_fma_f32 v36, v34, v34, v20
	v_fma_f32 v37, v35, v35, v20
	v_mul_f32_e32 v20, v32, v32
	v_add_f32 v23, v22, v23
	v_add_f32 v22, v22, v22
	v_fma_f32 v48, v32, v32, v20
	v_fma_f32 v49, v33, v33, v20
	v_mul_f32 v28, v6, v24
	v_mul_f32 v29, v7, v24
	v_mul_f32 v30, v4, v24
	v_mul_f32 v31, v5, v24
	v_mul_f32_e32 v20, v28, v28
	v_mul_f32_e32 v36, v30, v30
	v_mul_f32_e32 v48, v31, v31
	v_mul_f32_e32 v22, v29, v29
	v_add_f32 v36, v36, v48
	v_add_f32 v37, v37, v49
	v_add_f32 v20, v20, v22
	v_add_f32 v21, v21, v23
	v_and_b32_e32 v22, 64, v236
	v_add_f32 v20, v36, v20
	v_add_f32 v21, v37, v21
	v_add_u32_e32 v22, 64, v22
	v_add_f32_e32 v20, v20, v21
	ds_swizzle_b32 v21, v20 offset:swizzle(SWAP,16)
	v_mov_b32_e32 v141, v2
	v_lshl_add_u64 v[46:47], v[46:47], 0, v[140:141]
	s_mov_b64 s[0:1], 0
	s_waitcnt lgkmcnt(0)
	v_add_f32_e32 v20, v20, v21
	v_xor_b32_e32 v21, 32, v236
	v_cmp_lt_i32_e32 vcc, v21, v22
	s_nop 1
	v_cndmask_b32_e32 v21, v236, v21, vcc
	v_lshlrev_b32_e32 v21, 2, v21
	ds_bpermute_b32 v21, v21, v20
	s_waitcnt lgkmcnt(0)
	v_add_f32_e32 v20, v20, v21
	v_fmamk_f32 v20, v20, 0x3c800000, v231
	v_cmp_gt_f32_e32 vcc, s11, v20
	v_mul_f32_e32 v21, 0x4b800000, v20
	s_nop 0
	v_cndmask_b32_e32 v20, v20, v21, vcc
	v_rsq_f32_e32 v20, v20
	s_nop 0
	v_mul_f32_e32 v21, 0x45800000, v20
	v_cndmask_b32_e32 v20, v20, v21, vcc
	v_mul_f32_e32 v36, 0x3e38aa3b, v20
	global_load_dwordx4 v[20:23], v166, s[26:27] offset:16
	global_load_dwordx4 v[48:51], v166, s[26:27]
	v_mul_f32 v44, v44, v36
	v_mul_f32 v45, v45, v36
	v_mul_f32 v42, v42, v36
	v_mul_f32 v43, v43, v36
	v_mul_f32 v40, v40, v36
	v_mul_f32 v41, v41, v36
	v_mul_f32 v38, v38, v36
	v_mul_f32 v39, v39, v36
	v_mul_f32 v34, v34, v36
	v_mul_f32 v35, v35, v36
	v_mul_f32 v32, v32, v36
	v_mul_f32 v33, v33, v36
	v_mul_f32 v30, v30, v36
	v_mul_f32 v31, v31, v36
	v_mul_f32 v28, v28, v36
	v_mul_f32 v29, v29, v36
	s_waitcnt vmcnt(1)
	v_mul_f32 v38, v22, v38
	v_mul_f32 v39, v23, v39
	s_waitcnt vmcnt(0)
	v_mul_f32 v42, v50, v42
	v_mul_f32 v43, v51, v43
	v_mul_f32 v44, v48, v44
	v_mul_f32 v45, v49, v45
	v_mul_f32 v22, v20, v40
	v_mul_f32 v23, v21, v41
	v_cvt_pk_bf16_f32 v20, v44, v45
	v_cvt_pk_bf16_f32 v21, v42, v43
	v_cvt_pk_bf16_f32 v22, v22, v23
	v_cvt_pk_bf16_f32 v23, v38, v39
	global_store_dwordx4 v[46:47], v[20:23], off
	global_load_dwordx4 v[20:23], v166, s[26:27] offset:144
	s_nop 0
	global_load_dwordx4 v[38:41], v166, s[26:27] offset:128
	s_waitcnt vmcnt(1)
	v_mul_f32 v28, v22, v28
	v_mul_f32 v29, v23, v29
	s_waitcnt vmcnt(0)
	v_mul_f32 v32, v40, v32
	v_mul_f32 v33, v41, v33
	v_mul_f32 v34, v38, v34
	v_mul_f32 v35, v39, v35
	v_mul_f32 v22, v20, v30
	v_mul_f32 v23, v21, v31
	v_cvt_pk_bf16_f32 v20, v34, v35
	v_cvt_pk_bf16_f32 v21, v32, v33
	v_cvt_pk_bf16_f32 v22, v22, v23
	v_cvt_pk_bf16_f32 v23, v28, v29
	global_store_dwordx4 v[46:47], v[20:23], off offset:64

.LBB0_1849:
	s_or_b64 exec, exec, s[0:1]
	s_lshl_b32 s0, s78, 8
	s_or_b32 s0, s14, s0
	v_or_b32_e32 v30, s0, v155
	v_mov_b64_e32 v[22:23], s[22:23]
	v_mul_f32 v18, v18, v24
	v_mul_f32 v19, v19, v24
	v_mul_f32 v16, v16, v24
	v_mul_f32 v17, v17, v24
	v_mul_f32 v14, v14, v24
	v_mul_f32 v15, v15, v24
	v_mul_f32 v12, v12, v24
	v_mul_f32 v13, v13, v24
	v_mad_i64_i32 v[22:23], s[0:1], v26, s71, v[22:23]
	v_ashrrev_i32_e32 v31, 31, v30
	v_cmp_ne_u64_e32 vcc, 0, v[20:21]
	v_lshl_add_u64 v[22:23], v[30:31], 1, v[22:23]
	v_cvt_pk_bf16_f32 v26, v16, v17
	v_cvt_pk_bf16_f32 v27, v18, v19
	v_cvt_pk_bf16_f32 v28, v12, v13
	v_cvt_pk_bf16_f32 v29, v14, v15
	v_lshl_add_u64 v[20:21], v[30:31], 2, v[20:21]
	global_store_dwordx4 v[22:23], v[26:29], off
	s_and_saveexec_b64 s[0:1], vcc
	s_cbranch_execz .LBB0_1851
	global_store_dwordx4 v[20:21], v[16:19], off
	global_store_dwordx4 v[20:21], v[12:15], off offset:16
.LBB0_1851:
	s_or_b64 exec, exec, s[0:1]
	v_mov_b32_e32 v25, v24
	v_mov_b32_e32 v12, v24
	v_mov_b32_e32 v13, v24
	v_mul_f32 v10, v10, v12
	v_mul_f32 v11, v11, v13
	v_mul_f32 v8, v8, v24
	v_mul_f32 v9, v9, v25
	v_mul_f32 v6, v6, v12
	v_mul_f32 v7, v7, v13
	v_mul_f32 v4, v4, v24
	v_mul_f32 v5, v5, v25
	v_cvt_pk_bf16_f32 v12, v8, v9
	v_cvt_pk_bf16_f32 v13, v10, v11
	v_cvt_pk_bf16_f32 v14, v4, v5
	v_cvt_pk_bf16_f32 v15, v6, v7
	global_store_dwordx4 v[22:23], v[12:15], off offset:64
	s_and_saveexec_b64 s[0:1], vcc
	s_cbranch_execz .LBB0_1756
	global_store_dwordx4 v[20:21], v[8:11], off offset:128
	global_store_dwordx4 v[20:21], v[4:7], off offset:144
	s_branch .LBB0_1756

.LBB0_1912:
	s_add_u32 s18, s16, s56
	s_addc_u32 s19, s17, s57
	s_add_u32 s26, s16, 0x7bfdd00
	s_addc_u32 s27, s17, 0
	s_cmp_eq_u32 s51, 12
	s_cselect_b32 s18, s14, s18
	s_cselect_b32 s19, s15, s19
	s_cselect_b32 s38, s8, s26
	s_cselect_b32 s39, s9, s27
	s_add_u32 s28, s18, 0x80
	s_addc_u32 s29, s19, 0
	s_add_u32 s26, s38, 0x80
	s_addc_u32 s27, s39, 0
	s_add_i32 s54, 0, 0x10000
	v_add_u32_e32 v148, s54, v1
	ds_read_b128 v[136:139], v148
	ds_read_b128 v[140:143], v148 offset:1024
	ds_read_b128 v[144:147], v148 offset:2048
	ds_read_b128 v[148:151], v148 offset:3072
	s_add_u32 s52, s16, 0x7c3dc80
	s_addc_u32 s53, s17, 0
	ds_read_b128 v[152:155], v3
	ds_read_b128 v[156:159], v3 offset:1024
	ds_read_b128 v[160:163], v3 offset:2048
	ds_read_b128 v[164:167], v3 offset:3072
	ds_read_b128 v[168:171], v3 offset:4096
	ds_read_b128 v[172:175], v3 offset:5120
	ds_read_b128 v[176:179], v3 offset:6144
	ds_read_b128 v[180:183], v3 offset:7168
	s_add_i32 m0, s42, 0xc000
	s_nop 0
	global_load_lds_dwordx4 v132, s[52:53]
	s_add_i32 m0, s42, 0xe000
	s_nop 0
	global_load_lds_dwordx4 v134, s[52:53]
	s_waitcnt lgkmcnt(8)
	s_barrier
	s_waitcnt lgkmcnt(0)
	s_setprio 1
	s_waitcnt lgkmcnt(0)
	v_mfma_f32_16x16x32_bf16 v[128:131], v[136:139], v[152:155], v[128:131]
	v_mfma_f32_16x16x32_bf16 v[124:127], v[144:147], v[152:155], v[124:127]
	v_mfma_f32_16x16x32_bf16 v[112:115], v[136:139], v[160:163], v[112:115]
	v_mfma_f32_16x16x32_bf16 v[108:111], v[144:147], v[160:163], v[108:111]
	v_mfma_f32_16x16x32_bf16 v[96:99], v[136:139], v[168:171], v[96:99]
	v_mfma_f32_16x16x32_bf16 v[92:95], v[144:147], v[168:171], v[92:95]
	v_mfma_f32_16x16x32_bf16 v[80:83], v[136:139], v[176:179], v[80:83]
	v_mfma_f32_16x16x32_bf16 v[76:79], v[144:147], v[176:179], v[76:79]
	v_mfma_f32_16x16x32_bf16 v[128:131], v[140:143], v[156:159], v[128:131]
	v_mfma_f32_16x16x32_bf16 v[124:127], v[148:151], v[156:159], v[124:127]
	v_mfma_f32_16x16x32_bf16 v[112:115], v[140:143], v[164:167], v[112:115]
	v_mfma_f32_16x16x32_bf16 v[108:111], v[148:151], v[164:167], v[108:111]
	v_mfma_f32_16x16x32_bf16 v[96:99], v[140:143], v[172:175], v[96:99]
	v_mfma_f32_16x16x32_bf16 v[92:95], v[148:151], v[172:175], v[92:95]
	v_mfma_f32_16x16x32_bf16 v[80:83], v[140:143], v[180:183], v[80:83]
	v_mfma_f32_16x16x32_bf16 v[76:79], v[148:151], v[180:183], v[76:79]
	s_setprio 0
	s_barrier
	s_add_i32 s55, 0, 0x14000
	v_add_u32_e32 v210, s55, v1
	s_mov_b64 s[52:53], s[18:19]
	s_add_i32 s54, s54, s41
	ds_read_b128 v[184:187], v210
	ds_read_b128 v[188:191], v210 offset:1024
	ds_read_b128 v[192:195], v210 offset:2048
	ds_read_b128 v[210:213], v210 offset:3072
	s_mov_b32 m0, s54
	s_nop 0
	global_load_lds_dwordx4 v132, s[52:53]
	s_add_i32 m0, s54, 0x2000
	s_nop 0
	global_load_lds_dwordx4 v134, s[52:53]
	s_barrier
	s_waitcnt lgkmcnt(0)
	s_setprio 1
	s_waitcnt lgkmcnt(0)
	v_mfma_f32_16x16x32_bf16 v[120:123], v[184:187], v[152:155], v[120:123]
	v_mfma_f32_16x16x32_bf16 v[116:119], v[192:195], v[152:155], v[116:119]
	v_mfma_f32_16x16x32_bf16 v[104:107], v[184:187], v[160:163], v[104:107]
	v_mfma_f32_16x16x32_bf16 v[100:103], v[192:195], v[160:163], v[100:103]
	v_mfma_f32_16x16x32_bf16 v[88:91], v[184:187], v[168:171], v[88:91]
	v_mfma_f32_16x16x32_bf16 v[84:87], v[192:195], v[168:171], v[84:87]
	v_mfma_f32_16x16x32_bf16 v[72:75], v[184:187], v[176:179], v[72:75]
	v_mfma_f32_16x16x32_bf16 v[68:71], v[192:195], v[176:179], v[68:71]
	v_mfma_f32_16x16x32_bf16 v[120:123], v[188:191], v[156:159], v[120:123]
	v_mfma_f32_16x16x32_bf16 v[116:119], v[210:213], v[156:159], v[116:119]
	v_mfma_f32_16x16x32_bf16 v[104:107], v[188:191], v[164:167], v[104:107]
	v_mfma_f32_16x16x32_bf16 v[100:103], v[210:213], v[164:167], v[100:103]
	v_mfma_f32_16x16x32_bf16 v[88:91], v[188:191], v[172:175], v[88:91]
	v_mfma_f32_16x16x32_bf16 v[84:87], v[210:213], v[172:175], v[84:87]
	v_mfma_f32_16x16x32_bf16 v[72:75], v[188:191], v[180:183], v[72:75]
	v_mfma_f32_16x16x32_bf16 v[68:71], v[210:213], v[180:183], v[68:71]
	s_setprio 0
	s_mov_b64 s[52:53], s[38:39]
	s_mov_b32 m0, s42
	s_barrier
	ds_read_b128 v[152:155], v3 offset:16384
	ds_read_b128 v[156:159], v3 offset:17408
	ds_read_b128 v[160:163], v3 offset:18432
	ds_read_b128 v[164:167], v3 offset:19456
	ds_read_b128 v[168:171], v3 offset:20480
	ds_read_b128 v[172:175], v3 offset:21504
	ds_read_b128 v[176:179], v3 offset:22528
	ds_read_b128 v[180:183], v3 offset:23552
	s_nop 0
	global_load_lds_dwordx4 v132, s[52:53]
	s_mov_b32 m0, s43
	s_nop 0
	global_load_lds_dwordx4 v134, s[52:53]
	s_barrier
	s_waitcnt lgkmcnt(0)
	s_setprio 1
	s_waitcnt lgkmcnt(0)
	v_mfma_f32_16x16x32_bf16 v[64:67], v[136:139], v[152:155], v[64:67]
	v_mfma_f32_16x16x32_bf16 v[60:63], v[144:147], v[152:155], v[60:63]
	v_mfma_f32_16x16x32_bf16 v[48:51], v[136:139], v[160:163], v[48:51]
	v_mfma_f32_16x16x32_bf16 v[44:47], v[144:147], v[160:163], v[44:47]
	v_mfma_f32_16x16x32_bf16 v[32:35], v[136:139], v[168:171], v[32:35]
	v_mfma_f32_16x16x32_bf16 v[28:31], v[144:147], v[168:171], v[28:31]
	v_mfma_f32_16x16x32_bf16 v[16:19], v[136:139], v[176:179], v[16:19]
	v_mfma_f32_16x16x32_bf16 v[12:15], v[144:147], v[176:179], v[12:15]
	v_mfma_f32_16x16x32_bf16 v[64:67], v[140:143], v[156:159], v[64:67]
	v_mfma_f32_16x16x32_bf16 v[60:63], v[148:151], v[156:159], v[60:63]
	v_mfma_f32_16x16x32_bf16 v[48:51], v[140:143], v[164:167], v[48:51]
	v_mfma_f32_16x16x32_bf16 v[44:47], v[148:151], v[164:167], v[44:47]
	v_mfma_f32_16x16x32_bf16 v[32:35], v[140:143], v[172:175], v[32:35]
	v_mfma_f32_16x16x32_bf16 v[28:31], v[148:151], v[172:175], v[28:31]
	v_mfma_f32_16x16x32_bf16 v[16:19], v[140:143], v[180:183], v[16:19]
	v_mfma_f32_16x16x32_bf16 v[12:15], v[148:151], v[180:183], v[12:15]
	s_setprio 0
	s_barrier
	s_add_u32 s52, s18, 0x40000
	s_addc_u32 s53, s19, 0
	s_add_i32 s54, s55, s41
	s_mov_b32 m0, s54
	s_nop 0
	global_load_lds_dwordx4 v132, s[52:53]
	s_add_i32 m0, s54, 0x2000
	s_nop 0
	global_load_lds_dwordx4 v134, s[52:53]
	s_waitcnt vmcnt(6)
	s_barrier
	s_setprio 1
	v_mfma_f32_16x16x32_bf16 v[56:59], v[184:187], v[152:155], v[56:59]
	v_mfma_f32_16x16x32_bf16 v[52:55], v[192:195], v[152:155], v[52:55]
	v_mfma_f32_16x16x32_bf16 v[40:43], v[184:187], v[160:163], v[40:43]
	v_mfma_f32_16x16x32_bf16 v[36:39], v[192:195], v[160:163], v[36:39]
	v_mfma_f32_16x16x32_bf16 v[24:27], v[184:187], v[168:171], v[24:27]
	v_mfma_f32_16x16x32_bf16 v[20:23], v[192:195], v[168:171], v[20:23]
	v_mfma_f32_16x16x32_bf16 v[8:11], v[184:187], v[176:179], v[8:11]
	v_mfma_f32_16x16x32_bf16 v[4:7], v[192:195], v[176:179], v[4:7]
	v_mfma_f32_16x16x32_bf16 v[56:59], v[188:191], v[156:159], v[56:59]
	v_mfma_f32_16x16x32_bf16 v[52:55], v[210:213], v[156:159], v[52:55]
	v_mfma_f32_16x16x32_bf16 v[40:43], v[188:191], v[164:167], v[40:43]
	v_mfma_f32_16x16x32_bf16 v[36:39], v[210:213], v[164:167], v[36:39]
	v_mfma_f32_16x16x32_bf16 v[24:27], v[188:191], v[172:175], v[24:27]
	v_mfma_f32_16x16x32_bf16 v[20:23], v[210:213], v[172:175], v[20:23]
	v_mfma_f32_16x16x32_bf16 v[8:11], v[188:191], v[180:183], v[8:11]
	v_mfma_f32_16x16x32_bf16 v[4:7], v[210:213], v[180:183], v[4:7]
	s_setprio 0
	s_add_i32 s52, 0, 0x18000
	v_add_u32_e32 v148, s52, v1
	s_barrier
	ds_read_b128 v[136:139], v148
	ds_read_b128 v[140:143], v148 offset:1024
	ds_read_b128 v[144:147], v148 offset:2048
	ds_read_b128 v[148:151], v148 offset:3072
	s_add_u32 s38, s38, 0x40000
	s_addc_u32 s39, s39, 0
	s_mov_b32 m0, s44
	ds_read_b128 v[152:155], v3 offset:32768
	ds_read_b128 v[156:159], v3 offset:33792
	ds_read_b128 v[160:163], v3 offset:34816
	ds_read_b128 v[164:167], v3 offset:35840
	ds_read_b128 v[168:171], v3 offset:36864
	ds_read_b128 v[172:175], v3 offset:37888
	ds_read_b128 v[176:179], v3 offset:38912
	ds_read_b128 v[180:183], v3 offset:39936
	s_nop 0
	global_load_lds_dwordx4 v132, s[38:39]
	s_mov_b32 m0, s45
	s_nop 0
	global_load_lds_dwordx4 v134, s[38:39]
	s_waitcnt lgkmcnt(8)
	s_barrier
	s_waitcnt lgkmcnt(0)
	s_setprio 1
	s_waitcnt lgkmcnt(0)
	v_mfma_f32_16x16x32_bf16 v[128:131], v[136:139], v[152:155], v[128:131]
	v_mfma_f32_16x16x32_bf16 v[124:127], v[144:147], v[152:155], v[124:127]
	v_mfma_f32_16x16x32_bf16 v[112:115], v[136:139], v[160:163], v[112:115]
	v_mfma_f32_16x16x32_bf16 v[108:111], v[144:147], v[160:163], v[108:111]
	v_mfma_f32_16x16x32_bf16 v[96:99], v[136:139], v[168:171], v[96:99]
	v_mfma_f32_16x16x32_bf16 v[92:95], v[144:147], v[168:171], v[92:95]
	v_mfma_f32_16x16x32_bf16 v[80:83], v[136:139], v[176:179], v[80:83]
	v_mfma_f32_16x16x32_bf16 v[76:79], v[144:147], v[176:179], v[76:79]
	v_mfma_f32_16x16x32_bf16 v[128:131], v[140:143], v[156:159], v[128:131]
	v_mfma_f32_16x16x32_bf16 v[124:127], v[148:151], v[156:159], v[124:127]
	v_mfma_f32_16x16x32_bf16 v[112:115], v[140:143], v[164:167], v[112:115]
	v_mfma_f32_16x16x32_bf16 v[108:111], v[148:151], v[164:167], v[108:111]
	v_mfma_f32_16x16x32_bf16 v[96:99], v[140:143], v[172:175], v[96:99]
	v_mfma_f32_16x16x32_bf16 v[92:95], v[148:151], v[172:175], v[92:95]
	v_mfma_f32_16x16x32_bf16 v[80:83], v[140:143], v[180:183], v[80:83]
	v_mfma_f32_16x16x32_bf16 v[76:79], v[148:151], v[180:183], v[76:79]
	s_setprio 0
	s_barrier
	s_add_i32 s38, 0, 0x1c000
	v_add_u32_e32 v210, s38, v1
	s_add_i32 s39, s52, s41
	ds_read_b128 v[184:187], v210
	ds_read_b128 v[188:191], v210 offset:1024
	ds_read_b128 v[192:195], v210 offset:2048
	ds_read_b128 v[210:213], v210 offset:3072
	s_mov_b32 m0, s39
	s_nop 0
	global_load_lds_dwordx4 v132, s[28:29]
	s_add_i32 m0, s39, 0x2000
	s_nop 0
	global_load_lds_dwordx4 v134, s[28:29]
	s_barrier
	s_waitcnt lgkmcnt(0)
	s_setprio 1
	s_waitcnt lgkmcnt(0)
	v_mfma_f32_16x16x32_bf16 v[120:123], v[184:187], v[152:155], v[120:123]
	v_mfma_f32_16x16x32_bf16 v[116:119], v[192:195], v[152:155], v[116:119]
	v_mfma_f32_16x16x32_bf16 v[104:107], v[184:187], v[160:163], v[104:107]
	v_mfma_f32_16x16x32_bf16 v[100:103], v[192:195], v[160:163], v[100:103]
	v_mfma_f32_16x16x32_bf16 v[88:91], v[184:187], v[168:171], v[88:91]
	v_mfma_f32_16x16x32_bf16 v[84:87], v[192:195], v[168:171], v[84:87]
	v_mfma_f32_16x16x32_bf16 v[72:75], v[184:187], v[176:179], v[72:75]
	v_mfma_f32_16x16x32_bf16 v[68:71], v[192:195], v[176:179], v[68:71]
	v_mfma_f32_16x16x32_bf16 v[120:123], v[188:191], v[156:159], v[120:123]
	v_mfma_f32_16x16x32_bf16 v[116:119], v[210:213], v[156:159], v[116:119]
	v_mfma_f32_16x16x32_bf16 v[104:107], v[188:191], v[164:167], v[104:107]
	v_mfma_f32_16x16x32_bf16 v[100:103], v[210:213], v[164:167], v[100:103]
	v_mfma_f32_16x16x32_bf16 v[88:91], v[188:191], v[172:175], v[88:91]
	v_mfma_f32_16x16x32_bf16 v[84:87], v[210:213], v[172:175], v[84:87]
	v_mfma_f32_16x16x32_bf16 v[72:75], v[188:191], v[180:183], v[72:75]
	v_mfma_f32_16x16x32_bf16 v[68:71], v[210:213], v[180:183], v[68:71]
	s_setprio 0
	s_mov_b32 m0, s46
	s_barrier
	ds_read_b128 v[152:155], v3 offset:49152
	ds_read_b128 v[156:159], v3 offset:50176
	ds_read_b128 v[160:163], v3 offset:51200
	ds_read_b128 v[164:167], v3 offset:52224
	ds_read_b128 v[168:171], v3 offset:53248
	ds_read_b128 v[172:175], v3 offset:54272
	ds_read_b128 v[176:179], v3 offset:55296
	ds_read_b128 v[180:183], v3 offset:56320
	s_nop 0
	global_load_lds_dwordx4 v132, s[26:27]
	s_mov_b32 m0, s47
	s_nop 0
	global_load_lds_dwordx4 v134, s[26:27]
	s_barrier
	s_waitcnt lgkmcnt(0)
	s_setprio 1
	s_waitcnt lgkmcnt(0)
	v_mfma_f32_16x16x32_bf16 v[64:67], v[136:139], v[152:155], v[64:67]
	v_mfma_f32_16x16x32_bf16 v[60:63], v[144:147], v[152:155], v[60:63]
	v_mfma_f32_16x16x32_bf16 v[48:51], v[136:139], v[160:163], v[48:51]
	v_mfma_f32_16x16x32_bf16 v[44:47], v[144:147], v[160:163], v[44:47]
	v_mfma_f32_16x16x32_bf16 v[32:35], v[136:139], v[168:171], v[32:35]
	v_mfma_f32_16x16x32_bf16 v[28:31], v[144:147], v[168:171], v[28:31]
	v_mfma_f32_16x16x32_bf16 v[16:19], v[136:139], v[176:179], v[16:19]
	v_mfma_f32_16x16x32_bf16 v[12:15], v[144:147], v[176:179], v[12:15]
	v_mfma_f32_16x16x32_bf16 v[64:67], v[140:143], v[156:159], v[64:67]
	v_mfma_f32_16x16x32_bf16 v[60:63], v[148:151], v[156:159], v[60:63]
	v_mfma_f32_16x16x32_bf16 v[48:51], v[140:143], v[164:167], v[48:51]
	v_mfma_f32_16x16x32_bf16 v[44:47], v[148:151], v[164:167], v[44:47]
	v_mfma_f32_16x16x32_bf16 v[32:35], v[140:143], v[172:175], v[32:35]
	v_mfma_f32_16x16x32_bf16 v[28:31], v[148:151], v[172:175], v[28:31]
	v_mfma_f32_16x16x32_bf16 v[16:19], v[140:143], v[180:183], v[16:19]
	v_mfma_f32_16x16x32_bf16 v[12:15], v[148:151], v[180:183], v[12:15]
	s_setprio 0
	s_barrier
	s_add_u32 s18, s18, 0x40080
	s_addc_u32 s19, s19, 0
	s_add_i32 s26, s38, s41
	s_mov_b32 m0, s26
	s_nop 0
	global_load_lds_dwordx4 v132, s[18:19]
	s_add_i32 m0, s26, 0x2000
	s_nop 0
	global_load_lds_dwordx4 v134, s[18:19]
	s_waitcnt vmcnt(6)
	s_barrier
	s_setprio 1
	v_mfma_f32_16x16x32_bf16 v[56:59], v[184:187], v[152:155], v[56:59]
	v_mfma_f32_16x16x32_bf16 v[52:55], v[192:195], v[152:155], v[52:55]
	v_mfma_f32_16x16x32_bf16 v[40:43], v[184:187], v[160:163], v[40:43]
	v_mfma_f32_16x16x32_bf16 v[36:39], v[192:195], v[160:163], v[36:39]
	v_mfma_f32_16x16x32_bf16 v[24:27], v[184:187], v[168:171], v[24:27]
	v_mfma_f32_16x16x32_bf16 v[20:23], v[192:195], v[168:171], v[20:23]
	v_mfma_f32_16x16x32_bf16 v[8:11], v[184:187], v[176:179], v[8:11]
	v_mfma_f32_16x16x32_bf16 v[4:7], v[192:195], v[176:179], v[4:7]
	v_mfma_f32_16x16x32_bf16 v[56:59], v[188:191], v[156:159], v[56:59]
	v_mfma_f32_16x16x32_bf16 v[52:55], v[210:213], v[156:159], v[52:55]
	v_mfma_f32_16x16x32_bf16 v[40:43], v[188:191], v[164:167], v[40:43]
	v_mfma_f32_16x16x32_bf16 v[36:39], v[210:213], v[164:167], v[36:39]
	v_mfma_f32_16x16x32_bf16 v[24:27], v[188:191], v[172:175], v[24:27]
	v_mfma_f32_16x16x32_bf16 v[20:23], v[210:213], v[172:175], v[20:23]
	v_mfma_f32_16x16x32_bf16 v[8:11], v[188:191], v[180:183], v[8:11]
	v_mfma_f32_16x16x32_bf16 v[4:7], v[210:213], v[180:183], v[4:7]
	s_setprio 0
	s_add_i32 s51, s51, 2
	s_add_u32 s16, s16, 0x100
	s_addc_u32 s17, s17, 0
	s_cmp_gt_u32 s51, 13
	s_barrier
	s_cbranch_scc0 .LBB0_1912
	s_add_u32 s8, s24, s50
	s_addc_u32 s9, s25, 0
	s_add_u32 s18, s24, 0x7c7dc00
	s_addc_u32 s19, s25, 0
	s_add_u32 s28, s24, 0x94ddc00
	s_addc_u32 s29, s25, 0
	s_lshl_b64 s[6:7], s[6:7], 2
	s_add_u32 s26, s0, s6
	s_addc_u32 s27, s1, s7
	s_add_u32 s0, s30, s49
	s_addc_u32 s1, s31, s48
	v_mov_b32_e32 v141, v0
	s_add_u32 s6, s0, 0x53fc000
	s_addc_u32 s7, s1, 0
	v_readfirstlane_b32 s0, v141
	s_ashr_i32 s15, s0, 2
	v_and_b32_e32 v164, 15, v141
	s_andn2_b32 s15, s15, 63
	v_or_b32_e32 v132, s15, v164
	v_ashrrev_i32_e32 v133, 31, v132
	s_and_b32 s14, s0, 0xc0
	v_lshl_add_u64 v[132:133], v[132:133], 2, s[8:9]
	s_mov_b32 s0, 0x15000
	v_add_co_u32_e32 v132, vcc, s0, v132
	v_readlane_b32 s8, v253, 54
	s_nop 0
	v_addc_co_u32_e32 v133, vcc, 0, v133, vcc
	global_load_dword v1, v[132:133], off
	global_load_dword v168, v[132:133], off offset:64
	global_load_dword v167, v[132:133], off offset:128
	global_load_dword v166, v[132:133], off offset:192
	global_load_dword v165, v[132:133], off offset:512
	global_load_dword v163, v[132:133], off offset:576
	global_load_dword v162, v[132:133], off offset:640
	global_load_dword v151, v[132:133], off offset:704
	s_add_i32 s38, s15, 0x4000
	v_readlane_b32 s9, v253, 55
	v_or_b32_e32 v138, s38, v164
	s_mov_b64 s[0:1], -1
	s_waitcnt vmcnt(0)
	v_fmamk_f32 v1, v1, 0x3a800000, v231
	v_cmp_gt_f32_e32 vcc, s11, v1
	v_mul_f32_e32 v3, 0x4b800000, v1
	s_nop 0
	v_cndmask_b32_e32 v1, v1, v3, vcc
	v_rsq_f32_e32 v1, v1
	s_nop 0
	v_mul_f32_e32 v3, 0x45800000, v1
	v_cndmask_b32_e32 v140, v1, v3, vcc
	v_lshrrev_b32_e32 v1, 1, v141
	v_and_b32_e32 v1, 24, v1
	s_and_b64 vcc, exec, s[8:9]
	v_lshlrev_b32_e32 v3, 2, v1
	v_lshlrev_b32_e32 v136, 1, v1
	s_cbranch_vccz .LBB0_1915
	v_ashrrev_i32_e32 v139, 31, v138
	v_lshlrev_b64 v[132:133], 9, v[138:139]
	v_lshl_add_u64 v[132:133], s[28:29], 0, v[132:133]
	s_lshl_b32 s68, s14, 1
	v_mul_f32 v156, v130, v140
	v_mul_f32 v157, v131, v140
	v_mul_f32 v158, v128, v140
	v_mul_f32 v159, v129, v140
	v_lshl_add_u64 v[160:161], v[132:133], 0, s[68:69]
	v_mul_f32 v132, v156, v156
	v_mul_f32 v133, v157, v157
	v_mul_f32 v134, v158, v158
	v_mul_f32 v135, v159, v159
	v_mul_f32 v152, v126, v140
	v_mul_f32 v153, v127, v140
	v_pk_mov_b32 v[142:143], v[134:135], v[132:133] op_sel:[1,0]
	v_mov_b32_e32 v135, v133
	v_add_f32 v132, v142, v134
	v_add_f32 v133, v143, v135
	v_mul_f32 v154, v124, v140
	v_mul_f32 v155, v125, v140
	v_add_f32 v133, v132, v133
	v_add_f32 v132, v132, v132
	v_mul_f32 v134, v152, v152
	v_mul_f32 v135, v153, v153
	v_mul_f32 v142, v154, v154
	v_mul_f32 v143, v155, v155
	v_mul_f32 v148, v120, v140
	v_mul_f32 v149, v121, v140
	v_pk_mov_b32 v[144:145], v[142:143], v[134:135] op_sel:[1,0]
	v_mov_b32_e32 v143, v135
	v_mul_f32 v146, v122, v140
	v_mul_f32 v147, v123, v140
	v_mul_f32_e32 v132, v148, v148
	v_add_f32 v134, v144, v142
	v_add_f32 v135, v145, v143
	v_fma_f32 v170, v148, v148, v132
	v_fma_f32 v171, v149, v149, v132
	v_mul_f32_e32 v132, v146, v146
	v_add_f32 v135, v134, v135
	v_add_f32 v134, v134, v134
	v_fma_f32 v172, v146, v146, v132
	v_fma_f32 v173, v147, v147, v132
	v_mul_f32 v142, v118, v140
	v_mul_f32 v143, v119, v140
	v_mul_f32 v144, v116, v140
	v_mul_f32 v145, v117, v140
	v_mul_f32_e32 v132, v142, v142
	v_mul_f32_e32 v170, v144, v144
	v_mul_f32_e32 v172, v145, v145
	v_mul_f32_e32 v134, v143, v143
	v_add_f32 v170, v170, v172
	v_add_f32 v171, v171, v173
	v_add_f32 v132, v132, v134
	v_add_f32 v133, v133, v135
	v_and_b32_e32 v134, 64, v236
	v_add_f32 v132, v170, v132
	v_add_f32 v133, v171, v133
	v_add_u32_e32 v134, 64, v134
	v_add_f32_e32 v132, v132, v133
	ds_swizzle_b32 v133, v132 offset:swizzle(SWAP,16)
	v_mov_b32_e32 v137, v2
	v_lshl_add_u64 v[160:161], v[160:161], 0, v[136:137]
	s_mov_b64 s[0:1], 0
	s_waitcnt lgkmcnt(0)
	v_add_f32_e32 v132, v132, v133
	v_xor_b32_e32 v133, 32, v236
	v_cmp_lt_i32_e32 vcc, v133, v134
	s_nop 1
	v_cndmask_b32_e32 v133, v236, v133, vcc
	v_lshlrev_b32_e32 v133, 2, v133
	ds_bpermute_b32 v133, v133, v132
	s_waitcnt lgkmcnt(0)
	v_add_f32_e32 v132, v132, v133
	v_fmamk_f32 v132, v132, 0x3c800000, v231
	v_cmp_gt_f32_e32 vcc, s11, v132
	v_mul_f32_e32 v133, 0x4b800000, v132
	s_nop 0
	v_cndmask_b32_e32 v132, v132, v133, vcc
	v_rsq_f32_e32 v132, v132
	s_nop 0
	v_mul_f32_e32 v133, 0x45800000, v132
	v_cndmask_b32_e32 v132, v132, v133, vcc
	v_mul_f32_e32 v150, 0x3e38aa3b, v132
	global_load_dwordx4 v[132:135], v3, s[26:27] offset:16
	global_load_dwordx4 v[170:173], v3, s[26:27]
	v_mul_f32 v158, v158, v150
	v_mul_f32 v159, v159, v150
	v_mul_f32 v156, v156, v150
	v_mul_f32 v157, v157, v150
	v_mul_f32 v154, v154, v150
	v_mul_f32 v155, v155, v150
	v_mul_f32 v152, v152, v150
	v_mul_f32 v153, v153, v150
	v_mul_f32 v148, v148, v150
	v_mul_f32 v149, v149, v150
	v_mul_f32 v146, v146, v150
	v_mul_f32 v147, v147, v150
	v_mul_f32 v144, v144, v150
	v_mul_f32 v145, v145, v150
	v_mul_f32 v142, v142, v150
	v_mul_f32 v143, v143, v150
	s_waitcnt vmcnt(1)
	v_mul_f32 v152, v134, v152
	v_mul_f32 v153, v135, v153
	s_waitcnt vmcnt(0)
	v_mul_f32 v156, v172, v156
	v_mul_f32 v157, v173, v157
	v_mul_f32 v158, v170, v158
	v_mul_f32 v159, v171, v159
	v_mul_f32 v134, v132, v154
	v_mul_f32 v135, v133, v155
	v_cvt_pk_bf16_f32 v132, v158, v159
	v_cvt_pk_bf16_f32 v133, v156, v157
	v_cvt_pk_bf16_f32 v134, v134, v135
	v_cvt_pk_bf16_f32 v135, v152, v153
	global_store_dwordx4 v[160:161], v[132:135], off
	global_load_dwordx4 v[132:135], v3, s[26:27] offset:144
	s_nop 0
	global_load_dwordx4 v[152:155], v3, s[26:27] offset:128
	s_waitcnt vmcnt(1)
	v_mul_f32 v142, v134, v142
	v_mul_f32 v143, v135, v143
	s_waitcnt vmcnt(0)
	v_mul_f32 v146, v154, v146
	v_mul_f32 v147, v155, v147
	v_mul_f32 v148, v152, v148
	v_mul_f32 v149, v153, v149
	v_mul_f32 v134, v132, v144
	v_mul_f32 v135, v133, v145
	v_cvt_pk_bf16_f32 v132, v148, v149
	v_cvt_pk_bf16_f32 v133, v146, v147
	v_cvt_pk_bf16_f32 v134, v134, v135
	v_cvt_pk_bf16_f32 v135, v142, v143
	global_store_dwordx4 v[160:161], v[132:135], off offset:64
.LBB0_1915:
	s_nop 1
	v_and_b32_e32 v132, 7, v141
	v_add_u32_e32 v132, 7, v132
	s_andn2_b64 vcc, exec, s[0:1]
	v_mov_b32_e32 v133, v2
	s_cbranch_vccnz .LBB0_1923
	s_movk_i32 s0, 0x3fff
	v_cmp_lt_i32_e32 vcc, s0, v138
	v_mov_b64_e32 v[134:135], 0
	s_and_saveexec_b64 s[0:1], vcc
	v_add_u32_e32 v134, 0xffffc000, v138
	v_lshrrev_b32_e32 v134, 3, v134
	v_mad_u64_u32 v[142:143], s[8:9], v134, 15, v[132:133]
	v_mov_b64_e32 v[134:135], s[6:7]
	v_mad_u64_u32 v[134:135], s[8:9], v142, s91, v[134:135]
	v_mad_u32_u24 v135, v143, s91, v135
	s_or_b64 exec, exec, s[0:1]
	v_readlane_b32 s0, v253, 56
	s_or_b32 s0, s14, s0
	v_mov_b64_e32 v[142:143], s[18:19]
	v_or_b32_e32 v148, s0, v1
	v_mul_f32 v130, v130, v140
	v_mul_f32 v131, v131, v140
	v_mul_f32 v128, v128, v140
	v_mul_f32 v129, v129, v140
	v_mul_f32 v126, v126, v140
	v_mul_f32 v127, v127, v140
	v_mul_f32 v124, v124, v140
	v_mul_f32 v125, v125, v140
	v_mad_i64_i32 v[142:143], s[0:1], v138, s71, v[142:143]
	v_ashrrev_i32_e32 v149, 31, v148
	v_cmp_ne_u64_e32 vcc, 0, v[134:135]
	v_lshl_add_u64 v[142:143], v[148:149], 1, v[142:143]
	v_cvt_pk_bf16_f32 v144, v128, v129
	v_cvt_pk_bf16_f32 v145, v130, v131
	v_cvt_pk_bf16_f32 v146, v124, v125
	v_cvt_pk_bf16_f32 v147, v126, v127
	v_lshl_add_u64 v[134:135], v[148:149], 2, v[134:135]
	global_store_dwordx4 v[142:143], v[144:147], off
	s_and_saveexec_b64 s[0:1], vcc
	s_cbranch_execz .LBB0_1920
	global_store_dwordx4 v[134:135], v[128:131], off
	global_store_dwordx4 v[134:135], v[124:127], off offset:16
.LBB0_1920:
	s_or_b64 exec, exec, s[0:1]
	v_mov_b32_e32 v141, v140
	v_mov_b32_e32 v124, v140
	v_mov_b32_e32 v125, v140
	v_mul_f32 v122, v122, v124
	v_mul_f32 v123, v123, v125
	v_mul_f32 v120, v120, v140
	v_mul_f32 v121, v121, v141
	v_mul_f32 v118, v118, v124
	v_mul_f32 v119, v119, v125
	v_mul_f32 v116, v116, v140
	v_mul_f32 v117, v117, v141
	v_cvt_pk_bf16_f32 v124, v120, v121
	v_cvt_pk_bf16_f32 v125, v122, v123
	v_cvt_pk_bf16_f32 v126, v116, v117
	v_cvt_pk_bf16_f32 v127, v118, v119
	global_store_dwordx4 v[142:143], v[124:127], off offset:64
	s_and_saveexec_b64 s[0:1], vcc
	s_cbranch_execz .LBB0_1922
	global_store_dwordx4 v[134:135], v[120:123], off offset:128
	global_store_dwordx4 v[134:135], v[116:119], off offset:144

.LBB0_1923:
	s_nop 0
	v_fmamk_f32 v116, v168, 0x3a800000, v231
	v_cmp_gt_f32_e32 vcc, s11, v116
	v_mul_f32_e32 v117, 0x4b800000, v116
	v_readlane_b32 s8, v253, 54
	v_cndmask_b32_e32 v116, v116, v117, vcc
	v_rsq_f32_e32 v116, v116
	v_readlane_b32 s9, v253, 55
	v_or_b32_e32 v122, 16, v138
	s_mov_b64 s[0:1], -1
	v_mul_f32_e32 v117, 0x45800000, v116
	v_cndmask_b32_e32 v120, v116, v117, vcc
	v_cndmask_b32_e64 v116, 0, 1, s[8:9]
	v_cmp_ne_u32_e64 s[16:17], 1, v116
	s_andn2_b64 vcc, exec, s[8:9]
	s_cbranch_vccnz .LBB0_1925
	v_ashrrev_i32_e32 v123, 31, v122
	v_lshlrev_b64 v[116:117], 9, v[122:123]
	v_lshl_add_u64 v[116:117], s[28:29], 0, v[116:117]
	s_lshl_b32 s68, s14, 1
	v_mul_f32 v144, v114, v120
	v_mul_f32 v145, v115, v120
	v_mul_f32 v146, v112, v120
	v_mul_f32 v147, v113, v120
	v_lshl_add_u64 v[148:149], v[116:117], 0, s[68:69]
	v_mul_f32 v116, v144, v144
	v_mul_f32 v117, v145, v145
	v_mul_f32 v118, v146, v146
	v_mul_f32 v119, v147, v147
	v_mul_f32 v140, v110, v120
	v_mul_f32 v141, v111, v120
	v_pk_mov_b32 v[124:125], v[118:119], v[116:117] op_sel:[1,0]
	v_mov_b32_e32 v119, v117
	v_add_f32 v116, v124, v118
	v_add_f32 v117, v125, v119
	v_mul_f32 v142, v108, v120
	v_mul_f32 v143, v109, v120
	v_add_f32 v117, v116, v117
	v_add_f32 v116, v116, v116
	v_mul_f32 v118, v140, v140
	v_mul_f32 v119, v141, v141
	v_mul_f32 v124, v142, v142
	v_mul_f32 v125, v143, v143
	v_mul_f32 v130, v104, v120
	v_mul_f32 v131, v105, v120
	v_pk_mov_b32 v[126:127], v[124:125], v[118:119] op_sel:[1,0]
	v_mov_b32_e32 v125, v119
	v_mul_f32 v128, v106, v120
	v_mul_f32 v129, v107, v120
	v_mul_f32_e32 v116, v130, v130
	v_add_f32 v118, v126, v124
	v_add_f32 v119, v127, v125
	v_fma_f32 v134, v130, v130, v116
	v_fma_f32 v135, v131, v131, v116
	v_mul_f32_e32 v116, v128, v128
	v_add_f32 v119, v118, v119
	v_add_f32 v118, v118, v118
	v_fma_f32 v152, v128, v128, v116
	v_fma_f32 v153, v129, v129, v116
	v_mul_f32 v124, v102, v120
	v_mul_f32 v125, v103, v120
	v_mul_f32 v126, v100, v120
	v_mul_f32 v127, v101, v120
	v_mul_f32_e32 v116, v124, v124
	v_mul_f32_e32 v134, v126, v126
	v_mul_f32_e32 v152, v127, v127
	v_mul_f32_e32 v118, v125, v125
	v_add_f32 v134, v134, v152
	v_add_f32 v135, v135, v153
	v_add_f32 v116, v116, v118
	v_add_f32 v117, v117, v119
	v_and_b32_e32 v118, 64, v236
	v_add_f32 v116, v134, v116
	v_add_f32 v117, v135, v117
	v_add_u32_e32 v118, 64, v118
	v_add_f32_e32 v116, v116, v117
	ds_swizzle_b32 v117, v116 offset:swizzle(SWAP,16)
	v_mov_b32_e32 v137, v2
	v_lshl_add_u64 v[148:149], v[148:149], 0, v[136:137]
	s_mov_b64 s[0:1], 0
	s_waitcnt lgkmcnt(0)
	v_add_f32_e32 v116, v116, v117
	v_xor_b32_e32 v117, 32, v236
	v_cmp_lt_i32_e32 vcc, v117, v118
	s_nop 1
	v_cndmask_b32_e32 v117, v236, v117, vcc
	v_lshlrev_b32_e32 v117, 2, v117
	ds_bpermute_b32 v117, v117, v116
	s_waitcnt lgkmcnt(0)
	v_add_f32_e32 v116, v116, v117
	v_fmamk_f32 v116, v116, 0x3c800000, v231
	v_cmp_gt_f32_e32 vcc, s11, v116
	v_mul_f32_e32 v117, 0x4b800000, v116
	s_nop 0
	v_cndmask_b32_e32 v116, v116, v117, vcc
	v_rsq_f32_e32 v116, v116
	s_nop 0
	v_mul_f32_e32 v117, 0x45800000, v116
	v_cndmask_b32_e32 v116, v116, v117, vcc
	v_mul_f32_e32 v134, 0x3e38aa3b, v116
	global_load_dwordx4 v[116:119], v3, s[26:27] offset:16
	global_load_dwordx4 v[152:155], v3, s[26:27]
	v_mul_f32 v146, v146, v134
	v_mul_f32 v147, v147, v134
	v_mul_f32 v144, v144, v134
	v_mul_f32 v145, v145, v134
	v_mul_f32 v142, v142, v134
	v_mul_f32 v143, v143, v134
	v_mul_f32 v140, v140, v134
	v_mul_f32 v141, v141, v134
	v_mul_f32 v130, v130, v134
	v_mul_f32 v131, v131, v134
	v_mul_f32 v128, v128, v134
	v_mul_f32 v129, v129, v134
	v_mul_f32 v126, v126, v134
	v_mul_f32 v127, v127, v134
	v_mul_f32 v124, v124, v134
	v_mul_f32 v125, v125, v134
	s_waitcnt vmcnt(1)
	v_mul_f32 v140, v118, v140
	v_mul_f32 v141, v119, v141
	s_waitcnt vmcnt(0)
	v_mul_f32 v144, v154, v144
	v_mul_f32 v145, v155, v145
	v_mul_f32 v146, v152, v146
	v_mul_f32 v147, v153, v147
	v_mul_f32 v118, v116, v142
	v_mul_f32 v119, v117, v143
	v_cvt_pk_bf16_f32 v116, v146, v147
	v_cvt_pk_bf16_f32 v117, v144, v145
	v_cvt_pk_bf16_f32 v118, v118, v119
	v_cvt_pk_bf16_f32 v119, v140, v141
	global_store_dwordx4 v[148:149], v[116:119], off
	global_load_dwordx4 v[116:119], v3, s[26:27] offset:144
	s_nop 0
	global_load_dwordx4 v[140:143], v3, s[26:27] offset:128
	s_waitcnt vmcnt(1)
	v_mul_f32 v124, v118, v124
	v_mul_f32 v125, v119, v125
	s_waitcnt vmcnt(0)
	v_mul_f32 v128, v142, v128
	v_mul_f32 v129, v143, v129
	v_mul_f32 v130, v140, v130
	v_mul_f32 v131, v141, v131
	v_mul_f32 v118, v116, v126
	v_mul_f32 v119, v117, v127
	v_cvt_pk_bf16_f32 v116, v130, v131
	v_cvt_pk_bf16_f32 v117, v128, v129
	v_cvt_pk_bf16_f32 v118, v118, v119
	v_cvt_pk_bf16_f32 v119, v124, v125
	global_store_dwordx4 v[148:149], v[116:119], off offset:64
.LBB0_1925:
	s_andn2_b64 vcc, exec, s[0:1]
	s_cbranch_vccnz .LBB0_1933
	s_movk_i32 s0, 0x3fff
	v_cmp_lt_i32_e32 vcc, s0, v122
	v_mov_b64_e32 v[116:117], 0
	s_and_saveexec_b64 s[0:1], vcc
	v_add_u32_e32 v116, 0xffffc010, v138
	v_lshrrev_b32_e32 v116, 3, v116
	v_mad_u64_u32 v[118:119], s[8:9], v116, 15, v[132:133]
	v_mov_b64_e32 v[116:117], s[6:7]
	v_mad_u64_u32 v[116:117], s[8:9], v118, s91, v[116:117]
	v_mad_u32_u24 v117, v119, s91, v117
	s_or_b64 exec, exec, s[0:1]
	v_readlane_b32 s0, v253, 56
	s_or_b32 s0, s14, s0
	v_mov_b64_e32 v[118:119], s[18:19]
	v_or_b32_e32 v126, s0, v1
	v_mul_f32 v114, v114, v120
	v_mul_f32 v115, v115, v120
	v_mul_f32 v112, v112, v120
	v_mul_f32 v113, v113, v120
	v_mul_f32 v110, v110, v120
	v_mul_f32 v111, v111, v120
	v_mul_f32 v108, v108, v120
	v_mul_f32 v109, v109, v120
	v_mad_i64_i32 v[118:119], s[0:1], v122, s71, v[118:119]
	v_ashrrev_i32_e32 v127, 31, v126
	v_cmp_ne_u64_e32 vcc, 0, v[116:117]
	v_lshl_add_u64 v[118:119], v[126:127], 1, v[118:119]
	v_cvt_pk_bf16_f32 v122, v112, v113
	v_cvt_pk_bf16_f32 v123, v114, v115
	v_cvt_pk_bf16_f32 v124, v108, v109
	v_cvt_pk_bf16_f32 v125, v110, v111
	v_lshl_add_u64 v[116:117], v[126:127], 2, v[116:117]
	global_store_dwordx4 v[118:119], v[122:125], off
	s_and_saveexec_b64 s[0:1], vcc
	s_cbranch_execz .LBB0_1930
	global_store_dwordx4 v[116:117], v[112:115], off
	global_store_dwordx4 v[116:117], v[108:111], off offset:16

.LBB0_1933:
	s_nop 0
	v_fmamk_f32 v100, v167, 0x3a800000, v231
	v_cmp_gt_f32_e32 vcc, s11, v100
	v_mul_f32_e32 v101, 0x4b800000, v100
	v_or_b32_e32 v106, 32, v138
	v_cndmask_b32_e32 v100, v100, v101, vcc
	v_rsq_f32_e32 v100, v100
	s_mov_b64 s[0:1], -1
	v_mul_f32_e32 v101, 0x45800000, v100
	v_cndmask_b32_e32 v104, v100, v101, vcc
	s_and_b64 vcc, exec, s[16:17]
	s_cbranch_vccnz .LBB0_1935
	v_ashrrev_i32_e32 v107, 31, v106
	v_lshlrev_b64 v[100:101], 9, v[106:107]
	v_lshl_add_u64 v[100:101], s[28:29], 0, v[100:101]
	s_lshl_b32 s68, s14, 1
	v_mul_f32 v122, v98, v104
	v_mul_f32 v123, v99, v104
	v_mul_f32 v124, v96, v104
	v_mul_f32 v125, v97, v104
	v_lshl_add_u64 v[126:127], v[100:101], 0, s[68:69]
	v_mul_f32 v100, v122, v122
	v_mul_f32 v101, v123, v123
	v_mul_f32 v102, v124, v124
	v_mul_f32 v103, v125, v125
	v_mul_f32 v118, v94, v104
	v_mul_f32 v119, v95, v104
	v_pk_mov_b32 v[108:109], v[102:103], v[100:101] op_sel:[1,0]
	v_mov_b32_e32 v103, v101
	v_add_f32 v100, v108, v102
	v_add_f32 v101, v109, v103
	v_mul_f32 v120, v92, v104
	v_mul_f32 v121, v93, v104
	v_add_f32 v101, v100, v101
	v_add_f32 v100, v100, v100
	v_mul_f32 v102, v118, v118
	v_mul_f32 v103, v119, v119
	v_mul_f32 v108, v120, v120
	v_mul_f32 v109, v121, v121
	v_mul_f32 v114, v88, v104
	v_mul_f32 v115, v89, v104
	v_pk_mov_b32 v[110:111], v[108:109], v[102:103] op_sel:[1,0]
	v_mov_b32_e32 v109, v103
	v_mul_f32 v112, v90, v104
	v_mul_f32 v113, v91, v104
	v_mul_f32_e32 v100, v114, v114
	v_add_f32 v102, v110, v108
	v_add_f32 v103, v111, v109
	v_fma_f32 v116, v114, v114, v100
	v_fma_f32 v117, v115, v115, v100
	v_mul_f32_e32 v100, v112, v112
	v_add_f32 v103, v102, v103
	v_add_f32 v102, v102, v102
	v_fma_f32 v128, v112, v112, v100
	v_fma_f32 v129, v113, v113, v100
	v_mul_f32 v108, v86, v104
	v_mul_f32 v109, v87, v104
	v_mul_f32 v110, v84, v104
	v_mul_f32 v111, v85, v104
	v_mul_f32_e32 v100, v108, v108
	v_mul_f32_e32 v116, v110, v110
	v_mul_f32_e32 v128, v111, v111
	v_mul_f32_e32 v102, v109, v109
	v_add_f32 v116, v116, v128
	v_add_f32 v117, v117, v129
	v_add_f32 v100, v100, v102
	v_add_f32 v101, v101, v103
	v_and_b32_e32 v102, 64, v236
	v_add_f32 v100, v116, v100
	v_add_f32 v101, v117, v101
	v_add_u32_e32 v102, 64, v102
	v_add_f32_e32 v100, v100, v101
	ds_swizzle_b32 v101, v100 offset:swizzle(SWAP,16)
	v_mov_b32_e32 v137, v2
	v_lshl_add_u64 v[126:127], v[126:127], 0, v[136:137]
	s_mov_b64 s[0:1], 0
	s_waitcnt lgkmcnt(0)
	v_add_f32_e32 v100, v100, v101
	v_xor_b32_e32 v101, 32, v236
	v_cmp_lt_i32_e32 vcc, v101, v102
	s_nop 1
	v_cndmask_b32_e32 v101, v236, v101, vcc
	v_lshlrev_b32_e32 v101, 2, v101
	ds_bpermute_b32 v101, v101, v100
	s_waitcnt lgkmcnt(0)
	v_add_f32_e32 v100, v100, v101
	v_fmamk_f32 v100, v100, 0x3c800000, v231
	v_cmp_gt_f32_e32 vcc, s11, v100
	v_mul_f32_e32 v101, 0x4b800000, v100
	s_nop 0
	v_cndmask_b32_e32 v100, v100, v101, vcc
	v_rsq_f32_e32 v100, v100
	s_nop 0
	v_mul_f32_e32 v101, 0x45800000, v100
	v_cndmask_b32_e32 v100, v100, v101, vcc
	v_mul_f32_e32 v116, 0x3e38aa3b, v100
	global_load_dwordx4 v[100:103], v3, s[26:27] offset:16
	global_load_dwordx4 v[128:131], v3, s[26:27]
	v_mul_f32 v124, v124, v116
	v_mul_f32 v125, v125, v116
	v_mul_f32 v122, v122, v116
	v_mul_f32 v123, v123, v116
	v_mul_f32 v120, v120, v116
	v_mul_f32 v121, v121, v116
	v_mul_f32 v118, v118, v116
	v_mul_f32 v119, v119, v116
	v_mul_f32 v114, v114, v116
	v_mul_f32 v115, v115, v116
	v_mul_f32 v112, v112, v116
	v_mul_f32 v113, v113, v116
	v_mul_f32 v110, v110, v116
	v_mul_f32 v111, v111, v116
	v_mul_f32 v108, v108, v116
	v_mul_f32 v109, v109, v116
	s_waitcnt vmcnt(1)
	v_mul_f32 v118, v102, v118
	v_mul_f32 v119, v103, v119
	s_waitcnt vmcnt(0)
	v_mul_f32 v122, v130, v122
	v_mul_f32 v123, v131, v123
	v_mul_f32 v124, v128, v124
	v_mul_f32 v125, v129, v125
	v_mul_f32 v102, v100, v120
	v_mul_f32 v103, v101, v121
	v_cvt_pk_bf16_f32 v100, v124, v125
	v_cvt_pk_bf16_f32 v101, v122, v123
	v_cvt_pk_bf16_f32 v102, v102, v103
	v_cvt_pk_bf16_f32 v103, v118, v119
	global_store_dwordx4 v[126:127], v[100:103], off
	global_load_dwordx4 v[100:103], v3, s[26:27] offset:144
	s_nop 0
	global_load_dwordx4 v[118:121], v3, s[26:27] offset:128
	s_waitcnt vmcnt(1)
	v_mul_f32 v108, v102, v108
	v_mul_f32 v109, v103, v109
	s_waitcnt vmcnt(0)
	v_mul_f32 v112, v120, v112
	v_mul_f32 v113, v121, v113
	v_mul_f32 v114, v118, v114
	v_mul_f32 v115, v119, v115
	v_mul_f32 v102, v100, v110
	v_mul_f32 v103, v101, v111
	v_cvt_pk_bf16_f32 v100, v114, v115
	v_cvt_pk_bf16_f32 v101, v112, v113
	v_cvt_pk_bf16_f32 v102, v102, v103
	v_cvt_pk_bf16_f32 v103, v108, v109
	global_store_dwordx4 v[126:127], v[100:103], off offset:64
.LBB0_1935:
	s_andn2_b64 vcc, exec, s[0:1]
	s_cbranch_vccnz .LBB0_1943
	s_movk_i32 s0, 0x3fff
	v_cmp_lt_i32_e32 vcc, s0, v106
	v_mov_b64_e32 v[100:101], 0
	s_and_saveexec_b64 s[0:1], vcc
	v_add_u32_e32 v100, 0xffffc020, v138
	v_lshrrev_b32_e32 v100, 3, v100
	v_mad_u64_u32 v[102:103], s[8:9], v100, 15, v[132:133]
	v_mov_b64_e32 v[100:101], s[6:7]
	v_mad_u64_u32 v[100:101], s[8:9], v102, s91, v[100:101]
	v_mad_u32_u24 v101, v103, s91, v101
	s_or_b64 exec, exec, s[0:1]
	v_readlane_b32 s0, v253, 56
	s_or_b32 s0, s14, s0
	v_mov_b64_e32 v[102:103], s[18:19]
	v_or_b32_e32 v110, s0, v1
	v_mul_f32 v98, v98, v104
	v_mul_f32 v99, v99, v104
	v_mul_f32 v96, v96, v104
	v_mul_f32 v97, v97, v104
	v_mul_f32 v94, v94, v104
	v_mul_f32 v95, v95, v104
	v_mul_f32 v92, v92, v104
	v_mul_f32 v93, v93, v104
	v_mad_i64_i32 v[102:103], s[0:1], v106, s71, v[102:103]
	v_ashrrev_i32_e32 v111, 31, v110
	v_cmp_ne_u64_e32 vcc, 0, v[100:101]
	v_lshl_add_u64 v[102:103], v[110:111], 1, v[102:103]
	v_cvt_pk_bf16_f32 v106, v96, v97
	v_cvt_pk_bf16_f32 v107, v98, v99
	v_cvt_pk_bf16_f32 v108, v92, v93
	v_cvt_pk_bf16_f32 v109, v94, v95
	v_lshl_add_u64 v[100:101], v[110:111], 2, v[100:101]
	global_store_dwordx4 v[102:103], v[106:109], off
	s_and_saveexec_b64 s[0:1], vcc
	s_cbranch_execz .LBB0_1940
	global_store_dwordx4 v[100:101], v[96:99], off
	global_store_dwordx4 v[100:101], v[92:95], off offset:16

.LBB0_1943:
	s_nop 0
	v_fmamk_f32 v84, v166, 0x3a800000, v231
	v_cmp_gt_f32_e32 vcc, s11, v84
	v_mul_f32_e32 v85, 0x4b800000, v84
	s_add_u32 s0, s30, s36
	v_cndmask_b32_e32 v84, v84, v85, vcc
	v_rsq_f32_e32 v84, v84
	s_addc_u32 s1, s31, s37
	s_add_u32 s30, s0, 0x5348000
	s_addc_u32 s31, s1, 0
	v_mul_f32_e32 v85, 0x45800000, v84
	v_cndmask_b32_e32 v88, v84, v85, vcc
	v_or_b32_e32 v90, 48, v138
	s_mov_b64 s[0:1], -1
	s_and_b64 vcc, exec, s[16:17]
	s_cbranch_vccnz .LBB0_1945
	v_ashrrev_i32_e32 v91, 31, v90
	v_lshlrev_b64 v[84:85], 9, v[90:91]
	v_lshl_add_u64 v[84:85], s[28:29], 0, v[84:85]
	s_lshl_b32 s68, s14, 1
	v_mul_f32 v106, v82, v88
	v_mul_f32 v107, v83, v88
	v_mul_f32 v108, v80, v88
	v_mul_f32 v109, v81, v88
	v_lshl_add_u64 v[110:111], v[84:85], 0, s[68:69]
	v_mul_f32 v84, v106, v106
	v_mul_f32 v85, v107, v107
	v_mul_f32 v86, v108, v108
	v_mul_f32 v87, v109, v109
	v_mul_f32 v102, v78, v88
	v_mul_f32 v103, v79, v88
	v_pk_mov_b32 v[92:93], v[86:87], v[84:85] op_sel:[1,0]
	v_mov_b32_e32 v87, v85
	v_add_f32 v84, v92, v86
	v_add_f32 v85, v93, v87
	v_mul_f32 v104, v76, v88
	v_mul_f32 v105, v77, v88
	v_add_f32 v85, v84, v85
	v_add_f32 v84, v84, v84
	v_mul_f32 v86, v102, v102
	v_mul_f32 v87, v103, v103
	v_mul_f32 v92, v104, v104
	v_mul_f32 v93, v105, v105
	v_mul_f32 v98, v72, v88
	v_mul_f32 v99, v73, v88
	v_pk_mov_b32 v[94:95], v[92:93], v[86:87] op_sel:[1,0]
	v_mov_b32_e32 v93, v87
	v_mul_f32 v96, v74, v88
	v_mul_f32 v97, v75, v88
	v_mul_f32_e32 v84, v98, v98
	v_add_f32 v86, v94, v92
	v_add_f32 v87, v95, v93
	v_fma_f32 v100, v98, v98, v84
	v_fma_f32 v101, v99, v99, v84
	v_mul_f32_e32 v84, v96, v96
	v_add_f32 v87, v86, v87
	v_add_f32 v86, v86, v86
	v_fma_f32 v112, v96, v96, v84
	v_fma_f32 v113, v97, v97, v84
	v_mul_f32 v92, v70, v88
	v_mul_f32 v93, v71, v88
	v_mul_f32 v94, v68, v88
	v_mul_f32 v95, v69, v88
	v_mul_f32_e32 v84, v92, v92
	v_mul_f32_e32 v100, v94, v94
	v_mul_f32_e32 v112, v95, v95
	v_mul_f32_e32 v86, v93, v93
	v_add_f32 v100, v100, v112
	v_add_f32 v101, v101, v113
	v_add_f32 v84, v84, v86
	v_add_f32 v85, v85, v87
	v_and_b32_e32 v86, 64, v236
	v_add_f32 v84, v100, v84
	v_add_f32 v85, v101, v85
	v_add_u32_e32 v86, 64, v86
	v_add_f32_e32 v84, v84, v85
	ds_swizzle_b32 v85, v84 offset:swizzle(SWAP,16)
	v_mov_b32_e32 v137, v2
	v_lshl_add_u64 v[110:111], v[110:111], 0, v[136:137]
	s_mov_b64 s[0:1], 0
	s_waitcnt lgkmcnt(0)
	v_add_f32_e32 v84, v84, v85
	v_xor_b32_e32 v85, 32, v236
	v_cmp_lt_i32_e32 vcc, v85, v86
	s_nop 1
	v_cndmask_b32_e32 v85, v236, v85, vcc
	v_lshlrev_b32_e32 v85, 2, v85
	ds_bpermute_b32 v85, v85, v84
	s_waitcnt lgkmcnt(0)
	v_add_f32_e32 v84, v84, v85
	v_fmamk_f32 v84, v84, 0x3c800000, v231
	v_cmp_gt_f32_e32 vcc, s11, v84
	v_mul_f32_e32 v85, 0x4b800000, v84
	s_nop 0
	v_cndmask_b32_e32 v84, v84, v85, vcc
	v_rsq_f32_e32 v84, v84
	s_nop 0
	v_mul_f32_e32 v85, 0x45800000, v84
	v_cndmask_b32_e32 v84, v84, v85, vcc
	v_mul_f32_e32 v100, 0x3e38aa3b, v84
	global_load_dwordx4 v[84:87], v3, s[26:27] offset:16
	global_load_dwordx4 v[112:115], v3, s[26:27]
	v_mul_f32 v108, v108, v100
	v_mul_f32 v109, v109, v100
	v_mul_f32 v106, v106, v100
	v_mul_f32 v107, v107, v100
	v_mul_f32 v104, v104, v100
	v_mul_f32 v105, v105, v100
	v_mul_f32 v102, v102, v100
	v_mul_f32 v103, v103, v100
	v_mul_f32 v98, v98, v100
	v_mul_f32 v99, v99, v100
	v_mul_f32 v96, v96, v100
	v_mul_f32 v97, v97, v100
	v_mul_f32 v94, v94, v100
	v_mul_f32 v95, v95, v100
	v_mul_f32 v92, v92, v100
	v_mul_f32 v93, v93, v100
	s_waitcnt vmcnt(1)
	v_mul_f32 v102, v86, v102
	v_mul_f32 v103, v87, v103
	s_waitcnt vmcnt(0)
	v_mul_f32 v106, v114, v106
	v_mul_f32 v107, v115, v107
	v_mul_f32 v108, v112, v108
	v_mul_f32 v109, v113, v109
	v_mul_f32 v86, v84, v104
	v_mul_f32 v87, v85, v105
	v_cvt_pk_bf16_f32 v84, v108, v109
	v_cvt_pk_bf16_f32 v85, v106, v107
	v_cvt_pk_bf16_f32 v86, v86, v87
	v_cvt_pk_bf16_f32 v87, v102, v103
	global_store_dwordx4 v[110:111], v[84:87], off
	global_load_dwordx4 v[84:87], v3, s[26:27] offset:144
	s_nop 0
	global_load_dwordx4 v[102:105], v3, s[26:27] offset:128
	s_waitcnt vmcnt(1)
	v_mul_f32 v92, v86, v92
	v_mul_f32 v93, v87, v93
	s_waitcnt vmcnt(0)
	v_mul_f32 v96, v104, v96
	v_mul_f32 v97, v105, v97
	v_mul_f32 v98, v102, v98
	v_mul_f32 v99, v103, v99
	v_mul_f32 v86, v84, v94
	v_mul_f32 v87, v85, v95
	v_cvt_pk_bf16_f32 v84, v98, v99
	v_cvt_pk_bf16_f32 v85, v96, v97
	v_cvt_pk_bf16_f32 v86, v86, v87
	v_cvt_pk_bf16_f32 v87, v92, v93
	global_store_dwordx4 v[110:111], v[84:87], off offset:64

.LBB0_1952:
	s_or_b64 exec, exec, s[0:1]
	v_readlane_b32 s0, v253, 56
	s_or_b32 s0, s14, s0
	v_mov_b64_e32 v[86:87], s[18:19]
	v_or_b32_e32 v94, s0, v1
	v_mul_f32 v82, v82, v88
	v_mul_f32 v83, v83, v88
	v_mul_f32 v80, v80, v88
	v_mul_f32 v81, v81, v88
	v_mul_f32 v78, v78, v88
	v_mul_f32 v79, v79, v88
	v_mul_f32 v76, v76, v88
	v_mul_f32 v77, v77, v88
	v_mad_i64_i32 v[86:87], s[0:1], v90, s71, v[86:87]
	v_ashrrev_i32_e32 v95, 31, v94
	v_cmp_ne_u64_e32 vcc, 0, v[84:85]
	v_lshl_add_u64 v[86:87], v[94:95], 1, v[86:87]
	v_cvt_pk_bf16_f32 v90, v80, v81
	v_cvt_pk_bf16_f32 v91, v82, v83
	v_cvt_pk_bf16_f32 v92, v76, v77
	v_cvt_pk_bf16_f32 v93, v78, v79
	v_lshl_add_u64 v[84:85], v[94:95], 2, v[84:85]
	global_store_dwordx4 v[86:87], v[90:93], off
	s_and_saveexec_b64 s[0:1], vcc
	s_cbranch_execz .LBB0_1954
	global_store_dwordx4 v[84:85], v[80:83], off
	global_store_dwordx4 v[84:85], v[76:79], off offset:16

.LBB0_1957:
	s_nop 0
	v_fmamk_f32 v68, v165, 0x3a800000, v231
	v_cmp_gt_f32_e32 vcc, s11, v68
	v_mul_f32_e32 v69, 0x4b800000, v68
	s_addk_i32 s15, 0x4080
	v_cndmask_b32_e32 v68, v68, v69, vcc
	v_rsq_f32_e32 v68, v68
	v_or_b32_e32 v72, s15, v164
	s_mov_b64 s[0:1], -1
	v_mul_f32_e32 v69, 0x45800000, v68
	v_cndmask_b32_e32 v74, v68, v69, vcc
	s_and_b64 vcc, exec, s[16:17]
	s_cbranch_vccnz .LBB0_1959
	v_ashrrev_i32_e32 v73, 31, v72
	v_lshlrev_b64 v[68:69], 9, v[72:73]
	v_lshl_add_u64 v[68:69], s[28:29], 0, v[68:69]
	s_lshl_b32 s68, s14, 1
	v_mul_f32 v90, v66, v74
	v_mul_f32 v91, v67, v74
	v_mul_f32 v92, v64, v74
	v_mul_f32 v93, v65, v74
	v_lshl_add_u64 v[94:95], v[68:69], 0, s[68:69]
	v_mul_f32 v68, v90, v90
	v_mul_f32 v69, v91, v91
	v_mul_f32 v70, v92, v92
	v_mul_f32 v71, v93, v93
	v_mul_f32 v86, v62, v74
	v_mul_f32 v87, v63, v74
	v_pk_mov_b32 v[76:77], v[70:71], v[68:69] op_sel:[1,0]
	v_mov_b32_e32 v71, v69
	v_add_f32 v68, v76, v70
	v_add_f32 v69, v77, v71
	v_mul_f32 v88, v60, v74
	v_mul_f32 v89, v61, v74
	v_add_f32 v69, v68, v69
	v_add_f32 v68, v68, v68
	v_mul_f32 v70, v86, v86
	v_mul_f32 v71, v87, v87
	v_mul_f32 v76, v88, v88
	v_mul_f32 v77, v89, v89
	v_mul_f32 v82, v56, v74
	v_mul_f32 v83, v57, v74
	v_pk_mov_b32 v[78:79], v[76:77], v[70:71] op_sel:[1,0]
	v_mov_b32_e32 v77, v71
	v_mul_f32 v80, v58, v74
	v_mul_f32 v81, v59, v74
	v_mul_f32_e32 v68, v82, v82
	v_add_f32 v70, v78, v76
	v_add_f32 v71, v79, v77
	v_fma_f32 v84, v82, v82, v68
	v_fma_f32 v85, v83, v83, v68
	v_mul_f32_e32 v68, v80, v80
	v_add_f32 v71, v70, v71
	v_add_f32 v70, v70, v70
	v_fma_f32 v96, v80, v80, v68
	v_fma_f32 v97, v81, v81, v68
	v_mul_f32 v76, v54, v74
	v_mul_f32 v77, v55, v74
	v_mul_f32 v78, v52, v74
	v_mul_f32 v79, v53, v74
	v_mul_f32_e32 v68, v76, v76
	v_mul_f32_e32 v84, v78, v78
	v_mul_f32_e32 v96, v79, v79
	v_mul_f32_e32 v70, v77, v77
	v_add_f32 v84, v84, v96
	v_add_f32 v85, v85, v97
	v_add_f32 v68, v68, v70
	v_add_f32 v69, v69, v71
	v_and_b32_e32 v70, 64, v236
	v_add_f32 v68, v84, v68
	v_add_f32 v69, v85, v69
	v_add_u32_e32 v70, 64, v70
	v_add_f32_e32 v68, v68, v69
	ds_swizzle_b32 v69, v68 offset:swizzle(SWAP,16)
	v_mov_b32_e32 v137, v2
	v_lshl_add_u64 v[94:95], v[94:95], 0, v[136:137]
	s_mov_b64 s[0:1], 0
	s_waitcnt lgkmcnt(0)
	v_add_f32_e32 v68, v68, v69
	v_xor_b32_e32 v69, 32, v236
	v_cmp_lt_i32_e32 vcc, v69, v70
	s_nop 1
	v_cndmask_b32_e32 v69, v236, v69, vcc
	v_lshlrev_b32_e32 v69, 2, v69
	ds_bpermute_b32 v69, v69, v68
	s_waitcnt lgkmcnt(0)
	v_add_f32_e32 v68, v68, v69
	v_fmamk_f32 v68, v68, 0x3c800000, v231
	v_cmp_gt_f32_e32 vcc, s11, v68
	v_mul_f32_e32 v69, 0x4b800000, v68
	s_nop 0
	v_cndmask_b32_e32 v68, v68, v69, vcc
	v_rsq_f32_e32 v68, v68
	s_nop 0
	v_mul_f32_e32 v69, 0x45800000, v68
	v_cndmask_b32_e32 v68, v68, v69, vcc
	v_mul_f32_e32 v84, 0x3e38aa3b, v68
	global_load_dwordx4 v[68:71], v3, s[26:27] offset:16
	global_load_dwordx4 v[96:99], v3, s[26:27]
	v_mul_f32 v92, v92, v84
	v_mul_f32 v93, v93, v84
	v_mul_f32 v90, v90, v84
	v_mul_f32 v91, v91, v84
	v_mul_f32 v88, v88, v84
	v_mul_f32 v89, v89, v84
	v_mul_f32 v86, v86, v84
	v_mul_f32 v87, v87, v84
	v_mul_f32 v82, v82, v84
	v_mul_f32 v83, v83, v84
	v_mul_f32 v80, v80, v84
	v_mul_f32 v81, v81, v84
	v_mul_f32 v78, v78, v84
	v_mul_f32 v79, v79, v84
	v_mul_f32 v76, v76, v84
	v_mul_f32 v77, v77, v84
	s_waitcnt vmcnt(1)
	v_mul_f32 v86, v70, v86
	v_mul_f32 v87, v71, v87
	s_waitcnt vmcnt(0)
	v_mul_f32 v90, v98, v90
	v_mul_f32 v91, v99, v91
	v_mul_f32 v92, v96, v92
	v_mul_f32 v93, v97, v93
	v_mul_f32 v70, v68, v88
	v_mul_f32 v71, v69, v89
	v_cvt_pk_bf16_f32 v68, v92, v93
	v_cvt_pk_bf16_f32 v69, v90, v91
	v_cvt_pk_bf16_f32 v70, v70, v71
	v_cvt_pk_bf16_f32 v71, v86, v87
	global_store_dwordx4 v[94:95], v[68:71], off
	global_load_dwordx4 v[68:71], v3, s[26:27] offset:144
	s_nop 0
	global_load_dwordx4 v[86:89], v3, s[26:27] offset:128
	s_waitcnt vmcnt(1)
	v_mul_f32 v76, v70, v76
	v_mul_f32 v77, v71, v77
	s_waitcnt vmcnt(0)
	v_mul_f32 v80, v88, v80
	v_mul_f32 v81, v89, v81
	v_mul_f32 v82, v86, v82
	v_mul_f32 v83, v87, v83
	v_mul_f32 v70, v68, v78
	v_mul_f32 v71, v69, v79
	v_cvt_pk_bf16_f32 v68, v82, v83
	v_cvt_pk_bf16_f32 v69, v80, v81
	v_cvt_pk_bf16_f32 v70, v70, v71
	v_cvt_pk_bf16_f32 v71, v76, v77
	global_store_dwordx4 v[94:95], v[68:71], off offset:64
.LBB0_1959:
	s_andn2_b64 vcc, exec, s[0:1]
	s_cbranch_vccnz .LBB0_1967
	s_movk_i32 s0, 0x3fff
	v_cmp_lt_i32_e32 vcc, s0, v72
	v_mov_b64_e32 v[68:69], 0
	s_and_saveexec_b64 s[0:1], vcc
	v_add_u32_e32 v68, 0xffffc000, v72
	v_lshrrev_b32_e32 v68, 3, v68
	v_mad_u64_u32 v[70:71], s[8:9], v68, 15, v[132:133]
	v_mov_b64_e32 v[68:69], s[6:7]
	v_mad_u64_u32 v[68:69], s[8:9], v70, s91, v[68:69]
	v_mad_u32_u24 v69, v71, s91, v69
	s_or_b64 exec, exec, s[0:1]
	v_readlane_b32 s0, v253, 56
	s_or_b32 s0, s14, s0
	v_mov_b64_e32 v[70:71], s[18:19]
	v_or_b32_e32 v80, s0, v1
	v_mul_f32 v66, v66, v74
	v_mul_f32 v67, v67, v74
	v_mul_f32 v64, v64, v74
	v_mul_f32 v65, v65, v74
	v_mul_f32 v62, v62, v74
	v_mul_f32 v63, v63, v74
	v_mul_f32 v60, v60, v74
	v_mul_f32 v61, v61, v74
	v_mad_i64_i32 v[70:71], s[0:1], v72, s71, v[70:71]
	v_ashrrev_i32_e32 v81, 31, v80
	v_cmp_ne_u64_e32 vcc, 0, v[68:69]
	v_lshl_add_u64 v[70:71], v[80:81], 1, v[70:71]
	v_cvt_pk_bf16_f32 v76, v64, v65
	v_cvt_pk_bf16_f32 v77, v66, v67
	v_cvt_pk_bf16_f32 v78, v60, v61
	v_cvt_pk_bf16_f32 v79, v62, v63
	v_lshl_add_u64 v[68:69], v[80:81], 2, v[68:69]
	global_store_dwordx4 v[70:71], v[76:79], off
	s_and_saveexec_b64 s[0:1], vcc
	s_cbranch_execz .LBB0_1964
	global_store_dwordx4 v[68:69], v[64:67], off
	global_store_dwordx4 v[68:69], v[60:63], off offset:16

.LBB0_1967:
	s_nop 0
	v_fmamk_f32 v52, v163, 0x3a800000, v231
	v_cmp_gt_f32_e32 vcc, s11, v52
	v_mul_f32_e32 v53, 0x4b800000, v52
	v_or_b32_e32 v58, 16, v72
	v_cndmask_b32_e32 v52, v52, v53, vcc
	v_rsq_f32_e32 v52, v52
	s_mov_b64 s[0:1], -1
	v_mul_f32_e32 v53, 0x45800000, v52
	v_cndmask_b32_e32 v56, v52, v53, vcc
	s_and_b64 vcc, exec, s[16:17]
	s_cbranch_vccnz .LBB0_1969
	v_ashrrev_i32_e32 v59, 31, v58
	v_lshlrev_b64 v[52:53], 9, v[58:59]
	v_lshl_add_u64 v[52:53], s[28:29], 0, v[52:53]
	s_lshl_b32 s68, s14, 1
	v_mul_f32 v76, v50, v56
	v_mul_f32 v77, v51, v56
	v_mul_f32 v78, v48, v56
	v_mul_f32 v79, v49, v56
	v_lshl_add_u64 v[80:81], v[52:53], 0, s[68:69]
	v_mul_f32 v52, v76, v76
	v_mul_f32 v53, v77, v77
	v_mul_f32 v54, v78, v78
	v_mul_f32 v55, v79, v79
	v_mul_f32 v70, v46, v56
	v_mul_f32 v71, v47, v56
	v_pk_mov_b32 v[60:61], v[54:55], v[52:53] op_sel:[1,0]
	v_mov_b32_e32 v55, v53
	v_add_f32 v52, v60, v54
	v_add_f32 v53, v61, v55
	v_mul_f32 v74, v44, v56
	v_mul_f32 v75, v45, v56
	v_add_f32 v53, v52, v53
	v_add_f32 v52, v52, v52
	v_mul_f32 v54, v70, v70
	v_mul_f32 v55, v71, v71
	v_mul_f32 v60, v74, v74
	v_mul_f32 v61, v75, v75
	v_mul_f32 v66, v40, v56
	v_mul_f32 v67, v41, v56
	v_pk_mov_b32 v[62:63], v[60:61], v[54:55] op_sel:[1,0]
	v_mov_b32_e32 v61, v55
	v_mul_f32 v64, v42, v56
	v_mul_f32 v65, v43, v56
	v_mul_f32_e32 v52, v66, v66
	v_add_f32 v54, v62, v60
	v_add_f32 v55, v63, v61
	v_fma_f32 v68, v66, v66, v52
	v_fma_f32 v69, v67, v67, v52
	v_mul_f32_e32 v52, v64, v64
	v_add_f32 v55, v54, v55
	v_add_f32 v54, v54, v54
	v_fma_f32 v82, v64, v64, v52
	v_fma_f32 v83, v65, v65, v52
	v_mul_f32 v60, v38, v56
	v_mul_f32 v61, v39, v56
	v_mul_f32 v62, v36, v56
	v_mul_f32 v63, v37, v56
	v_mul_f32_e32 v52, v60, v60
	v_mul_f32_e32 v68, v62, v62
	v_mul_f32_e32 v82, v63, v63
	v_mul_f32_e32 v54, v61, v61
	v_add_f32 v68, v68, v82
	v_add_f32 v69, v69, v83
	v_add_f32 v52, v52, v54
	v_add_f32 v53, v53, v55
	v_and_b32_e32 v54, 64, v236
	v_add_f32 v52, v68, v52
	v_add_f32 v53, v69, v53
	v_add_u32_e32 v54, 64, v54
	v_add_f32_e32 v52, v52, v53
	ds_swizzle_b32 v53, v52 offset:swizzle(SWAP,16)
	v_mov_b32_e32 v137, v2
	v_lshl_add_u64 v[80:81], v[80:81], 0, v[136:137]
	s_mov_b64 s[0:1], 0
	s_waitcnt lgkmcnt(0)
	v_add_f32_e32 v52, v52, v53
	v_xor_b32_e32 v53, 32, v236
	v_cmp_lt_i32_e32 vcc, v53, v54
	s_nop 1
	v_cndmask_b32_e32 v53, v236, v53, vcc
	v_lshlrev_b32_e32 v53, 2, v53
	ds_bpermute_b32 v53, v53, v52
	s_waitcnt lgkmcnt(0)
	v_add_f32_e32 v52, v52, v53
	v_fmamk_f32 v52, v52, 0x3c800000, v231
	v_cmp_gt_f32_e32 vcc, s11, v52
	v_mul_f32_e32 v53, 0x4b800000, v52
	s_nop 0
	v_cndmask_b32_e32 v52, v52, v53, vcc
	v_rsq_f32_e32 v52, v52
	s_nop 0
	v_mul_f32_e32 v53, 0x45800000, v52
	v_cndmask_b32_e32 v52, v52, v53, vcc
	v_mul_f32_e32 v68, 0x3e38aa3b, v52
	global_load_dwordx4 v[52:55], v3, s[26:27] offset:16
	global_load_dwordx4 v[82:85], v3, s[26:27]
	v_mul_f32 v78, v78, v68
	v_mul_f32 v79, v79, v68
	v_mul_f32 v76, v76, v68
	v_mul_f32 v77, v77, v68
	v_mul_f32 v74, v74, v68
	v_mul_f32 v75, v75, v68
	v_mul_f32 v70, v70, v68
	v_mul_f32 v71, v71, v68
	v_mul_f32 v66, v66, v68
	v_mul_f32 v67, v67, v68
	v_mul_f32 v64, v64, v68
	v_mul_f32 v65, v65, v68
	v_mul_f32 v62, v62, v68
	v_mul_f32 v63, v63, v68
	v_mul_f32 v60, v60, v68
	v_mul_f32 v61, v61, v68
	s_waitcnt vmcnt(1)
	v_mul_f32 v70, v54, v70
	v_mul_f32 v71, v55, v71
	s_waitcnt vmcnt(0)
	v_mul_f32 v76, v84, v76
	v_mul_f32 v77, v85, v77
	v_mul_f32 v78, v82, v78
	v_mul_f32 v79, v83, v79
	v_mul_f32 v54, v52, v74
	v_mul_f32 v55, v53, v75
	v_cvt_pk_bf16_f32 v52, v78, v79
	v_cvt_pk_bf16_f32 v53, v76, v77
	v_cvt_pk_bf16_f32 v54, v54, v55
	v_cvt_pk_bf16_f32 v55, v70, v71
	global_store_dwordx4 v[80:81], v[52:55], off
	global_load_dwordx4 v[52:55], v3, s[26:27] offset:144
	s_nop 0
	global_load_dwordx4 v[74:77], v3, s[26:27] offset:128
	s_waitcnt vmcnt(1)
	v_mul_f32 v60, v54, v60
	v_mul_f32 v61, v55, v61
	s_waitcnt vmcnt(0)
	v_mul_f32 v64, v76, v64
	v_mul_f32 v65, v77, v65
	v_mul_f32 v66, v74, v66
	v_mul_f32 v67, v75, v67
	v_mul_f32 v54, v52, v62
	v_mul_f32 v55, v53, v63
	v_cvt_pk_bf16_f32 v52, v66, v67
	v_cvt_pk_bf16_f32 v53, v64, v65
	v_cvt_pk_bf16_f32 v54, v54, v55
	v_cvt_pk_bf16_f32 v55, v60, v61
	global_store_dwordx4 v[80:81], v[52:55], off offset:64
.LBB0_1969:
	s_andn2_b64 vcc, exec, s[0:1]
	s_cbranch_vccnz .LBB0_1977
	s_movk_i32 s0, 0x3fff
	v_cmp_lt_i32_e32 vcc, s0, v58
	v_mov_b64_e32 v[52:53], 0
	s_and_saveexec_b64 s[0:1], vcc
	v_add_u32_e32 v52, 0xffffc010, v72
	v_lshrrev_b32_e32 v52, 3, v52
	v_mad_u64_u32 v[54:55], s[8:9], v52, 15, v[132:133]
	v_mov_b64_e32 v[52:53], s[6:7]
	v_mad_u64_u32 v[52:53], s[8:9], v54, s91, v[52:53]
	v_mad_u32_u24 v53, v55, s91, v53
	s_or_b64 exec, exec, s[0:1]
	v_readlane_b32 s0, v253, 56
	s_or_b32 s0, s14, s0
	v_mov_b64_e32 v[54:55], s[18:19]
	v_or_b32_e32 v62, s0, v1
	v_mul_f32 v50, v50, v56
	v_mul_f32 v51, v51, v56
	v_mul_f32 v48, v48, v56
	v_mul_f32 v49, v49, v56
	v_mul_f32 v46, v46, v56
	v_mul_f32 v47, v47, v56
	v_mul_f32 v44, v44, v56
	v_mul_f32 v45, v45, v56
	v_mad_i64_i32 v[54:55], s[0:1], v58, s71, v[54:55]
	v_ashrrev_i32_e32 v63, 31, v62
	v_cmp_ne_u64_e32 vcc, 0, v[52:53]
	v_lshl_add_u64 v[54:55], v[62:63], 1, v[54:55]
	v_cvt_pk_bf16_f32 v58, v48, v49
	v_cvt_pk_bf16_f32 v59, v50, v51
	v_cvt_pk_bf16_f32 v60, v44, v45
	v_cvt_pk_bf16_f32 v61, v46, v47
	v_lshl_add_u64 v[52:53], v[62:63], 2, v[52:53]
	global_store_dwordx4 v[54:55], v[58:61], off
	s_and_saveexec_b64 s[0:1], vcc
	s_cbranch_execz .LBB0_1974
	global_store_dwordx4 v[52:53], v[48:51], off
	global_store_dwordx4 v[52:53], v[44:47], off offset:16

.LBB0_1977:
	s_nop 0
	v_fmamk_f32 v36, v162, 0x3a800000, v231
	v_cmp_gt_f32_e32 vcc, s11, v36
	v_mul_f32_e32 v37, 0x4b800000, v36
	v_or_b32_e32 v42, 32, v72
	v_cndmask_b32_e32 v36, v36, v37, vcc
	v_rsq_f32_e32 v36, v36
	s_mov_b64 s[0:1], -1
	v_mul_f32_e32 v37, 0x45800000, v36
	v_cndmask_b32_e32 v40, v36, v37, vcc
	s_and_b64 vcc, exec, s[16:17]
	s_cbranch_vccnz .LBB0_1979
	v_ashrrev_i32_e32 v43, 31, v42
	v_lshlrev_b64 v[36:37], 9, v[42:43]
	v_lshl_add_u64 v[36:37], s[28:29], 0, v[36:37]
	s_lshl_b32 s68, s14, 1
	v_mul_f32 v58, v34, v40
	v_mul_f32 v59, v35, v40
	v_mul_f32 v60, v32, v40
	v_mul_f32 v61, v33, v40
	v_lshl_add_u64 v[62:63], v[36:37], 0, s[68:69]
	v_mul_f32 v36, v58, v58
	v_mul_f32 v37, v59, v59
	v_mul_f32 v38, v60, v60
	v_mul_f32 v39, v61, v61
	v_mul_f32 v54, v30, v40
	v_mul_f32 v55, v31, v40
	v_pk_mov_b32 v[44:45], v[38:39], v[36:37] op_sel:[1,0]
	v_mov_b32_e32 v39, v37
	v_add_f32 v36, v44, v38
	v_add_f32 v37, v45, v39
	v_mul_f32 v56, v28, v40
	v_mul_f32 v57, v29, v40
	v_add_f32 v37, v36, v37
	v_add_f32 v36, v36, v36
	v_mul_f32 v38, v54, v54
	v_mul_f32 v39, v55, v55
	v_mul_f32 v44, v56, v56
	v_mul_f32 v45, v57, v57
	v_mul_f32 v50, v24, v40
	v_mul_f32 v51, v25, v40
	v_pk_mov_b32 v[46:47], v[44:45], v[38:39] op_sel:[1,0]
	v_mov_b32_e32 v45, v39
	v_mul_f32 v48, v26, v40
	v_mul_f32 v49, v27, v40
	v_mul_f32_e32 v36, v50, v50
	v_add_f32 v38, v46, v44
	v_add_f32 v39, v47, v45
	v_fma_f32 v52, v50, v50, v36
	v_fma_f32 v53, v51, v51, v36
	v_mul_f32_e32 v36, v48, v48
	v_add_f32 v39, v38, v39
	v_add_f32 v38, v38, v38
	v_fma_f32 v64, v48, v48, v36
	v_fma_f32 v65, v49, v49, v36
	v_mul_f32 v44, v22, v40
	v_mul_f32 v45, v23, v40
	v_mul_f32 v46, v20, v40
	v_mul_f32 v47, v21, v40
	v_mul_f32_e32 v36, v44, v44
	v_mul_f32_e32 v52, v46, v46
	v_mul_f32_e32 v64, v47, v47
	v_mul_f32_e32 v38, v45, v45
	v_add_f32 v52, v52, v64
	v_add_f32 v53, v53, v65
	v_add_f32 v36, v36, v38
	v_add_f32 v37, v37, v39
	v_and_b32_e32 v38, 64, v236
	v_add_f32 v36, v52, v36
	v_add_f32 v37, v53, v37
	v_add_u32_e32 v38, 64, v38
	v_add_f32_e32 v36, v36, v37
	ds_swizzle_b32 v37, v36 offset:swizzle(SWAP,16)
	v_mov_b32_e32 v137, v2
	v_lshl_add_u64 v[62:63], v[62:63], 0, v[136:137]
	s_mov_b64 s[0:1], 0
	s_waitcnt lgkmcnt(0)
	v_add_f32_e32 v36, v36, v37
	v_xor_b32_e32 v37, 32, v236
	v_cmp_lt_i32_e32 vcc, v37, v38
	s_nop 1
	v_cndmask_b32_e32 v37, v236, v37, vcc
	v_lshlrev_b32_e32 v37, 2, v37
	ds_bpermute_b32 v37, v37, v36
	s_waitcnt lgkmcnt(0)
	v_add_f32_e32 v36, v36, v37
	v_fmamk_f32 v36, v36, 0x3c800000, v231
	v_cmp_gt_f32_e32 vcc, s11, v36
	v_mul_f32_e32 v37, 0x4b800000, v36
	s_nop 0
	v_cndmask_b32_e32 v36, v36, v37, vcc
	v_rsq_f32_e32 v36, v36
	s_nop 0
	v_mul_f32_e32 v37, 0x45800000, v36
	v_cndmask_b32_e32 v36, v36, v37, vcc
	v_mul_f32_e32 v52, 0x3e38aa3b, v36
	global_load_dwordx4 v[36:39], v3, s[26:27] offset:16
	global_load_dwordx4 v[64:67], v3, s[26:27]
	v_mul_f32 v60, v60, v52
	v_mul_f32 v61, v61, v52
	v_mul_f32 v58, v58, v52
	v_mul_f32 v59, v59, v52
	v_mul_f32 v56, v56, v52
	v_mul_f32 v57, v57, v52
	v_mul_f32 v54, v54, v52
	v_mul_f32 v55, v55, v52
	v_mul_f32 v50, v50, v52
	v_mul_f32 v51, v51, v52
	v_mul_f32 v48, v48, v52
	v_mul_f32 v49, v49, v52
	v_mul_f32 v46, v46, v52
	v_mul_f32 v47, v47, v52
	v_mul_f32 v44, v44, v52
	v_mul_f32 v45, v45, v52
	s_waitcnt vmcnt(1)
	v_mul_f32 v54, v38, v54
	v_mul_f32 v55, v39, v55
	s_waitcnt vmcnt(0)
	v_mul_f32 v58, v66, v58
	v_mul_f32 v59, v67, v59
	v_mul_f32 v60, v64, v60
	v_mul_f32 v61, v65, v61
	v_mul_f32 v38, v36, v56
	v_mul_f32 v39, v37, v57
	v_cvt_pk_bf16_f32 v36, v60, v61
	v_cvt_pk_bf16_f32 v37, v58, v59
	v_cvt_pk_bf16_f32 v38, v38, v39
	v_cvt_pk_bf16_f32 v39, v54, v55
	global_store_dwordx4 v[62:63], v[36:39], off
	global_load_dwordx4 v[36:39], v3, s[26:27] offset:144
	s_nop 0
	global_load_dwordx4 v[54:57], v3, s[26:27] offset:128
	s_waitcnt vmcnt(1)
	v_mul_f32 v44, v38, v44
	v_mul_f32 v45, v39, v45
	s_waitcnt vmcnt(0)
	v_mul_f32 v48, v56, v48
	v_mul_f32 v49, v57, v49
	v_mul_f32 v50, v54, v50
	v_mul_f32 v51, v55, v51
	v_mul_f32 v38, v36, v46
	v_mul_f32 v39, v37, v47
	v_cvt_pk_bf16_f32 v36, v50, v51
	v_cvt_pk_bf16_f32 v37, v48, v49
	v_cvt_pk_bf16_f32 v38, v38, v39
	v_cvt_pk_bf16_f32 v39, v44, v45
	global_store_dwordx4 v[62:63], v[36:39], off offset:64
.LBB0_1979:
	s_andn2_b64 vcc, exec, s[0:1]
	s_cbranch_vccnz .LBB0_1987
	s_movk_i32 s0, 0x3fff
	v_cmp_lt_i32_e32 vcc, s0, v42
	v_mov_b64_e32 v[36:37], 0
	s_and_saveexec_b64 s[0:1], vcc
	v_add_u32_e32 v36, 0xffffc020, v72
	v_lshrrev_b32_e32 v36, 3, v36
	v_mad_u64_u32 v[38:39], s[8:9], v36, 15, v[132:133]
	v_mov_b64_e32 v[36:37], s[6:7]
	v_mad_u64_u32 v[36:37], s[8:9], v38, s91, v[36:37]
	v_mad_u32_u24 v37, v39, s91, v37
	s_or_b64 exec, exec, s[0:1]
	v_readlane_b32 s0, v253, 56
	s_or_b32 s0, s14, s0
	v_mov_b64_e32 v[38:39], s[18:19]
	v_or_b32_e32 v46, s0, v1
	v_mul_f32 v34, v34, v40
	v_mul_f32 v35, v35, v40
	v_mul_f32 v32, v32, v40
	v_mul_f32 v33, v33, v40
	v_mul_f32 v30, v30, v40
	v_mul_f32 v31, v31, v40
	v_mul_f32 v28, v28, v40
	v_mul_f32 v29, v29, v40
	v_mad_i64_i32 v[38:39], s[0:1], v42, s71, v[38:39]
	v_ashrrev_i32_e32 v47, 31, v46
	v_cmp_ne_u64_e32 vcc, 0, v[36:37]
	v_lshl_add_u64 v[38:39], v[46:47], 1, v[38:39]
	v_cvt_pk_bf16_f32 v42, v32, v33
	v_cvt_pk_bf16_f32 v43, v34, v35
	v_cvt_pk_bf16_f32 v44, v28, v29
	v_cvt_pk_bf16_f32 v45, v30, v31
	v_lshl_add_u64 v[36:37], v[46:47], 2, v[36:37]
	global_store_dwordx4 v[38:39], v[42:45], off
	s_and_saveexec_b64 s[0:1], vcc
	s_cbranch_execz .LBB0_1984
	global_store_dwordx4 v[36:37], v[32:35], off
	global_store_dwordx4 v[36:37], v[28:31], off offset:16

.LBB0_1987:
	s_nop 0
	v_fmamk_f32 v20, v151, 0x3a800000, v231
	v_cmp_gt_f32_e32 vcc, s11, v20
	v_mul_f32_e32 v21, 0x4b800000, v20
	v_or_b32_e32 v26, 48, v72
	v_cndmask_b32_e32 v20, v20, v21, vcc
	v_rsq_f32_e32 v20, v20
	s_mov_b64 s[0:1], -1
	v_mul_f32_e32 v21, 0x45800000, v20
	v_cndmask_b32_e32 v24, v20, v21, vcc
	s_and_b64 vcc, exec, s[16:17]
	s_cbranch_vccnz .LBB0_1989
	v_ashrrev_i32_e32 v27, 31, v26
	v_lshlrev_b64 v[20:21], 9, v[26:27]
	v_lshl_add_u64 v[20:21], s[28:29], 0, v[20:21]
	s_lshl_b32 s68, s14, 1
	v_mul_f32 v42, v18, v24
	v_mul_f32 v43, v19, v24
	v_mul_f32 v44, v16, v24
	v_mul_f32 v45, v17, v24
	v_lshl_add_u64 v[46:47], v[20:21], 0, s[68:69]
	v_mul_f32 v20, v42, v42
	v_mul_f32 v21, v43, v43
	v_mul_f32 v22, v44, v44
	v_mul_f32 v23, v45, v45
	v_mul_f32 v38, v14, v24
	v_mul_f32 v39, v15, v24
	v_pk_mov_b32 v[28:29], v[22:23], v[20:21] op_sel:[1,0]
	v_mov_b32_e32 v23, v21
	v_add_f32 v20, v28, v22
	v_add_f32 v21, v29, v23
	v_mul_f32 v40, v12, v24
	v_mul_f32 v41, v13, v24
	v_add_f32 v21, v20, v21
	v_add_f32 v20, v20, v20
	v_mul_f32 v22, v38, v38
	v_mul_f32 v23, v39, v39
	v_mul_f32 v28, v40, v40
	v_mul_f32 v29, v41, v41
	v_mul_f32 v34, v8, v24
	v_mul_f32 v35, v9, v24
	v_pk_mov_b32 v[30:31], v[28:29], v[22:23] op_sel:[1,0]
	v_mov_b32_e32 v29, v23
	v_mul_f32 v32, v10, v24
	v_mul_f32 v33, v11, v24
	v_mul_f32_e32 v20, v34, v34
	v_add_f32 v22, v30, v28
	v_add_f32 v23, v31, v29
	v_fma_f32 v36, v34, v34, v20
	v_fma_f32 v37, v35, v35, v20
	v_mul_f32_e32 v20, v32, v32
	v_add_f32 v23, v22, v23
	v_add_f32 v22, v22, v22
	v_fma_f32 v48, v32, v32, v20
	v_fma_f32 v49, v33, v33, v20
	v_mul_f32 v28, v6, v24
	v_mul_f32 v29, v7, v24
	v_mul_f32 v30, v4, v24
	v_mul_f32 v31, v5, v24
	v_mul_f32_e32 v20, v28, v28
	v_mul_f32_e32 v36, v30, v30
	v_mul_f32_e32 v48, v31, v31
	v_mul_f32_e32 v22, v29, v29
	v_add_f32 v36, v36, v48
	v_add_f32 v37, v37, v49
	v_add_f32 v20, v20, v22
	v_add_f32 v21, v21, v23
	v_and_b32_e32 v22, 64, v236
	v_add_f32 v20, v36, v20
	v_add_f32 v21, v37, v21
	v_add_u32_e32 v22, 64, v22
	v_add_f32_e32 v20, v20, v21
	ds_swizzle_b32 v21, v20 offset:swizzle(SWAP,16)
	v_mov_b32_e32 v137, v2
	v_lshl_add_u64 v[46:47], v[46:47], 0, v[136:137]
	s_mov_b64 s[0:1], 0
	s_waitcnt lgkmcnt(0)
	v_add_f32_e32 v20, v20, v21
	v_xor_b32_e32 v21, 32, v236
	v_cmp_lt_i32_e32 vcc, v21, v22
	s_nop 1
	v_cndmask_b32_e32 v21, v236, v21, vcc
	v_lshlrev_b32_e32 v21, 2, v21
	ds_bpermute_b32 v21, v21, v20
	s_waitcnt lgkmcnt(0)
	v_add_f32_e32 v20, v20, v21
	v_fmamk_f32 v20, v20, 0x3c800000, v231
	v_cmp_gt_f32_e32 vcc, s11, v20
	v_mul_f32_e32 v21, 0x4b800000, v20
	s_nop 0
	v_cndmask_b32_e32 v20, v20, v21, vcc
	v_rsq_f32_e32 v20, v20
	s_nop 0
	v_mul_f32_e32 v21, 0x45800000, v20
	v_cndmask_b32_e32 v20, v20, v21, vcc
	v_mul_f32_e32 v36, 0x3e38aa3b, v20
	global_load_dwordx4 v[20:23], v3, s[26:27] offset:16
	global_load_dwordx4 v[48:51], v3, s[26:27]
	v_mul_f32 v44, v44, v36
	v_mul_f32 v45, v45, v36
	v_mul_f32 v42, v42, v36
	v_mul_f32 v43, v43, v36
	v_mul_f32 v40, v40, v36
	v_mul_f32 v41, v41, v36
	v_mul_f32 v38, v38, v36
	v_mul_f32 v39, v39, v36
	v_mul_f32 v34, v34, v36
	v_mul_f32 v35, v35, v36
	v_mul_f32 v32, v32, v36
	v_mul_f32 v33, v33, v36
	v_mul_f32 v30, v30, v36
	v_mul_f32 v31, v31, v36
	v_mul_f32 v28, v28, v36
	v_mul_f32 v29, v29, v36
	s_waitcnt vmcnt(1)
	v_mul_f32 v38, v22, v38
	v_mul_f32 v39, v23, v39
	s_waitcnt vmcnt(0)
	v_mul_f32 v42, v50, v42
	v_mul_f32 v43, v51, v43
	v_mul_f32 v44, v48, v44
	v_mul_f32 v45, v49, v45
	v_mul_f32 v22, v20, v40
	v_mul_f32 v23, v21, v41
	v_cvt_pk_bf16_f32 v20, v44, v45
	v_cvt_pk_bf16_f32 v21, v42, v43
	v_cvt_pk_bf16_f32 v22, v22, v23
	v_cvt_pk_bf16_f32 v23, v38, v39
	global_store_dwordx4 v[46:47], v[20:23], off
	global_load_dwordx4 v[20:23], v3, s[26:27] offset:144
	s_nop 0
	global_load_dwordx4 v[38:41], v3, s[26:27] offset:128
	s_waitcnt vmcnt(1)
	v_mul_f32 v28, v22, v28
	v_mul_f32 v29, v23, v29
	s_waitcnt vmcnt(0)
	v_mul_f32 v32, v40, v32
	v_mul_f32 v33, v41, v33
	v_mul_f32 v34, v38, v34
	v_mul_f32 v35, v39, v35
	v_mul_f32 v22, v20, v30
	v_mul_f32 v23, v21, v31
	v_cvt_pk_bf16_f32 v20, v34, v35
	v_cvt_pk_bf16_f32 v21, v32, v33
	v_cvt_pk_bf16_f32 v22, v22, v23
	v_cvt_pk_bf16_f32 v23, v28, v29
	global_store_dwordx4 v[46:47], v[20:23], off offset:64

.LBB0_1996:
	s_or_b64 exec, exec, s[0:1]
	v_readlane_b32 s0, v253, 56
	s_or_b32 s0, s14, s0
	v_mov_b64_e32 v[22:23], s[18:19]
	v_or_b32_e32 v30, s0, v1
	v_mul_f32 v18, v18, v24
	v_mul_f32 v19, v19, v24
	v_mul_f32 v16, v16, v24
	v_mul_f32 v17, v17, v24
	v_mul_f32 v14, v14, v24
	v_mul_f32 v15, v15, v24
	v_mul_f32 v12, v12, v24
	v_mul_f32 v13, v13, v24
	v_mad_i64_i32 v[22:23], s[0:1], v26, s71, v[22:23]
	v_ashrrev_i32_e32 v31, 31, v30
	v_cmp_ne_u64_e32 vcc, 0, v[20:21]
	v_lshl_add_u64 v[22:23], v[30:31], 1, v[22:23]
	v_cvt_pk_bf16_f32 v26, v16, v17
	v_cvt_pk_bf16_f32 v27, v18, v19
	v_cvt_pk_bf16_f32 v28, v12, v13
	v_cvt_pk_bf16_f32 v29, v14, v15
	v_lshl_add_u64 v[20:21], v[30:31], 2, v[20:21]
	global_store_dwordx4 v[22:23], v[26:29], off
	s_and_saveexec_b64 s[0:1], vcc
	s_cbranch_execz .LBB0_1998
	global_store_dwordx4 v[20:21], v[16:19], off
	global_store_dwordx4 v[20:21], v[12:15], off offset:16
.LBB0_1998:
	s_or_b64 exec, exec, s[0:1]
	v_mov_b32_e32 v25, v24
	v_mov_b32_e32 v12, v24
	v_mov_b32_e32 v13, v24
	v_mul_f32 v10, v10, v12
	v_mul_f32 v11, v11, v13
	v_mul_f32 v8, v8, v24
	v_mul_f32 v9, v9, v25
	v_mul_f32 v6, v6, v12
	v_mul_f32 v7, v7, v13
	v_mul_f32 v4, v4, v24
	v_mul_f32 v5, v5, v25
	v_cvt_pk_bf16_f32 v12, v8, v9
	v_cvt_pk_bf16_f32 v13, v10, v11
	v_cvt_pk_bf16_f32 v14, v4, v5
	v_cvt_pk_bf16_f32 v15, v6, v7
	global_store_dwordx4 v[22:23], v[12:15], off offset:64
	s_and_saveexec_b64 s[0:1], vcc
	s_cbranch_execz .LBB0_2000
	global_store_dwordx4 v[20:21], v[8:11], off offset:128
	global_store_dwordx4 v[20:21], v[4:7], off offset:144

.LBB0_2016:
	s_or_b64 exec, exec, s[8:9]
	s_waitcnt vmcnt(0)
	v_lshlrev_b32_e32 v32, 16, v12
	v_and_b32_e32 v33, 0xffff0000, v12
	v_pk_add_f32 v[34:35], v[32:33], 0 op_sel_hi:[1,0]
	v_lshlrev_b32_e32 v36, 16, v16
	v_and_b32_e32 v37, 0xffff0000, v16
	v_cndmask_b32_e64 v30, 0.5, 1.0, s[16:17]
	v_add_f32 v34, v34, v36
	v_add_f32 v35, v35, v37
	v_lshlrev_b32_e32 v16, 16, v17
	v_fma_f32 v32, v30, v34, -v32
	v_fma_f32 v33, v30, v35, -v33
	v_cvt_pk_bf16_f32 v12, v32, v33
	v_lshlrev_b32_e32 v32, 16, v13
	v_and_b32_e32 v33, 0xffff0000, v13
	v_pk_add_f32 v[34:35], v[32:33], 0 op_sel_hi:[1,0]
	v_and_b32_e32 v17, 0xffff0000, v17
	v_add_f32 v16, v34, v16
	v_add_f32 v17, v35, v17
	v_lshlrev_b32_e32 v34, 16, v18
	v_fma_f32 v16, v30, v16, -v32
	v_fma_f32 v17, v30, v17, -v33
	v_cvt_pk_bf16_f32 v13, v16, v17
	v_lshlrev_b32_e32 v16, 16, v14
	v_and_b32_e32 v17, 0xffff0000, v14
	v_pk_add_f32 v[32:33], v[16:17], 0 op_sel_hi:[1,0]
	v_and_b32_e32 v35, 0xffff0000, v18
	v_add_f32 v32, v32, v34
	v_add_f32 v33, v33, v35
	v_lshlrev_b32_e32 v18, 16, v19
	v_fma_f32 v16, v30, v32, -v16
	v_fma_f32 v17, v30, v33, -v17
	v_cvt_pk_bf16_f32 v14, v16, v17
	v_lshlrev_b32_e32 v16, 16, v15
	v_and_b32_e32 v17, 0xffff0000, v15
	v_pk_add_f32 v[32:33], v[16:17], 0 op_sel_hi:[1,0]
	v_and_b32_e32 v19, 0xffff0000, v19
	v_add_f32 v18, v32, v18
	v_add_f32 v19, v33, v19
	v_mad_i64_i32 v[28:29], s[8:9], v25, s71, 0
	v_fma_f32 v16, v30, v18, -v16
	v_fma_f32 v17, v30, v19, -v17
	v_cvt_pk_bf16_f32 v15, v16, v17
	v_lshl_add_u64 v[16:17], s[28:29], 0, v[28:29]
	v_lshl_add_u64 v[16:17], v[22:23], 1, v[16:17]
	global_store_dwordx4 v[16:17], v[12:15], off
	s_and_saveexec_b64 s[8:9], vcc
	s_cbranch_execz .LBB0_2007
	v_lshlrev_b32_e32 v12, 16, v4
	v_and_b32_e32 v13, 0xffff0000, v4
	v_cmp_eq_u32_e32 vcc, 0, v26
	v_pk_add_f32 v[14:15], v[12:13], 0 op_sel_hi:[1,0]
	v_lshlrev_b32_e32 v18, 16, v8
	v_and_b32_e32 v19, 0xffff0000, v8
	v_cndmask_b32_e64 v16, 0.5, 1.0, vcc
	v_add_f32 v14, v14, v18
	v_add_f32 v15, v15, v19
	v_lshlrev_b32_e32 v22, 16, v9
	v_fma_f32 v12, v16, v14, -v12
	v_fma_f32 v13, v16, v15, -v13
	v_lshlrev_b32_e32 v14, 16, v5
	v_and_b32_e32 v15, 0xffff0000, v5
	v_pk_add_f32 v[18:19], v[14:15], 0 op_sel_hi:[1,0]
	v_and_b32_e32 v23, 0xffff0000, v9
	v_add_f32 v18, v18, v22
	v_add_f32 v19, v19, v23
	v_cvt_pk_bf16_f32 v12, v12, v13
	v_fma_f32 v14, v16, v18, -v14
	v_fma_f32 v15, v16, v19, -v15
	v_cvt_pk_bf16_f32 v13, v14, v15
	v_lshlrev_b32_e32 v14, 16, v6
	v_and_b32_e32 v15, 0xffff0000, v6
	v_pk_add_f32 v[18:19], v[14:15], 0 op_sel_hi:[1,0]
	v_lshlrev_b32_e32 v22, 16, v10
	v_and_b32_e32 v23, 0xffff0000, v10
	v_add_f32 v18, v18, v22
	v_add_f32 v19, v19, v23
	v_lshlrev_b32_e32 v26, 16, v11
	v_fma_f32 v14, v16, v18, -v14
	v_fma_f32 v15, v16, v19, -v15
	v_lshlrev_b32_e32 v18, 16, v7
	v_and_b32_e32 v19, 0xffff0000, v7
	v_pk_add_f32 v[22:23], v[18:19], 0 op_sel_hi:[1,0]
	v_and_b32_e32 v27, 0xffff0000, v11
	v_add_f32 v22, v22, v26
	v_add_f32 v23, v23, v27
	v_cvt_pk_bf16_f32 v14, v14, v15
	v_fma_f32 v17, v16, v23, -v19
	v_fma_f32 v16, v16, v22, -v18
	v_cvt_pk_bf16_f32 v15, v16, v17
	v_mov_b64_e32 v[16:17], s[28:29]
	v_mad_i64_i32 v[16:17], s[14:15], v24, s71, v[16:17]
	v_lshl_add_u64 v[16:17], v[20:21], 1, v[16:17]
	global_store_dwordx4 v[16:17], v[12:15], off
	s_branch .LBB0_2007

.LBB0_2036:
	s_or_b64 exec, exec, s[8:9]
	v_min_u32_e32 v39, 3, v45
	v_add_u32_e32 v39, 1, v39
	v_cvt_f32_ubyte0_e32 v39, v39
	v_div_scale_f32 v45, s[8:9], v39, v39, 1.0
	v_rcp_f32_e32 v47, v45
	v_div_scale_f32 v48, vcc, 1.0, v39, 1.0
	s_waitcnt vmcnt(0)
	v_and_b32_e32 v51, 0xffff0000, v24
	v_fma_f32 v49, -v45, v47, 1.0
	v_fmac_f32_e32 v47, v49, v47
	v_mul_f32_e32 v49, v48, v47
	v_fma_f32 v50, -v45, v49, v48
	v_fmac_f32_e32 v49, v50, v47
	v_lshlrev_b32_e32 v50, 16, v24
	v_pk_add_f32 v[52:53], v[50:51], 0 op_sel_hi:[1,0]
	v_lshlrev_b32_e32 v54, 16, v28
	v_and_b32_e32 v55, 0xffff0000, v28
	v_fma_f32 v45, -v45, v49, v48
	v_add_f32 v52, v52, v54
	v_add_f32 v53, v53, v55
	v_lshlrev_b32_e32 v54, 16, v32
	v_and_b32_e32 v55, 0xffff0000, v32
	v_div_fmas_f32 v45, v45, v47, v49
	v_add_f32 v52, v52, v54
	v_add_f32 v53, v53, v55
	v_lshlrev_b32_e32 v54, 16, v20
	v_and_b32_e32 v55, 0xffff0000, v20
	v_div_fixup_f32 v48, v45, v39, 1.0
	v_add_f32 v52, v52, v54
	v_add_f32 v53, v53, v55
	v_lshlrev_b32_e32 v24, 16, v25
	v_fma_f32 v50, v48, v52, -v50
	v_fma_f32 v51, v48, v53, -v51
	v_and_b32_e32 v25, 0xffff0000, v25
	v_cvt_pk_bf16_f32 v20, v50, v51
	v_pk_add_f32 v[50:51], v[24:25], 0 op_sel_hi:[1,0]
	v_lshlrev_b32_e32 v28, 16, v29
	v_and_b32_e32 v29, 0xffff0000, v29
	v_add_f32 v28, v50, v28
	v_add_f32 v29, v51, v29
	v_lshlrev_b32_e32 v32, 16, v33
	v_and_b32_e32 v33, 0xffff0000, v33
	v_add_f32 v28, v28, v32
	v_add_f32 v29, v29, v33
	v_lshlrev_b32_e32 v32, 16, v21
	v_and_b32_e32 v33, 0xffff0000, v21
	v_add_f32 v28, v28, v32
	v_add_f32 v29, v29, v33
	v_lshlrev_b32_e32 v32, 16, v30
	v_fma_f32 v24, v48, v28, -v24
	v_fma_f32 v25, v48, v29, -v25
	v_cvt_pk_bf16_f32 v21, v24, v25
	v_lshlrev_b32_e32 v24, 16, v26
	v_and_b32_e32 v25, 0xffff0000, v26
	v_pk_add_f32 v[28:29], v[24:25], 0 op_sel_hi:[1,0]
	v_and_b32_e32 v33, 0xffff0000, v30
	v_add_f32 v28, v28, v32
	v_add_f32 v29, v29, v33
	v_lshlrev_b32_e32 v32, 16, v34
	v_and_b32_e32 v33, 0xffff0000, v34
	v_add_f32 v28, v28, v32
	v_add_f32 v29, v29, v33
	v_lshlrev_b32_e32 v32, 16, v22
	v_and_b32_e32 v33, 0xffff0000, v22
	v_add_f32 v28, v28, v32
	v_add_f32 v29, v29, v33
	v_mad_i64_i32 v[42:43], s[8:9], v42, s71, 0
	v_fma_f32 v24, v48, v28, -v24
	v_fma_f32 v25, v48, v29, -v25
	v_cvt_pk_bf16_f32 v22, v24, v25
	v_lshlrev_b32_e32 v24, 16, v27
	v_and_b32_e32 v25, 0xffff0000, v27
	v_pk_add_f32 v[26:27], v[24:25], 0 op_sel_hi:[1,0]
	v_lshlrev_b32_e32 v28, 16, v31
	v_and_b32_e32 v29, 0xffff0000, v31
	v_add_f32 v26, v26, v28
	v_add_f32 v27, v27, v29
	v_lshlrev_b32_e32 v28, 16, v35
	v_and_b32_e32 v29, 0xffff0000, v35
	v_add_f32 v26, v26, v28
	v_add_f32 v27, v27, v29
	v_lshlrev_b32_e32 v28, 16, v23
	v_and_b32_e32 v29, 0xffff0000, v23
	v_add_f32 v26, v26, v28
	v_add_f32 v27, v27, v29
	s_nop 0
	v_fma_f32 v24, v48, v26, -v24
	v_fma_f32 v25, v48, v27, -v25
	v_cvt_pk_bf16_f32 v23, v24, v25
	v_lshl_add_u64 v[24:25], s[28:29], 0, v[42:43]
	v_lshl_add_u64 v[24:25], v[40:41], 1, v[24:25]
	global_store_dwordx4 v[24:25], v[20:23], off
	s_and_saveexec_b64 s[8:9], s[16:17]
	s_cbranch_execz .LBB0_2019
	v_min_u32_e32 v20, 3, v46
	v_add_u32_e32 v20, 1, v20
	v_cvt_f32_ubyte0_e32 v20, v20
	v_div_scale_f32 v21, s[14:15], v20, v20, 1.0
	v_rcp_f32_e32 v22, v21
	v_div_scale_f32 v23, vcc, 1.0, v20, 1.0
	v_lshlrev_b32_e32 v26, 16, v8
	v_fma_f32 v24, -v21, v22, 1.0
	v_fmac_f32_e32 v22, v24, v22
	v_mul_f32_e32 v24, v23, v22
	v_fma_f32 v25, -v21, v24, v23
	v_fmac_f32_e32 v24, v25, v22
	v_fma_f32 v21, -v21, v24, v23
	v_div_fmas_f32 v21, v21, v22, v24
	v_div_fixup_f32 v24, v21, v20, 1.0
	v_lshlrev_b32_e32 v20, 16, v4
	v_and_b32_e32 v21, 0xffff0000, v4
	v_pk_add_f32 v[22:23], v[20:21], 0 op_sel_hi:[1,0]
	v_and_b32_e32 v27, 0xffff0000, v8
	v_add_f32 v22, v22, v26
	v_add_f32 v23, v23, v27
	v_lshlrev_b32_e32 v26, 16, v16
	v_and_b32_e32 v27, 0xffff0000, v16
	v_add_f32 v22, v22, v26
	v_add_f32 v23, v23, v27
	v_lshlrev_b32_e32 v26, 16, v12
	v_and_b32_e32 v27, 0xffff0000, v12
	v_add_f32 v22, v22, v26
	v_add_f32 v23, v23, v27
	v_lshlrev_b32_e32 v28, 16, v9
	v_fma_f32 v20, v24, v22, -v20
	v_fma_f32 v21, v24, v23, -v21
	v_lshlrev_b32_e32 v22, 16, v5
	v_and_b32_e32 v23, 0xffff0000, v5
	v_pk_add_f32 v[26:27], v[22:23], 0 op_sel_hi:[1,0]
	v_and_b32_e32 v29, 0xffff0000, v9
	v_add_f32 v26, v26, v28
	v_add_f32 v27, v27, v29
	v_lshlrev_b32_e32 v28, 16, v17
	v_and_b32_e32 v29, 0xffff0000, v17
	v_add_f32 v26, v26, v28
	v_add_f32 v27, v27, v29
	v_lshlrev_b32_e32 v28, 16, v13
	v_and_b32_e32 v29, 0xffff0000, v13
	v_add_f32 v26, v26, v28
	v_add_f32 v27, v27, v29
	v_cvt_pk_bf16_f32 v20, v20, v21
	v_fma_f32 v22, v24, v26, -v22
	v_fma_f32 v23, v24, v27, -v23
	v_cvt_pk_bf16_f32 v21, v22, v23
	v_lshlrev_b32_e32 v22, 16, v6
	v_and_b32_e32 v23, 0xffff0000, v6
	v_pk_add_f32 v[26:27], v[22:23], 0 op_sel_hi:[1,0]
	v_lshlrev_b32_e32 v28, 16, v10
	v_and_b32_e32 v29, 0xffff0000, v10
	v_add_f32 v26, v26, v28
	v_add_f32 v27, v27, v29
	v_lshlrev_b32_e32 v28, 16, v18
	v_and_b32_e32 v29, 0xffff0000, v18
	v_add_f32 v26, v26, v28
	v_add_f32 v27, v27, v29
	v_lshlrev_b32_e32 v28, 16, v14
	v_and_b32_e32 v29, 0xffff0000, v14
	v_add_f32 v26, v26, v28
	v_add_f32 v27, v27, v29
	v_lshlrev_b32_e32 v30, 16, v11
	v_fma_f32 v22, v24, v26, -v22
	v_fma_f32 v23, v24, v27, -v23
	v_lshlrev_b32_e32 v26, 16, v7
	v_and_b32_e32 v27, 0xffff0000, v7
	v_pk_add_f32 v[28:29], v[26:27], 0 op_sel_hi:[1,0]
	v_and_b32_e32 v31, 0xffff0000, v11
	v_add_f32 v28, v28, v30
	v_add_f32 v29, v29, v31
	v_lshlrev_b32_e32 v30, 16, v19
	v_and_b32_e32 v31, 0xffff0000, v19
	v_add_f32 v28, v28, v30
	v_add_f32 v29, v29, v31
	v_lshlrev_b32_e32 v30, 16, v15
	v_and_b32_e32 v31, 0xffff0000, v15
	v_add_f32 v28, v28, v30
	v_add_f32 v29, v29, v31
	v_cvt_pk_bf16_f32 v22, v22, v23
	v_fma_f32 v25, v24, v29, -v27
	v_fma_f32 v24, v24, v28, -v26
	v_cvt_pk_bf16_f32 v23, v24, v25
	v_mov_b64_e32 v[24:25], s[28:29]
	v_mad_i64_i32 v[24:25], s[14:15], v44, s71, v[24:25]
	v_mov_b32_e32 v39, v2
	v_lshl_add_u64 v[24:25], v[38:39], 1, v[24:25]
	global_store_dwordx4 v[24:25], v[20:23], off
	s_branch .LBB0_2019

.LBB0_2072:
	s_or_b64 exec, exec, s[8:9]
	v_min_u32_e32 v71, 7, v77
	v_add_u32_e32 v71, 1, v71
	v_cvt_f32_ubyte0_e32 v71, v71
	v_div_scale_f32 v77, s[8:9], v71, v71, 1.0
	v_rcp_f32_e32 v79, v77
	s_waitcnt vmcnt(0)
	v_lshlrev_b32_e32 v80, 16, v52
	v_and_b32_e32 v81, 0xffff0000, v52
	v_lshlrev_b32_e32 v84, 16, v56
	v_fma_f32 v88, -v77, v79, 1.0
	v_fmac_f32_e32 v79, v88, v79
	v_div_scale_f32 v88, vcc, 1.0, v71, 1.0
	v_mul_f32_e32 v89, v88, v79
	v_fma_f32 v90, -v77, v89, v88
	v_and_b32_e32 v85, 0xffff0000, v56
	v_fmac_f32_e32 v89, v90, v79
	v_pk_add_f32 v[90:91], v[80:81], 0 op_sel_hi:[1,0]
	v_fma_f32 v77, -v77, v89, v88
	v_add_f32 v84, v90, v84
	v_add_f32 v85, v91, v85
	v_lshlrev_b32_e32 v90, 16, v40
	v_and_b32_e32 v91, 0xffff0000, v40
	v_add_f32 v84, v84, v90
	v_add_f32 v85, v85, v91
	v_lshlrev_b32_e32 v90, 16, v36
	v_and_b32_e32 v91, 0xffff0000, v36
	v_add_f32 v84, v84, v90
	v_add_f32 v85, v85, v91
	v_lshlrev_b32_e32 v90, 16, v48
	v_and_b32_e32 v91, 0xffff0000, v48
	v_add_f32 v84, v84, v90
	v_add_f32 v85, v85, v91
	v_lshlrev_b32_e32 v90, 16, v44
	v_and_b32_e32 v91, 0xffff0000, v44
	v_add_f32 v84, v84, v90
	v_add_f32 v85, v85, v91
	v_lshlrev_b32_e32 v90, 16, v64
	v_and_b32_e32 v91, 0xffff0000, v64
	v_div_fmas_f32 v77, v77, v79, v89
	v_add_f32 v84, v84, v90
	v_add_f32 v85, v85, v91
	v_lshlrev_b32_e32 v90, 16, v60
	v_and_b32_e32 v91, 0xffff0000, v60
	v_div_fixup_f32 v88, v77, v71, 1.0
	v_add_f32 v84, v84, v90
	v_add_f32 v85, v85, v91
	v_lshlrev_b32_e32 v52, 16, v53
	v_and_b32_e32 v53, 0xffff0000, v53
	v_fma_f32 v80, v88, v84, -v80
	v_fma_f32 v81, v88, v85, -v81
	v_lshlrev_b32_e32 v56, 16, v57
	v_and_b32_e32 v57, 0xffff0000, v57
	v_cvt_pk_bf16_f32 v36, v80, v81
	v_pk_add_f32 v[80:81], v[52:53], 0 op_sel_hi:[1,0]
	v_lshlrev_b32_e32 v40, 16, v41
	v_add_f32 v56, v80, v56
	v_add_f32 v57, v81, v57
	v_and_b32_e32 v41, 0xffff0000, v41
	v_add_f32 v40, v56, v40
	v_add_f32 v41, v57, v41
	v_lshlrev_b32_e32 v56, 16, v37
	v_and_b32_e32 v57, 0xffff0000, v37
	v_add_f32 v40, v40, v56
	v_add_f32 v41, v41, v57
	v_lshlrev_b32_e32 v48, 16, v49
	v_and_b32_e32 v49, 0xffff0000, v49
	v_add_f32 v40, v40, v48
	v_add_f32 v41, v41, v49
	v_lshlrev_b32_e32 v44, 16, v45
	v_and_b32_e32 v45, 0xffff0000, v45
	v_add_f32 v40, v40, v44
	v_add_f32 v41, v41, v45
	v_lshlrev_b32_e32 v44, 16, v65
	v_and_b32_e32 v45, 0xffff0000, v65
	v_add_f32 v40, v40, v44
	v_add_f32 v41, v41, v45
	v_lshlrev_b32_e32 v44, 16, v61
	v_and_b32_e32 v45, 0xffff0000, v61
	v_add_f32 v40, v40, v44
	v_add_f32 v41, v41, v45
	v_lshlrev_b32_e32 v82, 16, v54
	v_and_b32_e32 v83, 0xffff0000, v54
	v_fma_f32 v40, v88, v40, -v52
	v_fma_f32 v41, v88, v41, -v53
	v_lshlrev_b32_e32 v86, 16, v58
	v_and_b32_e32 v87, 0xffff0000, v58
	v_cvt_pk_bf16_f32 v37, v40, v41
	v_pk_add_f32 v[40:41], v[82:83], 0 op_sel_hi:[1,0]
	v_lshlrev_b32_e32 v44, 16, v42
	v_add_f32 v40, v40, v86
	v_add_f32 v41, v41, v87
	v_and_b32_e32 v45, 0xffff0000, v42
	v_add_f32 v40, v40, v44
	v_add_f32 v41, v41, v45
	v_lshlrev_b32_e32 v44, 16, v38
	v_and_b32_e32 v45, 0xffff0000, v38
	v_add_f32 v40, v40, v44
	v_add_f32 v41, v41, v45
	v_lshlrev_b32_e32 v44, 16, v50
	v_and_b32_e32 v45, 0xffff0000, v50
	v_add_f32 v40, v40, v44
	v_add_f32 v41, v41, v45
	v_lshlrev_b32_e32 v44, 16, v46
	v_and_b32_e32 v45, 0xffff0000, v46
	v_add_f32 v40, v40, v44
	v_add_f32 v41, v41, v45
	v_lshlrev_b32_e32 v44, 16, v66
	v_and_b32_e32 v45, 0xffff0000, v66
	v_add_f32 v40, v40, v44
	v_add_f32 v41, v41, v45
	v_lshlrev_b32_e32 v44, 16, v62
	v_and_b32_e32 v45, 0xffff0000, v62
	v_add_f32 v40, v40, v44
	v_add_f32 v41, v41, v45
	v_lshlrev_b32_e32 v54, 16, v55
	v_and_b32_e32 v55, 0xffff0000, v55
	v_fma_f32 v40, v88, v40, -v82
	v_fma_f32 v41, v88, v41, -v83
	v_lshlrev_b32_e32 v58, 16, v59
	v_and_b32_e32 v59, 0xffff0000, v59
	v_cvt_pk_bf16_f32 v38, v40, v41
	v_pk_add_f32 v[40:41], v[54:55], 0 op_sel_hi:[1,0]
	v_lshlrev_b32_e32 v42, 16, v43
	v_add_f32 v40, v40, v58
	v_add_f32 v41, v41, v59
	v_and_b32_e32 v43, 0xffff0000, v43
	v_add_f32 v40, v40, v42
	v_add_f32 v41, v41, v43
	v_lshlrev_b32_e32 v42, 16, v39
	v_and_b32_e32 v43, 0xffff0000, v39
	v_add_f32 v40, v40, v42
	v_add_f32 v41, v41, v43
	v_lshlrev_b32_e32 v42, 16, v51
	v_and_b32_e32 v43, 0xffff0000, v51
	v_add_f32 v40, v40, v42
	v_add_f32 v41, v41, v43
	v_lshlrev_b32_e32 v42, 16, v47
	v_and_b32_e32 v43, 0xffff0000, v47
	v_add_f32 v40, v40, v42
	v_add_f32 v41, v41, v43
	v_lshlrev_b32_e32 v42, 16, v67
	v_and_b32_e32 v43, 0xffff0000, v67
	v_add_f32 v40, v40, v42
	v_add_f32 v41, v41, v43
	v_lshlrev_b32_e32 v42, 16, v63
	v_and_b32_e32 v43, 0xffff0000, v63
	v_add_f32 v40, v40, v42
	v_add_f32 v41, v41, v43
	v_mad_i64_i32 v[74:75], s[8:9], v74, s71, 0
	v_fma_f32 v40, v88, v40, -v54
	v_fma_f32 v41, v88, v41, -v55
	v_cvt_pk_bf16_f32 v39, v40, v41
	v_lshl_add_u64 v[40:41], s[28:29], 0, v[74:75]
	v_lshl_add_u64 v[40:41], v[72:73], 1, v[40:41]
	global_store_dwordx4 v[40:41], v[36:39], off
	s_and_saveexec_b64 s[8:9], s[16:17]
	s_cbranch_execz .LBB0_2039
	v_min_u32_e32 v49, 7, v78
	v_add_u32_e32 v49, 1, v49
	v_cvt_f32_ubyte0_e32 v52, v49
	v_div_scale_f32 v53, s[14:15], v52, v52, 1.0
	v_rcp_f32_e32 v54, v53
	v_lshlrev_b32_e32 v36, 16, v4
	v_and_b32_e32 v37, 0xffff0000, v4
	v_lshlrev_b32_e32 v44, 16, v8
	v_fma_f32 v55, -v53, v54, 1.0
	v_fmac_f32_e32 v54, v55, v54
	v_div_scale_f32 v55, vcc, 1.0, v52, 1.0
	v_mul_f32_e32 v56, v55, v54
	v_fma_f32 v57, -v53, v56, v55
	v_fmac_f32_e32 v56, v57, v54
	v_fma_f32 v53, -v53, v56, v55
	v_and_b32_e32 v45, 0xffff0000, v8
	v_div_fmas_f32 v53, v53, v54, v56
	v_pk_add_f32 v[54:55], v[36:37], 0 op_sel_hi:[1,0]
	v_lshlrev_b32_e32 v38, 16, v5
	v_add_f32 v44, v54, v44
	v_add_f32 v45, v55, v45
	v_lshlrev_b32_e32 v54, 16, v12
	v_and_b32_e32 v55, 0xffff0000, v12
	v_add_f32 v44, v44, v54
	v_add_f32 v45, v45, v55
	v_lshlrev_b32_e32 v54, 16, v16
	v_and_b32_e32 v55, 0xffff0000, v16
	v_add_f32 v44, v44, v54
	v_add_f32 v45, v45, v55
	v_lshlrev_b32_e32 v54, 16, v20
	v_and_b32_e32 v55, 0xffff0000, v20
	v_add_f32 v44, v44, v54
	v_add_f32 v45, v45, v55
	v_lshlrev_b32_e32 v54, 16, v24
	v_and_b32_e32 v55, 0xffff0000, v24
	v_add_f32 v44, v44, v54
	v_add_f32 v45, v45, v55
	v_lshlrev_b32_e32 v54, 16, v28
	v_and_b32_e32 v55, 0xffff0000, v28
	v_add_f32 v44, v44, v54
	v_add_f32 v45, v45, v55
	v_lshlrev_b32_e32 v54, 16, v32
	v_and_b32_e32 v55, 0xffff0000, v32
	v_and_b32_e32 v39, 0xffff0000, v5
	v_div_fixup_f32 v52, v53, v52, 1.0
	v_add_f32 v44, v44, v54
	v_add_f32 v45, v45, v55
	v_lshlrev_b32_e32 v46, 16, v9
	v_and_b32_e32 v47, 0xffff0000, v9
	v_fma_f32 v36, v52, v44, -v36
	v_fma_f32 v37, v52, v45, -v37
	v_pk_add_f32 v[44:45], v[38:39], 0 op_sel_hi:[1,0]
	v_lshlrev_b32_e32 v40, 16, v6
	v_add_f32 v44, v44, v46
	v_add_f32 v45, v45, v47
	v_lshlrev_b32_e32 v46, 16, v13
	v_and_b32_e32 v47, 0xffff0000, v13
	v_add_f32 v44, v44, v46
	v_add_f32 v45, v45, v47
	v_lshlrev_b32_e32 v46, 16, v17
	v_and_b32_e32 v47, 0xffff0000, v17
	v_add_f32 v44, v44, v46
	v_add_f32 v45, v45, v47
	v_lshlrev_b32_e32 v46, 16, v21
	v_and_b32_e32 v47, 0xffff0000, v21
	v_add_f32 v44, v44, v46
	v_add_f32 v45, v45, v47
	v_lshlrev_b32_e32 v46, 16, v25
	v_and_b32_e32 v47, 0xffff0000, v25
	v_add_f32 v44, v44, v46
	v_add_f32 v45, v45, v47
	v_lshlrev_b32_e32 v46, 16, v29
	v_and_b32_e32 v47, 0xffff0000, v29
	v_add_f32 v44, v44, v46
	v_add_f32 v45, v45, v47
	v_lshlrev_b32_e32 v46, 16, v33
	v_and_b32_e32 v47, 0xffff0000, v33
	v_add_f32 v44, v44, v46
	v_add_f32 v45, v45, v47
	v_and_b32_e32 v41, 0xffff0000, v6
	v_fma_f32 v38, v52, v44, -v38
	v_fma_f32 v39, v52, v45, -v39
	v_lshlrev_b32_e32 v48, 16, v10
	v_and_b32_e32 v49, 0xffff0000, v10
	v_cvt_pk_bf16_f32 v36, v36, v37
	v_cvt_pk_bf16_f32 v37, v38, v39
	v_pk_add_f32 v[38:39], v[40:41], 0 op_sel_hi:[1,0]
	v_lshlrev_b32_e32 v44, 16, v14
	v_add_f32 v38, v38, v48
	v_add_f32 v39, v39, v49
	v_and_b32_e32 v45, 0xffff0000, v14
	v_add_f32 v38, v38, v44
	v_add_f32 v39, v39, v45
	v_lshlrev_b32_e32 v44, 16, v18
	v_and_b32_e32 v45, 0xffff0000, v18
	v_add_f32 v38, v38, v44
	v_add_f32 v39, v39, v45
	v_lshlrev_b32_e32 v44, 16, v22
	v_and_b32_e32 v45, 0xffff0000, v22
	v_add_f32 v38, v38, v44
	v_add_f32 v39, v39, v45
	v_lshlrev_b32_e32 v44, 16, v26
	v_and_b32_e32 v45, 0xffff0000, v26
	v_add_f32 v38, v38, v44
	v_add_f32 v39, v39, v45
	v_lshlrev_b32_e32 v44, 16, v30
	v_and_b32_e32 v45, 0xffff0000, v30
	v_add_f32 v38, v38, v44
	v_add_f32 v39, v39, v45
	v_lshlrev_b32_e32 v44, 16, v34
	v_and_b32_e32 v45, 0xffff0000, v34
	v_lshlrev_b32_e32 v42, 16, v7
	v_and_b32_e32 v43, 0xffff0000, v7
	v_add_f32 v38, v38, v44
	v_add_f32 v39, v39, v45
	v_lshlrev_b32_e32 v50, 16, v11
	v_and_b32_e32 v51, 0xffff0000, v11
	v_fma_f32 v38, v52, v38, -v40
	v_fma_f32 v39, v52, v39, -v41
	v_pk_add_f32 v[40:41], v[42:43], 0 op_sel_hi:[1,0]
	v_lshlrev_b32_e32 v44, 16, v15
	v_add_f32 v40, v40, v50
	v_add_f32 v41, v41, v51
	v_and_b32_e32 v45, 0xffff0000, v15
	v_add_f32 v40, v40, v44
	v_add_f32 v41, v41, v45
	v_lshlrev_b32_e32 v44, 16, v19
	v_and_b32_e32 v45, 0xffff0000, v19
	v_add_f32 v40, v40, v44
	v_add_f32 v41, v41, v45
	v_lshlrev_b32_e32 v44, 16, v23
	v_and_b32_e32 v45, 0xffff0000, v23
	v_add_f32 v40, v40, v44
	v_add_f32 v41, v41, v45
	v_lshlrev_b32_e32 v44, 16, v27
	v_and_b32_e32 v45, 0xffff0000, v27
	v_add_f32 v40, v40, v44
	v_add_f32 v41, v41, v45
	v_lshlrev_b32_e32 v44, 16, v31
	v_and_b32_e32 v45, 0xffff0000, v31
	v_add_f32 v40, v40, v44
	v_add_f32 v41, v41, v45
	v_lshlrev_b32_e32 v44, 16, v35
	v_and_b32_e32 v45, 0xffff0000, v35
	v_add_f32 v40, v40, v44
	v_add_f32 v41, v41, v45
	v_cvt_pk_bf16_f32 v38, v38, v39
	v_fma_f32 v40, v52, v40, -v42
	v_fma_f32 v41, v52, v41, -v43
	v_cvt_pk_bf16_f32 v39, v40, v41
	v_mov_b64_e32 v[40:41], s[28:29]
	v_mad_i64_i32 v[40:41], s[14:15], v76, s71, v[40:41]
	v_mov_b32_e32 v71, v2
	v_lshl_add_u64 v[40:41], v[70:71], 1, v[40:41]
	global_store_dwordx4 v[40:41], v[36:39], off
	s_branch .LBB0_2039

.LBB0_2140:
	s_or_b64 exec, exec, s[0:1]
	s_waitcnt vmcnt(0)
	v_lshlrev_b32_e32 v148, 16, v120
	v_and_b32_e32 v149, 0xffff0000, v120
	v_min_u32_e32 v120, 15, v140
	v_add_u32_e32 v120, 1, v120
	v_cvt_f32_ubyte0_e32 v120, v120
	v_lshlrev_b32_e32 v150, 16, v121
	v_and_b32_e32 v151, 0xffff0000, v121
	v_div_scale_f32 v121, s[0:1], v120, v120, 1.0
	v_mad_i64_i32 v[138:139], s[0:1], v133, s71, 0
	v_rcp_f32_e32 v133, v121
	v_lshlrev_b32_e32 v156, 16, v130
	v_and_b32_e32 v157, 0xffff0000, v130
	v_lshlrev_b32_e32 v142, 16, v124
	v_fma_f32 v130, -v121, v133, 1.0
	v_fmac_f32_e32 v133, v130, v133
	v_div_scale_f32 v130, vcc, 1.0, v120, 1.0
	v_and_b32_e32 v143, 0xffff0000, v124
	v_lshlrev_b32_e32 v144, 16, v125
	v_and_b32_e32 v145, 0xffff0000, v125
	v_lshlrev_b32_e32 v146, 16, v126
	v_and_b32_e32 v147, 0xffff0000, v126
	v_lshlrev_b32_e32 v124, 16, v127
	v_and_b32_e32 v125, 0xffff0000, v127
	v_lshlrev_b32_e32 v126, 16, v131
	v_and_b32_e32 v127, 0xffff0000, v131
	v_mul_f32_e32 v131, v130, v133
	v_fma_f32 v135, -v121, v131, v130
	v_fmac_f32_e32 v131, v135, v133
	v_fma_f32 v121, -v121, v131, v130
	v_div_fmas_f32 v121, v121, v133, v131
	v_lshlrev_b32_e32 v130, 16, v72
	v_and_b32_e32 v131, 0xffff0000, v72
	v_lshlrev_b32_e32 v158, 16, v76
	v_and_b32_e32 v159, 0xffff0000, v76
	v_pk_add_f32 v[170:171], v[130:131], 0 op_sel_hi:[1,0]
	v_lshlrev_b32_e32 v160, 16, v68
	v_and_b32_e32 v161, 0xffff0000, v68
	v_add_f32 v158, v170, v158
	v_add_f32 v159, v171, v159
	v_lshlrev_b32_e32 v162, 16, v84
	v_and_b32_e32 v163, 0xffff0000, v84
	v_add_f32 v158, v158, v160
	v_add_f32 v159, v159, v161
	v_lshlrev_b32_e32 v164, 16, v80
	v_and_b32_e32 v165, 0xffff0000, v80
	v_add_f32 v158, v158, v162
	v_add_f32 v159, v159, v163
	v_lshlrev_b32_e32 v166, 16, v92
	v_and_b32_e32 v167, 0xffff0000, v92
	v_add_f32 v158, v158, v164
	v_add_f32 v159, v159, v165
	v_lshlrev_b32_e32 v168, 16, v88
	v_and_b32_e32 v169, 0xffff0000, v88
	v_add_f32 v158, v158, v166
	v_add_f32 v159, v159, v167
	v_lshlrev_b32_e32 v154, 16, v128
	v_add_f32 v158, v158, v168
	v_add_f32 v159, v159, v169
	v_and_b32_e32 v155, 0xffff0000, v128
	v_add_f32 v142, v158, v142
	v_add_f32 v143, v159, v143
	v_div_fixup_f32 v120, v121, v120, 1.0
	v_add_f32 v142, v142, v148
	v_add_f32 v143, v143, v149
	v_lshlrev_b32_e32 v148, 16, v96
	v_add_f32 v142, v142, v154
	v_add_f32 v143, v143, v155
	v_and_b32_e32 v149, 0xffff0000, v96
	v_add_f32 v142, v142, v148
	v_add_f32 v143, v143, v149
	v_lshlrev_b32_e32 v148, 16, v104
	v_and_b32_e32 v149, 0xffff0000, v104
	v_add_f32 v142, v142, v148
	v_add_f32 v143, v143, v149
	v_lshlrev_b32_e32 v148, 16, v100
	v_and_b32_e32 v149, 0xffff0000, v100
	v_add_f32 v142, v142, v148
	v_add_f32 v143, v143, v149
	v_lshlrev_b32_e32 v148, 16, v112
	v_and_b32_e32 v149, 0xffff0000, v112
	v_add_f32 v142, v142, v148
	v_add_f32 v143, v143, v149
	v_lshlrev_b32_e32 v148, 16, v108
	v_and_b32_e32 v149, 0xffff0000, v108
	v_add_f32 v142, v142, v148
	v_add_f32 v143, v143, v149
	v_lshlrev_b32_e32 v148, 16, v116
	v_and_b32_e32 v149, 0xffff0000, v116
	v_add_f32 v142, v142, v148
	v_add_f32 v143, v143, v149
	v_lshlrev_b32_e32 v72, 16, v73
	v_and_b32_e32 v73, 0xffff0000, v73
	v_fma_f32 v130, v120, v142, -v130
	v_fma_f32 v131, v120, v143, -v131
	v_lshlrev_b32_e32 v76, 16, v77
	v_and_b32_e32 v77, 0xffff0000, v77
	v_pk_add_f32 v[142:143], v[72:73], 0 op_sel_hi:[1,0]
	v_cvt_pk_bf16_f32 v68, v130, v131
	v_lshlrev_b32_e32 v130, 16, v69
	v_and_b32_e32 v131, 0xffff0000, v69
	v_add_f32 v76, v142, v76
	v_add_f32 v77, v143, v77
	v_lshlrev_b32_e32 v84, 16, v85
	v_and_b32_e32 v85, 0xffff0000, v85
	v_add_f32 v76, v76, v130
	v_add_f32 v77, v77, v131
	v_lshlrev_b32_e32 v80, 16, v81
	v_and_b32_e32 v81, 0xffff0000, v81
	v_add_f32 v76, v76, v84
	v_add_f32 v77, v77, v85
	v_lshlrev_b32_e32 v92, 16, v93
	v_and_b32_e32 v93, 0xffff0000, v93
	v_add_f32 v76, v76, v80
	v_add_f32 v77, v77, v81
	v_lshlrev_b32_e32 v88, 16, v89
	v_and_b32_e32 v89, 0xffff0000, v89
	v_add_f32 v76, v76, v92
	v_add_f32 v77, v77, v93
	v_lshlrev_b32_e32 v128, 16, v129
	v_add_f32 v76, v76, v88
	v_add_f32 v77, v77, v89
	v_and_b32_e32 v129, 0xffff0000, v129
	v_add_f32 v76, v76, v144
	v_add_f32 v77, v77, v145
	v_lshlrev_b32_e32 v80, 16, v97
	v_add_f32 v76, v76, v150
	v_add_f32 v77, v77, v151
	v_and_b32_e32 v81, 0xffff0000, v97
	v_add_f32 v76, v76, v128
	v_add_f32 v77, v77, v129
	v_lshlrev_b32_e32 v84, 16, v86
	v_add_f32 v76, v76, v80
	v_add_f32 v77, v77, v81
	v_lshlrev_b32_e32 v80, 16, v105
	v_and_b32_e32 v81, 0xffff0000, v105
	v_add_f32 v76, v76, v80
	v_add_f32 v77, v77, v81
	v_lshlrev_b32_e32 v80, 16, v101
	v_and_b32_e32 v81, 0xffff0000, v101
	v_add_f32 v76, v76, v80
	v_add_f32 v77, v77, v81
	v_lshlrev_b32_e32 v80, 16, v113
	v_and_b32_e32 v81, 0xffff0000, v113
	v_add_f32 v76, v76, v80
	v_add_f32 v77, v77, v81
	v_lshlrev_b32_e32 v80, 16, v109
	v_and_b32_e32 v81, 0xffff0000, v109
	v_add_f32 v76, v76, v80
	v_add_f32 v77, v77, v81
	v_lshlrev_b32_e32 v80, 16, v117
	v_and_b32_e32 v81, 0xffff0000, v117
	v_add_f32 v76, v76, v80
	v_add_f32 v77, v77, v81
	v_lshlrev_b32_e32 v80, 16, v70
	v_fma_f32 v72, v120, v76, -v72
	v_fma_f32 v73, v120, v77, -v73
	v_cvt_pk_bf16_f32 v69, v72, v73
	v_lshlrev_b32_e32 v72, 16, v74
	v_and_b32_e32 v73, 0xffff0000, v74
	v_lshlrev_b32_e32 v76, 16, v78
	v_and_b32_e32 v77, 0xffff0000, v78
	v_pk_add_f32 v[100:101], v[72:73], 0 op_sel_hi:[1,0]
	v_and_b32_e32 v81, 0xffff0000, v70
	v_add_f32 v76, v100, v76
	v_add_f32 v77, v101, v77
	v_and_b32_e32 v85, 0xffff0000, v86
	v_add_f32 v76, v76, v80
	v_add_f32 v77, v77, v81
	v_lshlrev_b32_e32 v88, 16, v82
	v_and_b32_e32 v89, 0xffff0000, v82
	v_add_f32 v76, v76, v84
	v_add_f32 v77, v77, v85
	v_lshlrev_b32_e32 v92, 16, v94
	v_and_b32_e32 v93, 0xffff0000, v94
	v_add_f32 v76, v76, v88
	v_add_f32 v77, v77, v89
	v_lshlrev_b32_e32 v96, 16, v90
	v_and_b32_e32 v97, 0xffff0000, v90
	v_add_f32 v76, v76, v92
	v_add_f32 v77, v77, v93
	v_lshlrev_b32_e32 v152, 16, v122
	v_add_f32 v76, v76, v96
	v_add_f32 v77, v77, v97
	v_and_b32_e32 v153, 0xffff0000, v122
	v_add_f32 v76, v76, v146
	v_add_f32 v77, v77, v147
	v_lshlrev_b32_e32 v80, 16, v98
	v_add_f32 v76, v76, v152
	v_add_f32 v77, v77, v153
	v_and_b32_e32 v81, 0xffff0000, v98
	v_add_f32 v76, v76, v156
	v_add_f32 v77, v77, v157
	v_lshlrev_b32_e32 v74, 16, v79
	v_add_f32 v76, v76, v80
	v_add_f32 v77, v77, v81
	v_lshlrev_b32_e32 v80, 16, v106
	v_and_b32_e32 v81, 0xffff0000, v106
	v_add_f32 v76, v76, v80
	v_add_f32 v77, v77, v81
	v_lshlrev_b32_e32 v80, 16, v102
	v_and_b32_e32 v81, 0xffff0000, v102
	v_add_f32 v76, v76, v80
	v_add_f32 v77, v77, v81
	v_lshlrev_b32_e32 v80, 16, v114
	v_and_b32_e32 v81, 0xffff0000, v114
	v_add_f32 v76, v76, v80
	v_add_f32 v77, v77, v81
	v_lshlrev_b32_e32 v80, 16, v110
	v_and_b32_e32 v81, 0xffff0000, v110
	v_add_f32 v76, v76, v80
	v_add_f32 v77, v77, v81
	v_lshlrev_b32_e32 v80, 16, v118
	v_and_b32_e32 v81, 0xffff0000, v118
	v_add_f32 v76, v76, v80
	v_add_f32 v77, v77, v81
	v_lshlrev_b32_e32 v78, 16, v87
	v_fma_f32 v72, v120, v76, -v72
	v_fma_f32 v73, v120, v77, -v73
	v_cvt_pk_bf16_f32 v70, v72, v73
	v_lshlrev_b32_e32 v72, 16, v75
	v_and_b32_e32 v73, 0xffff0000, v75
	v_and_b32_e32 v75, 0xffff0000, v79
	v_and_b32_e32 v79, 0xffff0000, v87
	v_pk_add_f32 v[86:87], v[72:73], 0 op_sel_hi:[1,0]
	v_lshlrev_b32_e32 v76, 16, v71
	v_and_b32_e32 v77, 0xffff0000, v71
	v_add_f32 v74, v86, v74
	v_add_f32 v75, v87, v75
	v_lshlrev_b32_e32 v80, 16, v83
	v_add_f32 v74, v74, v76
	v_add_f32 v75, v75, v77
	v_and_b32_e32 v81, 0xffff0000, v83
	v_add_f32 v74, v74, v78
	v_add_f32 v75, v75, v79
	v_lshlrev_b32_e32 v82, 16, v95
	v_and_b32_e32 v83, 0xffff0000, v95
	v_add_f32 v74, v74, v80
	v_add_f32 v75, v75, v81
	v_lshlrev_b32_e32 v84, 16, v91
	v_and_b32_e32 v85, 0xffff0000, v91
	v_add_f32 v74, v74, v82
	v_add_f32 v75, v75, v83
	v_lshlrev_b32_e32 v122, 16, v123
	v_add_f32 v74, v74, v84
	v_add_f32 v75, v75, v85
	v_and_b32_e32 v123, 0xffff0000, v123
	v_add_f32 v74, v74, v124
	v_add_f32 v75, v75, v125
	v_lshlrev_b32_e32 v76, 16, v99
	v_add_f32 v74, v74, v122
	v_add_f32 v75, v75, v123
	v_and_b32_e32 v77, 0xffff0000, v99
	v_add_f32 v74, v74, v126
	v_add_f32 v75, v75, v127
	s_nop 0
	v_add_f32 v74, v74, v76
	v_add_f32 v75, v75, v77
	v_lshlrev_b32_e32 v76, 16, v107
	v_and_b32_e32 v77, 0xffff0000, v107
	v_add_f32 v74, v74, v76
	v_add_f32 v75, v75, v77
	v_lshlrev_b32_e32 v76, 16, v103
	v_and_b32_e32 v77, 0xffff0000, v103
	v_add_f32 v74, v74, v76
	v_add_f32 v75, v75, v77
	v_lshlrev_b32_e32 v76, 16, v115
	v_and_b32_e32 v77, 0xffff0000, v115
	v_add_f32 v74, v74, v76
	v_add_f32 v75, v75, v77
	v_lshlrev_b32_e32 v76, 16, v111
	v_and_b32_e32 v77, 0xffff0000, v111
	v_add_f32 v74, v74, v76
	v_add_f32 v75, v75, v77
	v_lshlrev_b32_e32 v76, 16, v119
	v_and_b32_e32 v77, 0xffff0000, v119
	v_add_f32 v74, v74, v76
	v_add_f32 v75, v75, v77
	s_nop 0
	v_fma_f32 v72, v120, v74, -v72
	v_fma_f32 v73, v120, v75, -v73
	v_cvt_pk_bf16_f32 v71, v72, v73
	v_lshl_add_u64 v[72:73], s[28:29], 0, v[138:139]
	v_lshl_add_u64 v[72:73], v[136:137], 1, v[72:73]
	global_store_dwordx4 v[72:73], v[68:71], off
	s_and_saveexec_b64 s[0:1], s[16:17]
	s_cbranch_execz .LBB0_2075
	v_min_u32_e32 v68, 15, v141
	v_add_u32_e32 v68, 1, v68
	v_cvt_f32_ubyte0_e32 v68, v68
	v_div_scale_f32 v69, s[14:15], v68, v68, 1.0
	v_rcp_f32_e32 v94, v69
	v_lshlrev_b32_e32 v98, 16, v12
	v_and_b32_e32 v99, 0xffff0000, v12
	v_lshlrev_b32_e32 v100, 16, v16
	v_fma_f32 v95, -v69, v94, 1.0
	v_fmac_f32_e32 v94, v95, v94
	v_div_scale_f32 v95, vcc, 1.0, v68, 1.0
	v_mul_f32_e32 v96, v95, v94
	v_fma_f32 v97, -v69, v96, v95
	v_fmac_f32_e32 v96, v97, v94
	v_fma_f32 v69, -v69, v96, v95
	v_div_fmas_f32 v69, v69, v94, v96
	v_lshlrev_b32_e32 v94, 16, v4
	v_and_b32_e32 v95, 0xffff0000, v4
	v_lshlrev_b32_e32 v96, 16, v8
	v_and_b32_e32 v97, 0xffff0000, v8
	v_pk_add_f32 v[108:109], v[94:95], 0 op_sel_hi:[1,0]
	v_and_b32_e32 v101, 0xffff0000, v16
	v_add_f32 v96, v108, v96
	v_add_f32 v97, v109, v97
	v_lshlrev_b32_e32 v102, 16, v20
	v_add_f32 v96, v96, v98
	v_add_f32 v97, v97, v99
	v_and_b32_e32 v103, 0xffff0000, v20
	v_add_f32 v96, v96, v100
	v_add_f32 v97, v97, v101
	v_lshlrev_b32_e32 v104, 16, v24
	v_and_b32_e32 v105, 0xffff0000, v24
	v_add_f32 v96, v96, v102
	v_add_f32 v97, v97, v103
	v_lshlrev_b32_e32 v106, 16, v28
	v_and_b32_e32 v107, 0xffff0000, v28
	v_add_f32 v96, v96, v104
	v_add_f32 v97, v97, v105
	v_lshlrev_b32_e32 v76, 16, v32
	v_and_b32_e32 v77, 0xffff0000, v32
	v_add_f32 v96, v96, v106
	v_add_f32 v97, v97, v107
	v_lshlrev_b32_e32 v82, 16, v36
	v_and_b32_e32 v83, 0xffff0000, v36
	v_add_f32 v76, v96, v76
	v_add_f32 v77, v97, v77
	v_lshlrev_b32_e32 v88, 16, v40
	v_and_b32_e32 v89, 0xffff0000, v40
	v_add_f32 v76, v76, v82
	v_add_f32 v77, v77, v83
	v_lshlrev_b32_e32 v82, 16, v44
	v_add_f32 v76, v76, v88
	v_add_f32 v77, v77, v89
	v_and_b32_e32 v83, 0xffff0000, v44
	v_add_f32 v76, v76, v82
	v_add_f32 v77, v77, v83
	v_lshlrev_b32_e32 v82, 16, v48
	v_and_b32_e32 v83, 0xffff0000, v48
	v_add_f32 v76, v76, v82
	v_add_f32 v77, v77, v83
	v_lshlrev_b32_e32 v82, 16, v52
	v_and_b32_e32 v83, 0xffff0000, v52
	v_add_f32 v76, v76, v82
	v_add_f32 v77, v77, v83
	v_lshlrev_b32_e32 v82, 16, v56
	v_and_b32_e32 v83, 0xffff0000, v56
	v_add_f32 v76, v76, v82
	v_add_f32 v77, v77, v83
	v_lshlrev_b32_e32 v82, 16, v60
	v_and_b32_e32 v83, 0xffff0000, v60
	v_add_f32 v76, v76, v82
	v_add_f32 v77, v77, v83
	v_lshlrev_b32_e32 v82, 16, v64
	v_and_b32_e32 v83, 0xffff0000, v64
	v_add_f32 v76, v76, v82
	v_add_f32 v77, v77, v83
	v_lshlrev_b32_e32 v82, 16, v5
	v_and_b32_e32 v83, 0xffff0000, v5
	v_div_fixup_f32 v68, v69, v68, 1.0
	v_lshlrev_b32_e32 v88, 16, v9
	v_and_b32_e32 v89, 0xffff0000, v9
	v_pk_add_f32 v[104:105], v[82:83], 0 op_sel_hi:[1,0]
	v_fma_f32 v76, v68, v76, -v94
	v_fma_f32 v77, v68, v77, -v95
	v_lshlrev_b32_e32 v94, 16, v13
	v_and_b32_e32 v95, 0xffff0000, v13
	v_add_f32 v88, v104, v88
	v_add_f32 v89, v105, v89
	v_lshlrev_b32_e32 v96, 16, v17
	v_and_b32_e32 v97, 0xffff0000, v17
	v_add_f32 v88, v88, v94
	v_add_f32 v89, v89, v95
	v_lshlrev_b32_e32 v98, 16, v21
	v_and_b32_e32 v99, 0xffff0000, v21
	v_add_f32 v88, v88, v96
	v_add_f32 v89, v89, v97
	v_lshlrev_b32_e32 v100, 16, v25
	v_and_b32_e32 v101, 0xffff0000, v25
	v_add_f32 v88, v88, v98
	v_add_f32 v89, v89, v99
	v_lshlrev_b32_e32 v102, 16, v29
	v_and_b32_e32 v103, 0xffff0000, v29
	v_add_f32 v88, v88, v100
	v_add_f32 v89, v89, v101
	v_lshlrev_b32_e32 v78, 16, v33
	v_and_b32_e32 v79, 0xffff0000, v33
	v_add_f32 v88, v88, v102
	v_add_f32 v89, v89, v103
	v_lshlrev_b32_e32 v84, 16, v37
	v_and_b32_e32 v85, 0xffff0000, v37
	v_add_f32 v78, v88, v78
	v_add_f32 v79, v89, v79
	v_lshlrev_b32_e32 v90, 16, v41
	v_and_b32_e32 v91, 0xffff0000, v41
	v_add_f32 v78, v78, v84
	v_add_f32 v79, v79, v85
	v_lshlrev_b32_e32 v84, 16, v45
	v_add_f32 v78, v78, v90
	v_add_f32 v79, v79, v91
	v_and_b32_e32 v85, 0xffff0000, v45
	v_add_f32 v78, v78, v84
	v_add_f32 v79, v79, v85
	v_lshlrev_b32_e32 v84, 16, v49
	v_and_b32_e32 v85, 0xffff0000, v49
	v_add_f32 v78, v78, v84
	v_add_f32 v79, v79, v85
	v_lshlrev_b32_e32 v84, 16, v53
	v_and_b32_e32 v85, 0xffff0000, v53
	v_add_f32 v78, v78, v84
	v_add_f32 v79, v79, v85
	v_lshlrev_b32_e32 v84, 16, v57
	v_and_b32_e32 v85, 0xffff0000, v57
	v_add_f32 v78, v78, v84
	v_add_f32 v79, v79, v85
	v_lshlrev_b32_e32 v84, 16, v61
	v_and_b32_e32 v85, 0xffff0000, v61
	v_add_f32 v78, v78, v84
	v_add_f32 v79, v79, v85
	v_lshlrev_b32_e32 v84, 16, v65
	v_and_b32_e32 v85, 0xffff0000, v65
	v_add_f32 v78, v78, v84
	v_add_f32 v79, v79, v85
	v_cvt_pk_bf16_f32 v76, v76, v77
	v_fma_f32 v78, v68, v78, -v82
	v_fma_f32 v79, v68, v79, -v83
	v_cvt_pk_bf16_f32 v77, v78, v79
	v_lshlrev_b32_e32 v78, 16, v6
	v_and_b32_e32 v79, 0xffff0000, v6
	v_lshlrev_b32_e32 v82, 16, v10
	v_and_b32_e32 v83, 0xffff0000, v10
	v_pk_add_f32 v[98:99], v[78:79], 0 op_sel_hi:[1,0]
	v_lshlrev_b32_e32 v84, 16, v14
	v_and_b32_e32 v85, 0xffff0000, v14
	v_add_f32 v82, v98, v82
	v_add_f32 v83, v99, v83
	v_lshlrev_b32_e32 v88, 16, v18
	v_and_b32_e32 v89, 0xffff0000, v18
	v_add_f32 v82, v82, v84
	v_add_f32 v83, v83, v85
	v_lshlrev_b32_e32 v90, 16, v22
	v_and_b32_e32 v91, 0xffff0000, v22
	v_add_f32 v82, v82, v88
	v_add_f32 v83, v83, v89
	v_lshlrev_b32_e32 v94, 16, v26
	v_and_b32_e32 v95, 0xffff0000, v26
	v_add_f32 v82, v82, v90
	v_add_f32 v83, v83, v91
	v_lshlrev_b32_e32 v96, 16, v30
	v_and_b32_e32 v97, 0xffff0000, v30
	v_add_f32 v82, v82, v94
	v_add_f32 v83, v83, v95
	v_lshlrev_b32_e32 v80, 16, v34
	v_and_b32_e32 v81, 0xffff0000, v34
	v_add_f32 v82, v82, v96
	v_add_f32 v83, v83, v97
	v_lshlrev_b32_e32 v86, 16, v38
	v_and_b32_e32 v87, 0xffff0000, v38
	v_add_f32 v80, v82, v80
	v_add_f32 v81, v83, v81
	v_lshlrev_b32_e32 v92, 16, v42
	v_and_b32_e32 v93, 0xffff0000, v42
	v_add_f32 v80, v80, v86
	v_add_f32 v81, v81, v87
	v_lshlrev_b32_e32 v82, 16, v46
	v_add_f32 v80, v80, v92
	v_add_f32 v81, v81, v93
	v_and_b32_e32 v83, 0xffff0000, v46
	v_add_f32 v80, v80, v82
	v_add_f32 v81, v81, v83
	v_lshlrev_b32_e32 v82, 16, v50
	v_and_b32_e32 v83, 0xffff0000, v50
	v_add_f32 v80, v80, v82
	v_add_f32 v81, v81, v83
	v_lshlrev_b32_e32 v82, 16, v54
	v_and_b32_e32 v83, 0xffff0000, v54
	v_add_f32 v80, v80, v82
	v_add_f32 v81, v81, v83
	v_lshlrev_b32_e32 v82, 16, v58
	v_and_b32_e32 v83, 0xffff0000, v58
	v_add_f32 v80, v80, v82
	v_add_f32 v81, v81, v83
	v_lshlrev_b32_e32 v82, 16, v62
	v_and_b32_e32 v83, 0xffff0000, v62
	v_add_f32 v80, v80, v82
	v_add_f32 v81, v81, v83
	v_lshlrev_b32_e32 v82, 16, v66
	v_and_b32_e32 v83, 0xffff0000, v66
	v_add_f32 v80, v80, v82
	v_add_f32 v81, v81, v83
	v_lshlrev_b32_e32 v82, 16, v11
	v_fma_f32 v78, v68, v80, -v78
	v_fma_f32 v79, v68, v81, -v79
	v_lshlrev_b32_e32 v80, 16, v7
	v_and_b32_e32 v81, 0xffff0000, v7
	v_and_b32_e32 v83, 0xffff0000, v11
	v_pk_add_f32 v[94:95], v[80:81], 0 op_sel_hi:[1,0]
	v_lshlrev_b32_e32 v84, 16, v15
	v_and_b32_e32 v85, 0xffff0000, v15
	v_add_f32 v82, v94, v82
	v_add_f32 v83, v95, v83
	v_lshlrev_b32_e32 v86, 16, v19
	v_and_b32_e32 v87, 0xffff0000, v19
	v_add_f32 v82, v82, v84
	v_add_f32 v83, v83, v85
	v_lshlrev_b32_e32 v88, 16, v23
	v_and_b32_e32 v89, 0xffff0000, v23
	v_add_f32 v82, v82, v86
	v_add_f32 v83, v83, v87
	v_lshlrev_b32_e32 v90, 16, v27
	v_and_b32_e32 v91, 0xffff0000, v27
	v_add_f32 v82, v82, v88
	v_add_f32 v83, v83, v89
	v_lshlrev_b32_e32 v92, 16, v31
	v_and_b32_e32 v93, 0xffff0000, v31
	v_add_f32 v82, v82, v90
	v_add_f32 v83, v83, v91
	v_lshlrev_b32_e32 v70, 16, v35
	v_and_b32_e32 v71, 0xffff0000, v35
	v_add_f32 v82, v82, v92
	v_add_f32 v83, v83, v93
	v_lshlrev_b32_e32 v72, 16, v39
	v_and_b32_e32 v73, 0xffff0000, v39
	v_add_f32 v70, v82, v70
	v_add_f32 v71, v83, v71
	v_lshlrev_b32_e32 v74, 16, v43
	v_and_b32_e32 v75, 0xffff0000, v43
	v_add_f32 v70, v70, v72
	v_add_f32 v71, v71, v73
	v_lshlrev_b32_e32 v72, 16, v47
	v_add_f32 v70, v70, v74
	v_add_f32 v71, v71, v75
	v_and_b32_e32 v73, 0xffff0000, v47
	v_add_f32 v70, v70, v72
	v_add_f32 v71, v71, v73
	v_lshlrev_b32_e32 v72, 16, v51
	v_and_b32_e32 v73, 0xffff0000, v51
	v_add_f32 v70, v70, v72
	v_add_f32 v71, v71, v73
	v_lshlrev_b32_e32 v72, 16, v55
	v_and_b32_e32 v73, 0xffff0000, v55
	v_add_f32 v70, v70, v72
	v_add_f32 v71, v71, v73
	v_lshlrev_b32_e32 v72, 16, v59
	v_and_b32_e32 v73, 0xffff0000, v59
	v_add_f32 v70, v70, v72
	v_add_f32 v71, v71, v73
	v_lshlrev_b32_e32 v72, 16, v63
	v_and_b32_e32 v73, 0xffff0000, v63
	v_add_f32 v70, v70, v72
	v_add_f32 v71, v71, v73
	v_lshlrev_b32_e32 v72, 16, v67
	v_and_b32_e32 v73, 0xffff0000, v67
	v_add_f32 v70, v70, v72
	v_add_f32 v71, v71, v73
	v_cvt_pk_bf16_f32 v78, v78, v79
	v_fma_f32 v69, v68, v71, -v81
	v_fma_f32 v68, v68, v70, -v80
	v_cvt_pk_bf16_f32 v79, v68, v69
	v_mov_b64_e32 v[68:69], s[28:29]
	v_mad_i64_i32 v[68:69], s[14:15], v3, s71, v[68:69]
	v_mov_b32_e32 v135, v2
	v_lshl_add_u64 v[68:69], v[134:135], 1, v[68:69]
	global_store_dwordx4 v[68:69], v[76:79], off
	s_branch .LBB0_2075

.LBB0_2198:
	s_and_saveexec_b64 s[8:9], s[26:27]
	s_cbranch_execz .LBB0_2145
	s_waitcnt vmcnt(13) lgkmcnt(0)
	v_add_f32_e32 v3, v3, v36
	v_div_scale_f32 v36, s[14:15], v3, v3, 1.0
	v_rcp_f32_e32 v37, v36
	v_div_scale_f32 v38, vcc, 1.0, v3, 1.0
	s_waitcnt vmcnt(12)
	v_mov_b32_e32 v41, v2
	v_fma_f32 v39, -v36, v37, 1.0
	v_fmac_f32_e32 v37, v39, v37
	v_mul_f32_e32 v39, v38, v37
	v_fma_f32 v40, -v36, v39, v38
	v_fmac_f32_e32 v39, v40, v37
	v_fma_f32 v36, -v36, v39, v38
	v_div_fmas_f32 v36, v36, v37, v39
	v_div_fixup_f32 v36, v36, v3, 1.0
	s_waitcnt vmcnt(7)
	v_lshlrev_b64 v[38:39], 11, v[132:133]
	v_lshl_add_u64 v[38:39], s[0:1], 0, v[38:39]
	v_lshlrev_b32_e32 v40, 3, v1
	v_mul_f32 v20, v36, v20
	v_mul_f32 v21, v36, v21
	v_mul_f32 v22, v36, v22
	v_mul_f32 v23, v36, v23
	v_mul_f32 v4, v36, v4
	v_mul_f32 v5, v36, v5
	v_mul_f32 v6, v36, v6
	v_mul_f32 v7, v36, v7
	v_lshl_add_u64 v[38:39], v[38:39], 0, v[40:41]
	v_cvt_pk_bf16_f32 v20, v20, v21
	v_cvt_pk_bf16_f32 v21, v22, v23
	v_cvt_pk_bf16_f32 v4, v4, v5
	v_cvt_pk_bf16_f32 v5, v6, v7
	global_store_dwordx2 v[38:39], v[20:21], off
	v_mul_f32 v20, v36, v24
	v_mul_f32 v21, v36, v25
	v_mul_f32 v22, v36, v26
	v_mul_f32 v23, v36, v27
	global_store_dwordx2 v[38:39], v[4:5], off offset:64
	v_mul_f32 v4, v36, v8
	v_mul_f32 v5, v36, v9
	v_mul_f32 v6, v36, v10
	v_mul_f32 v7, v36, v11
	v_cvt_pk_bf16_f32 v20, v20, v21
	v_cvt_pk_bf16_f32 v21, v22, v23
	v_cvt_pk_bf16_f32 v4, v4, v5
	v_cvt_pk_bf16_f32 v5, v6, v7
	global_store_dwordx2 v[38:39], v[20:21], off offset:16
	v_mul_f32 v20, v36, v28
	v_mul_f32 v21, v36, v29
	v_mul_f32 v22, v36, v30
	v_mul_f32 v23, v36, v31
	global_store_dwordx2 v[38:39], v[4:5], off offset:80
	v_mul_f32 v4, v36, v12
	v_mul_f32 v5, v36, v13
	s_waitcnt vmcnt(4)
	v_mul_f32 v6, v36, v14
	v_mul_f32 v7, v36, v15
	v_cvt_pk_bf16_f32 v20, v20, v21
	v_cvt_pk_bf16_f32 v21, v22, v23
	v_cvt_pk_bf16_f32 v4, v4, v5
	v_cvt_pk_bf16_f32 v5, v6, v7
	global_store_dwordx2 v[38:39], v[20:21], off offset:32
	v_mul_f32 v20, v36, v32
	v_mul_f32 v21, v36, v33
	v_mul_f32 v22, v36, v34
	v_mul_f32 v23, v36, v35
	global_store_dwordx2 v[38:39], v[4:5], off offset:96
	v_mul_f32 v4, v36, v16
	v_mul_f32 v5, v36, v17
	v_mul_f32 v6, v36, v18
	v_mul_f32 v7, v36, v19
	v_cvt_pk_bf16_f32 v20, v20, v21
	v_cvt_pk_bf16_f32 v21, v22, v23
	v_cvt_pk_bf16_f32 v4, v4, v5
	v_cvt_pk_bf16_f32 v5, v6, v7
	global_store_dwordx2 v[38:39], v[20:21], off offset:48
	global_store_dwordx2 v[38:39], v[4:5], off offset:112
	s_branch .LBB0_2145

.LBB0_2288:
	s_or_b64 exec, exec, s[14:15]
	v_fma_f32 v12, v28, v32, -v12
	v_fma_f32 v13, v29, v32, -v13
	v_fma_f32 v14, v26, v32, -v14
	v_fma_f32 v15, v27, v32, -v15
	v_cvt_pk_bf16_f32 v26, v12, v13
	v_fma_f32 v12, v30, v32, -v18
	v_fma_f32 v13, v31, v32, -v19
	v_fma_f32 v16, v24, v32, -v16
	v_fma_f32 v17, v25, v32, -v17
	v_cvt_pk_bf16_f32 v27, v12, v13
	v_mov_b64_e32 v[12:13], s[40:41]
	v_mad_i64_i32 v[12:13], s[14:15], v35, s71, v[12:13]
	v_cvt_pk_bf16_f32 v24, v16, v17
	v_cvt_pk_bf16_f32 v25, v14, v15
	v_lshl_add_u64 v[12:13], v[22:23], 1, v[12:13]
	global_store_dwordx4 v[12:13], v[24:27], off

.LBB0_2300:
	s_or_b64 exec, exec, s[8:9]
	s_waitcnt vmcnt(0)
	v_lshlrev_b32_e32 v28, 16, v16
	v_and_b32_e32 v29, 0xffff0000, v16
	v_lshlrev_b32_e32 v26, 16, v17
	v_and_b32_e32 v27, 0xffff0000, v17
	v_pk_add_f32 v[30:31], v[28:29], 0 op_sel_hi:[1,0]
	v_lshlrev_b32_e32 v32, 16, v12
	v_and_b32_e32 v33, 0xffff0000, v12
	v_lshlrev_b32_e32 v16, 16, v18
	v_and_b32_e32 v17, 0xffff0000, v18
	v_add_f32 v30, v30, v32
	v_add_f32 v31, v31, v33
	v_pk_add_f32 v[32:33], v[26:27], 0 op_sel_hi:[1,0]
	v_lshlrev_b32_e32 v12, 16, v13
	v_and_b32_e32 v13, 0xffff0000, v13
	v_lshlrev_b32_e32 v18, 16, v19
	v_and_b32_e32 v19, 0xffff0000, v19
	v_add_f32 v12, v32, v12
	v_add_f32 v13, v33, v13
	v_pk_add_f32 v[32:33], v[16:17], 0 op_sel_hi:[1,0]
	v_lshlrev_b32_e32 v38, 16, v14
	v_and_b32_e32 v39, 0xffff0000, v14
	s_movk_i32 s8, 0xffe8
	v_and_b32_e32 v34, 7, v37
	v_add_f32 v32, v32, v38
	v_add_f32 v33, v33, v39
	v_pk_add_f32 v[38:39], v[18:19], 0 op_sel_hi:[1,0]
	v_lshlrev_b32_e32 v14, 16, v15
	v_and_b32_e32 v15, 0xffff0000, v15
	v_cmp_lt_i32_e32 vcc, s8, v21
	v_cmp_eq_u32_e64 s[20:21], 0, v34
	v_add_f32 v14, v38, v14
	v_add_f32 v15, v39, v15
	s_and_b64 s[14:15], vcc, s[20:21]
	s_and_saveexec_b64 s[8:9], s[14:15]
	s_cbranch_execz .LBB0_2302
	v_lshrrev_b32_e32 v34, 3, v37
	v_mov_b64_e32 v[38:39], s[6:7]
	s_mov_b32 s14, 0xb400
	v_mad_u64_u32 v[38:39], s[14:15], v34, s14, v[38:39]
	v_lshl_add_u64 v[42:43], v[24:25], 2, v[38:39]
	v_add_co_u32_e32 v38, vcc, 0xa000, v42
	s_mov_b64 s[14:15], 0xa800
	s_nop 0
	v_addc_co_u32_e32 v39, vcc, 0, v43, vcc
	v_lshl_add_u64 v[42:43], v[42:43], 0, s[14:15]
	global_load_dwordx4 v[38:41], v[38:39], off offset:2048
	s_nop 0
	global_load_dwordx4 v[42:45], v[42:43], off offset:16
	s_waitcnt vmcnt(1)
	v_add_f32 v30, v30, v38
	v_add_f32 v31, v31, v39
	v_add_f32 v12, v12, v40
	v_add_f32 v13, v13, v41
	s_waitcnt vmcnt(0)
	v_add_f32 v32, v32, v42
	v_add_f32 v33, v33, v43
	v_add_f32 v14, v14, v44
	v_add_f32 v15, v15, v45
.LBB0_2302:
	s_or_b64 exec, exec, s[8:9]
	v_mov_b32_e32 v34, 0.5
	s_and_saveexec_b64 s[8:9], s[18:19]
	v_and_b32_e32 v34, 0x7ff, v37
	v_cmp_eq_u32_e32 vcc, 0, v34
	s_nop 1
	v_cndmask_b32_e64 v34, 0.5, 1.0, vcc
	s_or_b64 exec, exec, s[8:9]
	v_fma_f32 v28, v30, v34, -v28
	v_fma_f32 v29, v31, v34, -v29
	v_fma_f32 v12, v12, v34, -v26
	v_fma_f32 v13, v13, v34, -v27
	v_cvt_pk_bf16_f32 v28, v28, v29
	v_cvt_pk_bf16_f32 v29, v12, v13
	v_fma_f32 v12, v32, v34, -v16
	v_fma_f32 v13, v33, v34, -v17
	v_mad_i64_i32 v[36:37], s[8:9], v36, s71, 0
	v_cvt_pk_bf16_f32 v30, v12, v13
	v_fma_f32 v12, v14, v34, -v18
	v_fma_f32 v13, v15, v34, -v19
	s_nop 0
	v_cvt_pk_bf16_f32 v31, v12, v13
	v_lshl_add_u64 v[12:13], s[40:41], 0, v[36:37]
	v_lshl_add_u64 v[12:13], v[24:25], 1, v[12:13]
	global_store_dwordx4 v[12:13], v[28:31], off
	s_and_saveexec_b64 s[8:9], s[16:17]
	s_cbranch_execz .LBB0_2289
	v_lshlrev_b32_e32 v16, 16, v4
	v_and_b32_e32 v17, 0xffff0000, v4
	v_lshlrev_b32_e32 v14, 16, v5
	v_and_b32_e32 v15, 0xffff0000, v5
	v_pk_add_f32 v[24:25], v[16:17], 0 op_sel_hi:[1,0]
	v_lshlrev_b32_e32 v26, 16, v8
	v_and_b32_e32 v27, 0xffff0000, v8
	v_lshlrev_b32_e32 v12, 16, v6
	v_and_b32_e32 v13, 0xffff0000, v6
	v_add_f32 v24, v24, v26
	v_add_f32 v25, v25, v27
	v_pk_add_f32 v[26:27], v[14:15], 0 op_sel_hi:[1,0]
	v_lshlrev_b32_e32 v28, 16, v9
	v_and_b32_e32 v29, 0xffff0000, v9
	v_lshlrev_b32_e32 v18, 16, v7
	v_and_b32_e32 v19, 0xffff0000, v7
	v_add_f32 v26, v26, v28
	v_add_f32 v27, v27, v29
	v_pk_add_f32 v[28:29], v[12:13], 0 op_sel_hi:[1,0]
	v_lshlrev_b32_e32 v30, 16, v10
	v_and_b32_e32 v31, 0xffff0000, v10
	v_add_f32 v28, v28, v30
	v_add_f32 v29, v29, v31
	v_pk_add_f32 v[30:31], v[18:19], 0 op_sel_hi:[1,0]
	v_lshlrev_b32_e32 v32, 16, v11
	v_and_b32_e32 v33, 0xffff0000, v11
	v_add_f32 v30, v30, v32
	v_add_f32 v31, v31, v33
	s_movk_i32 s14, 0x3fff
	v_and_b32_e32 v32, 7, v35
	v_cmp_lt_i32_e32 vcc, s14, v35
	v_cmp_eq_u32_e64 s[16:17], 0, v32
	s_and_b64 s[16:17], vcc, s[16:17]
	s_and_saveexec_b64 s[14:15], s[16:17]
	s_cbranch_execz .LBB0_2307
	v_add_u32_e32 v32, 0xffffc000, v35
	v_lshrrev_b32_e32 v34, 3, v32
	v_mov_b64_e32 v[32:33], s[6:7]
	s_mov_b32 s16, 0xb400
	v_mad_u64_u32 v[32:33], s[16:17], v34, s16, v[32:33]
	v_lshl_add_u64 v[32:33], v[22:23], 2, v[32:33]
	v_add_co_u32_e32 v36, vcc, 0xa000, v32
	s_mov_b64 s[16:17], 0xa800
	s_nop 0
	v_addc_co_u32_e32 v37, vcc, 0, v33, vcc
	v_lshl_add_u64 v[32:33], v[32:33], 0, s[16:17]
	global_load_dwordx4 v[36:39], v[36:37], off offset:2048
	s_nop 0
	global_load_dwordx4 v[40:43], v[32:33], off offset:16
	s_waitcnt vmcnt(1)
	v_add_f32 v24, v24, v36
	v_add_f32 v25, v25, v37
	v_add_f32 v26, v26, v38
	v_add_f32 v27, v27, v39
	s_waitcnt vmcnt(0)
	v_add_f32 v28, v28, v40
	v_add_f32 v29, v29, v41
	v_add_f32 v30, v30, v42
	v_add_f32 v31, v31, v43

.LBB0_2310:
	s_or_b64 exec, exec, s[14:15]
	v_fma_f32 v20, v34, v40, -v20
	v_fma_f32 v21, v35, v40, -v21
	v_fma_f32 v26, v28, v40, -v26
	v_fma_f32 v27, v29, v40, -v27
	v_cvt_pk_bf16_f32 v29, v20, v21
	v_mov_b64_e32 v[20:21], s[40:41]
	v_fma_f32 v24, v30, v40, -v24
	v_fma_f32 v25, v31, v40, -v25
	v_fma_f32 v22, v32, v40, -v22
	v_fma_f32 v23, v33, v40, -v23
	v_mad_i64_i32 v[20:21], s[14:15], v50, s71, v[20:21]
	v_mov_b32_e32 v39, v2
	v_cvt_pk_bf16_f32 v26, v26, v27
	v_cvt_pk_bf16_f32 v27, v24, v25
	v_cvt_pk_bf16_f32 v28, v22, v23
	v_lshl_add_u64 v[20:21], v[38:39], 1, v[20:21]
	global_store_dwordx4 v[20:21], v[26:29], off

.LBB0_2330:
	s_or_b64 exec, exec, s[8:9]
	s_waitcnt vmcnt(0)
	v_lshlrev_b32_e32 v48, 16, v28
	v_and_b32_e32 v49, 0xffff0000, v28
	v_lshlrev_b32_e32 v46, 16, v29
	v_and_b32_e32 v47, 0xffff0000, v29
	v_lshlrev_b32_e32 v44, 16, v30
	v_and_b32_e32 v45, 0xffff0000, v30
	v_lshlrev_b32_e32 v28, 16, v31
	v_and_b32_e32 v29, 0xffff0000, v31
	v_pk_add_f32 v[30:31], v[48:49], 0 op_sel_hi:[1,0]
	v_lshlrev_b32_e32 v52, 16, v24
	v_and_b32_e32 v53, 0xffff0000, v24
	v_add_f32 v30, v30, v52
	v_add_f32 v31, v31, v53
	v_lshlrev_b32_e32 v52, 16, v32
	v_and_b32_e32 v53, 0xffff0000, v32
	v_add_f32 v30, v30, v52
	v_add_f32 v31, v31, v53
	v_lshlrev_b32_e32 v52, 16, v20
	v_and_b32_e32 v53, 0xffff0000, v20
	v_add_f32 v30, v30, v52
	v_add_f32 v31, v31, v53
	v_pk_add_f32 v[52:53], v[46:47], 0 op_sel_hi:[1,0]
	v_lshlrev_b32_e32 v24, 16, v25
	v_and_b32_e32 v25, 0xffff0000, v25
	v_add_f32 v24, v52, v24
	v_add_f32 v25, v53, v25
	v_lshlrev_b32_e32 v32, 16, v33
	v_and_b32_e32 v33, 0xffff0000, v33
	v_add_f32 v24, v24, v32
	v_add_f32 v25, v25, v33
	v_lshlrev_b32_e32 v20, 16, v21
	v_and_b32_e32 v21, 0xffff0000, v21
	v_add_f32 v20, v24, v20
	v_add_f32 v21, v25, v21
	v_pk_add_f32 v[24:25], v[44:45], 0 op_sel_hi:[1,0]
	v_lshlrev_b32_e32 v32, 16, v26
	v_and_b32_e32 v33, 0xffff0000, v26
	v_add_f32 v24, v24, v32
	v_add_f32 v25, v25, v33
	v_lshlrev_b32_e32 v32, 16, v34
	v_and_b32_e32 v33, 0xffff0000, v34
	v_add_f32 v24, v24, v32
	v_add_f32 v25, v25, v33
	v_lshlrev_b32_e32 v32, 16, v22
	v_and_b32_e32 v33, 0xffff0000, v22
	v_add_f32 v24, v24, v32
	v_add_f32 v25, v25, v33
	v_pk_add_f32 v[32:33], v[28:29], 0 op_sel_hi:[1,0]
	v_lshlrev_b32_e32 v26, 16, v27
	v_and_b32_e32 v27, 0xffff0000, v27
	v_mad_i64_i32 v[42:43], s[8:9], v42, s71, 0
	v_add_f32 v26, v32, v26
	v_add_f32 v27, v33, v27
	v_lshlrev_b32_e32 v32, 16, v35
	v_and_b32_e32 v33, 0xffff0000, v35
	v_add_f32 v26, v26, v32
	v_add_f32 v27, v27, v33
	v_lshlrev_b32_e32 v22, 16, v23
	v_and_b32_e32 v23, 0xffff0000, v23
	s_movk_i32 s8, 0xffe8
	v_add_f32 v22, v26, v22
	v_add_f32 v23, v27, v23
	v_cmp_lt_i32_e32 vcc, s8, v37
	s_and_saveexec_b64 s[8:9], vcc
	s_cbranch_execz .LBB0_2338
	v_and_b32_e32 v34, 7, v51
	v_lshrrev_b32_e32 v32, 3, v51
	v_lshl_add_u64 v[26:27], v[40:41], 2, s[6:7]
	v_cmp_eq_u32_e32 vcc, 0, v34
	s_and_saveexec_b64 s[14:15], vcc
	s_cbranch_execz .LBB0_2333
	s_mov_b32 s20, 0xb400
	v_mad_u64_u32 v[56:57], s[20:21], v32, s20, v[26:27]
	v_add_co_u32_e32 v52, vcc, 0xa000, v56
	s_mov_b64 s[20:21], 0xa800
	s_nop 0
	v_addc_co_u32_e32 v53, vcc, 0, v57, vcc
	v_lshl_add_u64 v[56:57], v[56:57], 0, s[20:21]
	global_load_dwordx4 v[52:55], v[52:53], off offset:2048
	s_nop 0
	global_load_dwordx4 v[56:59], v[56:57], off offset:16
	s_waitcnt vmcnt(1)
	v_add_f32 v30, v30, v52
	v_add_f32 v31, v31, v53
	v_add_f32 v20, v20, v54
	v_add_f32 v21, v21, v55
	s_waitcnt vmcnt(0)
	v_add_f32 v24, v24, v56
	v_add_f32 v25, v25, v57
	v_add_f32 v22, v22, v58
	v_add_f32 v23, v23, v59
.LBB0_2333:
	s_or_b64 exec, exec, s[14:15]
	v_mad_u64_u32 v[32:33], s[14:15], v32, 15, 15
	v_cmp_gt_u32_e32 vcc, 2, v34
	s_and_saveexec_b64 s[14:15], vcc
	s_cbranch_execz .LBB0_2335
	v_or_b32_e32 v52, -2, v51
	v_ashrrev_i32_e32 v53, 31, v52
	v_lshl_add_u64 v[52:53], v[32:33], 0, v[52:53]
	v_mad_u64_u32 v[56:57], s[20:21], v52, s91, v[26:27]
	v_mov_b32_e32 v52, v57
	v_mad_u64_u32 v[52:53], s[20:21], v53, s91, v[52:53]
	v_mov_b32_e32 v57, v52
	global_load_dwordx4 v[52:55], v[56:57], off offset:16
	s_nop 0
	global_load_dwordx4 v[56:59], v[56:57], off
	s_waitcnt vmcnt(1)
	v_add_f32 v22, v22, v54
	v_add_f32 v23, v23, v55
	s_waitcnt vmcnt(0)
	v_add_f32 v20, v20, v58
	v_add_f32 v21, v21, v59
	v_add_f32 v24, v24, v52
	v_add_f32 v25, v25, v53
	v_add_f32 v30, v30, v56
	v_add_f32 v31, v31, v57
.LBB0_2335:
	s_or_b64 exec, exec, s[14:15]
	v_cmp_gt_u32_e32 vcc, 3, v34
	s_and_saveexec_b64 s[14:15], vcc
	s_cbranch_execz .LBB0_2337
	v_add_u32_e32 v34, -3, v34
	v_ashrrev_i32_e32 v35, 31, v34
	v_lshl_add_u64 v[32:33], v[32:33], 0, v[34:35]
	v_mad_u64_u32 v[26:27], s[20:21], v32, s91, v[26:27]
	v_mov_b32_e32 v32, v27
	v_mad_u64_u32 v[32:33], s[20:21], v33, s91, v[32:33]
	v_mov_b32_e32 v27, v32
	global_load_dwordx4 v[32:35], v[26:27], off offset:16
	global_load_dwordx4 v[52:55], v[26:27], off
	s_waitcnt vmcnt(1)
	v_add_f32 v22, v22, v34
	v_add_f32 v23, v23, v35
	s_waitcnt vmcnt(0)
	v_add_f32 v20, v20, v54
	v_add_f32 v21, v21, v55
	v_add_f32 v24, v24, v32
	v_add_f32 v25, v25, v33
	v_add_f32 v30, v30, v52
	v_add_f32 v31, v31, v53

.LBB0_2340:
	s_or_b64 exec, exec, s[8:9]
	v_fma_f32 v30, v30, v26, -v48
	v_fma_f32 v31, v31, v26, -v49
	v_fma_f32 v20, v20, v26, -v46
	v_fma_f32 v21, v21, v26, -v47
	v_cvt_pk_bf16_f32 v30, v30, v31
	v_cvt_pk_bf16_f32 v31, v20, v21
	v_fma_f32 v20, v24, v26, -v44
	v_fma_f32 v21, v25, v26, -v45
	s_nop 0
	v_cvt_pk_bf16_f32 v32, v20, v21
	v_fma_f32 v20, v22, v26, -v28
	v_fma_f32 v21, v23, v26, -v29
	s_nop 0
	v_cvt_pk_bf16_f32 v33, v20, v21
	v_lshl_add_u64 v[20:21], s[40:41], 0, v[42:43]
	v_lshl_add_u64 v[20:21], v[40:41], 1, v[20:21]
	global_store_dwordx4 v[20:21], v[30:33], off
	s_and_saveexec_b64 s[8:9], s[16:17]
	s_cbranch_execz .LBB0_2311
	v_lshlrev_b32_e32 v26, 16, v4
	v_and_b32_e32 v27, 0xffff0000, v4
	v_pk_add_f32 v[28:29], v[26:27], 0 op_sel_hi:[1,0]
	v_lshlrev_b32_e32 v30, 16, v8
	v_and_b32_e32 v31, 0xffff0000, v8
	v_add_f32 v28, v28, v30
	v_add_f32 v29, v29, v31
	v_lshlrev_b32_e32 v30, 16, v16
	v_and_b32_e32 v31, 0xffff0000, v16
	v_lshlrev_b32_e32 v24, 16, v5
	v_and_b32_e32 v25, 0xffff0000, v5
	v_add_f32 v28, v28, v30
	v_add_f32 v29, v29, v31
	v_lshlrev_b32_e32 v30, 16, v12
	v_and_b32_e32 v31, 0xffff0000, v12
	v_add_f32 v28, v28, v30
	v_add_f32 v29, v29, v31
	v_pk_add_f32 v[30:31], v[24:25], 0 op_sel_hi:[1,0]
	v_lshlrev_b32_e32 v32, 16, v9
	v_and_b32_e32 v33, 0xffff0000, v9
	v_add_f32 v30, v30, v32
	v_add_f32 v31, v31, v33
	v_lshlrev_b32_e32 v32, 16, v17
	v_and_b32_e32 v33, 0xffff0000, v17
	v_lshlrev_b32_e32 v22, 16, v6
	v_and_b32_e32 v23, 0xffff0000, v6
	v_add_f32 v30, v30, v32
	v_add_f32 v31, v31, v33
	v_lshlrev_b32_e32 v32, 16, v13
	v_and_b32_e32 v33, 0xffff0000, v13
	v_add_f32 v30, v30, v32
	v_add_f32 v31, v31, v33
	v_pk_add_f32 v[32:33], v[22:23], 0 op_sel_hi:[1,0]
	v_lshlrev_b32_e32 v34, 16, v10
	v_and_b32_e32 v35, 0xffff0000, v10
	v_add_f32 v32, v32, v34
	v_add_f32 v33, v33, v35
	v_lshlrev_b32_e32 v34, 16, v18
	v_and_b32_e32 v35, 0xffff0000, v18
	v_lshlrev_b32_e32 v20, 16, v7
	v_and_b32_e32 v21, 0xffff0000, v7
	v_add_f32 v32, v32, v34
	v_add_f32 v33, v33, v35
	v_lshlrev_b32_e32 v34, 16, v14
	v_and_b32_e32 v35, 0xffff0000, v14
	v_add_f32 v32, v32, v34
	v_add_f32 v33, v33, v35
	v_pk_add_f32 v[34:35], v[20:21], 0 op_sel_hi:[1,0]
	v_lshlrev_b32_e32 v40, 16, v11
	v_and_b32_e32 v41, 0xffff0000, v11
	v_add_f32 v34, v34, v40
	v_add_f32 v35, v35, v41
	v_lshlrev_b32_e32 v40, 16, v19
	v_and_b32_e32 v41, 0xffff0000, v19
	v_add_f32 v34, v34, v40
	v_add_f32 v35, v35, v41
	v_lshlrev_b32_e32 v40, 16, v15
	v_and_b32_e32 v41, 0xffff0000, v15
	s_movk_i32 s14, 0x3fff
	v_add_f32 v34, v34, v40
	v_add_f32 v35, v35, v41
	v_cmp_lt_i32_e32 vcc, s14, v50
	s_and_saveexec_b64 s[14:15], vcc
	s_cbranch_execz .LBB0_2349
	v_add_u32_e32 v39, 0xffffc000, v50
	v_and_b32_e32 v44, 7, v50
	v_lshrrev_b32_e32 v42, 3, v39
	v_mov_b32_e32 v39, v2
	v_lshl_add_u64 v[40:41], v[38:39], 2, s[6:7]
	v_cmp_eq_u32_e32 vcc, 0, v44
	s_and_saveexec_b64 s[16:17], vcc
	s_cbranch_execz .LBB0_2344
	s_mov_b32 s18, 0xb400
	v_mad_u64_u32 v[52:53], s[18:19], v42, s18, v[40:41]
	v_add_co_u32_e32 v46, vcc, 0xa000, v52
	s_mov_b64 s[18:19], 0xa800
	s_nop 0
	v_addc_co_u32_e32 v47, vcc, 0, v53, vcc
	v_lshl_add_u64 v[52:53], v[52:53], 0, s[18:19]
	global_load_dwordx4 v[46:49], v[46:47], off offset:2048
	s_nop 0
	global_load_dwordx4 v[52:55], v[52:53], off offset:16
	s_waitcnt vmcnt(1)
	v_add_f32 v28, v28, v46
	v_add_f32 v29, v29, v47
	v_add_f32 v30, v30, v48
	v_add_f32 v31, v31, v49
	s_waitcnt vmcnt(0)
	v_add_f32 v32, v32, v52
	v_add_f32 v33, v33, v53
	v_add_f32 v34, v34, v54
	v_add_f32 v35, v35, v55
.LBB0_2344:
	s_or_b64 exec, exec, s[16:17]
	v_mad_u64_u32 v[42:43], s[16:17], v42, 15, 15
	v_cmp_gt_u32_e32 vcc, 2, v44
	s_and_saveexec_b64 s[16:17], vcc
	s_cbranch_execz .LBB0_2346
	v_or_b32_e32 v46, -2, v50
	v_ashrrev_i32_e32 v47, 31, v46
	v_lshl_add_u64 v[46:47], v[42:43], 0, v[46:47]
	v_mad_u64_u32 v[52:53], s[18:19], v46, s91, v[40:41]
	v_mov_b32_e32 v46, v53
	v_mad_u64_u32 v[46:47], s[18:19], v47, s91, v[46:47]
	v_mov_b32_e32 v53, v46
	global_load_dwordx4 v[46:49], v[52:53], off offset:16
	s_nop 0
	global_load_dwordx4 v[52:55], v[52:53], off
	s_waitcnt vmcnt(1)
	v_add_f32 v34, v34, v48
	v_add_f32 v35, v35, v49
	s_waitcnt vmcnt(0)
	v_add_f32 v30, v30, v54
	v_add_f32 v31, v31, v55
	v_add_f32 v32, v32, v46
	v_add_f32 v33, v33, v47
	v_add_f32 v28, v28, v52
	v_add_f32 v29, v29, v53
.LBB0_2346:
	s_or_b64 exec, exec, s[16:17]
	v_cmp_gt_u32_e32 vcc, 3, v44
	s_and_saveexec_b64 s[16:17], vcc
	s_cbranch_execz .LBB0_2348
	v_add_u32_e32 v44, -3, v44
	v_ashrrev_i32_e32 v45, 31, v44
	v_lshl_add_u64 v[42:43], v[42:43], 0, v[44:45]
	v_mad_u64_u32 v[44:45], s[18:19], v42, s91, v[40:41]
	v_mov_b32_e32 v40, v45
	v_mad_u64_u32 v[40:41], s[18:19], v43, s91, v[40:41]
	v_mov_b32_e32 v45, v40
	global_load_dwordx4 v[40:43], v[44:45], off offset:16
	s_nop 0
	global_load_dwordx4 v[44:47], v[44:45], off
	s_waitcnt vmcnt(1)
	v_add_f32 v34, v34, v42
	v_add_f32 v35, v35, v43
	s_waitcnt vmcnt(0)
	v_add_f32 v30, v30, v46
	v_add_f32 v31, v31, v47
	v_add_f32 v32, v32, v40
	v_add_f32 v33, v33, v41
	v_add_f32 v28, v28, v44
	v_add_f32 v29, v29, v45

.LBB0_2352:
	s_or_b64 exec, exec, s[14:15]
	v_fma_f32 v36, v50, v52, -v36
	v_fma_f32 v37, v51, v52, -v37
	v_fma_f32 v42, v44, v52, -v42
	v_fma_f32 v43, v45, v52, -v43
	v_cvt_pk_bf16_f32 v45, v36, v37
	v_mov_b64_e32 v[36:37], s[40:41]
	v_fma_f32 v40, v46, v52, -v40
	v_fma_f32 v41, v47, v52, -v41
	v_fma_f32 v38, v48, v52, -v38
	v_fma_f32 v39, v49, v52, -v39
	v_mad_i64_i32 v[36:37], s[14:15], v82, s71, v[36:37]
	v_mov_b32_e32 v71, v2
	v_cvt_pk_bf16_f32 v42, v42, v43
	v_cvt_pk_bf16_f32 v43, v40, v41
	v_cvt_pk_bf16_f32 v44, v38, v39
	v_lshl_add_u64 v[36:37], v[70:71], 1, v[36:37]
	global_store_dwordx4 v[36:37], v[42:45], off

.LBB0_2388:
	s_or_b64 exec, exec, s[0:1]
	s_waitcnt vmcnt(0)
	v_lshlrev_b32_e32 v80, 16, v56
	v_and_b32_e32 v81, 0xffff0000, v56
	v_lshlrev_b32_e32 v78, 16, v57
	v_and_b32_e32 v79, 0xffff0000, v57
	v_lshlrev_b32_e32 v76, 16, v58
	v_and_b32_e32 v77, 0xffff0000, v58
	v_lshlrev_b32_e32 v56, 16, v59
	v_and_b32_e32 v57, 0xffff0000, v59
	v_pk_add_f32 v[58:59], v[80:81], 0 op_sel_hi:[1,0]
	v_lshlrev_b32_e32 v84, 16, v40
	v_and_b32_e32 v85, 0xffff0000, v40
	v_add_f32 v58, v58, v84
	v_add_f32 v59, v59, v85
	v_lshlrev_b32_e32 v84, 16, v44
	v_and_b32_e32 v85, 0xffff0000, v44
	v_add_f32 v58, v58, v84
	v_add_f32 v59, v59, v85
	v_lshlrev_b32_e32 v84, 16, v36
	v_and_b32_e32 v85, 0xffff0000, v36
	v_add_f32 v58, v58, v84
	v_add_f32 v59, v59, v85
	v_lshlrev_b32_e32 v84, 16, v52
	v_and_b32_e32 v85, 0xffff0000, v52
	v_add_f32 v58, v58, v84
	v_add_f32 v59, v59, v85
	v_lshlrev_b32_e32 v84, 16, v48
	v_and_b32_e32 v85, 0xffff0000, v48
	v_add_f32 v58, v58, v84
	v_add_f32 v59, v59, v85
	v_lshlrev_b32_e32 v84, 16, v64
	v_and_b32_e32 v85, 0xffff0000, v64
	v_add_f32 v58, v58, v84
	v_add_f32 v59, v59, v85
	v_lshlrev_b32_e32 v84, 16, v60
	v_and_b32_e32 v85, 0xffff0000, v60
	v_add_f32 v58, v58, v84
	v_add_f32 v59, v59, v85
	v_pk_add_f32 v[84:85], v[78:79], 0 op_sel_hi:[1,0]
	v_lshlrev_b32_e32 v40, 16, v41
	v_and_b32_e32 v41, 0xffff0000, v41
	v_add_f32 v40, v84, v40
	v_add_f32 v41, v85, v41
	v_lshlrev_b32_e32 v44, 16, v45
	v_and_b32_e32 v45, 0xffff0000, v45
	v_add_f32 v40, v40, v44
	v_add_f32 v41, v41, v45
	v_lshlrev_b32_e32 v36, 16, v37
	v_and_b32_e32 v37, 0xffff0000, v37
	v_add_f32 v36, v40, v36
	v_add_f32 v37, v41, v37
	v_lshlrev_b32_e32 v40, 16, v53
	v_and_b32_e32 v41, 0xffff0000, v53
	v_add_f32 v36, v36, v40
	v_add_f32 v37, v37, v41
	v_lshlrev_b32_e32 v40, 16, v49
	v_and_b32_e32 v41, 0xffff0000, v49
	v_add_f32 v36, v36, v40
	v_add_f32 v37, v37, v41
	v_lshlrev_b32_e32 v40, 16, v65
	v_and_b32_e32 v41, 0xffff0000, v65
	v_add_f32 v36, v36, v40
	v_add_f32 v37, v37, v41
	v_lshlrev_b32_e32 v40, 16, v61
	v_and_b32_e32 v41, 0xffff0000, v61
	v_add_f32 v36, v36, v40
	v_add_f32 v37, v37, v41
	v_pk_add_f32 v[40:41], v[76:77], 0 op_sel_hi:[1,0]
	v_lshlrev_b32_e32 v44, 16, v42
	v_and_b32_e32 v45, 0xffff0000, v42
	v_add_f32 v40, v40, v44
	v_add_f32 v41, v41, v45
	v_lshlrev_b32_e32 v44, 16, v46
	v_and_b32_e32 v45, 0xffff0000, v46
	v_add_f32 v40, v40, v44
	v_add_f32 v41, v41, v45
	v_lshlrev_b32_e32 v44, 16, v38
	v_and_b32_e32 v45, 0xffff0000, v38
	v_add_f32 v40, v40, v44
	v_add_f32 v41, v41, v45
	v_lshlrev_b32_e32 v44, 16, v54
	v_and_b32_e32 v45, 0xffff0000, v54
	v_add_f32 v40, v40, v44
	v_add_f32 v41, v41, v45
	v_lshlrev_b32_e32 v44, 16, v50
	v_and_b32_e32 v45, 0xffff0000, v50
	v_add_f32 v40, v40, v44
	v_add_f32 v41, v41, v45
	v_lshlrev_b32_e32 v44, 16, v66
	v_and_b32_e32 v45, 0xffff0000, v66
	v_add_f32 v40, v40, v44
	v_add_f32 v41, v41, v45
	v_lshlrev_b32_e32 v44, 16, v62
	v_and_b32_e32 v45, 0xffff0000, v62
	v_add_f32 v40, v40, v44
	v_add_f32 v41, v41, v45
	v_pk_add_f32 v[44:45], v[56:57], 0 op_sel_hi:[1,0]
	v_lshlrev_b32_e32 v42, 16, v43
	v_and_b32_e32 v43, 0xffff0000, v43
	v_add_f32 v42, v44, v42
	v_add_f32 v43, v45, v43
	v_lshlrev_b32_e32 v44, 16, v47
	v_and_b32_e32 v45, 0xffff0000, v47
	v_add_f32 v42, v42, v44
	v_add_f32 v43, v43, v45
	v_lshlrev_b32_e32 v38, 16, v39
	v_and_b32_e32 v39, 0xffff0000, v39
	v_add_f32 v38, v42, v38
	v_add_f32 v39, v43, v39
	v_lshlrev_b32_e32 v42, 16, v55
	v_and_b32_e32 v43, 0xffff0000, v55
	v_add_f32 v38, v38, v42
	v_add_f32 v39, v39, v43
	v_lshlrev_b32_e32 v42, 16, v51
	v_and_b32_e32 v43, 0xffff0000, v51
	v_mad_i64_i32 v[74:75], s[0:1], v74, s71, 0
	v_add_f32 v38, v38, v42
	v_add_f32 v39, v39, v43
	v_lshlrev_b32_e32 v42, 16, v67
	v_and_b32_e32 v43, 0xffff0000, v67
	v_add_f32 v38, v38, v42
	v_add_f32 v39, v39, v43
	v_lshlrev_b32_e32 v42, 16, v63
	v_and_b32_e32 v43, 0xffff0000, v63
	s_movk_i32 s0, 0xffe8
	v_add_f32 v38, v38, v42
	v_add_f32 v39, v39, v43
	v_cmp_lt_i32_e32 vcc, s0, v69
	s_and_saveexec_b64 s[0:1], vcc
	s_cbranch_execz .LBB0_2404
	v_and_b32_e32 v46, 7, v83
	v_lshrrev_b32_e32 v44, 3, v83
	v_lshl_add_u64 v[42:43], v[72:73], 2, s[6:7]
	v_cmp_eq_u32_e32 vcc, 0, v46
	s_and_saveexec_b64 s[14:15], vcc
	s_cbranch_execz .LBB0_2391
	s_mov_b32 s20, 0xb400
	v_mad_u64_u32 v[52:53], s[20:21], v44, s20, v[42:43]
	v_add_co_u32_e32 v48, vcc, 0xa000, v52
	s_mov_b64 s[20:21], 0xa800
	s_nop 0
	v_addc_co_u32_e32 v49, vcc, 0, v53, vcc
	v_lshl_add_u64 v[52:53], v[52:53], 0, s[20:21]
	global_load_dwordx4 v[48:51], v[48:49], off offset:2048
	s_nop 0
	global_load_dwordx4 v[52:55], v[52:53], off offset:16
	s_waitcnt vmcnt(1)
	v_add_f32 v58, v58, v48
	v_add_f32 v59, v59, v49
	v_add_f32 v36, v36, v50
	v_add_f32 v37, v37, v51
	s_waitcnt vmcnt(0)
	v_add_f32 v40, v40, v52
	v_add_f32 v41, v41, v53
	v_add_f32 v38, v38, v54
	v_add_f32 v39, v39, v55
.LBB0_2391:
	s_or_b64 exec, exec, s[14:15]
	v_mad_u64_u32 v[44:45], s[14:15], v44, 15, 15
	v_cmp_gt_u32_e32 vcc, 2, v46
	s_and_saveexec_b64 s[14:15], vcc
	s_cbranch_execz .LBB0_2397
	v_or_b32_e32 v48, -2, v83
	v_ashrrev_i32_e32 v49, 31, v48
	v_lshl_add_u64 v[48:49], v[44:45], 0, v[48:49]
	v_mad_u64_u32 v[52:53], s[20:21], v48, s91, v[42:43]
	v_mov_b32_e32 v48, v53
	v_mad_u64_u32 v[48:49], s[20:21], v49, s91, v[48:49]
	v_mov_b32_e32 v53, v48
	global_load_dwordx4 v[48:51], v[52:53], off offset:16
	s_nop 0
	global_load_dwordx4 v[52:55], v[52:53], off
	s_waitcnt vmcnt(1)
	v_add_f32 v38, v38, v50
	v_add_f32 v39, v39, v51
	s_waitcnt vmcnt(0)
	v_add_f32 v36, v36, v54
	v_add_f32 v37, v37, v55
	v_add_f32 v40, v40, v48
	v_add_f32 v41, v41, v49
	v_add_f32 v58, v58, v52
	v_add_f32 v59, v59, v53
	s_or_b64 exec, exec, s[14:15]
	v_cmp_gt_u32_e32 vcc, 3, v46
	s_and_saveexec_b64 s[14:15], vcc
	s_cbranch_execnz .LBB0_2398

.LBB0_2394:
	v_or_b32_e32 v48, -4, v83
	v_ashrrev_i32_e32 v49, 31, v48
	v_lshl_add_u64 v[48:49], v[44:45], 0, v[48:49]
	v_mad_u64_u32 v[52:53], s[20:21], v48, s91, v[42:43]
	v_mov_b32_e32 v48, v53
	v_mad_u64_u32 v[48:49], s[20:21], v49, s91, v[48:49]
	v_mov_b32_e32 v53, v48
	global_load_dwordx4 v[48:51], v[52:53], off offset:16
	s_nop 0
	global_load_dwordx4 v[52:55], v[52:53], off
	s_waitcnt vmcnt(1)
	v_add_f32 v38, v38, v50
	v_add_f32 v39, v39, v51
	s_waitcnt vmcnt(0)
	v_add_f32 v36, v36, v54
	v_add_f32 v37, v37, v55
	v_add_f32 v40, v40, v48
	v_add_f32 v41, v41, v49
	v_add_f32 v58, v58, v52
	v_add_f32 v59, v59, v53
	s_or_b64 exec, exec, s[14:15]
	v_cmp_gt_u32_e32 vcc, 5, v46
	s_and_saveexec_b64 s[14:15], vcc
	s_cbranch_execnz .LBB0_2400

.LBB0_2396:
	v_add_u32_e32 v48, -6, v46
	v_ashrrev_i32_e32 v49, 31, v48
	v_lshl_add_u64 v[48:49], v[44:45], 0, v[48:49]
	v_mad_u64_u32 v[52:53], s[20:21], v48, s91, v[42:43]
	v_mov_b32_e32 v48, v53
	v_mad_u64_u32 v[48:49], s[20:21], v49, s91, v[48:49]
	v_mov_b32_e32 v53, v48
	global_load_dwordx4 v[48:51], v[52:53], off offset:16
	s_nop 0
	global_load_dwordx4 v[52:55], v[52:53], off
	s_waitcnt vmcnt(1)
	v_add_f32 v38, v38, v50
	v_add_f32 v39, v39, v51
	s_waitcnt vmcnt(0)
	v_add_f32 v36, v36, v54
	v_add_f32 v37, v37, v55
	v_add_f32 v40, v40, v48
	v_add_f32 v41, v41, v49
	v_add_f32 v58, v58, v52
	v_add_f32 v59, v59, v53
	s_or_b64 exec, exec, s[14:15]
	v_cmp_ne_u32_e32 vcc, 7, v46
	s_and_saveexec_b64 s[14:15], vcc
	s_cbranch_execnz .LBB0_2402
	s_branch .LBB0_2403

.LBB0_2398:
	v_add_u32_e32 v48, -3, v46
	v_ashrrev_i32_e32 v49, 31, v48
	v_lshl_add_u64 v[48:49], v[44:45], 0, v[48:49]
	v_mad_u64_u32 v[52:53], s[20:21], v48, s91, v[42:43]
	v_mov_b32_e32 v48, v53
	v_mad_u64_u32 v[48:49], s[20:21], v49, s91, v[48:49]
	v_mov_b32_e32 v53, v48
	global_load_dwordx4 v[48:51], v[52:53], off offset:16
	s_nop 0
	global_load_dwordx4 v[52:55], v[52:53], off
	s_waitcnt vmcnt(1)
	v_add_f32 v38, v38, v50
	v_add_f32 v39, v39, v51
	s_waitcnt vmcnt(0)
	v_add_f32 v36, v36, v54
	v_add_f32 v37, v37, v55
	v_add_f32 v40, v40, v48
	v_add_f32 v41, v41, v49
	v_add_f32 v58, v58, v52
	v_add_f32 v59, v59, v53
	s_or_b64 exec, exec, s[14:15]
	v_cmp_gt_u32_e32 vcc, 4, v46
	s_and_saveexec_b64 s[14:15], vcc
	s_cbranch_execnz .LBB0_2394

.LBB0_2400:
	v_add_u32_e32 v48, -5, v46
	v_ashrrev_i32_e32 v49, 31, v48
	v_lshl_add_u64 v[48:49], v[44:45], 0, v[48:49]
	v_mad_u64_u32 v[52:53], s[20:21], v48, s91, v[42:43]
	v_mov_b32_e32 v48, v53
	v_mad_u64_u32 v[48:49], s[20:21], v49, s91, v[48:49]
	v_mov_b32_e32 v53, v48
	global_load_dwordx4 v[48:51], v[52:53], off offset:16
	s_nop 0
	global_load_dwordx4 v[52:55], v[52:53], off
	s_waitcnt vmcnt(1)
	v_add_f32 v38, v38, v50
	v_add_f32 v39, v39, v51
	s_waitcnt vmcnt(0)
	v_add_f32 v36, v36, v54
	v_add_f32 v37, v37, v55
	v_add_f32 v40, v40, v48
	v_add_f32 v41, v41, v49
	v_add_f32 v58, v58, v52
	v_add_f32 v59, v59, v53
	s_or_b64 exec, exec, s[14:15]
	v_cmp_gt_u32_e32 vcc, 6, v46
	s_and_saveexec_b64 s[14:15], vcc
	s_cbranch_execnz .LBB0_2396

.LBB0_2402:
	v_add_u32_e32 v46, -7, v46
	v_ashrrev_i32_e32 v47, 31, v46
	v_lshl_add_u64 v[44:45], v[44:45], 0, v[46:47]
	v_mad_u64_u32 v[46:47], s[20:21], v44, s91, v[42:43]
	v_mov_b32_e32 v42, v47
	v_mad_u64_u32 v[42:43], s[20:21], v45, s91, v[42:43]
	v_mov_b32_e32 v47, v42
	global_load_dwordx4 v[42:45], v[46:47], off offset:16
	s_nop 0
	global_load_dwordx4 v[46:49], v[46:47], off
	s_waitcnt vmcnt(1)
	v_add_f32 v38, v38, v44
	v_add_f32 v39, v39, v45
	s_waitcnt vmcnt(0)
	v_add_f32 v36, v36, v48
	v_add_f32 v37, v37, v49
	v_add_f32 v40, v40, v42
	v_add_f32 v41, v41, v43
	v_add_f32 v58, v58, v46
	v_add_f32 v59, v59, v47

.LBB0_2406:
	s_or_b64 exec, exec, s[0:1]
	v_fma_f32 v44, v58, v42, -v80
	v_fma_f32 v45, v59, v42, -v81
	v_fma_f32 v36, v36, v42, -v78
	v_fma_f32 v37, v37, v42, -v79
	v_cvt_pk_bf16_f32 v44, v44, v45
	v_cvt_pk_bf16_f32 v45, v36, v37
	v_fma_f32 v36, v40, v42, -v76
	v_fma_f32 v37, v41, v42, -v77
	s_nop 0
	v_cvt_pk_bf16_f32 v46, v36, v37
	v_fma_f32 v36, v38, v42, -v56
	v_fma_f32 v37, v39, v42, -v57
	s_nop 0
	v_cvt_pk_bf16_f32 v47, v36, v37
	v_lshl_add_u64 v[36:37], s[40:41], 0, v[74:75]
	v_lshl_add_u64 v[36:37], v[72:73], 1, v[36:37]
	global_store_dwordx4 v[36:37], v[44:47], off
	s_and_saveexec_b64 s[0:1], s[16:17]
	s_cbranch_execz .LBB0_2353
	v_lshlrev_b32_e32 v42, 16, v4
	v_and_b32_e32 v43, 0xffff0000, v4
	v_pk_add_f32 v[44:45], v[42:43], 0 op_sel_hi:[1,0]
	v_lshlrev_b32_e32 v46, 16, v8
	v_and_b32_e32 v47, 0xffff0000, v8
	v_add_f32 v44, v44, v46
	v_add_f32 v45, v45, v47
	v_lshlrev_b32_e32 v46, 16, v12
	v_and_b32_e32 v47, 0xffff0000, v12
	v_add_f32 v44, v44, v46
	v_add_f32 v45, v45, v47
	v_lshlrev_b32_e32 v46, 16, v16
	v_and_b32_e32 v47, 0xffff0000, v16
	v_add_f32 v44, v44, v46
	v_add_f32 v45, v45, v47
	v_lshlrev_b32_e32 v46, 16, v20
	v_and_b32_e32 v47, 0xffff0000, v20
	v_add_f32 v44, v44, v46
	v_add_f32 v45, v45, v47
	v_lshlrev_b32_e32 v46, 16, v24
	v_and_b32_e32 v47, 0xffff0000, v24
	v_add_f32 v44, v44, v46
	v_add_f32 v45, v45, v47
	v_lshlrev_b32_e32 v46, 16, v28
	v_and_b32_e32 v47, 0xffff0000, v28
	v_lshlrev_b32_e32 v40, 16, v5
	v_and_b32_e32 v41, 0xffff0000, v5
	v_add_f32 v44, v44, v46
	v_add_f32 v45, v45, v47
	v_lshlrev_b32_e32 v46, 16, v32
	v_and_b32_e32 v47, 0xffff0000, v32
	v_add_f32 v44, v44, v46
	v_add_f32 v45, v45, v47
	v_pk_add_f32 v[46:47], v[40:41], 0 op_sel_hi:[1,0]
	v_lshlrev_b32_e32 v48, 16, v9
	v_and_b32_e32 v49, 0xffff0000, v9
	v_add_f32 v46, v46, v48
	v_add_f32 v47, v47, v49
	v_lshlrev_b32_e32 v48, 16, v13
	v_and_b32_e32 v49, 0xffff0000, v13
	v_add_f32 v46, v46, v48
	v_add_f32 v47, v47, v49
	v_lshlrev_b32_e32 v48, 16, v17
	v_and_b32_e32 v49, 0xffff0000, v17
	v_add_f32 v46, v46, v48
	v_add_f32 v47, v47, v49
	v_lshlrev_b32_e32 v48, 16, v21
	v_and_b32_e32 v49, 0xffff0000, v21
	v_add_f32 v46, v46, v48
	v_add_f32 v47, v47, v49
	v_lshlrev_b32_e32 v48, 16, v25
	v_and_b32_e32 v49, 0xffff0000, v25
	v_add_f32 v46, v46, v48
	v_add_f32 v47, v47, v49
	v_lshlrev_b32_e32 v48, 16, v29
	v_and_b32_e32 v49, 0xffff0000, v29
	v_lshlrev_b32_e32 v38, 16, v6
	v_and_b32_e32 v39, 0xffff0000, v6
	v_add_f32 v46, v46, v48
	v_add_f32 v47, v47, v49
	v_lshlrev_b32_e32 v48, 16, v33
	v_and_b32_e32 v49, 0xffff0000, v33
	v_add_f32 v46, v46, v48
	v_add_f32 v47, v47, v49
	v_pk_add_f32 v[48:49], v[38:39], 0 op_sel_hi:[1,0]
	v_lshlrev_b32_e32 v50, 16, v10
	v_and_b32_e32 v51, 0xffff0000, v10
	v_add_f32 v48, v48, v50
	v_add_f32 v49, v49, v51
	v_lshlrev_b32_e32 v50, 16, v14
	v_and_b32_e32 v51, 0xffff0000, v14
	v_add_f32 v48, v48, v50
	v_add_f32 v49, v49, v51
	v_lshlrev_b32_e32 v50, 16, v18
	v_and_b32_e32 v51, 0xffff0000, v18
	v_add_f32 v48, v48, v50
	v_add_f32 v49, v49, v51
	v_lshlrev_b32_e32 v50, 16, v22
	v_and_b32_e32 v51, 0xffff0000, v22
	v_add_f32 v48, v48, v50
	v_add_f32 v49, v49, v51
	v_lshlrev_b32_e32 v50, 16, v26
	v_and_b32_e32 v51, 0xffff0000, v26
	v_add_f32 v48, v48, v50
	v_add_f32 v49, v49, v51
	v_lshlrev_b32_e32 v50, 16, v30
	v_and_b32_e32 v51, 0xffff0000, v30
	v_lshlrev_b32_e32 v36, 16, v7
	v_and_b32_e32 v37, 0xffff0000, v7
	v_add_f32 v48, v48, v50
	v_add_f32 v49, v49, v51
	v_lshlrev_b32_e32 v50, 16, v34
	v_and_b32_e32 v51, 0xffff0000, v34
	v_add_f32 v48, v48, v50
	v_add_f32 v49, v49, v51
	v_pk_add_f32 v[50:51], v[36:37], 0 op_sel_hi:[1,0]
	v_lshlrev_b32_e32 v52, 16, v11
	v_and_b32_e32 v53, 0xffff0000, v11
	v_add_f32 v50, v50, v52
	v_add_f32 v51, v51, v53
	v_lshlrev_b32_e32 v52, 16, v15
	v_and_b32_e32 v53, 0xffff0000, v15
	v_add_f32 v50, v50, v52
	v_add_f32 v51, v51, v53
	v_lshlrev_b32_e32 v52, 16, v19
	v_and_b32_e32 v53, 0xffff0000, v19
	v_add_f32 v50, v50, v52
	v_add_f32 v51, v51, v53
	v_lshlrev_b32_e32 v52, 16, v23
	v_and_b32_e32 v53, 0xffff0000, v23
	v_add_f32 v50, v50, v52
	v_add_f32 v51, v51, v53
	v_lshlrev_b32_e32 v52, 16, v27
	v_and_b32_e32 v53, 0xffff0000, v27
	v_add_f32 v50, v50, v52
	v_add_f32 v51, v51, v53
	v_lshlrev_b32_e32 v52, 16, v31
	v_and_b32_e32 v53, 0xffff0000, v31
	v_add_f32 v50, v50, v52
	v_add_f32 v51, v51, v53
	v_lshlrev_b32_e32 v52, 16, v35
	v_and_b32_e32 v53, 0xffff0000, v35
	s_movk_i32 s14, 0x3fff
	v_add_f32 v50, v50, v52
	v_add_f32 v51, v51, v53
	v_cmp_lt_i32_e32 vcc, s14, v82
	s_and_saveexec_b64 s[14:15], vcc
	s_cbranch_execz .LBB0_2423
	v_and_b32_e32 v56, 7, v82
	v_add_u32_e32 v52, 0xffffc000, v82
	v_mov_b32_e32 v71, v2
	v_lshrrev_b32_e32 v54, 3, v52
	v_lshl_add_u64 v[52:53], v[70:71], 2, s[6:7]
	v_cmp_eq_u32_e32 vcc, 0, v56
	s_and_saveexec_b64 s[16:17], vcc
	s_cbranch_execz .LBB0_2410
	s_mov_b32 s18, 0xb400
	v_mad_u64_u32 v[62:63], s[18:19], v54, s18, v[52:53]
	v_add_co_u32_e32 v58, vcc, 0xa000, v62
	s_mov_b64 s[18:19], 0xa800
	s_nop 0
	v_addc_co_u32_e32 v59, vcc, 0, v63, vcc
	v_lshl_add_u64 v[62:63], v[62:63], 0, s[18:19]
	global_load_dwordx4 v[58:61], v[58:59], off offset:2048
	s_nop 0
	global_load_dwordx4 v[62:65], v[62:63], off offset:16
	s_waitcnt vmcnt(1)
	v_add_f32 v44, v44, v58
	v_add_f32 v45, v45, v59
	v_add_f32 v46, v46, v60
	v_add_f32 v47, v47, v61
	s_waitcnt vmcnt(0)
	v_add_f32 v48, v48, v62
	v_add_f32 v49, v49, v63
	v_add_f32 v50, v50, v64
	v_add_f32 v51, v51, v65
.LBB0_2410:
	s_or_b64 exec, exec, s[16:17]
	v_mad_u64_u32 v[54:55], s[16:17], v54, 15, 15
	v_cmp_gt_u32_e32 vcc, 2, v56
	s_and_saveexec_b64 s[16:17], vcc
	s_cbranch_execz .LBB0_2416
	v_or_b32_e32 v58, -2, v82
	v_ashrrev_i32_e32 v59, 31, v58
	v_lshl_add_u64 v[58:59], v[54:55], 0, v[58:59]
	v_mad_u64_u32 v[62:63], s[18:19], v58, s91, v[52:53]
	v_mov_b32_e32 v58, v63
	v_mad_u64_u32 v[58:59], s[18:19], v59, s91, v[58:59]
	v_mov_b32_e32 v63, v58
	global_load_dwordx4 v[58:61], v[62:63], off offset:16
	s_nop 0
	global_load_dwordx4 v[62:65], v[62:63], off
	s_waitcnt vmcnt(1)
	v_add_f32 v50, v50, v60
	v_add_f32 v51, v51, v61
	s_waitcnt vmcnt(0)
	v_add_f32 v46, v46, v64
	v_add_f32 v47, v47, v65
	v_add_f32 v48, v48, v58
	v_add_f32 v49, v49, v59
	v_add_f32 v44, v44, v62
	v_add_f32 v45, v45, v63
	s_or_b64 exec, exec, s[16:17]
	v_cmp_gt_u32_e32 vcc, 3, v56
	s_and_saveexec_b64 s[16:17], vcc
	s_cbranch_execnz .LBB0_2417

.LBB0_2413:
	v_or_b32_e32 v58, -4, v82
	v_ashrrev_i32_e32 v59, 31, v58
	v_lshl_add_u64 v[58:59], v[54:55], 0, v[58:59]
	v_mad_u64_u32 v[62:63], s[18:19], v58, s91, v[52:53]
	v_mov_b32_e32 v58, v63
	v_mad_u64_u32 v[58:59], s[18:19], v59, s91, v[58:59]
	v_mov_b32_e32 v63, v58
	global_load_dwordx4 v[58:61], v[62:63], off offset:16
	s_nop 0
	global_load_dwordx4 v[62:65], v[62:63], off
	s_waitcnt vmcnt(1)
	v_add_f32 v50, v50, v60
	v_add_f32 v51, v51, v61
	s_waitcnt vmcnt(0)
	v_add_f32 v46, v46, v64
	v_add_f32 v47, v47, v65
	v_add_f32 v48, v48, v58
	v_add_f32 v49, v49, v59
	v_add_f32 v44, v44, v62
	v_add_f32 v45, v45, v63
	s_or_b64 exec, exec, s[16:17]
	v_cmp_gt_u32_e32 vcc, 5, v56
	s_and_saveexec_b64 s[16:17], vcc
	s_cbranch_execnz .LBB0_2419

.LBB0_2415:
	v_add_u32_e32 v58, -6, v56
	v_ashrrev_i32_e32 v59, 31, v58
	v_lshl_add_u64 v[58:59], v[54:55], 0, v[58:59]
	v_mad_u64_u32 v[62:63], s[18:19], v58, s91, v[52:53]
	v_mov_b32_e32 v58, v63
	v_mad_u64_u32 v[58:59], s[18:19], v59, s91, v[58:59]
	v_mov_b32_e32 v63, v58
	global_load_dwordx4 v[58:61], v[62:63], off offset:16
	s_nop 0
	global_load_dwordx4 v[62:65], v[62:63], off
	s_waitcnt vmcnt(1)
	v_add_f32 v50, v50, v60
	v_add_f32 v51, v51, v61
	s_waitcnt vmcnt(0)
	v_add_f32 v46, v46, v64
	v_add_f32 v47, v47, v65
	v_add_f32 v48, v48, v58
	v_add_f32 v49, v49, v59
	v_add_f32 v44, v44, v62
	v_add_f32 v45, v45, v63
	s_or_b64 exec, exec, s[16:17]
	v_cmp_ne_u32_e32 vcc, 7, v56
	s_and_saveexec_b64 s[16:17], vcc
	s_cbranch_execnz .LBB0_2421
	s_branch .LBB0_2422

.LBB0_2417:
	v_add_u32_e32 v58, -3, v56
	v_ashrrev_i32_e32 v59, 31, v58
	v_lshl_add_u64 v[58:59], v[54:55], 0, v[58:59]
	v_mad_u64_u32 v[62:63], s[18:19], v58, s91, v[52:53]
	v_mov_b32_e32 v58, v63
	v_mad_u64_u32 v[58:59], s[18:19], v59, s91, v[58:59]
	v_mov_b32_e32 v63, v58
	global_load_dwordx4 v[58:61], v[62:63], off offset:16
	s_nop 0
	global_load_dwordx4 v[62:65], v[62:63], off
	s_waitcnt vmcnt(1)
	v_add_f32 v50, v50, v60
	v_add_f32 v51, v51, v61
	s_waitcnt vmcnt(0)
	v_add_f32 v46, v46, v64
	v_add_f32 v47, v47, v65
	v_add_f32 v48, v48, v58
	v_add_f32 v49, v49, v59
	v_add_f32 v44, v44, v62
	v_add_f32 v45, v45, v63
	s_or_b64 exec, exec, s[16:17]
	v_cmp_gt_u32_e32 vcc, 4, v56
	s_and_saveexec_b64 s[16:17], vcc
	s_cbranch_execnz .LBB0_2413

.LBB0_2419:
	v_add_u32_e32 v58, -5, v56
	v_ashrrev_i32_e32 v59, 31, v58
	v_lshl_add_u64 v[58:59], v[54:55], 0, v[58:59]
	v_mad_u64_u32 v[62:63], s[18:19], v58, s91, v[52:53]
	v_mov_b32_e32 v58, v63
	v_mad_u64_u32 v[58:59], s[18:19], v59, s91, v[58:59]
	v_mov_b32_e32 v63, v58
	global_load_dwordx4 v[58:61], v[62:63], off offset:16
	s_nop 0
	global_load_dwordx4 v[62:65], v[62:63], off
	s_waitcnt vmcnt(1)
	v_add_f32 v50, v50, v60
	v_add_f32 v51, v51, v61
	s_waitcnt vmcnt(0)
	v_add_f32 v46, v46, v64
	v_add_f32 v47, v47, v65
	v_add_f32 v48, v48, v58
	v_add_f32 v49, v49, v59
	v_add_f32 v44, v44, v62
	v_add_f32 v45, v45, v63
	s_or_b64 exec, exec, s[16:17]
	v_cmp_gt_u32_e32 vcc, 6, v56
	s_and_saveexec_b64 s[16:17], vcc
	s_cbranch_execnz .LBB0_2415

.LBB0_2421:
	v_add_u32_e32 v56, -7, v56
	v_ashrrev_i32_e32 v57, 31, v56
	v_lshl_add_u64 v[54:55], v[54:55], 0, v[56:57]
	v_mad_u64_u32 v[56:57], s[18:19], v54, s91, v[52:53]
	v_mov_b32_e32 v52, v57
	v_mad_u64_u32 v[52:53], s[18:19], v55, s91, v[52:53]
	v_mov_b32_e32 v57, v52
	global_load_dwordx4 v[52:55], v[56:57], off offset:16
	s_nop 0
	global_load_dwordx4 v[56:59], v[56:57], off
	s_waitcnt vmcnt(1)
	v_add_f32 v50, v50, v54
	v_add_f32 v51, v51, v55
	s_waitcnt vmcnt(0)
	v_add_f32 v46, v46, v58
	v_add_f32 v47, v47, v59
	v_add_f32 v48, v48, v52
	v_add_f32 v49, v49, v53
	v_add_f32 v44, v44, v56
	v_add_f32 v45, v45, v57

.LBB0_2426:
	s_or_b64 exec, exec, s[8:9]
	v_fma_f32 v68, v82, v84, -v68
	v_fma_f32 v69, v83, v84, -v69
	v_fma_f32 v74, v76, v84, -v74
	v_fma_f32 v75, v77, v84, -v75
	v_cvt_pk_bf16_f32 v77, v68, v69
	v_mov_b64_e32 v[68:69], s[40:41]
	v_fma_f32 v72, v78, v84, -v72
	v_fma_f32 v73, v79, v84, -v73
	v_fma_f32 v70, v80, v84, -v70
	v_fma_f32 v71, v81, v84, -v71
	v_mad_i64_i32 v[68:69], s[8:9], v133, s71, v[68:69]
	v_mov_b32_e32 v135, v2
	v_cvt_pk_bf16_f32 v74, v74, v75
	v_cvt_pk_bf16_f32 v75, v72, v73
	v_cvt_pk_bf16_f32 v76, v70, v71
	v_lshl_add_u64 v[68:69], v[134:135], 1, v[68:69]
	global_store_dwordx4 v[68:69], v[74:77], off

.LBB0_2494:
	s_or_b64 exec, exec, s[0:1]
	s_waitcnt vmcnt(0)
	v_lshlrev_b32_e32 v144, 16, v92
	v_and_b32_e32 v145, 0xffff0000, v92
	v_lshlrev_b32_e32 v142, 16, v93
	v_and_b32_e32 v143, 0xffff0000, v93
	v_lshlrev_b32_e32 v140, 16, v94
	v_and_b32_e32 v141, 0xffff0000, v94
	v_lshlrev_b32_e32 v92, 16, v95
	v_and_b32_e32 v93, 0xffff0000, v95
	v_pk_add_f32 v[94:95], v[144:145], 0 op_sel_hi:[1,0]
	v_lshlrev_b32_e32 v148, 16, v72
	v_and_b32_e32 v149, 0xffff0000, v72
	v_add_f32 v94, v94, v148
	v_add_f32 v95, v95, v149
	v_lshlrev_b32_e32 v148, 16, v68
	v_and_b32_e32 v149, 0xffff0000, v68
	v_add_f32 v94, v94, v148
	v_add_f32 v95, v95, v149
	v_lshlrev_b32_e32 v148, 16, v84
	v_and_b32_e32 v149, 0xffff0000, v84
	v_add_f32 v94, v94, v148
	v_add_f32 v95, v95, v149
	v_lshlrev_b32_e32 v148, 16, v76
	v_and_b32_e32 v149, 0xffff0000, v76
	v_add_f32 v94, v94, v148
	v_add_f32 v95, v95, v149
	v_lshlrev_b32_e32 v148, 16, v104
	v_and_b32_e32 v149, 0xffff0000, v104
	v_add_f32 v94, v94, v148
	v_add_f32 v95, v95, v149
	v_pk_add_f32 v[148:149], v[142:143], 0 op_sel_hi:[1,0]
	v_lshlrev_b32_e32 v72, 16, v73
	v_and_b32_e32 v73, 0xffff0000, v73
	v_add_f32 v72, v148, v72
	v_add_f32 v73, v149, v73
	v_lshlrev_b32_e32 v68, 16, v69
	v_and_b32_e32 v69, 0xffff0000, v69
	v_add_f32 v68, v72, v68
	v_add_f32 v69, v73, v69
	v_lshlrev_b32_e32 v72, 16, v85
	v_and_b32_e32 v73, 0xffff0000, v85
	v_add_f32 v68, v68, v72
	v_add_f32 v69, v69, v73
	v_lshlrev_b32_e32 v72, 16, v77
	v_and_b32_e32 v73, 0xffff0000, v77
	v_add_f32 v68, v68, v72
	v_add_f32 v69, v69, v73
	v_lshlrev_b32_e32 v72, 16, v105
	v_and_b32_e32 v73, 0xffff0000, v105
	v_add_f32 v72, v68, v72
	v_add_f32 v73, v69, v73
	v_pk_add_f32 v[68:69], v[140:141], 0 op_sel_hi:[1,0]
	v_lshlrev_b32_e32 v76, 16, v74
	v_and_b32_e32 v77, 0xffff0000, v74
	v_add_f32 v68, v68, v76
	v_add_f32 v69, v69, v77
	v_lshlrev_b32_e32 v76, 16, v70
	v_and_b32_e32 v77, 0xffff0000, v70
	v_add_f32 v68, v68, v76
	v_add_f32 v69, v69, v77
	v_lshlrev_b32_e32 v76, 16, v86
	v_and_b32_e32 v77, 0xffff0000, v86
	v_add_f32 v68, v68, v76
	v_add_f32 v69, v69, v77
	v_lshlrev_b32_e32 v76, 16, v78
	v_and_b32_e32 v77, 0xffff0000, v78
	v_add_f32 v68, v68, v76
	v_add_f32 v69, v69, v77
	v_lshlrev_b32_e32 v76, 16, v106
	v_and_b32_e32 v77, 0xffff0000, v106
	v_add_f32 v76, v68, v76
	v_add_f32 v77, v69, v77
	v_pk_add_f32 v[68:69], v[92:93], 0 op_sel_hi:[1,0]
	v_lshlrev_b32_e32 v74, 16, v75
	v_and_b32_e32 v75, 0xffff0000, v75
	v_add_f32 v68, v68, v74
	v_add_f32 v69, v69, v75
	v_lshlrev_b32_e32 v70, 16, v71
	v_and_b32_e32 v71, 0xffff0000, v71
	v_add_f32 v68, v68, v70
	v_add_f32 v69, v69, v71
	v_lshlrev_b32_e32 v70, 16, v87
	v_and_b32_e32 v71, 0xffff0000, v87
	v_add_f32 v68, v68, v70
	v_add_f32 v69, v69, v71
	v_lshlrev_b32_e32 v70, 16, v79
	v_and_b32_e32 v71, 0xffff0000, v79
	v_add_f32 v68, v68, v70
	v_add_f32 v69, v69, v71
	v_lshlrev_b32_e32 v70, 16, v107
	v_and_b32_e32 v71, 0xffff0000, v107
	v_add_f32 v74, v68, v70
	v_add_f32 v75, v69, v71
	v_lshlrev_b32_e32 v70, 16, v97
	v_and_b32_e32 v71, 0xffff0000, v97
	v_lshlrev_b32_e32 v68, 16, v96
	v_and_b32_e32 v69, 0xffff0000, v96
	v_lshlrev_b32_e32 v96, 16, v117
	v_and_b32_e32 v97, 0xffff0000, v117
	v_add_f32 v70, v72, v70
	v_add_f32 v71, v73, v71
	v_lshlrev_b32_e32 v106, 16, v112
	v_and_b32_e32 v107, 0xffff0000, v112
	v_lshlrev_b32_e32 v112, 16, v113
	v_and_b32_e32 v113, 0xffff0000, v113
	v_add_f32 v70, v70, v96
	v_add_f32 v71, v71, v97
	v_lshlrev_b32_e32 v72, 16, v89
	v_add_f32 v70, v70, v112
	v_add_f32 v71, v71, v113
	v_and_b32_e32 v73, 0xffff0000, v89
	v_add_f32 v70, v70, v72
	v_add_f32 v71, v71, v73
	v_lshlrev_b32_e32 v72, 16, v81
	v_and_b32_e32 v73, 0xffff0000, v81
	v_add_f32 v70, v70, v72
	v_add_f32 v71, v71, v73
	v_lshlrev_b32_e32 v72, 16, v109
	v_and_b32_e32 v73, 0xffff0000, v109
	v_add_f32 v70, v70, v72
	v_add_f32 v71, v71, v73
	v_lshlrev_b32_e32 v72, 16, v101
	v_and_b32_e32 v73, 0xffff0000, v101
	v_add_f32 v70, v70, v72
	v_add_f32 v71, v71, v73
	v_lshlrev_b32_e32 v72, 16, v125
	v_and_b32_e32 v73, 0xffff0000, v125
	v_add_f32 v70, v70, v72
	v_add_f32 v71, v71, v73
	v_lshlrev_b32_e32 v72, 16, v121
	v_and_b32_e32 v73, 0xffff0000, v121
	v_lshlrev_b32_e32 v78, 16, v98
	v_and_b32_e32 v79, 0xffff0000, v98
	v_add_f32 v70, v70, v72
	v_add_f32 v71, v71, v73
	v_lshlrev_b32_e32 v72, 16, v129
	v_and_b32_e32 v73, 0xffff0000, v129
	v_lshlrev_b32_e32 v84, 16, v99
	v_and_b32_e32 v85, 0xffff0000, v99
	v_lshlrev_b32_e32 v98, 16, v118
	v_and_b32_e32 v99, 0xffff0000, v118
	v_add_f32 v70, v70, v72
	v_add_f32 v71, v71, v73
	v_add_f32 v72, v76, v78
	v_add_f32 v73, v77, v79
	v_lshlrev_b32_e32 v86, 16, v116
	v_and_b32_e32 v87, 0xffff0000, v116
	v_lshlrev_b32_e32 v116, 16, v114
	v_and_b32_e32 v117, 0xffff0000, v114
	v_add_f32 v72, v72, v98
	v_add_f32 v73, v73, v99
	v_lshlrev_b32_e32 v76, 16, v90
	v_add_f32 v72, v72, v116
	v_add_f32 v73, v73, v117
	v_and_b32_e32 v77, 0xffff0000, v90
	v_add_f32 v72, v72, v76
	v_add_f32 v73, v73, v77
	v_lshlrev_b32_e32 v76, 16, v82
	v_and_b32_e32 v77, 0xffff0000, v82
	v_add_f32 v72, v72, v76
	v_add_f32 v73, v73, v77
	v_lshlrev_b32_e32 v76, 16, v110
	v_and_b32_e32 v77, 0xffff0000, v110
	v_add_f32 v72, v72, v76
	v_add_f32 v73, v73, v77
	v_lshlrev_b32_e32 v76, 16, v102
	v_and_b32_e32 v77, 0xffff0000, v102
	v_add_f32 v72, v72, v76
	v_add_f32 v73, v73, v77
	v_lshlrev_b32_e32 v76, 16, v126
	v_and_b32_e32 v77, 0xffff0000, v126
	v_lshlrev_b32_e32 v104, 16, v119
	v_and_b32_e32 v105, 0xffff0000, v119
	v_add_f32 v68, v94, v68
	v_add_f32 v69, v95, v69
	v_add_f32 v72, v72, v76
	v_add_f32 v73, v73, v77
	v_lshlrev_b32_e32 v76, 16, v122
	v_and_b32_e32 v77, 0xffff0000, v122
	v_add_f32 v74, v74, v84
	v_add_f32 v75, v75, v85
	v_lshlrev_b32_e32 v114, 16, v115
	v_and_b32_e32 v115, 0xffff0000, v115
	v_add_f32 v68, v68, v86
	v_add_f32 v69, v69, v87
	v_add_f32 v72, v72, v76
	v_add_f32 v73, v73, v77
	v_lshlrev_b32_e32 v76, 16, v130
	v_and_b32_e32 v77, 0xffff0000, v130
	v_add_f32 v74, v74, v104
	v_add_f32 v75, v75, v105
	v_add_f32 v68, v68, v106
	v_add_f32 v69, v69, v107
	v_lshlrev_b32_e32 v86, 16, v88
	v_and_b32_e32 v87, 0xffff0000, v88
	v_add_f32 v72, v72, v76
	v_add_f32 v73, v73, v77
	v_add_f32 v74, v74, v114
	v_add_f32 v75, v75, v115
	v_lshlrev_b32_e32 v76, 16, v91
	v_and_b32_e32 v77, 0xffff0000, v91
	v_add_f32 v68, v68, v86
	v_add_f32 v69, v69, v87
	v_lshlrev_b32_e32 v86, 16, v80
	v_and_b32_e32 v87, 0xffff0000, v80
	v_add_f32 v74, v74, v76
	v_add_f32 v75, v75, v77
	v_lshlrev_b32_e32 v76, 16, v83
	v_and_b32_e32 v77, 0xffff0000, v83
	v_add_f32 v68, v68, v86
	v_add_f32 v69, v69, v87
	v_lshlrev_b32_e32 v86, 16, v108
	v_and_b32_e32 v87, 0xffff0000, v108
	v_add_f32 v74, v74, v76
	v_add_f32 v75, v75, v77
	v_lshlrev_b32_e32 v76, 16, v111
	v_and_b32_e32 v77, 0xffff0000, v111
	v_add_f32 v68, v68, v86
	v_add_f32 v69, v69, v87
	v_lshlrev_b32_e32 v86, 16, v100
	v_and_b32_e32 v87, 0xffff0000, v100
	v_add_f32 v74, v74, v76
	v_add_f32 v75, v75, v77
	v_lshlrev_b32_e32 v76, 16, v103
	v_and_b32_e32 v77, 0xffff0000, v103
	v_add_f32 v68, v68, v86
	v_add_f32 v69, v69, v87
	v_lshlrev_b32_e32 v86, 16, v124
	v_and_b32_e32 v87, 0xffff0000, v124
	v_add_f32 v74, v74, v76
	v_add_f32 v75, v75, v77
	v_lshlrev_b32_e32 v76, 16, v127
	v_and_b32_e32 v77, 0xffff0000, v127
	v_mad_i64_i32 v[138:139], s[0:1], v138, s71, 0
	v_add_f32 v68, v68, v86
	v_add_f32 v69, v69, v87
	v_lshlrev_b32_e32 v86, 16, v120
	v_and_b32_e32 v87, 0xffff0000, v120
	v_add_f32 v74, v74, v76
	v_add_f32 v75, v75, v77
	v_lshlrev_b32_e32 v76, 16, v123
	v_and_b32_e32 v77, 0xffff0000, v123
	v_add_f32 v68, v68, v86
	v_add_f32 v69, v69, v87
	v_lshlrev_b32_e32 v86, 16, v128
	v_and_b32_e32 v87, 0xffff0000, v128
	v_add_f32 v74, v74, v76
	v_add_f32 v75, v75, v77
	v_lshlrev_b32_e32 v76, 16, v131
	v_and_b32_e32 v77, 0xffff0000, v131
	s_movk_i32 s0, 0xffe8
	v_add_f32 v68, v68, v86
	v_add_f32 v69, v69, v87
	v_add_f32 v74, v74, v76
	v_add_f32 v75, v75, v77
	v_cmp_lt_i32_e32 vcc, s0, v3
	s_and_saveexec_b64 s[0:1], vcc
	s_cbranch_execz .LBB0_2510
	v_and_b32_e32 v80, 7, v146
	v_lshrrev_b32_e32 v78, 3, v146
	v_lshl_add_u64 v[76:77], v[136:137], 2, s[6:7]
	v_cmp_eq_u32_e32 vcc, 0, v80
	s_and_saveexec_b64 s[8:9], vcc
	s_cbranch_execz .LBB0_2497
	s_mov_b32 s14, 0xb400
	v_mad_u64_u32 v[86:87], s[14:15], v78, s14, v[76:77]
	v_add_co_u32_e32 v82, vcc, 0xa000, v86
	s_mov_b64 s[14:15], 0xa800
	s_nop 0
	v_addc_co_u32_e32 v83, vcc, 0, v87, vcc
	v_lshl_add_u64 v[86:87], v[86:87], 0, s[14:15]
	global_load_dwordx4 v[82:85], v[82:83], off offset:2048
	s_nop 0
	global_load_dwordx4 v[86:89], v[86:87], off offset:16
	s_waitcnt vmcnt(1)
	v_add_f32 v68, v68, v82
	v_add_f32 v69, v69, v83
	v_add_f32 v70, v70, v84
	v_add_f32 v71, v71, v85
	s_waitcnt vmcnt(0)
	v_add_f32 v72, v72, v86
	v_add_f32 v73, v73, v87
	v_add_f32 v74, v74, v88
	v_add_f32 v75, v75, v89
.LBB0_2497:
	s_or_b64 exec, exec, s[8:9]
	v_mad_u64_u32 v[78:79], s[8:9], v78, 15, 15
	v_cmp_gt_u32_e32 vcc, 2, v80
	s_and_saveexec_b64 s[8:9], vcc
	s_cbranch_execz .LBB0_2503
	v_or_b32_e32 v82, -2, v146
	v_ashrrev_i32_e32 v83, 31, v82
	v_lshl_add_u64 v[82:83], v[78:79], 0, v[82:83]
	v_mad_u64_u32 v[86:87], s[14:15], v82, s91, v[76:77]
	v_mov_b32_e32 v82, v87
	v_mad_u64_u32 v[82:83], s[14:15], v83, s91, v[82:83]
	v_mov_b32_e32 v87, v82
	global_load_dwordx4 v[82:85], v[86:87], off offset:16
	s_nop 0
	global_load_dwordx4 v[86:89], v[86:87], off
	s_waitcnt vmcnt(1)
	v_add_f32 v74, v74, v84
	v_add_f32 v75, v75, v85
	s_waitcnt vmcnt(0)
	v_add_f32 v70, v70, v88
	v_add_f32 v71, v71, v89
	v_add_f32 v72, v72, v82
	v_add_f32 v73, v73, v83
	v_add_f32 v68, v68, v86
	v_add_f32 v69, v69, v87
	s_or_b64 exec, exec, s[8:9]
	v_cmp_gt_u32_e32 vcc, 3, v80
	s_and_saveexec_b64 s[8:9], vcc
	s_cbranch_execnz .LBB0_2504

.LBB0_2500:
	v_or_b32_e32 v82, -4, v146
	v_ashrrev_i32_e32 v83, 31, v82
	v_lshl_add_u64 v[82:83], v[78:79], 0, v[82:83]
	v_mad_u64_u32 v[86:87], s[14:15], v82, s91, v[76:77]
	v_mov_b32_e32 v82, v87
	v_mad_u64_u32 v[82:83], s[14:15], v83, s91, v[82:83]
	v_mov_b32_e32 v87, v82
	global_load_dwordx4 v[82:85], v[86:87], off offset:16
	s_nop 0
	global_load_dwordx4 v[86:89], v[86:87], off
	s_waitcnt vmcnt(1)
	v_add_f32 v74, v74, v84
	v_add_f32 v75, v75, v85
	s_waitcnt vmcnt(0)
	v_add_f32 v70, v70, v88
	v_add_f32 v71, v71, v89
	v_add_f32 v72, v72, v82
	v_add_f32 v73, v73, v83
	v_add_f32 v68, v68, v86
	v_add_f32 v69, v69, v87
	s_or_b64 exec, exec, s[8:9]
	v_cmp_gt_u32_e32 vcc, 5, v80
	s_and_saveexec_b64 s[8:9], vcc
	s_cbranch_execnz .LBB0_2506

.LBB0_2502:
	v_add_u32_e32 v82, -6, v80
	v_ashrrev_i32_e32 v83, 31, v82
	v_lshl_add_u64 v[82:83], v[78:79], 0, v[82:83]
	v_mad_u64_u32 v[86:87], s[14:15], v82, s91, v[76:77]
	v_mov_b32_e32 v82, v87
	v_mad_u64_u32 v[82:83], s[14:15], v83, s91, v[82:83]
	v_mov_b32_e32 v87, v82
	global_load_dwordx4 v[82:85], v[86:87], off offset:16
	s_nop 0
	global_load_dwordx4 v[86:89], v[86:87], off
	s_waitcnt vmcnt(1)
	v_add_f32 v74, v74, v84
	v_add_f32 v75, v75, v85
	s_waitcnt vmcnt(0)
	v_add_f32 v70, v70, v88
	v_add_f32 v71, v71, v89
	v_add_f32 v72, v72, v82
	v_add_f32 v73, v73, v83
	v_add_f32 v68, v68, v86
	v_add_f32 v69, v69, v87
	s_or_b64 exec, exec, s[8:9]
	v_cmp_ne_u32_e32 vcc, 7, v80
	s_and_saveexec_b64 s[8:9], vcc
	s_cbranch_execnz .LBB0_2508
	s_branch .LBB0_2509

.LBB0_2504:
	v_add_u32_e32 v82, -3, v80
	v_ashrrev_i32_e32 v83, 31, v82
	v_lshl_add_u64 v[82:83], v[78:79], 0, v[82:83]
	v_mad_u64_u32 v[86:87], s[14:15], v82, s91, v[76:77]
	v_mov_b32_e32 v82, v87
	v_mad_u64_u32 v[82:83], s[14:15], v83, s91, v[82:83]
	v_mov_b32_e32 v87, v82
	global_load_dwordx4 v[82:85], v[86:87], off offset:16
	s_nop 0
	global_load_dwordx4 v[86:89], v[86:87], off
	s_waitcnt vmcnt(1)
	v_add_f32 v74, v74, v84
	v_add_f32 v75, v75, v85
	s_waitcnt vmcnt(0)
	v_add_f32 v70, v70, v88
	v_add_f32 v71, v71, v89
	v_add_f32 v72, v72, v82
	v_add_f32 v73, v73, v83
	v_add_f32 v68, v68, v86
	v_add_f32 v69, v69, v87
	s_or_b64 exec, exec, s[8:9]
	v_cmp_gt_u32_e32 vcc, 4, v80
	s_and_saveexec_b64 s[8:9], vcc
	s_cbranch_execnz .LBB0_2500

.LBB0_2506:
	v_add_u32_e32 v82, -5, v80
	v_ashrrev_i32_e32 v83, 31, v82
	v_lshl_add_u64 v[82:83], v[78:79], 0, v[82:83]
	v_mad_u64_u32 v[86:87], s[14:15], v82, s91, v[76:77]
	v_mov_b32_e32 v82, v87
	v_mad_u64_u32 v[82:83], s[14:15], v83, s91, v[82:83]
	v_mov_b32_e32 v87, v82
	global_load_dwordx4 v[82:85], v[86:87], off offset:16
	s_nop 0
	global_load_dwordx4 v[86:89], v[86:87], off
	s_waitcnt vmcnt(1)
	v_add_f32 v74, v74, v84
	v_add_f32 v75, v75, v85
	s_waitcnt vmcnt(0)
	v_add_f32 v70, v70, v88
	v_add_f32 v71, v71, v89
	v_add_f32 v72, v72, v82
	v_add_f32 v73, v73, v83
	v_add_f32 v68, v68, v86
	v_add_f32 v69, v69, v87
	s_or_b64 exec, exec, s[8:9]
	v_cmp_gt_u32_e32 vcc, 6, v80
	s_and_saveexec_b64 s[8:9], vcc
	s_cbranch_execnz .LBB0_2502

.LBB0_2508:
	v_add_u32_e32 v82, -7, v80
	v_ashrrev_i32_e32 v83, 31, v82
	v_lshl_add_u64 v[82:83], v[78:79], 0, v[82:83]
	v_mad_u64_u32 v[86:87], s[14:15], v82, s91, v[76:77]
	v_mov_b32_e32 v82, v87
	v_mad_u64_u32 v[82:83], s[14:15], v83, s91, v[82:83]
	v_mov_b32_e32 v87, v82
	global_load_dwordx4 v[82:85], v[86:87], off offset:16
	s_nop 0
	global_load_dwordx4 v[86:89], v[86:87], off
	s_waitcnt vmcnt(1)
	v_add_f32 v74, v74, v84
	v_add_f32 v75, v75, v85
	s_waitcnt vmcnt(0)
	v_add_f32 v70, v70, v88
	v_add_f32 v71, v71, v89
	v_add_f32 v72, v72, v82
	v_add_f32 v73, v73, v83
	v_add_f32 v68, v68, v86
	v_add_f32 v69, v69, v87
.LBB0_2509:
	s_or_b64 exec, exec, s[8:9]
	v_or_b32_e32 v82, -8, v146
	v_ashrrev_i32_e32 v83, 31, v82
	v_lshl_add_u64 v[82:83], v[78:79], 0, v[82:83]
	v_mad_u64_u32 v[86:87], s[8:9], v82, s91, v[76:77]
	v_mov_b32_e32 v82, v87
	v_mad_u64_u32 v[82:83], s[8:9], v83, s91, v[82:83]
	v_mov_b32_e32 v87, v82
	v_add_u32_e32 v82, -9, v80
	v_ashrrev_i32_e32 v83, 31, v82
	v_lshl_add_u64 v[82:83], v[78:79], 0, v[82:83]
	v_mad_u64_u32 v[90:91], s[8:9], v82, s91, v[76:77]
	v_mov_b32_e32 v82, v91
	v_mad_u64_u32 v[82:83], s[8:9], v83, s91, v[82:83]
	v_mov_b32_e32 v91, v82
	v_add_u32_e32 v82, -10, v80
	v_ashrrev_i32_e32 v83, 31, v82
	v_lshl_add_u64 v[82:83], v[78:79], 0, v[82:83]
	v_mad_u64_u32 v[106:107], s[8:9], v82, s91, v[76:77]
	v_mov_b32_e32 v82, v107
	v_mad_u64_u32 v[82:83], s[8:9], v83, s91, v[82:83]
	v_mov_b32_e32 v107, v82
	v_add_u32_e32 v82, -11, v80
	v_ashrrev_i32_e32 v83, 31, v82
	v_lshl_add_u64 v[82:83], v[78:79], 0, v[82:83]
	v_mad_u64_u32 v[114:115], s[8:9], v82, s91, v[76:77]
	v_mov_b32_e32 v82, v115
	v_mad_u64_u32 v[82:83], s[8:9], v83, s91, v[82:83]
	v_mov_b32_e32 v115, v82
	v_add_u32_e32 v82, -12, v80
	v_ashrrev_i32_e32 v83, 31, v82
	v_lshl_add_u64 v[82:83], v[78:79], 0, v[82:83]
	v_mad_u64_u32 v[122:123], s[8:9], v82, s91, v[76:77]
	v_mov_b32_e32 v82, v123
	v_mad_u64_u32 v[82:83], s[8:9], v83, s91, v[82:83]
	v_mov_b32_e32 v123, v82
	v_add_u32_e32 v82, -13, v80
	v_ashrrev_i32_e32 v83, 31, v82
	v_lshl_add_u64 v[82:83], v[78:79], 0, v[82:83]
	v_mad_u64_u32 v[126:127], s[8:9], v82, s91, v[76:77]
	v_mov_b32_e32 v82, v127
	v_mad_u64_u32 v[82:83], s[8:9], v83, s91, v[82:83]
	v_mov_b32_e32 v127, v82
	v_add_u32_e32 v82, -14, v80
	v_ashrrev_i32_e32 v83, 31, v82
	v_lshl_add_u64 v[110:111], v[78:79], 0, v[82:83]
	v_mad_u64_u32 v[130:131], s[8:9], v110, s91, v[76:77]
	global_load_dwordx4 v[82:85], v[86:87], off offset:16
	s_nop 0
	global_load_dwordx4 v[86:89], v[86:87], off
	s_nop 0
	global_load_dwordx4 v[94:97], v[90:91], off
	global_load_dwordx4 v[98:101], v[90:91], off offset:16
	v_mov_b32_e32 v90, v131
	v_add_u32_e32 v80, -15, v80
	v_mad_u64_u32 v[90:91], s[8:9], v111, s91, v[90:91]
	v_ashrrev_i32_e32 v81, 31, v80
	global_load_dwordx4 v[102:105], v[106:107], off offset:16
	s_nop 0
	global_load_dwordx4 v[106:109], v[106:107], off
	v_mov_b32_e32 v131, v90
	v_lshl_add_u64 v[90:91], v[78:79], 0, v[80:81]
	global_load_dwordx4 v[110:113], v[114:115], off
	s_nop 0
	global_load_dwordx4 v[114:117], v[114:115], off offset:16
	v_mad_u64_u32 v[76:77], s[8:9], v90, s91, v[76:77]
	global_load_dwordx4 v[118:121], v[122:123], off offset:16
	s_nop 0
	global_load_dwordx4 v[122:125], v[122:123], off
	v_mov_b32_e32 v90, v77
	global_load_dwordx4 v[78:81], v[126:127], off
	s_nop 0
	global_load_dwordx4 v[126:129], v[126:127], off offset:16
	v_mad_u64_u32 v[90:91], s[8:9], v91, s91, v[90:91]
	global_load_dwordx4 v[148:151], v[130:131], off offset:16
	global_load_dwordx4 v[152:155], v[130:131], off
	v_mov_b32_e32 v77, v90
	global_load_dwordx4 v[156:159], v[76:77], off offset:16
	global_load_dwordx4 v[160:163], v[76:77], off
	s_waitcnt vmcnt(15)
	v_add_f32 v74, v74, v84
	v_add_f32 v75, v75, v85
	s_waitcnt vmcnt(14)
	v_add_f32 v70, v70, v88
	v_add_f32 v71, v71, v89
	v_add_f32 v68, v68, v86
	v_add_f32 v69, v69, v87
	v_add_f32 v72, v72, v82
	v_add_f32 v73, v73, v83
	s_waitcnt vmcnt(12)
	v_add_f32 v74, v74, v100
	v_add_f32 v75, v75, v101
	v_add_f32 v70, v70, v96
	v_add_f32 v71, v71, v97
	v_add_f32 v72, v72, v98
	v_add_f32 v73, v73, v99
	v_add_f32 v68, v68, v94
	v_add_f32 v69, v69, v95
	s_waitcnt vmcnt(10)
	v_add_f32 v70, v70, v108
	v_add_f32 v71, v71, v109
	v_add_f32 v74, v74, v104
	v_add_f32 v75, v75, v105
	v_add_f32 v68, v68, v106
	v_add_f32 v69, v69, v107
	v_add_f32 v72, v72, v102
	v_add_f32 v73, v73, v103
	s_waitcnt vmcnt(8)
	v_add_f32 v74, v74, v116
	v_add_f32 v75, v75, v117
	v_add_f32 v70, v70, v112
	v_add_f32 v71, v71, v113
	v_add_f32 v72, v72, v114
	v_add_f32 v73, v73, v115
	v_add_f32 v68, v68, v110
	v_add_f32 v69, v69, v111
	s_waitcnt vmcnt(6)
	v_add_f32 v70, v70, v124
	v_add_f32 v71, v71, v125
	v_add_f32 v74, v74, v120
	v_add_f32 v75, v75, v121
	v_add_f32 v68, v68, v122
	v_add_f32 v69, v69, v123
	v_add_f32 v72, v72, v118
	v_add_f32 v73, v73, v119
	s_waitcnt vmcnt(4)
	v_add_f32 v74, v74, v128
	v_add_f32 v75, v75, v129
	v_add_f32 v70, v70, v80
	v_add_f32 v71, v71, v81
	v_add_f32 v72, v72, v126
	v_add_f32 v73, v73, v127
	v_add_f32 v68, v68, v78
	v_add_f32 v69, v69, v79
	s_waitcnt vmcnt(2)
	v_add_f32 v70, v70, v154
	v_add_f32 v71, v71, v155
	v_add_f32 v74, v74, v150
	v_add_f32 v75, v75, v151
	v_add_f32 v68, v68, v152
	v_add_f32 v69, v69, v153
	v_add_f32 v72, v72, v148
	v_add_f32 v73, v73, v149
	s_waitcnt vmcnt(1)
	v_add_f32 v74, v74, v158
	v_add_f32 v75, v75, v159
	s_waitcnt vmcnt(0)
	v_add_f32 v70, v70, v162
	v_add_f32 v71, v71, v163
	v_add_f32 v72, v72, v156
	v_add_f32 v73, v73, v157
	v_add_f32 v68, v68, v160
	v_add_f32 v69, v69, v161

.LBB0_2512:
	s_or_b64 exec, exec, s[0:1]
	v_fma_f32 v68, v68, v76, -v144
	v_fma_f32 v69, v69, v76, -v145
	v_fma_f32 v70, v70, v76, -v142
	v_fma_f32 v71, v71, v76, -v143
	v_cvt_pk_bf16_f32 v68, v68, v69
	v_cvt_pk_bf16_f32 v69, v70, v71
	v_fma_f32 v70, v72, v76, -v140
	v_fma_f32 v71, v73, v76, -v141
	v_fma_f32 v72, v74, v76, -v92
	v_fma_f32 v73, v75, v76, -v93
	v_cvt_pk_bf16_f32 v70, v70, v71
	v_cvt_pk_bf16_f32 v71, v72, v73
	v_lshl_add_u64 v[72:73], s[40:41], 0, v[138:139]
	v_lshl_add_u64 v[72:73], v[136:137], 1, v[72:73]
	global_store_dwordx4 v[72:73], v[68:71], off
	s_and_saveexec_b64 s[0:1], s[16:17]
	s_cbranch_execz .LBB0_2427
	v_lshlrev_b32_e32 v74, 16, v4
	v_and_b32_e32 v75, 0xffff0000, v4
	v_pk_add_f32 v[76:77], v[74:75], 0 op_sel_hi:[1,0]
	v_lshlrev_b32_e32 v78, 16, v8
	v_and_b32_e32 v79, 0xffff0000, v8
	v_add_f32 v76, v76, v78
	v_add_f32 v77, v77, v79
	v_lshlrev_b32_e32 v78, 16, v12
	v_and_b32_e32 v79, 0xffff0000, v12
	v_add_f32 v76, v76, v78
	v_add_f32 v77, v77, v79
	v_lshlrev_b32_e32 v78, 16, v16
	v_and_b32_e32 v79, 0xffff0000, v16
	v_add_f32 v76, v76, v78
	v_add_f32 v77, v77, v79
	v_lshlrev_b32_e32 v78, 16, v20
	v_and_b32_e32 v79, 0xffff0000, v20
	v_lshlrev_b32_e32 v72, 16, v5
	v_and_b32_e32 v73, 0xffff0000, v5
	v_add_f32 v76, v76, v78
	v_add_f32 v77, v77, v79
	v_lshlrev_b32_e32 v78, 16, v24
	v_and_b32_e32 v79, 0xffff0000, v24
	v_add_f32 v76, v76, v78
	v_add_f32 v77, v77, v79
	v_pk_add_f32 v[78:79], v[72:73], 0 op_sel_hi:[1,0]
	v_lshlrev_b32_e32 v80, 16, v9
	v_and_b32_e32 v81, 0xffff0000, v9
	v_add_f32 v78, v78, v80
	v_add_f32 v79, v79, v81
	v_lshlrev_b32_e32 v80, 16, v13
	v_and_b32_e32 v81, 0xffff0000, v13
	v_add_f32 v78, v78, v80
	v_add_f32 v79, v79, v81
	v_lshlrev_b32_e32 v80, 16, v17
	v_and_b32_e32 v81, 0xffff0000, v17
	v_add_f32 v78, v78, v80
	v_add_f32 v79, v79, v81
	v_lshlrev_b32_e32 v80, 16, v21
	v_and_b32_e32 v81, 0xffff0000, v21
	v_lshlrev_b32_e32 v70, 16, v6
	v_and_b32_e32 v71, 0xffff0000, v6
	v_add_f32 v78, v78, v80
	v_add_f32 v79, v79, v81
	v_lshlrev_b32_e32 v80, 16, v25
	v_and_b32_e32 v81, 0xffff0000, v25
	v_add_f32 v78, v78, v80
	v_add_f32 v79, v79, v81
	v_pk_add_f32 v[80:81], v[70:71], 0 op_sel_hi:[1,0]
	v_lshlrev_b32_e32 v82, 16, v10
	v_and_b32_e32 v83, 0xffff0000, v10
	v_add_f32 v80, v80, v82
	v_add_f32 v81, v81, v83
	v_lshlrev_b32_e32 v82, 16, v14
	v_and_b32_e32 v83, 0xffff0000, v14
	v_add_f32 v80, v80, v82
	v_add_f32 v81, v81, v83
	v_lshlrev_b32_e32 v82, 16, v18
	v_and_b32_e32 v83, 0xffff0000, v18
	v_add_f32 v80, v80, v82
	v_add_f32 v81, v81, v83
	v_lshlrev_b32_e32 v82, 16, v22
	v_and_b32_e32 v83, 0xffff0000, v22
	v_lshlrev_b32_e32 v68, 16, v7
	v_and_b32_e32 v69, 0xffff0000, v7
	v_add_f32 v80, v80, v82
	v_add_f32 v81, v81, v83
	v_lshlrev_b32_e32 v82, 16, v26
	v_and_b32_e32 v83, 0xffff0000, v26
	v_add_f32 v80, v80, v82
	v_add_f32 v81, v81, v83
	v_pk_add_f32 v[82:83], v[68:69], 0 op_sel_hi:[1,0]
	v_lshlrev_b32_e32 v84, 16, v11
	v_and_b32_e32 v85, 0xffff0000, v11
	v_add_f32 v82, v82, v84
	v_add_f32 v83, v83, v85
	v_lshlrev_b32_e32 v84, 16, v15
	v_and_b32_e32 v85, 0xffff0000, v15
	v_add_f32 v82, v82, v84
	v_add_f32 v83, v83, v85
	v_lshlrev_b32_e32 v84, 16, v19
	v_and_b32_e32 v85, 0xffff0000, v19
	v_add_f32 v82, v82, v84
	v_add_f32 v83, v83, v85
	v_lshlrev_b32_e32 v84, 16, v23
	v_and_b32_e32 v85, 0xffff0000, v23
	v_add_f32 v82, v82, v84
	v_add_f32 v83, v83, v85
	v_lshlrev_b32_e32 v84, 16, v27
	v_and_b32_e32 v85, 0xffff0000, v27
	v_add_f32 v82, v82, v84
	v_add_f32 v83, v83, v85
	v_lshlrev_b32_e32 v84, 16, v28
	v_and_b32_e32 v85, 0xffff0000, v28
	v_lshlrev_b32_e32 v92, 16, v32
	v_and_b32_e32 v93, 0xffff0000, v32
	v_add_f32 v76, v76, v84
	v_add_f32 v77, v77, v85
	v_lshlrev_b32_e32 v100, 16, v36
	v_and_b32_e32 v101, 0xffff0000, v36
	v_add_f32 v76, v76, v92
	v_add_f32 v77, v77, v93
	v_lshlrev_b32_e32 v84, 16, v40
	v_add_f32 v76, v76, v100
	v_add_f32 v77, v77, v101
	v_and_b32_e32 v85, 0xffff0000, v40
	v_add_f32 v76, v76, v84
	v_add_f32 v77, v77, v85
	v_lshlrev_b32_e32 v84, 16, v44
	v_and_b32_e32 v85, 0xffff0000, v44
	v_add_f32 v76, v76, v84
	v_add_f32 v77, v77, v85
	v_lshlrev_b32_e32 v84, 16, v48
	v_and_b32_e32 v85, 0xffff0000, v48
	v_add_f32 v76, v76, v84
	v_add_f32 v77, v77, v85
	v_lshlrev_b32_e32 v84, 16, v52
	v_and_b32_e32 v85, 0xffff0000, v52
	v_lshlrev_b32_e32 v86, 16, v29
	v_and_b32_e32 v87, 0xffff0000, v29
	v_add_f32 v76, v76, v84
	v_add_f32 v77, v77, v85
	v_lshlrev_b32_e32 v84, 16, v56
	v_and_b32_e32 v85, 0xffff0000, v56
	v_lshlrev_b32_e32 v94, 16, v33
	v_and_b32_e32 v95, 0xffff0000, v33
	v_add_f32 v76, v76, v84
	v_add_f32 v77, v77, v85
	v_lshlrev_b32_e32 v84, 16, v60
	v_and_b32_e32 v85, 0xffff0000, v60
	v_add_f32 v78, v78, v86
	v_add_f32 v79, v79, v87
	v_lshlrev_b32_e32 v102, 16, v37
	v_and_b32_e32 v103, 0xffff0000, v37
	v_add_f32 v76, v76, v84
	v_add_f32 v77, v77, v85
	v_lshlrev_b32_e32 v84, 16, v64
	v_and_b32_e32 v85, 0xffff0000, v64
	v_add_f32 v78, v78, v94
	v_add_f32 v79, v79, v95
	v_add_f32 v76, v76, v84
	v_add_f32 v77, v77, v85
	v_add_f32 v78, v78, v102
	v_add_f32 v79, v79, v103
	v_lshlrev_b32_e32 v84, 16, v41
	v_and_b32_e32 v85, 0xffff0000, v41
	v_add_f32 v78, v78, v84
	v_add_f32 v79, v79, v85
	v_lshlrev_b32_e32 v84, 16, v45
	v_and_b32_e32 v85, 0xffff0000, v45
	v_add_f32 v78, v78, v84
	v_add_f32 v79, v79, v85
	v_lshlrev_b32_e32 v84, 16, v49
	v_and_b32_e32 v85, 0xffff0000, v49
	v_add_f32 v78, v78, v84
	v_add_f32 v79, v79, v85
	v_lshlrev_b32_e32 v84, 16, v53
	v_and_b32_e32 v85, 0xffff0000, v53
	v_lshlrev_b32_e32 v88, 16, v30
	v_and_b32_e32 v89, 0xffff0000, v30
	v_add_f32 v78, v78, v84
	v_add_f32 v79, v79, v85
	v_lshlrev_b32_e32 v84, 16, v57
	v_and_b32_e32 v85, 0xffff0000, v57
	v_lshlrev_b32_e32 v96, 16, v34
	v_and_b32_e32 v97, 0xffff0000, v34
	v_add_f32 v78, v78, v84
	v_add_f32 v79, v79, v85
	v_lshlrev_b32_e32 v84, 16, v61
	v_and_b32_e32 v85, 0xffff0000, v61
	v_add_f32 v80, v80, v88
	v_add_f32 v81, v81, v89
	v_lshlrev_b32_e32 v104, 16, v38
	v_and_b32_e32 v105, 0xffff0000, v38
	v_add_f32 v78, v78, v84
	v_add_f32 v79, v79, v85
	v_lshlrev_b32_e32 v84, 16, v65
	v_and_b32_e32 v85, 0xffff0000, v65
	v_add_f32 v80, v80, v96
	v_add_f32 v81, v81, v97
	v_add_f32 v78, v78, v84
	v_add_f32 v79, v79, v85
	v_add_f32 v80, v80, v104
	v_add_f32 v81, v81, v105
	v_lshlrev_b32_e32 v84, 16, v42
	v_and_b32_e32 v85, 0xffff0000, v42
	v_add_f32 v80, v80, v84
	v_add_f32 v81, v81, v85
	v_lshlrev_b32_e32 v84, 16, v46
	v_and_b32_e32 v85, 0xffff0000, v46
	v_add_f32 v80, v80, v84
	v_add_f32 v81, v81, v85
	v_lshlrev_b32_e32 v84, 16, v50
	v_and_b32_e32 v85, 0xffff0000, v50
	v_add_f32 v80, v80, v84
	v_add_f32 v81, v81, v85
	v_lshlrev_b32_e32 v84, 16, v54
	v_and_b32_e32 v85, 0xffff0000, v54
	v_lshlrev_b32_e32 v90, 16, v31
	v_and_b32_e32 v91, 0xffff0000, v31
	v_add_f32 v80, v80, v84
	v_add_f32 v81, v81, v85
	v_lshlrev_b32_e32 v84, 16, v58
	v_and_b32_e32 v85, 0xffff0000, v58
	v_lshlrev_b32_e32 v98, 16, v35
	v_and_b32_e32 v99, 0xffff0000, v35
	v_add_f32 v80, v80, v84
	v_add_f32 v81, v81, v85
	v_lshlrev_b32_e32 v84, 16, v62
	v_and_b32_e32 v85, 0xffff0000, v62
	v_add_f32 v82, v82, v90
	v_add_f32 v83, v83, v91
	v_lshlrev_b32_e32 v106, 16, v39
	v_and_b32_e32 v107, 0xffff0000, v39
	v_add_f32 v80, v80, v84
	v_add_f32 v81, v81, v85
	v_lshlrev_b32_e32 v84, 16, v66
	v_and_b32_e32 v85, 0xffff0000, v66
	v_add_f32 v82, v82, v98
	v_add_f32 v83, v83, v99
	v_add_f32 v80, v80, v84
	v_add_f32 v81, v81, v85
	v_add_f32 v82, v82, v106
	v_add_f32 v83, v83, v107
	v_lshlrev_b32_e32 v84, 16, v43
	v_and_b32_e32 v85, 0xffff0000, v43
	v_add_f32 v82, v82, v84
	v_add_f32 v83, v83, v85
	v_lshlrev_b32_e32 v84, 16, v47
	v_and_b32_e32 v85, 0xffff0000, v47
	v_add_f32 v82, v82, v84
	v_add_f32 v83, v83, v85
	v_lshlrev_b32_e32 v84, 16, v51
	v_and_b32_e32 v85, 0xffff0000, v51
	v_add_f32 v82, v82, v84
	v_add_f32 v83, v83, v85
	v_lshlrev_b32_e32 v84, 16, v55
	v_and_b32_e32 v85, 0xffff0000, v55
	v_add_f32 v82, v82, v84
	v_add_f32 v83, v83, v85
	v_lshlrev_b32_e32 v84, 16, v59
	v_and_b32_e32 v85, 0xffff0000, v59
	v_add_f32 v82, v82, v84
	v_add_f32 v83, v83, v85
	v_lshlrev_b32_e32 v84, 16, v63
	v_and_b32_e32 v85, 0xffff0000, v63
	v_add_f32 v82, v82, v84
	v_add_f32 v83, v83, v85
	v_lshlrev_b32_e32 v84, 16, v67
	v_and_b32_e32 v85, 0xffff0000, v67
	s_movk_i32 s8, 0x3fff
	v_add_f32 v82, v82, v84
	v_add_f32 v83, v83, v85
	v_cmp_lt_i32_e32 vcc, s8, v133
	s_and_saveexec_b64 s[8:9], vcc
	s_cbranch_execz .LBB0_2529
	v_and_b32_e32 v88, 7, v133
	v_add_u32_e32 v84, 0xffffc000, v133
	v_mov_b32_e32 v135, v2
	v_lshrrev_b32_e32 v86, 3, v84
	v_lshl_add_u64 v[84:85], v[134:135], 2, s[6:7]
	v_cmp_eq_u32_e32 vcc, 0, v88
	s_and_saveexec_b64 s[14:15], vcc
	s_cbranch_execz .LBB0_2516
	s_mov_b32 s16, 0xb400
	v_mad_u64_u32 v[94:95], s[16:17], v86, s16, v[84:85]
	v_add_co_u32_e32 v90, vcc, 0xa000, v94
	s_mov_b64 s[16:17], 0xa800
	s_nop 0
	v_addc_co_u32_e32 v91, vcc, 0, v95, vcc
	v_lshl_add_u64 v[94:95], v[94:95], 0, s[16:17]
	global_load_dwordx4 v[90:93], v[90:91], off offset:2048
	s_nop 0
	global_load_dwordx4 v[94:97], v[94:95], off offset:16
	s_waitcnt vmcnt(1)
	v_add_f32 v76, v76, v90
	v_add_f32 v77, v77, v91
	v_add_f32 v78, v78, v92
	v_add_f32 v79, v79, v93
	s_waitcnt vmcnt(0)
	v_add_f32 v80, v80, v94
	v_add_f32 v81, v81, v95
	v_add_f32 v82, v82, v96
	v_add_f32 v83, v83, v97
.LBB0_2516:
	s_or_b64 exec, exec, s[14:15]
	v_mad_u64_u32 v[86:87], s[14:15], v86, 15, 15
	v_cmp_gt_u32_e32 vcc, 2, v88
	s_and_saveexec_b64 s[14:15], vcc
	s_cbranch_execz .LBB0_2522
	v_or_b32_e32 v90, -2, v133
	v_ashrrev_i32_e32 v91, 31, v90
	v_lshl_add_u64 v[90:91], v[86:87], 0, v[90:91]
	v_mad_u64_u32 v[94:95], s[16:17], v90, s91, v[84:85]
	v_mov_b32_e32 v90, v95
	v_mad_u64_u32 v[90:91], s[16:17], v91, s91, v[90:91]
	v_mov_b32_e32 v95, v90
	global_load_dwordx4 v[90:93], v[94:95], off offset:16
	s_nop 0
	global_load_dwordx4 v[94:97], v[94:95], off
	s_waitcnt vmcnt(1)
	v_add_f32 v82, v82, v92
	v_add_f32 v83, v83, v93
	s_waitcnt vmcnt(0)
	v_add_f32 v78, v78, v96
	v_add_f32 v79, v79, v97
	v_add_f32 v80, v80, v90
	v_add_f32 v81, v81, v91
	v_add_f32 v76, v76, v94
	v_add_f32 v77, v77, v95
	s_or_b64 exec, exec, s[14:15]
	v_cmp_gt_u32_e32 vcc, 3, v88
	s_and_saveexec_b64 s[14:15], vcc
	s_cbranch_execnz .LBB0_2523

.LBB0_2519:
	v_or_b32_e32 v90, -4, v133
	v_ashrrev_i32_e32 v91, 31, v90
	v_lshl_add_u64 v[90:91], v[86:87], 0, v[90:91]
	v_mad_u64_u32 v[94:95], s[16:17], v90, s91, v[84:85]
	v_mov_b32_e32 v90, v95
	v_mad_u64_u32 v[90:91], s[16:17], v91, s91, v[90:91]
	v_mov_b32_e32 v95, v90
	global_load_dwordx4 v[90:93], v[94:95], off offset:16
	s_nop 0
	global_load_dwordx4 v[94:97], v[94:95], off
	s_waitcnt vmcnt(1)
	v_add_f32 v82, v82, v92
	v_add_f32 v83, v83, v93
	s_waitcnt vmcnt(0)
	v_add_f32 v78, v78, v96
	v_add_f32 v79, v79, v97
	v_add_f32 v80, v80, v90
	v_add_f32 v81, v81, v91
	v_add_f32 v76, v76, v94
	v_add_f32 v77, v77, v95
	s_or_b64 exec, exec, s[14:15]
	v_cmp_gt_u32_e32 vcc, 5, v88
	s_and_saveexec_b64 s[14:15], vcc
	s_cbranch_execnz .LBB0_2525

.LBB0_2521:
	v_add_u32_e32 v90, -6, v88
	v_ashrrev_i32_e32 v91, 31, v90
	v_lshl_add_u64 v[90:91], v[86:87], 0, v[90:91]
	v_mad_u64_u32 v[94:95], s[16:17], v90, s91, v[84:85]
	v_mov_b32_e32 v90, v95
	v_mad_u64_u32 v[90:91], s[16:17], v91, s91, v[90:91]
	v_mov_b32_e32 v95, v90
	global_load_dwordx4 v[90:93], v[94:95], off offset:16
	s_nop 0
	global_load_dwordx4 v[94:97], v[94:95], off
	s_waitcnt vmcnt(1)
	v_add_f32 v82, v82, v92
	v_add_f32 v83, v83, v93
	s_waitcnt vmcnt(0)
	v_add_f32 v78, v78, v96
	v_add_f32 v79, v79, v97
	v_add_f32 v80, v80, v90
	v_add_f32 v81, v81, v91
	v_add_f32 v76, v76, v94
	v_add_f32 v77, v77, v95
	s_or_b64 exec, exec, s[14:15]
	v_cmp_ne_u32_e32 vcc, 7, v88
	s_and_saveexec_b64 s[14:15], vcc
	s_cbranch_execnz .LBB0_2527
	s_branch .LBB0_2528

.LBB0_2523:
	v_add_u32_e32 v90, -3, v88
	v_ashrrev_i32_e32 v91, 31, v90
	v_lshl_add_u64 v[90:91], v[86:87], 0, v[90:91]
	v_mad_u64_u32 v[94:95], s[16:17], v90, s91, v[84:85]
	v_mov_b32_e32 v90, v95
	v_mad_u64_u32 v[90:91], s[16:17], v91, s91, v[90:91]
	v_mov_b32_e32 v95, v90
	global_load_dwordx4 v[90:93], v[94:95], off offset:16
	s_nop 0
	global_load_dwordx4 v[94:97], v[94:95], off
	s_waitcnt vmcnt(1)
	v_add_f32 v82, v82, v92
	v_add_f32 v83, v83, v93
	s_waitcnt vmcnt(0)
	v_add_f32 v78, v78, v96
	v_add_f32 v79, v79, v97
	v_add_f32 v80, v80, v90
	v_add_f32 v81, v81, v91
	v_add_f32 v76, v76, v94
	v_add_f32 v77, v77, v95
	s_or_b64 exec, exec, s[14:15]
	v_cmp_gt_u32_e32 vcc, 4, v88
	s_and_saveexec_b64 s[14:15], vcc
	s_cbranch_execnz .LBB0_2519

.LBB0_2525:
	v_add_u32_e32 v90, -5, v88
	v_ashrrev_i32_e32 v91, 31, v90
	v_lshl_add_u64 v[90:91], v[86:87], 0, v[90:91]
	v_mad_u64_u32 v[94:95], s[16:17], v90, s91, v[84:85]
	v_mov_b32_e32 v90, v95
	v_mad_u64_u32 v[90:91], s[16:17], v91, s91, v[90:91]
	v_mov_b32_e32 v95, v90
	global_load_dwordx4 v[90:93], v[94:95], off offset:16
	s_nop 0
	global_load_dwordx4 v[94:97], v[94:95], off
	s_waitcnt vmcnt(1)
	v_add_f32 v82, v82, v92
	v_add_f32 v83, v83, v93
	s_waitcnt vmcnt(0)
	v_add_f32 v78, v78, v96
	v_add_f32 v79, v79, v97
	v_add_f32 v80, v80, v90
	v_add_f32 v81, v81, v91
	v_add_f32 v76, v76, v94
	v_add_f32 v77, v77, v95
	s_or_b64 exec, exec, s[14:15]
	v_cmp_gt_u32_e32 vcc, 6, v88
	s_and_saveexec_b64 s[14:15], vcc
	s_cbranch_execnz .LBB0_2521

.LBB0_2527:
	v_add_u32_e32 v90, -7, v88
	v_ashrrev_i32_e32 v91, 31, v90
	v_lshl_add_u64 v[90:91], v[86:87], 0, v[90:91]
	v_mad_u64_u32 v[94:95], s[16:17], v90, s91, v[84:85]
	v_mov_b32_e32 v90, v95
	v_mad_u64_u32 v[90:91], s[16:17], v91, s91, v[90:91]
	v_mov_b32_e32 v95, v90
	global_load_dwordx4 v[90:93], v[94:95], off offset:16
	s_nop 0
	global_load_dwordx4 v[94:97], v[94:95], off
	s_waitcnt vmcnt(1)
	v_add_f32 v82, v82, v92
	v_add_f32 v83, v83, v93
	s_waitcnt vmcnt(0)
	v_add_f32 v78, v78, v96
	v_add_f32 v79, v79, v97
	v_add_f32 v80, v80, v90
	v_add_f32 v81, v81, v91
	v_add_f32 v76, v76, v94
	v_add_f32 v77, v77, v95
.LBB0_2528:
	s_or_b64 exec, exec, s[14:15]
	v_or_b32_e32 v90, -8, v133
	v_ashrrev_i32_e32 v91, 31, v90
	v_lshl_add_u64 v[90:91], v[86:87], 0, v[90:91]
	v_mad_u64_u32 v[94:95], s[14:15], v90, s91, v[84:85]
	v_mov_b32_e32 v90, v95
	v_mad_u64_u32 v[90:91], s[14:15], v91, s91, v[90:91]
	v_mov_b32_e32 v95, v90
	v_add_u32_e32 v90, -9, v88
	v_ashrrev_i32_e32 v91, 31, v90
	v_lshl_add_u64 v[90:91], v[86:87], 0, v[90:91]
	v_mad_u64_u32 v[102:103], s[14:15], v90, s91, v[84:85]
	v_mov_b32_e32 v90, v103
	v_mad_u64_u32 v[90:91], s[14:15], v91, s91, v[90:91]
	v_mov_b32_e32 v103, v90
	v_add_u32_e32 v90, -10, v88
	v_ashrrev_i32_e32 v91, 31, v90
	v_lshl_add_u64 v[90:91], v[86:87], 0, v[90:91]
	v_mad_u64_u32 v[110:111], s[14:15], v90, s91, v[84:85]
	v_mov_b32_e32 v90, v111
	v_mad_u64_u32 v[90:91], s[14:15], v91, s91, v[90:91]
	v_mov_b32_e32 v111, v90
	v_add_u32_e32 v90, -11, v88
	v_ashrrev_i32_e32 v91, 31, v90
	v_lshl_add_u64 v[90:91], v[86:87], 0, v[90:91]
	v_mad_u64_u32 v[118:119], s[14:15], v90, s91, v[84:85]
	v_mov_b32_e32 v90, v119
	v_mad_u64_u32 v[90:91], s[14:15], v91, s91, v[90:91]
	v_mov_b32_e32 v119, v90
	v_add_u32_e32 v90, -12, v88
	v_ashrrev_i32_e32 v91, 31, v90
	v_lshl_add_u64 v[90:91], v[86:87], 0, v[90:91]
	v_mad_u64_u32 v[126:127], s[14:15], v90, s91, v[84:85]
	v_mov_b32_e32 v90, v127
	v_mad_u64_u32 v[90:91], s[14:15], v91, s91, v[90:91]
	v_mov_b32_e32 v127, v90
	v_add_u32_e32 v90, -13, v88
	v_ashrrev_i32_e32 v91, 31, v90
	v_lshl_add_u64 v[90:91], v[86:87], 0, v[90:91]
	v_mad_u64_u32 v[130:131], s[14:15], v90, s91, v[84:85]
	v_mov_b32_e32 v90, v131
	v_mad_u64_u32 v[90:91], s[14:15], v91, s91, v[90:91]
	v_mov_b32_e32 v131, v90
	v_add_u32_e32 v90, -14, v88
	v_ashrrev_i32_e32 v91, 31, v90
	v_lshl_add_u64 v[114:115], v[86:87], 0, v[90:91]
	global_load_dwordx4 v[90:93], v[94:95], off offset:16
	s_nop 0
	global_load_dwordx4 v[94:97], v[94:95], off
	v_mad_u64_u32 v[144:145], s[14:15], v114, s91, v[84:85]
	v_add_u32_e32 v88, -15, v88
	global_load_dwordx4 v[98:101], v[102:103], off
	s_nop 0
	global_load_dwordx4 v[102:105], v[102:103], off offset:16
	v_mov_b32_e32 v114, v145
	v_ashrrev_i32_e32 v89, 31, v88
	global_load_dwordx4 v[106:109], v[110:111], off offset:16
	s_nop 0
	global_load_dwordx4 v[110:113], v[110:111], off
	v_mad_u64_u32 v[114:115], s[14:15], v115, s91, v[114:115]
	v_lshl_add_u64 v[148:149], v[86:87], 0, v[88:89]
	v_mov_b32_e32 v145, v114
	global_load_dwordx4 v[114:117], v[118:119], off
	s_nop 0
	global_load_dwordx4 v[118:121], v[118:119], off offset:16
	v_mad_u64_u32 v[84:85], s[14:15], v148, s91, v[84:85]
	global_load_dwordx4 v[122:125], v[126:127], off offset:16
	s_nop 0
	global_load_dwordx4 v[126:129], v[126:127], off
	s_nop 0
	global_load_dwordx4 v[86:89], v[130:131], off
	global_load_dwordx4 v[136:139], v[130:131], off offset:16
	v_mov_b32_e32 v130, v85
	v_mad_u64_u32 v[130:131], s[14:15], v149, s91, v[130:131]
	global_load_dwordx4 v[140:143], v[144:145], off offset:16
	s_nop 0
	global_load_dwordx4 v[144:147], v[144:145], off
	v_mov_b32_e32 v85, v130
	global_load_dwordx4 v[148:151], v[84:85], off offset:16
	global_load_dwordx4 v[152:155], v[84:85], off
	s_waitcnt vmcnt(15)
	v_add_f32 v82, v82, v92
	v_add_f32 v83, v83, v93
	s_waitcnt vmcnt(14)
	v_add_f32 v78, v78, v96
	v_add_f32 v79, v79, v97
	v_add_f32 v76, v76, v94
	v_add_f32 v77, v77, v95
	v_add_f32 v80, v80, v90
	v_add_f32 v81, v81, v91
	s_waitcnt vmcnt(13)
	v_add_f32 v78, v78, v100
	v_add_f32 v79, v79, v101
	s_waitcnt vmcnt(12)
	v_add_f32 v82, v82, v104
	v_add_f32 v83, v83, v105
	v_add_f32 v80, v80, v102
	v_add_f32 v81, v81, v103
	v_add_f32 v76, v76, v98
	v_add_f32 v77, v77, v99
	s_waitcnt vmcnt(10)
	v_add_f32 v78, v78, v112
	v_add_f32 v79, v79, v113
	v_add_f32 v82, v82, v108
	v_add_f32 v83, v83, v109
	v_add_f32 v76, v76, v110
	v_add_f32 v77, v77, v111
	v_add_f32 v80, v80, v106
	v_add_f32 v81, v81, v107
	s_waitcnt vmcnt(9)
	v_add_f32 v78, v78, v116
	v_add_f32 v79, v79, v117
	s_waitcnt vmcnt(8)
	v_add_f32 v82, v82, v120
	v_add_f32 v83, v83, v121
	v_add_f32 v80, v80, v118
	v_add_f32 v81, v81, v119
	v_add_f32 v76, v76, v114
	v_add_f32 v77, v77, v115
	s_waitcnt vmcnt(6)
	v_add_f32 v78, v78, v128
	v_add_f32 v79, v79, v129
	v_add_f32 v82, v82, v124
	v_add_f32 v83, v83, v125
	v_add_f32 v76, v76, v126
	v_add_f32 v77, v77, v127
	v_add_f32 v80, v80, v122
	v_add_f32 v81, v81, v123
	s_waitcnt vmcnt(4)
	v_add_f32 v82, v82, v138
	v_add_f32 v83, v83, v139
	v_add_f32 v78, v78, v88
	v_add_f32 v79, v79, v89
	v_add_f32 v80, v80, v136
	v_add_f32 v81, v81, v137
	v_add_f32 v76, v76, v86
	v_add_f32 v77, v77, v87
	s_waitcnt vmcnt(2)
	v_add_f32 v78, v78, v146
	v_add_f32 v79, v79, v147
	v_add_f32 v82, v82, v142
	v_add_f32 v83, v83, v143
	v_add_f32 v76, v76, v144
	v_add_f32 v77, v77, v145
	v_add_f32 v80, v80, v140
	v_add_f32 v81, v81, v141
	s_waitcnt vmcnt(1)
	v_add_f32 v82, v82, v150
	v_add_f32 v83, v83, v151
	s_waitcnt vmcnt(0)
	v_add_f32 v78, v78, v154
	v_add_f32 v79, v79, v155
	v_add_f32 v80, v80, v148
	v_add_f32 v81, v81, v149
	v_add_f32 v76, v76, v152
	v_add_f32 v77, v77, v153

.LBB0_2589:
	s_and_saveexec_b64 s[8:9], s[20:21]
	s_cbranch_execz .LBB0_2536
	s_waitcnt lgkmcnt(0)
	v_add_f32_e32 v3, v3, v36
	v_div_scale_f32 v36, s[14:15], v3, v3, 1.0
	v_rcp_f32_e32 v37, v36
	v_div_scale_f32 v38, vcc, 1.0, v3, 1.0
	v_mov_b32_e32 v41, v2
	v_fma_f32 v39, -v36, v37, 1.0
	v_fmac_f32_e32 v37, v39, v37
	v_mul_f32_e32 v39, v38, v37
	v_fma_f32 v40, -v36, v39, v38
	v_fmac_f32_e32 v39, v40, v37
	v_fma_f32 v36, -v36, v39, v38
	v_div_fmas_f32 v36, v36, v37, v39
	v_div_fixup_f32 v36, v36, v3, 1.0
	v_lshlrev_b64 v[38:39], 11, v[132:133]
	v_lshl_add_u64 v[38:39], s[0:1], 0, v[38:39]
	v_lshlrev_b32_e32 v40, 3, v1
	v_mul_f32 v20, v36, v20
	v_mul_f32 v21, v36, v21
	v_mul_f32 v22, v36, v22
	v_mul_f32 v23, v36, v23
	v_mul_f32 v4, v36, v4
	v_mul_f32 v5, v36, v5
	v_mul_f32 v6, v36, v6
	v_mul_f32 v7, v36, v7
	v_lshl_add_u64 v[38:39], v[38:39], 0, v[40:41]
	v_cvt_pk_bf16_f32 v20, v20, v21
	v_cvt_pk_bf16_f32 v21, v22, v23
	v_cvt_pk_bf16_f32 v4, v4, v5
	v_cvt_pk_bf16_f32 v5, v6, v7
	global_store_dwordx2 v[38:39], v[20:21], off
	v_mul_f32 v20, v36, v24
	v_mul_f32 v21, v36, v25
	v_mul_f32 v22, v36, v26
	v_mul_f32 v23, v36, v27
	global_store_dwordx2 v[38:39], v[4:5], off offset:64
	v_mul_f32 v4, v36, v8
	v_mul_f32 v5, v36, v9
	v_mul_f32 v6, v36, v10
	v_mul_f32 v7, v36, v11
	v_cvt_pk_bf16_f32 v20, v20, v21
	v_cvt_pk_bf16_f32 v21, v22, v23
	v_cvt_pk_bf16_f32 v4, v4, v5
	v_cvt_pk_bf16_f32 v5, v6, v7
	global_store_dwordx2 v[38:39], v[20:21], off offset:16
	v_mul_f32 v20, v36, v28
	v_mul_f32 v21, v36, v29
	v_mul_f32 v22, v36, v30
	v_mul_f32 v23, v36, v31
	global_store_dwordx2 v[38:39], v[4:5], off offset:80
	v_mul_f32 v4, v36, v12
	v_mul_f32 v5, v36, v13
	v_mul_f32 v6, v36, v14
	v_mul_f32 v7, v36, v15
	v_cvt_pk_bf16_f32 v20, v20, v21
	v_cvt_pk_bf16_f32 v21, v22, v23
	v_cvt_pk_bf16_f32 v4, v4, v5
	v_cvt_pk_bf16_f32 v5, v6, v7
	global_store_dwordx2 v[38:39], v[20:21], off offset:32
	v_mul_f32 v20, v36, v32
	v_mul_f32 v21, v36, v33
	v_mul_f32 v22, v36, v34
	v_mul_f32 v23, v36, v35
	global_store_dwordx2 v[38:39], v[4:5], off offset:96
	v_mul_f32 v4, v36, v16
	v_mul_f32 v5, v36, v17
	v_mul_f32 v6, v36, v18
	v_mul_f32 v7, v36, v19
	v_cvt_pk_bf16_f32 v20, v20, v21
	v_cvt_pk_bf16_f32 v21, v22, v23
	v_cvt_pk_bf16_f32 v4, v4, v5
	v_cvt_pk_bf16_f32 v5, v6, v7
	global_store_dwordx2 v[38:39], v[20:21], off offset:48
	global_store_dwordx2 v[38:39], v[4:5], off offset:112
	s_branch .LBB0_2536

.LBB0_2677:
	v_mov_b32_e32 v132, v0
	s_lshl_b32 s1, s67, 8
	v_readfirstlane_b32 s0, v132
	s_and_b32 s8, s0, 0xc0
	s_ashr_i32 s0, s0, 2
	s_andn2_b32 s0, s0, 63
	s_add_i32 s0, s0, s1
	v_and_or_b32 v194, v132, 15, s0
	s_lshl_b32 s0, s65, 8
	s_ashr_i32 s1, s0, 31
	s_or_b32 s9, s8, s0
	v_and_b32_e32 v134, 64, v236
	s_lshl_b64 s[0:1], s[0:1], 2
	v_bfe_u32 v133, v132, 4, 2
	v_xor_b32_e32 v132, 32, v236
	v_add_u32_e32 v134, 64, v134
	s_add_u32 s0, s55, s0
	v_cmp_lt_i32_e32 vcc, v132, v134
	s_addc_u32 s1, s54, s1
	s_lshl_b32 s8, s8, 2
	v_cndmask_b32_e32 v132, v236, v132, vcc
	s_add_u32 s0, s0, s8
	v_lshl_or_b32 v224, v133, 3, s9
	v_lshlrev_b32_e32 v228, 2, v132
	v_cmp_eq_u32_e32 vcc, 0, v133
	s_addc_u32 s1, s1, 0
	v_lshlrev_b32_e32 v132, 5, v133
	v_mov_b32_e32 v133, v2
	v_ashrrev_i32_e32 v195, 31, v194
	v_lshl_add_u64 v[210:211], s[0:1], 0, v[132:133]
	v_lshlrev_b64 v[192:193], 12, v[194:195]
	v_lshl_add_u64 v[132:133], v[210:211], 0, v[192:193]
	global_load_dwordx4 v[244:247], v[132:133], off offset:16
	global_load_dwordx4 v[248:251], v[132:133], off
	global_load_dwordx4 v[180:183], v[132:133], off offset:144
	global_load_dwordx4 v[184:187], v[132:133], off offset:128
	v_or_b32_e32 v220, 16, v194
	v_ashrrev_i32_e32 v221, 31, v220
	v_lshlrev_b64 v[222:223], 12, v[220:221]
	v_lshl_add_u64 v[132:133], v[210:211], 0, v[222:223]
	global_load_dwordx4 v[172:175], v[132:133], off offset:16
	global_load_dwordx4 v[176:179], v[132:133], off
	global_load_dwordx4 v[164:167], v[132:133], off offset:144
	global_load_dwordx4 v[168:171], v[132:133], off offset:128
	v_or_b32_e32 v216, 32, v194
	v_ashrrev_i32_e32 v217, 31, v216
	v_lshlrev_b64 v[218:219], 12, v[216:217]
	v_lshl_add_u64 v[132:133], v[210:211], 0, v[218:219]
	global_load_dwordx4 v[156:159], v[132:133], off offset:16
	global_load_dwordx4 v[160:163], v[132:133], off
	global_load_dwordx4 v[148:151], v[132:133], off offset:144
	global_load_dwordx4 v[152:155], v[132:133], off offset:128
	v_or_b32_e32 v212, 48, v194
	v_ashrrev_i32_e32 v213, 31, v212
	v_lshlrev_b64 v[214:215], 12, v[212:213]
	v_lshl_add_u64 v[136:137], v[210:211], 0, v[214:215]
	global_load_dwordx4 v[140:143], v[136:137], off offset:16
	global_load_dwordx4 v[144:147], v[136:137], off
	global_load_dwordx4 v[132:135], v[136:137], off offset:144
	s_nop 0
	global_load_dwordx4 v[136:139], v[136:137], off offset:128
	v_ashrrev_i32_e32 v225, 31, v224
	v_lshl_add_u64 v[226:227], s[20:21], 0, v[192:193]
	v_lshlrev_b64 v[192:193], 2, v[224:225]
	v_lshl_add_u64 v[226:227], v[226:227], 0, v[192:193]
	s_waitcnt vmcnt(0)
	v_add_f32 v244, v124, v244
	v_add_f32 v245, v125, v245
	v_add_f32 v130, v130, v250
	v_add_f32 v131, v131, v251
	v_add_f32 v128, v128, v248
	v_add_f32 v129, v129, v249
	v_mul_f32_e32 v125, v131, v131
	v_mul_f32_e32 v124, v129, v129
	v_add_f32 v246, v126, v246
	v_add_f32 v247, v127, v247
	v_fmac_f32_e32 v124, v128, v128
	v_fmac_f32_e32 v125, v130, v130
	v_add_f32_e32 v124, v124, v125
	v_mul_f32_e32 v125, v245, v245
	v_mul_f32_e32 v126, v247, v247
	v_fmac_f32_e32 v125, v244, v244
	v_fmac_f32_e32 v126, v246, v246
	v_add_f32_e32 v125, v125, v126
	v_add_f32_e32 v196, v124, v125
	v_lshlrev_b64 v[124:125], 11, v[194:195]
	v_lshl_add_u64 v[126:127], s[24:25], 0, v[124:125]
	v_lshlrev_b64 v[124:125], 1, v[224:225]
	global_store_dwordx4 v[226:227], v[128:131], off
	global_store_dwordx4 v[226:227], v[244:247], off offset:16
	v_lshl_add_u64 v[224:225], v[126:127], 0, v[124:125]
	v_cvt_pk_bf16_f32 v126, v128, v129
	v_cvt_pk_bf16_f32 v127, v130, v131
	v_cvt_pk_bf16_f32 v128, v244, v245
	v_cvt_pk_bf16_f32 v129, v246, v247
	v_add_f32 v122, v122, v186
	v_add_f32 v123, v123, v187
	v_add_f32 v120, v120, v184
	v_add_f32 v121, v121, v185
	global_store_dwordx4 v[224:225], v[126:129], off
	v_add_f32 v118, v118, v182
	v_add_f32 v119, v119, v183
	v_add_f32 v116, v116, v180
	v_add_f32 v117, v117, v181
	v_mul_f32_e32 v126, v121, v121
	v_mul_f32_e32 v127, v123, v123
	global_store_dwordx4 v[226:227], v[120:123], off offset:128
	global_store_dwordx4 v[226:227], v[116:119], off offset:144
	v_fmac_f32_e32 v126, v120, v120
	v_fmac_f32_e32 v127, v122, v122
	v_cvt_pk_bf16_f32 v120, v120, v121
	v_cvt_pk_bf16_f32 v121, v122, v123
	v_cvt_pk_bf16_f32 v122, v116, v117
	v_cvt_pk_bf16_f32 v123, v118, v119
	v_add_f32 v114, v114, v178
	v_add_f32 v115, v115, v179
	v_add_f32 v112, v112, v176
	v_add_f32 v113, v113, v177
	global_store_dwordx4 v[224:225], v[120:123], off offset:64
	v_add_f32 v110, v110, v174
	v_add_f32 v111, v111, v175
	v_add_f32 v108, v108, v172
	v_add_f32 v109, v109, v173
	v_mul_f32_e32 v120, v113, v113
	v_mul_f32_e32 v121, v115, v115
	v_fmac_f32_e32 v120, v112, v112
	v_fmac_f32_e32 v121, v114, v114
	v_add_f32_e32 v120, v120, v121
	v_mul_f32_e32 v121, v109, v109
	v_mul_f32_e32 v122, v111, v111
	v_fmac_f32_e32 v121, v108, v108
	v_fmac_f32_e32 v122, v110, v110
	v_mul_f32_e32 v128, v119, v119
	v_add_f32_e32 v121, v121, v122
	v_fmac_f32_e32 v128, v118, v118
	v_lshl_add_u64 v[118:119], s[20:21], 0, v[222:223]
	v_add_f32_e32 v122, v120, v121
	v_lshlrev_b64 v[120:121], 11, v[220:221]
	v_lshl_add_u64 v[118:119], v[118:119], 0, v[192:193]
	v_lshl_add_u64 v[120:121], s[24:25], 0, v[120:121]
	v_add_f32 v106, v106, v170
	v_add_f32 v107, v107, v171
	v_add_f32 v104, v104, v168
	v_add_f32 v105, v105, v169
	global_store_dwordx4 v[118:119], v[112:115], off
	global_store_dwordx4 v[118:119], v[108:111], off offset:16
	v_lshl_add_u64 v[120:121], v[120:121], 0, v[124:125]
	v_cvt_pk_bf16_f32 v112, v112, v113
	v_cvt_pk_bf16_f32 v113, v114, v115
	v_cvt_pk_bf16_f32 v114, v108, v109
	v_cvt_pk_bf16_f32 v115, v110, v111
	v_add_f32 v102, v102, v166
	v_add_f32 v103, v103, v167
	v_add_f32 v100, v100, v164
	v_add_f32 v101, v101, v165
	v_mul_f32_e32 v108, v105, v105
	v_mul_f32_e32 v109, v107, v107
	global_store_dwordx4 v[120:121], v[112:115], off
	global_store_dwordx4 v[118:119], v[104:107], off offset:128
	global_store_dwordx4 v[118:119], v[100:103], off offset:144
	v_fmac_f32_e32 v108, v104, v104
	v_fmac_f32_e32 v109, v106, v106
	v_cvt_pk_bf16_f32 v104, v104, v105
	v_cvt_pk_bf16_f32 v105, v106, v107
	v_cvt_pk_bf16_f32 v106, v100, v101
	v_cvt_pk_bf16_f32 v107, v102, v103
	v_add_f32 v98, v98, v162
	v_add_f32 v99, v99, v163
	v_add_f32 v96, v96, v160
	v_add_f32 v97, v97, v161
	v_mul_f32_e32 v110, v103, v103
	global_store_dwordx4 v[120:121], v[104:107], off offset:64
	v_fmac_f32_e32 v110, v102, v102
	v_lshl_add_u64 v[102:103], s[20:21], 0, v[218:219]
	v_mul_f32_e32 v104, v97, v97
	v_mul_f32_e32 v105, v99, v99
	v_add_f32 v92, v92, v156
	v_add_f32 v93, v93, v157
	v_fmac_f32_e32 v104, v96, v96
	v_fmac_f32_e32 v105, v98, v98
	v_lshl_add_u64 v[102:103], v[102:103], 0, v[192:193]
	v_add_f32_e32 v104, v104, v105
	v_mul_f32_e32 v105, v93, v93
	v_add_f32 v90, v90, v154
	v_add_f32 v91, v91, v155
	v_add_f32 v88, v88, v152
	v_add_f32 v89, v89, v153
	v_add_f32 v94, v94, v158
	v_add_f32 v95, v95, v159
	global_store_dwordx4 v[102:103], v[96:99], off
	global_store_dwordx4 v[102:103], v[92:95], off offset:16
	v_fmac_f32_e32 v105, v92, v92
	v_cvt_pk_bf16_f32 v96, v96, v97
	v_cvt_pk_bf16_f32 v97, v98, v99
	v_cvt_pk_bf16_f32 v98, v92, v93
	v_mul_f32_e32 v92, v89, v89
	v_mul_f32_e32 v93, v91, v91
	v_mul_f32_e32 v106, v95, v95
	v_add_f32 v86, v86, v150
	v_add_f32 v87, v87, v151
	v_add_f32 v84, v84, v148
	v_add_f32 v85, v85, v149
	v_fmac_f32_e32 v92, v88, v88
	v_fmac_f32_e32 v93, v90, v90
	v_fmac_f32_e32 v106, v94, v94
	v_cvt_pk_bf16_f32 v99, v94, v95
	v_add_f32_e32 v92, v92, v93
	v_mul_f32_e32 v93, v85, v85
	v_mul_f32_e32 v94, v87, v87
	v_add_f32_e32 v105, v105, v106
	v_fmac_f32_e32 v93, v84, v84
	v_fmac_f32_e32 v94, v86, v86
	v_add_f32_e32 v106, v104, v105
	v_lshlrev_b64 v[104:105], 11, v[216:217]
	v_add_f32_e32 v93, v93, v94
	v_lshl_add_u64 v[104:105], s[24:25], 0, v[104:105]
	v_add_f32_e32 v92, v92, v93
	v_lshl_add_u64 v[104:105], v[104:105], 0, v[124:125]
	v_add_f32_e32 v92, v106, v92
	global_store_dwordx4 v[104:105], v[96:99], off
	global_store_dwordx4 v[102:103], v[88:91], off offset:128
	global_store_dwordx4 v[102:103], v[84:87], off offset:144
	v_add_f32 v82, v82, v146
	v_add_f32 v83, v83, v147
	v_cvt_pk_bf16_f32 v88, v88, v89
	v_cvt_pk_bf16_f32 v89, v90, v91
	v_cvt_pk_bf16_f32 v90, v84, v85
	ds_swizzle_b32 v84, v92 offset:swizzle(SWAP,16)
	v_cvt_pk_bf16_f32 v91, v86, v87
	v_add_f32 v80, v80, v144
	v_add_f32 v81, v81, v145
	global_store_dwordx4 v[104:105], v[88:91], off offset:64
	v_add_f32 v76, v76, v140
	v_add_f32 v77, v77, v141
	s_waitcnt lgkmcnt(0)
	v_add_f32_e32 v86, v92, v84
	v_mul_f32_e32 v88, v81, v81
	v_mul_f32_e32 v89, v83, v83
	v_lshl_add_u64 v[84:85], s[20:21], 0, v[214:215]
	v_fmac_f32_e32 v88, v80, v80
	v_fmac_f32_e32 v89, v82, v82
	v_lshl_add_u64 v[84:85], v[84:85], 0, v[192:193]
	v_add_f32_e32 v88, v88, v89
	v_mul_f32_e32 v89, v77, v77
	v_add_f32 v74, v74, v138
	v_add_f32 v75, v75, v139
	v_add_f32 v72, v72, v136
	v_add_f32 v73, v73, v137
	v_add_f32 v78, v78, v142
	v_add_f32 v79, v79, v143
	global_store_dwordx4 v[84:85], v[80:83], off
	global_store_dwordx4 v[84:85], v[76:79], off offset:16
	v_fmac_f32_e32 v89, v76, v76
	v_cvt_pk_bf16_f32 v80, v80, v81
	v_cvt_pk_bf16_f32 v81, v82, v83
	v_cvt_pk_bf16_f32 v82, v76, v77
	v_mul_f32_e32 v76, v73, v73
	v_mul_f32_e32 v77, v75, v75
	v_mul_f32_e32 v90, v79, v79
	v_add_f32 v70, v70, v134
	v_add_f32 v71, v71, v135
	v_add_f32 v68, v68, v132
	v_add_f32 v69, v69, v133
	v_fmac_f32_e32 v76, v72, v72
	v_fmac_f32_e32 v77, v74, v74
	v_add_f32_e32 v126, v126, v127
	v_mul_f32_e32 v127, v117, v117
	v_add_f32_e32 v108, v108, v109
	v_mul_f32_e32 v109, v101, v101
	v_fmac_f32_e32 v90, v78, v78
	v_cvt_pk_bf16_f32 v83, v78, v79
	v_add_f32_e32 v76, v76, v77
	v_mul_f32_e32 v77, v69, v69
	v_mul_f32_e32 v78, v71, v71
	v_fmac_f32_e32 v127, v116, v116
	v_fmac_f32_e32 v109, v100, v100
	v_add_f32_e32 v89, v89, v90
	v_fmac_f32_e32 v77, v68, v68
	v_fmac_f32_e32 v78, v70, v70
	v_add_f32_e32 v127, v127, v128
	v_add_f32_e32 v109, v109, v110
	v_add_f32_e32 v90, v88, v89
	v_lshlrev_b64 v[88:89], 11, v[212:213]
	v_add_f32_e32 v77, v77, v78
	v_add_f32_e32 v126, v126, v127
	v_add_f32_e32 v108, v108, v109
	v_lshl_add_u64 v[88:89], s[24:25], 0, v[88:89]
	v_add_f32_e32 v76, v76, v77
	v_add_f32_e32 v126, v196, v126
	v_add_f32_e32 v108, v122, v108
	v_lshl_add_u64 v[88:89], v[88:89], 0, v[124:125]
	v_add_f32_e32 v76, v90, v76
	ds_swizzle_b32 v116, v126 offset:swizzle(SWAP,16)
	ds_swizzle_b32 v100, v108 offset:swizzle(SWAP,16)
	global_store_dwordx4 v[88:89], v[80:83], off
	global_store_dwordx4 v[84:85], v[72:75], off offset:128
	global_store_dwordx4 v[84:85], v[68:71], off offset:144
	ds_bpermute_b32 v87, v228, v86
	v_cvt_pk_bf16_f32 v72, v72, v73
	v_cvt_pk_bf16_f32 v73, v74, v75
	v_cvt_pk_bf16_f32 v74, v68, v69
	ds_swizzle_b32 v68, v76 offset:swizzle(SWAP,16)
	s_waitcnt lgkmcnt(3)
	v_add_f32_e32 v116, v126, v116
	s_waitcnt lgkmcnt(2)
	v_add_f32_e32 v100, v108, v100
	ds_bpermute_b32 v117, v228, v116
	ds_bpermute_b32 v101, v228, v100
	s_waitcnt lgkmcnt(2)
	v_add_f32_e32 v68, v76, v68
	ds_bpermute_b32 v69, v228, v68
	v_cvt_pk_bf16_f32 v75, v70, v71
	v_lshl_add_u64 v[84:85], v[194:195], 2, s[22:23]
	global_store_dwordx4 v[88:89], v[72:75], off offset:64
	s_and_saveexec_b64 s[0:1], vcc
	s_cbranch_execz .LBB0_2679
	s_waitcnt lgkmcnt(2)
	v_add_f32_e32 v71, v116, v117
	s_waitcnt lgkmcnt(0)
	v_add_f32_e32 v68, v68, v69
	v_add_f32_e32 v69, v86, v87
	v_add_f32_e32 v70, v100, v101
	global_atomic_add_f32 v[84:85], v71, off
	global_atomic_add_f32 v[84:85], v70, off offset:64
	global_atomic_add_f32 v[84:85], v69, off offset:128
	global_atomic_add_f32 v[84:85], v68, off offset:192
.LBB0_2679:
	s_or_b64 exec, exec, s[0:1]
	v_add_u32_e32 v68, 0x80, v194
	s_waitcnt lgkmcnt(0)
	v_ashrrev_i32_e32 v69, 31, v68
	v_lshlrev_b64 v[70:71], 12, v[68:69]
	v_lshl_add_u64 v[72:73], v[210:211], 0, v[70:71]
	v_add_u32_e32 v122, 0x90, v194
	global_load_dwordx4 v[94:97], v[72:73], off
	global_load_dwordx4 v[98:101], v[72:73], off offset:16
	global_load_dwordx4 v[102:105], v[72:73], off offset:144
	global_load_dwordx4 v[106:109], v[72:73], off offset:128
	v_ashrrev_i32_e32 v123, 31, v122
	v_lshlrev_b64 v[72:73], 12, v[122:123]
	v_lshl_add_u64 v[74:75], v[210:211], 0, v[72:73]
	global_load_dwordx4 v[110:113], v[74:75], off
	global_load_dwordx4 v[114:117], v[74:75], off offset:16
	v_add_u32_e32 v90, 0xa0, v194
	v_add_u32_e32 v86, 0xb0, v194
	v_ashrrev_i32_e32 v91, 31, v90
	v_ashrrev_i32_e32 v87, 31, v86
	v_lshlrev_b64 v[92:93], 12, v[90:91]
	v_lshlrev_b64 v[88:89], 12, v[86:87]
	v_lshlrev_b64 v[68:69], 11, v[68:69]
	v_lshl_add_u64 v[76:77], v[210:211], 0, v[92:93]
	v_lshl_add_u64 v[146:147], v[210:211], 0, v[88:89]
	v_lshl_add_u64 v[148:149], s[20:21], 0, v[70:71]
	v_lshl_add_u64 v[150:151], s[24:25], 0, v[68:69]
	v_lshl_add_u64 v[152:153], s[20:21], 0, v[72:73]
	global_load_dwordx4 v[118:121], v[74:75], off offset:144
	global_load_dwordx4 v[126:129], v[74:75], off offset:128
	global_load_dwordx4 v[130:133], v[76:77], off offset:16
	global_load_dwordx4 v[134:137], v[76:77], off
	global_load_dwordx4 v[138:141], v[76:77], off offset:144
	global_load_dwordx4 v[142:145], v[76:77], off offset:128
	s_nop 0
	global_load_dwordx4 v[76:79], v[146:147], off offset:16
	global_load_dwordx4 v[80:83], v[146:147], off
	global_load_dwordx4 v[68:71], v[146:147], off offset:144
	global_load_dwordx4 v[72:75], v[146:147], off offset:128
	v_lshl_add_u64 v[146:147], v[148:149], 0, v[192:193]
	v_lshl_add_u64 v[148:149], v[150:151], 0, v[124:125]
	v_lshl_add_u64 v[150:151], v[152:153], 0, v[192:193]
	s_waitcnt vmcnt(14)
	v_add_f32 v62, v62, v100
	v_add_f32 v63, v63, v101
	v_add_f32 v66, v66, v96
	v_add_f32 v67, v67, v97
	v_add_f32 v64, v64, v94
	v_add_f32 v65, v65, v95
	v_add_f32 v60, v60, v98
	v_add_f32 v61, v61, v99
	s_waitcnt vmcnt(12)
	v_add_f32 v50, v50, v108
	v_add_f32 v51, v51, v109
	v_add_f32 v48, v48, v106
	v_add_f32 v49, v49, v107
	v_add_f32 v46, v46, v104
	v_add_f32 v47, v47, v105
	v_add_f32 v44, v44, v102
	v_add_f32 v45, v45, v103
	global_store_dwordx4 v[146:147], v[64:67], off
	global_store_dwordx4 v[146:147], v[60:63], off offset:16
	v_mul_f32_e32 v102, v65, v65
	v_mul_f32_e32 v103, v67, v67
	v_mul_f32_e32 v104, v61, v61
	v_mul_f32_e32 v105, v63, v63
	v_cvt_pk_bf16_f32 v94, v64, v65
	v_cvt_pk_bf16_f32 v95, v66, v67
	v_cvt_pk_bf16_f32 v96, v60, v61
	v_cvt_pk_bf16_f32 v97, v62, v63
	v_mul_f32_e32 v61, v49, v49
	v_mul_f32_e32 v63, v51, v51
	v_mul_f32_e32 v65, v45, v45
	v_mul_f32_e32 v67, v47, v47
	v_fmac_f32_e32 v102, v64, v64
	v_fmac_f32_e32 v103, v66, v66
	v_fmac_f32_e32 v104, v60, v60
	v_fmac_f32_e32 v105, v62, v62
	v_fmac_f32_e32 v61, v48, v48
	v_fmac_f32_e32 v63, v50, v50
	v_fmac_f32_e32 v65, v44, v44
	v_fmac_f32_e32 v67, v46, v46
	s_waitcnt vmcnt(13)
	v_add_f32 v58, v58, v112
	v_add_f32 v59, v59, v113
	v_add_f32 v56, v56, v110
	v_add_f32 v57, v57, v111
	s_waitcnt vmcnt(12)
	v_add_f32 v54, v54, v116
	v_add_f32 v55, v55, v117
	v_add_f32 v52, v52, v114
	v_add_f32 v53, v53, v115
	v_cvt_pk_bf16_f32 v100, v44, v45
	v_cvt_pk_bf16_f32 v101, v46, v47
	global_store_dwordx4 v[148:149], v[94:97], off
	global_store_dwordx4 v[146:147], v[48:51], off offset:128
	global_store_dwordx4 v[146:147], v[44:47], off offset:144
	v_cvt_pk_bf16_f32 v98, v48, v49
	v_mul_f32_e32 v106, v57, v57
	v_add_f32_e32 v44, v102, v103
	v_add_f32_e32 v45, v104, v105
	v_add_f32_e32 v46, v61, v63
	v_add_f32_e32 v47, v65, v67
	v_mul_f32_e32 v107, v59, v59
	v_add_f32_e32 v44, v44, v45
	v_add_f32_e32 v45, v46, v47
	v_mul_f32_e32 v47, v53, v53
	v_mul_f32_e32 v48, v55, v55
	v_fmac_f32_e32 v106, v56, v56
	v_fmac_f32_e32 v107, v58, v58
	v_fmac_f32_e32 v47, v52, v52
	v_fmac_f32_e32 v48, v54, v54
	v_add_f32_e32 v46, v106, v107
	v_add_f32_e32 v47, v47, v48
	v_add_f32_e32 v60, v46, v47
	v_lshlrev_b64 v[46:47], 11, v[122:123]
	v_lshl_add_u64 v[46:47], s[24:25], 0, v[46:47]
	v_cvt_pk_bf16_f32 v99, v50, v51
	v_lshl_add_u64 v[50:51], v[46:47], 0, v[124:125]
	v_cvt_pk_bf16_f32 v46, v56, v57
	v_cvt_pk_bf16_f32 v47, v58, v59
	v_cvt_pk_bf16_f32 v48, v52, v53
	v_cvt_pk_bf16_f32 v49, v54, v55
	s_waitcnt vmcnt(13)
	v_add_f32 v42, v42, v128
	v_add_f32 v43, v43, v129
	v_add_f32 v40, v40, v126
	v_add_f32 v41, v41, v127
	global_store_dwordx4 v[148:149], v[98:101], off offset:64
	global_store_dwordx4 v[150:151], v[56:59], off
	global_store_dwordx4 v[150:151], v[52:55], off offset:16
	global_store_dwordx4 v[50:51], v[46:49], off
	v_add_f32 v38, v38, v120
	v_add_f32 v39, v39, v121
	v_add_f32 v36, v36, v118
	v_add_f32 v37, v37, v119
	v_mul_f32_e32 v46, v41, v41
	v_mul_f32_e32 v47, v43, v43
	global_store_dwordx4 v[150:151], v[40:43], off offset:128
	global_store_dwordx4 v[150:151], v[36:39], off offset:144
	v_fmac_f32_e32 v46, v40, v40
	v_fmac_f32_e32 v47, v42, v42
	v_cvt_pk_bf16_f32 v40, v40, v41
	v_cvt_pk_bf16_f32 v41, v42, v43
	v_cvt_pk_bf16_f32 v42, v36, v37
	v_cvt_pk_bf16_f32 v43, v38, v39
	s_waitcnt vmcnt(17)
	v_add_f32 v34, v34, v136
	v_add_f32 v35, v35, v137
	v_add_f32 v32, v32, v134
	v_add_f32 v33, v33, v135
	global_store_dwordx4 v[50:51], v[40:43], off offset:64
	v_add_f32 v30, v30, v132
	v_add_f32 v31, v31, v133
	v_add_f32 v28, v28, v130
	v_add_f32 v29, v29, v131
	v_mul_f32_e32 v40, v33, v33
	v_mul_f32_e32 v41, v35, v35
	v_fmac_f32_e32 v40, v32, v32
	v_fmac_f32_e32 v41, v34, v34
	v_add_f32_e32 v40, v40, v41
	v_mul_f32_e32 v41, v29, v29
	v_mul_f32_e32 v42, v31, v31
	v_fmac_f32_e32 v41, v28, v28
	v_fmac_f32_e32 v42, v30, v30
	v_mul_f32_e32 v48, v39, v39
	v_add_f32_e32 v41, v41, v42
	v_fmac_f32_e32 v48, v38, v38
	v_lshl_add_u64 v[38:39], s[20:21], 0, v[92:93]
	v_add_f32_e32 v42, v40, v41
	v_lshlrev_b64 v[40:41], 11, v[90:91]
	v_lshl_add_u64 v[38:39], v[38:39], 0, v[192:193]
	v_lshl_add_u64 v[40:41], s[24:25], 0, v[40:41]
	s_waitcnt vmcnt(16)
	v_add_f32 v26, v26, v144
	v_add_f32 v27, v27, v145
	v_add_f32 v24, v24, v142
	v_add_f32 v25, v25, v143
	global_store_dwordx4 v[38:39], v[32:35], off
	global_store_dwordx4 v[38:39], v[28:31], off offset:16
	v_lshl_add_u64 v[40:41], v[40:41], 0, v[124:125]
	v_cvt_pk_bf16_f32 v32, v32, v33
	v_cvt_pk_bf16_f32 v33, v34, v35
	v_cvt_pk_bf16_f32 v34, v28, v29
	v_cvt_pk_bf16_f32 v35, v30, v31
	v_add_f32 v22, v22, v140
	v_add_f32 v23, v23, v141
	v_add_f32 v20, v20, v138
	v_add_f32 v21, v21, v139
	v_mul_f32_e32 v28, v25, v25
	v_mul_f32_e32 v29, v27, v27
	global_store_dwordx4 v[40:41], v[32:35], off
	global_store_dwordx4 v[38:39], v[24:27], off offset:128
	global_store_dwordx4 v[38:39], v[20:23], off offset:144
	v_fmac_f32_e32 v28, v24, v24
	v_fmac_f32_e32 v29, v26, v26
	v_cvt_pk_bf16_f32 v24, v24, v25
	v_cvt_pk_bf16_f32 v25, v26, v27
	v_cvt_pk_bf16_f32 v26, v20, v21
	v_cvt_pk_bf16_f32 v27, v22, v23
	s_waitcnt vmcnt(19)
	v_add_f32 v18, v18, v82
	v_add_f32 v19, v19, v83
	v_add_f32 v16, v16, v80
	v_add_f32 v17, v17, v81
	v_mul_f32_e32 v30, v23, v23
	global_store_dwordx4 v[40:41], v[24:27], off offset:64
	v_fmac_f32_e32 v30, v22, v22
	v_lshl_add_u64 v[22:23], s[20:21], 0, v[88:89]
	v_mul_f32_e32 v24, v17, v17
	v_mul_f32_e32 v25, v19, v19
	v_add_f32 v12, v12, v76
	v_add_f32 v13, v13, v77
	v_fmac_f32_e32 v24, v16, v16
	v_fmac_f32_e32 v25, v18, v18
	v_lshl_add_u64 v[22:23], v[22:23], 0, v[192:193]
	v_add_f32 v14, v14, v78
	v_add_f32 v15, v15, v79
	v_add_f32_e32 v24, v24, v25
	v_mul_f32_e32 v25, v13, v13
	s_waitcnt vmcnt(18)
	v_add_f32 v10, v10, v74
	v_add_f32 v11, v11, v75
	v_add_f32 v8, v8, v72
	v_add_f32 v9, v9, v73
	global_store_dwordx4 v[22:23], v[16:19], off
	global_store_dwordx4 v[22:23], v[12:15], off offset:16
	v_fmac_f32_e32 v25, v12, v12
	v_mul_f32_e32 v26, v15, v15
	v_cvt_pk_bf16_f32 v16, v16, v17
	v_cvt_pk_bf16_f32 v17, v18, v19
	v_cvt_pk_bf16_f32 v18, v12, v13
	v_add_f32 v12, v4, v68
	v_add_f32 v13, v5, v69
	v_mul_f32_e32 v4, v9, v9
	v_mul_f32_e32 v5, v11, v11
	v_fmac_f32_e32 v26, v14, v14
	v_cvt_pk_bf16_f32 v19, v14, v15
	v_add_f32 v14, v6, v70
	v_add_f32 v15, v7, v71
	v_fmac_f32_e32 v4, v8, v8
	v_fmac_f32_e32 v5, v10, v10
	v_add_f32_e32 v46, v46, v47
	v_mul_f32_e32 v47, v37, v37
	v_add_f32_e32 v28, v28, v29
	v_mul_f32_e32 v29, v21, v21
	v_add_f32_e32 v4, v4, v5
	v_mul_f32_e32 v5, v13, v13
	v_mul_f32_e32 v6, v15, v15
	v_fmac_f32_e32 v47, v36, v36
	v_fmac_f32_e32 v29, v20, v20
	v_fmac_f32_e32 v5, v12, v12
	v_fmac_f32_e32 v6, v14, v14
	v_add_f32_e32 v47, v47, v48
	v_add_f32_e32 v29, v29, v30
	v_add_f32_e32 v25, v25, v26
	v_add_f32_e32 v5, v5, v6
	v_add_f32_e32 v46, v46, v47
	v_add_f32_e32 v28, v28, v29
	v_add_f32_e32 v26, v24, v25
	v_add_f32_e32 v4, v4, v5
	v_add_f32_e32 v44, v44, v45
	v_add_f32_e32 v46, v60, v46
	v_add_f32_e32 v28, v42, v28
	v_add_f32_e32 v4, v26, v4
	ds_swizzle_b32 v45, v44 offset:swizzle(SWAP,16)
	ds_swizzle_b32 v47, v46 offset:swizzle(SWAP,16)
	ds_swizzle_b32 v29, v28 offset:swizzle(SWAP,16)
	ds_swizzle_b32 v5, v4 offset:swizzle(SWAP,16)
	v_lshlrev_b64 v[24:25], 11, v[86:87]
	s_waitcnt lgkmcnt(3)
	v_add_f32_e32 v44, v44, v45
	s_waitcnt lgkmcnt(2)
	v_add_f32_e32 v36, v46, v47
	s_waitcnt lgkmcnt(1)
	v_add_f32_e32 v20, v28, v29
	s_waitcnt lgkmcnt(0)
	v_add_f32_e32 v4, v4, v5
	ds_bpermute_b32 v45, v228, v44
	ds_bpermute_b32 v37, v228, v36
	ds_bpermute_b32 v21, v228, v20
	ds_bpermute_b32 v5, v228, v4
	v_lshl_add_u64 v[24:25], s[24:25], 0, v[24:25]
	v_lshl_add_u64 v[24:25], v[24:25], 0, v[124:125]
	global_store_dwordx4 v[24:25], v[16:19], off
	global_store_dwordx4 v[22:23], v[8:11], off offset:128
	global_store_dwordx4 v[22:23], v[12:15], off offset:144
	v_cvt_pk_bf16_f32 v6, v8, v9
	v_cvt_pk_bf16_f32 v7, v10, v11
	v_cvt_pk_bf16_f32 v8, v12, v13
	v_cvt_pk_bf16_f32 v9, v14, v15
	global_store_dwordx4 v[24:25], v[6:9], off offset:64
	s_and_saveexec_b64 s[0:1], vcc
	s_cbranch_execz .LBB0_2681
	s_waitcnt lgkmcnt(3)
	v_add_f32_e32 v7, v44, v45
	s_waitcnt lgkmcnt(0)
	v_add_f32_e32 v4, v4, v5
	v_add_f32_e32 v5, v20, v21
	v_add_f32_e32 v6, v36, v37
	global_atomic_add_f32 v[84:85], v7, off offset:512
	global_atomic_add_f32 v[84:85], v6, off offset:576
	global_atomic_add_f32 v[84:85], v5, off offset:640
	global_atomic_add_f32 v[84:85], v4, off offset:704

.LBB0_2769:
	s_add_u32 s8, s16, 0xfc000000
	s_addc_u32 s9, s17, -1
	s_and_b64 s[0:1], s[6:7], exec
	s_cselect_b32 s0, s9, s37
	s_cselect_b32 s1, s8, s36
	s_add_u32 s8, s38, 0x5bfdc00
	s_addc_u32 s9, s39, 0
	s_add_u32 s6, s38, s63
	s_addc_u32 s7, s39, 0
	v_mov_b32_e32 v1, v0
	s_add_u32 s6, s6, 0x5000
	s_addc_u32 s7, s7, 0
	v_readfirstlane_b32 s14, v1
	s_and_b32 s15, s14, 0xc0
	s_ashr_i32 s14, s14, 2
	s_andn2_b32 s14, s14, 63
	v_readlane_b32 s16, v255, 15
	s_addk_i32 s14, 0x4000
	v_readlane_b32 s17, v255, 16
	v_and_or_b32 v214, v1, 15, s14
	s_or_b32 s14, s15, s16
	v_readlane_b32 s16, v255, 17
	v_readlane_b32 s17, v255, 18
	s_add_u32 s1, s1, s16
	s_addc_u32 s16, s0, s17
	s_lshl_b32 s0, s15, 2
	v_bfe_u32 v3, v1, 4, 2
	s_add_u32 s0, s1, s0
	s_addc_u32 s1, s16, 0
	v_lshlrev_b32_e32 v132, 5, v3
	v_mov_b32_e32 v133, v2
	v_ashrrev_i32_e32 v215, 31, v214
	v_lshl_add_u64 v[216:217], s[0:1], 0, v[132:133]
	v_lshlrev_b64 v[132:133], 12, v[214:215]
	v_lshl_add_u64 v[134:135], v[216:217], 0, v[132:133]
	global_load_dwordx4 v[160:163], v[134:135], off
	global_load_dwordx4 v[156:159], v[134:135], off offset:16
	global_load_dwordx4 v[168:171], v[134:135], off offset:128
	global_load_dwordx4 v[164:167], v[134:135], off offset:144
	v_or_b32_e32 v218, 16, v214
	v_lshl_or_b32 v134, v3, 3, s14
	v_ashrrev_i32_e32 v219, 31, v218
	v_ashrrev_i32_e32 v135, 31, v134
	v_lshlrev_b64 v[228:229], 12, v[218:219]
	v_lshlrev_b64 v[210:211], 2, v[134:135]
	v_lshlrev_b64 v[212:213], 1, v[134:135]
	v_lshl_add_u64 v[134:135], v[216:217], 0, v[228:229]
	global_load_dwordx4 v[180:183], v[134:135], off offset:16
	global_load_dwordx4 v[184:187], v[134:135], off
	v_or_b32_e32 v220, 32, v214
	v_or_b32_e32 v222, 48, v214
	v_ashrrev_i32_e32 v221, 31, v220
	v_ashrrev_i32_e32 v223, 31, v222
	v_lshlrev_b64 v[136:137], 11, v[214:215]
	v_lshlrev_b64 v[226:227], 12, v[220:221]
	v_lshlrev_b64 v[224:225], 12, v[222:223]
	v_lshl_add_u64 v[132:133], s[36:37], 0, v[132:133]
	v_lshl_add_u64 v[136:137], s[8:9], 0, v[136:137]
	v_lshl_add_u64 v[244:245], v[132:133], 0, v[210:211]
	v_lshl_add_u64 v[246:247], v[136:137], 0, v[212:213]
	v_lshl_add_u64 v[132:133], v[216:217], 0, v[226:227]
	v_lshl_add_u64 v[136:137], v[216:217], 0, v[224:225]
	global_load_dwordx4 v[188:191], v[134:135], off offset:144
	global_load_dwordx4 v[192:195], v[134:135], off offset:128
	global_load_dwordx4 v[172:175], v[132:133], off offset:16
	global_load_dwordx4 v[176:179], v[132:133], off
	global_load_dwordx4 v[148:151], v[132:133], off offset:144
	global_load_dwordx4 v[152:155], v[132:133], off offset:128
	global_load_dwordx4 v[140:143], v[136:137], off offset:16
	global_load_dwordx4 v[144:147], v[136:137], off
	s_nop 0
	global_load_dwordx4 v[132:135], v[136:137], off offset:144
	s_nop 0
	global_load_dwordx4 v[136:139], v[136:137], off offset:128
	v_cmp_eq_u32_e32 vcc, 0, v3
	v_lshl_add_u64 v[248:249], v[244:245], 0, 16
	s_mov_b64 s[0:1], 0x80
	v_lshl_add_u64 v[250:251], v[244:245], 0, s[0:1]
	s_mov_b64 s[14:15], 0x90
	v_lshl_add_u64 v[232:233], v[244:245], 0, s[14:15]
	s_waitcnt vmcnt(0)
	v_add_f32 v130, v130, v162
	v_add_f32 v131, v131, v163
	v_add_f32 v128, v128, v160
	v_add_f32 v129, v129, v161
	v_add_f32 v126, v126, v158
	v_add_f32 v127, v127, v159
	v_add_f32 v124, v124, v156
	v_add_f32 v125, v125, v157
	v_mul_f32_e32 v1, v129, v129
	v_mul_f32_e32 v3, v131, v131
	v_mul_f32_e32 v160, v125, v125
	v_mul_f32_e32 v161, v127, v127
	global_store_dwordx4 v[244:245], v[128:131], off sc1
	s_nop 1
	v_fmac_f32_e32 v1, v128, v128
	v_fmac_f32_e32 v3, v130, v130
	v_fmac_f32_e32 v160, v124, v124
	v_fmac_f32_e32 v161, v126, v126
	v_add_f32 v122, v122, v170
	v_add_f32 v123, v123, v171
	v_add_f32 v120, v120, v168
	v_add_f32 v121, v121, v169
	v_add_f32 v118, v118, v166
	v_add_f32 v119, v119, v167
	v_add_f32 v116, v116, v164
	v_add_f32 v117, v117, v165
	global_store_dwordx4 v[248:249], v[124:127], off sc1
	s_nop 1
	v_add_f32_e32 v1, v1, v3
	v_add_f32_e32 v3, v160, v161
	v_cvt_pk_bf16_f32 v156, v128, v129
	v_cvt_pk_bf16_f32 v157, v130, v131
	v_cvt_pk_bf16_f32 v158, v124, v125
	v_cvt_pk_bf16_f32 v159, v126, v127
	v_mul_f32_e32 v129, v121, v121
	global_store_dwordx4 v[246:247], v[156:159], off sc1
	s_nop 1
	v_add_f32_e32 v1, v1, v3
	v_mul_f32_e32 v3, v123, v123
	v_mul_f32_e32 v124, v117, v117
	v_mul_f32_e32 v125, v119, v119
	v_fmac_f32_e32 v129, v120, v120
	global_store_dwordx4 v[250:251], v[120:123], off sc1
	s_nop 1
	v_fmac_f32_e32 v3, v122, v122
	v_fmac_f32_e32 v124, v116, v116
	v_fmac_f32_e32 v125, v118, v118
	global_store_dwordx4 v[232:233], v[116:119], off sc1
	s_nop 1
	v_add_f32_e32 v3, v129, v3
	v_add_f32_e32 v124, v124, v125
	v_cvt_pk_bf16_f32 v120, v120, v121
	v_cvt_pk_bf16_f32 v121, v122, v123
	v_cvt_pk_bf16_f32 v123, v118, v119
	v_lshl_add_u64 v[118:119], s[36:37], 0, v[228:229]
	v_add_f32_e32 v3, v3, v124
	v_lshl_add_u64 v[124:125], v[246:247], 0, 64
	v_cvt_pk_bf16_f32 v122, v116, v117
	global_store_dwordx4 v[124:125], v[120:123], off sc1
	s_nop 1
	v_lshl_add_u64 v[118:119], v[118:119], 0, v[210:211]
	v_add_f32 v114, v114, v186
	v_add_f32 v115, v115, v187
	v_add_f32 v112, v112, v184
	v_add_f32 v113, v113, v185
	v_lshl_add_u64 v[120:121], v[118:119], 0, 16
	global_store_dwordx4 v[118:119], v[112:115], off sc1
	s_nop 1
	v_add_f32 v110, v110, v182
	v_add_f32 v111, v111, v183
	v_add_f32 v108, v108, v180
	v_add_f32 v109, v109, v181
	v_mul_f32_e32 v117, v113, v113
	global_store_dwordx4 v[120:121], v[108:111], off sc1
	s_nop 1
	v_mul_f32_e32 v120, v115, v115
	v_fmac_f32_e32 v117, v112, v112
	v_fmac_f32_e32 v120, v114, v114
	v_add_f32_e32 v117, v117, v120
	v_mul_f32_e32 v120, v109, v109
	v_mul_f32_e32 v121, v111, v111
	v_fmac_f32_e32 v120, v108, v108
	v_fmac_f32_e32 v121, v110, v110
	v_add_f32_e32 v120, v120, v121
	v_add_f32_e32 v117, v117, v120
	v_lshlrev_b64 v[120:121], 11, v[218:219]
	v_lshl_add_u64 v[120:121], s[8:9], 0, v[120:121]
	v_lshl_add_u64 v[120:121], v[120:121], 0, v[212:213]
	v_cvt_pk_bf16_f32 v112, v112, v113
	v_cvt_pk_bf16_f32 v113, v114, v115
	v_cvt_pk_bf16_f32 v114, v108, v109
	v_cvt_pk_bf16_f32 v115, v110, v111
	global_store_dwordx4 v[120:121], v[112:115], off sc1
	s_nop 1
	v_lshl_add_u64 v[108:109], v[118:119], 0, s[0:1]
	v_add_f32 v106, v106, v194
	v_add_f32 v107, v107, v195
	v_add_f32 v104, v104, v192
	v_add_f32 v105, v105, v193
	v_add_f32 v102, v102, v190
	v_add_f32 v103, v103, v191
	global_store_dwordx4 v[108:109], v[104:107], off sc1
	s_nop 1
	v_lshl_add_u64 v[108:109], v[118:119], 0, s[14:15]
	v_add_f32 v100, v100, v188
	v_add_f32 v101, v101, v189
	v_mul_f32_e32 v110, v103, v103
	global_store_dwordx4 v[108:109], v[100:103], off sc1
	s_nop 1
	v_mul_f32_e32 v108, v105, v105
	v_mul_f32_e32 v109, v107, v107
	v_fmac_f32_e32 v108, v104, v104
	v_fmac_f32_e32 v109, v106, v106
	v_add_f32_e32 v108, v108, v109
	v_mul_f32_e32 v109, v101, v101
	v_fmac_f32_e32 v109, v100, v100
	v_fmac_f32_e32 v110, v102, v102
	v_add_f32_e32 v109, v109, v110
	v_add_f32_e32 v108, v108, v109
	v_cvt_pk_bf16_f32 v104, v104, v105
	v_cvt_pk_bf16_f32 v105, v106, v107
	v_cvt_pk_bf16_f32 v107, v102, v103
	v_lshl_add_u64 v[102:103], s[36:37], 0, v[226:227]
	v_add_f32_e32 v110, v117, v108
	v_lshl_add_u64 v[108:109], v[120:121], 0, 64
	v_cvt_pk_bf16_f32 v106, v100, v101
	global_store_dwordx4 v[108:109], v[104:107], off sc1
	s_nop 1
	v_lshl_add_u64 v[102:103], v[102:103], 0, v[210:211]
	v_add_f32 v98, v98, v178
	v_add_f32 v99, v99, v179
	v_add_f32 v96, v96, v176
	v_add_f32 v97, v97, v177
	v_lshl_add_u64 v[104:105], v[102:103], 0, 16
	global_store_dwordx4 v[102:103], v[96:99], off sc1
	s_nop 1
	v_add_f32 v94, v94, v174
	v_add_f32 v95, v95, v175
	v_add_f32 v92, v92, v172
	v_add_f32 v93, v93, v173
	v_mul_f32_e32 v106, v95, v95
	global_store_dwordx4 v[104:105], v[92:95], off sc1
	s_nop 1
	v_mul_f32_e32 v104, v97, v97
	v_mul_f32_e32 v105, v99, v99
	v_fmac_f32_e32 v104, v96, v96
	v_fmac_f32_e32 v105, v98, v98
	v_add_f32_e32 v104, v104, v105
	v_mul_f32_e32 v105, v93, v93
	v_fmac_f32_e32 v105, v92, v92
	v_fmac_f32_e32 v106, v94, v94
	v_add_f32_e32 v105, v105, v106
	v_add_f32_e32 v106, v104, v105
	v_lshlrev_b64 v[104:105], 11, v[220:221]
	v_lshl_add_u64 v[104:105], s[8:9], 0, v[104:105]
	v_lshl_add_u64 v[104:105], v[104:105], 0, v[212:213]
	v_cvt_pk_bf16_f32 v96, v96, v97
	v_cvt_pk_bf16_f32 v97, v98, v99
	v_cvt_pk_bf16_f32 v98, v92, v93
	v_cvt_pk_bf16_f32 v99, v94, v95
	global_store_dwordx4 v[104:105], v[96:99], off sc1
	s_nop 1
	v_lshl_add_u64 v[92:93], v[102:103], 0, s[0:1]
	v_add_f32 v90, v90, v154
	v_add_f32 v91, v91, v155
	v_add_f32 v88, v88, v152
	v_add_f32 v89, v89, v153
	v_add_f32 v86, v86, v150
	v_add_f32 v87, v87, v151
	global_store_dwordx4 v[92:93], v[88:91], off sc1
	s_nop 1
	v_lshl_add_u64 v[92:93], v[102:103], 0, s[14:15]
	v_add_f32 v84, v84, v148
	v_add_f32 v85, v85, v149
	v_mul_f32_e32 v94, v87, v87
	global_store_dwordx4 v[92:93], v[84:87], off sc1
	s_nop 1
	v_mul_f32_e32 v92, v89, v89
	v_mul_f32_e32 v93, v91, v91
	v_fmac_f32_e32 v92, v88, v88
	v_fmac_f32_e32 v93, v90, v90
	v_add_f32_e32 v92, v92, v93
	v_mul_f32_e32 v93, v85, v85
	v_fmac_f32_e32 v93, v84, v84
	v_fmac_f32_e32 v94, v86, v86
	v_add_f32_e32 v93, v93, v94
	v_add_f32_e32 v92, v92, v93
	v_cvt_pk_bf16_f32 v88, v88, v89
	v_cvt_pk_bf16_f32 v89, v90, v91
	v_cvt_pk_bf16_f32 v91, v86, v87
	v_lshl_add_u64 v[86:87], s[36:37], 0, v[224:225]
	v_add_f32_e32 v94, v106, v92
	v_lshl_add_u64 v[92:93], v[104:105], 0, 64
	v_cvt_pk_bf16_f32 v90, v84, v85
	global_store_dwordx4 v[92:93], v[88:91], off sc1
	s_nop 1
	v_lshl_add_u64 v[86:87], v[86:87], 0, v[210:211]
	v_add_f32 v82, v82, v146
	v_add_f32 v83, v83, v147
	v_add_f32 v80, v80, v144
	v_add_f32 v81, v81, v145
	v_lshl_add_u64 v[88:89], v[86:87], 0, 16
	global_store_dwordx4 v[86:87], v[80:83], off sc1
	s_nop 1
	v_add_f32 v78, v78, v142
	v_add_f32 v79, v79, v143
	v_add_f32 v76, v76, v140
	v_add_f32 v77, v77, v141
	v_mul_f32_e32 v90, v79, v79
	global_store_dwordx4 v[88:89], v[76:79], off sc1
	s_nop 1
	v_mul_f32_e32 v88, v81, v81
	v_mul_f32_e32 v89, v83, v83
	v_fmac_f32_e32 v88, v80, v80
	v_fmac_f32_e32 v89, v82, v82
	v_add_f32_e32 v88, v88, v89
	v_mul_f32_e32 v89, v77, v77
	v_fmac_f32_e32 v89, v76, v76
	v_fmac_f32_e32 v90, v78, v78
	v_add_f32_e32 v89, v89, v90
	v_add_f32_e32 v90, v88, v89
	v_lshlrev_b64 v[88:89], 11, v[222:223]
	v_lshl_add_u64 v[88:89], s[8:9], 0, v[88:89]
	v_lshl_add_u64 v[88:89], v[88:89], 0, v[212:213]
	v_cvt_pk_bf16_f32 v80, v80, v81
	v_cvt_pk_bf16_f32 v81, v82, v83
	v_cvt_pk_bf16_f32 v82, v76, v77
	v_cvt_pk_bf16_f32 v83, v78, v79
	global_store_dwordx4 v[88:89], v[80:83], off sc1
	s_nop 1
	v_lshl_add_u64 v[76:77], v[86:87], 0, s[0:1]
	v_add_f32 v74, v74, v138
	v_add_f32 v75, v75, v139
	v_add_f32 v72, v72, v136
	v_add_f32 v73, v73, v137
	v_add_f32 v70, v70, v134
	v_add_f32 v71, v71, v135
	global_store_dwordx4 v[76:77], v[72:75], off sc1
	s_nop 1
	v_lshl_add_u64 v[76:77], v[86:87], 0, s[14:15]
	v_add_f32 v68, v68, v132
	v_add_f32 v69, v69, v133
	v_mul_f32_e32 v78, v71, v71
	global_store_dwordx4 v[76:77], v[68:71], off sc1
	s_nop 1
	v_mul_f32_e32 v76, v73, v73
	v_mul_f32_e32 v77, v75, v75
	v_fmac_f32_e32 v76, v72, v72
	v_fmac_f32_e32 v77, v74, v74
	v_add_f32_e32 v76, v76, v77
	v_mul_f32_e32 v77, v69, v69
	v_add_f32_e32 v1, v1, v3
	v_fmac_f32_e32 v77, v68, v68
	v_fmac_f32_e32 v78, v70, v70
	ds_swizzle_b32 v3, v1 offset:swizzle(SWAP,16)
	v_add_f32_e32 v77, v77, v78
	v_add_f32_e32 v76, v76, v77
	v_add_f32_e32 v78, v90, v76
	ds_swizzle_b32 v111, v110 offset:swizzle(SWAP,16)
	ds_swizzle_b32 v95, v94 offset:swizzle(SWAP,16)
	ds_swizzle_b32 v79, v78 offset:swizzle(SWAP,16)
	v_and_b32_e32 v116, 64, v236
	s_waitcnt lgkmcnt(3)
	v_add_f32_e32 v3, v1, v3
	v_xor_b32_e32 v1, 32, v236
	v_add_u32_e32 v116, 64, v116
	v_cmp_lt_i32_e64 s[16:17], v1, v116
	s_waitcnt lgkmcnt(2)
	v_add_f32_e32 v100, v110, v111
	s_waitcnt lgkmcnt(1)
	v_add_f32_e32 v84, v94, v95
	v_cndmask_b32_e64 v1, v236, v1, s[16:17]
	v_lshlrev_b32_e32 v1, 2, v1
	v_cvt_pk_bf16_f32 v72, v72, v73
	v_cvt_pk_bf16_f32 v73, v74, v75
	v_cvt_pk_bf16_f32 v74, v68, v69
	s_waitcnt lgkmcnt(0)
	v_add_f32_e32 v68, v78, v79
	ds_bpermute_b32 v116, v1, v3
	ds_bpermute_b32 v101, v1, v100
	ds_bpermute_b32 v85, v1, v84
	ds_bpermute_b32 v69, v1, v68
	v_lshl_add_u64 v[76:77], v[88:89], 0, 64
	v_cvt_pk_bf16_f32 v75, v70, v71
	global_store_dwordx4 v[76:77], v[72:75], off sc1
	s_nop 1
	s_and_saveexec_b64 s[0:1], vcc
	s_cbranch_execz .LBB0_2771
	v_lshl_add_u64 v[76:77], v[214:215], 2, s[6:7]
	s_waitcnt lgkmcnt(3)
	v_add_f32_e32 v3, v3, v116
	v_lshl_add_u64 v[70:71], v[222:223], 2, s[6:7]
	v_lshl_add_u64 v[72:73], v[220:221], 2, s[6:7]
	v_lshl_add_u64 v[74:75], v[218:219], 2, s[6:7]
	s_waitcnt lgkmcnt(0)
	v_add_f32_e32 v68, v68, v69
	v_add_f32_e32 v69, v84, v85
	v_add_f32_e32 v78, v100, v101
	global_atomic_add_f32 v[76:77], v3, off
	global_atomic_add_f32 v[74:75], v78, off
	global_atomic_add_f32 v[72:73], v69, off
	global_atomic_add_f32 v[70:71], v68, off
.LBB0_2771:
	s_or_b64 exec, exec, s[0:1]
	v_add_u32_e32 v124, 0x80, v214
	v_ashrrev_i32_e32 v125, 31, v124
	v_lshlrev_b64 v[146:147], 12, v[124:125]
	s_waitcnt lgkmcnt(0)
	v_lshl_add_u64 v[68:69], v[216:217], 0, v[146:147]
	global_load_dwordx4 v[138:141], v[68:69], off offset:16
	global_load_dwordx4 v[142:145], v[68:69], off
	global_load_dwordx4 v[116:119], v[68:69], off offset:144
	global_load_dwordx4 v[120:123], v[68:69], off offset:128
	v_add_u32_e32 v126, 0x90, v214
	v_ashrrev_i32_e32 v127, 31, v126
	v_lshlrev_b64 v[136:137], 12, v[126:127]
	v_lshl_add_u64 v[68:69], v[216:217], 0, v[136:137]
	global_load_dwordx4 v[108:111], v[68:69], off offset:16
	global_load_dwordx4 v[112:115], v[68:69], off
	global_load_dwordx4 v[100:103], v[68:69], off offset:144
	global_load_dwordx4 v[104:107], v[68:69], off offset:128
	v_add_u32_e32 v128, 0xa0, v214
	v_ashrrev_i32_e32 v129, 31, v128
	v_lshlrev_b64 v[134:135], 12, v[128:129]
	v_lshl_add_u64 v[68:69], v[216:217], 0, v[134:135]
	global_load_dwordx4 v[92:95], v[68:69], off offset:16
	global_load_dwordx4 v[96:99], v[68:69], off
	global_load_dwordx4 v[84:87], v[68:69], off offset:144
	global_load_dwordx4 v[88:91], v[68:69], off offset:128
	v_add_u32_e32 v130, 0xb0, v214
	v_ashrrev_i32_e32 v131, 31, v130
	v_lshlrev_b64 v[132:133], 12, v[130:131]
	v_lshl_add_u64 v[72:73], v[216:217], 0, v[132:133]
	global_load_dwordx4 v[76:79], v[72:73], off offset:16
	global_load_dwordx4 v[80:83], v[72:73], off
	global_load_dwordx4 v[68:71], v[72:73], off offset:144
	s_nop 0
	global_load_dwordx4 v[72:75], v[72:73], off offset:128
	v_lshl_add_u64 v[146:147], s[36:37], 0, v[146:147]
	v_lshl_add_u64 v[146:147], v[146:147], 0, v[210:211]
	s_mov_b64 s[0:1], 0x80
	s_waitcnt vmcnt(15)
	v_add_f32 v60, v60, v138
	v_add_f32 v61, v61, v139
	s_waitcnt vmcnt(14)
	v_add_f32 v66, v66, v144
	v_add_f32 v67, v67, v145
	v_add_f32 v64, v64, v142
	v_add_f32 v65, v65, v143
	v_lshl_add_u64 v[138:139], v[146:147], 0, 16
	global_store_dwordx4 v[146:147], v[64:67], off sc1
	s_nop 1
	v_add_f32 v62, v62, v140
	v_add_f32 v63, v63, v141
	v_mul_f32_e32 v3, v65, v65
	global_store_dwordx4 v[138:139], v[60:63], off sc1
	s_nop 1
	v_mul_f32_e32 v138, v67, v67
	v_fmac_f32_e32 v3, v64, v64
	v_fmac_f32_e32 v138, v66, v66
	v_add_f32_e32 v3, v3, v138
	v_mul_f32_e32 v138, v61, v61
	v_mul_f32_e32 v139, v63, v63
	v_fmac_f32_e32 v138, v60, v60
	v_fmac_f32_e32 v139, v62, v62
	v_add_f32_e32 v138, v138, v139
	v_add_f32_e32 v3, v3, v138
	v_lshlrev_b64 v[138:139], 11, v[124:125]
	v_lshl_add_u64 v[138:139], s[8:9], 0, v[138:139]
	v_lshl_add_u64 v[138:139], v[138:139], 0, v[212:213]
	v_cvt_pk_bf16_f32 v64, v64, v65
	v_cvt_pk_bf16_f32 v65, v66, v67
	v_cvt_pk_bf16_f32 v66, v60, v61
	v_cvt_pk_bf16_f32 v67, v62, v63
	global_store_dwordx4 v[138:139], v[64:67], off sc1
	s_nop 1
	v_lshl_add_u64 v[60:61], v[146:147], 0, s[0:1]
	s_waitcnt vmcnt(12)
	v_add_f32 v58, v58, v122
	v_add_f32 v59, v59, v123
	v_add_f32 v56, v56, v120
	v_add_f32 v57, v57, v121
	v_add_f32 v54, v54, v118
	v_add_f32 v55, v55, v119
	global_store_dwordx4 v[60:61], v[56:59], off sc1
	s_nop 1
	v_lshl_add_u64 v[60:61], v[146:147], 0, s[14:15]
	v_add_f32 v52, v52, v116
	v_add_f32 v53, v53, v117
	v_mul_f32_e32 v62, v55, v55
	global_store_dwordx4 v[60:61], v[52:55], off sc1
	s_nop 1
	v_mul_f32_e32 v60, v57, v57
	v_mul_f32_e32 v61, v59, v59
	v_fmac_f32_e32 v60, v56, v56
	v_fmac_f32_e32 v61, v58, v58
	v_add_f32_e32 v60, v60, v61
	v_mul_f32_e32 v61, v53, v53
	v_fmac_f32_e32 v61, v52, v52
	v_fmac_f32_e32 v62, v54, v54
	v_add_f32_e32 v61, v61, v62
	v_add_f32_e32 v60, v60, v61
	v_add_f32_e32 v3, v3, v60
	v_cvt_pk_bf16_f32 v56, v56, v57
	v_cvt_pk_bf16_f32 v57, v58, v59
	v_cvt_pk_bf16_f32 v58, v52, v53
	ds_swizzle_b32 v52, v3 offset:swizzle(SWAP,16)
	v_lshl_add_u64 v[60:61], v[138:139], 0, 64
	v_cvt_pk_bf16_f32 v59, v54, v55
	global_store_dwordx4 v[60:61], v[56:59], off sc1
	s_nop 1
	s_waitcnt vmcnt(10)
	v_add_f32 v50, v50, v114
	v_add_f32 v51, v51, v115
	s_waitcnt lgkmcnt(0)
	v_add_f32_e32 v3, v3, v52
	v_lshl_add_u64 v[52:53], s[36:37], 0, v[136:137]
	v_lshl_add_u64 v[52:53], v[52:53], 0, v[210:211]
	v_add_f32 v48, v48, v112
	v_add_f32 v49, v49, v113
	v_lshl_add_u64 v[56:57], v[52:53], 0, 16
	global_store_dwordx4 v[52:53], v[48:51], off sc1
	s_nop 1
	v_add_f32 v46, v46, v110
	v_add_f32 v47, v47, v111
	v_add_f32 v44, v44, v108
	v_add_f32 v45, v45, v109
	v_mul_f32_e32 v55, v49, v49
	global_store_dwordx4 v[56:57], v[44:47], off sc1
	s_nop 1
	v_mul_f32_e32 v56, v51, v51
	v_fmac_f32_e32 v55, v48, v48
	v_fmac_f32_e32 v56, v50, v50
	v_add_f32_e32 v55, v55, v56
	v_mul_f32_e32 v56, v45, v45
	v_mul_f32_e32 v57, v47, v47
	v_fmac_f32_e32 v56, v44, v44
	v_fmac_f32_e32 v57, v46, v46
	v_add_f32_e32 v56, v56, v57
	v_add_f32_e32 v55, v55, v56
	v_lshlrev_b64 v[56:57], 11, v[126:127]
	v_lshl_add_u64 v[56:57], s[8:9], 0, v[56:57]
	v_lshl_add_u64 v[56:57], v[56:57], 0, v[212:213]
	v_cvt_pk_bf16_f32 v48, v48, v49
	v_cvt_pk_bf16_f32 v49, v50, v51
	v_cvt_pk_bf16_f32 v50, v44, v45
	v_cvt_pk_bf16_f32 v51, v46, v47
	global_store_dwordx4 v[56:57], v[48:51], off sc1
	s_nop 1
	v_lshl_add_u64 v[44:45], v[52:53], 0, s[0:1]
	s_waitcnt vmcnt(8)
	v_add_f32 v42, v42, v106
	v_add_f32 v43, v43, v107
	v_add_f32 v40, v40, v104
	v_add_f32 v41, v41, v105
	v_add_f32 v38, v38, v102
	v_add_f32 v39, v39, v103
	global_store_dwordx4 v[44:45], v[40:43], off sc1
	s_nop 1
	v_lshl_add_u64 v[44:45], v[52:53], 0, s[14:15]
	v_add_f32 v36, v36, v100
	v_add_f32 v37, v37, v101
	v_mul_f32_e32 v46, v39, v39
	global_store_dwordx4 v[44:45], v[36:39], off sc1
	s_nop 1
	v_mul_f32_e32 v44, v41, v41
	v_mul_f32_e32 v45, v43, v43
	v_fmac_f32_e32 v44, v40, v40
	v_fmac_f32_e32 v45, v42, v42
	v_add_f32_e32 v44, v44, v45
	v_mul_f32_e32 v45, v37, v37
	v_fmac_f32_e32 v45, v36, v36
	v_fmac_f32_e32 v46, v38, v38
	v_add_f32_e32 v45, v45, v46
	v_add_f32_e32 v44, v44, v45
	v_cvt_pk_bf16_f32 v40, v40, v41
	v_cvt_pk_bf16_f32 v41, v42, v43
	v_cvt_pk_bf16_f32 v43, v38, v39
	v_lshl_add_u64 v[38:39], s[36:37], 0, v[134:135]
	v_add_f32_e32 v46, v55, v44
	v_lshl_add_u64 v[44:45], v[56:57], 0, 64
	v_cvt_pk_bf16_f32 v42, v36, v37
	global_store_dwordx4 v[44:45], v[40:43], off sc1
	s_nop 1
	v_lshl_add_u64 v[38:39], v[38:39], 0, v[210:211]
	s_waitcnt vmcnt(6)
	v_add_f32 v34, v34, v98
	v_add_f32 v35, v35, v99
	v_add_f32 v32, v32, v96
	v_add_f32 v33, v33, v97
	v_lshl_add_u64 v[40:41], v[38:39], 0, 16
	global_store_dwordx4 v[38:39], v[32:35], off sc1
	s_nop 1
	v_add_f32 v30, v30, v94
	v_add_f32 v31, v31, v95
	v_add_f32 v28, v28, v92
	v_add_f32 v29, v29, v93
	v_mul_f32_e32 v42, v31, v31
	global_store_dwordx4 v[40:41], v[28:31], off sc1
	s_nop 1
	v_mul_f32_e32 v40, v33, v33
	v_mul_f32_e32 v41, v35, v35
	v_fmac_f32_e32 v40, v32, v32
	v_fmac_f32_e32 v41, v34, v34
	v_add_f32_e32 v40, v40, v41
	v_mul_f32_e32 v41, v29, v29
	v_fmac_f32_e32 v41, v28, v28
	v_fmac_f32_e32 v42, v30, v30
	v_add_f32_e32 v41, v41, v42
	v_add_f32_e32 v42, v40, v41
	v_lshlrev_b64 v[40:41], 11, v[128:129]
	v_lshl_add_u64 v[40:41], s[8:9], 0, v[40:41]
	v_lshl_add_u64 v[40:41], v[40:41], 0, v[212:213]
	v_cvt_pk_bf16_f32 v32, v32, v33
	v_cvt_pk_bf16_f32 v33, v34, v35
	v_cvt_pk_bf16_f32 v34, v28, v29
	v_cvt_pk_bf16_f32 v35, v30, v31
	global_store_dwordx4 v[40:41], v[32:35], off sc1
	s_nop 1
	v_lshl_add_u64 v[28:29], v[38:39], 0, s[0:1]
	s_waitcnt vmcnt(4)
	v_add_f32 v26, v26, v90
	v_add_f32 v27, v27, v91
	v_add_f32 v24, v24, v88
	v_add_f32 v25, v25, v89
	v_add_f32 v22, v22, v86
	v_add_f32 v23, v23, v87
	global_store_dwordx4 v[28:29], v[24:27], off sc1
	s_nop 1
	v_lshl_add_u64 v[28:29], v[38:39], 0, s[14:15]
	v_add_f32 v20, v20, v84
	v_add_f32 v21, v21, v85
	v_mul_f32_e32 v30, v23, v23
	global_store_dwordx4 v[28:29], v[20:23], off sc1
	s_nop 1
	v_mul_f32_e32 v28, v25, v25
	v_mul_f32_e32 v29, v27, v27
	v_fmac_f32_e32 v28, v24, v24
	v_fmac_f32_e32 v29, v26, v26
	v_add_f32_e32 v28, v28, v29
	v_mul_f32_e32 v29, v21, v21
	v_fmac_f32_e32 v29, v20, v20
	v_fmac_f32_e32 v30, v22, v22
	v_add_f32_e32 v29, v29, v30
	v_add_f32_e32 v28, v28, v29
	v_cvt_pk_bf16_f32 v24, v24, v25
	v_cvt_pk_bf16_f32 v25, v26, v27
	v_cvt_pk_bf16_f32 v27, v22, v23
	v_lshl_add_u64 v[22:23], s[36:37], 0, v[132:133]
	v_add_f32_e32 v30, v42, v28
	v_lshl_add_u64 v[28:29], v[40:41], 0, 64
	v_cvt_pk_bf16_f32 v26, v20, v21
	global_store_dwordx4 v[28:29], v[24:27], off sc1
	s_nop 1
	v_lshl_add_u64 v[22:23], v[22:23], 0, v[210:211]
	s_waitcnt vmcnt(2)
	v_add_f32 v18, v18, v82
	v_add_f32 v19, v19, v83
	v_add_f32 v16, v16, v80
	v_add_f32 v17, v17, v81
	v_lshl_add_u64 v[24:25], v[22:23], 0, 16
	global_store_dwordx4 v[22:23], v[16:19], off sc1
	s_nop 1
	v_add_f32 v14, v14, v78
	v_add_f32 v15, v15, v79
	v_add_f32 v12, v12, v76
	v_add_f32 v13, v13, v77
	v_mul_f32_e32 v26, v15, v15
	global_store_dwordx4 v[24:25], v[12:15], off sc1
	s_nop 1
	v_mul_f32_e32 v24, v17, v17
	v_mul_f32_e32 v25, v19, v19
	v_fmac_f32_e32 v24, v16, v16
	v_fmac_f32_e32 v25, v18, v18
	v_add_f32_e32 v24, v24, v25
	v_mul_f32_e32 v25, v13, v13
	v_fmac_f32_e32 v25, v12, v12
	v_fmac_f32_e32 v26, v14, v14
	v_add_f32_e32 v25, v25, v26
	v_add_f32_e32 v26, v24, v25
	v_lshlrev_b64 v[24:25], 11, v[130:131]
	v_lshl_add_u64 v[24:25], s[8:9], 0, v[24:25]
	v_lshl_add_u64 v[24:25], v[24:25], 0, v[212:213]
	v_cvt_pk_bf16_f32 v16, v16, v17
	v_cvt_pk_bf16_f32 v17, v18, v19
	v_cvt_pk_bf16_f32 v18, v12, v13
	v_cvt_pk_bf16_f32 v19, v14, v15
	global_store_dwordx4 v[24:25], v[16:19], off sc1
	s_nop 1
	v_lshl_add_u64 v[12:13], v[22:23], 0, s[0:1]
	s_waitcnt vmcnt(0)
	v_add_f32 v10, v10, v74
	v_add_f32 v11, v11, v75
	v_add_f32 v8, v8, v72
	v_add_f32 v9, v9, v73
	v_add_f32 v6, v6, v70
	v_add_f32 v7, v7, v71
	global_store_dwordx4 v[12:13], v[8:11], off sc1
	s_nop 1
	v_lshl_add_u64 v[12:13], v[22:23], 0, s[14:15]
	v_add_f32 v4, v4, v68
	v_add_f32 v5, v5, v69
	v_mul_f32_e32 v14, v7, v7
	global_store_dwordx4 v[12:13], v[4:7], off sc1
	s_nop 1
	v_mul_f32_e32 v12, v9, v9
	v_mul_f32_e32 v13, v11, v11
	v_fmac_f32_e32 v12, v8, v8
	v_fmac_f32_e32 v13, v10, v10
	v_add_f32_e32 v12, v12, v13
	v_mul_f32_e32 v13, v5, v5
	v_fmac_f32_e32 v13, v4, v4
	v_fmac_f32_e32 v14, v6, v6
	v_add_f32_e32 v13, v13, v14
	v_add_f32_e32 v12, v12, v13
	v_add_f32_e32 v14, v26, v12
	ds_swizzle_b32 v36, v46 offset:swizzle(SWAP,16)
	ds_swizzle_b32 v20, v30 offset:swizzle(SWAP,16)
	v_cvt_pk_bf16_f32 v8, v8, v9
	v_cvt_pk_bf16_f32 v9, v10, v11
	v_cvt_pk_bf16_f32 v10, v4, v5
	ds_swizzle_b32 v4, v14 offset:swizzle(SWAP,16)
	s_waitcnt lgkmcnt(2)
	v_add_f32_e32 v36, v46, v36
	s_waitcnt lgkmcnt(1)
	v_add_f32_e32 v20, v30, v20
	ds_bpermute_b32 v54, v1, v3
	ds_bpermute_b32 v37, v1, v36
	s_waitcnt lgkmcnt(2)
	v_add_f32_e32 v4, v14, v4
	ds_bpermute_b32 v21, v1, v20
	ds_bpermute_b32 v1, v1, v4
	v_lshl_add_u64 v[12:13], v[24:25], 0, 64
	v_cvt_pk_bf16_f32 v11, v6, v7
	global_store_dwordx4 v[12:13], v[8:11], off sc1
	s_nop 1
	s_and_saveexec_b64 s[0:1], vcc
	s_cbranch_execz .LBB0_2773
	v_lshl_add_u64 v[12:13], v[124:125], 2, s[6:7]
	s_waitcnt lgkmcnt(3)
	v_add_f32_e32 v3, v3, v54
	v_lshl_add_u64 v[6:7], v[130:131], 2, s[6:7]
	v_lshl_add_u64 v[8:9], v[128:129], 2, s[6:7]
	v_lshl_add_u64 v[10:11], v[126:127], 2, s[6:7]
	s_waitcnt lgkmcnt(0)
	v_add_f32_e32 v1, v4, v1
	v_add_f32_e32 v4, v20, v21
	v_add_f32_e32 v5, v36, v37
	global_atomic_add_f32 v[12:13], v3, off
	global_atomic_add_f32 v[10:11], v5, off
	global_atomic_add_f32 v[8:9], v4, off
	global_atomic_add_f32 v[6:7], v1, off

.LBB0_2850:
	v_mov_b32_e32 v146, v0
	s_nop 0
	v_readfirstlane_b32 s0, v146
	s_ashr_i32 s1, s0, 2
	s_andn2_b32 s1, s1, 63
	v_and_or_b32 v136, v146, 15, s1
	v_lshl_add_u32 v136, s68, 8, v136
	v_ashrrev_i32_e32 v137, 31, v136
	v_lshl_add_u64 v[144:145], v[136:137], 2, s[22:23]
	global_load_dword v147, v[144:145], off
	global_load_dword v143, v[144:145], off offset:64
	global_load_dword v142, v[144:145], off offset:128
	global_load_dword v141, v[144:145], off offset:192
	global_load_dword v140, v[144:145], off offset:512
	global_load_dword v139, v[144:145], off offset:576
	global_load_dword v138, v[144:145], off offset:640
	global_load_dword v137, v[144:145], off offset:704
	s_lshr_b32 s0, s0, 1
	s_and_b32 s8, s0, 0x60
	s_cmp_eq_u32 s68, 64
	s_cselect_b64 s[90:91], -1, 0
	s_cmp_lg_u32 s68, 64
	s_cselect_b64 s[0:1], -1, 0
	s_lshl_b32 s92, s51, 7
	s_ashr_i32 s93, s92, 31
	s_lshl_b32 s68, s8, 1
	s_mov_b64 s[8:9], -1
	s_waitcnt vmcnt(0)
	v_fmamk_f32 v144, v147, 0x3a800000, v231
	v_cmp_gt_f32_e32 vcc, s11, v144
	v_mul_f32_e32 v145, 0x4b800000, v144
	s_nop 0
	v_cndmask_b32_e32 v144, v144, v145, vcc
	v_rsq_f32_e32 v144, v144
	s_nop 0
	v_mul_f32_e32 v145, 0x45800000, v144
	v_cndmask_b32_e32 v144, v144, v145, vcc
	v_lshrrev_b32_e32 v145, 1, v146
	v_and_b32_e32 v145, 24, v145
	v_mul_f32 v128, v128, v144
	v_mul_f32 v129, v129, v144
	v_mul_f32 v120, v120, v144
	v_mul_f32 v121, v121, v144
	v_mul_f32_e32 v146, 0xbfb8aa3b, v128
	v_mul_f32_e32 v147, 0xbfb8aa3b, v129
	v_exp_f32_e32 v146, v146
	v_exp_f32_e32 v147, v147
	v_mul_f32 v122, v122, v144
	v_mul_f32 v123, v123, v144
	v_mul_f32 v116, v116, v144
	v_mul_f32 v117, v117, v144
	v_add_f32_e32 v146, 1.0, v146
	v_add_f32_e32 v147, 1.0, v147
	v_rcp_f32_e32 v146, v146
	v_rcp_f32_e32 v147, v147
	v_mul_f32 v118, v118, v144
	v_mul_f32 v119, v119, v144
	s_and_b64 vcc, exec, s[0:1]
	v_mul_f32 v128, v128, v146
	v_mul_f32 v129, v129, v147
	s_nop 0
	v_mul_f32 v128, v120, v128
	v_mul_f32 v129, v121, v129
	v_mul_f32 v120, v130, v144
	v_mul_f32 v121, v131, v144
	s_nop 0
	v_mul_f32_e32 v130, 0xbfb8aa3b, v120
	v_mul_f32_e32 v131, 0xbfb8aa3b, v121
	v_exp_f32_e32 v130, v130
	v_exp_f32_e32 v131, v131
	v_add_f32_e32 v130, 1.0, v130
	v_add_f32_e32 v131, 1.0, v131
	v_rcp_f32_e32 v130, v130
	v_rcp_f32_e32 v131, v131
	s_nop 0
	v_mul_f32 v120, v120, v130
	v_mul_f32 v121, v121, v131
	s_nop 0
	v_mul_f32 v130, v122, v120
	v_mul_f32 v131, v123, v121
	v_mul_f32 v120, v124, v144
	v_mul_f32 v121, v125, v144
	s_nop 0
	v_mul_f32_e32 v122, 0xbfb8aa3b, v120
	v_mul_f32_e32 v123, 0xbfb8aa3b, v121
	v_exp_f32_e32 v122, v122
	v_exp_f32_e32 v123, v123
	v_add_f32_e32 v122, 1.0, v122
	v_add_f32_e32 v123, 1.0, v123
	v_rcp_f32_e32 v122, v122
	v_rcp_f32_e32 v123, v123
	s_nop 0
	v_mul_f32 v120, v120, v122
	v_mul_f32 v121, v121, v123
	s_nop 0
	v_mul_f32 v124, v116, v120
	v_mul_f32 v125, v117, v121
	v_mul_f32 v116, v126, v144
	v_mul_f32 v117, v127, v144
	s_nop 0
	v_mul_f32_e32 v120, 0xbfb8aa3b, v116
	v_mul_f32_e32 v121, 0xbfb8aa3b, v117
	v_exp_f32_e32 v120, v120
	v_exp_f32_e32 v121, v121
	v_add_f32_e32 v120, 1.0, v120
	v_add_f32_e32 v121, 1.0, v121
	v_rcp_f32_e32 v120, v120
	v_rcp_f32_e32 v121, v121
	s_nop 0
	v_mul_f32 v116, v116, v120
	v_mul_f32 v117, v117, v121
	s_nop 0
	v_mul_f32 v126, v118, v116
	v_mul_f32 v127, v119, v117
	v_mov_b64_e32 v[116:117], s[54:55]
	v_mad_i64_i32 v[116:117], s[14:15], v136, s76, v[116:117]
	v_lshl_add_u64 v[116:117], s[92:93], 1, v[116:117]
	v_lshl_add_u64 v[116:117], v[116:117], 0, s[68:69]
	v_lshlrev_b32_e32 v120, 1, v145
	v_mov_b32_e32 v121, v2
	v_lshl_add_u64 v[122:123], v[116:117], 0, v[120:121]
	v_cvt_pk_bf16_f32 v116, v128, v129
	v_cvt_pk_bf16_f32 v117, v130, v131
	v_cvt_pk_bf16_f32 v118, v124, v125
	v_cvt_pk_bf16_f32 v119, v126, v127
	s_cbranch_vccz .LBB0_2852
	global_store_dwordx4 v[122:123], v[116:119], off
	s_mov_b64 s[8:9], 0

.LBB0_2854:
	v_fmamk_f32 v116, v143, 0x3a800000, v231
	v_cmp_gt_f32_e32 vcc, s11, v116
	v_mul_f32_e32 v117, 0x4b800000, v116
	v_mov_b32_e32 v121, v2
	v_cndmask_b32_e32 v116, v116, v117, vcc
	v_rsq_f32_e32 v116, v116
	s_nop 0
	v_mul_f32_e32 v117, 0x45800000, v116
	v_cndmask_b32_e32 v116, v116, v117, vcc
	v_mul_f32 v112, v112, v116
	v_mul_f32 v113, v113, v116
	s_andn2_b64 vcc, exec, s[0:1]
	v_mul_f32_e32 v117, 0xbfb8aa3b, v112
	v_exp_f32_e32 v117, v117
	s_nop 0
	v_add_f32_e32 v117, 1.0, v117
	v_rcp_f32_e32 v118, v117
	v_mul_f32_e32 v117, 0xbfb8aa3b, v113
	v_exp_f32_e32 v117, v117
	s_nop 0
	v_add_f32_e32 v117, 1.0, v117
	v_rcp_f32_e32 v119, v117
	v_mul_f32 v108, v108, v116
	v_mul_f32 v109, v109, v116
	v_mul_f32 v110, v110, v116
	v_mul_f32 v111, v111, v116
	v_mul_f32 v104, v104, v116
	v_mul_f32 v105, v105, v116
	v_mul_f32 v112, v112, v118
	v_mul_f32 v113, v113, v119
	v_mul_f32 v100, v100, v116
	v_mul_f32 v101, v101, v116
	v_mul_f32 v108, v108, v112
	v_mul_f32 v109, v109, v113
	v_mul_f32 v112, v114, v116
	v_mul_f32 v113, v115, v116
	v_mul_f32 v102, v102, v116
	v_mul_f32 v103, v103, v116
	v_mul_f32_e32 v114, 0xbfb8aa3b, v112
	v_mul_f32_e32 v115, 0xbfb8aa3b, v113
	v_exp_f32_e32 v114, v114
	v_exp_f32_e32 v115, v115
	v_add_f32_e32 v114, 1.0, v114
	v_add_f32_e32 v115, 1.0, v115
	v_rcp_f32_e32 v114, v114
	v_rcp_f32_e32 v115, v115
	s_nop 0
	v_mul_f32 v112, v112, v114
	v_mul_f32 v113, v113, v115
	s_nop 0
	v_mul_f32 v110, v110, v112
	v_mul_f32 v111, v111, v113
	v_mul_f32_e32 v112, 0xbfb8aa3b, v104
	v_mul_f32_e32 v113, 0xbfb8aa3b, v105
	v_exp_f32_e32 v112, v112
	v_exp_f32_e32 v113, v113
	v_add_f32_e32 v112, 1.0, v112
	v_add_f32_e32 v113, 1.0, v113
	v_rcp_f32_e32 v112, v112
	v_rcp_f32_e32 v113, v113
	s_nop 0
	v_mul_f32 v104, v104, v112
	v_mul_f32 v105, v105, v113
	s_nop 0
	v_mul_f32 v112, v100, v104
	v_mul_f32 v113, v101, v105
	v_mul_f32 v100, v106, v116
	v_mul_f32 v101, v107, v116
	s_nop 0
	v_mul_f32_e32 v104, 0xbfb8aa3b, v100
	v_mul_f32_e32 v105, 0xbfb8aa3b, v101
	v_exp_f32_e32 v104, v104
	v_exp_f32_e32 v105, v105
	v_add_f32_e32 v104, 1.0, v104
	v_add_f32_e32 v105, 1.0, v105
	v_rcp_f32_e32 v104, v104
	v_rcp_f32_e32 v105, v105
	s_nop 0
	v_mul_f32 v100, v100, v104
	v_mul_f32 v101, v101, v105
	s_nop 0
	v_mul_f32 v106, v102, v100
	v_mul_f32 v107, v103, v101
	v_or_b32_e32 v102, 16, v136
	v_mov_b64_e32 v[100:101], s[54:55]
	v_mad_i64_i32 v[100:101], s[8:9], v102, s76, v[100:101]
	v_lshl_add_u64 v[100:101], s[92:93], 1, v[100:101]
	v_lshl_add_u64 v[100:101], v[100:101], 0, s[68:69]
	v_cvt_pk_bf16_f32 v103, v106, v107
	v_cndmask_b32_e64 v106, 0, 1, s[0:1]
	v_lshl_add_u64 v[104:105], v[100:101], 0, v[120:121]
	v_cvt_pk_bf16_f32 v100, v108, v109
	v_cvt_pk_bf16_f32 v101, v110, v111
	v_cvt_pk_bf16_f32 v102, v112, v113
	s_mov_b64 s[8:9], -1
	v_cmp_ne_u32_e64 s[16:17], 1, v106
	s_cbranch_vccnz .LBB0_2856
	s_mov_b64 s[8:9], 0
	global_store_dwordx4 v[104:105], v[100:103], off

.LBB0_2858:
	v_fmamk_f32 v100, v142, 0x3a800000, v231
	v_cmp_gt_f32_e32 vcc, s11, v100
	v_mul_f32_e32 v101, 0x4b800000, v100
	v_mov_b32_e32 v121, v2
	v_cndmask_b32_e32 v100, v100, v101, vcc
	v_rsq_f32_e32 v100, v100
	s_nop 0
	v_mul_f32_e32 v101, 0x45800000, v100
	v_cndmask_b32_e32 v100, v100, v101, vcc
	v_mul_f32 v96, v96, v100
	v_mul_f32 v97, v97, v100
	s_and_b64 vcc, exec, s[16:17]
	v_mul_f32_e32 v101, 0xbfb8aa3b, v96
	v_exp_f32_e32 v101, v101
	s_nop 0
	v_add_f32_e32 v101, 1.0, v101
	v_rcp_f32_e32 v102, v101
	v_mul_f32_e32 v101, 0xbfb8aa3b, v97
	v_exp_f32_e32 v101, v101
	s_nop 0
	v_add_f32_e32 v101, 1.0, v101
	v_rcp_f32_e32 v103, v101
	v_mul_f32 v92, v92, v100
	v_mul_f32 v93, v93, v100
	v_mul_f32 v94, v94, v100
	v_mul_f32 v95, v95, v100
	v_mul_f32 v88, v88, v100
	v_mul_f32 v89, v89, v100
	v_mul_f32 v96, v96, v102
	v_mul_f32 v97, v97, v103
	v_mul_f32 v84, v84, v100
	v_mul_f32 v85, v85, v100
	v_mul_f32 v92, v92, v96
	v_mul_f32 v93, v93, v97
	v_mul_f32 v96, v98, v100
	v_mul_f32 v97, v99, v100
	v_mul_f32 v86, v86, v100
	v_mul_f32 v87, v87, v100
	v_mul_f32_e32 v98, 0xbfb8aa3b, v96
	v_mul_f32_e32 v99, 0xbfb8aa3b, v97
	v_exp_f32_e32 v98, v98
	v_exp_f32_e32 v99, v99
	v_add_f32_e32 v98, 1.0, v98
	v_add_f32_e32 v99, 1.0, v99
	v_rcp_f32_e32 v98, v98
	v_rcp_f32_e32 v99, v99
	s_nop 0
	v_mul_f32 v96, v96, v98
	v_mul_f32 v97, v97, v99
	s_nop 0
	v_mul_f32 v94, v94, v96
	v_mul_f32 v95, v95, v97
	v_mul_f32_e32 v96, 0xbfb8aa3b, v88
	v_mul_f32_e32 v97, 0xbfb8aa3b, v89
	v_exp_f32_e32 v96, v96
	v_exp_f32_e32 v97, v97
	v_add_f32_e32 v96, 1.0, v96
	v_add_f32_e32 v97, 1.0, v97
	v_rcp_f32_e32 v96, v96
	v_rcp_f32_e32 v97, v97
	s_nop 0
	v_mul_f32 v88, v88, v96
	v_mul_f32 v89, v89, v97
	s_nop 0
	v_mul_f32 v96, v84, v88
	v_mul_f32 v97, v85, v89
	v_mul_f32 v84, v90, v100
	v_mul_f32 v85, v91, v100
	s_nop 0
	v_mul_f32_e32 v88, 0xbfb8aa3b, v84
	v_mul_f32_e32 v89, 0xbfb8aa3b, v85
	v_exp_f32_e32 v88, v88
	v_exp_f32_e32 v89, v89
	v_add_f32_e32 v88, 1.0, v88
	v_add_f32_e32 v89, 1.0, v89
	v_rcp_f32_e32 v88, v88
	v_rcp_f32_e32 v89, v89
	s_nop 0
	v_mul_f32 v84, v84, v88
	v_mul_f32 v85, v85, v89
	s_nop 0
	v_mul_f32 v90, v86, v84
	v_mul_f32 v91, v87, v85
	v_or_b32_e32 v86, 32, v136
	v_mov_b64_e32 v[84:85], s[54:55]
	v_mad_i64_i32 v[84:85], s[0:1], v86, s76, v[84:85]
	v_lshl_add_u64 v[84:85], s[92:93], 1, v[84:85]
	v_lshl_add_u64 v[84:85], v[84:85], 0, s[68:69]
	v_lshl_add_u64 v[88:89], v[84:85], 0, v[120:121]
	v_cvt_pk_bf16_f32 v84, v92, v93
	v_cvt_pk_bf16_f32 v85, v94, v95
	v_cvt_pk_bf16_f32 v86, v96, v97
	v_cvt_pk_bf16_f32 v87, v90, v91
	s_mov_b64 s[0:1], -1
	s_cbranch_vccnz .LBB0_2860
	s_mov_b64 s[0:1], 0
	global_store_dwordx4 v[88:89], v[84:87], off

.LBB0_2862:
	v_fmamk_f32 v84, v141, 0x3a800000, v231
	v_cmp_gt_f32_e32 vcc, s11, v84
	v_mul_f32_e32 v85, 0x4b800000, v84
	v_mov_b32_e32 v121, v2
	v_cndmask_b32_e32 v84, v84, v85, vcc
	v_rsq_f32_e32 v84, v84
	s_nop 0
	v_mul_f32_e32 v85, 0x45800000, v84
	v_cndmask_b32_e32 v84, v84, v85, vcc
	v_mul_f32 v80, v80, v84
	v_mul_f32 v81, v81, v84
	s_and_b64 vcc, exec, s[16:17]
	v_mul_f32_e32 v85, 0xbfb8aa3b, v80
	v_exp_f32_e32 v85, v85
	s_nop 0
	v_add_f32_e32 v85, 1.0, v85
	v_rcp_f32_e32 v86, v85
	v_mul_f32_e32 v85, 0xbfb8aa3b, v81
	v_exp_f32_e32 v85, v85
	s_nop 0
	v_add_f32_e32 v85, 1.0, v85
	v_rcp_f32_e32 v87, v85
	v_mul_f32 v76, v76, v84
	v_mul_f32 v77, v77, v84
	v_mul_f32 v78, v78, v84
	v_mul_f32 v79, v79, v84
	v_mul_f32 v72, v72, v84
	v_mul_f32 v73, v73, v84
	v_mul_f32 v80, v80, v86
	v_mul_f32 v81, v81, v87
	v_mul_f32 v68, v68, v84
	v_mul_f32 v69, v69, v84
	v_mul_f32 v76, v76, v80
	v_mul_f32 v77, v77, v81
	v_mul_f32 v80, v82, v84
	v_mul_f32 v81, v83, v84
	v_mul_f32 v70, v70, v84
	v_mul_f32 v71, v71, v84
	v_mul_f32_e32 v82, 0xbfb8aa3b, v80
	v_mul_f32_e32 v83, 0xbfb8aa3b, v81
	v_exp_f32_e32 v82, v82
	v_exp_f32_e32 v83, v83
	v_add_f32_e32 v82, 1.0, v82
	v_add_f32_e32 v83, 1.0, v83
	v_rcp_f32_e32 v82, v82
	v_rcp_f32_e32 v83, v83
	s_nop 0
	v_mul_f32 v80, v80, v82
	v_mul_f32 v81, v81, v83
	s_nop 0
	v_mul_f32 v78, v78, v80
	v_mul_f32 v79, v79, v81
	v_mul_f32_e32 v80, 0xbfb8aa3b, v72
	v_mul_f32_e32 v81, 0xbfb8aa3b, v73
	v_exp_f32_e32 v80, v80
	v_exp_f32_e32 v81, v81
	v_add_f32_e32 v80, 1.0, v80
	v_add_f32_e32 v81, 1.0, v81
	v_rcp_f32_e32 v80, v80
	v_rcp_f32_e32 v81, v81
	s_nop 0
	v_mul_f32 v72, v72, v80
	v_mul_f32 v73, v73, v81
	s_nop 0
	v_mul_f32 v80, v68, v72
	v_mul_f32 v81, v69, v73
	v_mul_f32 v68, v74, v84
	v_mul_f32 v69, v75, v84
	s_nop 0
	v_mul_f32_e32 v72, 0xbfb8aa3b, v68
	v_mul_f32_e32 v73, 0xbfb8aa3b, v69
	v_exp_f32_e32 v72, v72
	v_exp_f32_e32 v73, v73
	v_add_f32_e32 v72, 1.0, v72
	v_add_f32_e32 v73, 1.0, v73
	v_rcp_f32_e32 v72, v72
	v_rcp_f32_e32 v73, v73
	s_nop 0
	v_mul_f32 v68, v68, v72
	v_mul_f32 v69, v69, v73
	s_nop 0
	v_mul_f32 v74, v70, v68
	v_mul_f32 v75, v71, v69
	v_or_b32_e32 v70, 48, v136
	v_mov_b64_e32 v[68:69], s[54:55]
	v_mad_i64_i32 v[68:69], s[0:1], v70, s76, v[68:69]
	v_lshl_add_u64 v[68:69], s[92:93], 1, v[68:69]
	v_lshl_add_u64 v[68:69], v[68:69], 0, s[68:69]
	v_lshl_add_u64 v[72:73], v[68:69], 0, v[120:121]
	v_cvt_pk_bf16_f32 v68, v76, v77
	v_cvt_pk_bf16_f32 v69, v78, v79
	v_cvt_pk_bf16_f32 v70, v80, v81
	v_cvt_pk_bf16_f32 v71, v74, v75
	s_mov_b64 s[0:1], -1
	s_cbranch_vccnz .LBB0_2864
	s_mov_b64 s[0:1], 0
	global_store_dwordx4 v[72:73], v[68:71], off

.LBB0_2866:
	v_fmamk_f32 v68, v140, 0x3a800000, v231
	v_cmp_gt_f32_e32 vcc, s11, v68
	v_mul_f32_e32 v70, 0x4b800000, v68
	v_add_u32_e32 v69, 0x80, v136
	v_cndmask_b32_e32 v68, v68, v70, vcc
	v_rsq_f32_e32 v68, v68
	v_mov_b32_e32 v121, v2
	v_mul_f32_e32 v70, 0x45800000, v68
	v_cndmask_b32_e32 v68, v68, v70, vcc
	v_mul_f32 v64, v64, v68
	v_mul_f32 v65, v65, v68
	v_mul_f32 v60, v60, v68
	v_mul_f32 v61, v61, v68
	v_mul_f32_e32 v70, 0xbfb8aa3b, v64
	v_mul_f32_e32 v71, 0xbfb8aa3b, v65
	v_exp_f32_e32 v70, v70
	v_exp_f32_e32 v71, v71
	v_mul_f32 v62, v62, v68
	v_mul_f32 v63, v63, v68
	v_mul_f32 v56, v56, v68
	v_mul_f32 v57, v57, v68
	v_add_f32_e32 v70, 1.0, v70
	v_add_f32_e32 v71, 1.0, v71
	v_rcp_f32_e32 v70, v70
	v_rcp_f32_e32 v71, v71
	v_mul_f32 v52, v52, v68
	v_mul_f32 v53, v53, v68
	v_mul_f32 v54, v54, v68
	v_mul_f32 v55, v55, v68
	s_and_b64 vcc, exec, s[16:17]
	v_mul_f32 v64, v64, v70
	v_mul_f32 v65, v65, v71
	s_nop 0
	v_mul_f32 v60, v60, v64
	v_mul_f32 v61, v61, v65
	v_mul_f32 v64, v66, v68
	v_mul_f32 v65, v67, v68
	s_nop 0
	v_mul_f32_e32 v66, 0xbfb8aa3b, v64
	v_mul_f32_e32 v67, 0xbfb8aa3b, v65
	v_exp_f32_e32 v66, v66
	v_exp_f32_e32 v67, v67
	v_add_f32_e32 v66, 1.0, v66
	v_add_f32_e32 v67, 1.0, v67
	v_rcp_f32_e32 v66, v66
	v_rcp_f32_e32 v67, v67
	s_nop 0
	v_mul_f32 v64, v64, v66
	v_mul_f32 v65, v65, v67
	s_nop 0
	v_mul_f32 v62, v62, v64
	v_mul_f32 v63, v63, v65
	v_mul_f32_e32 v64, 0xbfb8aa3b, v56
	v_mul_f32_e32 v65, 0xbfb8aa3b, v57
	v_exp_f32_e32 v64, v64
	v_exp_f32_e32 v65, v65
	v_add_f32_e32 v64, 1.0, v64
	v_add_f32_e32 v65, 1.0, v65
	v_rcp_f32_e32 v64, v64
	v_rcp_f32_e32 v65, v65
	s_nop 0
	v_mul_f32 v56, v56, v64
	v_mul_f32 v57, v57, v65
	s_nop 0
	v_mul_f32 v64, v52, v56
	v_mul_f32 v65, v53, v57
	v_mul_f32 v52, v58, v68
	v_mul_f32 v53, v59, v68
	s_nop 0
	v_mul_f32_e32 v56, 0xbfb8aa3b, v52
	v_mul_f32_e32 v57, 0xbfb8aa3b, v53
	v_exp_f32_e32 v56, v56
	v_exp_f32_e32 v57, v57
	v_add_f32_e32 v56, 1.0, v56
	v_add_f32_e32 v57, 1.0, v57
	v_rcp_f32_e32 v56, v56
	v_rcp_f32_e32 v57, v57
	s_nop 0
	v_mul_f32 v52, v52, v56
	v_mul_f32 v53, v53, v57
	s_nop 0
	v_mul_f32 v58, v54, v52
	v_mul_f32 v59, v55, v53
	v_mov_b64_e32 v[52:53], s[54:55]
	v_mad_i64_i32 v[52:53], s[0:1], v69, s76, v[52:53]
	v_lshl_add_u64 v[52:53], s[92:93], 1, v[52:53]
	v_lshl_add_u64 v[52:53], v[52:53], 0, s[68:69]
	v_lshl_add_u64 v[56:57], v[52:53], 0, v[120:121]
	v_cvt_pk_bf16_f32 v52, v60, v61
	v_cvt_pk_bf16_f32 v53, v62, v63
	v_cvt_pk_bf16_f32 v54, v64, v65
	v_cvt_pk_bf16_f32 v55, v58, v59
	s_mov_b64 s[0:1], -1
	s_cbranch_vccnz .LBB0_2868
	s_mov_b64 s[0:1], 0
	global_store_dwordx4 v[56:57], v[52:55], off

.LBB0_2870:
	v_fmamk_f32 v52, v139, 0x3a800000, v231
	v_cmp_gt_f32_e32 vcc, s11, v52
	v_mul_f32_e32 v54, 0x4b800000, v52
	v_add_u32_e32 v53, 0x90, v136
	v_cndmask_b32_e32 v52, v52, v54, vcc
	v_rsq_f32_e32 v52, v52
	v_mov_b32_e32 v121, v2
	v_mul_f32_e32 v54, 0x45800000, v52
	v_cndmask_b32_e32 v52, v52, v54, vcc
	v_mul_f32 v48, v48, v52
	v_mul_f32 v49, v49, v52
	v_mul_f32 v44, v44, v52
	v_mul_f32 v45, v45, v52
	v_mul_f32_e32 v54, 0xbfb8aa3b, v48
	v_mul_f32_e32 v55, 0xbfb8aa3b, v49
	v_exp_f32_e32 v54, v54
	v_exp_f32_e32 v55, v55
	v_mul_f32 v46, v46, v52
	v_mul_f32 v47, v47, v52
	v_mul_f32 v40, v40, v52
	v_mul_f32 v41, v41, v52
	v_add_f32_e32 v54, 1.0, v54
	v_add_f32_e32 v55, 1.0, v55
	v_rcp_f32_e32 v54, v54
	v_rcp_f32_e32 v55, v55
	v_mul_f32 v36, v36, v52
	v_mul_f32 v37, v37, v52
	v_mul_f32 v38, v38, v52
	v_mul_f32 v39, v39, v52
	s_and_b64 vcc, exec, s[16:17]
	v_mul_f32 v48, v48, v54
	v_mul_f32 v49, v49, v55
	s_nop 0
	v_mul_f32 v44, v44, v48
	v_mul_f32 v45, v45, v49
	v_mul_f32 v48, v50, v52
	v_mul_f32 v49, v51, v52
	s_nop 0
	v_mul_f32_e32 v50, 0xbfb8aa3b, v48
	v_mul_f32_e32 v51, 0xbfb8aa3b, v49
	v_exp_f32_e32 v50, v50
	v_exp_f32_e32 v51, v51
	v_add_f32_e32 v50, 1.0, v50
	v_add_f32_e32 v51, 1.0, v51
	v_rcp_f32_e32 v50, v50
	v_rcp_f32_e32 v51, v51
	s_nop 0
	v_mul_f32 v48, v48, v50
	v_mul_f32 v49, v49, v51
	s_nop 0
	v_mul_f32 v46, v46, v48
	v_mul_f32 v47, v47, v49
	v_mul_f32_e32 v48, 0xbfb8aa3b, v40
	v_mul_f32_e32 v49, 0xbfb8aa3b, v41
	v_exp_f32_e32 v48, v48
	v_exp_f32_e32 v49, v49
	v_add_f32_e32 v48, 1.0, v48
	v_add_f32_e32 v49, 1.0, v49
	v_rcp_f32_e32 v48, v48
	v_rcp_f32_e32 v49, v49
	s_nop 0
	v_mul_f32 v40, v40, v48
	v_mul_f32 v41, v41, v49
	s_nop 0
	v_mul_f32 v48, v36, v40
	v_mul_f32 v49, v37, v41
	v_mul_f32 v36, v42, v52
	v_mul_f32 v37, v43, v52
	s_nop 0
	v_mul_f32_e32 v40, 0xbfb8aa3b, v36
	v_mul_f32_e32 v41, 0xbfb8aa3b, v37
	v_exp_f32_e32 v40, v40
	v_exp_f32_e32 v41, v41
	v_add_f32_e32 v40, 1.0, v40
	v_add_f32_e32 v41, 1.0, v41
	v_rcp_f32_e32 v40, v40
	v_rcp_f32_e32 v41, v41
	s_nop 0
	v_mul_f32 v36, v36, v40
	v_mul_f32 v37, v37, v41
	s_nop 0
	v_mul_f32 v42, v38, v36
	v_mul_f32 v43, v39, v37
	v_mov_b64_e32 v[36:37], s[54:55]
	v_mad_i64_i32 v[36:37], s[0:1], v53, s76, v[36:37]
	v_lshl_add_u64 v[36:37], s[92:93], 1, v[36:37]
	v_lshl_add_u64 v[36:37], v[36:37], 0, s[68:69]
	v_lshl_add_u64 v[40:41], v[36:37], 0, v[120:121]
	v_cvt_pk_bf16_f32 v36, v44, v45
	v_cvt_pk_bf16_f32 v37, v46, v47
	v_cvt_pk_bf16_f32 v38, v48, v49
	v_cvt_pk_bf16_f32 v39, v42, v43
	s_mov_b64 s[0:1], -1
	s_cbranch_vccnz .LBB0_2872
	s_mov_b64 s[0:1], 0
	global_store_dwordx4 v[40:41], v[36:39], off

.LBB0_2874:
	v_fmamk_f32 v36, v138, 0x3a800000, v231
	v_cmp_gt_f32_e32 vcc, s11, v36
	v_mul_f32_e32 v38, 0x4b800000, v36
	v_add_u32_e32 v37, 0xa0, v136
	v_cndmask_b32_e32 v36, v36, v38, vcc
	v_rsq_f32_e32 v36, v36
	v_mov_b32_e32 v121, v2
	v_mul_f32_e32 v38, 0x45800000, v36
	v_cndmask_b32_e32 v36, v36, v38, vcc
	v_mul_f32 v32, v32, v36
	v_mul_f32 v33, v33, v36
	v_mul_f32 v28, v28, v36
	v_mul_f32 v29, v29, v36
	v_mul_f32_e32 v38, 0xbfb8aa3b, v32
	v_mul_f32_e32 v39, 0xbfb8aa3b, v33
	v_exp_f32_e32 v38, v38
	v_exp_f32_e32 v39, v39
	v_mul_f32 v30, v30, v36
	v_mul_f32 v31, v31, v36
	v_mul_f32 v24, v24, v36
	v_mul_f32 v25, v25, v36
	v_add_f32_e32 v38, 1.0, v38
	v_add_f32_e32 v39, 1.0, v39
	v_rcp_f32_e32 v38, v38
	v_rcp_f32_e32 v39, v39
	v_mul_f32 v20, v20, v36
	v_mul_f32 v21, v21, v36
	v_mul_f32 v22, v22, v36
	v_mul_f32 v23, v23, v36
	s_and_b64 vcc, exec, s[16:17]
	v_mul_f32 v32, v32, v38
	v_mul_f32 v33, v33, v39
	s_nop 0
	v_mul_f32 v28, v28, v32
	v_mul_f32 v29, v29, v33
	v_mul_f32 v32, v34, v36
	v_mul_f32 v33, v35, v36
	s_nop 0
	v_mul_f32_e32 v34, 0xbfb8aa3b, v32
	v_mul_f32_e32 v35, 0xbfb8aa3b, v33
	v_exp_f32_e32 v34, v34
	v_exp_f32_e32 v35, v35
	v_add_f32_e32 v34, 1.0, v34
	v_add_f32_e32 v35, 1.0, v35
	v_rcp_f32_e32 v34, v34
	v_rcp_f32_e32 v35, v35
	s_nop 0
	v_mul_f32 v32, v32, v34
	v_mul_f32 v33, v33, v35
	s_nop 0
	v_mul_f32 v30, v30, v32
	v_mul_f32 v31, v31, v33
	v_mul_f32_e32 v32, 0xbfb8aa3b, v24
	v_mul_f32_e32 v33, 0xbfb8aa3b, v25
	v_exp_f32_e32 v32, v32
	v_exp_f32_e32 v33, v33
	v_add_f32_e32 v32, 1.0, v32
	v_add_f32_e32 v33, 1.0, v33
	v_rcp_f32_e32 v32, v32
	v_rcp_f32_e32 v33, v33
	s_nop 0
	v_mul_f32 v24, v24, v32
	v_mul_f32 v25, v25, v33
	s_nop 0
	v_mul_f32 v32, v20, v24
	v_mul_f32 v33, v21, v25
	v_mul_f32 v20, v26, v36
	v_mul_f32 v21, v27, v36
	s_nop 0
	v_mul_f32_e32 v24, 0xbfb8aa3b, v20
	v_mul_f32_e32 v25, 0xbfb8aa3b, v21
	v_exp_f32_e32 v24, v24
	v_exp_f32_e32 v25, v25
	v_add_f32_e32 v24, 1.0, v24
	v_add_f32_e32 v25, 1.0, v25
	v_rcp_f32_e32 v24, v24
	v_rcp_f32_e32 v25, v25
	s_nop 0
	v_mul_f32 v20, v20, v24
	v_mul_f32 v21, v21, v25
	s_nop 0
	v_mul_f32 v26, v22, v20
	v_mul_f32 v27, v23, v21
	v_mov_b64_e32 v[20:21], s[54:55]
	v_mad_i64_i32 v[20:21], s[0:1], v37, s76, v[20:21]
	v_lshl_add_u64 v[20:21], s[92:93], 1, v[20:21]
	v_lshl_add_u64 v[20:21], v[20:21], 0, s[68:69]
	v_lshl_add_u64 v[24:25], v[20:21], 0, v[120:121]
	v_cvt_pk_bf16_f32 v20, v28, v29
	v_cvt_pk_bf16_f32 v21, v30, v31
	v_cvt_pk_bf16_f32 v22, v32, v33
	v_cvt_pk_bf16_f32 v23, v26, v27
	s_mov_b64 s[0:1], -1
	s_cbranch_vccnz .LBB0_2876
	s_mov_b64 s[0:1], 0
	global_store_dwordx4 v[24:25], v[20:23], off

.LBB0_2878:
	v_fmamk_f32 v20, v137, 0x3a800000, v231
	v_cmp_gt_f32_e32 vcc, s11, v20
	v_mul_f32_e32 v22, 0x4b800000, v20
	v_add_u32_e32 v21, 0xb0, v136
	v_cndmask_b32_e32 v20, v20, v22, vcc
	v_rsq_f32_e32 v20, v20
	v_mov_b32_e32 v121, v2
	v_mul_f32_e32 v22, 0x45800000, v20
	v_cndmask_b32_e32 v20, v20, v22, vcc
	v_mul_f32 v16, v16, v20
	v_mul_f32 v17, v17, v20
	v_mul_f32 v12, v12, v20
	v_mul_f32 v13, v13, v20
	v_mul_f32_e32 v22, 0xbfb8aa3b, v16
	v_mul_f32_e32 v23, 0xbfb8aa3b, v17
	v_exp_f32_e32 v22, v22
	v_exp_f32_e32 v23, v23
	v_mul_f32 v14, v14, v20
	v_mul_f32 v15, v15, v20
	v_mul_f32 v8, v8, v20
	v_mul_f32 v9, v9, v20
	v_add_f32_e32 v22, 1.0, v22
	v_add_f32_e32 v23, 1.0, v23
	v_rcp_f32_e32 v22, v22
	v_rcp_f32_e32 v23, v23
	v_mul_f32 v4, v4, v20
	v_mul_f32 v5, v5, v20
	v_mul_f32 v6, v6, v20
	v_mul_f32 v7, v7, v20
	s_and_b64 vcc, exec, s[16:17]
	v_mul_f32 v16, v16, v22
	v_mul_f32 v17, v17, v23
	s_nop 0
	v_mul_f32 v12, v12, v16
	v_mul_f32 v13, v13, v17
	v_mul_f32 v16, v18, v20
	v_mul_f32 v17, v19, v20
	s_nop 0
	v_mul_f32_e32 v18, 0xbfb8aa3b, v16
	v_mul_f32_e32 v19, 0xbfb8aa3b, v17
	v_exp_f32_e32 v18, v18
	v_exp_f32_e32 v19, v19
	v_add_f32_e32 v18, 1.0, v18
	v_add_f32_e32 v19, 1.0, v19
	v_rcp_f32_e32 v18, v18
	v_rcp_f32_e32 v19, v19
	s_nop 0
	v_mul_f32 v16, v16, v18
	v_mul_f32 v17, v17, v19
	s_nop 0
	v_mul_f32 v14, v14, v16
	v_mul_f32 v15, v15, v17
	v_mul_f32_e32 v16, 0xbfb8aa3b, v8
	v_mul_f32_e32 v17, 0xbfb8aa3b, v9
	v_exp_f32_e32 v16, v16
	v_exp_f32_e32 v17, v17
	v_add_f32_e32 v16, 1.0, v16
	v_add_f32_e32 v17, 1.0, v17
	v_rcp_f32_e32 v16, v16
	v_rcp_f32_e32 v17, v17
	s_nop 0
	v_mul_f32 v8, v8, v16
	v_mul_f32 v9, v9, v17
	s_nop 0
	v_mul_f32 v16, v4, v8
	v_mul_f32 v17, v5, v9
	v_mul_f32 v4, v10, v20
	v_mul_f32 v5, v11, v20
	s_nop 0
	v_mul_f32_e32 v8, 0xbfb8aa3b, v4
	v_mul_f32_e32 v9, 0xbfb8aa3b, v5
	v_exp_f32_e32 v8, v8
	v_exp_f32_e32 v9, v9
	v_add_f32_e32 v8, 1.0, v8
	v_add_f32_e32 v9, 1.0, v9
	v_rcp_f32_e32 v8, v8
	v_rcp_f32_e32 v9, v9
	s_nop 0
	v_mul_f32 v4, v4, v8
	v_mul_f32 v5, v5, v9
	s_nop 0
	v_mul_f32 v10, v6, v4
	v_mul_f32 v11, v7, v5
	v_mov_b64_e32 v[4:5], s[54:55]
	v_mad_i64_i32 v[4:5], s[0:1], v21, s76, v[4:5]
	v_lshl_add_u64 v[4:5], s[92:93], 1, v[4:5]
	v_lshl_add_u64 v[4:5], v[4:5], 0, s[68:69]
	v_lshl_add_u64 v[8:9], v[4:5], 0, v[120:121]
	v_cvt_pk_bf16_f32 v4, v12, v13
	v_cvt_pk_bf16_f32 v5, v14, v15
	v_cvt_pk_bf16_f32 v6, v16, v17
	v_cvt_pk_bf16_f32 v7, v10, v11
	s_mov_b64 s[0:1], -1
	s_cbranch_vccnz .LBB0_2880
	s_mov_b64 s[0:1], 0
	global_store_dwordx4 v[8:9], v[4:7], off

.LBB0_3028:
	v_ashrrev_i32_e32 v3, 3, v3
	v_subrev_u32_e32 v68, s1, v3
	s_add_i32 s1, s68, s62
	v_add_u32_e32 v70, s1, v68
	v_ashrrev_i32_e32 v68, 8, v70
	v_ashrrev_i32_e32 v69, 31, v68
	v_and_b32_e32 v71, 3, v3
	v_lshlrev_b32_e32 v3, 2, v3
	v_lshrrev_b32_e32 v70, 1, v70
	v_lshlrev_b64 v[68:69], 8, v[68:69]
	v_and_b32_e32 v70, 0x6c, v70
	v_and_or_b32 v71, v3, s10, v71
	v_add_u32_e32 v3, 0, v3
	v_or3_b32 v68, v71, v70, v68
	s_and_b64 vcc, exec, s[22:23]
	v_mad_u32_u24 v3, v1, s96, v3
	s_waitcnt lgkmcnt(0)
	s_barrier
	s_cbranch_vccnz .LBB0_3032
	ds_read2_b32 v[72:73], v3 offset1:65
	v_add_u32_e32 v71, 0x400, v3
	v_or_b32_e32 v70, s0, v1
	s_waitcnt lgkmcnt(0)
	v_mul_f32 v64, v64, v72
	v_mul_f32 v65, v65, v73
	ds_read2_b32 v[72:73], v3 offset0:130 offset1:195
	s_waitcnt lgkmcnt(0)
	v_mul_f32 v66, v66, v72
	v_mul_f32 v67, v67, v73
	ds_read2_b32 v[72:73], v71 offset0:4 offset1:69
	s_waitcnt lgkmcnt(0)
	v_mul_f32 v72, v56, v72
	v_mul_f32 v73, v57, v73
	ds_read2_b32 v[56:57], v71 offset0:134 offset1:199
	v_ashrrev_i32_e32 v71, 31, v70
	s_waitcnt lgkmcnt(0)
	v_mul_f32 v74, v58, v56
	v_mul_f32 v75, v59, v57
	v_cvt_pk_bf16_f32 v56, v64, v65
	v_mad_u64_u32 v[64:65], s[0:1], v68, s40, 0
	v_cvt_pk_bf16_f32 v57, v66, v67
	v_mov_b32_e32 v66, v65
	v_mad_u64_u32 v[66:67], s[0:1], v69, s40, v[66:67]
	v_mov_b32_e32 v65, v66
	v_lshl_add_u64 v[64:65], v[64:65], 1, s[90:91]
	v_cvt_pk_bf16_f32 v58, v72, v73
	v_cvt_pk_bf16_f32 v59, v74, v75
	v_lshl_add_u64 v[64:65], v[70:71], 1, v[64:65]
	global_store_dwordx4 v[64:65], v[56:59], off
	s_nop 1
	v_add_u32_e32 v56, 0x4000, v3
	ds_read2_b32 v[56:57], v56 offset0:64 offset1:129
	v_add_u32_e32 v58, 0x4200, v3
	ds_read2_b32 v[58:59], v58 offset0:66 offset1:131
	s_waitcnt lgkmcnt(1)
	v_mul_f32 v56, v60, v56
	v_mul_f32 v57, v61, v57
	v_add_u32_e32 v60, 0x4400, v3
	ds_read2_b32 v[60:61], v60 offset0:68 offset1:133
	s_waitcnt lgkmcnt(1)
	v_mul_f32 v58, v62, v58
	v_mul_f32 v59, v63, v59
	s_waitcnt lgkmcnt(0)
	v_mul_f32 v60, v40, v60
	v_mul_f32 v61, v41, v61
	v_add_u32_e32 v40, 0x4600, v3
	ds_read2_b32 v[40:41], v40 offset0:70 offset1:135
	s_waitcnt lgkmcnt(0)
	v_mul_f32 v62, v42, v40
	v_mul_f32 v63, v43, v41
	v_cvt_pk_bf16_f32 v40, v56, v57
	v_cvt_pk_bf16_f32 v41, v58, v59
	v_cvt_pk_bf16_f32 v42, v60, v61
	v_cvt_pk_bf16_f32 v43, v62, v63
	global_store_dwordx4 v[64:65], v[40:43], off offset:128
	s_and_b64 vcc, exec, s[20:21]
	s_cbranch_vccz .LBB0_3033

.LBB0_3031:
	v_add_u32_e32 v33, 0x10400, v3
	ds_read_b32 v34, v33
	v_add_u32_e32 v33, 0x10504, v3
	ds_read_b32 v35, v33
	v_add_u32_e32 v33, 0x10608, v3
	v_or_b32_e32 v32, s14, v1
	s_waitcnt lgkmcnt(0)
	v_mul_f32 v34, v36, v34
	v_mul_f32 v35, v37, v35
	ds_read_b32 v36, v33
	v_add_u32_e32 v33, 0x1070c, v3
	ds_read_b32 v37, v33
	v_add_u32_e32 v33, 0x10810, v3
	s_waitcnt lgkmcnt(0)
	v_mul_f32 v36, v38, v36
	v_mul_f32 v37, v39, v37
	ds_read_b32 v38, v33
	v_add_u32_e32 v33, 0x10914, v3
	ds_read_b32 v39, v33
	v_ashrrev_i32_e32 v33, 31, v32
	s_waitcnt lgkmcnt(0)
	v_mul_f32 v38, v24, v38
	v_mul_f32 v39, v25, v39
	v_add_u32_e32 v24, 0x10a18, v3
	v_add_u32_e32 v25, 0x10b1c, v3
	ds_read_b32 v24, v24
	ds_read_b32 v25, v25
	s_waitcnt lgkmcnt(0)
	v_mul_f32 v40, v26, v24
	v_mul_f32 v41, v27, v25
	v_cvt_pk_bf16_f32 v24, v34, v35
	v_mad_u64_u32 v[34:35], s[0:1], v68, s40, 0
	v_cvt_pk_bf16_f32 v25, v36, v37
	v_mov_b32_e32 v36, v35
	v_mad_u64_u32 v[36:37], s[0:1], v69, s40, v[36:37]
	v_mov_b32_e32 v35, v36
	v_lshl_add_u64 v[34:35], v[34:35], 1, s[90:91]
	v_cvt_pk_bf16_f32 v26, v38, v39
	v_cvt_pk_bf16_f32 v27, v40, v41
	v_lshl_add_u64 v[32:33], v[32:33], 1, v[34:35]
	global_store_dwordx4 v[32:33], v[24:27], off
	s_nop 1
	v_add_u32_e32 v24, 0x14500, v3
	v_add_u32_e32 v25, 0x14604, v3
	ds_read_b32 v24, v24
	ds_read_b32 v25, v25
	v_add_u32_e32 v27, 0x1480c, v3
	v_add_u32_e32 v26, 0x14708, v3
	ds_read_b32 v27, v27
	ds_read_b32 v26, v26
	s_waitcnt lgkmcnt(2)
	v_mul_f32 v24, v28, v24
	v_mul_f32 v25, v29, v25
	v_add_u32_e32 v28, 0x14910, v3
	v_add_u32_e32 v29, 0x14a14, v3
	ds_read_b32 v28, v28
	ds_read_b32 v29, v29
	s_waitcnt lgkmcnt(0)
	v_mul_f32 v28, v16, v28
	v_mul_f32 v29, v17, v29
	v_add_u32_e32 v16, 0x14b18, v3
	v_add_u32_e32 v17, 0x14c1c, v3
	ds_read_b32 v16, v16
	ds_read_b32 v17, v17
	v_mul_f32 v26, v30, v26
	v_mul_f32 v27, v31, v27
	s_waitcnt lgkmcnt(0)
	v_mul_f32 v30, v18, v16
	v_mul_f32 v31, v19, v17
	v_cvt_pk_bf16_f32 v16, v24, v25
	v_cvt_pk_bf16_f32 v17, v26, v27
	v_cvt_pk_bf16_f32 v18, v28, v29
	v_cvt_pk_bf16_f32 v19, v30, v31
	global_store_dwordx4 v[32:33], v[16:19], off offset:128
	s_and_b64 vcc, exec, s[16:17]
	s_cbranch_vccnz .LBB0_2947
	s_branch .LBB0_3035

.LBB0_3033:
	v_add_u32_e32 v40, 0x8000, v3
	ds_read2_b32 v[40:41], v40 offset0:128 offset1:193
	v_or_b32_e32 v56, s52, v1
	v_ashrrev_i32_e32 v57, 31, v56
	s_waitcnt lgkmcnt(0)
	v_mul_f32 v40, v52, v40
	v_mul_f32 v41, v53, v41
	v_add_u32_e32 v52, 0x8400, v3
	ds_read2_b32 v[42:43], v52 offset0:2 offset1:67
	ds_read2_b32 v[52:53], v52 offset0:132 offset1:197
	v_cvt_pk_bf16_f32 v40, v40, v41
	s_waitcnt lgkmcnt(1)
	v_mul_f32 v42, v54, v42
	v_mul_f32 v43, v55, v43
	s_waitcnt lgkmcnt(0)
	v_mul_f32 v44, v44, v52
	v_mul_f32 v45, v45, v53
	v_add_u32_e32 v52, 0x8800, v3
	ds_read2_b32 v[52:53], v52 offset0:6 offset1:71
	v_cvt_pk_bf16_f32 v41, v42, v43
	v_cvt_pk_bf16_f32 v42, v44, v45
	v_mad_u64_u32 v[44:45], s[0:1], v68, s40, 0
	s_waitcnt lgkmcnt(0)
	v_mul_f32 v46, v46, v52
	v_mul_f32 v47, v47, v53
	s_nop 0
	v_cvt_pk_bf16_f32 v43, v46, v47
	v_mov_b32_e32 v46, v45
	v_mad_u64_u32 v[46:47], s[0:1], v69, s40, v[46:47]
	v_mov_b32_e32 v45, v46
	v_add_u32_e32 v46, 0xc600, v3
	ds_read2_b32 v[46:47], v46 offset0:68 offset1:133
	v_lshl_add_u64 v[44:45], v[44:45], 1, s[90:91]
	v_lshl_add_u64 v[44:45], v[56:57], 1, v[44:45]
	global_store_dwordx4 v[44:45], v[40:43], off
	s_waitcnt lgkmcnt(0)
	v_mul_f32 v46, v32, v46
	v_mul_f32 v47, v33, v47
	v_add_u32_e32 v40, 0xc200, v3
	v_add_u32_e32 v42, 0xc400, v3
	v_add_u32_e32 v32, 0xc800, v3
	ds_read2_b32 v[40:41], v40 offset0:64 offset1:129
	ds_read2_b32 v[42:43], v42 offset0:66 offset1:131
	ds_read2_b32 v[32:33], v32 offset0:70 offset1:135
	s_waitcnt lgkmcnt(2)
	v_mul_f32 v40, v48, v40
	v_mul_f32 v41, v49, v41
	s_waitcnt lgkmcnt(1)
	v_mul_f32 v42, v50, v42
	v_mul_f32 v43, v51, v43
	s_waitcnt lgkmcnt(0)
	v_mul_f32 v48, v34, v32
	v_mul_f32 v49, v35, v33
	v_cvt_pk_bf16_f32 v32, v40, v41
	v_cvt_pk_bf16_f32 v33, v42, v43
	v_cvt_pk_bf16_f32 v34, v46, v47
	v_cvt_pk_bf16_f32 v35, v48, v49
	global_store_dwordx4 v[44:45], v[32:35], off offset:128
	s_and_b64 vcc, exec, s[18:19]
	s_cbranch_vccz .LBB0_3031

.LBB0_3035:
	v_or_b32_e32 v16, s8, v1
	v_add_u32_e32 v1, 0x18600, v3
	ds_read_b32 v18, v1
	v_add_u32_e32 v1, 0x18704, v3
	ds_read_b32 v19, v1
	v_add_u32_e32 v1, 0x18808, v3
	v_ashrrev_i32_e32 v17, 31, v16
	s_waitcnt lgkmcnt(0)
	v_mul_f32 v18, v20, v18
	v_mul_f32 v19, v21, v19
	ds_read_b32 v20, v1
	v_add_u32_e32 v1, 0x1890c, v3
	ds_read_b32 v21, v1
	v_add_u32_e32 v1, 0x18a10, v3
	s_waitcnt lgkmcnt(0)
	v_mul_f32 v20, v22, v20
	v_mul_f32 v21, v23, v21
	ds_read_b32 v22, v1
	v_add_u32_e32 v1, 0x18b14, v3
	ds_read_b32 v23, v1
	v_add_u32_e32 v1, 0x18c18, v3
	s_waitcnt lgkmcnt(0)
	v_mul_f32 v22, v8, v22
	v_mul_f32 v23, v9, v23
	ds_read_b32 v8, v1
	v_add_u32_e32 v1, 0x18d1c, v3
	ds_read_b32 v9, v1
	v_add_u32_e32 v1, 0x1c700, v3
	s_waitcnt lgkmcnt(0)
	v_mul_f32 v24, v10, v8
	v_mul_f32 v25, v11, v9
	v_cvt_pk_bf16_f32 v8, v18, v19
	v_mad_u64_u32 v[18:19], s[0:1], v68, s40, 0
	v_cvt_pk_bf16_f32 v9, v20, v21
	v_mov_b32_e32 v20, v19
	v_mad_u64_u32 v[20:21], s[0:1], v69, s40, v[20:21]
	v_mov_b32_e32 v19, v20
	v_lshl_add_u64 v[18:19], v[18:19], 1, s[90:91]
	v_cvt_pk_bf16_f32 v10, v22, v23
	v_cvt_pk_bf16_f32 v11, v24, v25
	v_lshl_add_u64 v[16:17], v[16:17], 1, v[18:19]
	global_store_dwordx4 v[16:17], v[8:11], off
	ds_read_b32 v8, v1
	v_add_u32_e32 v1, 0x1c804, v3
	ds_read_b32 v9, v1
	v_add_u32_e32 v1, 0x1c908, v3
	ds_read_b32 v10, v1
	v_add_u32_e32 v1, 0x1ca0c, v3
	ds_read_b32 v11, v1
	v_add_u32_e32 v1, 0x1cb10, v3
	s_waitcnt lgkmcnt(2)
	v_mul_f32 v8, v12, v8
	v_mul_f32 v9, v13, v9
	ds_read_b32 v12, v1
	v_add_u32_e32 v1, 0x1cc14, v3
	ds_read_b32 v13, v1
	v_add_u32_e32 v1, 0x1cd18, v3
	s_waitcnt lgkmcnt(2)
	v_mul_f32 v10, v14, v10
	v_mul_f32 v11, v15, v11
	s_waitcnt lgkmcnt(0)
	v_mul_f32 v12, v4, v12
	v_mul_f32 v13, v5, v13
	ds_read_b32 v4, v1
	v_add_u32_e32 v1, 0x1ce1c, v3
	ds_read_b32 v5, v1
	s_waitcnt lgkmcnt(0)
	v_mul_f32 v14, v6, v4
	v_mul_f32 v15, v7, v5
	v_cvt_pk_bf16_f32 v4, v8, v9
	v_cvt_pk_bf16_f32 v5, v10, v11
	v_cvt_pk_bf16_f32 v6, v12, v13
	v_cvt_pk_bf16_f32 v7, v14, v15
	global_store_dwordx4 v[16:17], v[4:7], off offset:128
	s_branch .LBB0_2947

.LBB0_3091:
	v_mov_b32_e32 v1, v0
	v_readlane_b32 s14, v254, 30
	v_readfirstlane_b32 s0, v1
	s_and_b32 s6, s0, 0xc0
	s_ashr_i32 s0, s0, 2
	s_andn2_b32 s0, s0, 63
	s_addk_i32 s0, 0x4000
	v_bfe_u32 v3, v1, 4, 2
	v_and_or_b32 v190, v1, 15, s0
	v_readlane_b32 s15, v254, 31
	s_or_b32 s0, s6, s14
	v_lshl_or_b32 v188, v3, 3, s0
	s_lshl_b64 s[0:1], s[14:15], 2
	s_add_u32 s0, s36, s0
	s_addc_u32 s1, s37, s1
	s_lshl_b32 s6, s6, 2
	s_add_u32 s0, s0, s6
	s_addc_u32 s1, s1, 0
	v_lshlrev_b32_e32 v132, 5, v3
	v_mov_b32_e32 v133, v2
	v_ashrrev_i32_e32 v191, 31, v190
	v_or_b32_e32 v194, 16, v190
	v_lshl_add_u64 v[192:193], s[0:1], 0, v[132:133]
	v_lshlrev_b64 v[220:221], 12, v[190:191]
	v_ashrrev_i32_e32 v195, 31, v194
	v_or_b32_e32 v210, 32, v190
	v_or_b32_e32 v212, 48, v190
	v_lshl_add_u64 v[132:133], v[192:193], 0, v[220:221]
	v_lshlrev_b64 v[218:219], 12, v[194:195]
	v_ashrrev_i32_e32 v211, 31, v210
	v_ashrrev_i32_e32 v213, 31, v212
	global_load_dwordx4 v[222:225], v[132:133], off offset:16
	global_load_dwordx4 v[226:229], v[132:133], off
	global_load_dwordx4 v[180:183], v[132:133], off offset:144
	global_load_dwordx4 v[184:187], v[132:133], off offset:128
	v_lshl_add_u64 v[132:133], v[192:193], 0, v[218:219]
	v_lshlrev_b64 v[216:217], 12, v[210:211]
	v_lshlrev_b64 v[214:215], 12, v[212:213]
	global_load_dwordx4 v[172:175], v[132:133], off offset:16
	global_load_dwordx4 v[176:179], v[132:133], off
	global_load_dwordx4 v[164:167], v[132:133], off offset:144
	global_load_dwordx4 v[168:171], v[132:133], off offset:128
	v_lshl_add_u64 v[132:133], v[192:193], 0, v[216:217]
	v_lshl_add_u64 v[136:137], v[192:193], 0, v[214:215]
	global_load_dwordx4 v[156:159], v[132:133], off offset:16
	global_load_dwordx4 v[160:163], v[132:133], off
	global_load_dwordx4 v[148:151], v[132:133], off offset:144
	global_load_dwordx4 v[152:155], v[132:133], off offset:128
	global_load_dwordx4 v[140:143], v[136:137], off offset:16
	global_load_dwordx4 v[144:147], v[136:137], off
	s_nop 0
	global_load_dwordx4 v[132:135], v[136:137], off offset:144
	s_nop 0
	global_load_dwordx4 v[136:139], v[136:137], off offset:128
	v_lshl_add_u64 v[220:221], s[36:37], 0, v[220:221]
	v_mov_b32_e32 v189, v2
	v_lshl_add_u64 v[220:221], v[188:189], 2, v[220:221]
	v_lshlrev_b64 v[232:233], 10, v[190:191]
	s_and_b64 vcc, exec, s[8:9]
	s_waitcnt vmcnt(0)
	v_add_f32 v126, v126, v224
	v_add_f32 v127, v127, v225
	v_add_f32 v130, v130, v228
	v_add_f32 v131, v131, v229
	v_add_f32 v128, v128, v226
	v_add_f32 v129, v129, v227
	v_add_f32 v124, v124, v222
	v_add_f32 v125, v125, v223
	global_store_dwordx4 v[220:221], v[128:131], off sc1
	s_nop 1
	v_lshl_add_u64 v[222:223], v[220:221], 0, 16
	global_store_dwordx4 v[222:223], v[124:127], off sc1
	s_nop 1
	v_lshl_add_u64 v[222:223], v[232:233], 1, s[34:35]
	s_cbranch_vccz .LBB0_3093
	v_lshl_add_u64 v[228:229], v[188:189], 1, v[222:223]
	v_cvt_pk_bf16_f32 v224, v128, v129
	v_cvt_pk_bf16_f32 v225, v130, v131
	v_cvt_pk_bf16_f32 v226, v124, v125
	v_cvt_pk_bf16_f32 v227, v126, v127
	global_store_dwordx4 v[228:229], v[224:227], off sc1
	s_nop 1
.LBB0_3093:
	s_mov_b64 s[0:1], 0x80
	v_lshl_add_u64 v[224:225], v[220:221], 0, s[0:1]
	v_add_f32 v122, v122, v186
	v_add_f32 v123, v123, v187
	v_add_f32 v120, v120, v184
	v_add_f32 v121, v121, v185
	s_mov_b64 s[0:1], 0x90
	global_store_dwordx4 v[224:225], v[120:123], off sc1
	s_nop 1
	v_add_f32 v118, v118, v182
	v_add_f32 v119, v119, v183
	v_add_f32 v116, v116, v180
	v_add_f32 v117, v117, v181
	v_lshl_add_u64 v[180:181], v[220:221], 0, s[0:1]
	global_store_dwordx4 v[180:181], v[116:119], off sc1
	s_nop 1
	v_cndmask_b32_e64 v1, 0, 1, s[8:9]
	v_cmp_ne_u32_e64 s[16:17], 1, v1
	s_andn2_b64 vcc, exec, s[8:9]
	s_cbranch_vccnz .LBB0_3095
	v_lshl_add_u64 v[180:181], v[188:189], 1, v[222:223]
	v_lshl_add_u64 v[184:185], v[180:181], 0, 64
	v_cvt_pk_bf16_f32 v180, v120, v121
	v_cvt_pk_bf16_f32 v181, v122, v123
	v_cvt_pk_bf16_f32 v182, v116, v117
	v_cvt_pk_bf16_f32 v183, v118, v119
	global_store_dwordx4 v[184:185], v[180:183], off sc1
	s_nop 1
.LBB0_3095:
	v_mul_f32_e32 v1, v129, v129
	v_mul_f32_e32 v125, v125, v125
	v_mul_f32_e32 v121, v121, v121
	v_mul_f32_e32 v117, v117, v117
	v_fmac_f32_e32 v1, v128, v128
	v_mul_f32_e32 v128, v131, v131
	v_fmac_f32_e32 v125, v124, v124
	v_mul_f32_e32 v124, v127, v127
	v_fmac_f32_e32 v121, v120, v120
	v_mul_f32_e32 v120, v123, v123
	v_fmac_f32_e32 v117, v116, v116
	v_mul_f32_e32 v116, v119, v119
	v_fmac_f32_e32 v128, v130, v130
	v_fmac_f32_e32 v124, v126, v126
	v_fmac_f32_e32 v120, v122, v122
	v_fmac_f32_e32 v116, v118, v118
	v_add_f32_e32 v1, v1, v128
	v_add_f32_e32 v124, v125, v124
	v_add_f32_e32 v120, v121, v120
	v_add_f32_e32 v116, v117, v116
	v_add_f32_e32 v1, v1, v124
	v_add_f32_e32 v116, v120, v116
	v_add_f32_e32 v1, v1, v116
	ds_swizzle_b32 v116, v1 offset:swizzle(SWAP,16)
	v_add_f32 v114, v114, v178
	v_add_f32 v115, v115, v179
	v_add_f32 v112, v112, v176
	v_add_f32 v113, v113, v177
	v_add_f32 v110, v110, v174
	v_add_f32 v111, v111, v175
	v_add_f32 v108, v108, v172
	v_add_f32 v109, v109, v173
	s_waitcnt lgkmcnt(0)
	v_add_f32_e32 v120, v1, v116
	v_and_b32_e32 v116, 64, v236
	v_xor_b32_e32 v1, 32, v236
	v_add_u32_e32 v116, 64, v116
	v_cmp_lt_i32_e32 vcc, v1, v116
	v_lshl_add_u64 v[116:117], s[36:37], 0, v[218:219]
	v_lshl_add_u64 v[116:117], v[188:189], 2, v[116:117]
	v_cndmask_b32_e32 v1, v236, v1, vcc
	v_lshlrev_b32_e32 v1, 2, v1
	ds_bpermute_b32 v121, v1, v120
	global_store_dwordx4 v[116:117], v[112:115], off sc1
	s_nop 1
	v_lshl_add_u64 v[122:123], v[116:117], 0, 16
	global_store_dwordx4 v[122:123], v[108:111], off sc1
	s_nop 1
	v_lshlrev_b64 v[118:119], 10, v[194:195]
	s_and_b64 vcc, exec, s[16:17]
	v_lshl_add_u64 v[118:119], v[118:119], 1, s[34:35]
	s_cbranch_vccnz .LBB0_3097
	v_lshl_add_u64 v[126:127], v[188:189], 1, v[118:119]
	v_cvt_pk_bf16_f32 v122, v112, v113
	v_cvt_pk_bf16_f32 v123, v114, v115
	v_cvt_pk_bf16_f32 v124, v108, v109
	v_cvt_pk_bf16_f32 v125, v110, v111
	global_store_dwordx4 v[126:127], v[122:125], off sc1
	s_nop 1
.LBB0_3097:
	s_mov_b64 s[0:1], 0x80
	v_lshl_add_u64 v[122:123], v[116:117], 0, s[0:1]
	v_add_f32 v106, v106, v170
	v_add_f32 v107, v107, v171
	v_add_f32 v104, v104, v168
	v_add_f32 v105, v105, v169
	s_mov_b64 s[0:1], 0x90
	global_store_dwordx4 v[122:123], v[104:107], off sc1
	s_nop 1
	v_add_f32 v102, v102, v166
	v_add_f32 v103, v103, v167
	v_add_f32 v100, v100, v164
	v_add_f32 v101, v101, v165
	v_lshl_add_u64 v[116:117], v[116:117], 0, s[0:1]
	global_store_dwordx4 v[116:117], v[100:103], off sc1
	s_nop 1
	s_and_b64 vcc, exec, s[16:17]
	s_cbranch_vccnz .LBB0_3099
	v_lshl_add_u64 v[116:117], v[188:189], 1, v[118:119]
	v_lshl_add_u64 v[122:123], v[116:117], 0, 64
	v_cvt_pk_bf16_f32 v116, v104, v105
	v_cvt_pk_bf16_f32 v117, v106, v107
	v_cvt_pk_bf16_f32 v118, v100, v101
	v_cvt_pk_bf16_f32 v119, v102, v103
	global_store_dwordx4 v[122:123], v[116:119], off sc1
	s_nop 1
.LBB0_3099:
	v_mul_f32_e32 v113, v113, v113
	v_mul_f32_e32 v109, v109, v109
	v_mul_f32_e32 v105, v105, v105
	v_mul_f32_e32 v101, v101, v101
	v_fmac_f32_e32 v113, v112, v112
	v_mul_f32_e32 v112, v115, v115
	v_fmac_f32_e32 v109, v108, v108
	v_mul_f32_e32 v108, v111, v111
	v_fmac_f32_e32 v105, v104, v104
	v_mul_f32_e32 v104, v107, v107
	v_fmac_f32_e32 v101, v100, v100
	v_mul_f32_e32 v100, v103, v103
	v_fmac_f32_e32 v112, v114, v114
	v_fmac_f32_e32 v108, v110, v110
	v_fmac_f32_e32 v104, v106, v106
	v_fmac_f32_e32 v100, v102, v102
	v_add_f32_e32 v112, v113, v112
	v_add_f32_e32 v108, v109, v108
	v_add_f32_e32 v104, v105, v104
	v_add_f32_e32 v100, v101, v100
	v_add_f32_e32 v108, v112, v108
	v_add_f32_e32 v100, v104, v100
	v_add_f32_e32 v100, v108, v100
	ds_swizzle_b32 v101, v100 offset:swizzle(SWAP,16)
	v_add_f32 v98, v98, v162
	v_add_f32 v99, v99, v163
	v_add_f32 v96, v96, v160
	v_add_f32 v97, v97, v161
	v_add_f32 v94, v94, v158
	v_add_f32 v95, v95, v159
	v_add_f32 v92, v92, v156
	v_add_f32 v93, v93, v157
	s_waitcnt lgkmcnt(0)
	v_add_f32_e32 v104, v100, v101
	ds_bpermute_b32 v105, v1, v104
	v_lshl_add_u64 v[100:101], s[36:37], 0, v[216:217]
	v_lshl_add_u64 v[100:101], v[188:189], 2, v[100:101]
	global_store_dwordx4 v[100:101], v[96:99], off sc1
	s_nop 1
	v_lshl_add_u64 v[106:107], v[100:101], 0, 16
	global_store_dwordx4 v[106:107], v[92:95], off sc1
	s_nop 1
	v_lshlrev_b64 v[102:103], 10, v[210:211]
	s_and_b64 vcc, exec, s[16:17]
	v_lshl_add_u64 v[102:103], v[102:103], 1, s[34:35]
	s_cbranch_vccnz .LBB0_3101
	v_lshl_add_u64 v[110:111], v[188:189], 1, v[102:103]
	v_cvt_pk_bf16_f32 v106, v96, v97
	v_cvt_pk_bf16_f32 v107, v98, v99
	v_cvt_pk_bf16_f32 v108, v92, v93
	v_cvt_pk_bf16_f32 v109, v94, v95
	global_store_dwordx4 v[110:111], v[106:109], off sc1
	s_nop 1
.LBB0_3101:
	s_mov_b64 s[0:1], 0x80
	v_lshl_add_u64 v[106:107], v[100:101], 0, s[0:1]
	v_add_f32 v90, v90, v154
	v_add_f32 v91, v91, v155
	v_add_f32 v88, v88, v152
	v_add_f32 v89, v89, v153
	s_mov_b64 s[0:1], 0x90
	global_store_dwordx4 v[106:107], v[88:91], off sc1
	s_nop 1
	v_add_f32 v86, v86, v150
	v_add_f32 v87, v87, v151
	v_add_f32 v84, v84, v148
	v_add_f32 v85, v85, v149
	v_lshl_add_u64 v[100:101], v[100:101], 0, s[0:1]
	global_store_dwordx4 v[100:101], v[84:87], off sc1
	s_nop 1
	s_and_b64 vcc, exec, s[16:17]
	s_cbranch_vccnz .LBB0_3103
	v_lshl_add_u64 v[100:101], v[188:189], 1, v[102:103]
	v_lshl_add_u64 v[106:107], v[100:101], 0, 64
	v_cvt_pk_bf16_f32 v100, v88, v89
	v_cvt_pk_bf16_f32 v101, v90, v91
	v_cvt_pk_bf16_f32 v102, v84, v85
	v_cvt_pk_bf16_f32 v103, v86, v87
	global_store_dwordx4 v[106:107], v[100:103], off sc1
	s_nop 1
.LBB0_3103:
	v_mul_f32_e32 v97, v97, v97
	v_mul_f32_e32 v93, v93, v93
	v_mul_f32_e32 v89, v89, v89
	v_mul_f32_e32 v85, v85, v85
	v_fmac_f32_e32 v97, v96, v96
	v_mul_f32_e32 v96, v99, v99
	v_fmac_f32_e32 v93, v92, v92
	v_mul_f32_e32 v92, v95, v95
	v_fmac_f32_e32 v89, v88, v88
	v_mul_f32_e32 v88, v91, v91
	v_fmac_f32_e32 v85, v84, v84
	v_mul_f32_e32 v84, v87, v87
	v_fmac_f32_e32 v96, v98, v98
	v_fmac_f32_e32 v92, v94, v94
	v_fmac_f32_e32 v88, v90, v90
	v_fmac_f32_e32 v84, v86, v86
	v_add_f32_e32 v96, v97, v96
	v_add_f32_e32 v92, v93, v92
	v_add_f32_e32 v88, v89, v88
	v_add_f32_e32 v84, v85, v84
	v_add_f32_e32 v92, v96, v92
	v_add_f32_e32 v84, v88, v84
	v_add_f32_e32 v84, v92, v84
	ds_swizzle_b32 v85, v84 offset:swizzle(SWAP,16)
	v_add_f32 v82, v82, v146
	v_add_f32 v83, v83, v147
	v_add_f32 v80, v80, v144
	v_add_f32 v81, v81, v145
	v_add_f32 v78, v78, v142
	v_add_f32 v79, v79, v143
	v_add_f32 v76, v76, v140
	v_add_f32 v77, v77, v141
	s_waitcnt lgkmcnt(0)
	v_add_f32_e32 v88, v84, v85
	ds_bpermute_b32 v89, v1, v88
	v_lshl_add_u64 v[84:85], s[36:37], 0, v[214:215]
	v_lshl_add_u64 v[84:85], v[188:189], 2, v[84:85]
	global_store_dwordx4 v[84:85], v[80:83], off sc1
	s_nop 1
	v_lshl_add_u64 v[90:91], v[84:85], 0, 16
	global_store_dwordx4 v[90:91], v[76:79], off sc1
	s_nop 1
	v_lshlrev_b64 v[86:87], 10, v[212:213]
	s_and_b64 vcc, exec, s[16:17]
	v_lshl_add_u64 v[86:87], v[86:87], 1, s[34:35]
	s_cbranch_vccnz .LBB0_3105
	v_lshl_add_u64 v[94:95], v[188:189], 1, v[86:87]
	v_cvt_pk_bf16_f32 v90, v80, v81
	v_cvt_pk_bf16_f32 v91, v82, v83
	v_cvt_pk_bf16_f32 v92, v76, v77
	v_cvt_pk_bf16_f32 v93, v78, v79
	global_store_dwordx4 v[94:95], v[90:93], off sc1
	s_nop 1
.LBB0_3105:
	s_mov_b64 s[0:1], 0x80
	v_lshl_add_u64 v[90:91], v[84:85], 0, s[0:1]
	v_add_f32 v74, v74, v138
	v_add_f32 v75, v75, v139
	v_add_f32 v72, v72, v136
	v_add_f32 v73, v73, v137
	s_mov_b64 s[0:1], 0x90
	global_store_dwordx4 v[90:91], v[72:75], off sc1
	s_nop 1
	v_add_f32 v70, v70, v134
	v_add_f32 v71, v71, v135
	v_add_f32 v68, v68, v132
	v_add_f32 v69, v69, v133
	v_lshl_add_u64 v[84:85], v[84:85], 0, s[0:1]
	global_store_dwordx4 v[84:85], v[68:71], off sc1
	s_nop 1
	s_and_b64 vcc, exec, s[16:17]
	s_cbranch_vccnz .LBB0_3107
	v_lshl_add_u64 v[84:85], v[188:189], 1, v[86:87]
	v_lshl_add_u64 v[90:91], v[84:85], 0, 64
	v_cvt_pk_bf16_f32 v84, v72, v73
	v_cvt_pk_bf16_f32 v85, v74, v75
	v_cvt_pk_bf16_f32 v86, v68, v69
	v_cvt_pk_bf16_f32 v87, v70, v71
	global_store_dwordx4 v[90:91], v[84:87], off sc1
	s_nop 1

.LBB0_3109:
	s_or_b64 exec, exec, s[6:7]
	v_add_u32_e32 v124, 0x80, v190
	v_ashrrev_i32_e32 v125, 31, v124
	v_add_u32_e32 v126, 0x90, v190
	v_lshlrev_b64 v[138:139], 12, v[124:125]
	v_ashrrev_i32_e32 v127, 31, v126
	v_add_u32_e32 v128, 0xa0, v190
	v_add_u32_e32 v130, 0xb0, v190
	s_waitcnt lgkmcnt(0)
	v_lshl_add_u64 v[68:69], v[192:193], 0, v[138:139]
	v_lshlrev_b64 v[136:137], 12, v[126:127]
	v_ashrrev_i32_e32 v129, 31, v128
	v_ashrrev_i32_e32 v131, 31, v130
	global_load_dwordx4 v[140:143], v[68:69], off offset:16
	global_load_dwordx4 v[144:147], v[68:69], off
	global_load_dwordx4 v[116:119], v[68:69], off offset:144
	global_load_dwordx4 v[120:123], v[68:69], off offset:128
	v_lshl_add_u64 v[68:69], v[192:193], 0, v[136:137]
	v_lshlrev_b64 v[134:135], 12, v[128:129]
	v_lshlrev_b64 v[132:133], 12, v[130:131]
	global_load_dwordx4 v[108:111], v[68:69], off offset:16
	global_load_dwordx4 v[112:115], v[68:69], off
	global_load_dwordx4 v[100:103], v[68:69], off offset:144
	global_load_dwordx4 v[104:107], v[68:69], off offset:128
	v_lshl_add_u64 v[68:69], v[192:193], 0, v[134:135]
	v_lshl_add_u64 v[72:73], v[192:193], 0, v[132:133]
	global_load_dwordx4 v[92:95], v[68:69], off offset:16
	global_load_dwordx4 v[96:99], v[68:69], off
	global_load_dwordx4 v[84:87], v[68:69], off offset:144
	global_load_dwordx4 v[88:91], v[68:69], off offset:128
	global_load_dwordx4 v[76:79], v[72:73], off offset:16
	global_load_dwordx4 v[80:83], v[72:73], off
	s_nop 0
	global_load_dwordx4 v[68:71], v[72:73], off offset:144
	s_nop 0
	global_load_dwordx4 v[72:75], v[72:73], off offset:128
	v_lshl_add_u64 v[138:139], s[36:37], 0, v[138:139]
	v_lshl_add_u64 v[138:139], v[188:189], 2, v[138:139]
	v_lshlrev_b64 v[148:149], 10, v[124:125]
	s_and_b64 vcc, exec, s[16:17]
	s_waitcnt vmcnt(15)
	v_add_f32 v62, v62, v142
	v_add_f32 v63, v63, v143
	s_waitcnt vmcnt(14)
	v_add_f32 v66, v66, v146
	v_add_f32 v67, v67, v147
	v_add_f32 v64, v64, v144
	v_add_f32 v65, v65, v145
	v_add_f32 v60, v60, v140
	v_add_f32 v61, v61, v141
	global_store_dwordx4 v[138:139], v[64:67], off sc1
	s_nop 1
	v_lshl_add_u64 v[140:141], v[138:139], 0, 16
	global_store_dwordx4 v[140:141], v[60:63], off sc1
	s_nop 1
	v_lshl_add_u64 v[140:141], v[148:149], 1, s[34:35]
	s_cbranch_vccnz .LBB0_3111
	v_lshl_add_u64 v[146:147], v[188:189], 1, v[140:141]
	v_cvt_pk_bf16_f32 v142, v64, v65
	v_cvt_pk_bf16_f32 v143, v66, v67
	v_cvt_pk_bf16_f32 v144, v60, v61
	v_cvt_pk_bf16_f32 v145, v62, v63
	global_store_dwordx4 v[146:147], v[142:145], off sc1
	s_nop 1
.LBB0_3111:
	s_mov_b64 s[6:7], 0x80
	v_lshl_add_u64 v[142:143], v[138:139], 0, s[6:7]
	s_waitcnt vmcnt(12)
	v_add_f32 v58, v58, v122
	v_add_f32 v59, v59, v123
	v_add_f32 v56, v56, v120
	v_add_f32 v57, v57, v121
	s_mov_b64 s[6:7], 0x90
	global_store_dwordx4 v[142:143], v[56:59], off sc1
	s_nop 1
	v_add_f32 v54, v54, v118
	v_add_f32 v55, v55, v119
	v_add_f32 v52, v52, v116
	v_add_f32 v53, v53, v117
	v_lshl_add_u64 v[116:117], v[138:139], 0, s[6:7]
	global_store_dwordx4 v[116:117], v[52:55], off sc1
	s_nop 1
	s_and_b64 vcc, exec, s[16:17]
	s_cbranch_vccnz .LBB0_3113
	v_lshl_add_u64 v[116:117], v[188:189], 1, v[140:141]
	v_lshl_add_u64 v[120:121], v[116:117], 0, 64
	v_cvt_pk_bf16_f32 v116, v56, v57
	v_cvt_pk_bf16_f32 v117, v58, v59
	v_cvt_pk_bf16_f32 v118, v52, v53
	v_cvt_pk_bf16_f32 v119, v54, v55
	global_store_dwordx4 v[120:121], v[116:119], off sc1
	s_nop 1
.LBB0_3113:
	v_mul_f32_e32 v3, v65, v65
	v_mul_f32_e32 v61, v61, v61
	v_mul_f32_e32 v57, v57, v57
	v_mul_f32_e32 v53, v53, v53
	v_fmac_f32_e32 v3, v64, v64
	v_mul_f32_e32 v64, v67, v67
	v_fmac_f32_e32 v61, v60, v60
	v_mul_f32_e32 v60, v63, v63
	v_fmac_f32_e32 v57, v56, v56
	v_mul_f32_e32 v56, v59, v59
	v_fmac_f32_e32 v53, v52, v52
	v_mul_f32_e32 v52, v55, v55
	v_fmac_f32_e32 v64, v66, v66
	v_fmac_f32_e32 v60, v62, v62
	v_fmac_f32_e32 v56, v58, v58
	v_fmac_f32_e32 v52, v54, v54
	v_add_f32_e32 v3, v3, v64
	v_add_f32_e32 v60, v61, v60
	v_add_f32_e32 v56, v57, v56
	v_add_f32_e32 v52, v53, v52
	v_add_f32_e32 v3, v3, v60
	v_add_f32_e32 v52, v56, v52
	v_add_f32_e32 v3, v3, v52
	ds_swizzle_b32 v52, v3 offset:swizzle(SWAP,16)
	s_waitcnt vmcnt(10)
	v_add_f32 v50, v50, v114
	v_add_f32 v51, v51, v115
	v_add_f32 v48, v48, v112
	v_add_f32 v49, v49, v113
	v_add_f32 v46, v46, v110
	v_add_f32 v47, v47, v111
	v_add_f32 v44, v44, v108
	v_add_f32 v45, v45, v109
	s_waitcnt lgkmcnt(0)
	v_add_f32_e32 v3, v3, v52
	ds_bpermute_b32 v56, v1, v3
	v_lshl_add_u64 v[52:53], s[36:37], 0, v[136:137]
	v_lshl_add_u64 v[52:53], v[188:189], 2, v[52:53]
	global_store_dwordx4 v[52:53], v[48:51], off sc1
	s_nop 1
	v_lshl_add_u64 v[58:59], v[52:53], 0, 16
	global_store_dwordx4 v[58:59], v[44:47], off sc1
	s_nop 1
	v_lshlrev_b64 v[54:55], 10, v[126:127]
	s_and_b64 vcc, exec, s[16:17]
	v_lshl_add_u64 v[54:55], v[54:55], 1, s[34:35]
	s_cbranch_vccnz .LBB0_3115
	v_lshl_add_u64 v[62:63], v[188:189], 1, v[54:55]
	v_cvt_pk_bf16_f32 v58, v48, v49
	v_cvt_pk_bf16_f32 v59, v50, v51
	v_cvt_pk_bf16_f32 v60, v44, v45
	v_cvt_pk_bf16_f32 v61, v46, v47
	global_store_dwordx4 v[62:63], v[58:61], off sc1
	s_nop 1
.LBB0_3115:
	s_mov_b64 s[6:7], 0x80
	v_lshl_add_u64 v[58:59], v[52:53], 0, s[6:7]
	s_waitcnt vmcnt(8)
	v_add_f32 v42, v42, v106
	v_add_f32 v43, v43, v107
	v_add_f32 v40, v40, v104
	v_add_f32 v41, v41, v105
	s_mov_b64 s[6:7], 0x90
	global_store_dwordx4 v[58:59], v[40:43], off sc1
	s_nop 1
	v_add_f32 v38, v38, v102
	v_add_f32 v39, v39, v103
	v_add_f32 v36, v36, v100
	v_add_f32 v37, v37, v101
	v_lshl_add_u64 v[52:53], v[52:53], 0, s[6:7]
	global_store_dwordx4 v[52:53], v[36:39], off sc1
	s_nop 1
	s_and_b64 vcc, exec, s[16:17]
	s_cbranch_vccnz .LBB0_3117
	v_lshl_add_u64 v[52:53], v[188:189], 1, v[54:55]
	v_lshl_add_u64 v[58:59], v[52:53], 0, 64
	v_cvt_pk_bf16_f32 v52, v40, v41
	v_cvt_pk_bf16_f32 v53, v42, v43
	v_cvt_pk_bf16_f32 v54, v36, v37
	v_cvt_pk_bf16_f32 v55, v38, v39
	global_store_dwordx4 v[58:59], v[52:55], off sc1
	s_nop 1
.LBB0_3117:
	v_mul_f32_e32 v49, v49, v49
	v_mul_f32_e32 v45, v45, v45
	v_mul_f32_e32 v41, v41, v41
	v_mul_f32_e32 v37, v37, v37
	v_fmac_f32_e32 v49, v48, v48
	v_mul_f32_e32 v48, v51, v51
	v_fmac_f32_e32 v45, v44, v44
	v_mul_f32_e32 v44, v47, v47
	v_fmac_f32_e32 v41, v40, v40
	v_mul_f32_e32 v40, v43, v43
	v_fmac_f32_e32 v37, v36, v36
	v_mul_f32_e32 v36, v39, v39
	v_fmac_f32_e32 v48, v50, v50
	v_fmac_f32_e32 v44, v46, v46
	v_fmac_f32_e32 v40, v42, v42
	v_fmac_f32_e32 v36, v38, v38
	v_add_f32_e32 v48, v49, v48
	v_add_f32_e32 v44, v45, v44
	v_add_f32_e32 v40, v41, v40
	v_add_f32_e32 v36, v37, v36
	v_add_f32_e32 v44, v48, v44
	v_add_f32_e32 v36, v40, v36
	v_add_f32_e32 v36, v44, v36
	ds_swizzle_b32 v37, v36 offset:swizzle(SWAP,16)
	s_waitcnt vmcnt(6)
	v_add_f32 v34, v34, v98
	v_add_f32 v35, v35, v99
	v_add_f32 v32, v32, v96
	v_add_f32 v33, v33, v97
	v_add_f32 v30, v30, v94
	v_add_f32 v31, v31, v95
	v_add_f32 v28, v28, v92
	v_add_f32 v29, v29, v93
	s_waitcnt lgkmcnt(0)
	v_add_f32_e32 v40, v36, v37
	ds_bpermute_b32 v41, v1, v40
	v_lshl_add_u64 v[36:37], s[36:37], 0, v[134:135]
	v_lshl_add_u64 v[36:37], v[188:189], 2, v[36:37]
	global_store_dwordx4 v[36:37], v[32:35], off sc1
	s_nop 1
	v_lshl_add_u64 v[42:43], v[36:37], 0, 16
	global_store_dwordx4 v[42:43], v[28:31], off sc1
	s_nop 1
	v_lshlrev_b64 v[38:39], 10, v[128:129]
	s_and_b64 vcc, exec, s[16:17]
	v_lshl_add_u64 v[38:39], v[38:39], 1, s[34:35]
	s_cbranch_vccnz .LBB0_3119
	v_lshl_add_u64 v[46:47], v[188:189], 1, v[38:39]
	v_cvt_pk_bf16_f32 v42, v32, v33
	v_cvt_pk_bf16_f32 v43, v34, v35
	v_cvt_pk_bf16_f32 v44, v28, v29
	v_cvt_pk_bf16_f32 v45, v30, v31
	global_store_dwordx4 v[46:47], v[42:45], off sc1
	s_nop 1
.LBB0_3119:
	s_mov_b64 s[6:7], 0x80
	v_lshl_add_u64 v[42:43], v[36:37], 0, s[6:7]
	s_waitcnt vmcnt(4)
	v_add_f32 v26, v26, v90
	v_add_f32 v27, v27, v91
	v_add_f32 v24, v24, v88
	v_add_f32 v25, v25, v89
	s_mov_b64 s[6:7], 0x90
	global_store_dwordx4 v[42:43], v[24:27], off sc1
	s_nop 1
	v_add_f32 v22, v22, v86
	v_add_f32 v23, v23, v87
	v_add_f32 v20, v20, v84
	v_add_f32 v21, v21, v85
	v_lshl_add_u64 v[36:37], v[36:37], 0, s[6:7]
	global_store_dwordx4 v[36:37], v[20:23], off sc1
	s_nop 1
	s_and_b64 vcc, exec, s[16:17]
	s_cbranch_vccnz .LBB0_3121
	v_lshl_add_u64 v[36:37], v[188:189], 1, v[38:39]
	v_lshl_add_u64 v[42:43], v[36:37], 0, 64
	v_cvt_pk_bf16_f32 v36, v24, v25
	v_cvt_pk_bf16_f32 v37, v26, v27
	v_cvt_pk_bf16_f32 v38, v20, v21
	v_cvt_pk_bf16_f32 v39, v22, v23
	global_store_dwordx4 v[42:43], v[36:39], off sc1
	s_nop 1
.LBB0_3121:
	v_mul_f32_e32 v33, v33, v33
	v_mul_f32_e32 v29, v29, v29
	v_mul_f32_e32 v25, v25, v25
	v_mul_f32_e32 v21, v21, v21
	v_fmac_f32_e32 v33, v32, v32
	v_mul_f32_e32 v32, v35, v35
	v_fmac_f32_e32 v29, v28, v28
	v_mul_f32_e32 v28, v31, v31
	v_fmac_f32_e32 v25, v24, v24
	v_mul_f32_e32 v24, v27, v27
	v_fmac_f32_e32 v21, v20, v20
	v_mul_f32_e32 v20, v23, v23
	v_fmac_f32_e32 v32, v34, v34
	v_fmac_f32_e32 v28, v30, v30
	v_fmac_f32_e32 v24, v26, v26
	v_fmac_f32_e32 v20, v22, v22
	v_add_f32_e32 v32, v33, v32
	v_add_f32_e32 v28, v29, v28
	v_add_f32_e32 v24, v25, v24
	v_add_f32_e32 v20, v21, v20
	v_add_f32_e32 v28, v32, v28
	v_add_f32_e32 v20, v24, v20
	v_add_f32_e32 v20, v28, v20
	ds_swizzle_b32 v21, v20 offset:swizzle(SWAP,16)
	s_waitcnt vmcnt(2)
	v_add_f32 v18, v18, v82
	v_add_f32 v19, v19, v83
	v_add_f32 v16, v16, v80
	v_add_f32 v17, v17, v81
	v_add_f32 v14, v14, v78
	v_add_f32 v15, v15, v79
	v_add_f32 v12, v12, v76
	v_add_f32 v13, v13, v77
	s_waitcnt lgkmcnt(0)
	v_add_f32_e32 v24, v20, v21
	ds_bpermute_b32 v25, v1, v24
	v_lshl_add_u64 v[20:21], s[36:37], 0, v[132:133]
	v_lshl_add_u64 v[20:21], v[188:189], 2, v[20:21]
	global_store_dwordx4 v[20:21], v[16:19], off sc1
	s_nop 1
	v_lshl_add_u64 v[26:27], v[20:21], 0, 16
	global_store_dwordx4 v[26:27], v[12:15], off sc1
	s_nop 1
	v_lshlrev_b64 v[22:23], 10, v[130:131]
	s_and_b64 vcc, exec, s[16:17]
	v_lshl_add_u64 v[22:23], v[22:23], 1, s[34:35]
	s_cbranch_vccnz .LBB0_3123
	v_lshl_add_u64 v[30:31], v[188:189], 1, v[22:23]
	v_cvt_pk_bf16_f32 v26, v16, v17
	v_cvt_pk_bf16_f32 v27, v18, v19
	v_cvt_pk_bf16_f32 v28, v12, v13
	v_cvt_pk_bf16_f32 v29, v14, v15
	global_store_dwordx4 v[30:31], v[26:29], off sc1
	s_nop 1
.LBB0_3123:
	s_mov_b64 s[6:7], 0x80
	v_lshl_add_u64 v[26:27], v[20:21], 0, s[6:7]
	s_waitcnt vmcnt(0)
	v_add_f32 v10, v10, v74
	v_add_f32 v11, v11, v75
	v_add_f32 v8, v8, v72
	v_add_f32 v9, v9, v73
	s_mov_b64 s[6:7], 0x90
	global_store_dwordx4 v[26:27], v[8:11], off sc1
	s_nop 1
	v_add_f32 v6, v6, v70
	v_add_f32 v7, v7, v71
	v_add_f32 v4, v4, v68
	v_add_f32 v5, v5, v69
	v_lshl_add_u64 v[20:21], v[20:21], 0, s[6:7]
	global_store_dwordx4 v[20:21], v[4:7], off sc1
	s_nop 1
	s_and_b64 vcc, exec, s[16:17]
	s_cbranch_vccnz .LBB0_3125
	v_lshl_add_u64 v[20:21], v[188:189], 1, v[22:23]
	v_lshl_add_u64 v[26:27], v[20:21], 0, 64
	v_cvt_pk_bf16_f32 v20, v8, v9
	v_cvt_pk_bf16_f32 v21, v10, v11
	v_cvt_pk_bf16_f32 v22, v4, v5
	v_cvt_pk_bf16_f32 v23, v6, v7
	global_store_dwordx4 v[26:27], v[20:23], off sc1
	s_nop 1

.LBB0_3202:
	v_mov_b32_e32 v132, v0
	s_lshl_b32 s1, s57, 8
	v_readfirstlane_b32 s0, v132
	s_and_b32 s8, s0, 0xc0
	s_ashr_i32 s0, s0, 2
	s_andn2_b32 s0, s0, 63
	s_add_i32 s0, s0, s1
	v_and_or_b32 v194, v132, 15, s0
	s_lshl_b32 s0, s56, 8
	s_ashr_i32 s1, s0, 31
	s_or_b32 s9, s8, s0
	s_lshl_b64 s[0:1], s[0:1], 2
	s_add_u32 s0, s20, s0
	s_addc_u32 s1, s21, s1
	s_lshl_b32 s8, s8, 2
	v_bfe_u32 v228, v132, 4, 2
	s_add_u32 s0, s0, s8
	s_addc_u32 s1, s1, 0
	v_lshlrev_b32_e32 v132, 5, v228
	v_mov_b32_e32 v133, v2
	v_ashrrev_i32_e32 v195, 31, v194
	v_or_b32_e32 v220, 16, v194
	v_lshl_add_u64 v[210:211], s[0:1], 0, v[132:133]
	v_lshlrev_b64 v[224:225], 12, v[194:195]
	v_ashrrev_i32_e32 v221, 31, v220
	v_or_b32_e32 v216, 32, v194
	v_or_b32_e32 v212, 48, v194
	v_lshl_add_u64 v[132:133], v[210:211], 0, v[224:225]
	v_lshlrev_b64 v[222:223], 12, v[220:221]
	v_ashrrev_i32_e32 v217, 31, v216
	v_ashrrev_i32_e32 v213, 31, v212
	global_load_dwordx4 v[244:247], v[132:133], off offset:16
	global_load_dwordx4 v[248:251], v[132:133], off
	global_load_dwordx4 v[180:183], v[132:133], off offset:144
	global_load_dwordx4 v[184:187], v[132:133], off offset:128
	v_lshl_add_u64 v[132:133], v[210:211], 0, v[222:223]
	v_lshlrev_b64 v[218:219], 12, v[216:217]
	v_lshlrev_b64 v[214:215], 12, v[212:213]
	global_load_dwordx4 v[172:175], v[132:133], off offset:16
	global_load_dwordx4 v[176:179], v[132:133], off
	global_load_dwordx4 v[164:167], v[132:133], off offset:144
	global_load_dwordx4 v[168:171], v[132:133], off offset:128
	v_lshl_add_u64 v[132:133], v[210:211], 0, v[218:219]
	v_lshl_add_u64 v[136:137], v[210:211], 0, v[214:215]
	global_load_dwordx4 v[156:159], v[132:133], off offset:16
	global_load_dwordx4 v[160:163], v[132:133], off
	global_load_dwordx4 v[148:151], v[132:133], off offset:144
	global_load_dwordx4 v[152:155], v[132:133], off offset:128
	global_load_dwordx4 v[140:143], v[136:137], off offset:16
	global_load_dwordx4 v[144:147], v[136:137], off
	s_nop 0
	global_load_dwordx4 v[132:135], v[136:137], off offset:144
	s_nop 0
	global_load_dwordx4 v[136:139], v[136:137], off offset:128
	v_lshl_or_b32 v192, v228, 3, s9
	v_lshlrev_b64 v[226:227], 10, v[194:195]
	v_lshl_add_u64 v[224:225], s[20:21], 0, v[224:225]
	v_ashrrev_i32_e32 v193, 31, v192
	v_lshl_add_u64 v[224:225], v[192:193], 2, v[224:225]
	s_and_b64 vcc, exec, s[28:29]
	v_lshl_add_u64 v[226:227], v[226:227], 1, s[18:19]
	s_waitcnt vmcnt(0)
	v_add_f32 v126, v126, v246
	v_add_f32 v127, v127, v247
	v_add_f32 v130, v130, v250
	v_add_f32 v131, v131, v251
	v_add_f32 v128, v128, v248
	v_add_f32 v129, v129, v249
	v_add_f32 v124, v124, v244
	v_add_f32 v125, v125, v245
	global_store_dwordx4 v[224:225], v[128:131], off
	global_store_dwordx4 v[224:225], v[124:127], off offset:16
	s_cbranch_vccz .LBB0_3204
	v_lshl_add_u64 v[232:233], v[192:193], 1, v[226:227]
	v_cvt_pk_bf16_f32 v244, v128, v129
	v_cvt_pk_bf16_f32 v245, v130, v131
	v_cvt_pk_bf16_f32 v246, v124, v125
	v_cvt_pk_bf16_f32 v247, v126, v127
	global_store_dwordx4 v[232:233], v[244:247], off
.LBB0_3204:
	v_add_f32 v116, v116, v180
	v_add_f32 v117, v117, v181
	v_cndmask_b32_e64 v180, 0, 1, s[28:29]
	v_add_f32 v122, v122, v186
	v_add_f32 v123, v123, v187
	v_add_f32 v120, v120, v184
	v_add_f32 v121, v121, v185
	v_add_f32 v118, v118, v182
	v_add_f32 v119, v119, v183
	v_cmp_ne_u32_e64 s[16:17], 1, v180
	s_andn2_b64 vcc, exec, s[28:29]
	global_store_dwordx4 v[224:225], v[120:123], off offset:128
	global_store_dwordx4 v[224:225], v[116:119], off offset:144
	s_cbranch_vccnz .LBB0_3206
	v_lshl_add_u64 v[184:185], v[192:193], 1, v[226:227]
	v_cvt_pk_bf16_f32 v180, v120, v121
	v_cvt_pk_bf16_f32 v181, v122, v123
	v_cvt_pk_bf16_f32 v182, v116, v117
	v_cvt_pk_bf16_f32 v183, v118, v119
	global_store_dwordx4 v[184:185], v[180:183], off offset:64
.LBB0_3206:
	v_mul_f32_e32 v129, v129, v129
	v_mul_f32_e32 v125, v125, v125
	v_mul_f32_e32 v121, v121, v121
	v_mul_f32_e32 v117, v117, v117
	v_fmac_f32_e32 v129, v128, v128
	v_mul_f32_e32 v128, v131, v131
	v_fmac_f32_e32 v125, v124, v124
	v_mul_f32_e32 v124, v127, v127
	v_fmac_f32_e32 v121, v120, v120
	v_mul_f32_e32 v120, v123, v123
	v_fmac_f32_e32 v117, v116, v116
	v_mul_f32_e32 v116, v119, v119
	v_fmac_f32_e32 v128, v130, v130
	v_fmac_f32_e32 v124, v126, v126
	v_fmac_f32_e32 v120, v122, v122
	v_fmac_f32_e32 v116, v118, v118
	v_add_f32_e32 v128, v129, v128
	v_add_f32_e32 v124, v125, v124
	v_add_f32_e32 v120, v121, v120
	v_add_f32_e32 v116, v117, v116
	v_add_f32_e32 v124, v128, v124
	v_add_f32_e32 v116, v120, v116
	v_add_f32_e32 v116, v124, v116
	ds_swizzle_b32 v119, v116 offset:swizzle(SWAP,16)
	v_and_b32_e32 v118, 64, v236
	v_xor_b32_e32 v117, 32, v236
	v_add_u32_e32 v118, 64, v118
	v_cmp_lt_i32_e32 vcc, v117, v118
	s_waitcnt lgkmcnt(0)
	v_add_f32_e32 v120, v116, v119
	v_lshlrev_b64 v[118:119], 10, v[220:221]
	v_cndmask_b32_e32 v117, v236, v117, vcc
	v_lshlrev_b32_e32 v180, 2, v117
	ds_bpermute_b32 v121, v180, v120
	v_lshl_add_u64 v[116:117], s[20:21], 0, v[222:223]
	v_lshl_add_u64 v[116:117], v[192:193], 2, v[116:117]
	v_add_f32 v114, v114, v178
	v_add_f32 v115, v115, v179
	v_add_f32 v112, v112, v176
	v_add_f32 v113, v113, v177
	v_add_f32 v110, v110, v174
	v_add_f32 v111, v111, v175
	v_add_f32 v108, v108, v172
	v_add_f32 v109, v109, v173
	s_and_b64 vcc, exec, s[16:17]
	v_lshl_add_u64 v[118:119], v[118:119], 1, s[18:19]
	global_store_dwordx4 v[116:117], v[112:115], off
	global_store_dwordx4 v[116:117], v[108:111], off offset:16
	s_cbranch_vccnz .LBB0_3208
	v_lshl_add_u64 v[126:127], v[192:193], 1, v[118:119]
	v_cvt_pk_bf16_f32 v122, v112, v113
	v_cvt_pk_bf16_f32 v123, v114, v115
	v_cvt_pk_bf16_f32 v124, v108, v109
	v_cvt_pk_bf16_f32 v125, v110, v111
	global_store_dwordx4 v[126:127], v[122:125], off
.LBB0_3208:
	v_add_f32 v106, v106, v170
	v_add_f32 v107, v107, v171
	v_add_f32 v104, v104, v168
	v_add_f32 v105, v105, v169
	v_add_f32 v102, v102, v166
	v_add_f32 v103, v103, v167
	v_add_f32 v100, v100, v164
	v_add_f32 v101, v101, v165
	s_and_b64 vcc, exec, s[16:17]
	global_store_dwordx4 v[116:117], v[104:107], off offset:128
	global_store_dwordx4 v[116:117], v[100:103], off offset:144
	s_cbranch_vccnz .LBB0_3210
	v_lshl_add_u64 v[122:123], v[192:193], 1, v[118:119]
	v_cvt_pk_bf16_f32 v116, v104, v105
	v_cvt_pk_bf16_f32 v117, v106, v107
	v_cvt_pk_bf16_f32 v118, v100, v101
	v_cvt_pk_bf16_f32 v119, v102, v103
	global_store_dwordx4 v[122:123], v[116:119], off offset:64
.LBB0_3210:
	v_mul_f32_e32 v113, v113, v113
	v_mul_f32_e32 v109, v109, v109
	v_mul_f32_e32 v105, v105, v105
	v_mul_f32_e32 v101, v101, v101
	v_fmac_f32_e32 v113, v112, v112
	v_mul_f32_e32 v112, v115, v115
	v_fmac_f32_e32 v109, v108, v108
	v_mul_f32_e32 v108, v111, v111
	v_fmac_f32_e32 v105, v104, v104
	v_mul_f32_e32 v104, v107, v107
	v_fmac_f32_e32 v101, v100, v100
	v_mul_f32_e32 v100, v103, v103
	v_fmac_f32_e32 v112, v114, v114
	v_fmac_f32_e32 v108, v110, v110
	v_fmac_f32_e32 v104, v106, v106
	v_fmac_f32_e32 v100, v102, v102
	v_add_f32_e32 v112, v113, v112
	v_add_f32_e32 v108, v109, v108
	v_add_f32_e32 v104, v105, v104
	v_add_f32_e32 v100, v101, v100
	v_add_f32_e32 v108, v112, v108
	v_add_f32_e32 v100, v104, v100
	v_add_f32_e32 v100, v108, v100
	ds_swizzle_b32 v101, v100 offset:swizzle(SWAP,16)
	v_lshlrev_b64 v[102:103], 10, v[216:217]
	v_add_f32 v98, v98, v162
	v_add_f32 v99, v99, v163
	v_add_f32 v96, v96, v160
	v_add_f32 v97, v97, v161
	v_add_f32 v94, v94, v158
	v_add_f32 v95, v95, v159
	s_waitcnt lgkmcnt(0)
	v_add_f32_e32 v104, v100, v101
	ds_bpermute_b32 v105, v180, v104
	v_lshl_add_u64 v[100:101], s[20:21], 0, v[218:219]
	v_lshl_add_u64 v[100:101], v[192:193], 2, v[100:101]
	v_add_f32 v92, v92, v156
	v_add_f32 v93, v93, v157
	s_and_b64 vcc, exec, s[16:17]
	v_lshl_add_u64 v[102:103], v[102:103], 1, s[18:19]
	global_store_dwordx4 v[100:101], v[96:99], off
	global_store_dwordx4 v[100:101], v[92:95], off offset:16
	s_cbranch_vccnz .LBB0_3212
	v_lshl_add_u64 v[110:111], v[192:193], 1, v[102:103]
	v_cvt_pk_bf16_f32 v106, v96, v97
	v_cvt_pk_bf16_f32 v107, v98, v99
	v_cvt_pk_bf16_f32 v108, v92, v93
	v_cvt_pk_bf16_f32 v109, v94, v95
	global_store_dwordx4 v[110:111], v[106:109], off
.LBB0_3212:
	v_add_f32 v90, v90, v154
	v_add_f32 v91, v91, v155
	v_add_f32 v88, v88, v152
	v_add_f32 v89, v89, v153
	v_add_f32 v86, v86, v150
	v_add_f32 v87, v87, v151
	v_add_f32 v84, v84, v148
	v_add_f32 v85, v85, v149
	s_and_b64 vcc, exec, s[16:17]
	global_store_dwordx4 v[100:101], v[88:91], off offset:128
	global_store_dwordx4 v[100:101], v[84:87], off offset:144
	s_cbranch_vccnz .LBB0_3214
	v_lshl_add_u64 v[106:107], v[192:193], 1, v[102:103]
	v_cvt_pk_bf16_f32 v100, v88, v89
	v_cvt_pk_bf16_f32 v101, v90, v91
	v_cvt_pk_bf16_f32 v102, v84, v85
	v_cvt_pk_bf16_f32 v103, v86, v87
	global_store_dwordx4 v[106:107], v[100:103], off offset:64
.LBB0_3214:
	v_mul_f32_e32 v97, v97, v97
	v_mul_f32_e32 v93, v93, v93
	v_mul_f32_e32 v89, v89, v89
	v_mul_f32_e32 v85, v85, v85
	v_fmac_f32_e32 v97, v96, v96
	v_mul_f32_e32 v96, v99, v99
	v_fmac_f32_e32 v93, v92, v92
	v_mul_f32_e32 v92, v95, v95
	v_fmac_f32_e32 v89, v88, v88
	v_mul_f32_e32 v88, v91, v91
	v_fmac_f32_e32 v85, v84, v84
	v_mul_f32_e32 v84, v87, v87
	v_fmac_f32_e32 v96, v98, v98
	v_fmac_f32_e32 v92, v94, v94
	v_fmac_f32_e32 v88, v90, v90
	v_fmac_f32_e32 v84, v86, v86
	v_add_f32_e32 v96, v97, v96
	v_add_f32_e32 v92, v93, v92
	v_add_f32_e32 v88, v89, v88
	v_add_f32_e32 v84, v85, v84
	v_add_f32_e32 v92, v96, v92
	v_add_f32_e32 v84, v88, v84
	v_add_f32_e32 v84, v92, v84
	ds_swizzle_b32 v85, v84 offset:swizzle(SWAP,16)
	v_lshlrev_b64 v[86:87], 10, v[212:213]
	v_add_f32 v82, v82, v146
	v_add_f32 v83, v83, v147
	v_add_f32 v80, v80, v144
	v_add_f32 v81, v81, v145
	v_add_f32 v78, v78, v142
	v_add_f32 v79, v79, v143
	s_waitcnt lgkmcnt(0)
	v_add_f32_e32 v88, v84, v85
	ds_bpermute_b32 v89, v180, v88
	v_lshl_add_u64 v[84:85], s[20:21], 0, v[214:215]
	v_lshl_add_u64 v[84:85], v[192:193], 2, v[84:85]
	v_add_f32 v76, v76, v140
	v_add_f32 v77, v77, v141
	s_and_b64 vcc, exec, s[16:17]
	v_lshl_add_u64 v[86:87], v[86:87], 1, s[18:19]
	global_store_dwordx4 v[84:85], v[80:83], off
	global_store_dwordx4 v[84:85], v[76:79], off offset:16
	s_cbranch_vccnz .LBB0_3216
	v_lshl_add_u64 v[94:95], v[192:193], 1, v[86:87]
	v_cvt_pk_bf16_f32 v90, v80, v81
	v_cvt_pk_bf16_f32 v91, v82, v83
	v_cvt_pk_bf16_f32 v92, v76, v77
	v_cvt_pk_bf16_f32 v93, v78, v79
	global_store_dwordx4 v[94:95], v[90:93], off
.LBB0_3216:
	v_add_f32 v74, v74, v138
	v_add_f32 v75, v75, v139
	v_add_f32 v72, v72, v136
	v_add_f32 v73, v73, v137
	v_add_f32 v70, v70, v134
	v_add_f32 v71, v71, v135
	v_add_f32 v68, v68, v132
	v_add_f32 v69, v69, v133
	s_and_b64 vcc, exec, s[16:17]
	global_store_dwordx4 v[84:85], v[72:75], off offset:128
	global_store_dwordx4 v[84:85], v[68:71], off offset:144
	s_cbranch_vccnz .LBB0_3218
	v_lshl_add_u64 v[90:91], v[192:193], 1, v[86:87]
	v_cvt_pk_bf16_f32 v84, v72, v73
	v_cvt_pk_bf16_f32 v85, v74, v75
	v_cvt_pk_bf16_f32 v86, v68, v69
	v_cvt_pk_bf16_f32 v87, v70, v71
	global_store_dwordx4 v[90:91], v[84:87], off offset:64

.LBB0_3220:
	s_or_b64 exec, exec, s[8:9]
	v_add_u32_e32 v138, 0x80, v194
	v_ashrrev_i32_e32 v139, 31, v138
	v_add_u32_e32 v134, 0x90, v194
	v_lshlrev_b64 v[148:149], 12, v[138:139]
	v_ashrrev_i32_e32 v135, 31, v134
	v_add_u32_e32 v130, 0xa0, v194
	v_add_u32_e32 v126, 0xb0, v194
	s_waitcnt lgkmcnt(0)
	v_lshl_add_u64 v[68:69], v[210:211], 0, v[148:149]
	v_lshlrev_b64 v[136:137], 12, v[134:135]
	v_ashrrev_i32_e32 v131, 31, v130
	v_ashrrev_i32_e32 v127, 31, v126
	global_load_dwordx4 v[140:143], v[68:69], off offset:16
	global_load_dwordx4 v[144:147], v[68:69], off
	global_load_dwordx4 v[116:119], v[68:69], off offset:144
	global_load_dwordx4 v[120:123], v[68:69], off offset:128
	v_lshl_add_u64 v[68:69], v[210:211], 0, v[136:137]
	v_lshlrev_b64 v[132:133], 12, v[130:131]
	v_lshlrev_b64 v[128:129], 12, v[126:127]
	global_load_dwordx4 v[108:111], v[68:69], off offset:16
	global_load_dwordx4 v[112:115], v[68:69], off
	global_load_dwordx4 v[100:103], v[68:69], off offset:144
	global_load_dwordx4 v[104:107], v[68:69], off offset:128
	v_lshl_add_u64 v[68:69], v[210:211], 0, v[132:133]
	v_lshl_add_u64 v[72:73], v[210:211], 0, v[128:129]
	global_load_dwordx4 v[92:95], v[68:69], off offset:16
	global_load_dwordx4 v[96:99], v[68:69], off
	global_load_dwordx4 v[84:87], v[68:69], off offset:144
	global_load_dwordx4 v[88:91], v[68:69], off offset:128
	global_load_dwordx4 v[76:79], v[72:73], off offset:16
	global_load_dwordx4 v[80:83], v[72:73], off
	s_nop 0
	global_load_dwordx4 v[68:71], v[72:73], off offset:144
	s_nop 0
	global_load_dwordx4 v[72:75], v[72:73], off offset:128
	v_lshlrev_b64 v[150:151], 10, v[138:139]
	v_lshl_add_u64 v[138:139], s[20:21], 0, v[148:149]
	s_and_b64 vcc, exec, s[16:17]
	v_lshl_add_u64 v[138:139], v[192:193], 2, v[138:139]
	s_waitcnt vmcnt(15)
	v_add_f32 v62, v62, v142
	v_add_f32 v63, v63, v143
	s_waitcnt vmcnt(14)
	v_add_f32 v66, v66, v146
	v_add_f32 v67, v67, v147
	v_add_f32 v64, v64, v144
	v_add_f32 v65, v65, v145
	v_add_f32 v60, v60, v140
	v_add_f32 v61, v61, v141
	v_lshl_add_u64 v[140:141], v[150:151], 1, s[18:19]
	global_store_dwordx4 v[138:139], v[64:67], off
	global_store_dwordx4 v[138:139], v[60:63], off offset:16
	s_cbranch_vccnz .LBB0_3222
	v_lshl_add_u64 v[146:147], v[192:193], 1, v[140:141]
	v_cvt_pk_bf16_f32 v142, v64, v65
	v_cvt_pk_bf16_f32 v143, v66, v67
	v_cvt_pk_bf16_f32 v144, v60, v61
	v_cvt_pk_bf16_f32 v145, v62, v63
	global_store_dwordx4 v[146:147], v[142:145], off
.LBB0_3222:
	s_waitcnt vmcnt(14)
	v_add_f32 v58, v58, v122
	v_add_f32 v59, v59, v123
	v_add_f32 v56, v56, v120
	v_add_f32 v57, v57, v121
	v_add_f32 v54, v54, v118
	v_add_f32 v55, v55, v119
	v_add_f32 v52, v52, v116
	v_add_f32 v53, v53, v117
	s_and_b64 vcc, exec, s[16:17]
	global_store_dwordx4 v[138:139], v[56:59], off offset:128
	global_store_dwordx4 v[138:139], v[52:55], off offset:144
	s_cbranch_vccnz .LBB0_3224
	v_lshl_add_u64 v[120:121], v[192:193], 1, v[140:141]
	v_cvt_pk_bf16_f32 v116, v56, v57
	v_cvt_pk_bf16_f32 v117, v58, v59
	v_cvt_pk_bf16_f32 v118, v52, v53
	v_cvt_pk_bf16_f32 v119, v54, v55
	global_store_dwordx4 v[120:121], v[116:119], off offset:64
.LBB0_3224:
	v_mul_f32_e32 v65, v65, v65
	v_mul_f32_e32 v61, v61, v61
	v_mul_f32_e32 v57, v57, v57
	v_mul_f32_e32 v53, v53, v53
	v_fmac_f32_e32 v65, v64, v64
	v_mul_f32_e32 v64, v67, v67
	v_fmac_f32_e32 v61, v60, v60
	v_mul_f32_e32 v60, v63, v63
	v_fmac_f32_e32 v57, v56, v56
	v_mul_f32_e32 v56, v59, v59
	v_fmac_f32_e32 v53, v52, v52
	v_mul_f32_e32 v52, v55, v55
	v_fmac_f32_e32 v64, v66, v66
	v_fmac_f32_e32 v60, v62, v62
	v_fmac_f32_e32 v56, v58, v58
	v_fmac_f32_e32 v52, v54, v54
	v_add_f32_e32 v64, v65, v64
	v_add_f32_e32 v60, v61, v60
	v_add_f32_e32 v56, v57, v56
	v_add_f32_e32 v52, v53, v52
	v_add_f32_e32 v60, v64, v60
	v_add_f32_e32 v52, v56, v52
	v_add_f32_e32 v52, v60, v52
	ds_swizzle_b32 v53, v52 offset:swizzle(SWAP,16)
	v_lshlrev_b64 v[54:55], 10, v[134:135]
	s_waitcnt vmcnt(14)
	v_add_f32 v50, v50, v114
	v_add_f32 v51, v51, v115
	v_add_f32 v48, v48, v112
	v_add_f32 v49, v49, v113
	v_add_f32 v46, v46, v110
	v_add_f32 v47, v47, v111
	s_waitcnt lgkmcnt(0)
	v_add_f32_e32 v56, v52, v53
	ds_bpermute_b32 v57, v180, v56
	v_lshl_add_u64 v[52:53], s[20:21], 0, v[136:137]
	v_lshl_add_u64 v[52:53], v[192:193], 2, v[52:53]
	v_add_f32 v44, v44, v108
	v_add_f32 v45, v45, v109
	s_and_b64 vcc, exec, s[16:17]
	v_lshl_add_u64 v[54:55], v[54:55], 1, s[18:19]
	global_store_dwordx4 v[52:53], v[48:51], off
	global_store_dwordx4 v[52:53], v[44:47], off offset:16
	s_cbranch_vccnz .LBB0_3226
	v_lshl_add_u64 v[62:63], v[192:193], 1, v[54:55]
	v_cvt_pk_bf16_f32 v58, v48, v49
	v_cvt_pk_bf16_f32 v59, v50, v51
	v_cvt_pk_bf16_f32 v60, v44, v45
	v_cvt_pk_bf16_f32 v61, v46, v47
	global_store_dwordx4 v[62:63], v[58:61], off
.LBB0_3226:
	s_waitcnt vmcnt(14)
	v_add_f32 v42, v42, v106
	v_add_f32 v43, v43, v107
	v_add_f32 v40, v40, v104
	v_add_f32 v41, v41, v105
	v_add_f32 v38, v38, v102
	v_add_f32 v39, v39, v103
	v_add_f32 v36, v36, v100
	v_add_f32 v37, v37, v101
	s_and_b64 vcc, exec, s[16:17]
	global_store_dwordx4 v[52:53], v[40:43], off offset:128
	global_store_dwordx4 v[52:53], v[36:39], off offset:144
	s_cbranch_vccnz .LBB0_3228
	v_lshl_add_u64 v[58:59], v[192:193], 1, v[54:55]
	v_cvt_pk_bf16_f32 v52, v40, v41
	v_cvt_pk_bf16_f32 v53, v42, v43
	v_cvt_pk_bf16_f32 v54, v36, v37
	v_cvt_pk_bf16_f32 v55, v38, v39
	global_store_dwordx4 v[58:59], v[52:55], off offset:64
.LBB0_3228:
	v_mul_f32_e32 v49, v49, v49
	v_mul_f32_e32 v45, v45, v45
	v_mul_f32_e32 v41, v41, v41
	v_mul_f32_e32 v37, v37, v37
	v_fmac_f32_e32 v49, v48, v48
	v_mul_f32_e32 v48, v51, v51
	v_fmac_f32_e32 v45, v44, v44
	v_mul_f32_e32 v44, v47, v47
	v_fmac_f32_e32 v41, v40, v40
	v_mul_f32_e32 v40, v43, v43
	v_fmac_f32_e32 v37, v36, v36
	v_mul_f32_e32 v36, v39, v39
	v_fmac_f32_e32 v48, v50, v50
	v_fmac_f32_e32 v44, v46, v46
	v_fmac_f32_e32 v40, v42, v42
	v_fmac_f32_e32 v36, v38, v38
	v_add_f32_e32 v48, v49, v48
	v_add_f32_e32 v44, v45, v44
	v_add_f32_e32 v40, v41, v40
	v_add_f32_e32 v36, v37, v36
	v_add_f32_e32 v44, v48, v44
	v_add_f32_e32 v36, v40, v36
	v_add_f32_e32 v36, v44, v36
	ds_swizzle_b32 v37, v36 offset:swizzle(SWAP,16)
	v_lshlrev_b64 v[38:39], 10, v[130:131]
	s_waitcnt vmcnt(14)
	v_add_f32 v34, v34, v98
	v_add_f32 v35, v35, v99
	v_add_f32 v32, v32, v96
	v_add_f32 v33, v33, v97
	v_add_f32 v30, v30, v94
	v_add_f32 v31, v31, v95
	s_waitcnt lgkmcnt(0)
	v_add_f32_e32 v40, v36, v37
	ds_bpermute_b32 v41, v180, v40
	v_lshl_add_u64 v[36:37], s[20:21], 0, v[132:133]
	v_lshl_add_u64 v[36:37], v[192:193], 2, v[36:37]
	v_add_f32 v28, v28, v92
	v_add_f32 v29, v29, v93
	s_and_b64 vcc, exec, s[16:17]
	v_lshl_add_u64 v[38:39], v[38:39], 1, s[18:19]
	global_store_dwordx4 v[36:37], v[32:35], off
	global_store_dwordx4 v[36:37], v[28:31], off offset:16
	s_cbranch_vccnz .LBB0_3230
	v_lshl_add_u64 v[46:47], v[192:193], 1, v[38:39]
	v_cvt_pk_bf16_f32 v42, v32, v33
	v_cvt_pk_bf16_f32 v43, v34, v35
	v_cvt_pk_bf16_f32 v44, v28, v29
	v_cvt_pk_bf16_f32 v45, v30, v31
	global_store_dwordx4 v[46:47], v[42:45], off
.LBB0_3230:
	s_waitcnt vmcnt(14)
	v_add_f32 v26, v26, v90
	v_add_f32 v27, v27, v91
	v_add_f32 v24, v24, v88
	v_add_f32 v25, v25, v89
	v_add_f32 v22, v22, v86
	v_add_f32 v23, v23, v87
	v_add_f32 v20, v20, v84
	v_add_f32 v21, v21, v85
	s_and_b64 vcc, exec, s[16:17]
	global_store_dwordx4 v[36:37], v[24:27], off offset:128
	global_store_dwordx4 v[36:37], v[20:23], off offset:144
	s_cbranch_vccnz .LBB0_3232
	v_lshl_add_u64 v[42:43], v[192:193], 1, v[38:39]
	v_cvt_pk_bf16_f32 v36, v24, v25
	v_cvt_pk_bf16_f32 v37, v26, v27
	v_cvt_pk_bf16_f32 v38, v20, v21
	v_cvt_pk_bf16_f32 v39, v22, v23
	global_store_dwordx4 v[42:43], v[36:39], off offset:64
.LBB0_3232:
	v_mul_f32_e32 v33, v33, v33
	v_mul_f32_e32 v29, v29, v29
	v_mul_f32_e32 v25, v25, v25
	v_mul_f32_e32 v21, v21, v21
	v_fmac_f32_e32 v33, v32, v32
	v_mul_f32_e32 v32, v35, v35
	v_fmac_f32_e32 v29, v28, v28
	v_mul_f32_e32 v28, v31, v31
	v_fmac_f32_e32 v25, v24, v24
	v_mul_f32_e32 v24, v27, v27
	v_fmac_f32_e32 v21, v20, v20
	v_mul_f32_e32 v20, v23, v23
	v_fmac_f32_e32 v32, v34, v34
	v_fmac_f32_e32 v28, v30, v30
	v_fmac_f32_e32 v24, v26, v26
	v_fmac_f32_e32 v20, v22, v22
	v_add_f32_e32 v32, v33, v32
	v_add_f32_e32 v28, v29, v28
	v_add_f32_e32 v24, v25, v24
	v_add_f32_e32 v20, v21, v20
	v_add_f32_e32 v28, v32, v28
	v_add_f32_e32 v20, v24, v20
	v_add_f32_e32 v20, v28, v20
	ds_swizzle_b32 v21, v20 offset:swizzle(SWAP,16)
	v_lshlrev_b64 v[22:23], 10, v[126:127]
	s_waitcnt vmcnt(14)
	v_add_f32 v18, v18, v82
	v_add_f32 v19, v19, v83
	v_add_f32 v16, v16, v80
	v_add_f32 v17, v17, v81
	v_add_f32 v14, v14, v78
	v_add_f32 v15, v15, v79
	s_waitcnt lgkmcnt(0)
	v_add_f32_e32 v24, v20, v21
	ds_bpermute_b32 v25, v180, v24
	v_lshl_add_u64 v[20:21], s[20:21], 0, v[128:129]
	v_lshl_add_u64 v[20:21], v[192:193], 2, v[20:21]
	v_add_f32 v12, v12, v76
	v_add_f32 v13, v13, v77
	s_and_b64 vcc, exec, s[16:17]
	v_lshl_add_u64 v[22:23], v[22:23], 1, s[18:19]
	global_store_dwordx4 v[20:21], v[16:19], off
	global_store_dwordx4 v[20:21], v[12:15], off offset:16
	s_cbranch_vccnz .LBB0_3234
	v_lshl_add_u64 v[30:31], v[192:193], 1, v[22:23]
	v_cvt_pk_bf16_f32 v26, v16, v17
	v_cvt_pk_bf16_f32 v27, v18, v19
	v_cvt_pk_bf16_f32 v28, v12, v13
	v_cvt_pk_bf16_f32 v29, v14, v15
	global_store_dwordx4 v[30:31], v[26:29], off
.LBB0_3234:
	s_waitcnt vmcnt(14)
	v_add_f32 v10, v10, v74
	v_add_f32 v11, v11, v75
	v_add_f32 v8, v8, v72
	v_add_f32 v9, v9, v73
	v_add_f32 v6, v6, v70
	v_add_f32 v7, v7, v71
	v_add_f32 v4, v4, v68
	v_add_f32 v5, v5, v69
	s_and_b64 vcc, exec, s[16:17]
	global_store_dwordx4 v[20:21], v[8:11], off offset:128
	global_store_dwordx4 v[20:21], v[4:7], off offset:144
	s_cbranch_vccnz .LBB0_3236
	v_lshl_add_u64 v[26:27], v[192:193], 1, v[22:23]
	v_cvt_pk_bf16_f32 v20, v8, v9
	v_cvt_pk_bf16_f32 v21, v10, v11
	v_cvt_pk_bf16_f32 v22, v4, v5
	v_cvt_pk_bf16_f32 v23, v6, v7
	global_store_dwordx4 v[26:27], v[20:23], off offset:64
